# flat->global loads, counted vmcnt/lgkmcnt waits re-derived, in-proj epilogue rewritten with hoisted loads
# speedup vs baseline: 1.0156x; 1.0156x over previous
.LBB0_19:
	s_or_b64 exec, exec, s[10:11]
	v_lshlrev_b32_e32 v32, 3, v46
	v_sub_u32_e32 v32, v39, v32
	v_and_b32_e32 v32, 0xffffffc0, v32
	v_ashrrev_i32_e32 v34, 1, v41
	v_add_u32_e32 v34, v32, v34
	v_ashrrev_i32_e32 v35, 31, v34
	v_lshlrev_b32_e32 v32, 5, v41
	v_lshlrev_b64 v[46:47], 6, v[34:35]
	v_and_b32_e32 v32, 32, v32
	v_and_b32_e32 v41, 28, v45
	v_or3_b32 v46, v46, v32, v41
	s_waitcnt vmcnt(0)
	v_cvt_pk_bf16_f32 v34, v0, v4
	v_cvt_pk_bf16_f32 v35, v12, v8
	v_cvt_pk_bf16_f32 v36, v20, v16
	v_cvt_pk_bf16_f32 v37, v28, v24
	v_lshl_add_u64 v[48:49], v[46:47], 4, s[2:3]
	global_store_dwordx4 v[48:49], v[34:37], off
	v_or_b32_e32 v0, 1, v46
	v_add_u32_e32 v40, s38, v40
	v_cvt_pk_bf16_f32 v34, v1, v5
	v_mov_b32_e32 v1, v47
	v_cvt_pk_bf16_f32 v35, v13, v9
	v_cvt_pk_bf16_f32 v36, v21, v17
	v_cvt_pk_bf16_f32 v37, v29, v25
	v_lshl_add_u64 v[0:1], v[0:1], 4, s[2:3]
	global_store_dwordx4 v[0:1], v[34:37], off
	v_or_b32_e32 v0, 2, v46
	v_mov_b32_e32 v1, v47
	v_cvt_pk_bf16_f32 v34, v2, v6
	v_cvt_pk_bf16_f32 v35, v14, v10
	v_cvt_pk_bf16_f32 v36, v22, v18
	v_cvt_pk_bf16_f32 v37, v30, v26
	v_lshl_add_u64 v[0:1], v[0:1], 4, s[2:3]
	v_or_b32_e32 v46, 3, v46
	v_cmp_lt_i32_e32 vcc, s25, v40
	global_store_dwordx4 v[0:1], v[34:37], off
	v_cvt_pk_bf16_f32 v0, v3, v7
	v_cvt_pk_bf16_f32 v1, v15, v11
	v_cvt_pk_bf16_f32 v2, v23, v19
	v_cvt_pk_bf16_f32 v3, v31, v27
	v_lshl_add_u64 v[4:5], v[46:47], 4, s[2:3]
	v_add_u32_e32 v38, s16, v38
	s_or_b64 s[8:9], vcc, s[8:9]
	v_add_u32_e32 v39, s17, v39
	global_store_dwordx4 v[4:5], v[0:3], off
	s_andn2_b64 exec, exec, s[8:9]
	s_cbranch_execz .LBB0_58

.LBB0_60:
	s_or_b64 exec, exec, s[12:13]
	v_ashrrev_i32_e32 v37, 31, v36
	v_lshl_add_u64 v[46:47], v[38:39], 1, s[10:11]
	v_lshlrev_b64 v[48:49], 9, v[36:37]
	s_waitcnt vmcnt(0)
	v_cvt_pk_bf16_f32 v38, v0, v8
	v_cvt_pk_bf16_f32 v39, v4, v16
	v_cvt_pk_bf16_f32 v40, v12, v24
	v_cvt_pk_bf16_f32 v41, v20, v28
	v_lshl_add_u64 v[48:49], v[46:47], 0, v[48:49]
	v_add_u32_e32 v0, 1, v36
	global_store_dwordx4 v[48:49], v[38:41], off
	v_add_u32_e32 v4, 3, v36
	v_add_u32_e32 v34, s38, v34
	v_cvt_pk_bf16_f32 v38, v1, v9
	v_ashrrev_i32_e32 v1, 31, v0
	v_lshlrev_b64 v[0:1], 9, v[0:1]
	v_cvt_pk_bf16_f32 v39, v5, v17
	v_cvt_pk_bf16_f32 v40, v13, v25
	v_cvt_pk_bf16_f32 v41, v21, v29
	v_lshl_add_u64 v[0:1], v[46:47], 0, v[0:1]
	global_store_dwordx4 v[0:1], v[38:41], off
	v_add_u32_e32 v0, 2, v36
	v_ashrrev_i32_e32 v1, 31, v0
	v_lshlrev_b64 v[0:1], 9, v[0:1]
	v_ashrrev_i32_e32 v5, 31, v4
	v_cvt_pk_bf16_f32 v38, v2, v10
	v_cvt_pk_bf16_f32 v39, v6, v18
	v_cvt_pk_bf16_f32 v40, v14, v26
	v_cvt_pk_bf16_f32 v41, v22, v30
	v_lshl_add_u64 v[0:1], v[46:47], 0, v[0:1]
	v_lshlrev_b64 v[4:5], 9, v[4:5]
	v_cmp_lt_i32_e32 vcc, s19, v34
	global_store_dwordx4 v[0:1], v[38:41], off
	v_cvt_pk_bf16_f32 v0, v3, v11
	v_cvt_pk_bf16_f32 v1, v7, v19
	v_cvt_pk_bf16_f32 v2, v15, v27
	v_cvt_pk_bf16_f32 v3, v23, v31
	v_lshl_add_u64 v[4:5], v[46:47], 0, v[4:5]
	s_or_b64 s[6:7], vcc, s[6:7]
	v_add_u32_e32 v32, s14, v32
	global_store_dwordx4 v[4:5], v[0:3], off
	s_andn2_b64 exec, exec, s[6:7]
	s_cbranch_execz .LBB0_85

.LBB0_87:
	s_or_b64 exec, exec, s[14:15]
	v_ashrrev_i32_e32 v47, 31, v32
	v_mov_b32_e32 v46, v32
	v_lshl_add_u64 v[40:41], v[34:35], 1, s[12:13]
	v_lshlrev_b64 v[46:47], 8, v[46:47]
	s_waitcnt vmcnt(0)
	v_cvt_pk_bf16_f32 v34, v0, v8
	v_cvt_pk_bf16_f32 v35, v4, v16
	v_cvt_pk_bf16_f32 v36, v12, v24
	v_cvt_pk_bf16_f32 v37, v20, v28
	v_lshl_add_u64 v[46:47], v[40:41], 0, v[46:47]
	v_add_u32_e32 v0, 1, v32
	global_store_dwordx4 v[46:47], v[34:37], off
	v_add_u32_e32 v4, 3, v32
	v_add_u32_e32 v39, s38, v39
	v_cvt_pk_bf16_f32 v34, v1, v9
	v_ashrrev_i32_e32 v1, 31, v0
	v_lshlrev_b64 v[0:1], 8, v[0:1]
	v_cvt_pk_bf16_f32 v35, v5, v17
	v_cvt_pk_bf16_f32 v36, v13, v25
	v_cvt_pk_bf16_f32 v37, v21, v29
	v_lshl_add_u64 v[0:1], v[40:41], 0, v[0:1]
	global_store_dwordx4 v[0:1], v[34:37], off
	v_add_u32_e32 v0, 2, v32
	v_ashrrev_i32_e32 v1, 31, v0
	v_lshlrev_b64 v[0:1], 8, v[0:1]
	v_ashrrev_i32_e32 v5, 31, v4
	v_cvt_pk_bf16_f32 v34, v2, v10
	v_cvt_pk_bf16_f32 v35, v6, v18
	v_cvt_pk_bf16_f32 v36, v14, v26
	v_cvt_pk_bf16_f32 v37, v22, v30
	v_lshl_add_u64 v[0:1], v[40:41], 0, v[0:1]
	v_lshlrev_b64 v[4:5], 8, v[4:5]
	v_cmp_lt_i32_e32 vcc, s17, v39
	global_store_dwordx4 v[0:1], v[34:37], off
	v_cvt_pk_bf16_f32 v0, v3, v11
	v_cvt_pk_bf16_f32 v1, v7, v19
	v_cvt_pk_bf16_f32 v2, v15, v27
	v_cvt_pk_bf16_f32 v3, v23, v31
	v_lshl_add_u64 v[4:5], v[40:41], 0, v[4:5]
	s_or_b64 s[8:9], vcc, s[8:9]
	v_add_u32_e32 v38, s16, v38
	global_store_dwordx4 v[4:5], v[0:3], off
	s_andn2_b64 exec, exec, s[8:9]
	s_cbranch_execz .LBB0_112

.LBB0_114:
	s_or_b64 exec, exec, s[12:13]
	v_lshlrev_b32_e32 v34, 10, v46
	v_sub_u32_e32 v34, v40, v34
	v_and_b32_e32 v34, 0xffffff80, v34
	v_ashrrev_i32_e32 v35, 1, v46
	v_add_u32_e32 v34, v34, v35
	v_ashrrev_i32_e32 v35, 31, v34
	v_lshlrev_b64 v[48:49], 6, v[34:35]
	v_lshlrev_b32_e32 v34, 5, v46
	v_and_b32_e32 v46, 32, v34
	v_and_b32_e32 v32, 28, v32
	v_or3_b32 v48, v48, v46, v32
	s_waitcnt vmcnt(0)
	v_cvt_pk_bf16_f32 v34, v0, v8
	v_cvt_pk_bf16_f32 v35, v4, v16
	v_cvt_pk_bf16_f32 v36, v12, v24
	v_cvt_pk_bf16_f32 v37, v20, v28
	v_lshl_add_u64 v[46:47], v[48:49], 4, s[8:9]
	global_store_dwordx4 v[46:47], v[34:37], off
	v_or_b32_e32 v0, 1, v48
	v_add_u32_e32 v45, s38, v45
	v_cvt_pk_bf16_f32 v34, v1, v9
	v_mov_b32_e32 v1, v49
	v_cvt_pk_bf16_f32 v35, v5, v17
	v_cvt_pk_bf16_f32 v36, v13, v25
	v_cvt_pk_bf16_f32 v37, v21, v29
	v_lshl_add_u64 v[0:1], v[0:1], 4, s[8:9]
	global_store_dwordx4 v[0:1], v[34:37], off
	v_or_b32_e32 v0, 2, v48
	v_mov_b32_e32 v1, v49
	v_cvt_pk_bf16_f32 v34, v2, v10
	v_cvt_pk_bf16_f32 v35, v6, v18
	v_cvt_pk_bf16_f32 v36, v14, v26
	v_cvt_pk_bf16_f32 v37, v22, v30
	v_lshl_add_u64 v[0:1], v[0:1], 4, s[8:9]
	v_or_b32_e32 v48, 3, v48
	v_cmp_lt_i32_e32 vcc, s16, v45
	global_store_dwordx4 v[0:1], v[34:37], off
	v_cvt_pk_bf16_f32 v0, v3, v11
	v_cvt_pk_bf16_f32 v1, v7, v19
	v_cvt_pk_bf16_f32 v2, v15, v27
	v_cvt_pk_bf16_f32 v3, v23, v31
	v_lshl_add_u64 v[4:5], v[48:49], 4, s[8:9]
	v_add_u32_e32 v41, s14, v41
	s_or_b64 s[10:11], vcc, s[10:11]
	v_add_u32_e32 v40, s15, v40
	global_store_dwordx4 v[4:5], v[0:3], off
	s_andn2_b64 exec, exec, s[10:11]
	s_cbranch_execz .LBB0_131

.LBB0_132:
	s_or_b64 exec, exec, s[12:13]
	v_lshlrev_b32_e32 v34, 10, v41
	v_sub_u32_e32 v34, v39, v34
	v_and_b32_e32 v34, 0xffffff80, v34
	v_ashrrev_i32_e32 v35, 1, v41
	v_add_u32_e32 v34, v34, v35
	v_ashrrev_i32_e32 v35, 31, v34
	v_lshlrev_b64 v[46:47], 6, v[34:35]
	v_lshlrev_b32_e32 v34, 5, v41
	v_and_b32_e32 v41, 32, v34
	v_and_b32_e32 v32, 28, v32
	v_or3_b32 v46, v46, v41, v32
	s_waitcnt vmcnt(0)
	v_cvt_pk_bf16_f32 v34, v0, v8
	v_cvt_pk_bf16_f32 v35, v4, v16
	v_cvt_pk_bf16_f32 v36, v12, v24
	v_cvt_pk_bf16_f32 v37, v20, v28
	v_lshl_add_u64 v[48:49], v[46:47], 4, s[8:9]
	global_store_dwordx4 v[48:49], v[34:37], off
	v_or_b32_e32 v0, 1, v46
	v_add_u32_e32 v40, s38, v40
	v_cvt_pk_bf16_f32 v34, v1, v9
	v_mov_b32_e32 v1, v47
	v_cvt_pk_bf16_f32 v35, v5, v17
	v_cvt_pk_bf16_f32 v36, v13, v25
	v_cvt_pk_bf16_f32 v37, v21, v29
	v_lshl_add_u64 v[0:1], v[0:1], 4, s[8:9]
	global_store_dwordx4 v[0:1], v[34:37], off
	v_or_b32_e32 v0, 2, v46
	v_mov_b32_e32 v1, v47
	v_cvt_pk_bf16_f32 v34, v2, v10
	v_cvt_pk_bf16_f32 v35, v6, v18
	v_cvt_pk_bf16_f32 v36, v14, v26
	v_cvt_pk_bf16_f32 v37, v22, v30
	v_lshl_add_u64 v[0:1], v[0:1], 4, s[8:9]
	v_or_b32_e32 v46, 3, v46
	v_cmp_lt_i32_e32 vcc, s16, v40
	global_store_dwordx4 v[0:1], v[34:37], off
	v_cvt_pk_bf16_f32 v0, v3, v11
	v_cvt_pk_bf16_f32 v1, v7, v19
	v_cvt_pk_bf16_f32 v2, v15, v27
	v_cvt_pk_bf16_f32 v3, v23, v31
	v_lshl_add_u64 v[4:5], v[46:47], 4, s[8:9]
	v_add_u32_e32 v38, s14, v38
	s_or_b64 s[10:11], vcc, s[10:11]
	v_add_u32_e32 v39, s15, v39
	global_store_dwordx4 v[4:5], v[0:3], off
	s_andn2_b64 exec, exec, s[10:11]
	s_cbranch_execz .LBB0_149

.LBB0_154:
	s_or_b64 exec, exec, s[14:15]
	v_ashrrev_i32_e32 v47, 31, v32
	v_mov_b32_e32 v46, v32
	v_lshl_add_u64 v[40:41], v[34:35], 1, s[10:11]
	v_lshlrev_b64 v[46:47], 9, v[46:47]
	s_waitcnt vmcnt(0)
	v_cvt_pk_bf16_f32 v34, v0, v8
	v_cvt_pk_bf16_f32 v35, v4, v16
	v_cvt_pk_bf16_f32 v36, v12, v24
	v_cvt_pk_bf16_f32 v37, v20, v28
	v_lshl_add_u64 v[46:47], v[40:41], 0, v[46:47]
	v_add_u32_e32 v0, 1, v32
	global_store_dwordx4 v[46:47], v[34:37], off
	v_add_u32_e32 v4, 3, v32
	v_add_u32_e32 v39, s38, v39
	v_cvt_pk_bf16_f32 v34, v1, v9
	v_ashrrev_i32_e32 v1, 31, v0
	v_lshlrev_b64 v[0:1], 9, v[0:1]
	v_cvt_pk_bf16_f32 v35, v5, v17
	v_cvt_pk_bf16_f32 v36, v13, v25
	v_cvt_pk_bf16_f32 v37, v21, v29
	v_lshl_add_u64 v[0:1], v[40:41], 0, v[0:1]
	global_store_dwordx4 v[0:1], v[34:37], off
	v_add_u32_e32 v0, 2, v32
	v_ashrrev_i32_e32 v1, 31, v0
	v_lshlrev_b64 v[0:1], 9, v[0:1]
	v_ashrrev_i32_e32 v5, 31, v4
	v_cvt_pk_bf16_f32 v34, v2, v10
	v_cvt_pk_bf16_f32 v35, v6, v18
	v_cvt_pk_bf16_f32 v36, v14, v26
	v_cvt_pk_bf16_f32 v37, v22, v30
	v_lshl_add_u64 v[0:1], v[40:41], 0, v[0:1]
	v_lshlrev_b64 v[4:5], 9, v[4:5]
	v_cmp_lt_i32_e64 s[0:1], s17, v39
	global_store_dwordx4 v[0:1], v[34:37], off
	v_cvt_pk_bf16_f32 v0, v3, v11
	v_cvt_pk_bf16_f32 v1, v7, v19
	v_cvt_pk_bf16_f32 v2, v15, v27
	v_cvt_pk_bf16_f32 v3, v23, v31
	v_lshl_add_u64 v[4:5], v[40:41], 0, v[4:5]
	s_or_b64 s[12:13], s[0:1], s[12:13]
	v_add_u32_e32 v38, s16, v38
	global_store_dwordx4 v[4:5], v[0:3], off
	s_andn2_b64 exec, exec, s[12:13]
	s_cbranch_execz .LBB0_171

.LBB0_172:
	s_or_b64 exec, exec, s[14:15]
	v_ashrrev_i32_e32 v47, 31, v32
	v_mov_b32_e32 v46, v32
	v_lshl_add_u64 v[40:41], v[34:35], 1, s[10:11]
	v_lshlrev_b64 v[46:47], 9, v[46:47]
	s_waitcnt vmcnt(0)
	v_cvt_pk_bf16_f32 v34, v0, v8
	v_cvt_pk_bf16_f32 v35, v4, v16
	v_cvt_pk_bf16_f32 v36, v12, v24
	v_cvt_pk_bf16_f32 v37, v20, v28
	v_lshl_add_u64 v[46:47], v[40:41], 0, v[46:47]
	v_add_u32_e32 v0, 1, v32
	global_store_dwordx4 v[46:47], v[34:37], off
	v_add_u32_e32 v4, 3, v32
	v_add_u32_e32 v38, s38, v38
	v_cvt_pk_bf16_f32 v34, v1, v9
	v_ashrrev_i32_e32 v1, 31, v0
	v_lshlrev_b64 v[0:1], 9, v[0:1]
	v_cvt_pk_bf16_f32 v35, v5, v17
	v_cvt_pk_bf16_f32 v36, v13, v25
	v_cvt_pk_bf16_f32 v37, v21, v29
	v_lshl_add_u64 v[0:1], v[40:41], 0, v[0:1]
	global_store_dwordx4 v[0:1], v[34:37], off
	v_add_u32_e32 v0, 2, v32
	v_ashrrev_i32_e32 v1, 31, v0
	v_lshlrev_b64 v[0:1], 9, v[0:1]
	v_ashrrev_i32_e32 v5, 31, v4
	v_cvt_pk_bf16_f32 v34, v2, v10
	v_cvt_pk_bf16_f32 v35, v6, v18
	v_cvt_pk_bf16_f32 v36, v14, v26
	v_cvt_pk_bf16_f32 v37, v22, v30
	v_lshl_add_u64 v[0:1], v[40:41], 0, v[0:1]
	v_lshlrev_b64 v[4:5], 9, v[4:5]
	v_cmp_lt_i32_e64 s[0:1], s17, v38
	global_store_dwordx4 v[0:1], v[34:37], off
	v_cvt_pk_bf16_f32 v0, v3, v11
	v_cvt_pk_bf16_f32 v1, v7, v19
	v_cvt_pk_bf16_f32 v2, v15, v27
	v_cvt_pk_bf16_f32 v3, v23, v31
	v_lshl_add_u64 v[4:5], v[40:41], 0, v[4:5]
	s_or_b64 s[12:13], s[0:1], s[12:13]
	v_add_u32_e32 v44, s16, v44
	global_store_dwordx4 v[4:5], v[0:3], off
	s_andn2_b64 exec, exec, s[12:13]
	s_cbranch_execz .LBB0_189

.LBB0_193:
	v_mul_hi_i32 v20, v18, s39
	v_lshrrev_b32_e32 v21, 31, v20
	v_ashrrev_i32_e32 v20, 3, v20
	v_add_u32_e32 v20, v20, v21
	v_readlane_b32 s44, v252, 10
	v_ashrrev_i32_e32 v21, 31, v20
	v_readlane_b32 s58, v252, 24
	v_readlane_b32 s59, v252, 25
	v_mad_u64_u32 v[24:25], s[0:1], v20, s40, v[18:19]
	s_nop 0
	v_lshl_add_u64 v[22:23], v[20:21], 2, s[58:59]
	global_load_dword v21, v[22:23], off
	v_cmp_lt_i32_e64 s[0:1], 31, v24
	v_readlane_b32 s45, v252, 11
	v_readlane_b32 s46, v252, 12
	v_readlane_b32 s47, v252, 13
	v_readlane_b32 s48, v252, 14
	v_readlane_b32 s49, v252, 15
	v_readlane_b32 s50, v252, 16
	v_readlane_b32 s51, v252, 17
	v_readlane_b32 s52, v252, 18
	v_readlane_b32 s53, v252, 19
	v_readlane_b32 s54, v252, 20
	v_readlane_b32 s55, v252, 21
	v_readlane_b32 s56, v252, 22
	v_readlane_b32 s57, v252, 23
	s_and_saveexec_b64 s[8:9], s[0:1]
	s_xor_b64 s[8:9], exec, s[8:9]
	v_subrev_u32_e32 v22, 32, v24
	v_cvt_f64_u32_e32 v[22:23], v22
	s_mov_b32 s22, s24
	v_mul_f64 v[22:23], v[22:23], s[22:23]
	s_andn2_saveexec_b64 s[8:9], s[8:9]
	v_cvt_f64_i32_e32 v[22:23], v24
	v_mul_f64 v[22:23], v[22:23], s[24:25]
	s_or_b64 exec, exec, s[8:9]
	v_rndne_f64_e32 v[24:25], v[22:23]
	v_add_f64 v[26:27], v[22:23], -v[24:25]
	v_mul_f64 v[28:29], v[26:27], s[26:27]
	v_fmac_f64_e32 v[28:29], s[28:29], v[26:27]
	v_fma_f64 v[26:27], s[30:31], v[28:29], v[0:1]
	v_fma_f64 v[26:27], v[28:29], v[26:27], v[2:3]
	v_fma_f64 v[26:27], v[28:29], v[26:27], v[4:5]
	v_fma_f64 v[26:27], v[28:29], v[26:27], v[6:7]
	v_fma_f64 v[26:27], v[28:29], v[26:27], v[8:9]
	v_fma_f64 v[26:27], v[28:29], v[26:27], v[10:11]
	v_fma_f64 v[26:27], v[28:29], v[26:27], v[12:13]
	v_fma_f64 v[26:27], v[28:29], v[26:27], v[14:15]
	v_fma_f64 v[26:27], v[28:29], v[26:27], v[16:17]
	v_fma_f64 v[26:27], v[28:29], v[26:27], 1.0
	v_fma_f64 v[26:27], v[28:29], v[26:27], 1.0
	v_cvt_i32_f64_e32 v24, v[24:25]
	s_waitcnt vmcnt(0)
	v_cvt_f32_i32_e32 v21, v21
	v_ldexp_f64 v[24:25], v[26:27], v24
	v_cmp_nlt_f64_e64 s[8:9], s[34:35], v[22:23]
	v_cmp_ngt_f64_e64 s[10:11], s[36:37], v[22:23]
	s_nop 0
	v_cndmask_b32_e64 v25, v19, v25, s[8:9]
	s_and_b64 s[8:9], s[10:11], s[8:9]
	v_cndmask_b32_e64 v23, 0, v25, s[10:11]
	v_cndmask_b32_e64 v22, 0, v24, s[8:9]
	v_cvt_f32_f64_e32 v22, v[22:23]
	v_mul_f32_e32 v21, v21, v22
	v_mul_f32_e32 v22, 0.15915494, v21
	v_floor_f32_e32 v22, v22
	v_fma_f32 v22, v21, 0.15915494, -v22
	v_sin_f32_e32 v21, v22
	v_cos_f32_e32 v22, v22
	s_and_saveexec_b64 s[8:9], s[0:1]
	s_xor_b64 s[0:1], exec, s[8:9]
	s_cbranch_execz .LBB0_199
	v_lshlrev_b32_e32 v20, 5, v20
	v_sub_u32_e32 v20, v18, v20
	v_subrev_u32_e32 v24, 32, v20
	v_ashrrev_i32_e32 v25, 31, v24
	v_lshlrev_b64 v[24:25], 2, v[24:25]
	v_lshl_add_u64 v[26:27], s[14:15], 0, v[24:25]
	global_store_dword v[26:27], v22, off
	v_lshl_add_u64 v[22:23], s[16:17], 0, v[24:25]
	global_store_dword v[22:23], v21, off
.LBB0_199:
	s_andn2_saveexec_b64 s[0:1], s[0:1]
	s_cbranch_execz .LBB0_192
	v_lshlrev_b32_e32 v20, 4, v20
	v_sub_u32_e32 v20, v18, v20
	v_cvt_pk_bf16_f32 v22, v22, v21
	v_ashrrev_i32_e32 v21, 31, v20
	v_lshl_add_u64 v[20:21], v[20:21], 2, s[18:19]
	global_store_dword v[20:21], v22, off
	s_branch .LBB0_192

.LBB0_203:
	v_or_b32_e32 v4, v1, v0
	v_add_u32_e32 v43, s38, v43
	v_ashrrev_i32_e32 v5, 31, v4
	v_cmp_lt_i32_e32 vcc, s15, v43
	v_lshlrev_b64 v[4:5], 1, v[4:5]
	v_add_u32_e32 v1, s14, v1
	s_or_b64 s[12:13], vcc, s[12:13]
	v_lshl_add_u64 v[6:7], s[8:9], 0, v[4:5]
	v_lshl_add_u64 v[4:5], s[10:11], 0, v[4:5]
	global_store_short v[6:7], v2, off
	global_store_short v[4:5], v2, off
	s_andn2_b64 exec, exec, s[12:13]
	s_cbranch_execnz .LBB0_203

.LBB0_207:
	s_waitcnt lgkmcnt(0)
	global_load_dwordx4 v[14:17], v[4:5], off offset:-3072
	global_load_dwordx4 v[18:21], v[4:5], off offset:-2048
	global_load_dwordx4 v[22:25], v[4:5], off offset:-1024
	global_load_dwordx4 v[26:29], v[4:5], off
	s_waitcnt vmcnt(0)
	v_mul_f32_e32 v30, v15, v15
	v_mul_f32_e32 v31, v19, v19
	v_mul_f32_e32 v32, v23, v23
	v_fmac_f32_e32 v30, v14, v14
	v_fmac_f32_e32 v31, v18, v18
	v_mul_f32_e32 v33, v27, v27
	v_fmac_f32_e32 v32, v22, v22
	v_fmac_f32_e32 v30, v16, v16
	v_fmac_f32_e32 v31, v20, v20
	v_fmac_f32_e32 v33, v26, v26
	v_fmac_f32_e32 v32, v24, v24
	v_fmac_f32_e32 v30, v17, v17
	v_fmac_f32_e32 v31, v21, v21
	v_fmac_f32_e32 v33, v28, v28
	v_fmac_f32_e32 v32, v25, v25
	v_add_f32_e32 v30, v30, v31
	v_fmac_f32_e32 v33, v29, v29
	v_add_f32_e32 v30, v30, v32
	v_add_f32_e32 v30, v30, v33
	ds_bpermute_b32 v31, v7, v30
	v_cvt_pk_bf16_f32 v14, v14, v15
	v_cvt_pk_bf16_f32 v15, v16, v17
	s_waitcnt lgkmcnt(0)
	v_add_f32_e32 v32, v30, v31
	ds_bpermute_b32 v33, v8, v32
	v_lshl_add_u64 v[30:31], s[2:3], 0, v[2:3]
	v_add_co_u32_e32 v30, vcc, s11, v30
	s_waitcnt lgkmcnt(0)
	v_add_f32_e32 v32, v32, v33
	ds_bpermute_b32 v33, v9, v32
	v_addc_co_u32_e32 v31, vcc, 0, v31, vcc
	global_store_dwordx2 v[30:31], v[14:15], off
	v_cvt_pk_bf16_f32 v14, v18, v19
	s_waitcnt lgkmcnt(0)
	v_add_f32_e32 v16, v32, v33
	ds_bpermute_b32 v17, v10, v16
	v_cvt_pk_bf16_f32 v15, v20, v21
	global_store_dwordx2 v[30:31], v[14:15], off offset:512
	s_waitcnt lgkmcnt(0)
	v_add_f32_e32 v18, v16, v17
	ds_bpermute_b32 v19, v11, v18
	v_cvt_pk_bf16_f32 v16, v22, v23
	v_cvt_pk_bf16_f32 v17, v24, v25
	global_store_dwordx2 v[30:31], v[16:17], off offset:1024
	v_cvt_pk_bf16_f32 v16, v26, v27
	s_waitcnt lgkmcnt(0)
	v_add_f32_e32 v14, v18, v19
	ds_bpermute_b32 v15, v12, v14
	v_cvt_pk_bf16_f32 v17, v28, v29
	global_store_dwordx2 v[30:31], v[16:17], off offset:1536
	s_and_saveexec_b64 s[20:21], s[0:1]
	s_cbranch_execz .LBB0_206
	s_waitcnt lgkmcnt(0)
	v_add_f32_e32 v14, v14, v15
	v_fmamk_f32 v14, v14, 0x3a800000, v13
	v_mul_f32_e32 v15, 0x4b800000, v14
	v_cmp_gt_f32_e32 vcc, s22, v14
	s_nop 1
	v_cndmask_b32_e32 v14, v14, v15, vcc
	v_rsq_f32_e32 v16, v14
	v_lshl_add_u64 v[14:15], s[2:3], 0, v[0:1]
	v_mul_f32_e32 v17, 0x45800000, v16
	v_cndmask_b32_e32 v16, v16, v17, vcc
	global_store_dword v[14:15], v16, off
	s_branch .LBB0_206

.LBB0_269:
	s_ashr_i32 s8, s1, 31
	s_lshr_b32 s8, s8, 25
	v_mov_b32_e32 v183, v185
	s_add_i32 s1, s1, s8
	s_ashr_i32 s9, s1, 7
	s_waitcnt lgkmcnt(0)
	v_ashrrev_i32_e32 v1, 5, v183
	v_and_b32_e32 v187, -2, v1
	s_lshl_b32 s8, s9, 14
	v_lshl_add_u32 v2, s9, 3, v187
	s_sub_i32 s30, s11, s8
	v_ashrrev_i32_e32 v3, 31, v2
	v_and_b32_e32 v182, 63, v183
	v_lshlrev_b64 v[2:3], 16, v[2:3]
	s_ashr_i32 s31, s30, 31
	s_xor_b64 s[22:23], s[22:23], -1
	v_ashrrev_i32_e32 v0, 3, v183
	v_lshl_add_u64 v[2:3], s[12:13], 0, v[2:3]
	v_lshlrev_b32_e32 v192, 4, v182
	s_lshl_b64 s[30:31], s[30:31], 11
	v_lshlrev_b32_e32 v1, 3, v183
	v_lshl_add_u64 v[178:179], v[2:3], 0, v[192:193]
	s_add_u32 s30, s26, s30
	v_and_b32_e32 v1, 56, v1
	v_lshlrev_b32_e32 v2, 11, v0
	s_addc_u32 s31, s27, s31
	v_lshl_or_b32 v176, v1, 1, v2
	v_mov_b32_e32 v177, v193
	s_andn2_b64 vcc, exec, s[22:23]
	v_lshl_add_u64 v[180:181], s[30:31], 0, v[176:177]
	s_barrier
	s_cbranch_vccnz .LBB0_271
	v_add_co_u32_e32 v2, vcc, 0x10000, v180
	s_nop 1
	v_addc_co_u32_e32 v3, vcc, 0, v181, vcc
	v_add_co_u32_e32 v4, vcc, 0x20000, v180
	s_nop 1
	v_addc_co_u32_e32 v5, vcc, 0, v181, vcc
	s_waitcnt vmcnt(0)
	global_load_dwordx4 v[156:159], v[2:3], off
	global_load_dwordx4 v[164:167], v[4:5], off
	v_add_co_u32_e32 v2, vcc, 0x30000, v180
	global_load_dwordx4 v[160:163], v[178:179], off
	global_load_dwordx4 v[144:147], v[178:179], off offset:1024
	global_load_dwordx4 v[132:135], v[178:179], off offset:2048
	global_load_dwordx4 v[128:131], v[178:179], off offset:3072
	v_addc_co_u32_e32 v3, vcc, 0, v181, vcc
	v_add_co_u32_e32 v4, vcc, 0x10000, v178
	s_nop 1
	v_addc_co_u32_e32 v5, vcc, 0, v179, vcc
	global_load_dwordx4 v[172:175], v[2:3], off
	global_load_dwordx4 v[152:155], v[4:5], off
	global_load_dwordx4 v[148:151], v[4:5], off offset:1024
	global_load_dwordx4 v[140:143], v[4:5], off offset:2048
	global_load_dwordx4 v[168:171], v[180:181], off
	global_load_dwordx4 v[136:139], v[4:5], off offset:3072
.LBB0_271:
	s_movk_i32 s1, 0x90
	v_mul_lo_u32 v0, v0, s1
	v_lshl_add_u32 v189, v1, 1, v0
	s_waitcnt vmcnt(0) lgkmcnt(0)
	ds_write_b128 v189, v[168:171]
	ds_write_b128 v189, v[156:159] offset:4608
	ds_write_b128 v189, v[164:167] offset:9216
	ds_write_b128 v189, v[172:175] offset:13824
	v_add_co_u32_e32 v156, vcc, 0x10000, v180
	v_lshrrev_b32_e32 v186, 5, v182
	s_nop 0
	v_addc_co_u32_e32 v157, vcc, 0, v181, vcc
	v_add_co_u32_e32 v164, vcc, 0x20000, v180
	v_and_b32_e32 v184, 31, v183
	s_nop 0
	v_addc_co_u32_e32 v165, vcc, 0, v181, vcc
	v_add_co_u32_e32 v172, vcc, 0x30000, v180
	global_load_dwordx4 v[166:169], v[156:157], off offset:128
	global_load_dwordx4 v[198:201], v[164:165], off offset:128
	v_addc_co_u32_e32 v173, vcc, 0, v181, vcc
	global_load_dwordx4 v[202:205], v[180:181], off offset:128
	global_load_dwordx4 v[206:209], v[172:173], off offset:128
	v_lshlrev_b32_e32 v0, 4, v186
	v_mad_u32_u24 v188, v184, s1, v0
	s_waitcnt lgkmcnt(0)
	s_barrier
	ds_read_b128 v[0:3], v188
	ds_read_b128 v[210:213], v188 offset:32
	ds_read_b128 v[4:7], v188 offset:4608
	ds_read_b128 v[234:237], v188 offset:4640
	ds_read_b128 v[8:11], v188 offset:9216
	ds_read_b128 v[238:241], v188 offset:9248
	ds_read_b128 v[12:15], v188 offset:13824
	ds_read_b128 v[242:245], v188 offset:13856
	s_setprio 2
	s_movk_i32 s1, 0x1000
	s_waitcnt lgkmcnt(7)
	v_mfma_f32_32x32x16_bf16 v[112:127], v[160:163], v[0:3], 0
	s_waitcnt lgkmcnt(5)
	v_mfma_f32_32x32x16_bf16 v[80:95], v[160:163], v[4:7], 0
	s_waitcnt lgkmcnt(3)
	v_mfma_f32_32x32x16_bf16 v[48:63], v[160:163], v[8:11], 0
	s_waitcnt lgkmcnt(1)
	v_mfma_f32_32x32x16_bf16 v[16:31], v[160:163], v[12:15], 0
	v_add_co_u32_e32 v162, vcc, s1, v178
	s_mov_b32 s1, 0x11000
	s_nop 0
	v_addc_co_u32_e32 v163, vcc, 0, v179, vcc
	v_add_co_u32_e32 v170, vcc, s1, v178
	global_load_dwordx4 v[158:161], v[162:163], off
	s_nop 0
	v_addc_co_u32_e32 v171, vcc, 0, v179, vcc
	v_mfma_f32_32x32x16_bf16 v[96:111], v[152:155], v[0:3], 0
	v_mfma_f32_32x32x16_bf16 v[64:79], v[152:155], v[4:7], 0
	v_mfma_f32_32x32x16_bf16 v[32:47], v[152:155], v[8:11], 0
	v_mfma_f32_32x32x16_bf16 v[0:15], v[152:155], v[12:15], 0
	global_load_dwordx4 v[152:155], v[170:171], off
	s_setprio 0
	ds_read_b128 v[246:249], v188 offset:64
	ds_read_b128 v[214:217], v188 offset:4672
	ds_read_b128 v[228:231], v188 offset:9280
	ds_read_b128 v[218:221], v188 offset:13888
	s_setprio 2
	v_mfma_f32_32x32x16_bf16 v[112:127], v[144:147], v[210:213], v[112:127]
	v_mfma_f32_32x32x16_bf16 v[80:95], v[144:147], v[234:237], v[80:95]
	v_mfma_f32_32x32x16_bf16 v[48:63], v[144:147], v[238:241], v[48:63]
	s_waitcnt lgkmcnt(4)
	v_mfma_f32_32x32x16_bf16 v[16:31], v[144:147], v[242:245], v[16:31]
	v_mfma_f32_32x32x16_bf16 v[96:111], v[148:151], v[210:213], v[96:111]
	global_load_dwordx4 v[144:147], v[162:163], off offset:1024
	global_load_dwordx4 v[210:213], v[170:171], off offset:1024
	v_mfma_f32_32x32x16_bf16 v[64:79], v[148:151], v[234:237], v[64:79]
	v_mfma_f32_32x32x16_bf16 v[32:47], v[148:151], v[238:241], v[32:47]
	v_mfma_f32_32x32x16_bf16 v[0:15], v[148:151], v[242:245], v[0:15]
	s_setprio 0
	ds_read_b128 v[148:151], v188 offset:96
	ds_read_b128 v[234:237], v188 offset:4704
	ds_read_b128 v[238:241], v188 offset:9312
	ds_read_b128 v[242:245], v188 offset:13920
	s_setprio 2
	s_waitcnt lgkmcnt(7)
	v_mfma_f32_32x32x16_bf16 v[112:127], v[132:135], v[246:249], v[112:127]
	s_waitcnt lgkmcnt(6)
	v_mfma_f32_32x32x16_bf16 v[80:95], v[132:135], v[214:217], v[80:95]
	s_waitcnt lgkmcnt(5)
	v_mfma_f32_32x32x16_bf16 v[48:63], v[132:135], v[228:231], v[48:63]
	s_waitcnt lgkmcnt(4)
	v_mfma_f32_32x32x16_bf16 v[16:31], v[132:135], v[218:221], v[16:31]
	v_mfma_f32_32x32x16_bf16 v[64:79], v[140:143], v[214:217], v[64:79]
	global_load_dwordx4 v[132:135], v[162:163], off offset:2048
	global_load_dwordx4 v[214:217], v[170:171], off offset:2048
	v_mfma_f32_32x32x16_bf16 v[96:111], v[140:143], v[246:249], v[96:111]
	v_mfma_f32_32x32x16_bf16 v[32:47], v[140:143], v[228:231], v[32:47]
	v_mfma_f32_32x32x16_bf16 v[0:15], v[140:143], v[218:221], v[0:15]
	s_setprio 0
	s_setprio 2
	s_waitcnt lgkmcnt(3)
	v_mfma_f32_32x32x16_bf16 v[112:127], v[128:131], v[148:151], v[112:127]
	s_waitcnt lgkmcnt(2)
	v_mfma_f32_32x32x16_bf16 v[80:95], v[128:131], v[234:237], v[80:95]
	s_waitcnt lgkmcnt(1)
	v_mfma_f32_32x32x16_bf16 v[48:63], v[128:131], v[238:241], v[48:63]
	s_waitcnt lgkmcnt(0)
	v_mfma_f32_32x32x16_bf16 v[16:31], v[128:131], v[242:245], v[16:31]
	global_load_dwordx4 v[128:131], v[162:163], off offset:3072
	global_load_dwordx4 v[140:143], v[170:171], off offset:3072
	v_mfma_f32_32x32x16_bf16 v[96:111], v[136:139], v[148:151], v[96:111]
	v_mfma_f32_32x32x16_bf16 v[64:79], v[136:139], v[234:237], v[64:79]
	v_mfma_f32_32x32x16_bf16 v[32:47], v[136:139], v[238:241], v[32:47]
	v_mfma_f32_32x32x16_bf16 v[0:15], v[136:139], v[242:245], v[0:15]
	s_setprio 0
	s_waitcnt vmcnt(9)
	ds_write_b128 v189, v[202:205] offset:18432
	ds_write_b128 v189, v[166:169] offset:23040
	ds_write_b128 v189, v[198:201] offset:27648
	s_waitcnt vmcnt(8)
	ds_write_b128 v189, v[206:209] offset:32256
	global_load_dwordx4 v[136:139], v[156:157], off offset:256
	global_load_dwordx4 v[148:151], v[164:165], off offset:256
	global_load_dwordx4 v[166:169], v[180:181], off offset:256
	global_load_dwordx4 v[198:201], v[172:173], off offset:256
	s_waitcnt lgkmcnt(0)
	s_barrier
	ds_read_b128 v[202:205], v188 offset:18432
	ds_read_b128 v[206:209], v188 offset:18464
	ds_read_b128 v[218:221], v188 offset:23040
	ds_read_b128 v[228:231], v188 offset:23072
	ds_read_b128 v[234:237], v188 offset:27648
	ds_read_b128 v[238:241], v188 offset:27680
	ds_read_b128 v[242:245], v188 offset:32256
	ds_read_b128 v[246:249], v188 offset:32288
	s_setprio 2
	s_movk_i32 s1, 0x2000
	v_add_co_u32_e32 v162, vcc, s1, v178
	s_mov_b32 s1, 0x12000
	s_nop 0
	v_addc_co_u32_e32 v163, vcc, 0, v179, vcc
	v_add_co_u32_e32 v170, vcc, s1, v178
	s_waitcnt vmcnt(11) lgkmcnt(7)
	v_mfma_f32_32x32x16_bf16 v[112:127], v[158:161], v[202:205], v[112:127]
	v_addc_co_u32_e32 v171, vcc, 0, v179, vcc
	s_waitcnt lgkmcnt(5)
	v_mfma_f32_32x32x16_bf16 v[80:95], v[158:161], v[218:221], v[80:95]
	s_waitcnt lgkmcnt(3)
	v_mfma_f32_32x32x16_bf16 v[48:63], v[158:161], v[234:237], v[48:63]
	s_waitcnt lgkmcnt(1)
	v_mfma_f32_32x32x16_bf16 v[16:31], v[158:161], v[242:245], v[16:31]
	s_waitcnt vmcnt(10)
	v_mfma_f32_32x32x16_bf16 v[96:111], v[152:155], v[202:205], v[96:111]
	global_load_dwordx4 v[158:161], v[162:163], off
	global_load_dwordx4 v[202:205], v[170:171], off
	v_mfma_f32_32x32x16_bf16 v[64:79], v[152:155], v[218:221], v[64:79]
	v_mfma_f32_32x32x16_bf16 v[32:47], v[152:155], v[234:237], v[32:47]
	v_mfma_f32_32x32x16_bf16 v[0:15], v[152:155], v[242:245], v[0:15]
	s_setprio 0
	ds_read_b128 v[152:155], v188 offset:18496
	ds_read_b128 v[218:221], v188 offset:23104
	ds_read_b128 v[234:237], v188 offset:27712
	ds_read_b128 v[242:245], v188 offset:32320
	s_setprio 2
	s_waitcnt vmcnt(11)
	v_mfma_f32_32x32x16_bf16 v[112:127], v[144:147], v[206:209], v[112:127]
	v_mfma_f32_32x32x16_bf16 v[80:95], v[144:147], v[228:231], v[80:95]
	v_mfma_f32_32x32x16_bf16 v[48:63], v[144:147], v[238:241], v[48:63]
	s_waitcnt lgkmcnt(4)
	v_mfma_f32_32x32x16_bf16 v[16:31], v[144:147], v[246:249], v[16:31]
	s_waitcnt vmcnt(10)
	v_mfma_f32_32x32x16_bf16 v[96:111], v[210:213], v[206:209], v[96:111]
	global_load_dwordx4 v[144:147], v[162:163], off offset:1024
	global_load_dwordx4 v[206:209], v[170:171], off offset:1024
	v_mfma_f32_32x32x16_bf16 v[64:79], v[210:213], v[228:231], v[64:79]
	v_mfma_f32_32x32x16_bf16 v[32:47], v[210:213], v[238:241], v[32:47]
	v_mfma_f32_32x32x16_bf16 v[0:15], v[210:213], v[246:249], v[0:15]
	s_setprio 0
	ds_read_b128 v[210:213], v188 offset:18528
	ds_read_b128 v[228:231], v188 offset:23136
	ds_read_b128 v[238:241], v188 offset:27744
	ds_read_b128 v[246:249], v188 offset:32352
	s_setprio 2
	s_waitcnt vmcnt(11) lgkmcnt(7)
	v_mfma_f32_32x32x16_bf16 v[112:127], v[132:135], v[152:155], v[112:127]
	s_waitcnt lgkmcnt(6)
	v_mfma_f32_32x32x16_bf16 v[80:95], v[132:135], v[218:221], v[80:95]
	s_waitcnt lgkmcnt(5)
	v_mfma_f32_32x32x16_bf16 v[48:63], v[132:135], v[234:237], v[48:63]
	s_waitcnt lgkmcnt(4)
	v_mfma_f32_32x32x16_bf16 v[16:31], v[132:135], v[242:245], v[16:31]
	s_waitcnt vmcnt(10)
	v_mfma_f32_32x32x16_bf16 v[96:111], v[214:217], v[152:155], v[96:111]
	global_load_dwordx4 v[132:135], v[162:163], off offset:2048
	global_load_dwordx4 v[152:155], v[170:171], off offset:2048
	v_mfma_f32_32x32x16_bf16 v[64:79], v[214:217], v[218:221], v[64:79]
	v_mfma_f32_32x32x16_bf16 v[32:47], v[214:217], v[234:237], v[32:47]
	v_mfma_f32_32x32x16_bf16 v[0:15], v[214:217], v[242:245], v[0:15]
	s_setprio 0
	s_setprio 2
	s_waitcnt vmcnt(11) lgkmcnt(3)
	v_mfma_f32_32x32x16_bf16 v[112:127], v[128:131], v[210:213], v[112:127]
	s_waitcnt lgkmcnt(2)
	v_mfma_f32_32x32x16_bf16 v[80:95], v[128:131], v[228:231], v[80:95]
	s_waitcnt lgkmcnt(1)
	v_mfma_f32_32x32x16_bf16 v[48:63], v[128:131], v[238:241], v[48:63]
	s_waitcnt lgkmcnt(0)
	v_mfma_f32_32x32x16_bf16 v[16:31], v[128:131], v[246:249], v[16:31]
	s_waitcnt vmcnt(10)
	v_mfma_f32_32x32x16_bf16 v[96:111], v[140:143], v[210:213], v[96:111]
	global_load_dwordx4 v[128:131], v[162:163], off offset:3072
	global_load_dwordx4 v[210:213], v[170:171], off offset:3072
	v_mfma_f32_32x32x16_bf16 v[64:79], v[140:143], v[228:231], v[64:79]
	v_mfma_f32_32x32x16_bf16 v[32:47], v[140:143], v[238:241], v[32:47]
	v_mfma_f32_32x32x16_bf16 v[0:15], v[140:143], v[246:249], v[0:15]
	s_setprio 0
	s_waitcnt vmcnt(9)
	ds_write_b128 v189, v[166:169]
	ds_write_b128 v189, v[136:139] offset:4608
	ds_write_b128 v189, v[148:151] offset:9216
	s_waitcnt vmcnt(8)
	ds_write_b128 v189, v[198:201] offset:13824
	global_load_dwordx4 v[136:139], v[164:165], off offset:384
	global_load_dwordx4 v[140:143], v[156:157], off offset:384
	global_load_dwordx4 v[148:151], v[172:173], off offset:384
	global_load_dwordx4 v[166:169], v[180:181], off offset:384
	s_waitcnt lgkmcnt(0)
	s_barrier
	ds_read_b128 v[198:201], v188
	ds_read_b128 v[214:217], v188 offset:32
	ds_read_b128 v[218:221], v188 offset:4608
	ds_read_b128 v[228:231], v188 offset:4640
	ds_read_b128 v[234:237], v188 offset:9216
	ds_read_b128 v[238:241], v188 offset:9248
	ds_read_b128 v[242:245], v188 offset:13824
	ds_read_b128 v[246:249], v188 offset:13856
	s_setprio 2
	s_movk_i32 s1, 0x3000
	v_add_co_u32_e32 v162, vcc, s1, v178
	s_mov_b32 s1, 0x13000
	s_nop 0
	v_addc_co_u32_e32 v163, vcc, 0, v179, vcc
	v_add_co_u32_e32 v170, vcc, s1, v178
	s_waitcnt vmcnt(11) lgkmcnt(7)
	v_mfma_f32_32x32x16_bf16 v[112:127], v[158:161], v[198:201], v[112:127]
	v_addc_co_u32_e32 v171, vcc, 0, v179, vcc
	s_waitcnt lgkmcnt(5)
	v_mfma_f32_32x32x16_bf16 v[80:95], v[158:161], v[218:221], v[80:95]
	s_waitcnt lgkmcnt(3)
	v_mfma_f32_32x32x16_bf16 v[48:63], v[158:161], v[234:237], v[48:63]
	s_waitcnt lgkmcnt(1)
	v_mfma_f32_32x32x16_bf16 v[16:31], v[158:161], v[242:245], v[16:31]
	s_waitcnt vmcnt(10)
	v_mfma_f32_32x32x16_bf16 v[96:111], v[202:205], v[198:201], v[96:111]
	global_load_dwordx4 v[158:161], v[162:163], off
	global_load_dwordx4 v[198:201], v[170:171], off
	v_mfma_f32_32x32x16_bf16 v[64:79], v[202:205], v[218:221], v[64:79]
	v_mfma_f32_32x32x16_bf16 v[32:47], v[202:205], v[234:237], v[32:47]
	v_mfma_f32_32x32x16_bf16 v[0:15], v[202:205], v[242:245], v[0:15]
	s_setprio 0
	ds_read_b128 v[202:205], v188 offset:64
	ds_read_b128 v[218:221], v188 offset:4672
	ds_read_b128 v[234:237], v188 offset:9280
	ds_read_b128 v[242:245], v188 offset:13888
	s_setprio 2
	s_waitcnt vmcnt(11)
	v_mfma_f32_32x32x16_bf16 v[112:127], v[144:147], v[214:217], v[112:127]
	v_mfma_f32_32x32x16_bf16 v[80:95], v[144:147], v[228:231], v[80:95]
	v_mfma_f32_32x32x16_bf16 v[48:63], v[144:147], v[238:241], v[48:63]
	s_waitcnt lgkmcnt(4)
	v_mfma_f32_32x32x16_bf16 v[16:31], v[144:147], v[246:249], v[16:31]
	s_waitcnt vmcnt(10)
	v_mfma_f32_32x32x16_bf16 v[96:111], v[206:209], v[214:217], v[96:111]
	global_load_dwordx4 v[144:147], v[162:163], off offset:1024
	global_load_dwordx4 v[214:217], v[170:171], off offset:1024
	v_mfma_f32_32x32x16_bf16 v[64:79], v[206:209], v[228:231], v[64:79]
	v_mfma_f32_32x32x16_bf16 v[32:47], v[206:209], v[238:241], v[32:47]
	v_mfma_f32_32x32x16_bf16 v[0:15], v[206:209], v[246:249], v[0:15]
	s_setprio 0
	ds_read_b128 v[206:209], v188 offset:96
	ds_read_b128 v[228:231], v188 offset:4704
	ds_read_b128 v[238:241], v188 offset:9312
	ds_read_b128 v[246:249], v188 offset:13920
	s_setprio 2
	s_waitcnt vmcnt(11) lgkmcnt(7)
	v_mfma_f32_32x32x16_bf16 v[112:127], v[132:135], v[202:205], v[112:127]
	s_waitcnt lgkmcnt(6)
	v_mfma_f32_32x32x16_bf16 v[80:95], v[132:135], v[218:221], v[80:95]
	s_waitcnt lgkmcnt(5)
	v_mfma_f32_32x32x16_bf16 v[48:63], v[132:135], v[234:237], v[48:63]
	s_waitcnt lgkmcnt(4)
	v_mfma_f32_32x32x16_bf16 v[16:31], v[132:135], v[242:245], v[16:31]
	s_waitcnt vmcnt(10)
	v_mfma_f32_32x32x16_bf16 v[96:111], v[152:155], v[202:205], v[96:111]
	global_load_dwordx4 v[132:135], v[162:163], off offset:2048
	global_load_dwordx4 v[202:205], v[170:171], off offset:2048
	v_mfma_f32_32x32x16_bf16 v[64:79], v[152:155], v[218:221], v[64:79]
	v_mfma_f32_32x32x16_bf16 v[32:47], v[152:155], v[234:237], v[32:47]
	v_mfma_f32_32x32x16_bf16 v[0:15], v[152:155], v[242:245], v[0:15]
	s_setprio 0
	s_setprio 2
	s_waitcnt vmcnt(11) lgkmcnt(3)
	v_mfma_f32_32x32x16_bf16 v[112:127], v[128:131], v[206:209], v[112:127]
	s_waitcnt lgkmcnt(2)
	v_mfma_f32_32x32x16_bf16 v[80:95], v[128:131], v[228:231], v[80:95]
	s_waitcnt lgkmcnt(1)
	v_mfma_f32_32x32x16_bf16 v[48:63], v[128:131], v[238:241], v[48:63]
	s_waitcnt lgkmcnt(0)
	v_mfma_f32_32x32x16_bf16 v[16:31], v[128:131], v[246:249], v[16:31]
	global_load_dwordx4 v[128:131], v[162:163], off offset:3072
	global_load_dwordx4 v[152:155], v[170:171], off offset:3072
	s_waitcnt vmcnt(12)
	v_mfma_f32_32x32x16_bf16 v[96:111], v[210:213], v[206:209], v[96:111]
	v_mfma_f32_32x32x16_bf16 v[64:79], v[210:213], v[228:231], v[64:79]
	v_mfma_f32_32x32x16_bf16 v[32:47], v[210:213], v[238:241], v[32:47]
	v_mfma_f32_32x32x16_bf16 v[0:15], v[210:213], v[246:249], v[0:15]
	s_setprio 0
	s_waitcnt vmcnt(8)
	ds_write_b128 v189, v[166:169] offset:18432
	ds_write_b128 v189, v[140:143] offset:23040
	ds_write_b128 v189, v[136:139] offset:27648
	ds_write_b128 v189, v[148:151] offset:32256
	global_load_dwordx4 v[136:139], v[156:157], off offset:512
	global_load_dwordx4 v[140:143], v[164:165], off offset:512
	global_load_dwordx4 v[148:151], v[180:181], off offset:512
	global_load_dwordx4 v[166:169], v[172:173], off offset:512
	s_waitcnt lgkmcnt(0)
	s_barrier
	ds_read_b128 v[206:209], v188 offset:18432
	ds_read_b128 v[210:213], v188 offset:18464
	ds_read_b128 v[218:221], v188 offset:23040
	ds_read_b128 v[228:231], v188 offset:23072
	ds_read_b128 v[234:237], v188 offset:27648
	ds_read_b128 v[238:241], v188 offset:27680
	ds_read_b128 v[242:245], v188 offset:32256
	ds_read_b128 v[246:249], v188 offset:32288
	s_setprio 2
	s_movk_i32 s1, 0x4000
	v_add_co_u32_e32 v162, vcc, s1, v178
	s_mov_b32 s1, 0x14000
	s_nop 0
	v_addc_co_u32_e32 v163, vcc, 0, v179, vcc
	v_add_co_u32_e32 v170, vcc, s1, v178
	s_waitcnt vmcnt(11) lgkmcnt(7)
	v_mfma_f32_32x32x16_bf16 v[112:127], v[158:161], v[206:209], v[112:127]
	v_addc_co_u32_e32 v171, vcc, 0, v179, vcc
	s_waitcnt lgkmcnt(5)
	v_mfma_f32_32x32x16_bf16 v[80:95], v[158:161], v[218:221], v[80:95]
	s_waitcnt lgkmcnt(3)
	v_mfma_f32_32x32x16_bf16 v[48:63], v[158:161], v[234:237], v[48:63]
	s_waitcnt lgkmcnt(1)
	v_mfma_f32_32x32x16_bf16 v[16:31], v[158:161], v[242:245], v[16:31]
	s_waitcnt vmcnt(10)
	v_mfma_f32_32x32x16_bf16 v[96:111], v[198:201], v[206:209], v[96:111]
	global_load_dwordx4 v[158:161], v[162:163], off
	global_load_dwordx4 v[206:209], v[170:171], off
	v_mfma_f32_32x32x16_bf16 v[64:79], v[198:201], v[218:221], v[64:79]
	v_mfma_f32_32x32x16_bf16 v[32:47], v[198:201], v[234:237], v[32:47]
	v_mfma_f32_32x32x16_bf16 v[0:15], v[198:201], v[242:245], v[0:15]
	s_setprio 0
	ds_read_b128 v[198:201], v188 offset:18496
	ds_read_b128 v[218:221], v188 offset:23104
	ds_read_b128 v[234:237], v188 offset:27712
	ds_read_b128 v[242:245], v188 offset:32320
	s_setprio 2
	s_waitcnt vmcnt(11)
	v_mfma_f32_32x32x16_bf16 v[112:127], v[144:147], v[210:213], v[112:127]
	v_mfma_f32_32x32x16_bf16 v[80:95], v[144:147], v[228:231], v[80:95]
	v_mfma_f32_32x32x16_bf16 v[48:63], v[144:147], v[238:241], v[48:63]
	s_waitcnt lgkmcnt(4)
	v_mfma_f32_32x32x16_bf16 v[16:31], v[144:147], v[246:249], v[16:31]
	s_waitcnt vmcnt(10)
	v_mfma_f32_32x32x16_bf16 v[96:111], v[214:217], v[210:213], v[96:111]
	global_load_dwordx4 v[144:147], v[162:163], off offset:1024
	global_load_dwordx4 v[210:213], v[170:171], off offset:1024
	v_mfma_f32_32x32x16_bf16 v[64:79], v[214:217], v[228:231], v[64:79]
	v_mfma_f32_32x32x16_bf16 v[32:47], v[214:217], v[238:241], v[32:47]
	v_mfma_f32_32x32x16_bf16 v[0:15], v[214:217], v[246:249], v[0:15]
	s_setprio 0
	ds_read_b128 v[214:217], v188 offset:18528
	ds_read_b128 v[228:231], v188 offset:23136
	ds_read_b128 v[238:241], v188 offset:27744
	ds_read_b128 v[246:249], v188 offset:32352
	s_setprio 2
	s_waitcnt vmcnt(11) lgkmcnt(7)
	v_mfma_f32_32x32x16_bf16 v[112:127], v[132:135], v[198:201], v[112:127]
	s_waitcnt lgkmcnt(6)
	v_mfma_f32_32x32x16_bf16 v[80:95], v[132:135], v[218:221], v[80:95]
	s_waitcnt lgkmcnt(5)
	v_mfma_f32_32x32x16_bf16 v[48:63], v[132:135], v[234:237], v[48:63]
	s_waitcnt lgkmcnt(4)
	v_mfma_f32_32x32x16_bf16 v[16:31], v[132:135], v[242:245], v[16:31]
	s_waitcnt vmcnt(10)
	v_mfma_f32_32x32x16_bf16 v[96:111], v[202:205], v[198:201], v[96:111]
	global_load_dwordx4 v[132:135], v[162:163], off offset:2048
	global_load_dwordx4 v[198:201], v[170:171], off offset:2048
	v_mfma_f32_32x32x16_bf16 v[64:79], v[202:205], v[218:221], v[64:79]
	v_mfma_f32_32x32x16_bf16 v[32:47], v[202:205], v[234:237], v[32:47]
	v_mfma_f32_32x32x16_bf16 v[0:15], v[202:205], v[242:245], v[0:15]
	s_setprio 0
	s_setprio 2
	s_waitcnt vmcnt(11) lgkmcnt(3)
	v_mfma_f32_32x32x16_bf16 v[112:127], v[128:131], v[214:217], v[112:127]
	s_waitcnt lgkmcnt(2)
	v_mfma_f32_32x32x16_bf16 v[80:95], v[128:131], v[228:231], v[80:95]
	s_waitcnt lgkmcnt(1)
	v_mfma_f32_32x32x16_bf16 v[48:63], v[128:131], v[238:241], v[48:63]
	s_waitcnt lgkmcnt(0)
	v_mfma_f32_32x32x16_bf16 v[16:31], v[128:131], v[246:249], v[16:31]
	global_load_dwordx4 v[128:131], v[162:163], off offset:3072
	global_load_dwordx4 v[202:205], v[170:171], off offset:3072
	s_waitcnt vmcnt(12)
	v_mfma_f32_32x32x16_bf16 v[96:111], v[152:155], v[214:217], v[96:111]
	v_mfma_f32_32x32x16_bf16 v[64:79], v[152:155], v[228:231], v[64:79]
	v_mfma_f32_32x32x16_bf16 v[32:47], v[152:155], v[238:241], v[32:47]
	v_mfma_f32_32x32x16_bf16 v[0:15], v[152:155], v[246:249], v[0:15]
	s_setprio 0
	s_waitcnt vmcnt(9)
	ds_write_b128 v189, v[148:151]
	ds_write_b128 v189, v[136:139] offset:4608
	ds_write_b128 v189, v[140:143] offset:9216
	s_waitcnt vmcnt(8)
	ds_write_b128 v189, v[166:169] offset:13824
	global_load_dwordx4 v[136:139], v[164:165], off offset:640
	global_load_dwordx4 v[140:143], v[156:157], off offset:640
	global_load_dwordx4 v[148:151], v[172:173], off offset:640
	global_load_dwordx4 v[152:155], v[180:181], off offset:640
	s_waitcnt lgkmcnt(0)
	s_barrier
	ds_read_b128 v[166:169], v188
	ds_read_b128 v[214:217], v188 offset:32
	ds_read_b128 v[218:221], v188 offset:4608
	ds_read_b128 v[228:231], v188 offset:4640
	ds_read_b128 v[234:237], v188 offset:9216
	ds_read_b128 v[238:241], v188 offset:9248
	ds_read_b128 v[242:245], v188 offset:13824
	ds_read_b128 v[246:249], v188 offset:13856
	s_setprio 2
	s_movk_i32 s1, 0x5000
	v_add_co_u32_e32 v162, vcc, s1, v178
	s_mov_b32 s1, 0x15000
	s_nop 0
	v_addc_co_u32_e32 v163, vcc, 0, v179, vcc
	v_add_co_u32_e32 v170, vcc, s1, v178
	s_waitcnt vmcnt(11) lgkmcnt(7)
	v_mfma_f32_32x32x16_bf16 v[112:127], v[158:161], v[166:169], v[112:127]
	v_addc_co_u32_e32 v171, vcc, 0, v179, vcc
	s_waitcnt lgkmcnt(5)
	v_mfma_f32_32x32x16_bf16 v[80:95], v[158:161], v[218:221], v[80:95]
	s_waitcnt lgkmcnt(3)
	v_mfma_f32_32x32x16_bf16 v[48:63], v[158:161], v[234:237], v[48:63]
	s_waitcnt lgkmcnt(1)
	v_mfma_f32_32x32x16_bf16 v[16:31], v[158:161], v[242:245], v[16:31]
	s_waitcnt vmcnt(10)
	v_mfma_f32_32x32x16_bf16 v[96:111], v[206:209], v[166:169], v[96:111]
	global_load_dwordx4 v[158:161], v[162:163], off
	global_load_dwordx4 v[166:169], v[170:171], off
	v_mfma_f32_32x32x16_bf16 v[64:79], v[206:209], v[218:221], v[64:79]
	v_mfma_f32_32x32x16_bf16 v[32:47], v[206:209], v[234:237], v[32:47]
	v_mfma_f32_32x32x16_bf16 v[0:15], v[206:209], v[242:245], v[0:15]
	s_setprio 0
	ds_read_b128 v[206:209], v188 offset:64
	ds_read_b128 v[218:221], v188 offset:4672
	ds_read_b128 v[234:237], v188 offset:9280
	ds_read_b128 v[242:245], v188 offset:13888
	s_setprio 2
	s_waitcnt vmcnt(11)
	v_mfma_f32_32x32x16_bf16 v[112:127], v[144:147], v[214:217], v[112:127]
	v_mfma_f32_32x32x16_bf16 v[80:95], v[144:147], v[228:231], v[80:95]
	v_mfma_f32_32x32x16_bf16 v[48:63], v[144:147], v[238:241], v[48:63]
	s_waitcnt lgkmcnt(4)
	v_mfma_f32_32x32x16_bf16 v[16:31], v[144:147], v[246:249], v[16:31]
	s_waitcnt vmcnt(10)
	v_mfma_f32_32x32x16_bf16 v[96:111], v[210:213], v[214:217], v[96:111]
	global_load_dwordx4 v[144:147], v[162:163], off offset:1024
	global_load_dwordx4 v[214:217], v[170:171], off offset:1024
	v_mfma_f32_32x32x16_bf16 v[64:79], v[210:213], v[228:231], v[64:79]
	v_mfma_f32_32x32x16_bf16 v[32:47], v[210:213], v[238:241], v[32:47]
	v_mfma_f32_32x32x16_bf16 v[0:15], v[210:213], v[246:249], v[0:15]
	s_setprio 0
	ds_read_b128 v[210:213], v188 offset:96
	ds_read_b128 v[228:231], v188 offset:4704
	ds_read_b128 v[238:241], v188 offset:9312
	ds_read_b128 v[246:249], v188 offset:13920
	s_setprio 2
	s_waitcnt vmcnt(11) lgkmcnt(7)
	v_mfma_f32_32x32x16_bf16 v[112:127], v[132:135], v[206:209], v[112:127]
	s_waitcnt lgkmcnt(6)
	v_mfma_f32_32x32x16_bf16 v[80:95], v[132:135], v[218:221], v[80:95]
	s_waitcnt lgkmcnt(5)
	v_mfma_f32_32x32x16_bf16 v[48:63], v[132:135], v[234:237], v[48:63]
	s_waitcnt lgkmcnt(4)
	v_mfma_f32_32x32x16_bf16 v[16:31], v[132:135], v[242:245], v[16:31]
	s_waitcnt vmcnt(10)
	v_mfma_f32_32x32x16_bf16 v[96:111], v[198:201], v[206:209], v[96:111]
	global_load_dwordx4 v[132:135], v[162:163], off offset:2048
	global_load_dwordx4 v[206:209], v[170:171], off offset:2048
	v_mfma_f32_32x32x16_bf16 v[64:79], v[198:201], v[218:221], v[64:79]
	v_mfma_f32_32x32x16_bf16 v[32:47], v[198:201], v[234:237], v[32:47]
	v_mfma_f32_32x32x16_bf16 v[0:15], v[198:201], v[242:245], v[0:15]
	s_setprio 0
	s_setprio 2
	s_waitcnt vmcnt(11) lgkmcnt(3)
	v_mfma_f32_32x32x16_bf16 v[112:127], v[128:131], v[210:213], v[112:127]
	s_waitcnt lgkmcnt(2)
	v_mfma_f32_32x32x16_bf16 v[80:95], v[128:131], v[228:231], v[80:95]
	s_waitcnt lgkmcnt(1)
	v_mfma_f32_32x32x16_bf16 v[48:63], v[128:131], v[238:241], v[48:63]
	s_waitcnt lgkmcnt(0)
	v_mfma_f32_32x32x16_bf16 v[16:31], v[128:131], v[246:249], v[16:31]
	global_load_dwordx4 v[128:131], v[162:163], off offset:3072
	global_load_dwordx4 v[198:201], v[170:171], off offset:3072
	s_waitcnt vmcnt(12)
	v_mfma_f32_32x32x16_bf16 v[96:111], v[202:205], v[210:213], v[96:111]
	v_mfma_f32_32x32x16_bf16 v[64:79], v[202:205], v[228:231], v[64:79]
	v_mfma_f32_32x32x16_bf16 v[32:47], v[202:205], v[238:241], v[32:47]
	v_mfma_f32_32x32x16_bf16 v[0:15], v[202:205], v[246:249], v[0:15]
	s_setprio 0
	s_waitcnt vmcnt(8)
	ds_write_b128 v189, v[152:155] offset:18432
	ds_write_b128 v189, v[140:143] offset:23040
	ds_write_b128 v189, v[136:139] offset:27648
	ds_write_b128 v189, v[148:151] offset:32256
	global_load_dwordx4 v[136:139], v[156:157], off offset:768
	global_load_dwordx4 v[140:143], v[164:165], off offset:768
	global_load_dwordx4 v[148:151], v[180:181], off offset:768
	global_load_dwordx4 v[152:155], v[172:173], off offset:768
	s_waitcnt lgkmcnt(0)
	s_barrier
	ds_read_b128 v[202:205], v188 offset:18432
	ds_read_b128 v[210:213], v188 offset:18464
	ds_read_b128 v[218:221], v188 offset:23040
	ds_read_b128 v[228:231], v188 offset:23072
	ds_read_b128 v[234:237], v188 offset:27648
	ds_read_b128 v[238:241], v188 offset:27680
	ds_read_b128 v[242:245], v188 offset:32256
	ds_read_b128 v[246:249], v188 offset:32288
	s_setprio 2
	s_movk_i32 s1, 0x6000
	v_add_co_u32_e32 v162, vcc, s1, v178
	s_mov_b32 s1, 0x16000
	s_nop 0
	v_addc_co_u32_e32 v163, vcc, 0, v179, vcc
	v_add_co_u32_e32 v170, vcc, s1, v178
	s_waitcnt vmcnt(11) lgkmcnt(7)
	v_mfma_f32_32x32x16_bf16 v[112:127], v[158:161], v[202:205], v[112:127]
	v_addc_co_u32_e32 v171, vcc, 0, v179, vcc
	s_waitcnt lgkmcnt(5)
	v_mfma_f32_32x32x16_bf16 v[80:95], v[158:161], v[218:221], v[80:95]
	s_waitcnt lgkmcnt(3)
	v_mfma_f32_32x32x16_bf16 v[48:63], v[158:161], v[234:237], v[48:63]
	s_waitcnt lgkmcnt(1)
	v_mfma_f32_32x32x16_bf16 v[16:31], v[158:161], v[242:245], v[16:31]
	s_waitcnt vmcnt(10)
	v_mfma_f32_32x32x16_bf16 v[96:111], v[166:169], v[202:205], v[96:111]
	global_load_dwordx4 v[158:161], v[162:163], off
	global_load_dwordx4 v[202:205], v[170:171], off
	v_mfma_f32_32x32x16_bf16 v[64:79], v[166:169], v[218:221], v[64:79]
	v_mfma_f32_32x32x16_bf16 v[32:47], v[166:169], v[234:237], v[32:47]
	v_mfma_f32_32x32x16_bf16 v[0:15], v[166:169], v[242:245], v[0:15]
	s_setprio 0
	ds_read_b128 v[166:169], v188 offset:18496
	ds_read_b128 v[218:221], v188 offset:23104
	ds_read_b128 v[234:237], v188 offset:27712
	ds_read_b128 v[242:245], v188 offset:32320
	s_setprio 2
	s_waitcnt vmcnt(11)
	v_mfma_f32_32x32x16_bf16 v[112:127], v[144:147], v[210:213], v[112:127]
	v_mfma_f32_32x32x16_bf16 v[80:95], v[144:147], v[228:231], v[80:95]
	v_mfma_f32_32x32x16_bf16 v[48:63], v[144:147], v[238:241], v[48:63]
	s_waitcnt lgkmcnt(4)
	v_mfma_f32_32x32x16_bf16 v[16:31], v[144:147], v[246:249], v[16:31]
	s_waitcnt vmcnt(10)
	v_mfma_f32_32x32x16_bf16 v[96:111], v[214:217], v[210:213], v[96:111]
	global_load_dwordx4 v[144:147], v[162:163], off offset:1024
	global_load_dwordx4 v[210:213], v[170:171], off offset:1024
	v_mfma_f32_32x32x16_bf16 v[64:79], v[214:217], v[228:231], v[64:79]
	v_mfma_f32_32x32x16_bf16 v[32:47], v[214:217], v[238:241], v[32:47]
	v_mfma_f32_32x32x16_bf16 v[0:15], v[214:217], v[246:249], v[0:15]
	s_setprio 0
	ds_read_b128 v[214:217], v188 offset:18528
	ds_read_b128 v[228:231], v188 offset:23136
	ds_read_b128 v[238:241], v188 offset:27744
	ds_read_b128 v[246:249], v188 offset:32352
	s_setprio 2
	s_waitcnt vmcnt(11) lgkmcnt(7)
	v_mfma_f32_32x32x16_bf16 v[112:127], v[132:135], v[166:169], v[112:127]
	s_waitcnt lgkmcnt(6)
	v_mfma_f32_32x32x16_bf16 v[80:95], v[132:135], v[218:221], v[80:95]
	s_waitcnt lgkmcnt(5)
	v_mfma_f32_32x32x16_bf16 v[48:63], v[132:135], v[234:237], v[48:63]
	s_waitcnt lgkmcnt(4)
	v_mfma_f32_32x32x16_bf16 v[16:31], v[132:135], v[242:245], v[16:31]
	s_waitcnt vmcnt(10)
	v_mfma_f32_32x32x16_bf16 v[96:111], v[206:209], v[166:169], v[96:111]
	global_load_dwordx4 v[132:135], v[162:163], off offset:2048
	global_load_dwordx4 v[166:169], v[170:171], off offset:2048
	v_mfma_f32_32x32x16_bf16 v[64:79], v[206:209], v[218:221], v[64:79]
	v_mfma_f32_32x32x16_bf16 v[32:47], v[206:209], v[234:237], v[32:47]
	v_mfma_f32_32x32x16_bf16 v[0:15], v[206:209], v[242:245], v[0:15]
	s_setprio 0
	s_setprio 2
	s_waitcnt vmcnt(11) lgkmcnt(3)
	v_mfma_f32_32x32x16_bf16 v[112:127], v[128:131], v[214:217], v[112:127]
	s_waitcnt lgkmcnt(2)
	v_mfma_f32_32x32x16_bf16 v[80:95], v[128:131], v[228:231], v[80:95]
	s_waitcnt lgkmcnt(1)
	v_mfma_f32_32x32x16_bf16 v[48:63], v[128:131], v[238:241], v[48:63]
	s_waitcnt lgkmcnt(0)
	v_mfma_f32_32x32x16_bf16 v[16:31], v[128:131], v[246:249], v[16:31]
	global_load_dwordx4 v[128:131], v[162:163], off offset:3072
	global_load_dwordx4 v[206:209], v[170:171], off offset:3072
	s_waitcnt vmcnt(12)
	v_mfma_f32_32x32x16_bf16 v[96:111], v[198:201], v[214:217], v[96:111]
	v_mfma_f32_32x32x16_bf16 v[64:79], v[198:201], v[228:231], v[64:79]
	v_mfma_f32_32x32x16_bf16 v[32:47], v[198:201], v[238:241], v[32:47]
	v_mfma_f32_32x32x16_bf16 v[0:15], v[198:201], v[246:249], v[0:15]
	s_setprio 0
	s_waitcnt vmcnt(9)
	ds_write_b128 v189, v[148:151]
	ds_write_b128 v189, v[136:139] offset:4608
	ds_write_b128 v189, v[140:143] offset:9216
	s_waitcnt vmcnt(8)
	ds_write_b128 v189, v[152:155] offset:13824
	global_load_dwordx4 v[136:139], v[164:165], off offset:896
	global_load_dwordx4 v[140:143], v[156:157], off offset:896
	global_load_dwordx4 v[148:151], v[172:173], off offset:896
	global_load_dwordx4 v[152:155], v[180:181], off offset:896
	s_waitcnt lgkmcnt(0)
	s_barrier
	ds_read_b128 v[198:201], v188
	ds_read_b128 v[214:217], v188 offset:32
	ds_read_b128 v[218:221], v188 offset:4608
	ds_read_b128 v[228:231], v188 offset:4640
	ds_read_b128 v[234:237], v188 offset:9216
	ds_read_b128 v[238:241], v188 offset:9248
	ds_read_b128 v[242:245], v188 offset:13824
	ds_read_b128 v[246:249], v188 offset:13856
	s_setprio 2
	s_movk_i32 s1, 0x7000
	v_add_co_u32_e32 v162, vcc, s1, v178
	s_mov_b32 s1, 0x17000
	s_nop 0
	v_addc_co_u32_e32 v163, vcc, 0, v179, vcc
	v_add_co_u32_e32 v170, vcc, s1, v178
	s_waitcnt vmcnt(11) lgkmcnt(7)
	v_mfma_f32_32x32x16_bf16 v[112:127], v[158:161], v[198:201], v[112:127]
	v_addc_co_u32_e32 v171, vcc, 0, v179, vcc
	s_waitcnt lgkmcnt(5)
	v_mfma_f32_32x32x16_bf16 v[80:95], v[158:161], v[218:221], v[80:95]
	s_waitcnt lgkmcnt(3)
	v_mfma_f32_32x32x16_bf16 v[48:63], v[158:161], v[234:237], v[48:63]
	s_waitcnt lgkmcnt(1)
	v_mfma_f32_32x32x16_bf16 v[16:31], v[158:161], v[242:245], v[16:31]
	s_waitcnt vmcnt(10)
	v_mfma_f32_32x32x16_bf16 v[96:111], v[202:205], v[198:201], v[96:111]
	global_load_dwordx4 v[158:161], v[162:163], off
	global_load_dwordx4 v[198:201], v[170:171], off
	v_mfma_f32_32x32x16_bf16 v[64:79], v[202:205], v[218:221], v[64:79]
	v_mfma_f32_32x32x16_bf16 v[32:47], v[202:205], v[234:237], v[32:47]
	v_mfma_f32_32x32x16_bf16 v[0:15], v[202:205], v[242:245], v[0:15]
	s_setprio 0
	ds_read_b128 v[202:205], v188 offset:64
	ds_read_b128 v[218:221], v188 offset:4672
	ds_read_b128 v[234:237], v188 offset:9280
	ds_read_b128 v[242:245], v188 offset:13888
	s_setprio 2
	s_waitcnt vmcnt(11)
	v_mfma_f32_32x32x16_bf16 v[112:127], v[144:147], v[214:217], v[112:127]
	v_mfma_f32_32x32x16_bf16 v[80:95], v[144:147], v[228:231], v[80:95]
	v_mfma_f32_32x32x16_bf16 v[48:63], v[144:147], v[238:241], v[48:63]
	s_waitcnt lgkmcnt(4)
	v_mfma_f32_32x32x16_bf16 v[16:31], v[144:147], v[246:249], v[16:31]
	s_waitcnt vmcnt(10)
	v_mfma_f32_32x32x16_bf16 v[96:111], v[210:213], v[214:217], v[96:111]
	global_load_dwordx4 v[144:147], v[162:163], off offset:1024
	global_load_dwordx4 v[214:217], v[170:171], off offset:1024
	v_mfma_f32_32x32x16_bf16 v[64:79], v[210:213], v[228:231], v[64:79]
	v_mfma_f32_32x32x16_bf16 v[32:47], v[210:213], v[238:241], v[32:47]
	v_mfma_f32_32x32x16_bf16 v[0:15], v[210:213], v[246:249], v[0:15]
	s_setprio 0
	ds_read_b128 v[210:213], v188 offset:96
	ds_read_b128 v[228:231], v188 offset:4704
	ds_read_b128 v[238:241], v188 offset:9312
	ds_read_b128 v[246:249], v188 offset:13920
	s_setprio 2
	s_waitcnt vmcnt(11) lgkmcnt(7)
	v_mfma_f32_32x32x16_bf16 v[112:127], v[132:135], v[202:205], v[112:127]
	s_waitcnt lgkmcnt(6)
	v_mfma_f32_32x32x16_bf16 v[80:95], v[132:135], v[218:221], v[80:95]
	s_waitcnt lgkmcnt(5)
	v_mfma_f32_32x32x16_bf16 v[48:63], v[132:135], v[234:237], v[48:63]
	s_waitcnt lgkmcnt(4)
	v_mfma_f32_32x32x16_bf16 v[16:31], v[132:135], v[242:245], v[16:31]
	s_waitcnt vmcnt(10)
	v_mfma_f32_32x32x16_bf16 v[96:111], v[166:169], v[202:205], v[96:111]
	global_load_dwordx4 v[132:135], v[162:163], off offset:2048
	global_load_dwordx4 v[202:205], v[170:171], off offset:2048
	v_mfma_f32_32x32x16_bf16 v[64:79], v[166:169], v[218:221], v[64:79]
	v_mfma_f32_32x32x16_bf16 v[32:47], v[166:169], v[234:237], v[32:47]
	v_mfma_f32_32x32x16_bf16 v[0:15], v[166:169], v[242:245], v[0:15]
	s_setprio 0
	s_setprio 2
	s_waitcnt vmcnt(11) lgkmcnt(3)
	v_mfma_f32_32x32x16_bf16 v[112:127], v[128:131], v[210:213], v[112:127]
	s_waitcnt lgkmcnt(2)
	v_mfma_f32_32x32x16_bf16 v[80:95], v[128:131], v[228:231], v[80:95]
	s_waitcnt lgkmcnt(1)
	v_mfma_f32_32x32x16_bf16 v[48:63], v[128:131], v[238:241], v[48:63]
	s_waitcnt lgkmcnt(0)
	v_mfma_f32_32x32x16_bf16 v[16:31], v[128:131], v[246:249], v[16:31]
	global_load_dwordx4 v[128:131], v[162:163], off offset:3072
	global_load_dwordx4 v[166:169], v[170:171], off offset:3072
	s_waitcnt vmcnt(12)
	v_mfma_f32_32x32x16_bf16 v[96:111], v[206:209], v[210:213], v[96:111]
	v_mfma_f32_32x32x16_bf16 v[64:79], v[206:209], v[228:231], v[64:79]
	v_mfma_f32_32x32x16_bf16 v[32:47], v[206:209], v[238:241], v[32:47]
	v_mfma_f32_32x32x16_bf16 v[0:15], v[206:209], v[246:249], v[0:15]
	s_setprio 0
	s_waitcnt vmcnt(8)
	ds_write_b128 v189, v[152:155] offset:18432
	ds_write_b128 v189, v[140:143] offset:23040
	ds_write_b128 v189, v[136:139] offset:27648
	ds_write_b128 v189, v[148:151] offset:32256
	global_load_dwordx4 v[136:139], v[156:157], off offset:1024
	global_load_dwordx4 v[140:143], v[164:165], off offset:1024
	global_load_dwordx4 v[148:151], v[180:181], off offset:1024
	global_load_dwordx4 v[152:155], v[172:173], off offset:1024
	s_waitcnt lgkmcnt(0)
	s_barrier
	ds_read_b128 v[206:209], v188 offset:18432
	ds_read_b128 v[210:213], v188 offset:18464
	ds_read_b128 v[218:221], v188 offset:23040
	ds_read_b128 v[228:231], v188 offset:23072
	ds_read_b128 v[234:237], v188 offset:27648
	ds_read_b128 v[238:241], v188 offset:27680
	ds_read_b128 v[242:245], v188 offset:32256
	ds_read_b128 v[246:249], v188 offset:32288
	s_setprio 2
	s_mov_b32 s1, 0x8000
	v_add_co_u32_e32 v162, vcc, s1, v178
	s_mov_b32 s1, 0x18000
	s_nop 0
	v_addc_co_u32_e32 v163, vcc, 0, v179, vcc
	v_add_co_u32_e32 v170, vcc, s1, v178
	s_waitcnt vmcnt(11) lgkmcnt(7)
	v_mfma_f32_32x32x16_bf16 v[112:127], v[158:161], v[206:209], v[112:127]
	v_addc_co_u32_e32 v171, vcc, 0, v179, vcc
	s_waitcnt lgkmcnt(5)
	v_mfma_f32_32x32x16_bf16 v[80:95], v[158:161], v[218:221], v[80:95]
	s_waitcnt lgkmcnt(3)
	v_mfma_f32_32x32x16_bf16 v[48:63], v[158:161], v[234:237], v[48:63]
	s_waitcnt lgkmcnt(1)
	v_mfma_f32_32x32x16_bf16 v[16:31], v[158:161], v[242:245], v[16:31]
	s_waitcnt vmcnt(10)
	v_mfma_f32_32x32x16_bf16 v[96:111], v[198:201], v[206:209], v[96:111]
	global_load_dwordx4 v[158:161], v[162:163], off
	global_load_dwordx4 v[206:209], v[170:171], off
	v_mfma_f32_32x32x16_bf16 v[64:79], v[198:201], v[218:221], v[64:79]
	v_mfma_f32_32x32x16_bf16 v[32:47], v[198:201], v[234:237], v[32:47]
	v_mfma_f32_32x32x16_bf16 v[0:15], v[198:201], v[242:245], v[0:15]
	s_setprio 0
	ds_read_b128 v[198:201], v188 offset:18496
	ds_read_b128 v[218:221], v188 offset:23104
	ds_read_b128 v[234:237], v188 offset:27712
	ds_read_b128 v[242:245], v188 offset:32320
	s_setprio 2
	s_waitcnt vmcnt(11)
	v_mfma_f32_32x32x16_bf16 v[112:127], v[144:147], v[210:213], v[112:127]
	v_mfma_f32_32x32x16_bf16 v[80:95], v[144:147], v[228:231], v[80:95]
	v_mfma_f32_32x32x16_bf16 v[48:63], v[144:147], v[238:241], v[48:63]
	s_waitcnt lgkmcnt(4)
	v_mfma_f32_32x32x16_bf16 v[16:31], v[144:147], v[246:249], v[16:31]
	s_waitcnt vmcnt(10)
	v_mfma_f32_32x32x16_bf16 v[96:111], v[214:217], v[210:213], v[96:111]
	global_load_dwordx4 v[144:147], v[162:163], off offset:1024
	global_load_dwordx4 v[210:213], v[170:171], off offset:1024
	v_mfma_f32_32x32x16_bf16 v[64:79], v[214:217], v[228:231], v[64:79]
	v_mfma_f32_32x32x16_bf16 v[32:47], v[214:217], v[238:241], v[32:47]
	v_mfma_f32_32x32x16_bf16 v[0:15], v[214:217], v[246:249], v[0:15]
	s_setprio 0
	ds_read_b128 v[214:217], v188 offset:18528
	ds_read_b128 v[228:231], v188 offset:23136
	ds_read_b128 v[238:241], v188 offset:27744
	ds_read_b128 v[246:249], v188 offset:32352
	s_setprio 2
	s_waitcnt vmcnt(11) lgkmcnt(7)
	v_mfma_f32_32x32x16_bf16 v[112:127], v[132:135], v[198:201], v[112:127]
	s_waitcnt lgkmcnt(6)
	v_mfma_f32_32x32x16_bf16 v[80:95], v[132:135], v[218:221], v[80:95]
	s_waitcnt lgkmcnt(5)
	v_mfma_f32_32x32x16_bf16 v[48:63], v[132:135], v[234:237], v[48:63]
	s_waitcnt lgkmcnt(4)
	v_mfma_f32_32x32x16_bf16 v[16:31], v[132:135], v[242:245], v[16:31]
	s_waitcnt vmcnt(10)
	v_mfma_f32_32x32x16_bf16 v[96:111], v[202:205], v[198:201], v[96:111]
	global_load_dwordx4 v[132:135], v[162:163], off offset:2048
	global_load_dwordx4 v[198:201], v[170:171], off offset:2048
	v_mfma_f32_32x32x16_bf16 v[64:79], v[202:205], v[218:221], v[64:79]
	v_mfma_f32_32x32x16_bf16 v[32:47], v[202:205], v[234:237], v[32:47]
	v_mfma_f32_32x32x16_bf16 v[0:15], v[202:205], v[242:245], v[0:15]
	s_setprio 0
	s_setprio 2
	s_waitcnt vmcnt(11) lgkmcnt(3)
	v_mfma_f32_32x32x16_bf16 v[112:127], v[128:131], v[214:217], v[112:127]
	s_waitcnt lgkmcnt(2)
	v_mfma_f32_32x32x16_bf16 v[80:95], v[128:131], v[228:231], v[80:95]
	s_waitcnt lgkmcnt(1)
	v_mfma_f32_32x32x16_bf16 v[48:63], v[128:131], v[238:241], v[48:63]
	s_waitcnt lgkmcnt(0)
	v_mfma_f32_32x32x16_bf16 v[16:31], v[128:131], v[246:249], v[16:31]
	global_load_dwordx4 v[128:131], v[162:163], off offset:3072
	global_load_dwordx4 v[202:205], v[170:171], off offset:3072
	s_waitcnt vmcnt(12)
	v_mfma_f32_32x32x16_bf16 v[96:111], v[166:169], v[214:217], v[96:111]
	v_mfma_f32_32x32x16_bf16 v[64:79], v[166:169], v[228:231], v[64:79]
	v_mfma_f32_32x32x16_bf16 v[32:47], v[166:169], v[238:241], v[32:47]
	v_mfma_f32_32x32x16_bf16 v[0:15], v[166:169], v[246:249], v[0:15]
	s_setprio 0
	s_waitcnt vmcnt(9)
	ds_write_b128 v189, v[148:151]
	ds_write_b128 v189, v[136:139] offset:4608
	ds_write_b128 v189, v[140:143] offset:9216
	s_waitcnt vmcnt(8)
	ds_write_b128 v189, v[152:155] offset:13824
	global_load_dwordx4 v[136:139], v[164:165], off offset:1152
	global_load_dwordx4 v[140:143], v[156:157], off offset:1152
	global_load_dwordx4 v[148:151], v[172:173], off offset:1152
	global_load_dwordx4 v[152:155], v[180:181], off offset:1152
	s_waitcnt lgkmcnt(0)
	s_barrier
	ds_read_b128 v[166:169], v188
	ds_read_b128 v[214:217], v188 offset:32
	ds_read_b128 v[218:221], v188 offset:4608
	ds_read_b128 v[228:231], v188 offset:4640
	ds_read_b128 v[234:237], v188 offset:9216
	ds_read_b128 v[238:241], v188 offset:9248
	ds_read_b128 v[242:245], v188 offset:13824
	ds_read_b128 v[246:249], v188 offset:13856
	s_setprio 2
	s_mov_b32 s1, 0x9000
	v_add_co_u32_e32 v162, vcc, s1, v178
	s_mov_b32 s1, 0x19000
	s_nop 0
	v_addc_co_u32_e32 v163, vcc, 0, v179, vcc
	v_add_co_u32_e32 v170, vcc, s1, v178
	s_waitcnt vmcnt(11) lgkmcnt(7)
	v_mfma_f32_32x32x16_bf16 v[112:127], v[158:161], v[166:169], v[112:127]
	v_addc_co_u32_e32 v171, vcc, 0, v179, vcc
	s_waitcnt lgkmcnt(5)
	v_mfma_f32_32x32x16_bf16 v[80:95], v[158:161], v[218:221], v[80:95]
	s_waitcnt lgkmcnt(3)
	v_mfma_f32_32x32x16_bf16 v[48:63], v[158:161], v[234:237], v[48:63]
	s_waitcnt lgkmcnt(1)
	v_mfma_f32_32x32x16_bf16 v[16:31], v[158:161], v[242:245], v[16:31]
	s_waitcnt vmcnt(10)
	v_mfma_f32_32x32x16_bf16 v[96:111], v[206:209], v[166:169], v[96:111]
	global_load_dwordx4 v[158:161], v[162:163], off
	global_load_dwordx4 v[166:169], v[170:171], off
	v_mfma_f32_32x32x16_bf16 v[64:79], v[206:209], v[218:221], v[64:79]
	v_mfma_f32_32x32x16_bf16 v[32:47], v[206:209], v[234:237], v[32:47]
	v_mfma_f32_32x32x16_bf16 v[0:15], v[206:209], v[242:245], v[0:15]
	s_setprio 0
	ds_read_b128 v[206:209], v188 offset:64
	ds_read_b128 v[218:221], v188 offset:4672
	ds_read_b128 v[234:237], v188 offset:9280
	ds_read_b128 v[242:245], v188 offset:13888
	s_setprio 2
	s_waitcnt vmcnt(11)
	v_mfma_f32_32x32x16_bf16 v[112:127], v[144:147], v[214:217], v[112:127]
	v_mfma_f32_32x32x16_bf16 v[80:95], v[144:147], v[228:231], v[80:95]
	v_mfma_f32_32x32x16_bf16 v[48:63], v[144:147], v[238:241], v[48:63]
	s_waitcnt lgkmcnt(4)
	v_mfma_f32_32x32x16_bf16 v[16:31], v[144:147], v[246:249], v[16:31]
	s_waitcnt vmcnt(10)
	v_mfma_f32_32x32x16_bf16 v[96:111], v[210:213], v[214:217], v[96:111]
	global_load_dwordx4 v[144:147], v[162:163], off offset:1024
	global_load_dwordx4 v[214:217], v[170:171], off offset:1024
	v_mfma_f32_32x32x16_bf16 v[64:79], v[210:213], v[228:231], v[64:79]
	v_mfma_f32_32x32x16_bf16 v[32:47], v[210:213], v[238:241], v[32:47]
	v_mfma_f32_32x32x16_bf16 v[0:15], v[210:213], v[246:249], v[0:15]
	s_setprio 0
	ds_read_b128 v[210:213], v188 offset:96
	ds_read_b128 v[228:231], v188 offset:4704
	ds_read_b128 v[238:241], v188 offset:9312
	ds_read_b128 v[246:249], v188 offset:13920
	s_setprio 2
	s_waitcnt vmcnt(11) lgkmcnt(7)
	v_mfma_f32_32x32x16_bf16 v[112:127], v[132:135], v[206:209], v[112:127]
	s_waitcnt lgkmcnt(6)
	v_mfma_f32_32x32x16_bf16 v[80:95], v[132:135], v[218:221], v[80:95]
	s_waitcnt lgkmcnt(5)
	v_mfma_f32_32x32x16_bf16 v[48:63], v[132:135], v[234:237], v[48:63]
	s_waitcnt lgkmcnt(4)
	v_mfma_f32_32x32x16_bf16 v[16:31], v[132:135], v[242:245], v[16:31]
	s_waitcnt vmcnt(10)
	v_mfma_f32_32x32x16_bf16 v[96:111], v[198:201], v[206:209], v[96:111]
	global_load_dwordx4 v[132:135], v[162:163], off offset:2048
	global_load_dwordx4 v[206:209], v[170:171], off offset:2048
	v_mfma_f32_32x32x16_bf16 v[64:79], v[198:201], v[218:221], v[64:79]
	v_mfma_f32_32x32x16_bf16 v[32:47], v[198:201], v[234:237], v[32:47]
	v_mfma_f32_32x32x16_bf16 v[0:15], v[198:201], v[242:245], v[0:15]
	s_setprio 0
	s_setprio 2
	s_waitcnt vmcnt(11) lgkmcnt(3)
	v_mfma_f32_32x32x16_bf16 v[112:127], v[128:131], v[210:213], v[112:127]
	s_waitcnt lgkmcnt(2)
	v_mfma_f32_32x32x16_bf16 v[80:95], v[128:131], v[228:231], v[80:95]
	s_waitcnt lgkmcnt(1)
	v_mfma_f32_32x32x16_bf16 v[48:63], v[128:131], v[238:241], v[48:63]
	s_waitcnt lgkmcnt(0)
	v_mfma_f32_32x32x16_bf16 v[16:31], v[128:131], v[246:249], v[16:31]
	global_load_dwordx4 v[128:131], v[162:163], off offset:3072
	global_load_dwordx4 v[198:201], v[170:171], off offset:3072
	s_waitcnt vmcnt(12)
	v_mfma_f32_32x32x16_bf16 v[96:111], v[202:205], v[210:213], v[96:111]
	v_mfma_f32_32x32x16_bf16 v[64:79], v[202:205], v[228:231], v[64:79]
	v_mfma_f32_32x32x16_bf16 v[32:47], v[202:205], v[238:241], v[32:47]
	v_mfma_f32_32x32x16_bf16 v[0:15], v[202:205], v[246:249], v[0:15]
	s_setprio 0
	s_waitcnt vmcnt(8)
	ds_write_b128 v189, v[152:155] offset:18432
	ds_write_b128 v189, v[140:143] offset:23040
	ds_write_b128 v189, v[136:139] offset:27648
	ds_write_b128 v189, v[148:151] offset:32256
	global_load_dwordx4 v[136:139], v[156:157], off offset:1280
	global_load_dwordx4 v[140:143], v[164:165], off offset:1280
	global_load_dwordx4 v[148:151], v[180:181], off offset:1280
	global_load_dwordx4 v[152:155], v[172:173], off offset:1280
	s_waitcnt lgkmcnt(0)
	s_barrier
	ds_read_b128 v[202:205], v188 offset:18432
	ds_read_b128 v[210:213], v188 offset:18464
	ds_read_b128 v[218:221], v188 offset:23040
	ds_read_b128 v[228:231], v188 offset:23072
	ds_read_b128 v[234:237], v188 offset:27648
	ds_read_b128 v[238:241], v188 offset:27680
	ds_read_b128 v[242:245], v188 offset:32256
	ds_read_b128 v[246:249], v188 offset:32288
	s_setprio 2
	s_mov_b32 s1, 0xa000
	v_add_co_u32_e32 v162, vcc, s1, v178
	s_mov_b32 s1, 0x1a000
	s_nop 0
	v_addc_co_u32_e32 v163, vcc, 0, v179, vcc
	v_add_co_u32_e32 v170, vcc, s1, v178
	s_waitcnt vmcnt(11) lgkmcnt(7)
	v_mfma_f32_32x32x16_bf16 v[112:127], v[158:161], v[202:205], v[112:127]
	v_addc_co_u32_e32 v171, vcc, 0, v179, vcc
	s_waitcnt lgkmcnt(5)
	v_mfma_f32_32x32x16_bf16 v[80:95], v[158:161], v[218:221], v[80:95]
	s_waitcnt lgkmcnt(3)
	v_mfma_f32_32x32x16_bf16 v[48:63], v[158:161], v[234:237], v[48:63]
	s_waitcnt lgkmcnt(1)
	v_mfma_f32_32x32x16_bf16 v[16:31], v[158:161], v[242:245], v[16:31]
	s_waitcnt vmcnt(10)
	v_mfma_f32_32x32x16_bf16 v[96:111], v[166:169], v[202:205], v[96:111]
	global_load_dwordx4 v[158:161], v[162:163], off
	global_load_dwordx4 v[202:205], v[170:171], off
	v_mfma_f32_32x32x16_bf16 v[64:79], v[166:169], v[218:221], v[64:79]
	v_mfma_f32_32x32x16_bf16 v[32:47], v[166:169], v[234:237], v[32:47]
	v_mfma_f32_32x32x16_bf16 v[0:15], v[166:169], v[242:245], v[0:15]
	s_setprio 0
	ds_read_b128 v[166:169], v188 offset:18496
	ds_read_b128 v[218:221], v188 offset:23104
	ds_read_b128 v[234:237], v188 offset:27712
	ds_read_b128 v[242:245], v188 offset:32320
	s_setprio 2
	s_waitcnt vmcnt(11)
	v_mfma_f32_32x32x16_bf16 v[112:127], v[144:147], v[210:213], v[112:127]
	v_mfma_f32_32x32x16_bf16 v[80:95], v[144:147], v[228:231], v[80:95]
	v_mfma_f32_32x32x16_bf16 v[48:63], v[144:147], v[238:241], v[48:63]
	s_waitcnt lgkmcnt(4)
	v_mfma_f32_32x32x16_bf16 v[16:31], v[144:147], v[246:249], v[16:31]
	s_waitcnt vmcnt(10)
	v_mfma_f32_32x32x16_bf16 v[96:111], v[214:217], v[210:213], v[96:111]
	global_load_dwordx4 v[144:147], v[162:163], off offset:1024
	global_load_dwordx4 v[210:213], v[170:171], off offset:1024
	v_mfma_f32_32x32x16_bf16 v[64:79], v[214:217], v[228:231], v[64:79]
	v_mfma_f32_32x32x16_bf16 v[32:47], v[214:217], v[238:241], v[32:47]
	v_mfma_f32_32x32x16_bf16 v[0:15], v[214:217], v[246:249], v[0:15]
	s_setprio 0
	ds_read_b128 v[214:217], v188 offset:18528
	ds_read_b128 v[228:231], v188 offset:23136
	ds_read_b128 v[238:241], v188 offset:27744
	ds_read_b128 v[246:249], v188 offset:32352
	s_setprio 2
	s_waitcnt vmcnt(11) lgkmcnt(7)
	v_mfma_f32_32x32x16_bf16 v[112:127], v[132:135], v[166:169], v[112:127]
	s_waitcnt lgkmcnt(6)
	v_mfma_f32_32x32x16_bf16 v[80:95], v[132:135], v[218:221], v[80:95]
	s_waitcnt lgkmcnt(5)
	v_mfma_f32_32x32x16_bf16 v[48:63], v[132:135], v[234:237], v[48:63]
	s_waitcnt lgkmcnt(4)
	v_mfma_f32_32x32x16_bf16 v[16:31], v[132:135], v[242:245], v[16:31]
	s_waitcnt vmcnt(10)
	v_mfma_f32_32x32x16_bf16 v[96:111], v[206:209], v[166:169], v[96:111]
	global_load_dwordx4 v[132:135], v[162:163], off offset:2048
	global_load_dwordx4 v[166:169], v[170:171], off offset:2048
	v_mfma_f32_32x32x16_bf16 v[64:79], v[206:209], v[218:221], v[64:79]
	v_mfma_f32_32x32x16_bf16 v[32:47], v[206:209], v[234:237], v[32:47]
	v_mfma_f32_32x32x16_bf16 v[0:15], v[206:209], v[242:245], v[0:15]
	s_setprio 0
	s_setprio 2
	s_waitcnt vmcnt(11) lgkmcnt(3)
	v_mfma_f32_32x32x16_bf16 v[112:127], v[128:131], v[214:217], v[112:127]
	s_waitcnt lgkmcnt(2)
	v_mfma_f32_32x32x16_bf16 v[80:95], v[128:131], v[228:231], v[80:95]
	s_waitcnt lgkmcnt(1)
	v_mfma_f32_32x32x16_bf16 v[48:63], v[128:131], v[238:241], v[48:63]
	s_waitcnt lgkmcnt(0)
	v_mfma_f32_32x32x16_bf16 v[16:31], v[128:131], v[246:249], v[16:31]
	global_load_dwordx4 v[128:131], v[162:163], off offset:3072
	global_load_dwordx4 v[206:209], v[170:171], off offset:3072
	s_waitcnt vmcnt(12)
	v_mfma_f32_32x32x16_bf16 v[96:111], v[198:201], v[214:217], v[96:111]
	v_mfma_f32_32x32x16_bf16 v[64:79], v[198:201], v[228:231], v[64:79]
	v_mfma_f32_32x32x16_bf16 v[32:47], v[198:201], v[238:241], v[32:47]
	v_mfma_f32_32x32x16_bf16 v[0:15], v[198:201], v[246:249], v[0:15]
	s_setprio 0
	s_waitcnt vmcnt(9)
	ds_write_b128 v189, v[148:151]
	ds_write_b128 v189, v[136:139] offset:4608
	ds_write_b128 v189, v[140:143] offset:9216
	s_waitcnt vmcnt(8)
	ds_write_b128 v189, v[152:155] offset:13824
	global_load_dwordx4 v[136:139], v[164:165], off offset:1408
	global_load_dwordx4 v[140:143], v[156:157], off offset:1408
	global_load_dwordx4 v[148:151], v[172:173], off offset:1408
	global_load_dwordx4 v[152:155], v[180:181], off offset:1408
	s_waitcnt lgkmcnt(0)
	s_barrier
	ds_read_b128 v[198:201], v188
	ds_read_b128 v[214:217], v188 offset:32
	ds_read_b128 v[218:221], v188 offset:4608
	ds_read_b128 v[228:231], v188 offset:4640
	ds_read_b128 v[234:237], v188 offset:9216
	ds_read_b128 v[238:241], v188 offset:9248
	ds_read_b128 v[242:245], v188 offset:13824
	ds_read_b128 v[246:249], v188 offset:13856
	s_setprio 2
	s_mov_b32 s1, 0xb000
	v_add_co_u32_e32 v162, vcc, s1, v178
	s_mov_b32 s1, 0x1b000
	s_nop 0
	v_addc_co_u32_e32 v163, vcc, 0, v179, vcc
	v_add_co_u32_e32 v170, vcc, s1, v178
	s_waitcnt vmcnt(11) lgkmcnt(7)
	v_mfma_f32_32x32x16_bf16 v[112:127], v[158:161], v[198:201], v[112:127]
	v_addc_co_u32_e32 v171, vcc, 0, v179, vcc
	s_waitcnt lgkmcnt(5)
	v_mfma_f32_32x32x16_bf16 v[80:95], v[158:161], v[218:221], v[80:95]
	s_waitcnt lgkmcnt(3)
	v_mfma_f32_32x32x16_bf16 v[48:63], v[158:161], v[234:237], v[48:63]
	s_waitcnt lgkmcnt(1)
	v_mfma_f32_32x32x16_bf16 v[16:31], v[158:161], v[242:245], v[16:31]
	s_waitcnt vmcnt(10)
	v_mfma_f32_32x32x16_bf16 v[96:111], v[202:205], v[198:201], v[96:111]
	global_load_dwordx4 v[158:161], v[162:163], off
	global_load_dwordx4 v[198:201], v[170:171], off
	v_mfma_f32_32x32x16_bf16 v[64:79], v[202:205], v[218:221], v[64:79]
	v_mfma_f32_32x32x16_bf16 v[32:47], v[202:205], v[234:237], v[32:47]
	v_mfma_f32_32x32x16_bf16 v[0:15], v[202:205], v[242:245], v[0:15]
	s_setprio 0
	ds_read_b128 v[202:205], v188 offset:64
	ds_read_b128 v[218:221], v188 offset:4672
	ds_read_b128 v[234:237], v188 offset:9280
	ds_read_b128 v[242:245], v188 offset:13888
	s_setprio 2
	s_waitcnt vmcnt(11)
	v_mfma_f32_32x32x16_bf16 v[112:127], v[144:147], v[214:217], v[112:127]
	v_mfma_f32_32x32x16_bf16 v[80:95], v[144:147], v[228:231], v[80:95]
	v_mfma_f32_32x32x16_bf16 v[48:63], v[144:147], v[238:241], v[48:63]
	s_waitcnt lgkmcnt(4)
	v_mfma_f32_32x32x16_bf16 v[16:31], v[144:147], v[246:249], v[16:31]
	s_waitcnt vmcnt(10)
	v_mfma_f32_32x32x16_bf16 v[96:111], v[210:213], v[214:217], v[96:111]
	global_load_dwordx4 v[144:147], v[162:163], off offset:1024
	global_load_dwordx4 v[214:217], v[170:171], off offset:1024
	v_mfma_f32_32x32x16_bf16 v[64:79], v[210:213], v[228:231], v[64:79]
	v_mfma_f32_32x32x16_bf16 v[32:47], v[210:213], v[238:241], v[32:47]
	v_mfma_f32_32x32x16_bf16 v[0:15], v[210:213], v[246:249], v[0:15]
	s_setprio 0
	ds_read_b128 v[210:213], v188 offset:96
	ds_read_b128 v[228:231], v188 offset:4704
	ds_read_b128 v[238:241], v188 offset:9312
	ds_read_b128 v[246:249], v188 offset:13920
	s_setprio 2
	s_waitcnt vmcnt(11) lgkmcnt(7)
	v_mfma_f32_32x32x16_bf16 v[112:127], v[132:135], v[202:205], v[112:127]
	s_waitcnt lgkmcnt(6)
	v_mfma_f32_32x32x16_bf16 v[80:95], v[132:135], v[218:221], v[80:95]
	s_waitcnt lgkmcnt(5)
	v_mfma_f32_32x32x16_bf16 v[48:63], v[132:135], v[234:237], v[48:63]
	s_waitcnt lgkmcnt(4)
	v_mfma_f32_32x32x16_bf16 v[16:31], v[132:135], v[242:245], v[16:31]
	s_waitcnt vmcnt(10)
	v_mfma_f32_32x32x16_bf16 v[96:111], v[166:169], v[202:205], v[96:111]
	global_load_dwordx4 v[132:135], v[162:163], off offset:2048
	global_load_dwordx4 v[202:205], v[170:171], off offset:2048
	v_mfma_f32_32x32x16_bf16 v[64:79], v[166:169], v[218:221], v[64:79]
	v_mfma_f32_32x32x16_bf16 v[32:47], v[166:169], v[234:237], v[32:47]
	v_mfma_f32_32x32x16_bf16 v[0:15], v[166:169], v[242:245], v[0:15]
	s_setprio 0
	s_setprio 2
	s_waitcnt vmcnt(11) lgkmcnt(3)
	v_mfma_f32_32x32x16_bf16 v[112:127], v[128:131], v[210:213], v[112:127]
	s_waitcnt lgkmcnt(2)
	v_mfma_f32_32x32x16_bf16 v[80:95], v[128:131], v[228:231], v[80:95]
	s_waitcnt lgkmcnt(1)
	v_mfma_f32_32x32x16_bf16 v[48:63], v[128:131], v[238:241], v[48:63]
	s_waitcnt lgkmcnt(0)
	v_mfma_f32_32x32x16_bf16 v[16:31], v[128:131], v[246:249], v[16:31]
	global_load_dwordx4 v[128:131], v[162:163], off offset:3072
	global_load_dwordx4 v[166:169], v[170:171], off offset:3072
	s_waitcnt vmcnt(12)
	v_mfma_f32_32x32x16_bf16 v[96:111], v[206:209], v[210:213], v[96:111]
	v_mfma_f32_32x32x16_bf16 v[64:79], v[206:209], v[228:231], v[64:79]
	v_mfma_f32_32x32x16_bf16 v[32:47], v[206:209], v[238:241], v[32:47]
	v_mfma_f32_32x32x16_bf16 v[0:15], v[206:209], v[246:249], v[0:15]
	s_setprio 0
	s_waitcnt vmcnt(8)
	ds_write_b128 v189, v[152:155] offset:18432
	ds_write_b128 v189, v[140:143] offset:23040
	ds_write_b128 v189, v[136:139] offset:27648
	ds_write_b128 v189, v[148:151] offset:32256
	global_load_dwordx4 v[136:139], v[156:157], off offset:1536
	global_load_dwordx4 v[140:143], v[164:165], off offset:1536
	global_load_dwordx4 v[148:151], v[180:181], off offset:1536
	global_load_dwordx4 v[152:155], v[172:173], off offset:1536
	s_waitcnt lgkmcnt(0)
	s_barrier
	ds_read_b128 v[206:209], v188 offset:18432
	ds_read_b128 v[210:213], v188 offset:18464
	ds_read_b128 v[218:221], v188 offset:23040
	ds_read_b128 v[228:231], v188 offset:23072
	ds_read_b128 v[234:237], v188 offset:27648
	ds_read_b128 v[238:241], v188 offset:27680
	ds_read_b128 v[242:245], v188 offset:32256
	ds_read_b128 v[246:249], v188 offset:32288
	s_setprio 2
	s_mov_b32 s1, 0xc000
	v_add_co_u32_e32 v162, vcc, s1, v178
	s_mov_b32 s1, 0x1c000
	s_nop 0
	v_addc_co_u32_e32 v163, vcc, 0, v179, vcc
	v_add_co_u32_e32 v170, vcc, s1, v178
	s_waitcnt vmcnt(11) lgkmcnt(7)
	v_mfma_f32_32x32x16_bf16 v[112:127], v[158:161], v[206:209], v[112:127]
	v_addc_co_u32_e32 v171, vcc, 0, v179, vcc
	s_waitcnt lgkmcnt(5)
	v_mfma_f32_32x32x16_bf16 v[80:95], v[158:161], v[218:221], v[80:95]
	s_waitcnt lgkmcnt(3)
	v_mfma_f32_32x32x16_bf16 v[48:63], v[158:161], v[234:237], v[48:63]
	s_waitcnt lgkmcnt(1)
	v_mfma_f32_32x32x16_bf16 v[16:31], v[158:161], v[242:245], v[16:31]
	s_waitcnt vmcnt(10)
	v_mfma_f32_32x32x16_bf16 v[96:111], v[198:201], v[206:209], v[96:111]
	global_load_dwordx4 v[158:161], v[162:163], off
	global_load_dwordx4 v[206:209], v[170:171], off
	v_mfma_f32_32x32x16_bf16 v[64:79], v[198:201], v[218:221], v[64:79]
	v_mfma_f32_32x32x16_bf16 v[32:47], v[198:201], v[234:237], v[32:47]
	v_mfma_f32_32x32x16_bf16 v[0:15], v[198:201], v[242:245], v[0:15]
	s_setprio 0
	ds_read_b128 v[198:201], v188 offset:18496
	ds_read_b128 v[218:221], v188 offset:23104
	ds_read_b128 v[234:237], v188 offset:27712
	ds_read_b128 v[242:245], v188 offset:32320
	s_setprio 2
	s_waitcnt vmcnt(11)
	v_mfma_f32_32x32x16_bf16 v[112:127], v[144:147], v[210:213], v[112:127]
	v_mfma_f32_32x32x16_bf16 v[80:95], v[144:147], v[228:231], v[80:95]
	v_mfma_f32_32x32x16_bf16 v[48:63], v[144:147], v[238:241], v[48:63]
	s_waitcnt lgkmcnt(4)
	v_mfma_f32_32x32x16_bf16 v[16:31], v[144:147], v[246:249], v[16:31]
	s_waitcnt vmcnt(10)
	v_mfma_f32_32x32x16_bf16 v[96:111], v[214:217], v[210:213], v[96:111]
	global_load_dwordx4 v[144:147], v[162:163], off offset:1024
	global_load_dwordx4 v[210:213], v[170:171], off offset:1024
	v_mfma_f32_32x32x16_bf16 v[64:79], v[214:217], v[228:231], v[64:79]
	v_mfma_f32_32x32x16_bf16 v[32:47], v[214:217], v[238:241], v[32:47]
	v_mfma_f32_32x32x16_bf16 v[0:15], v[214:217], v[246:249], v[0:15]
	s_setprio 0
	ds_read_b128 v[214:217], v188 offset:18528
	ds_read_b128 v[228:231], v188 offset:23136
	ds_read_b128 v[238:241], v188 offset:27744
	ds_read_b128 v[246:249], v188 offset:32352
	s_setprio 2
	s_waitcnt vmcnt(11) lgkmcnt(7)
	v_mfma_f32_32x32x16_bf16 v[112:127], v[132:135], v[198:201], v[112:127]
	s_waitcnt lgkmcnt(6)
	v_mfma_f32_32x32x16_bf16 v[80:95], v[132:135], v[218:221], v[80:95]
	s_waitcnt lgkmcnt(5)
	v_mfma_f32_32x32x16_bf16 v[48:63], v[132:135], v[234:237], v[48:63]
	s_waitcnt lgkmcnt(4)
	v_mfma_f32_32x32x16_bf16 v[16:31], v[132:135], v[242:245], v[16:31]
	s_waitcnt vmcnt(10)
	v_mfma_f32_32x32x16_bf16 v[96:111], v[202:205], v[198:201], v[96:111]
	global_load_dwordx4 v[132:135], v[162:163], off offset:2048
	global_load_dwordx4 v[198:201], v[170:171], off offset:2048
	v_mfma_f32_32x32x16_bf16 v[64:79], v[202:205], v[218:221], v[64:79]
	v_mfma_f32_32x32x16_bf16 v[32:47], v[202:205], v[234:237], v[32:47]
	v_mfma_f32_32x32x16_bf16 v[0:15], v[202:205], v[242:245], v[0:15]
	s_setprio 0
	s_setprio 2
	s_waitcnt vmcnt(11) lgkmcnt(3)
	v_mfma_f32_32x32x16_bf16 v[112:127], v[128:131], v[214:217], v[112:127]
	s_waitcnt lgkmcnt(2)
	v_mfma_f32_32x32x16_bf16 v[80:95], v[128:131], v[228:231], v[80:95]
	s_waitcnt lgkmcnt(1)
	v_mfma_f32_32x32x16_bf16 v[48:63], v[128:131], v[238:241], v[48:63]
	s_waitcnt lgkmcnt(0)
	v_mfma_f32_32x32x16_bf16 v[16:31], v[128:131], v[246:249], v[16:31]
	global_load_dwordx4 v[128:131], v[162:163], off offset:3072
	global_load_dwordx4 v[202:205], v[170:171], off offset:3072
	s_waitcnt vmcnt(12)
	v_mfma_f32_32x32x16_bf16 v[96:111], v[166:169], v[214:217], v[96:111]
	v_mfma_f32_32x32x16_bf16 v[64:79], v[166:169], v[228:231], v[64:79]
	v_mfma_f32_32x32x16_bf16 v[32:47], v[166:169], v[238:241], v[32:47]
	v_mfma_f32_32x32x16_bf16 v[0:15], v[166:169], v[246:249], v[0:15]
	s_setprio 0
	s_waitcnt vmcnt(9)
	ds_write_b128 v189, v[148:151]
	ds_write_b128 v189, v[136:139] offset:4608
	ds_write_b128 v189, v[140:143] offset:9216
	s_waitcnt vmcnt(8)
	ds_write_b128 v189, v[152:155] offset:13824
	global_load_dwordx4 v[136:139], v[164:165], off offset:1664
	global_load_dwordx4 v[140:143], v[156:157], off offset:1664
	global_load_dwordx4 v[148:151], v[172:173], off offset:1664
	global_load_dwordx4 v[152:155], v[180:181], off offset:1664
	s_waitcnt lgkmcnt(0)
	s_barrier
	ds_read_b128 v[166:169], v188
	ds_read_b128 v[214:217], v188 offset:32
	ds_read_b128 v[218:221], v188 offset:4608
	ds_read_b128 v[228:231], v188 offset:4640
	ds_read_b128 v[234:237], v188 offset:9216
	ds_read_b128 v[238:241], v188 offset:9248
	ds_read_b128 v[242:245], v188 offset:13824
	ds_read_b128 v[246:249], v188 offset:13856
	s_setprio 2
	s_mov_b32 s1, 0xd000
	v_add_co_u32_e32 v162, vcc, s1, v178
	s_mov_b32 s1, 0x1d000
	s_nop 0
	v_addc_co_u32_e32 v163, vcc, 0, v179, vcc
	v_add_co_u32_e32 v170, vcc, s1, v178
	s_waitcnt vmcnt(11) lgkmcnt(7)
	v_mfma_f32_32x32x16_bf16 v[112:127], v[158:161], v[166:169], v[112:127]
	v_addc_co_u32_e32 v171, vcc, 0, v179, vcc
	s_waitcnt lgkmcnt(5)
	v_mfma_f32_32x32x16_bf16 v[80:95], v[158:161], v[218:221], v[80:95]
	s_waitcnt lgkmcnt(3)
	v_mfma_f32_32x32x16_bf16 v[48:63], v[158:161], v[234:237], v[48:63]
	s_waitcnt lgkmcnt(1)
	v_mfma_f32_32x32x16_bf16 v[16:31], v[158:161], v[242:245], v[16:31]
	s_waitcnt vmcnt(10)
	v_mfma_f32_32x32x16_bf16 v[96:111], v[206:209], v[166:169], v[96:111]
	global_load_dwordx4 v[158:161], v[162:163], off
	global_load_dwordx4 v[166:169], v[170:171], off
	v_mfma_f32_32x32x16_bf16 v[64:79], v[206:209], v[218:221], v[64:79]
	v_mfma_f32_32x32x16_bf16 v[32:47], v[206:209], v[234:237], v[32:47]
	v_mfma_f32_32x32x16_bf16 v[0:15], v[206:209], v[242:245], v[0:15]
	s_setprio 0
	ds_read_b128 v[206:209], v188 offset:64
	ds_read_b128 v[218:221], v188 offset:4672
	ds_read_b128 v[234:237], v188 offset:9280
	ds_read_b128 v[242:245], v188 offset:13888
	s_setprio 2
	s_waitcnt vmcnt(11)
	v_mfma_f32_32x32x16_bf16 v[112:127], v[144:147], v[214:217], v[112:127]
	v_mfma_f32_32x32x16_bf16 v[80:95], v[144:147], v[228:231], v[80:95]
	v_mfma_f32_32x32x16_bf16 v[48:63], v[144:147], v[238:241], v[48:63]
	s_waitcnt lgkmcnt(4)
	v_mfma_f32_32x32x16_bf16 v[16:31], v[144:147], v[246:249], v[16:31]
	s_waitcnt vmcnt(10)
	v_mfma_f32_32x32x16_bf16 v[96:111], v[210:213], v[214:217], v[96:111]
	global_load_dwordx4 v[144:147], v[162:163], off offset:1024
	global_load_dwordx4 v[214:217], v[170:171], off offset:1024
	v_mfma_f32_32x32x16_bf16 v[64:79], v[210:213], v[228:231], v[64:79]
	v_mfma_f32_32x32x16_bf16 v[32:47], v[210:213], v[238:241], v[32:47]
	v_mfma_f32_32x32x16_bf16 v[0:15], v[210:213], v[246:249], v[0:15]
	s_setprio 0
	ds_read_b128 v[210:213], v188 offset:96
	ds_read_b128 v[228:231], v188 offset:4704
	ds_read_b128 v[238:241], v188 offset:9312
	ds_read_b128 v[246:249], v188 offset:13920
	s_setprio 2
	s_waitcnt vmcnt(11) lgkmcnt(7)
	v_mfma_f32_32x32x16_bf16 v[112:127], v[132:135], v[206:209], v[112:127]
	s_waitcnt lgkmcnt(6)
	v_mfma_f32_32x32x16_bf16 v[80:95], v[132:135], v[218:221], v[80:95]
	s_waitcnt lgkmcnt(5)
	v_mfma_f32_32x32x16_bf16 v[48:63], v[132:135], v[234:237], v[48:63]
	s_waitcnt lgkmcnt(4)
	v_mfma_f32_32x32x16_bf16 v[16:31], v[132:135], v[242:245], v[16:31]
	s_waitcnt vmcnt(10)
	v_mfma_f32_32x32x16_bf16 v[96:111], v[198:201], v[206:209], v[96:111]
	global_load_dwordx4 v[132:135], v[162:163], off offset:2048
	global_load_dwordx4 v[206:209], v[170:171], off offset:2048
	v_mfma_f32_32x32x16_bf16 v[64:79], v[198:201], v[218:221], v[64:79]
	v_mfma_f32_32x32x16_bf16 v[32:47], v[198:201], v[234:237], v[32:47]
	v_mfma_f32_32x32x16_bf16 v[0:15], v[198:201], v[242:245], v[0:15]
	s_setprio 0
	s_setprio 2
	s_waitcnt vmcnt(11) lgkmcnt(3)
	v_mfma_f32_32x32x16_bf16 v[112:127], v[128:131], v[210:213], v[112:127]
	s_waitcnt lgkmcnt(2)
	v_mfma_f32_32x32x16_bf16 v[80:95], v[128:131], v[228:231], v[80:95]
	s_waitcnt lgkmcnt(1)
	v_mfma_f32_32x32x16_bf16 v[48:63], v[128:131], v[238:241], v[48:63]
	s_waitcnt lgkmcnt(0)
	v_mfma_f32_32x32x16_bf16 v[16:31], v[128:131], v[246:249], v[16:31]
	global_load_dwordx4 v[128:131], v[162:163], off offset:3072
	global_load_dwordx4 v[198:201], v[170:171], off offset:3072
	s_waitcnt vmcnt(12)
	v_mfma_f32_32x32x16_bf16 v[96:111], v[202:205], v[210:213], v[96:111]
	v_mfma_f32_32x32x16_bf16 v[64:79], v[202:205], v[228:231], v[64:79]
	v_mfma_f32_32x32x16_bf16 v[32:47], v[202:205], v[238:241], v[32:47]
	v_mfma_f32_32x32x16_bf16 v[0:15], v[202:205], v[246:249], v[0:15]
	s_setprio 0
	s_waitcnt vmcnt(8)
	ds_write_b128 v189, v[152:155] offset:18432
	ds_write_b128 v189, v[140:143] offset:23040
	ds_write_b128 v189, v[136:139] offset:27648
	ds_write_b128 v189, v[148:151] offset:32256
	global_load_dwordx4 v[136:139], v[156:157], off offset:1792
	global_load_dwordx4 v[140:143], v[164:165], off offset:1792
	global_load_dwordx4 v[148:151], v[180:181], off offset:1792
	global_load_dwordx4 v[152:155], v[172:173], off offset:1792
	s_waitcnt lgkmcnt(0)
	s_barrier
	ds_read_b128 v[202:205], v188 offset:18432
	ds_read_b128 v[210:213], v188 offset:18464
	ds_read_b128 v[218:221], v188 offset:23040
	ds_read_b128 v[228:231], v188 offset:23072
	ds_read_b128 v[234:237], v188 offset:27648
	ds_read_b128 v[238:241], v188 offset:27680
	ds_read_b128 v[242:245], v188 offset:32256
	ds_read_b128 v[246:249], v188 offset:32288
	s_setprio 2
	s_mov_b32 s1, 0xe000
	s_waitcnt vmcnt(11) lgkmcnt(7)
	v_mfma_f32_32x32x16_bf16 v[112:127], v[158:161], v[202:205], v[112:127]
	s_waitcnt lgkmcnt(5)
	v_mfma_f32_32x32x16_bf16 v[80:95], v[158:161], v[218:221], v[80:95]
	s_waitcnt lgkmcnt(3)
	v_mfma_f32_32x32x16_bf16 v[48:63], v[158:161], v[234:237], v[48:63]
	s_waitcnt lgkmcnt(1)
	v_mfma_f32_32x32x16_bf16 v[16:31], v[158:161], v[242:245], v[16:31]
	v_add_co_u32_e32 v158, vcc, s1, v178
	s_mov_b32 s1, 0x1e000
	s_nop 0
	v_addc_co_u32_e32 v159, vcc, 0, v179, vcc
	v_add_co_u32_e32 v170, vcc, s1, v178
	s_waitcnt vmcnt(10)
	v_mfma_f32_32x32x16_bf16 v[96:111], v[166:169], v[202:205], v[96:111]
	s_nop 0
	v_addc_co_u32_e32 v171, vcc, 0, v179, vcc
	global_load_dwordx4 v[160:163], v[158:159], off
	global_load_dwordx4 v[202:205], v[170:171], off
	v_mfma_f32_32x32x16_bf16 v[64:79], v[166:169], v[218:221], v[64:79]
	v_mfma_f32_32x32x16_bf16 v[32:47], v[166:169], v[234:237], v[32:47]
	v_mfma_f32_32x32x16_bf16 v[0:15], v[166:169], v[242:245], v[0:15]
	s_setprio 0
	ds_read_b128 v[166:169], v188 offset:18496
	ds_read_b128 v[218:221], v188 offset:23104
	ds_read_b128 v[234:237], v188 offset:27712
	ds_read_b128 v[242:245], v188 offset:32320
	s_setprio 2
	s_waitcnt vmcnt(11)
	v_mfma_f32_32x32x16_bf16 v[112:127], v[144:147], v[210:213], v[112:127]
	v_mfma_f32_32x32x16_bf16 v[80:95], v[144:147], v[228:231], v[80:95]
	v_mfma_f32_32x32x16_bf16 v[48:63], v[144:147], v[238:241], v[48:63]
	s_waitcnt lgkmcnt(4)
	v_mfma_f32_32x32x16_bf16 v[16:31], v[144:147], v[246:249], v[16:31]
	s_waitcnt vmcnt(10)
	v_mfma_f32_32x32x16_bf16 v[96:111], v[214:217], v[210:213], v[96:111]
	global_load_dwordx4 v[144:147], v[158:159], off offset:1024
	global_load_dwordx4 v[210:213], v[170:171], off offset:1024
	v_mfma_f32_32x32x16_bf16 v[64:79], v[214:217], v[228:231], v[64:79]
	v_mfma_f32_32x32x16_bf16 v[32:47], v[214:217], v[238:241], v[32:47]
	v_mfma_f32_32x32x16_bf16 v[0:15], v[214:217], v[246:249], v[0:15]
	s_setprio 0
	ds_read_b128 v[214:217], v188 offset:18528
	ds_read_b128 v[228:231], v188 offset:23136
	ds_read_b128 v[238:241], v188 offset:27744
	ds_read_b128 v[246:249], v188 offset:32352
	s_setprio 2
	s_waitcnt vmcnt(11) lgkmcnt(7)
	v_mfma_f32_32x32x16_bf16 v[112:127], v[132:135], v[166:169], v[112:127]
	s_waitcnt lgkmcnt(6)
	v_mfma_f32_32x32x16_bf16 v[80:95], v[132:135], v[218:221], v[80:95]
	s_waitcnt lgkmcnt(5)
	v_mfma_f32_32x32x16_bf16 v[48:63], v[132:135], v[234:237], v[48:63]
	s_waitcnt lgkmcnt(4)
	v_mfma_f32_32x32x16_bf16 v[16:31], v[132:135], v[242:245], v[16:31]
	s_waitcnt vmcnt(10)
	v_mfma_f32_32x32x16_bf16 v[64:79], v[206:209], v[218:221], v[64:79]
	global_load_dwordx4 v[132:135], v[158:159], off offset:2048
	global_load_dwordx4 v[218:221], v[170:171], off offset:2048
	v_mfma_f32_32x32x16_bf16 v[96:111], v[206:209], v[166:169], v[96:111]
	v_mfma_f32_32x32x16_bf16 v[32:47], v[206:209], v[234:237], v[32:47]
	v_mfma_f32_32x32x16_bf16 v[0:15], v[206:209], v[242:245], v[0:15]
	s_setprio 0
	s_setprio 2
	s_waitcnt vmcnt(11) lgkmcnt(3)
	v_mfma_f32_32x32x16_bf16 v[112:127], v[128:131], v[214:217], v[112:127]
	s_waitcnt lgkmcnt(2)
	v_mfma_f32_32x32x16_bf16 v[80:95], v[128:131], v[228:231], v[80:95]
	s_waitcnt lgkmcnt(1)
	v_mfma_f32_32x32x16_bf16 v[48:63], v[128:131], v[238:241], v[48:63]
	s_waitcnt lgkmcnt(0)
	v_mfma_f32_32x32x16_bf16 v[16:31], v[128:131], v[246:249], v[16:31]
	global_load_dwordx4 v[128:131], v[158:159], off offset:3072
	global_load_dwordx4 v[206:209], v[170:171], off offset:3072
	s_waitcnt vmcnt(12)
	v_mfma_f32_32x32x16_bf16 v[96:111], v[198:201], v[214:217], v[96:111]
	v_mfma_f32_32x32x16_bf16 v[64:79], v[198:201], v[228:231], v[64:79]
	v_mfma_f32_32x32x16_bf16 v[32:47], v[198:201], v[238:241], v[32:47]
	v_mfma_f32_32x32x16_bf16 v[0:15], v[198:201], v[246:249], v[0:15]
	s_setprio 0
	s_waitcnt vmcnt(9)
	ds_write_b128 v189, v[148:151]
	ds_write_b128 v189, v[136:139] offset:4608
	ds_write_b128 v189, v[140:143] offset:9216
	s_waitcnt vmcnt(8)
	ds_write_b128 v189, v[152:155] offset:13824
	global_load_dwordx4 v[156:159], v[156:157], off offset:1920
	s_nop 0
	global_load_dwordx4 v[164:167], v[164:165], off offset:1920
	s_nop 0
	global_load_dwordx4 v[168:171], v[180:181], off offset:1920
	s_nop 0
	global_load_dwordx4 v[172:175], v[172:173], off offset:1920
	s_waitcnt lgkmcnt(0)
	s_barrier
	ds_read_b128 v[136:139], v188
	ds_read_b128 v[140:143], v188 offset:32
	ds_read_b128 v[148:151], v188 offset:4608
	ds_read_b128 v[198:201], v188 offset:4640
	ds_read_b128 v[152:155], v188 offset:9216
	ds_read_b128 v[214:217], v188 offset:9248
	ds_read_b128 v[228:231], v188 offset:13824
	ds_read_b128 v[234:237], v188 offset:13856
	s_setprio 2
	s_mov_b32 s1, 0xf000
	v_add_co_u32_e32 v190, vcc, s1, v178
	s_mov_b32 s1, 0x1f000
	s_nop 0
	v_addc_co_u32_e32 v191, vcc, 0, v179, vcc
	v_add_co_u32_e32 v238, vcc, s1, v178
	s_waitcnt vmcnt(11) lgkmcnt(7)
	v_mfma_f32_32x32x16_bf16 v[112:127], v[160:163], v[136:139], v[112:127]
	v_addc_co_u32_e32 v239, vcc, 0, v179, vcc
	s_waitcnt lgkmcnt(5)
	v_mfma_f32_32x32x16_bf16 v[80:95], v[160:163], v[148:151], v[80:95]
	s_waitcnt lgkmcnt(3)
	v_mfma_f32_32x32x16_bf16 v[48:63], v[160:163], v[152:155], v[48:63]
	s_waitcnt lgkmcnt(1)
	v_mfma_f32_32x32x16_bf16 v[16:31], v[160:163], v[228:231], v[16:31]
	s_waitcnt vmcnt(10)
	v_mfma_f32_32x32x16_bf16 v[32:47], v[202:205], v[152:155], v[32:47]
	global_load_dwordx4 v[160:163], v[190:191], off
	global_load_dwordx4 v[152:155], v[238:239], off
	v_mfma_f32_32x32x16_bf16 v[96:111], v[202:205], v[136:139], v[96:111]
	v_mfma_f32_32x32x16_bf16 v[64:79], v[202:205], v[148:151], v[64:79]
	v_mfma_f32_32x32x16_bf16 v[0:15], v[202:205], v[228:231], v[0:15]
	s_setprio 0
	ds_read_b128 v[136:139], v188 offset:64
	ds_read_b128 v[178:181], v188 offset:4672
	ds_read_b128 v[202:205], v188 offset:9280
	ds_read_b128 v[228:231], v188 offset:13888
	s_setprio 2
	s_waitcnt vmcnt(11)
	v_mfma_f32_32x32x16_bf16 v[112:127], v[144:147], v[140:143], v[112:127]
	v_mfma_f32_32x32x16_bf16 v[80:95], v[144:147], v[198:201], v[80:95]
	v_mfma_f32_32x32x16_bf16 v[48:63], v[144:147], v[214:217], v[48:63]
	s_waitcnt lgkmcnt(4)
	v_mfma_f32_32x32x16_bf16 v[16:31], v[144:147], v[234:237], v[16:31]
	global_load_dwordx4 v[144:147], v[190:191], off offset:1024
	global_load_dwordx4 v[148:151], v[238:239], off offset:1024
	s_waitcnt vmcnt(12)
	v_mfma_f32_32x32x16_bf16 v[96:111], v[210:213], v[140:143], v[96:111]
	v_mfma_f32_32x32x16_bf16 v[64:79], v[210:213], v[198:201], v[64:79]
	v_mfma_f32_32x32x16_bf16 v[32:47], v[210:213], v[214:217], v[32:47]
	v_mfma_f32_32x32x16_bf16 v[0:15], v[210:213], v[234:237], v[0:15]
	s_setprio 0
	ds_read_b128 v[198:201], v188 offset:96
	ds_read_b128 v[210:213], v188 offset:4704
	ds_read_b128 v[214:217], v188 offset:9312
	ds_read_b128 v[234:237], v188 offset:13920
	s_setprio 2
	s_waitcnt vmcnt(11) lgkmcnt(7)
	v_mfma_f32_32x32x16_bf16 v[112:127], v[132:135], v[136:139], v[112:127]
	s_waitcnt lgkmcnt(6)
	v_mfma_f32_32x32x16_bf16 v[80:95], v[132:135], v[178:181], v[80:95]
	s_waitcnt lgkmcnt(5)
	v_mfma_f32_32x32x16_bf16 v[48:63], v[132:135], v[202:205], v[48:63]
	s_waitcnt lgkmcnt(4)
	v_mfma_f32_32x32x16_bf16 v[16:31], v[132:135], v[228:231], v[16:31]
	global_load_dwordx4 v[132:135], v[190:191], off offset:2048
	global_load_dwordx4 v[140:143], v[238:239], off offset:2048
	s_waitcnt vmcnt(12)
	v_mfma_f32_32x32x16_bf16 v[96:111], v[218:221], v[136:139], v[96:111]
	v_mfma_f32_32x32x16_bf16 v[64:79], v[218:221], v[178:181], v[64:79]
	v_mfma_f32_32x32x16_bf16 v[32:47], v[218:221], v[202:205], v[32:47]
	v_mfma_f32_32x32x16_bf16 v[0:15], v[218:221], v[228:231], v[0:15]
	s_setprio 0
	s_setprio 2
	s_waitcnt vmcnt(11) lgkmcnt(3)
	v_mfma_f32_32x32x16_bf16 v[112:127], v[128:131], v[198:201], v[112:127]
	s_waitcnt lgkmcnt(2)
	v_mfma_f32_32x32x16_bf16 v[80:95], v[128:131], v[210:213], v[80:95]
	s_waitcnt lgkmcnt(1)
	v_mfma_f32_32x32x16_bf16 v[48:63], v[128:131], v[214:217], v[48:63]
	s_waitcnt lgkmcnt(0)
	v_mfma_f32_32x32x16_bf16 v[16:31], v[128:131], v[234:237], v[16:31]
	global_load_dwordx4 v[128:131], v[190:191], off offset:3072
	global_load_dwordx4 v[136:139], v[238:239], off offset:3072
	s_waitcnt vmcnt(12)
	v_mfma_f32_32x32x16_bf16 v[96:111], v[206:209], v[198:201], v[96:111]
	v_mfma_f32_32x32x16_bf16 v[64:79], v[206:209], v[210:213], v[64:79]
	v_mfma_f32_32x32x16_bf16 v[32:47], v[206:209], v[214:217], v[32:47]
	v_mfma_f32_32x32x16_bf16 v[0:15], v[206:209], v[234:237], v[0:15]
	s_setprio 0
	s_waitcnt vmcnt(9)
	ds_write_b128 v189, v[168:171] offset:18432
	ds_write_b128 v189, v[156:159] offset:23040
	ds_write_b128 v189, v[164:167] offset:27648
	s_waitcnt vmcnt(8)
	ds_write_b128 v189, v[172:175] offset:32256
	s_waitcnt lgkmcnt(0)
	s_barrier
	ds_read_b128 v[178:181], v188 offset:18432
	ds_read_b128 v[198:201], v188 offset:18464
	ds_read_b128 v[202:205], v188 offset:23040
	ds_read_b128 v[206:209], v188 offset:23072
	ds_read_b128 v[210:213], v188 offset:27648
	ds_read_b128 v[214:217], v188 offset:27680
	ds_read_b128 v[218:221], v188 offset:32256
	ds_read_b128 v[228:231], v188 offset:32288
	s_setprio 2
	s_waitcnt vmcnt(7) lgkmcnt(7)
	v_mfma_f32_32x32x16_bf16 v[112:127], v[160:163], v[178:181], v[112:127]
	s_waitcnt lgkmcnt(5)
	v_mfma_f32_32x32x16_bf16 v[80:95], v[160:163], v[202:205], v[80:95]
	s_waitcnt lgkmcnt(3)
	v_mfma_f32_32x32x16_bf16 v[48:63], v[160:163], v[210:213], v[48:63]
	s_waitcnt lgkmcnt(1)
	v_mfma_f32_32x32x16_bf16 v[16:31], v[160:163], v[218:221], v[16:31]
	s_waitcnt vmcnt(6)
	v_mfma_f32_32x32x16_bf16 v[96:111], v[152:155], v[178:181], v[96:111]
	v_mfma_f32_32x32x16_bf16 v[64:79], v[152:155], v[202:205], v[64:79]
	v_mfma_f32_32x32x16_bf16 v[32:47], v[152:155], v[210:213], v[32:47]
	v_mfma_f32_32x32x16_bf16 v[0:15], v[152:155], v[218:221], v[0:15]
	s_setprio 0
	ds_read_b128 v[178:181], v188 offset:18496
	ds_read_b128 v[202:205], v188 offset:23104
	ds_read_b128 v[210:213], v188 offset:27712
	ds_read_b128 v[218:221], v188 offset:32320
	s_setprio 2
	s_waitcnt vmcnt(5)
	v_mfma_f32_32x32x16_bf16 v[112:127], v[144:147], v[198:201], v[112:127]
	v_mfma_f32_32x32x16_bf16 v[80:95], v[144:147], v[206:209], v[80:95]
	v_mfma_f32_32x32x16_bf16 v[48:63], v[144:147], v[214:217], v[48:63]
	s_waitcnt lgkmcnt(4)
	v_mfma_f32_32x32x16_bf16 v[16:31], v[144:147], v[228:231], v[16:31]
	s_waitcnt vmcnt(4)
	v_mfma_f32_32x32x16_bf16 v[96:111], v[148:151], v[198:201], v[96:111]
	v_mfma_f32_32x32x16_bf16 v[64:79], v[148:151], v[206:209], v[64:79]
	v_mfma_f32_32x32x16_bf16 v[32:47], v[148:151], v[214:217], v[32:47]
	v_mfma_f32_32x32x16_bf16 v[0:15], v[148:151], v[228:231], v[0:15]
	s_setprio 0
	ds_read_b128 v[198:201], v188 offset:18528
	ds_read_b128 v[206:209], v188 offset:23136
	ds_read_b128 v[214:217], v188 offset:27744
	ds_read_b128 v[188:191], v188 offset:32352
	s_setprio 2
	s_waitcnt vmcnt(3) lgkmcnt(7)
	v_mfma_f32_32x32x16_bf16 v[112:127], v[132:135], v[178:181], v[112:127]
	s_waitcnt lgkmcnt(6)
	v_mfma_f32_32x32x16_bf16 v[80:95], v[132:135], v[202:205], v[80:95]
	s_waitcnt lgkmcnt(5)
	v_mfma_f32_32x32x16_bf16 v[48:63], v[132:135], v[210:213], v[48:63]
	s_waitcnt lgkmcnt(4)
	v_mfma_f32_32x32x16_bf16 v[16:31], v[132:135], v[218:221], v[16:31]
	s_waitcnt vmcnt(2)
	v_mfma_f32_32x32x16_bf16 v[96:111], v[140:143], v[178:181], v[96:111]
	v_mfma_f32_32x32x16_bf16 v[64:79], v[140:143], v[202:205], v[64:79]
	v_mfma_f32_32x32x16_bf16 v[32:47], v[140:143], v[210:213], v[32:47]
	v_mfma_f32_32x32x16_bf16 v[0:15], v[140:143], v[218:221], v[0:15]
	s_setprio 0
	s_setprio 2
	s_waitcnt vmcnt(1) lgkmcnt(3)
	v_mfma_f32_32x32x16_bf16 v[112:127], v[128:131], v[198:201], v[112:127]
	s_waitcnt lgkmcnt(2)
	v_mfma_f32_32x32x16_bf16 v[80:95], v[128:131], v[206:209], v[80:95]
	s_waitcnt lgkmcnt(1)
	v_mfma_f32_32x32x16_bf16 v[48:63], v[128:131], v[214:217], v[48:63]
	s_waitcnt lgkmcnt(0)
	v_mfma_f32_32x32x16_bf16 v[16:31], v[128:131], v[188:191], v[16:31]
	s_waitcnt vmcnt(0)
	v_mfma_f32_32x32x16_bf16 v[96:111], v[136:139], v[198:201], v[96:111]
	v_mfma_f32_32x32x16_bf16 v[64:79], v[136:139], v[206:209], v[64:79]
	v_mfma_f32_32x32x16_bf16 v[32:47], v[136:139], v[214:217], v[32:47]
	v_mfma_f32_32x32x16_bf16 v[0:15], v[136:139], v[188:191], v[0:15]
	s_setprio 0
	s_cmp_gt_i32 s0, -1
	s_cselect_b64 s[22:23], -1, 0
	s_cmp_lt_i32 s0, 0
	s_barrier
	s_cbranch_scc1 .LBB0_273
	s_mov_b64 s[30:31], 0x3e38aa3b
	s_mov_b32 s1, s31
	s_lshl_b64 s[0:1], s[0:1], 18
	s_add_u32 s0, s26, s0
	s_addc_u32 s1, s27, s1
	v_lshl_add_u64 v[130:131], s[0:1], 0, v[176:177]
	s_mov_b32 s0, 0x10000
	v_add_co_u32_e32 v132, vcc, s0, v130
	v_lshl_add_u32 v128, s24, 3, v187
	s_nop 0
	v_addc_co_u32_e32 v133, vcc, 0, v131, vcc
	s_mov_b32 s1, 0x20000
	v_ashrrev_i32_e32 v129, 31, v128
	global_load_dwordx4 v[168:171], v[130:131], off
	global_load_dwordx4 v[156:159], v[132:133], off
	v_add_co_u32_e32 v132, vcc, s1, v130
	v_lshlrev_b64 v[128:129], 16, v[128:129]
	s_nop 0
	v_addc_co_u32_e32 v133, vcc, 0, v131, vcc
	s_mov_b32 s1, 0x30000
	v_lshl_add_u64 v[128:129], s[12:13], 0, v[128:129]
	v_add_co_u32_e32 v130, vcc, s1, v130
	v_lshl_add_u64 v[136:137], v[128:129], 0, v[192:193]
	s_nop 0
	v_addc_co_u32_e32 v131, vcc, 0, v131, vcc
	global_load_dwordx4 v[164:167], v[132:133], off
	global_load_dwordx4 v[172:175], v[130:131], off
	global_load_dwordx4 v[160:163], v[136:137], off
	global_load_dwordx4 v[144:147], v[136:137], off offset:1024
	s_nop 0
	global_load_dwordx4 v[132:135], v[136:137], off offset:2048
	global_load_dwordx4 v[128:131], v[136:137], off offset:3072
	v_add_co_u32_e32 v136, vcc, s0, v136
	s_nop 1
	v_addc_co_u32_e32 v137, vcc, 0, v137, vcc
	global_load_dwordx4 v[152:155], v[136:137], off
	global_load_dwordx4 v[148:151], v[136:137], off offset:1024
	global_load_dwordx4 v[140:143], v[136:137], off offset:2048
	s_nop 0
	global_load_dwordx4 v[136:139], v[136:137], off offset:3072
.LBB0_273:
	v_and_b32_e32 v176, 0xffffffc0, v183
	v_lshl_add_u32 v176, s9, 8, v176
	s_movk_i32 s0, 0xe80
	v_cmp_gt_i32_e32 vcc, s0, v176
	s_and_saveexec_b64 s[24:25], vcc
	s_cbranch_execz .LBB0_290
	v_subrev_u32_e32 v177, s8, v184
	v_add_u32_e32 v178, s11, v177
	v_ashrrev_i32_e32 v179, 31, v178
	v_lshl_add_u64 v[180:181], v[178:179], 2, s[14:15]
	global_load_dword v218, v[180:181], off
	global_load_dword v220, v[180:181], off offset:128
	global_load_dword v228, v[180:181], off offset:256
	global_load_dword v230, v[180:181], off offset:384
	s_movk_i32 s0, 0x1ff
	v_cmp_lt_i32_e32 vcc, s0, v176
	v_add_u32_e32 v177, 0xfffff980, v176
	s_movk_i32 s0, 0x13f
	v_cmp_lt_u32_e64 s[0:1], s0, v177
	v_and_b32_e32 v177, 0xffffff40, v176
	s_movk_i32 s8, 0x800
	v_cmp_ne_u32_e64 s[8:9], s8, v177
	s_and_b64 s[0:1], s[0:1], s[8:9]
	s_and_b64 s[0:1], vcc, s[0:1]
	v_cmp_gt_u32_e32 vcc, 32, v182
	v_mov_b64_e32 v[180:181], s[16:17]
	s_movk_i32 s8, 0x1d00
	v_ashrrev_i32_e32 v177, 31, v176
	v_cndmask_b32_e64 v179, 8, 0, vcc
	v_mad_i64_i32 v[180:181], s[8:9], v178, s8, v[180:181]
	v_lshl_add_u64 v[182:183], v[176:177], 1, v[180:181]
	v_lshlrev_b32_e32 v192, 1, v179
	v_lshl_add_u64 v[182:183], v[182:183], 0, v[192:193]
	s_mov_b64 s[8:9], 0x3a000
	s_and_b64 vcc, exec, s[0:1]
	s_cbranch_vccnz .Lep1_plain
	v_lshlrev_b32_e32 v186, 5, v178
	v_ashrrev_i32_e32 v187, 31, v186
	v_lshl_add_u64 v[186:187], v[186:187], 2, s[18:19]
	v_lshl_add_u64 v[186:187], v[186:187], 0, v[192:193]
	v_add_co_u32_e32 v188, vcc, 0x1000, v186
	s_nop 1
	v_addc_co_u32_e32 v189, vcc, 0, v187, vcc
	v_add_co_u32_e32 v190, vcc, 0x3000, v186
	s_nop 1
	v_addc_co_u32_e32 v191, vcc, 0, v187, vcc
	global_load_dwordx4 v[202:205], v[188:189], off offset:-4096
	global_load_dwordx4 v[206:209], v[188:189], off offset:-4064
	global_load_dwordx4 v[210:213], v[188:189], off offset:-4032
	global_load_dwordx4 v[214:217], v[188:189], off offset:-4000
	global_load_dwordx4 v[234:237], v[188:189], off
	global_load_dwordx4 v[238:241], v[188:189], off offset:32
	global_load_dwordx4 v[242:245], v[188:189], off offset:64
	global_load_dwordx4 v[246:249], v[188:189], off offset:96
	s_waitcnt vmcnt(11)
	v_pk_mul_f32 v[112:113], v[112:113], v[218:219] op_sel_hi:[1,0]
	v_pk_mul_f32 v[96:97], v[96:97], v[218:219] op_sel_hi:[1,0]
	s_waitcnt vmcnt(7)
	v_lshlrev_b32_e32 v198, 16, v202
	v_lshlrev_b32_e32 v199, 16, v203
	v_and_b32_e32 v202, 0xffff0000, v202
	v_and_b32_e32 v203, 0xffff0000, v203
	v_pk_mul_f32 v[200:201], v[96:97], v[202:203]
	v_pk_mul_f32 v[96:97], v[96:97], v[198:199]
	v_pk_fma_f32 v[200:201], v[112:113], v[198:199], v[200:201] neg_lo:[0,0,1] neg_hi:[0,0,1]
	v_pk_fma_f32 v[96:97], v[112:113], v[202:203], v[96:97]
	v_pk_mul_f32 v[114:115], v[114:115], v[218:219] op_sel_hi:[1,0]
	v_pk_mul_f32 v[98:99], v[98:99], v[218:219] op_sel_hi:[1,0]
	v_lshlrev_b32_e32 v198, 16, v204
	v_lshlrev_b32_e32 v199, 16, v205
	v_and_b32_e32 v204, 0xffff0000, v204
	v_and_b32_e32 v205, 0xffff0000, v205
	v_pk_mul_f32 v[176:177], v[98:99], v[204:205]
	v_pk_mul_f32 v[98:99], v[98:99], v[198:199]
	v_pk_fma_f32 v[176:177], v[114:115], v[198:199], v[176:177] neg_lo:[0,0,1] neg_hi:[0,0,1]
	v_pk_fma_f32 v[98:99], v[114:115], v[204:205], v[98:99]
	v_pk_mul_f32 v[116:117], v[116:117], v[218:219] op_sel_hi:[1,0]
	v_pk_mul_f32 v[100:101], v[100:101], v[218:219] op_sel_hi:[1,0]
	s_waitcnt vmcnt(6)
	v_lshlrev_b32_e32 v198, 16, v206
	v_lshlrev_b32_e32 v199, 16, v207
	v_and_b32_e32 v206, 0xffff0000, v206
	v_and_b32_e32 v207, 0xffff0000, v207
	v_pk_mul_f32 v[178:179], v[100:101], v[206:207]
	v_pk_mul_f32 v[100:101], v[100:101], v[198:199]
	v_pk_fma_f32 v[178:179], v[116:117], v[198:199], v[178:179] neg_lo:[0,0,1] neg_hi:[0,0,1]
	v_pk_fma_f32 v[100:101], v[116:117], v[206:207], v[100:101]
	v_pk_mul_f32 v[118:119], v[118:119], v[218:219] op_sel_hi:[1,0]
	v_pk_mul_f32 v[102:103], v[102:103], v[218:219] op_sel_hi:[1,0]
	v_lshlrev_b32_e32 v198, 16, v208
	v_lshlrev_b32_e32 v199, 16, v209
	v_and_b32_e32 v208, 0xffff0000, v208
	v_and_b32_e32 v209, 0xffff0000, v209
	v_pk_mul_f32 v[180:181], v[102:103], v[208:209]
	v_pk_mul_f32 v[102:103], v[102:103], v[198:199]
	v_pk_fma_f32 v[180:181], v[118:119], v[198:199], v[180:181] neg_lo:[0,0,1] neg_hi:[0,0,1]
	v_pk_fma_f32 v[102:103], v[118:119], v[208:209], v[102:103]
	v_cvt_pk_bf16_f32 v112, v200, v201
	v_cvt_pk_bf16_f32 v113, v176, v177
	v_cvt_pk_bf16_f32 v114, v178, v179
	v_cvt_pk_bf16_f32 v115, v180, v181
	v_cvt_pk_bf16_f32 v116, v96, v97
	v_cvt_pk_bf16_f32 v117, v98, v99
	v_cvt_pk_bf16_f32 v118, v100, v101
	v_cvt_pk_bf16_f32 v119, v102, v103
	v_permlane32_swap_b32_e32 v112, v114
	v_permlane32_swap_b32_e32 v113, v115
	v_permlane32_swap_b32_e32 v116, v118
	v_permlane32_swap_b32_e32 v117, v119
	global_store_dwordx4 v[182:183], v[112:115], off
	global_store_dwordx4 v[182:183], v[116:119], off offset:64
	v_pk_mul_f32 v[120:121], v[120:121], v[218:219] op_sel_hi:[1,0]
	v_pk_mul_f32 v[104:105], v[104:105], v[218:219] op_sel_hi:[1,0]
	s_waitcnt vmcnt(7)
	v_lshlrev_b32_e32 v198, 16, v210
	v_lshlrev_b32_e32 v199, 16, v211
	v_and_b32_e32 v210, 0xffff0000, v210
	v_and_b32_e32 v211, 0xffff0000, v211
	v_pk_mul_f32 v[200:201], v[104:105], v[210:211]
	v_pk_mul_f32 v[104:105], v[104:105], v[198:199]
	v_pk_fma_f32 v[200:201], v[120:121], v[198:199], v[200:201] neg_lo:[0,0,1] neg_hi:[0,0,1]
	v_pk_fma_f32 v[104:105], v[120:121], v[210:211], v[104:105]
	v_pk_mul_f32 v[122:123], v[122:123], v[218:219] op_sel_hi:[1,0]
	v_pk_mul_f32 v[106:107], v[106:107], v[218:219] op_sel_hi:[1,0]
	v_lshlrev_b32_e32 v198, 16, v212
	v_lshlrev_b32_e32 v199, 16, v213
	v_and_b32_e32 v212, 0xffff0000, v212
	v_and_b32_e32 v213, 0xffff0000, v213
	v_pk_mul_f32 v[176:177], v[106:107], v[212:213]
	v_pk_mul_f32 v[106:107], v[106:107], v[198:199]
	v_pk_fma_f32 v[176:177], v[122:123], v[198:199], v[176:177] neg_lo:[0,0,1] neg_hi:[0,0,1]
	v_pk_fma_f32 v[106:107], v[122:123], v[212:213], v[106:107]
	v_pk_mul_f32 v[124:125], v[124:125], v[218:219] op_sel_hi:[1,0]
	v_pk_mul_f32 v[108:109], v[108:109], v[218:219] op_sel_hi:[1,0]
	s_waitcnt vmcnt(6)
	v_lshlrev_b32_e32 v198, 16, v214
	v_lshlrev_b32_e32 v199, 16, v215
	v_and_b32_e32 v214, 0xffff0000, v214
	v_and_b32_e32 v215, 0xffff0000, v215
	v_pk_mul_f32 v[178:179], v[108:109], v[214:215]
	v_pk_mul_f32 v[108:109], v[108:109], v[198:199]
	v_pk_fma_f32 v[178:179], v[124:125], v[198:199], v[178:179] neg_lo:[0,0,1] neg_hi:[0,0,1]
	v_pk_fma_f32 v[108:109], v[124:125], v[214:215], v[108:109]
	v_pk_mul_f32 v[126:127], v[126:127], v[218:219] op_sel_hi:[1,0]
	v_pk_mul_f32 v[110:111], v[110:111], v[218:219] op_sel_hi:[1,0]
	v_lshlrev_b32_e32 v198, 16, v216
	v_lshlrev_b32_e32 v199, 16, v217
	v_and_b32_e32 v216, 0xffff0000, v216
	v_and_b32_e32 v217, 0xffff0000, v217
	v_pk_mul_f32 v[180:181], v[110:111], v[216:217]
	v_pk_mul_f32 v[110:111], v[110:111], v[198:199]
	v_pk_fma_f32 v[180:181], v[126:127], v[198:199], v[180:181] neg_lo:[0,0,1] neg_hi:[0,0,1]
	v_pk_fma_f32 v[110:111], v[126:127], v[216:217], v[110:111]
	global_load_dwordx4 v[202:205], v[190:191], off offset:-4096
	global_load_dwordx4 v[206:209], v[190:191], off offset:-4064
	global_load_dwordx4 v[210:213], v[190:191], off offset:-4032
	global_load_dwordx4 v[214:217], v[190:191], off offset:-4000
	v_cvt_pk_bf16_f32 v120, v200, v201
	v_cvt_pk_bf16_f32 v121, v176, v177
	v_cvt_pk_bf16_f32 v122, v178, v179
	v_cvt_pk_bf16_f32 v123, v180, v181
	v_cvt_pk_bf16_f32 v124, v104, v105
	v_cvt_pk_bf16_f32 v125, v106, v107
	v_cvt_pk_bf16_f32 v126, v108, v109
	v_cvt_pk_bf16_f32 v127, v110, v111
	v_permlane32_swap_b32_e32 v120, v122
	v_permlane32_swap_b32_e32 v121, v123
	v_permlane32_swap_b32_e32 v124, v126
	v_permlane32_swap_b32_e32 v125, v127
	global_store_dwordx4 v[182:183], v[120:123], off offset:32
	global_store_dwordx4 v[182:183], v[124:127], off offset:96
	v_lshl_add_u64 v[182:183], v[182:183], 0, s[8:9]
	v_pk_mul_f32 v[80:81], v[80:81], v[220:221] op_sel_hi:[1,0]
	v_pk_mul_f32 v[64:65], v[64:65], v[220:221] op_sel_hi:[1,0]
	s_waitcnt vmcnt(11)
	v_lshlrev_b32_e32 v198, 16, v234
	v_lshlrev_b32_e32 v199, 16, v235
	v_and_b32_e32 v234, 0xffff0000, v234
	v_and_b32_e32 v235, 0xffff0000, v235
	v_pk_mul_f32 v[200:201], v[64:65], v[234:235]
	v_pk_mul_f32 v[64:65], v[64:65], v[198:199]
	v_pk_fma_f32 v[200:201], v[80:81], v[198:199], v[200:201] neg_lo:[0,0,1] neg_hi:[0,0,1]
	v_pk_fma_f32 v[64:65], v[80:81], v[234:235], v[64:65]
	v_pk_mul_f32 v[82:83], v[82:83], v[220:221] op_sel_hi:[1,0]
	v_pk_mul_f32 v[66:67], v[66:67], v[220:221] op_sel_hi:[1,0]
	v_lshlrev_b32_e32 v198, 16, v236
	v_lshlrev_b32_e32 v199, 16, v237
	v_and_b32_e32 v236, 0xffff0000, v236
	v_and_b32_e32 v237, 0xffff0000, v237
	v_pk_mul_f32 v[176:177], v[66:67], v[236:237]
	v_pk_mul_f32 v[66:67], v[66:67], v[198:199]
	v_pk_fma_f32 v[176:177], v[82:83], v[198:199], v[176:177] neg_lo:[0,0,1] neg_hi:[0,0,1]
	v_pk_fma_f32 v[66:67], v[82:83], v[236:237], v[66:67]
	v_pk_mul_f32 v[84:85], v[84:85], v[220:221] op_sel_hi:[1,0]
	v_pk_mul_f32 v[68:69], v[68:69], v[220:221] op_sel_hi:[1,0]
	s_waitcnt vmcnt(10)
	v_lshlrev_b32_e32 v198, 16, v238
	v_lshlrev_b32_e32 v199, 16, v239
	v_and_b32_e32 v238, 0xffff0000, v238
	v_and_b32_e32 v239, 0xffff0000, v239
	v_pk_mul_f32 v[178:179], v[68:69], v[238:239]
	v_pk_mul_f32 v[68:69], v[68:69], v[198:199]
	v_pk_fma_f32 v[178:179], v[84:85], v[198:199], v[178:179] neg_lo:[0,0,1] neg_hi:[0,0,1]
	v_pk_fma_f32 v[68:69], v[84:85], v[238:239], v[68:69]
	v_pk_mul_f32 v[86:87], v[86:87], v[220:221] op_sel_hi:[1,0]
	v_pk_mul_f32 v[70:71], v[70:71], v[220:221] op_sel_hi:[1,0]
	v_lshlrev_b32_e32 v198, 16, v240
	v_lshlrev_b32_e32 v199, 16, v241
	v_and_b32_e32 v240, 0xffff0000, v240
	v_and_b32_e32 v241, 0xffff0000, v241
	v_pk_mul_f32 v[180:181], v[70:71], v[240:241]
	v_pk_mul_f32 v[70:71], v[70:71], v[198:199]
	v_pk_fma_f32 v[180:181], v[86:87], v[198:199], v[180:181] neg_lo:[0,0,1] neg_hi:[0,0,1]
	v_pk_fma_f32 v[70:71], v[86:87], v[240:241], v[70:71]
	v_cvt_pk_bf16_f32 v80, v200, v201
	v_cvt_pk_bf16_f32 v81, v176, v177
	v_cvt_pk_bf16_f32 v82, v178, v179
	v_cvt_pk_bf16_f32 v83, v180, v181
	v_cvt_pk_bf16_f32 v84, v64, v65
	v_cvt_pk_bf16_f32 v85, v66, v67
	v_cvt_pk_bf16_f32 v86, v68, v69
	v_cvt_pk_bf16_f32 v87, v70, v71
	v_permlane32_swap_b32_e32 v80, v82
	v_permlane32_swap_b32_e32 v81, v83
	v_permlane32_swap_b32_e32 v84, v86
	v_permlane32_swap_b32_e32 v85, v87
	global_store_dwordx4 v[182:183], v[80:83], off
	global_store_dwordx4 v[182:183], v[84:87], off offset:64
	v_pk_mul_f32 v[88:89], v[88:89], v[220:221] op_sel_hi:[1,0]
	v_pk_mul_f32 v[72:73], v[72:73], v[220:221] op_sel_hi:[1,0]
	s_waitcnt vmcnt(11)
	v_lshlrev_b32_e32 v198, 16, v242
	v_lshlrev_b32_e32 v199, 16, v243
	v_and_b32_e32 v242, 0xffff0000, v242
	v_and_b32_e32 v243, 0xffff0000, v243
	v_pk_mul_f32 v[200:201], v[72:73], v[242:243]
	v_pk_mul_f32 v[72:73], v[72:73], v[198:199]
	v_pk_fma_f32 v[200:201], v[88:89], v[198:199], v[200:201] neg_lo:[0,0,1] neg_hi:[0,0,1]
	v_pk_fma_f32 v[72:73], v[88:89], v[242:243], v[72:73]
	v_pk_mul_f32 v[90:91], v[90:91], v[220:221] op_sel_hi:[1,0]
	v_pk_mul_f32 v[74:75], v[74:75], v[220:221] op_sel_hi:[1,0]
	v_lshlrev_b32_e32 v198, 16, v244
	v_lshlrev_b32_e32 v199, 16, v245
	v_and_b32_e32 v244, 0xffff0000, v244
	v_and_b32_e32 v245, 0xffff0000, v245
	v_pk_mul_f32 v[176:177], v[74:75], v[244:245]
	v_pk_mul_f32 v[74:75], v[74:75], v[198:199]
	v_pk_fma_f32 v[176:177], v[90:91], v[198:199], v[176:177] neg_lo:[0,0,1] neg_hi:[0,0,1]
	v_pk_fma_f32 v[74:75], v[90:91], v[244:245], v[74:75]
	v_pk_mul_f32 v[92:93], v[92:93], v[220:221] op_sel_hi:[1,0]
	v_pk_mul_f32 v[76:77], v[76:77], v[220:221] op_sel_hi:[1,0]
	s_waitcnt vmcnt(10)
	v_lshlrev_b32_e32 v198, 16, v246
	v_lshlrev_b32_e32 v199, 16, v247
	v_and_b32_e32 v246, 0xffff0000, v246
	v_and_b32_e32 v247, 0xffff0000, v247
	v_pk_mul_f32 v[178:179], v[76:77], v[246:247]
	v_pk_mul_f32 v[76:77], v[76:77], v[198:199]
	v_pk_fma_f32 v[178:179], v[92:93], v[198:199], v[178:179] neg_lo:[0,0,1] neg_hi:[0,0,1]
	v_pk_fma_f32 v[76:77], v[92:93], v[246:247], v[76:77]
	v_pk_mul_f32 v[94:95], v[94:95], v[220:221] op_sel_hi:[1,0]
	v_pk_mul_f32 v[78:79], v[78:79], v[220:221] op_sel_hi:[1,0]
	v_lshlrev_b32_e32 v198, 16, v248
	v_lshlrev_b32_e32 v199, 16, v249
	v_and_b32_e32 v248, 0xffff0000, v248
	v_and_b32_e32 v249, 0xffff0000, v249
	v_pk_mul_f32 v[180:181], v[78:79], v[248:249]
	v_pk_mul_f32 v[78:79], v[78:79], v[198:199]
	v_pk_fma_f32 v[180:181], v[94:95], v[198:199], v[180:181] neg_lo:[0,0,1] neg_hi:[0,0,1]
	v_pk_fma_f32 v[78:79], v[94:95], v[248:249], v[78:79]
	global_load_dwordx4 v[234:237], v[190:191], off
	global_load_dwordx4 v[238:241], v[190:191], off offset:32
	global_load_dwordx4 v[242:245], v[190:191], off offset:64
	global_load_dwordx4 v[246:249], v[190:191], off offset:96
	v_cvt_pk_bf16_f32 v88, v200, v201
	v_cvt_pk_bf16_f32 v89, v176, v177
	v_cvt_pk_bf16_f32 v90, v178, v179
	v_cvt_pk_bf16_f32 v91, v180, v181
	v_cvt_pk_bf16_f32 v92, v72, v73
	v_cvt_pk_bf16_f32 v93, v74, v75
	v_cvt_pk_bf16_f32 v94, v76, v77
	v_cvt_pk_bf16_f32 v95, v78, v79
	v_permlane32_swap_b32_e32 v88, v90
	v_permlane32_swap_b32_e32 v89, v91
	v_permlane32_swap_b32_e32 v92, v94
	v_permlane32_swap_b32_e32 v93, v95
	global_store_dwordx4 v[182:183], v[88:91], off offset:32
	global_store_dwordx4 v[182:183], v[92:95], off offset:96
	v_lshl_add_u64 v[182:183], v[182:183], 0, s[8:9]
	v_pk_mul_f32 v[48:49], v[48:49], v[228:229] op_sel_hi:[1,0]
	v_pk_mul_f32 v[32:33], v[32:33], v[228:229] op_sel_hi:[1,0]
	s_waitcnt vmcnt(13)
	v_lshlrev_b32_e32 v198, 16, v202
	v_lshlrev_b32_e32 v199, 16, v203
	v_and_b32_e32 v202, 0xffff0000, v202
	v_and_b32_e32 v203, 0xffff0000, v203
	v_pk_mul_f32 v[200:201], v[32:33], v[202:203]
	v_pk_mul_f32 v[32:33], v[32:33], v[198:199]
	v_pk_fma_f32 v[200:201], v[48:49], v[198:199], v[200:201] neg_lo:[0,0,1] neg_hi:[0,0,1]
	v_pk_fma_f32 v[32:33], v[48:49], v[202:203], v[32:33]
	v_pk_mul_f32 v[50:51], v[50:51], v[228:229] op_sel_hi:[1,0]
	v_pk_mul_f32 v[34:35], v[34:35], v[228:229] op_sel_hi:[1,0]
	v_lshlrev_b32_e32 v198, 16, v204
	v_lshlrev_b32_e32 v199, 16, v205
	v_and_b32_e32 v204, 0xffff0000, v204
	v_and_b32_e32 v205, 0xffff0000, v205
	v_pk_mul_f32 v[176:177], v[34:35], v[204:205]
	v_pk_mul_f32 v[34:35], v[34:35], v[198:199]
	v_pk_fma_f32 v[176:177], v[50:51], v[198:199], v[176:177] neg_lo:[0,0,1] neg_hi:[0,0,1]
	v_pk_fma_f32 v[34:35], v[50:51], v[204:205], v[34:35]
	v_pk_mul_f32 v[52:53], v[52:53], v[228:229] op_sel_hi:[1,0]
	v_pk_mul_f32 v[36:37], v[36:37], v[228:229] op_sel_hi:[1,0]
	s_waitcnt vmcnt(12)
	v_lshlrev_b32_e32 v198, 16, v206
	v_lshlrev_b32_e32 v199, 16, v207
	v_and_b32_e32 v206, 0xffff0000, v206
	v_and_b32_e32 v207, 0xffff0000, v207
	v_pk_mul_f32 v[178:179], v[36:37], v[206:207]
	v_pk_mul_f32 v[36:37], v[36:37], v[198:199]
	v_pk_fma_f32 v[178:179], v[52:53], v[198:199], v[178:179] neg_lo:[0,0,1] neg_hi:[0,0,1]
	v_pk_fma_f32 v[36:37], v[52:53], v[206:207], v[36:37]
	v_pk_mul_f32 v[54:55], v[54:55], v[228:229] op_sel_hi:[1,0]
	v_pk_mul_f32 v[38:39], v[38:39], v[228:229] op_sel_hi:[1,0]
	v_lshlrev_b32_e32 v198, 16, v208
	v_lshlrev_b32_e32 v199, 16, v209
	v_and_b32_e32 v208, 0xffff0000, v208
	v_and_b32_e32 v209, 0xffff0000, v209
	v_pk_mul_f32 v[180:181], v[38:39], v[208:209]
	v_pk_mul_f32 v[38:39], v[38:39], v[198:199]
	v_pk_fma_f32 v[180:181], v[54:55], v[198:199], v[180:181] neg_lo:[0,0,1] neg_hi:[0,0,1]
	v_pk_fma_f32 v[38:39], v[54:55], v[208:209], v[38:39]
	v_cvt_pk_bf16_f32 v48, v200, v201
	v_cvt_pk_bf16_f32 v49, v176, v177
	v_cvt_pk_bf16_f32 v50, v178, v179
	v_cvt_pk_bf16_f32 v51, v180, v181
	v_cvt_pk_bf16_f32 v52, v32, v33
	v_cvt_pk_bf16_f32 v53, v34, v35
	v_cvt_pk_bf16_f32 v54, v36, v37
	v_cvt_pk_bf16_f32 v55, v38, v39
	v_permlane32_swap_b32_e32 v48, v50
	v_permlane32_swap_b32_e32 v49, v51
	v_permlane32_swap_b32_e32 v52, v54
	v_permlane32_swap_b32_e32 v53, v55
	global_store_dwordx4 v[182:183], v[48:51], off
	global_store_dwordx4 v[182:183], v[52:55], off offset:64
	v_pk_mul_f32 v[56:57], v[56:57], v[228:229] op_sel_hi:[1,0]
	v_pk_mul_f32 v[40:41], v[40:41], v[228:229] op_sel_hi:[1,0]
	s_waitcnt vmcnt(13)
	v_lshlrev_b32_e32 v198, 16, v210
	v_lshlrev_b32_e32 v199, 16, v211
	v_and_b32_e32 v210, 0xffff0000, v210
	v_and_b32_e32 v211, 0xffff0000, v211
	v_pk_mul_f32 v[200:201], v[40:41], v[210:211]
	v_pk_mul_f32 v[40:41], v[40:41], v[198:199]
	v_pk_fma_f32 v[200:201], v[56:57], v[198:199], v[200:201] neg_lo:[0,0,1] neg_hi:[0,0,1]
	v_pk_fma_f32 v[40:41], v[56:57], v[210:211], v[40:41]
	v_pk_mul_f32 v[58:59], v[58:59], v[228:229] op_sel_hi:[1,0]
	v_pk_mul_f32 v[42:43], v[42:43], v[228:229] op_sel_hi:[1,0]
	v_lshlrev_b32_e32 v198, 16, v212
	v_lshlrev_b32_e32 v199, 16, v213
	v_and_b32_e32 v212, 0xffff0000, v212
	v_and_b32_e32 v213, 0xffff0000, v213
	v_pk_mul_f32 v[176:177], v[42:43], v[212:213]
	v_pk_mul_f32 v[42:43], v[42:43], v[198:199]
	v_pk_fma_f32 v[176:177], v[58:59], v[198:199], v[176:177] neg_lo:[0,0,1] neg_hi:[0,0,1]
	v_pk_fma_f32 v[42:43], v[58:59], v[212:213], v[42:43]
	v_pk_mul_f32 v[60:61], v[60:61], v[228:229] op_sel_hi:[1,0]
	v_pk_mul_f32 v[44:45], v[44:45], v[228:229] op_sel_hi:[1,0]
	s_waitcnt vmcnt(12)
	v_lshlrev_b32_e32 v198, 16, v214
	v_lshlrev_b32_e32 v199, 16, v215
	v_and_b32_e32 v214, 0xffff0000, v214
	v_and_b32_e32 v215, 0xffff0000, v215
	v_pk_mul_f32 v[178:179], v[44:45], v[214:215]
	v_pk_mul_f32 v[44:45], v[44:45], v[198:199]
	v_pk_fma_f32 v[178:179], v[60:61], v[198:199], v[178:179] neg_lo:[0,0,1] neg_hi:[0,0,1]
	v_pk_fma_f32 v[44:45], v[60:61], v[214:215], v[44:45]
	v_pk_mul_f32 v[62:63], v[62:63], v[228:229] op_sel_hi:[1,0]
	v_pk_mul_f32 v[46:47], v[46:47], v[228:229] op_sel_hi:[1,0]
	v_lshlrev_b32_e32 v198, 16, v216
	v_lshlrev_b32_e32 v199, 16, v217
	v_and_b32_e32 v216, 0xffff0000, v216
	v_and_b32_e32 v217, 0xffff0000, v217
	v_pk_mul_f32 v[180:181], v[46:47], v[216:217]
	v_pk_mul_f32 v[46:47], v[46:47], v[198:199]
	v_pk_fma_f32 v[180:181], v[62:63], v[198:199], v[180:181] neg_lo:[0,0,1] neg_hi:[0,0,1]
	v_pk_fma_f32 v[46:47], v[62:63], v[216:217], v[46:47]
	v_cvt_pk_bf16_f32 v56, v200, v201
	v_cvt_pk_bf16_f32 v57, v176, v177
	v_cvt_pk_bf16_f32 v58, v178, v179
	v_cvt_pk_bf16_f32 v59, v180, v181
	v_cvt_pk_bf16_f32 v60, v40, v41
	v_cvt_pk_bf16_f32 v61, v42, v43
	v_cvt_pk_bf16_f32 v62, v44, v45
	v_cvt_pk_bf16_f32 v63, v46, v47
	v_permlane32_swap_b32_e32 v56, v58
	v_permlane32_swap_b32_e32 v57, v59
	v_permlane32_swap_b32_e32 v60, v62
	v_permlane32_swap_b32_e32 v61, v63
	global_store_dwordx4 v[182:183], v[56:59], off offset:32
	global_store_dwordx4 v[182:183], v[60:63], off offset:96
	v_lshl_add_u64 v[182:183], v[182:183], 0, s[8:9]
	v_pk_mul_f32 v[16:17], v[16:17], v[230:231] op_sel_hi:[1,0]
	v_pk_mul_f32 v[0:1], v[0:1], v[230:231] op_sel_hi:[1,0]
	s_waitcnt vmcnt(9)
	v_lshlrev_b32_e32 v198, 16, v234
	v_lshlrev_b32_e32 v199, 16, v235
	v_and_b32_e32 v234, 0xffff0000, v234
	v_and_b32_e32 v235, 0xffff0000, v235
	v_pk_mul_f32 v[200:201], v[0:1], v[234:235]
	v_pk_mul_f32 v[0:1], v[0:1], v[198:199]
	v_pk_fma_f32 v[200:201], v[16:17], v[198:199], v[200:201] neg_lo:[0,0,1] neg_hi:[0,0,1]
	v_pk_fma_f32 v[0:1], v[16:17], v[234:235], v[0:1]
	v_pk_mul_f32 v[18:19], v[18:19], v[230:231] op_sel_hi:[1,0]
	v_pk_mul_f32 v[2:3], v[2:3], v[230:231] op_sel_hi:[1,0]
	v_lshlrev_b32_e32 v198, 16, v236
	v_lshlrev_b32_e32 v199, 16, v237
	v_and_b32_e32 v236, 0xffff0000, v236
	v_and_b32_e32 v237, 0xffff0000, v237
	v_pk_mul_f32 v[176:177], v[2:3], v[236:237]
	v_pk_mul_f32 v[2:3], v[2:3], v[198:199]
	v_pk_fma_f32 v[176:177], v[18:19], v[198:199], v[176:177] neg_lo:[0,0,1] neg_hi:[0,0,1]
	v_pk_fma_f32 v[2:3], v[18:19], v[236:237], v[2:3]
	v_pk_mul_f32 v[20:21], v[20:21], v[230:231] op_sel_hi:[1,0]
	v_pk_mul_f32 v[4:5], v[4:5], v[230:231] op_sel_hi:[1,0]
	s_waitcnt vmcnt(8)
	v_lshlrev_b32_e32 v198, 16, v238
	v_lshlrev_b32_e32 v199, 16, v239
	v_and_b32_e32 v238, 0xffff0000, v238
	v_and_b32_e32 v239, 0xffff0000, v239
	v_pk_mul_f32 v[178:179], v[4:5], v[238:239]
	v_pk_mul_f32 v[4:5], v[4:5], v[198:199]
	v_pk_fma_f32 v[178:179], v[20:21], v[198:199], v[178:179] neg_lo:[0,0,1] neg_hi:[0,0,1]
	v_pk_fma_f32 v[4:5], v[20:21], v[238:239], v[4:5]
	v_pk_mul_f32 v[22:23], v[22:23], v[230:231] op_sel_hi:[1,0]
	v_pk_mul_f32 v[6:7], v[6:7], v[230:231] op_sel_hi:[1,0]
	v_lshlrev_b32_e32 v198, 16, v240
	v_lshlrev_b32_e32 v199, 16, v241
	v_and_b32_e32 v240, 0xffff0000, v240
	v_and_b32_e32 v241, 0xffff0000, v241
	v_pk_mul_f32 v[180:181], v[6:7], v[240:241]
	v_pk_mul_f32 v[6:7], v[6:7], v[198:199]
	v_pk_fma_f32 v[180:181], v[22:23], v[198:199], v[180:181] neg_lo:[0,0,1] neg_hi:[0,0,1]
	v_pk_fma_f32 v[6:7], v[22:23], v[240:241], v[6:7]
	v_cvt_pk_bf16_f32 v16, v200, v201
	v_cvt_pk_bf16_f32 v17, v176, v177
	v_cvt_pk_bf16_f32 v18, v178, v179
	v_cvt_pk_bf16_f32 v19, v180, v181
	v_cvt_pk_bf16_f32 v20, v0, v1
	v_cvt_pk_bf16_f32 v21, v2, v3
	v_cvt_pk_bf16_f32 v22, v4, v5
	v_cvt_pk_bf16_f32 v23, v6, v7
	v_permlane32_swap_b32_e32 v16, v18
	v_permlane32_swap_b32_e32 v17, v19
	v_permlane32_swap_b32_e32 v20, v22
	v_permlane32_swap_b32_e32 v21, v23
	global_store_dwordx4 v[182:183], v[16:19], off
	global_store_dwordx4 v[182:183], v[20:23], off offset:64
	v_pk_mul_f32 v[24:25], v[24:25], v[230:231] op_sel_hi:[1,0]
	v_pk_mul_f32 v[8:9], v[8:9], v[230:231] op_sel_hi:[1,0]
	s_waitcnt vmcnt(9)
	v_lshlrev_b32_e32 v198, 16, v242
	v_lshlrev_b32_e32 v199, 16, v243
	v_and_b32_e32 v242, 0xffff0000, v242
	v_and_b32_e32 v243, 0xffff0000, v243
	v_pk_mul_f32 v[200:201], v[8:9], v[242:243]
	v_pk_mul_f32 v[8:9], v[8:9], v[198:199]
	v_pk_fma_f32 v[200:201], v[24:25], v[198:199], v[200:201] neg_lo:[0,0,1] neg_hi:[0,0,1]
	v_pk_fma_f32 v[8:9], v[24:25], v[242:243], v[8:9]
	v_pk_mul_f32 v[26:27], v[26:27], v[230:231] op_sel_hi:[1,0]
	v_pk_mul_f32 v[10:11], v[10:11], v[230:231] op_sel_hi:[1,0]
	v_lshlrev_b32_e32 v198, 16, v244
	v_lshlrev_b32_e32 v199, 16, v245
	v_and_b32_e32 v244, 0xffff0000, v244
	v_and_b32_e32 v245, 0xffff0000, v245
	v_pk_mul_f32 v[176:177], v[10:11], v[244:245]
	v_pk_mul_f32 v[10:11], v[10:11], v[198:199]
	v_pk_fma_f32 v[176:177], v[26:27], v[198:199], v[176:177] neg_lo:[0,0,1] neg_hi:[0,0,1]
	v_pk_fma_f32 v[10:11], v[26:27], v[244:245], v[10:11]
	v_pk_mul_f32 v[28:29], v[28:29], v[230:231] op_sel_hi:[1,0]
	v_pk_mul_f32 v[12:13], v[12:13], v[230:231] op_sel_hi:[1,0]
	s_waitcnt vmcnt(8)
	v_lshlrev_b32_e32 v198, 16, v246
	v_lshlrev_b32_e32 v199, 16, v247
	v_and_b32_e32 v246, 0xffff0000, v246
	v_and_b32_e32 v247, 0xffff0000, v247
	v_pk_mul_f32 v[178:179], v[12:13], v[246:247]
	v_pk_mul_f32 v[12:13], v[12:13], v[198:199]
	v_pk_fma_f32 v[178:179], v[28:29], v[198:199], v[178:179] neg_lo:[0,0,1] neg_hi:[0,0,1]
	v_pk_fma_f32 v[12:13], v[28:29], v[246:247], v[12:13]
	v_pk_mul_f32 v[30:31], v[30:31], v[230:231] op_sel_hi:[1,0]
	v_pk_mul_f32 v[14:15], v[14:15], v[230:231] op_sel_hi:[1,0]
	v_lshlrev_b32_e32 v198, 16, v248
	v_lshlrev_b32_e32 v199, 16, v249
	v_and_b32_e32 v248, 0xffff0000, v248
	v_and_b32_e32 v249, 0xffff0000, v249
	v_pk_mul_f32 v[180:181], v[14:15], v[248:249]
	v_pk_mul_f32 v[14:15], v[14:15], v[198:199]
	v_pk_fma_f32 v[180:181], v[30:31], v[198:199], v[180:181] neg_lo:[0,0,1] neg_hi:[0,0,1]
	v_pk_fma_f32 v[14:15], v[30:31], v[248:249], v[14:15]
	v_cvt_pk_bf16_f32 v24, v200, v201
	v_cvt_pk_bf16_f32 v25, v176, v177
	v_cvt_pk_bf16_f32 v26, v178, v179
	v_cvt_pk_bf16_f32 v27, v180, v181
	v_cvt_pk_bf16_f32 v28, v8, v9
	v_cvt_pk_bf16_f32 v29, v10, v11
	v_cvt_pk_bf16_f32 v30, v12, v13
	v_cvt_pk_bf16_f32 v31, v14, v15
	v_permlane32_swap_b32_e32 v24, v26
	v_permlane32_swap_b32_e32 v25, v27
	v_permlane32_swap_b32_e32 v28, v30
	v_permlane32_swap_b32_e32 v29, v31
	global_store_dwordx4 v[182:183], v[24:27], off offset:32
	global_store_dwordx4 v[182:183], v[28:31], off offset:96
	s_branch .LBB0_290
.Lep1_plain:
	s_waitcnt vmcnt(3)
	v_pk_mul_f32 v[112:113], v[112:113], v[218:219] op_sel_hi:[1,0]
	v_pk_mul_f32 v[114:115], v[114:115], v[218:219] op_sel_hi:[1,0]
	v_pk_mul_f32 v[116:117], v[116:117], v[218:219] op_sel_hi:[1,0]
	v_pk_mul_f32 v[118:119], v[118:119], v[218:219] op_sel_hi:[1,0]
	v_pk_mul_f32 v[120:121], v[120:121], v[218:219] op_sel_hi:[1,0]
	v_pk_mul_f32 v[122:123], v[122:123], v[218:219] op_sel_hi:[1,0]
	v_pk_mul_f32 v[124:125], v[124:125], v[218:219] op_sel_hi:[1,0]
	v_pk_mul_f32 v[126:127], v[126:127], v[218:219] op_sel_hi:[1,0]
	v_cvt_pk_bf16_f32 v112, v112, v113
	v_cvt_pk_bf16_f32 v113, v114, v115
	v_cvt_pk_bf16_f32 v114, v116, v117
	v_cvt_pk_bf16_f32 v115, v118, v119
	v_cvt_pk_bf16_f32 v120, v120, v121
	v_cvt_pk_bf16_f32 v121, v122, v123
	v_cvt_pk_bf16_f32 v122, v124, v125
	v_cvt_pk_bf16_f32 v123, v126, v127
	v_permlane32_swap_b32_e32 v112, v114
	v_permlane32_swap_b32_e32 v113, v115
	v_permlane32_swap_b32_e32 v120, v122
	v_permlane32_swap_b32_e32 v121, v123
	global_store_dwordx4 v[182:183], v[112:115], off
	global_store_dwordx4 v[182:183], v[120:123], off offset:32
	v_pk_mul_f32 v[96:97], v[96:97], v[218:219] op_sel_hi:[1,0]
	v_pk_mul_f32 v[98:99], v[98:99], v[218:219] op_sel_hi:[1,0]
	v_pk_mul_f32 v[100:101], v[100:101], v[218:219] op_sel_hi:[1,0]
	v_pk_mul_f32 v[102:103], v[102:103], v[218:219] op_sel_hi:[1,0]
	v_pk_mul_f32 v[104:105], v[104:105], v[218:219] op_sel_hi:[1,0]
	v_pk_mul_f32 v[106:107], v[106:107], v[218:219] op_sel_hi:[1,0]
	v_pk_mul_f32 v[108:109], v[108:109], v[218:219] op_sel_hi:[1,0]
	v_pk_mul_f32 v[110:111], v[110:111], v[218:219] op_sel_hi:[1,0]
	v_cvt_pk_bf16_f32 v96, v96, v97
	v_cvt_pk_bf16_f32 v97, v98, v99
	v_cvt_pk_bf16_f32 v98, v100, v101
	v_cvt_pk_bf16_f32 v99, v102, v103
	v_cvt_pk_bf16_f32 v104, v104, v105
	v_cvt_pk_bf16_f32 v105, v106, v107
	v_cvt_pk_bf16_f32 v106, v108, v109
	v_cvt_pk_bf16_f32 v107, v110, v111
	v_permlane32_swap_b32_e32 v96, v98
	v_permlane32_swap_b32_e32 v97, v99
	v_permlane32_swap_b32_e32 v104, v106
	v_permlane32_swap_b32_e32 v105, v107
	global_store_dwordx4 v[182:183], v[96:99], off offset:64
	global_store_dwordx4 v[182:183], v[104:107], off offset:96
	v_lshl_add_u64 v[182:183], v[182:183], 0, s[8:9]
	s_waitcnt vmcnt(6)
	v_pk_mul_f32 v[80:81], v[80:81], v[220:221] op_sel_hi:[1,0]
	v_pk_mul_f32 v[82:83], v[82:83], v[220:221] op_sel_hi:[1,0]
	v_pk_mul_f32 v[84:85], v[84:85], v[220:221] op_sel_hi:[1,0]
	v_pk_mul_f32 v[86:87], v[86:87], v[220:221] op_sel_hi:[1,0]
	v_pk_mul_f32 v[88:89], v[88:89], v[220:221] op_sel_hi:[1,0]
	v_pk_mul_f32 v[90:91], v[90:91], v[220:221] op_sel_hi:[1,0]
	v_pk_mul_f32 v[92:93], v[92:93], v[220:221] op_sel_hi:[1,0]
	v_pk_mul_f32 v[94:95], v[94:95], v[220:221] op_sel_hi:[1,0]
	v_cvt_pk_bf16_f32 v80, v80, v81
	v_cvt_pk_bf16_f32 v81, v82, v83
	v_cvt_pk_bf16_f32 v82, v84, v85
	v_cvt_pk_bf16_f32 v83, v86, v87
	v_cvt_pk_bf16_f32 v88, v88, v89
	v_cvt_pk_bf16_f32 v89, v90, v91
	v_cvt_pk_bf16_f32 v90, v92, v93
	v_cvt_pk_bf16_f32 v91, v94, v95
	v_permlane32_swap_b32_e32 v80, v82
	v_permlane32_swap_b32_e32 v81, v83
	v_permlane32_swap_b32_e32 v88, v90
	v_permlane32_swap_b32_e32 v89, v91
	global_store_dwordx4 v[182:183], v[80:83], off
	global_store_dwordx4 v[182:183], v[88:91], off offset:32
	v_pk_mul_f32 v[64:65], v[64:65], v[220:221] op_sel_hi:[1,0]
	v_pk_mul_f32 v[66:67], v[66:67], v[220:221] op_sel_hi:[1,0]
	v_pk_mul_f32 v[68:69], v[68:69], v[220:221] op_sel_hi:[1,0]
	v_pk_mul_f32 v[70:71], v[70:71], v[220:221] op_sel_hi:[1,0]
	v_pk_mul_f32 v[72:73], v[72:73], v[220:221] op_sel_hi:[1,0]
	v_pk_mul_f32 v[74:75], v[74:75], v[220:221] op_sel_hi:[1,0]
	v_pk_mul_f32 v[76:77], v[76:77], v[220:221] op_sel_hi:[1,0]
	v_pk_mul_f32 v[78:79], v[78:79], v[220:221] op_sel_hi:[1,0]
	v_cvt_pk_bf16_f32 v64, v64, v65
	v_cvt_pk_bf16_f32 v65, v66, v67
	v_cvt_pk_bf16_f32 v66, v68, v69
	v_cvt_pk_bf16_f32 v67, v70, v71
	v_cvt_pk_bf16_f32 v72, v72, v73
	v_cvt_pk_bf16_f32 v73, v74, v75
	v_cvt_pk_bf16_f32 v74, v76, v77
	v_cvt_pk_bf16_f32 v75, v78, v79
	v_permlane32_swap_b32_e32 v64, v66
	v_permlane32_swap_b32_e32 v65, v67
	v_permlane32_swap_b32_e32 v72, v74
	v_permlane32_swap_b32_e32 v73, v75
	global_store_dwordx4 v[182:183], v[64:67], off offset:64
	global_store_dwordx4 v[182:183], v[72:75], off offset:96
	v_lshl_add_u64 v[182:183], v[182:183], 0, s[8:9]
	s_waitcnt vmcnt(9)
	v_pk_mul_f32 v[48:49], v[48:49], v[228:229] op_sel_hi:[1,0]
	v_pk_mul_f32 v[50:51], v[50:51], v[228:229] op_sel_hi:[1,0]
	v_pk_mul_f32 v[52:53], v[52:53], v[228:229] op_sel_hi:[1,0]
	v_pk_mul_f32 v[54:55], v[54:55], v[228:229] op_sel_hi:[1,0]
	v_pk_mul_f32 v[56:57], v[56:57], v[228:229] op_sel_hi:[1,0]
	v_pk_mul_f32 v[58:59], v[58:59], v[228:229] op_sel_hi:[1,0]
	v_pk_mul_f32 v[60:61], v[60:61], v[228:229] op_sel_hi:[1,0]
	v_pk_mul_f32 v[62:63], v[62:63], v[228:229] op_sel_hi:[1,0]
	v_cvt_pk_bf16_f32 v48, v48, v49
	v_cvt_pk_bf16_f32 v49, v50, v51
	v_cvt_pk_bf16_f32 v50, v52, v53
	v_cvt_pk_bf16_f32 v51, v54, v55
	v_cvt_pk_bf16_f32 v56, v56, v57
	v_cvt_pk_bf16_f32 v57, v58, v59
	v_cvt_pk_bf16_f32 v58, v60, v61
	v_cvt_pk_bf16_f32 v59, v62, v63
	v_permlane32_swap_b32_e32 v48, v50
	v_permlane32_swap_b32_e32 v49, v51
	v_permlane32_swap_b32_e32 v56, v58
	v_permlane32_swap_b32_e32 v57, v59
	global_store_dwordx4 v[182:183], v[48:51], off
	global_store_dwordx4 v[182:183], v[56:59], off offset:32
	v_pk_mul_f32 v[32:33], v[32:33], v[228:229] op_sel_hi:[1,0]
	v_pk_mul_f32 v[34:35], v[34:35], v[228:229] op_sel_hi:[1,0]
	v_pk_mul_f32 v[36:37], v[36:37], v[228:229] op_sel_hi:[1,0]
	v_pk_mul_f32 v[38:39], v[38:39], v[228:229] op_sel_hi:[1,0]
	v_pk_mul_f32 v[40:41], v[40:41], v[228:229] op_sel_hi:[1,0]
	v_pk_mul_f32 v[42:43], v[42:43], v[228:229] op_sel_hi:[1,0]
	v_pk_mul_f32 v[44:45], v[44:45], v[228:229] op_sel_hi:[1,0]
	v_pk_mul_f32 v[46:47], v[46:47], v[228:229] op_sel_hi:[1,0]
	v_cvt_pk_bf16_f32 v32, v32, v33
	v_cvt_pk_bf16_f32 v33, v34, v35
	v_cvt_pk_bf16_f32 v34, v36, v37
	v_cvt_pk_bf16_f32 v35, v38, v39
	v_cvt_pk_bf16_f32 v40, v40, v41
	v_cvt_pk_bf16_f32 v41, v42, v43
	v_cvt_pk_bf16_f32 v42, v44, v45
	v_cvt_pk_bf16_f32 v43, v46, v47
	v_permlane32_swap_b32_e32 v32, v34
	v_permlane32_swap_b32_e32 v33, v35
	v_permlane32_swap_b32_e32 v40, v42
	v_permlane32_swap_b32_e32 v41, v43
	global_store_dwordx4 v[182:183], v[32:35], off offset:64
	global_store_dwordx4 v[182:183], v[40:43], off offset:96
	v_lshl_add_u64 v[182:183], v[182:183], 0, s[8:9]
	s_waitcnt vmcnt(12)
	v_pk_mul_f32 v[16:17], v[16:17], v[230:231] op_sel_hi:[1,0]
	v_pk_mul_f32 v[18:19], v[18:19], v[230:231] op_sel_hi:[1,0]
	v_pk_mul_f32 v[20:21], v[20:21], v[230:231] op_sel_hi:[1,0]
	v_pk_mul_f32 v[22:23], v[22:23], v[230:231] op_sel_hi:[1,0]
	v_pk_mul_f32 v[24:25], v[24:25], v[230:231] op_sel_hi:[1,0]
	v_pk_mul_f32 v[26:27], v[26:27], v[230:231] op_sel_hi:[1,0]
	v_pk_mul_f32 v[28:29], v[28:29], v[230:231] op_sel_hi:[1,0]
	v_pk_mul_f32 v[30:31], v[30:31], v[230:231] op_sel_hi:[1,0]
	v_cvt_pk_bf16_f32 v16, v16, v17
	v_cvt_pk_bf16_f32 v17, v18, v19
	v_cvt_pk_bf16_f32 v18, v20, v21
	v_cvt_pk_bf16_f32 v19, v22, v23
	v_cvt_pk_bf16_f32 v24, v24, v25
	v_cvt_pk_bf16_f32 v25, v26, v27
	v_cvt_pk_bf16_f32 v26, v28, v29
	v_cvt_pk_bf16_f32 v27, v30, v31
	v_permlane32_swap_b32_e32 v16, v18
	v_permlane32_swap_b32_e32 v17, v19
	v_permlane32_swap_b32_e32 v24, v26
	v_permlane32_swap_b32_e32 v25, v27
	global_store_dwordx4 v[182:183], v[16:19], off
	global_store_dwordx4 v[182:183], v[24:27], off offset:32
	v_pk_mul_f32 v[0:1], v[0:1], v[230:231] op_sel_hi:[1,0]
	v_pk_mul_f32 v[2:3], v[2:3], v[230:231] op_sel_hi:[1,0]
	v_pk_mul_f32 v[4:5], v[4:5], v[230:231] op_sel_hi:[1,0]
	v_pk_mul_f32 v[6:7], v[6:7], v[230:231] op_sel_hi:[1,0]
	v_pk_mul_f32 v[8:9], v[8:9], v[230:231] op_sel_hi:[1,0]
	v_pk_mul_f32 v[10:11], v[10:11], v[230:231] op_sel_hi:[1,0]
	v_pk_mul_f32 v[12:13], v[12:13], v[230:231] op_sel_hi:[1,0]
	v_pk_mul_f32 v[14:15], v[14:15], v[230:231] op_sel_hi:[1,0]
	v_cvt_pk_bf16_f32 v0, v0, v1
	v_cvt_pk_bf16_f32 v1, v2, v3
	v_cvt_pk_bf16_f32 v2, v4, v5
	v_cvt_pk_bf16_f32 v3, v6, v7
	v_cvt_pk_bf16_f32 v8, v8, v9
	v_cvt_pk_bf16_f32 v9, v10, v11
	v_cvt_pk_bf16_f32 v10, v12, v13
	v_cvt_pk_bf16_f32 v11, v14, v15
	v_permlane32_swap_b32_e32 v0, v2
	v_permlane32_swap_b32_e32 v1, v3
	v_permlane32_swap_b32_e32 v8, v10
	v_permlane32_swap_b32_e32 v9, v11
	global_store_dwordx4 v[182:183], v[0:3], off offset:64
	global_store_dwordx4 v[182:183], v[8:11], off offset:96

.LBB0_295:
	s_ashr_i32 s0, s26, 31
	s_lshr_b32 s0, s0, 25
	s_add_i32 s0, s26, s0
	v_mov_b32_e32 v181, v185
	s_ashr_i32 s0, s0, 7
	s_add_i32 s1, s0, 12
	s_waitcnt lgkmcnt(0)
	v_ashrrev_i32_e32 v1, 5, v181
	v_and_b32_e32 v1, -2, v1
	s_lshl_b32 s0, s0, 14
	v_lshl_add_u32 v2, s1, 3, v1
	s_sub_i32 s20, s11, s0
	v_ashrrev_i32_e32 v3, 31, v2
	v_and_b32_e32 v180, 63, v181
	v_lshlrev_b64 v[2:3], 16, v[2:3]
	s_ashr_i32 s21, s20, 31
	s_and_b64 s[8:9], s[68:69], s[22:23]
	v_ashrrev_i32_e32 v0, 3, v181
	v_lshl_add_u64 v[2:3], s[12:13], 0, v[2:3]
	v_lshlrev_b32_e32 v192, 4, v180
	s_lshl_b64 s[20:21], s[20:21], 11
	v_lshlrev_b32_e32 v1, 3, v181
	v_lshl_add_u64 v[176:177], v[2:3], 0, v[192:193]
	s_add_u32 s20, s24, s20
	v_and_b32_e32 v1, 56, v1
	v_lshlrev_b32_e32 v2, 11, v0
	s_addc_u32 s21, s25, s21
	v_lshl_or_b32 v192, v1, 1, v2
	s_and_b64 vcc, exec, s[8:9]
	v_lshl_add_u64 v[178:179], s[20:21], 0, v[192:193]
	s_waitcnt lgkmcnt(0)
	s_barrier
	s_cbranch_vccnz .LBB0_297
	v_add_co_u32_e32 v2, vcc, 0x10000, v178
	s_nop 1
	v_addc_co_u32_e32 v3, vcc, 0, v179, vcc
	v_add_co_u32_e32 v4, vcc, 0x20000, v178
	s_nop 1
	v_addc_co_u32_e32 v5, vcc, 0, v179, vcc
	s_waitcnt vmcnt(0)
	global_load_dwordx4 v[156:159], v[2:3], off
	global_load_dwordx4 v[164:167], v[4:5], off
	v_add_co_u32_e32 v2, vcc, 0x30000, v178
	global_load_dwordx4 v[160:163], v[176:177], off
	global_load_dwordx4 v[144:147], v[176:177], off offset:1024
	global_load_dwordx4 v[132:135], v[176:177], off offset:2048
	global_load_dwordx4 v[128:131], v[176:177], off offset:3072
	v_addc_co_u32_e32 v3, vcc, 0, v179, vcc
	v_add_co_u32_e32 v4, vcc, 0x10000, v176
	s_nop 1
	v_addc_co_u32_e32 v5, vcc, 0, v177, vcc
	global_load_dwordx4 v[172:175], v[2:3], off
	global_load_dwordx4 v[152:155], v[4:5], off
	global_load_dwordx4 v[148:151], v[4:5], off offset:1024
	global_load_dwordx4 v[140:143], v[4:5], off offset:2048
	global_load_dwordx4 v[168:171], v[178:179], off
	global_load_dwordx4 v[136:139], v[4:5], off offset:3072
.LBB0_297:
	s_movk_i32 s8, 0x90
	v_mul_lo_u32 v0, v0, s8
	s_waitcnt vmcnt(0)
	v_lshl_add_u32 v184, v1, 1, v0
	s_waitcnt lgkmcnt(0)
	ds_write_b128 v184, v[168:171]
	ds_write_b128 v184, v[156:159] offset:4608
	ds_write_b128 v184, v[164:167] offset:9216
	ds_write_b128 v184, v[172:175] offset:13824
	v_add_co_u32_e32 v156, vcc, 0x10000, v178
	v_lshrrev_b32_e32 v186, 5, v180
	s_nop 0
	v_addc_co_u32_e32 v157, vcc, 0, v179, vcc
	v_add_co_u32_e32 v164, vcc, 0x20000, v178
	v_and_b32_e32 v182, 31, v181
	s_nop 0
	v_addc_co_u32_e32 v165, vcc, 0, v179, vcc
	v_add_co_u32_e32 v172, vcc, 0x30000, v178
	global_load_dwordx4 v[166:169], v[156:157], off offset:128
	global_load_dwordx4 v[188:191], v[164:165], off offset:128
	v_addc_co_u32_e32 v173, vcc, 0, v179, vcc
	global_load_dwordx4 v[198:201], v[178:179], off offset:128
	global_load_dwordx4 v[202:205], v[172:173], off offset:128
	v_lshlrev_b32_e32 v0, 4, v186
	v_mad_u32_u24 v183, v182, s8, v0
	s_waitcnt lgkmcnt(0)
	s_barrier
	ds_read_b128 v[0:3], v183
	ds_read_b128 v[206:209], v183 offset:32
	ds_read_b128 v[4:7], v183 offset:4608
	ds_read_b128 v[210:213], v183 offset:4640
	ds_read_b128 v[8:11], v183 offset:9216
	ds_read_b128 v[214:217], v183 offset:9248
	ds_read_b128 v[12:15], v183 offset:13824
	ds_read_b128 v[218:221], v183 offset:13856
	s_setprio 2
	s_movk_i32 s8, 0x1000
	s_waitcnt lgkmcnt(7)
	v_mfma_f32_32x32x16_bf16 v[112:127], v[160:163], v[0:3], 0
	s_waitcnt lgkmcnt(5)
	v_mfma_f32_32x32x16_bf16 v[80:95], v[160:163], v[4:7], 0
	s_waitcnt lgkmcnt(3)
	v_mfma_f32_32x32x16_bf16 v[48:63], v[160:163], v[8:11], 0
	s_waitcnt lgkmcnt(1)
	v_mfma_f32_32x32x16_bf16 v[16:31], v[160:163], v[12:15], 0
	v_add_co_u32_e32 v162, vcc, s8, v176
	s_mov_b32 s8, 0x11000
	s_nop 0
	v_addc_co_u32_e32 v163, vcc, 0, v177, vcc
	v_add_co_u32_e32 v170, vcc, s8, v176
	global_load_dwordx4 v[158:161], v[162:163], off
	s_nop 0
	v_addc_co_u32_e32 v171, vcc, 0, v177, vcc
	v_mfma_f32_32x32x16_bf16 v[96:111], v[152:155], v[0:3], 0
	v_mfma_f32_32x32x16_bf16 v[64:79], v[152:155], v[4:7], 0
	v_mfma_f32_32x32x16_bf16 v[32:47], v[152:155], v[8:11], 0
	v_mfma_f32_32x32x16_bf16 v[0:15], v[152:155], v[12:15], 0
	global_load_dwordx4 v[152:155], v[170:171], off
	s_setprio 0
	ds_read_b128 v[228:231], v183 offset:64
	ds_read_b128 v[234:237], v183 offset:4672
	ds_read_b128 v[238:241], v183 offset:9280
	ds_read_b128 v[242:245], v183 offset:13888
	s_setprio 2
	v_mfma_f32_32x32x16_bf16 v[112:127], v[144:147], v[206:209], v[112:127]
	v_mfma_f32_32x32x16_bf16 v[80:95], v[144:147], v[210:213], v[80:95]
	v_mfma_f32_32x32x16_bf16 v[48:63], v[144:147], v[214:217], v[48:63]
	s_waitcnt lgkmcnt(4)
	v_mfma_f32_32x32x16_bf16 v[16:31], v[144:147], v[218:221], v[16:31]
	v_mfma_f32_32x32x16_bf16 v[96:111], v[148:151], v[206:209], v[96:111]
	global_load_dwordx4 v[144:147], v[162:163], off offset:1024
	global_load_dwordx4 v[206:209], v[170:171], off offset:1024
	v_mfma_f32_32x32x16_bf16 v[64:79], v[148:151], v[210:213], v[64:79]
	v_mfma_f32_32x32x16_bf16 v[32:47], v[148:151], v[214:217], v[32:47]
	v_mfma_f32_32x32x16_bf16 v[0:15], v[148:151], v[218:221], v[0:15]
	s_setprio 0
	ds_read_b128 v[148:151], v183 offset:96
	ds_read_b128 v[210:213], v183 offset:4704
	ds_read_b128 v[214:217], v183 offset:9312
	ds_read_b128 v[218:221], v183 offset:13920
	s_setprio 2
	s_waitcnt lgkmcnt(7)
	v_mfma_f32_32x32x16_bf16 v[112:127], v[132:135], v[228:231], v[112:127]
	s_waitcnt lgkmcnt(6)
	v_mfma_f32_32x32x16_bf16 v[80:95], v[132:135], v[234:237], v[80:95]
	s_waitcnt lgkmcnt(5)
	v_mfma_f32_32x32x16_bf16 v[48:63], v[132:135], v[238:241], v[48:63]
	s_waitcnt lgkmcnt(4)
	v_mfma_f32_32x32x16_bf16 v[16:31], v[132:135], v[242:245], v[16:31]
	v_mfma_f32_32x32x16_bf16 v[96:111], v[140:143], v[228:231], v[96:111]
	global_load_dwordx4 v[132:135], v[162:163], off offset:2048
	global_load_dwordx4 v[228:231], v[170:171], off offset:2048
	v_mfma_f32_32x32x16_bf16 v[64:79], v[140:143], v[234:237], v[64:79]
	v_mfma_f32_32x32x16_bf16 v[32:47], v[140:143], v[238:241], v[32:47]
	v_mfma_f32_32x32x16_bf16 v[0:15], v[140:143], v[242:245], v[0:15]
	s_setprio 0
	s_setprio 2
	s_waitcnt lgkmcnt(3)
	v_mfma_f32_32x32x16_bf16 v[112:127], v[128:131], v[148:151], v[112:127]
	s_waitcnt lgkmcnt(2)
	v_mfma_f32_32x32x16_bf16 v[80:95], v[128:131], v[210:213], v[80:95]
	s_waitcnt lgkmcnt(1)
	v_mfma_f32_32x32x16_bf16 v[48:63], v[128:131], v[214:217], v[48:63]
	s_waitcnt lgkmcnt(0)
	v_mfma_f32_32x32x16_bf16 v[16:31], v[128:131], v[218:221], v[16:31]
	global_load_dwordx4 v[128:131], v[162:163], off offset:3072
	global_load_dwordx4 v[140:143], v[170:171], off offset:3072
	v_mfma_f32_32x32x16_bf16 v[96:111], v[136:139], v[148:151], v[96:111]
	v_mfma_f32_32x32x16_bf16 v[64:79], v[136:139], v[210:213], v[64:79]
	v_mfma_f32_32x32x16_bf16 v[32:47], v[136:139], v[214:217], v[32:47]
	v_mfma_f32_32x32x16_bf16 v[0:15], v[136:139], v[218:221], v[0:15]
	s_setprio 0
	s_waitcnt vmcnt(9)
	ds_write_b128 v184, v[198:201] offset:18432
	ds_write_b128 v184, v[166:169] offset:23040
	ds_write_b128 v184, v[188:191] offset:27648
	s_waitcnt vmcnt(8)
	ds_write_b128 v184, v[202:205] offset:32256
	global_load_dwordx4 v[136:139], v[156:157], off offset:256
	global_load_dwordx4 v[148:151], v[164:165], off offset:256
	global_load_dwordx4 v[166:169], v[178:179], off offset:256
	global_load_dwordx4 v[188:191], v[172:173], off offset:256
	s_waitcnt lgkmcnt(0)
	s_barrier
	ds_read_b128 v[198:201], v183 offset:18432
	ds_read_b128 v[202:205], v183 offset:18464
	ds_read_b128 v[210:213], v183 offset:23040
	ds_read_b128 v[214:217], v183 offset:23072
	ds_read_b128 v[218:221], v183 offset:27648
	ds_read_b128 v[234:237], v183 offset:27680
	ds_read_b128 v[238:241], v183 offset:32256
	ds_read_b128 v[242:245], v183 offset:32288
	s_setprio 2
	s_movk_i32 s8, 0x2000
	v_add_co_u32_e32 v162, vcc, s8, v176
	s_mov_b32 s8, 0x12000
	s_nop 0
	v_addc_co_u32_e32 v163, vcc, 0, v177, vcc
	v_add_co_u32_e32 v170, vcc, s8, v176
	s_waitcnt vmcnt(11) lgkmcnt(7)
	v_mfma_f32_32x32x16_bf16 v[112:127], v[158:161], v[198:201], v[112:127]
	v_addc_co_u32_e32 v171, vcc, 0, v177, vcc
	s_waitcnt lgkmcnt(5)
	v_mfma_f32_32x32x16_bf16 v[80:95], v[158:161], v[210:213], v[80:95]
	s_waitcnt lgkmcnt(3)
	v_mfma_f32_32x32x16_bf16 v[48:63], v[158:161], v[218:221], v[48:63]
	s_waitcnt lgkmcnt(1)
	v_mfma_f32_32x32x16_bf16 v[16:31], v[158:161], v[238:241], v[16:31]
	s_waitcnt vmcnt(10)
	v_mfma_f32_32x32x16_bf16 v[96:111], v[152:155], v[198:201], v[96:111]
	global_load_dwordx4 v[158:161], v[162:163], off
	global_load_dwordx4 v[198:201], v[170:171], off
	v_mfma_f32_32x32x16_bf16 v[64:79], v[152:155], v[210:213], v[64:79]
	v_mfma_f32_32x32x16_bf16 v[32:47], v[152:155], v[218:221], v[32:47]
	v_mfma_f32_32x32x16_bf16 v[0:15], v[152:155], v[238:241], v[0:15]
	s_setprio 0
	ds_read_b128 v[152:155], v183 offset:18496
	ds_read_b128 v[210:213], v183 offset:23104
	ds_read_b128 v[218:221], v183 offset:27712
	ds_read_b128 v[238:241], v183 offset:32320
	s_setprio 2
	s_waitcnt vmcnt(11)
	v_mfma_f32_32x32x16_bf16 v[112:127], v[144:147], v[202:205], v[112:127]
	v_mfma_f32_32x32x16_bf16 v[80:95], v[144:147], v[214:217], v[80:95]
	v_mfma_f32_32x32x16_bf16 v[48:63], v[144:147], v[234:237], v[48:63]
	s_waitcnt lgkmcnt(4)
	v_mfma_f32_32x32x16_bf16 v[16:31], v[144:147], v[242:245], v[16:31]
	s_waitcnt vmcnt(10)
	v_mfma_f32_32x32x16_bf16 v[96:111], v[206:209], v[202:205], v[96:111]
	global_load_dwordx4 v[144:147], v[162:163], off offset:1024
	global_load_dwordx4 v[202:205], v[170:171], off offset:1024
	v_mfma_f32_32x32x16_bf16 v[64:79], v[206:209], v[214:217], v[64:79]
	v_mfma_f32_32x32x16_bf16 v[32:47], v[206:209], v[234:237], v[32:47]
	v_mfma_f32_32x32x16_bf16 v[0:15], v[206:209], v[242:245], v[0:15]
	s_setprio 0
	ds_read_b128 v[206:209], v183 offset:18528
	ds_read_b128 v[214:217], v183 offset:23136
	ds_read_b128 v[234:237], v183 offset:27744
	ds_read_b128 v[242:245], v183 offset:32352
	s_setprio 2
	s_waitcnt vmcnt(11) lgkmcnt(7)
	v_mfma_f32_32x32x16_bf16 v[112:127], v[132:135], v[152:155], v[112:127]
	s_waitcnt lgkmcnt(6)
	v_mfma_f32_32x32x16_bf16 v[80:95], v[132:135], v[210:213], v[80:95]
	s_waitcnt lgkmcnt(5)
	v_mfma_f32_32x32x16_bf16 v[48:63], v[132:135], v[218:221], v[48:63]
	s_waitcnt lgkmcnt(4)
	v_mfma_f32_32x32x16_bf16 v[16:31], v[132:135], v[238:241], v[16:31]
	s_waitcnt vmcnt(10)
	v_mfma_f32_32x32x16_bf16 v[96:111], v[228:231], v[152:155], v[96:111]
	global_load_dwordx4 v[132:135], v[162:163], off offset:2048
	global_load_dwordx4 v[152:155], v[170:171], off offset:2048
	v_mfma_f32_32x32x16_bf16 v[64:79], v[228:231], v[210:213], v[64:79]
	v_mfma_f32_32x32x16_bf16 v[32:47], v[228:231], v[218:221], v[32:47]
	v_mfma_f32_32x32x16_bf16 v[0:15], v[228:231], v[238:241], v[0:15]
	s_setprio 0
	s_setprio 2
	s_waitcnt vmcnt(11) lgkmcnt(3)
	v_mfma_f32_32x32x16_bf16 v[112:127], v[128:131], v[206:209], v[112:127]
	s_waitcnt lgkmcnt(2)
	v_mfma_f32_32x32x16_bf16 v[80:95], v[128:131], v[214:217], v[80:95]
	s_waitcnt lgkmcnt(1)
	v_mfma_f32_32x32x16_bf16 v[48:63], v[128:131], v[234:237], v[48:63]
	s_waitcnt lgkmcnt(0)
	v_mfma_f32_32x32x16_bf16 v[16:31], v[128:131], v[242:245], v[16:31]
	s_waitcnt vmcnt(10)
	v_mfma_f32_32x32x16_bf16 v[96:111], v[140:143], v[206:209], v[96:111]
	global_load_dwordx4 v[128:131], v[162:163], off offset:3072
	global_load_dwordx4 v[206:209], v[170:171], off offset:3072
	v_mfma_f32_32x32x16_bf16 v[64:79], v[140:143], v[214:217], v[64:79]
	v_mfma_f32_32x32x16_bf16 v[32:47], v[140:143], v[234:237], v[32:47]
	v_mfma_f32_32x32x16_bf16 v[0:15], v[140:143], v[242:245], v[0:15]
	s_setprio 0
	s_waitcnt vmcnt(9)
	ds_write_b128 v184, v[166:169]
	ds_write_b128 v184, v[136:139] offset:4608
	ds_write_b128 v184, v[148:151] offset:9216
	s_waitcnt vmcnt(8)
	ds_write_b128 v184, v[188:191] offset:13824
	global_load_dwordx4 v[136:139], v[164:165], off offset:384
	global_load_dwordx4 v[140:143], v[156:157], off offset:384
	global_load_dwordx4 v[148:151], v[172:173], off offset:384
	global_load_dwordx4 v[166:169], v[178:179], off offset:384
	s_waitcnt lgkmcnt(0)
	s_barrier
	ds_read_b128 v[188:191], v183
	ds_read_b128 v[210:213], v183 offset:32
	ds_read_b128 v[214:217], v183 offset:4608
	ds_read_b128 v[218:221], v183 offset:4640
	ds_read_b128 v[228:231], v183 offset:9216
	ds_read_b128 v[234:237], v183 offset:9248
	ds_read_b128 v[238:241], v183 offset:13824
	ds_read_b128 v[242:245], v183 offset:13856
	s_setprio 2
	s_movk_i32 s8, 0x3000
	v_add_co_u32_e32 v162, vcc, s8, v176
	s_mov_b32 s8, 0x13000
	s_nop 0
	v_addc_co_u32_e32 v163, vcc, 0, v177, vcc
	v_add_co_u32_e32 v170, vcc, s8, v176
	s_waitcnt vmcnt(11) lgkmcnt(7)
	v_mfma_f32_32x32x16_bf16 v[112:127], v[158:161], v[188:191], v[112:127]
	v_addc_co_u32_e32 v171, vcc, 0, v177, vcc
	s_waitcnt lgkmcnt(5)
	v_mfma_f32_32x32x16_bf16 v[80:95], v[158:161], v[214:217], v[80:95]
	s_waitcnt lgkmcnt(3)
	v_mfma_f32_32x32x16_bf16 v[48:63], v[158:161], v[228:231], v[48:63]
	s_waitcnt lgkmcnt(1)
	v_mfma_f32_32x32x16_bf16 v[16:31], v[158:161], v[238:241], v[16:31]
	s_waitcnt vmcnt(10)
	v_mfma_f32_32x32x16_bf16 v[96:111], v[198:201], v[188:191], v[96:111]
	global_load_dwordx4 v[158:161], v[162:163], off
	global_load_dwordx4 v[188:191], v[170:171], off
	v_mfma_f32_32x32x16_bf16 v[64:79], v[198:201], v[214:217], v[64:79]
	v_mfma_f32_32x32x16_bf16 v[32:47], v[198:201], v[228:231], v[32:47]
	v_mfma_f32_32x32x16_bf16 v[0:15], v[198:201], v[238:241], v[0:15]
	s_setprio 0
	ds_read_b128 v[198:201], v183 offset:64
	ds_read_b128 v[214:217], v183 offset:4672
	ds_read_b128 v[228:231], v183 offset:9280
	ds_read_b128 v[238:241], v183 offset:13888
	s_setprio 2
	s_waitcnt vmcnt(11)
	v_mfma_f32_32x32x16_bf16 v[112:127], v[144:147], v[210:213], v[112:127]
	v_mfma_f32_32x32x16_bf16 v[80:95], v[144:147], v[218:221], v[80:95]
	v_mfma_f32_32x32x16_bf16 v[48:63], v[144:147], v[234:237], v[48:63]
	s_waitcnt lgkmcnt(4)
	v_mfma_f32_32x32x16_bf16 v[16:31], v[144:147], v[242:245], v[16:31]
	s_waitcnt vmcnt(10)
	v_mfma_f32_32x32x16_bf16 v[96:111], v[202:205], v[210:213], v[96:111]
	global_load_dwordx4 v[144:147], v[162:163], off offset:1024
	global_load_dwordx4 v[210:213], v[170:171], off offset:1024
	v_mfma_f32_32x32x16_bf16 v[64:79], v[202:205], v[218:221], v[64:79]
	v_mfma_f32_32x32x16_bf16 v[32:47], v[202:205], v[234:237], v[32:47]
	v_mfma_f32_32x32x16_bf16 v[0:15], v[202:205], v[242:245], v[0:15]
	s_setprio 0
	ds_read_b128 v[202:205], v183 offset:96
	ds_read_b128 v[218:221], v183 offset:4704
	ds_read_b128 v[234:237], v183 offset:9312
	ds_read_b128 v[242:245], v183 offset:13920
	s_setprio 2
	s_waitcnt vmcnt(11) lgkmcnt(7)
	v_mfma_f32_32x32x16_bf16 v[112:127], v[132:135], v[198:201], v[112:127]
	s_waitcnt lgkmcnt(6)
	v_mfma_f32_32x32x16_bf16 v[80:95], v[132:135], v[214:217], v[80:95]
	s_waitcnt lgkmcnt(5)
	v_mfma_f32_32x32x16_bf16 v[48:63], v[132:135], v[228:231], v[48:63]
	s_waitcnt lgkmcnt(4)
	v_mfma_f32_32x32x16_bf16 v[16:31], v[132:135], v[238:241], v[16:31]
	s_waitcnt vmcnt(10)
	v_mfma_f32_32x32x16_bf16 v[96:111], v[152:155], v[198:201], v[96:111]
	global_load_dwordx4 v[132:135], v[162:163], off offset:2048
	global_load_dwordx4 v[198:201], v[170:171], off offset:2048
	v_mfma_f32_32x32x16_bf16 v[64:79], v[152:155], v[214:217], v[64:79]
	v_mfma_f32_32x32x16_bf16 v[32:47], v[152:155], v[228:231], v[32:47]
	v_mfma_f32_32x32x16_bf16 v[0:15], v[152:155], v[238:241], v[0:15]
	s_setprio 0
	s_setprio 2
	s_waitcnt vmcnt(11) lgkmcnt(3)
	v_mfma_f32_32x32x16_bf16 v[112:127], v[128:131], v[202:205], v[112:127]
	s_waitcnt lgkmcnt(2)
	v_mfma_f32_32x32x16_bf16 v[80:95], v[128:131], v[218:221], v[80:95]
	s_waitcnt lgkmcnt(1)
	v_mfma_f32_32x32x16_bf16 v[48:63], v[128:131], v[234:237], v[48:63]
	s_waitcnt lgkmcnt(0)
	v_mfma_f32_32x32x16_bf16 v[16:31], v[128:131], v[242:245], v[16:31]
	global_load_dwordx4 v[128:131], v[162:163], off offset:3072
	global_load_dwordx4 v[152:155], v[170:171], off offset:3072
	s_waitcnt vmcnt(12)
	v_mfma_f32_32x32x16_bf16 v[96:111], v[206:209], v[202:205], v[96:111]
	v_mfma_f32_32x32x16_bf16 v[64:79], v[206:209], v[218:221], v[64:79]
	v_mfma_f32_32x32x16_bf16 v[32:47], v[206:209], v[234:237], v[32:47]
	v_mfma_f32_32x32x16_bf16 v[0:15], v[206:209], v[242:245], v[0:15]
	s_setprio 0
	s_waitcnt vmcnt(8)
	ds_write_b128 v184, v[166:169] offset:18432
	ds_write_b128 v184, v[140:143] offset:23040
	ds_write_b128 v184, v[136:139] offset:27648
	ds_write_b128 v184, v[148:151] offset:32256
	global_load_dwordx4 v[136:139], v[156:157], off offset:512
	global_load_dwordx4 v[140:143], v[164:165], off offset:512
	global_load_dwordx4 v[148:151], v[178:179], off offset:512
	global_load_dwordx4 v[166:169], v[172:173], off offset:512
	s_waitcnt lgkmcnt(0)
	s_barrier
	ds_read_b128 v[202:205], v183 offset:18432
	ds_read_b128 v[206:209], v183 offset:18464
	ds_read_b128 v[214:217], v183 offset:23040
	ds_read_b128 v[218:221], v183 offset:23072
	ds_read_b128 v[228:231], v183 offset:27648
	ds_read_b128 v[234:237], v183 offset:27680
	ds_read_b128 v[238:241], v183 offset:32256
	ds_read_b128 v[242:245], v183 offset:32288
	s_setprio 2
	s_movk_i32 s8, 0x4000
	v_add_co_u32_e32 v162, vcc, s8, v176
	s_mov_b32 s8, 0x14000
	s_nop 0
	v_addc_co_u32_e32 v163, vcc, 0, v177, vcc
	v_add_co_u32_e32 v170, vcc, s8, v176
	s_waitcnt vmcnt(11) lgkmcnt(7)
	v_mfma_f32_32x32x16_bf16 v[112:127], v[158:161], v[202:205], v[112:127]
	v_addc_co_u32_e32 v171, vcc, 0, v177, vcc
	s_waitcnt lgkmcnt(5)
	v_mfma_f32_32x32x16_bf16 v[80:95], v[158:161], v[214:217], v[80:95]
	s_waitcnt lgkmcnt(3)
	v_mfma_f32_32x32x16_bf16 v[48:63], v[158:161], v[228:231], v[48:63]
	s_waitcnt lgkmcnt(1)
	v_mfma_f32_32x32x16_bf16 v[16:31], v[158:161], v[238:241], v[16:31]
	s_waitcnt vmcnt(10)
	v_mfma_f32_32x32x16_bf16 v[96:111], v[188:191], v[202:205], v[96:111]
	global_load_dwordx4 v[158:161], v[162:163], off
	global_load_dwordx4 v[202:205], v[170:171], off
	v_mfma_f32_32x32x16_bf16 v[64:79], v[188:191], v[214:217], v[64:79]
	v_mfma_f32_32x32x16_bf16 v[32:47], v[188:191], v[228:231], v[32:47]
	v_mfma_f32_32x32x16_bf16 v[0:15], v[188:191], v[238:241], v[0:15]
	s_setprio 0
	ds_read_b128 v[188:191], v183 offset:18496
	ds_read_b128 v[214:217], v183 offset:23104
	ds_read_b128 v[228:231], v183 offset:27712
	ds_read_b128 v[238:241], v183 offset:32320
	s_setprio 2
	s_waitcnt vmcnt(11)
	v_mfma_f32_32x32x16_bf16 v[112:127], v[144:147], v[206:209], v[112:127]
	v_mfma_f32_32x32x16_bf16 v[80:95], v[144:147], v[218:221], v[80:95]
	v_mfma_f32_32x32x16_bf16 v[48:63], v[144:147], v[234:237], v[48:63]
	s_waitcnt lgkmcnt(4)
	v_mfma_f32_32x32x16_bf16 v[16:31], v[144:147], v[242:245], v[16:31]
	s_waitcnt vmcnt(10)
	v_mfma_f32_32x32x16_bf16 v[96:111], v[210:213], v[206:209], v[96:111]
	global_load_dwordx4 v[144:147], v[162:163], off offset:1024
	global_load_dwordx4 v[206:209], v[170:171], off offset:1024
	v_mfma_f32_32x32x16_bf16 v[64:79], v[210:213], v[218:221], v[64:79]
	v_mfma_f32_32x32x16_bf16 v[32:47], v[210:213], v[234:237], v[32:47]
	v_mfma_f32_32x32x16_bf16 v[0:15], v[210:213], v[242:245], v[0:15]
	s_setprio 0
	ds_read_b128 v[210:213], v183 offset:18528
	ds_read_b128 v[218:221], v183 offset:23136
	ds_read_b128 v[234:237], v183 offset:27744
	ds_read_b128 v[242:245], v183 offset:32352
	s_setprio 2
	s_waitcnt vmcnt(11) lgkmcnt(7)
	v_mfma_f32_32x32x16_bf16 v[112:127], v[132:135], v[188:191], v[112:127]
	s_waitcnt lgkmcnt(6)
	v_mfma_f32_32x32x16_bf16 v[80:95], v[132:135], v[214:217], v[80:95]
	s_waitcnt lgkmcnt(5)
	v_mfma_f32_32x32x16_bf16 v[48:63], v[132:135], v[228:231], v[48:63]
	s_waitcnt lgkmcnt(4)
	v_mfma_f32_32x32x16_bf16 v[16:31], v[132:135], v[238:241], v[16:31]
	s_waitcnt vmcnt(10)
	v_mfma_f32_32x32x16_bf16 v[96:111], v[198:201], v[188:191], v[96:111]
	global_load_dwordx4 v[132:135], v[162:163], off offset:2048
	global_load_dwordx4 v[188:191], v[170:171], off offset:2048
	v_mfma_f32_32x32x16_bf16 v[64:79], v[198:201], v[214:217], v[64:79]
	v_mfma_f32_32x32x16_bf16 v[32:47], v[198:201], v[228:231], v[32:47]
	v_mfma_f32_32x32x16_bf16 v[0:15], v[198:201], v[238:241], v[0:15]
	s_setprio 0
	s_setprio 2
	s_waitcnt vmcnt(11) lgkmcnt(3)
	v_mfma_f32_32x32x16_bf16 v[112:127], v[128:131], v[210:213], v[112:127]
	s_waitcnt lgkmcnt(2)
	v_mfma_f32_32x32x16_bf16 v[80:95], v[128:131], v[218:221], v[80:95]
	s_waitcnt lgkmcnt(1)
	v_mfma_f32_32x32x16_bf16 v[48:63], v[128:131], v[234:237], v[48:63]
	s_waitcnt lgkmcnt(0)
	v_mfma_f32_32x32x16_bf16 v[16:31], v[128:131], v[242:245], v[16:31]
	global_load_dwordx4 v[128:131], v[162:163], off offset:3072
	global_load_dwordx4 v[198:201], v[170:171], off offset:3072
	s_waitcnt vmcnt(12)
	v_mfma_f32_32x32x16_bf16 v[96:111], v[152:155], v[210:213], v[96:111]
	v_mfma_f32_32x32x16_bf16 v[64:79], v[152:155], v[218:221], v[64:79]
	v_mfma_f32_32x32x16_bf16 v[32:47], v[152:155], v[234:237], v[32:47]
	v_mfma_f32_32x32x16_bf16 v[0:15], v[152:155], v[242:245], v[0:15]
	s_setprio 0
	s_waitcnt vmcnt(9)
	ds_write_b128 v184, v[148:151]
	ds_write_b128 v184, v[136:139] offset:4608
	ds_write_b128 v184, v[140:143] offset:9216
	s_waitcnt vmcnt(8)
	ds_write_b128 v184, v[166:169] offset:13824
	global_load_dwordx4 v[136:139], v[164:165], off offset:640
	global_load_dwordx4 v[140:143], v[156:157], off offset:640
	global_load_dwordx4 v[148:151], v[172:173], off offset:640
	global_load_dwordx4 v[152:155], v[178:179], off offset:640
	s_waitcnt lgkmcnt(0)
	s_barrier
	ds_read_b128 v[166:169], v183
	ds_read_b128 v[210:213], v183 offset:32
	ds_read_b128 v[214:217], v183 offset:4608
	ds_read_b128 v[218:221], v183 offset:4640
	ds_read_b128 v[228:231], v183 offset:9216
	ds_read_b128 v[234:237], v183 offset:9248
	ds_read_b128 v[238:241], v183 offset:13824
	ds_read_b128 v[242:245], v183 offset:13856
	s_setprio 2
	s_movk_i32 s8, 0x5000
	v_add_co_u32_e32 v162, vcc, s8, v176
	s_mov_b32 s8, 0x15000
	s_nop 0
	v_addc_co_u32_e32 v163, vcc, 0, v177, vcc
	v_add_co_u32_e32 v170, vcc, s8, v176
	s_waitcnt vmcnt(11) lgkmcnt(7)
	v_mfma_f32_32x32x16_bf16 v[112:127], v[158:161], v[166:169], v[112:127]
	v_addc_co_u32_e32 v171, vcc, 0, v177, vcc
	s_waitcnt lgkmcnt(5)
	v_mfma_f32_32x32x16_bf16 v[80:95], v[158:161], v[214:217], v[80:95]
	s_waitcnt lgkmcnt(3)
	v_mfma_f32_32x32x16_bf16 v[48:63], v[158:161], v[228:231], v[48:63]
	s_waitcnt lgkmcnt(1)
	v_mfma_f32_32x32x16_bf16 v[16:31], v[158:161], v[238:241], v[16:31]
	s_waitcnt vmcnt(10)
	v_mfma_f32_32x32x16_bf16 v[96:111], v[202:205], v[166:169], v[96:111]
	global_load_dwordx4 v[158:161], v[162:163], off
	global_load_dwordx4 v[166:169], v[170:171], off
	v_mfma_f32_32x32x16_bf16 v[64:79], v[202:205], v[214:217], v[64:79]
	v_mfma_f32_32x32x16_bf16 v[32:47], v[202:205], v[228:231], v[32:47]
	v_mfma_f32_32x32x16_bf16 v[0:15], v[202:205], v[238:241], v[0:15]
	s_setprio 0
	ds_read_b128 v[202:205], v183 offset:64
	ds_read_b128 v[214:217], v183 offset:4672
	ds_read_b128 v[228:231], v183 offset:9280
	ds_read_b128 v[238:241], v183 offset:13888
	s_setprio 2
	s_waitcnt vmcnt(11)
	v_mfma_f32_32x32x16_bf16 v[112:127], v[144:147], v[210:213], v[112:127]
	v_mfma_f32_32x32x16_bf16 v[80:95], v[144:147], v[218:221], v[80:95]
	v_mfma_f32_32x32x16_bf16 v[48:63], v[144:147], v[234:237], v[48:63]
	s_waitcnt lgkmcnt(4)
	v_mfma_f32_32x32x16_bf16 v[16:31], v[144:147], v[242:245], v[16:31]
	s_waitcnt vmcnt(10)
	v_mfma_f32_32x32x16_bf16 v[96:111], v[206:209], v[210:213], v[96:111]
	global_load_dwordx4 v[144:147], v[162:163], off offset:1024
	global_load_dwordx4 v[210:213], v[170:171], off offset:1024
	v_mfma_f32_32x32x16_bf16 v[64:79], v[206:209], v[218:221], v[64:79]
	v_mfma_f32_32x32x16_bf16 v[32:47], v[206:209], v[234:237], v[32:47]
	v_mfma_f32_32x32x16_bf16 v[0:15], v[206:209], v[242:245], v[0:15]
	s_setprio 0
	ds_read_b128 v[206:209], v183 offset:96
	ds_read_b128 v[218:221], v183 offset:4704
	ds_read_b128 v[234:237], v183 offset:9312
	ds_read_b128 v[242:245], v183 offset:13920
	s_setprio 2
	s_waitcnt vmcnt(11) lgkmcnt(7)
	v_mfma_f32_32x32x16_bf16 v[112:127], v[132:135], v[202:205], v[112:127]
	s_waitcnt lgkmcnt(6)
	v_mfma_f32_32x32x16_bf16 v[80:95], v[132:135], v[214:217], v[80:95]
	s_waitcnt lgkmcnt(5)
	v_mfma_f32_32x32x16_bf16 v[48:63], v[132:135], v[228:231], v[48:63]
	s_waitcnt lgkmcnt(4)
	v_mfma_f32_32x32x16_bf16 v[16:31], v[132:135], v[238:241], v[16:31]
	s_waitcnt vmcnt(10)
	v_mfma_f32_32x32x16_bf16 v[96:111], v[188:191], v[202:205], v[96:111]
	global_load_dwordx4 v[132:135], v[162:163], off offset:2048
	global_load_dwordx4 v[202:205], v[170:171], off offset:2048
	v_mfma_f32_32x32x16_bf16 v[64:79], v[188:191], v[214:217], v[64:79]
	v_mfma_f32_32x32x16_bf16 v[32:47], v[188:191], v[228:231], v[32:47]
	v_mfma_f32_32x32x16_bf16 v[0:15], v[188:191], v[238:241], v[0:15]
	s_setprio 0
	s_setprio 2
	s_waitcnt vmcnt(11) lgkmcnt(3)
	v_mfma_f32_32x32x16_bf16 v[112:127], v[128:131], v[206:209], v[112:127]
	s_waitcnt lgkmcnt(2)
	v_mfma_f32_32x32x16_bf16 v[80:95], v[128:131], v[218:221], v[80:95]
	s_waitcnt lgkmcnt(1)
	v_mfma_f32_32x32x16_bf16 v[48:63], v[128:131], v[234:237], v[48:63]
	s_waitcnt lgkmcnt(0)
	v_mfma_f32_32x32x16_bf16 v[16:31], v[128:131], v[242:245], v[16:31]
	global_load_dwordx4 v[128:131], v[162:163], off offset:3072
	global_load_dwordx4 v[188:191], v[170:171], off offset:3072
	s_waitcnt vmcnt(12)
	v_mfma_f32_32x32x16_bf16 v[96:111], v[198:201], v[206:209], v[96:111]
	v_mfma_f32_32x32x16_bf16 v[64:79], v[198:201], v[218:221], v[64:79]
	v_mfma_f32_32x32x16_bf16 v[32:47], v[198:201], v[234:237], v[32:47]
	v_mfma_f32_32x32x16_bf16 v[0:15], v[198:201], v[242:245], v[0:15]
	s_setprio 0
	s_waitcnt vmcnt(8)
	ds_write_b128 v184, v[152:155] offset:18432
	ds_write_b128 v184, v[140:143] offset:23040
	ds_write_b128 v184, v[136:139] offset:27648
	ds_write_b128 v184, v[148:151] offset:32256
	global_load_dwordx4 v[136:139], v[156:157], off offset:768
	global_load_dwordx4 v[140:143], v[164:165], off offset:768
	global_load_dwordx4 v[148:151], v[178:179], off offset:768
	global_load_dwordx4 v[152:155], v[172:173], off offset:768
	s_waitcnt lgkmcnt(0)
	s_barrier
	ds_read_b128 v[198:201], v183 offset:18432
	ds_read_b128 v[206:209], v183 offset:18464
	ds_read_b128 v[214:217], v183 offset:23040
	ds_read_b128 v[218:221], v183 offset:23072
	ds_read_b128 v[228:231], v183 offset:27648
	ds_read_b128 v[234:237], v183 offset:27680
	ds_read_b128 v[238:241], v183 offset:32256
	ds_read_b128 v[242:245], v183 offset:32288
	s_setprio 2
	s_movk_i32 s8, 0x6000
	v_add_co_u32_e32 v162, vcc, s8, v176
	s_mov_b32 s8, 0x16000
	s_nop 0
	v_addc_co_u32_e32 v163, vcc, 0, v177, vcc
	v_add_co_u32_e32 v170, vcc, s8, v176
	s_waitcnt vmcnt(11) lgkmcnt(7)
	v_mfma_f32_32x32x16_bf16 v[112:127], v[158:161], v[198:201], v[112:127]
	v_addc_co_u32_e32 v171, vcc, 0, v177, vcc
	s_waitcnt lgkmcnt(5)
	v_mfma_f32_32x32x16_bf16 v[80:95], v[158:161], v[214:217], v[80:95]
	s_waitcnt lgkmcnt(3)
	v_mfma_f32_32x32x16_bf16 v[48:63], v[158:161], v[228:231], v[48:63]
	s_waitcnt lgkmcnt(1)
	v_mfma_f32_32x32x16_bf16 v[16:31], v[158:161], v[238:241], v[16:31]
	s_waitcnt vmcnt(10)
	v_mfma_f32_32x32x16_bf16 v[96:111], v[166:169], v[198:201], v[96:111]
	global_load_dwordx4 v[158:161], v[162:163], off
	global_load_dwordx4 v[198:201], v[170:171], off
	v_mfma_f32_32x32x16_bf16 v[64:79], v[166:169], v[214:217], v[64:79]
	v_mfma_f32_32x32x16_bf16 v[32:47], v[166:169], v[228:231], v[32:47]
	v_mfma_f32_32x32x16_bf16 v[0:15], v[166:169], v[238:241], v[0:15]
	s_setprio 0
	ds_read_b128 v[166:169], v183 offset:18496
	ds_read_b128 v[214:217], v183 offset:23104
	ds_read_b128 v[228:231], v183 offset:27712
	ds_read_b128 v[238:241], v183 offset:32320
	s_setprio 2
	s_waitcnt vmcnt(11)
	v_mfma_f32_32x32x16_bf16 v[112:127], v[144:147], v[206:209], v[112:127]
	v_mfma_f32_32x32x16_bf16 v[80:95], v[144:147], v[218:221], v[80:95]
	v_mfma_f32_32x32x16_bf16 v[48:63], v[144:147], v[234:237], v[48:63]
	s_waitcnt lgkmcnt(4)
	v_mfma_f32_32x32x16_bf16 v[16:31], v[144:147], v[242:245], v[16:31]
	s_waitcnt vmcnt(10)
	v_mfma_f32_32x32x16_bf16 v[96:111], v[210:213], v[206:209], v[96:111]
	global_load_dwordx4 v[144:147], v[162:163], off offset:1024
	global_load_dwordx4 v[206:209], v[170:171], off offset:1024
	v_mfma_f32_32x32x16_bf16 v[64:79], v[210:213], v[218:221], v[64:79]
	v_mfma_f32_32x32x16_bf16 v[32:47], v[210:213], v[234:237], v[32:47]
	v_mfma_f32_32x32x16_bf16 v[0:15], v[210:213], v[242:245], v[0:15]
	s_setprio 0
	ds_read_b128 v[210:213], v183 offset:18528
	ds_read_b128 v[218:221], v183 offset:23136
	ds_read_b128 v[234:237], v183 offset:27744
	ds_read_b128 v[242:245], v183 offset:32352
	s_setprio 2
	s_waitcnt vmcnt(11) lgkmcnt(7)
	v_mfma_f32_32x32x16_bf16 v[112:127], v[132:135], v[166:169], v[112:127]
	s_waitcnt lgkmcnt(6)
	v_mfma_f32_32x32x16_bf16 v[80:95], v[132:135], v[214:217], v[80:95]
	s_waitcnt lgkmcnt(5)
	v_mfma_f32_32x32x16_bf16 v[48:63], v[132:135], v[228:231], v[48:63]
	s_waitcnt lgkmcnt(4)
	v_mfma_f32_32x32x16_bf16 v[16:31], v[132:135], v[238:241], v[16:31]
	s_waitcnt vmcnt(10)
	v_mfma_f32_32x32x16_bf16 v[96:111], v[202:205], v[166:169], v[96:111]
	global_load_dwordx4 v[132:135], v[162:163], off offset:2048
	global_load_dwordx4 v[166:169], v[170:171], off offset:2048
	v_mfma_f32_32x32x16_bf16 v[64:79], v[202:205], v[214:217], v[64:79]
	v_mfma_f32_32x32x16_bf16 v[32:47], v[202:205], v[228:231], v[32:47]
	v_mfma_f32_32x32x16_bf16 v[0:15], v[202:205], v[238:241], v[0:15]
	s_setprio 0
	s_setprio 2
	s_waitcnt vmcnt(11) lgkmcnt(3)
	v_mfma_f32_32x32x16_bf16 v[112:127], v[128:131], v[210:213], v[112:127]
	s_waitcnt lgkmcnt(2)
	v_mfma_f32_32x32x16_bf16 v[80:95], v[128:131], v[218:221], v[80:95]
	s_waitcnt lgkmcnt(1)
	v_mfma_f32_32x32x16_bf16 v[48:63], v[128:131], v[234:237], v[48:63]
	s_waitcnt lgkmcnt(0)
	v_mfma_f32_32x32x16_bf16 v[16:31], v[128:131], v[242:245], v[16:31]
	global_load_dwordx4 v[128:131], v[162:163], off offset:3072
	global_load_dwordx4 v[202:205], v[170:171], off offset:3072
	s_waitcnt vmcnt(12)
	v_mfma_f32_32x32x16_bf16 v[96:111], v[188:191], v[210:213], v[96:111]
	v_mfma_f32_32x32x16_bf16 v[64:79], v[188:191], v[218:221], v[64:79]
	v_mfma_f32_32x32x16_bf16 v[32:47], v[188:191], v[234:237], v[32:47]
	v_mfma_f32_32x32x16_bf16 v[0:15], v[188:191], v[242:245], v[0:15]
	s_setprio 0
	s_waitcnt vmcnt(9)
	ds_write_b128 v184, v[148:151]
	ds_write_b128 v184, v[136:139] offset:4608
	ds_write_b128 v184, v[140:143] offset:9216
	s_waitcnt vmcnt(8)
	ds_write_b128 v184, v[152:155] offset:13824
	global_load_dwordx4 v[136:139], v[164:165], off offset:896
	global_load_dwordx4 v[140:143], v[156:157], off offset:896
	global_load_dwordx4 v[148:151], v[172:173], off offset:896
	global_load_dwordx4 v[152:155], v[178:179], off offset:896
	s_waitcnt lgkmcnt(0)
	s_barrier
	ds_read_b128 v[188:191], v183
	ds_read_b128 v[210:213], v183 offset:32
	ds_read_b128 v[214:217], v183 offset:4608
	ds_read_b128 v[218:221], v183 offset:4640
	ds_read_b128 v[228:231], v183 offset:9216
	ds_read_b128 v[234:237], v183 offset:9248
	ds_read_b128 v[238:241], v183 offset:13824
	ds_read_b128 v[242:245], v183 offset:13856
	s_setprio 2
	s_movk_i32 s8, 0x7000
	v_add_co_u32_e32 v162, vcc, s8, v176
	s_mov_b32 s8, 0x17000
	s_nop 0
	v_addc_co_u32_e32 v163, vcc, 0, v177, vcc
	v_add_co_u32_e32 v170, vcc, s8, v176
	s_waitcnt vmcnt(11) lgkmcnt(7)
	v_mfma_f32_32x32x16_bf16 v[112:127], v[158:161], v[188:191], v[112:127]
	v_addc_co_u32_e32 v171, vcc, 0, v177, vcc
	s_waitcnt lgkmcnt(5)
	v_mfma_f32_32x32x16_bf16 v[80:95], v[158:161], v[214:217], v[80:95]
	s_waitcnt lgkmcnt(3)
	v_mfma_f32_32x32x16_bf16 v[48:63], v[158:161], v[228:231], v[48:63]
	s_waitcnt lgkmcnt(1)
	v_mfma_f32_32x32x16_bf16 v[16:31], v[158:161], v[238:241], v[16:31]
	s_waitcnt vmcnt(10)
	v_mfma_f32_32x32x16_bf16 v[96:111], v[198:201], v[188:191], v[96:111]
	global_load_dwordx4 v[158:161], v[162:163], off
	global_load_dwordx4 v[188:191], v[170:171], off
	v_mfma_f32_32x32x16_bf16 v[64:79], v[198:201], v[214:217], v[64:79]
	v_mfma_f32_32x32x16_bf16 v[32:47], v[198:201], v[228:231], v[32:47]
	v_mfma_f32_32x32x16_bf16 v[0:15], v[198:201], v[238:241], v[0:15]
	s_setprio 0
	ds_read_b128 v[198:201], v183 offset:64
	ds_read_b128 v[214:217], v183 offset:4672
	ds_read_b128 v[228:231], v183 offset:9280
	ds_read_b128 v[238:241], v183 offset:13888
	s_setprio 2
	s_waitcnt vmcnt(11)
	v_mfma_f32_32x32x16_bf16 v[112:127], v[144:147], v[210:213], v[112:127]
	v_mfma_f32_32x32x16_bf16 v[80:95], v[144:147], v[218:221], v[80:95]
	v_mfma_f32_32x32x16_bf16 v[48:63], v[144:147], v[234:237], v[48:63]
	s_waitcnt lgkmcnt(4)
	v_mfma_f32_32x32x16_bf16 v[16:31], v[144:147], v[242:245], v[16:31]
	s_waitcnt vmcnt(10)
	v_mfma_f32_32x32x16_bf16 v[96:111], v[206:209], v[210:213], v[96:111]
	global_load_dwordx4 v[144:147], v[162:163], off offset:1024
	global_load_dwordx4 v[210:213], v[170:171], off offset:1024
	v_mfma_f32_32x32x16_bf16 v[64:79], v[206:209], v[218:221], v[64:79]
	v_mfma_f32_32x32x16_bf16 v[32:47], v[206:209], v[234:237], v[32:47]
	v_mfma_f32_32x32x16_bf16 v[0:15], v[206:209], v[242:245], v[0:15]
	s_setprio 0
	ds_read_b128 v[206:209], v183 offset:96
	ds_read_b128 v[218:221], v183 offset:4704
	ds_read_b128 v[234:237], v183 offset:9312
	ds_read_b128 v[242:245], v183 offset:13920
	s_setprio 2
	s_waitcnt vmcnt(11) lgkmcnt(7)
	v_mfma_f32_32x32x16_bf16 v[112:127], v[132:135], v[198:201], v[112:127]
	s_waitcnt lgkmcnt(6)
	v_mfma_f32_32x32x16_bf16 v[80:95], v[132:135], v[214:217], v[80:95]
	s_waitcnt lgkmcnt(5)
	v_mfma_f32_32x32x16_bf16 v[48:63], v[132:135], v[228:231], v[48:63]
	s_waitcnt lgkmcnt(4)
	v_mfma_f32_32x32x16_bf16 v[16:31], v[132:135], v[238:241], v[16:31]
	s_waitcnt vmcnt(10)
	v_mfma_f32_32x32x16_bf16 v[96:111], v[166:169], v[198:201], v[96:111]
	global_load_dwordx4 v[132:135], v[162:163], off offset:2048
	global_load_dwordx4 v[198:201], v[170:171], off offset:2048
	v_mfma_f32_32x32x16_bf16 v[64:79], v[166:169], v[214:217], v[64:79]
	v_mfma_f32_32x32x16_bf16 v[32:47], v[166:169], v[228:231], v[32:47]
	v_mfma_f32_32x32x16_bf16 v[0:15], v[166:169], v[238:241], v[0:15]
	s_setprio 0
	s_setprio 2
	s_waitcnt vmcnt(11) lgkmcnt(3)
	v_mfma_f32_32x32x16_bf16 v[112:127], v[128:131], v[206:209], v[112:127]
	s_waitcnt lgkmcnt(2)
	v_mfma_f32_32x32x16_bf16 v[80:95], v[128:131], v[218:221], v[80:95]
	s_waitcnt lgkmcnt(1)
	v_mfma_f32_32x32x16_bf16 v[48:63], v[128:131], v[234:237], v[48:63]
	s_waitcnt lgkmcnt(0)
	v_mfma_f32_32x32x16_bf16 v[16:31], v[128:131], v[242:245], v[16:31]
	global_load_dwordx4 v[128:131], v[162:163], off offset:3072
	global_load_dwordx4 v[166:169], v[170:171], off offset:3072
	s_waitcnt vmcnt(12)
	v_mfma_f32_32x32x16_bf16 v[96:111], v[202:205], v[206:209], v[96:111]
	v_mfma_f32_32x32x16_bf16 v[64:79], v[202:205], v[218:221], v[64:79]
	v_mfma_f32_32x32x16_bf16 v[32:47], v[202:205], v[234:237], v[32:47]
	v_mfma_f32_32x32x16_bf16 v[0:15], v[202:205], v[242:245], v[0:15]
	s_setprio 0
	s_waitcnt vmcnt(8)
	ds_write_b128 v184, v[152:155] offset:18432
	ds_write_b128 v184, v[140:143] offset:23040
	ds_write_b128 v184, v[136:139] offset:27648
	ds_write_b128 v184, v[148:151] offset:32256
	global_load_dwordx4 v[136:139], v[156:157], off offset:1024
	global_load_dwordx4 v[140:143], v[164:165], off offset:1024
	global_load_dwordx4 v[148:151], v[178:179], off offset:1024
	global_load_dwordx4 v[152:155], v[172:173], off offset:1024
	s_waitcnt lgkmcnt(0)
	s_barrier
	ds_read_b128 v[202:205], v183 offset:18432
	ds_read_b128 v[206:209], v183 offset:18464
	ds_read_b128 v[214:217], v183 offset:23040
	ds_read_b128 v[218:221], v183 offset:23072
	ds_read_b128 v[228:231], v183 offset:27648
	ds_read_b128 v[234:237], v183 offset:27680
	ds_read_b128 v[238:241], v183 offset:32256
	ds_read_b128 v[242:245], v183 offset:32288
	s_setprio 2
	s_mov_b32 s8, 0x8000
	v_add_co_u32_e32 v162, vcc, s8, v176
	s_mov_b32 s8, 0x18000
	s_nop 0
	v_addc_co_u32_e32 v163, vcc, 0, v177, vcc
	v_add_co_u32_e32 v170, vcc, s8, v176
	s_waitcnt vmcnt(11) lgkmcnt(7)
	v_mfma_f32_32x32x16_bf16 v[112:127], v[158:161], v[202:205], v[112:127]
	v_addc_co_u32_e32 v171, vcc, 0, v177, vcc
	s_waitcnt lgkmcnt(5)
	v_mfma_f32_32x32x16_bf16 v[80:95], v[158:161], v[214:217], v[80:95]
	s_waitcnt lgkmcnt(3)
	v_mfma_f32_32x32x16_bf16 v[48:63], v[158:161], v[228:231], v[48:63]
	s_waitcnt lgkmcnt(1)
	v_mfma_f32_32x32x16_bf16 v[16:31], v[158:161], v[238:241], v[16:31]
	s_waitcnt vmcnt(10)
	v_mfma_f32_32x32x16_bf16 v[96:111], v[188:191], v[202:205], v[96:111]
	global_load_dwordx4 v[158:161], v[162:163], off
	global_load_dwordx4 v[202:205], v[170:171], off
	v_mfma_f32_32x32x16_bf16 v[64:79], v[188:191], v[214:217], v[64:79]
	v_mfma_f32_32x32x16_bf16 v[32:47], v[188:191], v[228:231], v[32:47]
	v_mfma_f32_32x32x16_bf16 v[0:15], v[188:191], v[238:241], v[0:15]
	s_setprio 0
	ds_read_b128 v[188:191], v183 offset:18496
	ds_read_b128 v[214:217], v183 offset:23104
	ds_read_b128 v[228:231], v183 offset:27712
	ds_read_b128 v[238:241], v183 offset:32320
	s_setprio 2
	s_waitcnt vmcnt(11)
	v_mfma_f32_32x32x16_bf16 v[112:127], v[144:147], v[206:209], v[112:127]
	v_mfma_f32_32x32x16_bf16 v[80:95], v[144:147], v[218:221], v[80:95]
	v_mfma_f32_32x32x16_bf16 v[48:63], v[144:147], v[234:237], v[48:63]
	s_waitcnt lgkmcnt(4)
	v_mfma_f32_32x32x16_bf16 v[16:31], v[144:147], v[242:245], v[16:31]
	s_waitcnt vmcnt(10)
	v_mfma_f32_32x32x16_bf16 v[96:111], v[210:213], v[206:209], v[96:111]
	global_load_dwordx4 v[144:147], v[162:163], off offset:1024
	global_load_dwordx4 v[206:209], v[170:171], off offset:1024
	v_mfma_f32_32x32x16_bf16 v[64:79], v[210:213], v[218:221], v[64:79]
	v_mfma_f32_32x32x16_bf16 v[32:47], v[210:213], v[234:237], v[32:47]
	v_mfma_f32_32x32x16_bf16 v[0:15], v[210:213], v[242:245], v[0:15]
	s_setprio 0
	ds_read_b128 v[210:213], v183 offset:18528
	ds_read_b128 v[218:221], v183 offset:23136
	ds_read_b128 v[234:237], v183 offset:27744
	ds_read_b128 v[242:245], v183 offset:32352
	s_setprio 2
	s_waitcnt vmcnt(11) lgkmcnt(7)
	v_mfma_f32_32x32x16_bf16 v[112:127], v[132:135], v[188:191], v[112:127]
	s_waitcnt lgkmcnt(6)
	v_mfma_f32_32x32x16_bf16 v[80:95], v[132:135], v[214:217], v[80:95]
	s_waitcnt lgkmcnt(5)
	v_mfma_f32_32x32x16_bf16 v[48:63], v[132:135], v[228:231], v[48:63]
	s_waitcnt lgkmcnt(4)
	v_mfma_f32_32x32x16_bf16 v[16:31], v[132:135], v[238:241], v[16:31]
	s_waitcnt vmcnt(10)
	v_mfma_f32_32x32x16_bf16 v[96:111], v[198:201], v[188:191], v[96:111]
	global_load_dwordx4 v[132:135], v[162:163], off offset:2048
	global_load_dwordx4 v[188:191], v[170:171], off offset:2048
	v_mfma_f32_32x32x16_bf16 v[64:79], v[198:201], v[214:217], v[64:79]
	v_mfma_f32_32x32x16_bf16 v[32:47], v[198:201], v[228:231], v[32:47]
	v_mfma_f32_32x32x16_bf16 v[0:15], v[198:201], v[238:241], v[0:15]
	s_setprio 0
	s_setprio 2
	s_waitcnt vmcnt(11) lgkmcnt(3)
	v_mfma_f32_32x32x16_bf16 v[112:127], v[128:131], v[210:213], v[112:127]
	s_waitcnt lgkmcnt(2)
	v_mfma_f32_32x32x16_bf16 v[80:95], v[128:131], v[218:221], v[80:95]
	s_waitcnt lgkmcnt(1)
	v_mfma_f32_32x32x16_bf16 v[48:63], v[128:131], v[234:237], v[48:63]
	s_waitcnt lgkmcnt(0)
	v_mfma_f32_32x32x16_bf16 v[16:31], v[128:131], v[242:245], v[16:31]
	global_load_dwordx4 v[128:131], v[162:163], off offset:3072
	global_load_dwordx4 v[198:201], v[170:171], off offset:3072
	s_waitcnt vmcnt(12)
	v_mfma_f32_32x32x16_bf16 v[96:111], v[166:169], v[210:213], v[96:111]
	v_mfma_f32_32x32x16_bf16 v[64:79], v[166:169], v[218:221], v[64:79]
	v_mfma_f32_32x32x16_bf16 v[32:47], v[166:169], v[234:237], v[32:47]
	v_mfma_f32_32x32x16_bf16 v[0:15], v[166:169], v[242:245], v[0:15]
	s_setprio 0
	s_waitcnt vmcnt(9)
	ds_write_b128 v184, v[148:151]
	ds_write_b128 v184, v[136:139] offset:4608
	ds_write_b128 v184, v[140:143] offset:9216
	s_waitcnt vmcnt(8)
	ds_write_b128 v184, v[152:155] offset:13824
	global_load_dwordx4 v[136:139], v[164:165], off offset:1152
	global_load_dwordx4 v[140:143], v[156:157], off offset:1152
	global_load_dwordx4 v[148:151], v[172:173], off offset:1152
	global_load_dwordx4 v[152:155], v[178:179], off offset:1152
	s_waitcnt lgkmcnt(0)
	s_barrier
	ds_read_b128 v[166:169], v183
	ds_read_b128 v[210:213], v183 offset:32
	ds_read_b128 v[214:217], v183 offset:4608
	ds_read_b128 v[218:221], v183 offset:4640
	ds_read_b128 v[228:231], v183 offset:9216
	ds_read_b128 v[234:237], v183 offset:9248
	ds_read_b128 v[238:241], v183 offset:13824
	ds_read_b128 v[242:245], v183 offset:13856
	s_setprio 2
	s_mov_b32 s8, 0x9000
	v_add_co_u32_e32 v162, vcc, s8, v176
	s_mov_b32 s8, 0x19000
	s_nop 0
	v_addc_co_u32_e32 v163, vcc, 0, v177, vcc
	v_add_co_u32_e32 v170, vcc, s8, v176
	s_waitcnt vmcnt(11) lgkmcnt(7)
	v_mfma_f32_32x32x16_bf16 v[112:127], v[158:161], v[166:169], v[112:127]
	v_addc_co_u32_e32 v171, vcc, 0, v177, vcc
	s_waitcnt lgkmcnt(5)
	v_mfma_f32_32x32x16_bf16 v[80:95], v[158:161], v[214:217], v[80:95]
	s_waitcnt lgkmcnt(3)
	v_mfma_f32_32x32x16_bf16 v[48:63], v[158:161], v[228:231], v[48:63]
	s_waitcnt lgkmcnt(1)
	v_mfma_f32_32x32x16_bf16 v[16:31], v[158:161], v[238:241], v[16:31]
	s_waitcnt vmcnt(10)
	v_mfma_f32_32x32x16_bf16 v[96:111], v[202:205], v[166:169], v[96:111]
	global_load_dwordx4 v[158:161], v[162:163], off
	global_load_dwordx4 v[166:169], v[170:171], off
	v_mfma_f32_32x32x16_bf16 v[64:79], v[202:205], v[214:217], v[64:79]
	v_mfma_f32_32x32x16_bf16 v[32:47], v[202:205], v[228:231], v[32:47]
	v_mfma_f32_32x32x16_bf16 v[0:15], v[202:205], v[238:241], v[0:15]
	s_setprio 0
	ds_read_b128 v[202:205], v183 offset:64
	ds_read_b128 v[214:217], v183 offset:4672
	ds_read_b128 v[228:231], v183 offset:9280
	ds_read_b128 v[238:241], v183 offset:13888
	s_setprio 2
	s_waitcnt vmcnt(11)
	v_mfma_f32_32x32x16_bf16 v[112:127], v[144:147], v[210:213], v[112:127]
	v_mfma_f32_32x32x16_bf16 v[80:95], v[144:147], v[218:221], v[80:95]
	v_mfma_f32_32x32x16_bf16 v[48:63], v[144:147], v[234:237], v[48:63]
	s_waitcnt lgkmcnt(4)
	v_mfma_f32_32x32x16_bf16 v[16:31], v[144:147], v[242:245], v[16:31]
	s_waitcnt vmcnt(10)
	v_mfma_f32_32x32x16_bf16 v[96:111], v[206:209], v[210:213], v[96:111]
	global_load_dwordx4 v[144:147], v[162:163], off offset:1024
	global_load_dwordx4 v[210:213], v[170:171], off offset:1024
	v_mfma_f32_32x32x16_bf16 v[64:79], v[206:209], v[218:221], v[64:79]
	v_mfma_f32_32x32x16_bf16 v[32:47], v[206:209], v[234:237], v[32:47]
	v_mfma_f32_32x32x16_bf16 v[0:15], v[206:209], v[242:245], v[0:15]
	s_setprio 0
	ds_read_b128 v[206:209], v183 offset:96
	ds_read_b128 v[218:221], v183 offset:4704
	ds_read_b128 v[234:237], v183 offset:9312
	ds_read_b128 v[242:245], v183 offset:13920
	s_setprio 2
	s_waitcnt vmcnt(11) lgkmcnt(7)
	v_mfma_f32_32x32x16_bf16 v[112:127], v[132:135], v[202:205], v[112:127]
	s_waitcnt lgkmcnt(6)
	v_mfma_f32_32x32x16_bf16 v[80:95], v[132:135], v[214:217], v[80:95]
	s_waitcnt lgkmcnt(5)
	v_mfma_f32_32x32x16_bf16 v[48:63], v[132:135], v[228:231], v[48:63]
	s_waitcnt lgkmcnt(4)
	v_mfma_f32_32x32x16_bf16 v[16:31], v[132:135], v[238:241], v[16:31]
	s_waitcnt vmcnt(10)
	v_mfma_f32_32x32x16_bf16 v[96:111], v[188:191], v[202:205], v[96:111]
	global_load_dwordx4 v[132:135], v[162:163], off offset:2048
	global_load_dwordx4 v[202:205], v[170:171], off offset:2048
	v_mfma_f32_32x32x16_bf16 v[64:79], v[188:191], v[214:217], v[64:79]
	v_mfma_f32_32x32x16_bf16 v[32:47], v[188:191], v[228:231], v[32:47]
	v_mfma_f32_32x32x16_bf16 v[0:15], v[188:191], v[238:241], v[0:15]
	s_setprio 0
	s_setprio 2
	s_waitcnt vmcnt(11) lgkmcnt(3)
	v_mfma_f32_32x32x16_bf16 v[112:127], v[128:131], v[206:209], v[112:127]
	s_waitcnt lgkmcnt(2)
	v_mfma_f32_32x32x16_bf16 v[80:95], v[128:131], v[218:221], v[80:95]
	s_waitcnt lgkmcnt(1)
	v_mfma_f32_32x32x16_bf16 v[48:63], v[128:131], v[234:237], v[48:63]
	s_waitcnt lgkmcnt(0)
	v_mfma_f32_32x32x16_bf16 v[16:31], v[128:131], v[242:245], v[16:31]
	global_load_dwordx4 v[128:131], v[162:163], off offset:3072
	global_load_dwordx4 v[188:191], v[170:171], off offset:3072
	s_waitcnt vmcnt(12)
	v_mfma_f32_32x32x16_bf16 v[96:111], v[198:201], v[206:209], v[96:111]
	v_mfma_f32_32x32x16_bf16 v[64:79], v[198:201], v[218:221], v[64:79]
	v_mfma_f32_32x32x16_bf16 v[32:47], v[198:201], v[234:237], v[32:47]
	v_mfma_f32_32x32x16_bf16 v[0:15], v[198:201], v[242:245], v[0:15]
	s_setprio 0
	s_waitcnt vmcnt(8)
	ds_write_b128 v184, v[152:155] offset:18432
	ds_write_b128 v184, v[140:143] offset:23040
	ds_write_b128 v184, v[136:139] offset:27648
	ds_write_b128 v184, v[148:151] offset:32256
	global_load_dwordx4 v[136:139], v[156:157], off offset:1280
	global_load_dwordx4 v[140:143], v[164:165], off offset:1280
	global_load_dwordx4 v[148:151], v[178:179], off offset:1280
	global_load_dwordx4 v[152:155], v[172:173], off offset:1280
	s_waitcnt lgkmcnt(0)
	s_barrier
	ds_read_b128 v[198:201], v183 offset:18432
	ds_read_b128 v[206:209], v183 offset:18464
	ds_read_b128 v[214:217], v183 offset:23040
	ds_read_b128 v[218:221], v183 offset:23072
	ds_read_b128 v[228:231], v183 offset:27648
	ds_read_b128 v[234:237], v183 offset:27680
	ds_read_b128 v[238:241], v183 offset:32256
	ds_read_b128 v[242:245], v183 offset:32288
	s_setprio 2
	s_mov_b32 s8, 0xa000
	v_add_co_u32_e32 v162, vcc, s8, v176
	s_mov_b32 s8, 0x1a000
	s_nop 0
	v_addc_co_u32_e32 v163, vcc, 0, v177, vcc
	v_add_co_u32_e32 v170, vcc, s8, v176
	s_waitcnt vmcnt(11) lgkmcnt(7)
	v_mfma_f32_32x32x16_bf16 v[112:127], v[158:161], v[198:201], v[112:127]
	v_addc_co_u32_e32 v171, vcc, 0, v177, vcc
	s_waitcnt lgkmcnt(5)
	v_mfma_f32_32x32x16_bf16 v[80:95], v[158:161], v[214:217], v[80:95]
	s_waitcnt lgkmcnt(3)
	v_mfma_f32_32x32x16_bf16 v[48:63], v[158:161], v[228:231], v[48:63]
	s_waitcnt lgkmcnt(1)
	v_mfma_f32_32x32x16_bf16 v[16:31], v[158:161], v[238:241], v[16:31]
	s_waitcnt vmcnt(10)
	v_mfma_f32_32x32x16_bf16 v[96:111], v[166:169], v[198:201], v[96:111]
	global_load_dwordx4 v[158:161], v[162:163], off
	global_load_dwordx4 v[198:201], v[170:171], off
	v_mfma_f32_32x32x16_bf16 v[64:79], v[166:169], v[214:217], v[64:79]
	v_mfma_f32_32x32x16_bf16 v[32:47], v[166:169], v[228:231], v[32:47]
	v_mfma_f32_32x32x16_bf16 v[0:15], v[166:169], v[238:241], v[0:15]
	s_setprio 0
	ds_read_b128 v[166:169], v183 offset:18496
	ds_read_b128 v[214:217], v183 offset:23104
	ds_read_b128 v[228:231], v183 offset:27712
	ds_read_b128 v[238:241], v183 offset:32320
	s_setprio 2
	s_waitcnt vmcnt(11)
	v_mfma_f32_32x32x16_bf16 v[112:127], v[144:147], v[206:209], v[112:127]
	v_mfma_f32_32x32x16_bf16 v[80:95], v[144:147], v[218:221], v[80:95]
	v_mfma_f32_32x32x16_bf16 v[48:63], v[144:147], v[234:237], v[48:63]
	s_waitcnt lgkmcnt(4)
	v_mfma_f32_32x32x16_bf16 v[16:31], v[144:147], v[242:245], v[16:31]
	s_waitcnt vmcnt(10)
	v_mfma_f32_32x32x16_bf16 v[96:111], v[210:213], v[206:209], v[96:111]
	global_load_dwordx4 v[144:147], v[162:163], off offset:1024
	global_load_dwordx4 v[206:209], v[170:171], off offset:1024
	v_mfma_f32_32x32x16_bf16 v[64:79], v[210:213], v[218:221], v[64:79]
	v_mfma_f32_32x32x16_bf16 v[32:47], v[210:213], v[234:237], v[32:47]
	v_mfma_f32_32x32x16_bf16 v[0:15], v[210:213], v[242:245], v[0:15]
	s_setprio 0
	ds_read_b128 v[210:213], v183 offset:18528
	ds_read_b128 v[218:221], v183 offset:23136
	ds_read_b128 v[234:237], v183 offset:27744
	ds_read_b128 v[242:245], v183 offset:32352
	s_setprio 2
	s_waitcnt vmcnt(11) lgkmcnt(7)
	v_mfma_f32_32x32x16_bf16 v[112:127], v[132:135], v[166:169], v[112:127]
	s_waitcnt lgkmcnt(6)
	v_mfma_f32_32x32x16_bf16 v[80:95], v[132:135], v[214:217], v[80:95]
	s_waitcnt lgkmcnt(5)
	v_mfma_f32_32x32x16_bf16 v[48:63], v[132:135], v[228:231], v[48:63]
	s_waitcnt lgkmcnt(4)
	v_mfma_f32_32x32x16_bf16 v[16:31], v[132:135], v[238:241], v[16:31]
	s_waitcnt vmcnt(10)
	v_mfma_f32_32x32x16_bf16 v[96:111], v[202:205], v[166:169], v[96:111]
	global_load_dwordx4 v[132:135], v[162:163], off offset:2048
	global_load_dwordx4 v[166:169], v[170:171], off offset:2048
	v_mfma_f32_32x32x16_bf16 v[64:79], v[202:205], v[214:217], v[64:79]
	v_mfma_f32_32x32x16_bf16 v[32:47], v[202:205], v[228:231], v[32:47]
	v_mfma_f32_32x32x16_bf16 v[0:15], v[202:205], v[238:241], v[0:15]
	s_setprio 0
	s_setprio 2
	s_waitcnt vmcnt(11) lgkmcnt(3)
	v_mfma_f32_32x32x16_bf16 v[112:127], v[128:131], v[210:213], v[112:127]
	s_waitcnt lgkmcnt(2)
	v_mfma_f32_32x32x16_bf16 v[80:95], v[128:131], v[218:221], v[80:95]
	s_waitcnt lgkmcnt(1)
	v_mfma_f32_32x32x16_bf16 v[48:63], v[128:131], v[234:237], v[48:63]
	s_waitcnt lgkmcnt(0)
	v_mfma_f32_32x32x16_bf16 v[16:31], v[128:131], v[242:245], v[16:31]
	global_load_dwordx4 v[128:131], v[162:163], off offset:3072
	global_load_dwordx4 v[202:205], v[170:171], off offset:3072
	s_waitcnt vmcnt(12)
	v_mfma_f32_32x32x16_bf16 v[96:111], v[188:191], v[210:213], v[96:111]
	v_mfma_f32_32x32x16_bf16 v[64:79], v[188:191], v[218:221], v[64:79]
	v_mfma_f32_32x32x16_bf16 v[32:47], v[188:191], v[234:237], v[32:47]
	v_mfma_f32_32x32x16_bf16 v[0:15], v[188:191], v[242:245], v[0:15]
	s_setprio 0
	s_waitcnt vmcnt(9)
	ds_write_b128 v184, v[148:151]
	ds_write_b128 v184, v[136:139] offset:4608
	ds_write_b128 v184, v[140:143] offset:9216
	s_waitcnt vmcnt(8)
	ds_write_b128 v184, v[152:155] offset:13824
	global_load_dwordx4 v[136:139], v[164:165], off offset:1408
	global_load_dwordx4 v[140:143], v[156:157], off offset:1408
	global_load_dwordx4 v[148:151], v[172:173], off offset:1408
	global_load_dwordx4 v[152:155], v[178:179], off offset:1408
	s_waitcnt lgkmcnt(0)
	s_barrier
	ds_read_b128 v[188:191], v183
	ds_read_b128 v[210:213], v183 offset:32
	ds_read_b128 v[214:217], v183 offset:4608
	ds_read_b128 v[218:221], v183 offset:4640
	ds_read_b128 v[228:231], v183 offset:9216
	ds_read_b128 v[234:237], v183 offset:9248
	ds_read_b128 v[238:241], v183 offset:13824
	ds_read_b128 v[242:245], v183 offset:13856
	s_setprio 2
	s_mov_b32 s8, 0xb000
	v_add_co_u32_e32 v162, vcc, s8, v176
	s_mov_b32 s8, 0x1b000
	s_nop 0
	v_addc_co_u32_e32 v163, vcc, 0, v177, vcc
	v_add_co_u32_e32 v170, vcc, s8, v176
	s_waitcnt vmcnt(11) lgkmcnt(7)
	v_mfma_f32_32x32x16_bf16 v[112:127], v[158:161], v[188:191], v[112:127]
	v_addc_co_u32_e32 v171, vcc, 0, v177, vcc
	s_waitcnt lgkmcnt(5)
	v_mfma_f32_32x32x16_bf16 v[80:95], v[158:161], v[214:217], v[80:95]
	s_waitcnt lgkmcnt(3)
	v_mfma_f32_32x32x16_bf16 v[48:63], v[158:161], v[228:231], v[48:63]
	s_waitcnt lgkmcnt(1)
	v_mfma_f32_32x32x16_bf16 v[16:31], v[158:161], v[238:241], v[16:31]
	s_waitcnt vmcnt(10)
	v_mfma_f32_32x32x16_bf16 v[96:111], v[198:201], v[188:191], v[96:111]
	global_load_dwordx4 v[158:161], v[162:163], off
	global_load_dwordx4 v[188:191], v[170:171], off
	v_mfma_f32_32x32x16_bf16 v[64:79], v[198:201], v[214:217], v[64:79]
	v_mfma_f32_32x32x16_bf16 v[32:47], v[198:201], v[228:231], v[32:47]
	v_mfma_f32_32x32x16_bf16 v[0:15], v[198:201], v[238:241], v[0:15]
	s_setprio 0
	ds_read_b128 v[198:201], v183 offset:64
	ds_read_b128 v[214:217], v183 offset:4672
	ds_read_b128 v[228:231], v183 offset:9280
	ds_read_b128 v[238:241], v183 offset:13888
	s_setprio 2
	s_waitcnt vmcnt(11)
	v_mfma_f32_32x32x16_bf16 v[112:127], v[144:147], v[210:213], v[112:127]
	v_mfma_f32_32x32x16_bf16 v[80:95], v[144:147], v[218:221], v[80:95]
	v_mfma_f32_32x32x16_bf16 v[48:63], v[144:147], v[234:237], v[48:63]
	s_waitcnt lgkmcnt(4)
	v_mfma_f32_32x32x16_bf16 v[16:31], v[144:147], v[242:245], v[16:31]
	s_waitcnt vmcnt(10)
	v_mfma_f32_32x32x16_bf16 v[96:111], v[206:209], v[210:213], v[96:111]
	global_load_dwordx4 v[144:147], v[162:163], off offset:1024
	global_load_dwordx4 v[210:213], v[170:171], off offset:1024
	v_mfma_f32_32x32x16_bf16 v[64:79], v[206:209], v[218:221], v[64:79]
	v_mfma_f32_32x32x16_bf16 v[32:47], v[206:209], v[234:237], v[32:47]
	v_mfma_f32_32x32x16_bf16 v[0:15], v[206:209], v[242:245], v[0:15]
	s_setprio 0
	ds_read_b128 v[206:209], v183 offset:96
	ds_read_b128 v[218:221], v183 offset:4704
	ds_read_b128 v[234:237], v183 offset:9312
	ds_read_b128 v[242:245], v183 offset:13920
	s_setprio 2
	s_waitcnt vmcnt(11) lgkmcnt(7)
	v_mfma_f32_32x32x16_bf16 v[112:127], v[132:135], v[198:201], v[112:127]
	s_waitcnt lgkmcnt(6)
	v_mfma_f32_32x32x16_bf16 v[80:95], v[132:135], v[214:217], v[80:95]
	s_waitcnt lgkmcnt(5)
	v_mfma_f32_32x32x16_bf16 v[48:63], v[132:135], v[228:231], v[48:63]
	s_waitcnt lgkmcnt(4)
	v_mfma_f32_32x32x16_bf16 v[16:31], v[132:135], v[238:241], v[16:31]
	s_waitcnt vmcnt(10)
	v_mfma_f32_32x32x16_bf16 v[96:111], v[166:169], v[198:201], v[96:111]
	global_load_dwordx4 v[132:135], v[162:163], off offset:2048
	global_load_dwordx4 v[198:201], v[170:171], off offset:2048
	v_mfma_f32_32x32x16_bf16 v[64:79], v[166:169], v[214:217], v[64:79]
	v_mfma_f32_32x32x16_bf16 v[32:47], v[166:169], v[228:231], v[32:47]
	v_mfma_f32_32x32x16_bf16 v[0:15], v[166:169], v[238:241], v[0:15]
	s_setprio 0
	s_setprio 2
	s_waitcnt vmcnt(11) lgkmcnt(3)
	v_mfma_f32_32x32x16_bf16 v[112:127], v[128:131], v[206:209], v[112:127]
	s_waitcnt lgkmcnt(2)
	v_mfma_f32_32x32x16_bf16 v[80:95], v[128:131], v[218:221], v[80:95]
	s_waitcnt lgkmcnt(1)
	v_mfma_f32_32x32x16_bf16 v[48:63], v[128:131], v[234:237], v[48:63]
	s_waitcnt lgkmcnt(0)
	v_mfma_f32_32x32x16_bf16 v[16:31], v[128:131], v[242:245], v[16:31]
	global_load_dwordx4 v[128:131], v[162:163], off offset:3072
	global_load_dwordx4 v[166:169], v[170:171], off offset:3072
	s_waitcnt vmcnt(12)
	v_mfma_f32_32x32x16_bf16 v[96:111], v[202:205], v[206:209], v[96:111]
	v_mfma_f32_32x32x16_bf16 v[64:79], v[202:205], v[218:221], v[64:79]
	v_mfma_f32_32x32x16_bf16 v[32:47], v[202:205], v[234:237], v[32:47]
	v_mfma_f32_32x32x16_bf16 v[0:15], v[202:205], v[242:245], v[0:15]
	s_setprio 0
	s_waitcnt vmcnt(8)
	ds_write_b128 v184, v[152:155] offset:18432
	ds_write_b128 v184, v[140:143] offset:23040
	ds_write_b128 v184, v[136:139] offset:27648
	ds_write_b128 v184, v[148:151] offset:32256
	global_load_dwordx4 v[136:139], v[156:157], off offset:1536
	global_load_dwordx4 v[140:143], v[164:165], off offset:1536
	global_load_dwordx4 v[148:151], v[178:179], off offset:1536
	global_load_dwordx4 v[152:155], v[172:173], off offset:1536
	s_waitcnt lgkmcnt(0)
	s_barrier
	ds_read_b128 v[202:205], v183 offset:18432
	ds_read_b128 v[206:209], v183 offset:18464
	ds_read_b128 v[214:217], v183 offset:23040
	ds_read_b128 v[218:221], v183 offset:23072
	ds_read_b128 v[228:231], v183 offset:27648
	ds_read_b128 v[234:237], v183 offset:27680
	ds_read_b128 v[238:241], v183 offset:32256
	ds_read_b128 v[242:245], v183 offset:32288
	s_setprio 2
	s_mov_b32 s8, 0xc000
	v_add_co_u32_e32 v162, vcc, s8, v176
	s_mov_b32 s8, 0x1c000
	s_nop 0
	v_addc_co_u32_e32 v163, vcc, 0, v177, vcc
	v_add_co_u32_e32 v170, vcc, s8, v176
	s_waitcnt vmcnt(11) lgkmcnt(7)
	v_mfma_f32_32x32x16_bf16 v[112:127], v[158:161], v[202:205], v[112:127]
	v_addc_co_u32_e32 v171, vcc, 0, v177, vcc
	s_waitcnt lgkmcnt(5)
	v_mfma_f32_32x32x16_bf16 v[80:95], v[158:161], v[214:217], v[80:95]
	s_waitcnt lgkmcnt(3)
	v_mfma_f32_32x32x16_bf16 v[48:63], v[158:161], v[228:231], v[48:63]
	s_waitcnt lgkmcnt(1)
	v_mfma_f32_32x32x16_bf16 v[16:31], v[158:161], v[238:241], v[16:31]
	s_waitcnt vmcnt(10)
	v_mfma_f32_32x32x16_bf16 v[96:111], v[188:191], v[202:205], v[96:111]
	global_load_dwordx4 v[158:161], v[162:163], off
	global_load_dwordx4 v[202:205], v[170:171], off
	v_mfma_f32_32x32x16_bf16 v[64:79], v[188:191], v[214:217], v[64:79]
	v_mfma_f32_32x32x16_bf16 v[32:47], v[188:191], v[228:231], v[32:47]
	v_mfma_f32_32x32x16_bf16 v[0:15], v[188:191], v[238:241], v[0:15]
	s_setprio 0
	ds_read_b128 v[188:191], v183 offset:18496
	ds_read_b128 v[214:217], v183 offset:23104
	ds_read_b128 v[228:231], v183 offset:27712
	ds_read_b128 v[238:241], v183 offset:32320
	s_setprio 2
	s_waitcnt vmcnt(11)
	v_mfma_f32_32x32x16_bf16 v[112:127], v[144:147], v[206:209], v[112:127]
	v_mfma_f32_32x32x16_bf16 v[80:95], v[144:147], v[218:221], v[80:95]
	v_mfma_f32_32x32x16_bf16 v[48:63], v[144:147], v[234:237], v[48:63]
	s_waitcnt lgkmcnt(4)
	v_mfma_f32_32x32x16_bf16 v[16:31], v[144:147], v[242:245], v[16:31]
	s_waitcnt vmcnt(10)
	v_mfma_f32_32x32x16_bf16 v[96:111], v[210:213], v[206:209], v[96:111]
	global_load_dwordx4 v[144:147], v[162:163], off offset:1024
	global_load_dwordx4 v[206:209], v[170:171], off offset:1024
	v_mfma_f32_32x32x16_bf16 v[64:79], v[210:213], v[218:221], v[64:79]
	v_mfma_f32_32x32x16_bf16 v[32:47], v[210:213], v[234:237], v[32:47]
	v_mfma_f32_32x32x16_bf16 v[0:15], v[210:213], v[242:245], v[0:15]
	s_setprio 0
	ds_read_b128 v[210:213], v183 offset:18528
	ds_read_b128 v[218:221], v183 offset:23136
	ds_read_b128 v[234:237], v183 offset:27744
	ds_read_b128 v[242:245], v183 offset:32352
	s_setprio 2
	s_waitcnt vmcnt(11) lgkmcnt(7)
	v_mfma_f32_32x32x16_bf16 v[112:127], v[132:135], v[188:191], v[112:127]
	s_waitcnt lgkmcnt(6)
	v_mfma_f32_32x32x16_bf16 v[80:95], v[132:135], v[214:217], v[80:95]
	s_waitcnt lgkmcnt(5)
	v_mfma_f32_32x32x16_bf16 v[48:63], v[132:135], v[228:231], v[48:63]
	s_waitcnt lgkmcnt(4)
	v_mfma_f32_32x32x16_bf16 v[16:31], v[132:135], v[238:241], v[16:31]
	s_waitcnt vmcnt(10)
	v_mfma_f32_32x32x16_bf16 v[96:111], v[198:201], v[188:191], v[96:111]
	global_load_dwordx4 v[132:135], v[162:163], off offset:2048
	global_load_dwordx4 v[188:191], v[170:171], off offset:2048
	v_mfma_f32_32x32x16_bf16 v[64:79], v[198:201], v[214:217], v[64:79]
	v_mfma_f32_32x32x16_bf16 v[32:47], v[198:201], v[228:231], v[32:47]
	v_mfma_f32_32x32x16_bf16 v[0:15], v[198:201], v[238:241], v[0:15]
	s_setprio 0
	s_setprio 2
	s_waitcnt vmcnt(11) lgkmcnt(3)
	v_mfma_f32_32x32x16_bf16 v[112:127], v[128:131], v[210:213], v[112:127]
	s_waitcnt lgkmcnt(2)
	v_mfma_f32_32x32x16_bf16 v[80:95], v[128:131], v[218:221], v[80:95]
	s_waitcnt lgkmcnt(1)
	v_mfma_f32_32x32x16_bf16 v[48:63], v[128:131], v[234:237], v[48:63]
	s_waitcnt lgkmcnt(0)
	v_mfma_f32_32x32x16_bf16 v[16:31], v[128:131], v[242:245], v[16:31]
	global_load_dwordx4 v[128:131], v[162:163], off offset:3072
	global_load_dwordx4 v[198:201], v[170:171], off offset:3072
	s_waitcnt vmcnt(12)
	v_mfma_f32_32x32x16_bf16 v[96:111], v[166:169], v[210:213], v[96:111]
	v_mfma_f32_32x32x16_bf16 v[64:79], v[166:169], v[218:221], v[64:79]
	v_mfma_f32_32x32x16_bf16 v[32:47], v[166:169], v[234:237], v[32:47]
	v_mfma_f32_32x32x16_bf16 v[0:15], v[166:169], v[242:245], v[0:15]
	s_setprio 0
	s_waitcnt vmcnt(9)
	ds_write_b128 v184, v[148:151]
	ds_write_b128 v184, v[136:139] offset:4608
	ds_write_b128 v184, v[140:143] offset:9216
	s_waitcnt vmcnt(8)
	ds_write_b128 v184, v[152:155] offset:13824
	global_load_dwordx4 v[136:139], v[164:165], off offset:1664
	global_load_dwordx4 v[140:143], v[156:157], off offset:1664
	global_load_dwordx4 v[148:151], v[172:173], off offset:1664
	global_load_dwordx4 v[152:155], v[178:179], off offset:1664
	s_waitcnt lgkmcnt(0)
	s_barrier
	ds_read_b128 v[166:169], v183
	ds_read_b128 v[210:213], v183 offset:32
	ds_read_b128 v[214:217], v183 offset:4608
	ds_read_b128 v[218:221], v183 offset:4640
	ds_read_b128 v[228:231], v183 offset:9216
	ds_read_b128 v[234:237], v183 offset:9248
	ds_read_b128 v[238:241], v183 offset:13824
	ds_read_b128 v[242:245], v183 offset:13856
	s_setprio 2
	s_mov_b32 s8, 0xd000
	v_add_co_u32_e32 v162, vcc, s8, v176
	s_mov_b32 s8, 0x1d000
	s_nop 0
	v_addc_co_u32_e32 v163, vcc, 0, v177, vcc
	v_add_co_u32_e32 v170, vcc, s8, v176
	s_waitcnt vmcnt(11) lgkmcnt(7)
	v_mfma_f32_32x32x16_bf16 v[112:127], v[158:161], v[166:169], v[112:127]
	v_addc_co_u32_e32 v171, vcc, 0, v177, vcc
	s_waitcnt lgkmcnt(5)
	v_mfma_f32_32x32x16_bf16 v[80:95], v[158:161], v[214:217], v[80:95]
	s_waitcnt lgkmcnt(3)
	v_mfma_f32_32x32x16_bf16 v[48:63], v[158:161], v[228:231], v[48:63]
	s_waitcnt lgkmcnt(1)
	v_mfma_f32_32x32x16_bf16 v[16:31], v[158:161], v[238:241], v[16:31]
	s_waitcnt vmcnt(10)
	v_mfma_f32_32x32x16_bf16 v[96:111], v[202:205], v[166:169], v[96:111]
	global_load_dwordx4 v[158:161], v[162:163], off
	global_load_dwordx4 v[166:169], v[170:171], off
	v_mfma_f32_32x32x16_bf16 v[64:79], v[202:205], v[214:217], v[64:79]
	v_mfma_f32_32x32x16_bf16 v[32:47], v[202:205], v[228:231], v[32:47]
	v_mfma_f32_32x32x16_bf16 v[0:15], v[202:205], v[238:241], v[0:15]
	s_setprio 0
	ds_read_b128 v[202:205], v183 offset:64
	ds_read_b128 v[214:217], v183 offset:4672
	ds_read_b128 v[228:231], v183 offset:9280
	ds_read_b128 v[238:241], v183 offset:13888
	s_setprio 2
	s_waitcnt vmcnt(11)
	v_mfma_f32_32x32x16_bf16 v[112:127], v[144:147], v[210:213], v[112:127]
	v_mfma_f32_32x32x16_bf16 v[80:95], v[144:147], v[218:221], v[80:95]
	v_mfma_f32_32x32x16_bf16 v[48:63], v[144:147], v[234:237], v[48:63]
	s_waitcnt lgkmcnt(4)
	v_mfma_f32_32x32x16_bf16 v[16:31], v[144:147], v[242:245], v[16:31]
	s_waitcnt vmcnt(10)
	v_mfma_f32_32x32x16_bf16 v[96:111], v[206:209], v[210:213], v[96:111]
	global_load_dwordx4 v[144:147], v[162:163], off offset:1024
	global_load_dwordx4 v[210:213], v[170:171], off offset:1024
	v_mfma_f32_32x32x16_bf16 v[64:79], v[206:209], v[218:221], v[64:79]
	v_mfma_f32_32x32x16_bf16 v[32:47], v[206:209], v[234:237], v[32:47]
	v_mfma_f32_32x32x16_bf16 v[0:15], v[206:209], v[242:245], v[0:15]
	s_setprio 0
	ds_read_b128 v[206:209], v183 offset:96
	ds_read_b128 v[218:221], v183 offset:4704
	ds_read_b128 v[234:237], v183 offset:9312
	ds_read_b128 v[242:245], v183 offset:13920
	s_setprio 2
	s_waitcnt vmcnt(11) lgkmcnt(7)
	v_mfma_f32_32x32x16_bf16 v[112:127], v[132:135], v[202:205], v[112:127]
	s_waitcnt lgkmcnt(6)
	v_mfma_f32_32x32x16_bf16 v[80:95], v[132:135], v[214:217], v[80:95]
	s_waitcnt lgkmcnt(5)
	v_mfma_f32_32x32x16_bf16 v[48:63], v[132:135], v[228:231], v[48:63]
	s_waitcnt lgkmcnt(4)
	v_mfma_f32_32x32x16_bf16 v[16:31], v[132:135], v[238:241], v[16:31]
	s_waitcnt vmcnt(10)
	v_mfma_f32_32x32x16_bf16 v[96:111], v[188:191], v[202:205], v[96:111]
	global_load_dwordx4 v[132:135], v[162:163], off offset:2048
	global_load_dwordx4 v[202:205], v[170:171], off offset:2048
	v_mfma_f32_32x32x16_bf16 v[64:79], v[188:191], v[214:217], v[64:79]
	v_mfma_f32_32x32x16_bf16 v[32:47], v[188:191], v[228:231], v[32:47]
	v_mfma_f32_32x32x16_bf16 v[0:15], v[188:191], v[238:241], v[0:15]
	s_setprio 0
	s_setprio 2
	s_waitcnt vmcnt(11) lgkmcnt(3)
	v_mfma_f32_32x32x16_bf16 v[112:127], v[128:131], v[206:209], v[112:127]
	s_waitcnt lgkmcnt(2)
	v_mfma_f32_32x32x16_bf16 v[80:95], v[128:131], v[218:221], v[80:95]
	s_waitcnt lgkmcnt(1)
	v_mfma_f32_32x32x16_bf16 v[48:63], v[128:131], v[234:237], v[48:63]
	s_waitcnt lgkmcnt(0)
	v_mfma_f32_32x32x16_bf16 v[16:31], v[128:131], v[242:245], v[16:31]
	global_load_dwordx4 v[128:131], v[162:163], off offset:3072
	global_load_dwordx4 v[188:191], v[170:171], off offset:3072
	s_waitcnt vmcnt(12)
	v_mfma_f32_32x32x16_bf16 v[96:111], v[198:201], v[206:209], v[96:111]
	v_mfma_f32_32x32x16_bf16 v[64:79], v[198:201], v[218:221], v[64:79]
	v_mfma_f32_32x32x16_bf16 v[32:47], v[198:201], v[234:237], v[32:47]
	v_mfma_f32_32x32x16_bf16 v[0:15], v[198:201], v[242:245], v[0:15]
	s_setprio 0
	s_waitcnt vmcnt(8)
	ds_write_b128 v184, v[152:155] offset:18432
	ds_write_b128 v184, v[140:143] offset:23040
	ds_write_b128 v184, v[136:139] offset:27648
	ds_write_b128 v184, v[148:151] offset:32256
	global_load_dwordx4 v[136:139], v[156:157], off offset:1792
	global_load_dwordx4 v[140:143], v[164:165], off offset:1792
	global_load_dwordx4 v[148:151], v[178:179], off offset:1792
	global_load_dwordx4 v[152:155], v[172:173], off offset:1792
	s_waitcnt lgkmcnt(0)
	s_barrier
	ds_read_b128 v[198:201], v183 offset:18432
	ds_read_b128 v[206:209], v183 offset:18464
	ds_read_b128 v[214:217], v183 offset:23040
	ds_read_b128 v[218:221], v183 offset:23072
	ds_read_b128 v[228:231], v183 offset:27648
	ds_read_b128 v[234:237], v183 offset:27680
	ds_read_b128 v[238:241], v183 offset:32256
	ds_read_b128 v[242:245], v183 offset:32288
	s_setprio 2
	s_mov_b32 s8, 0xe000
	s_waitcnt vmcnt(11) lgkmcnt(7)
	v_mfma_f32_32x32x16_bf16 v[112:127], v[158:161], v[198:201], v[112:127]
	s_waitcnt lgkmcnt(5)
	v_mfma_f32_32x32x16_bf16 v[80:95], v[158:161], v[214:217], v[80:95]
	s_waitcnt lgkmcnt(3)
	v_mfma_f32_32x32x16_bf16 v[48:63], v[158:161], v[228:231], v[48:63]
	s_waitcnt lgkmcnt(1)
	v_mfma_f32_32x32x16_bf16 v[16:31], v[158:161], v[238:241], v[16:31]
	v_add_co_u32_e32 v158, vcc, s8, v176
	s_mov_b32 s8, 0x1e000
	s_nop 0
	v_addc_co_u32_e32 v159, vcc, 0, v177, vcc
	v_add_co_u32_e32 v170, vcc, s8, v176
	s_waitcnt vmcnt(10)
	v_mfma_f32_32x32x16_bf16 v[96:111], v[166:169], v[198:201], v[96:111]
	s_nop 0
	v_addc_co_u32_e32 v171, vcc, 0, v177, vcc
	global_load_dwordx4 v[160:163], v[158:159], off
	global_load_dwordx4 v[198:201], v[170:171], off
	v_mfma_f32_32x32x16_bf16 v[64:79], v[166:169], v[214:217], v[64:79]
	v_mfma_f32_32x32x16_bf16 v[32:47], v[166:169], v[228:231], v[32:47]
	v_mfma_f32_32x32x16_bf16 v[0:15], v[166:169], v[238:241], v[0:15]
	s_setprio 0
	ds_read_b128 v[166:169], v183 offset:18496
	ds_read_b128 v[214:217], v183 offset:23104
	ds_read_b128 v[228:231], v183 offset:27712
	ds_read_b128 v[238:241], v183 offset:32320
	s_setprio 2
	s_waitcnt vmcnt(11)
	v_mfma_f32_32x32x16_bf16 v[112:127], v[144:147], v[206:209], v[112:127]
	v_mfma_f32_32x32x16_bf16 v[80:95], v[144:147], v[218:221], v[80:95]
	v_mfma_f32_32x32x16_bf16 v[48:63], v[144:147], v[234:237], v[48:63]
	s_waitcnt lgkmcnt(4)
	v_mfma_f32_32x32x16_bf16 v[16:31], v[144:147], v[242:245], v[16:31]
	s_waitcnt vmcnt(10)
	v_mfma_f32_32x32x16_bf16 v[96:111], v[210:213], v[206:209], v[96:111]
	global_load_dwordx4 v[144:147], v[158:159], off offset:1024
	global_load_dwordx4 v[206:209], v[170:171], off offset:1024
	v_mfma_f32_32x32x16_bf16 v[64:79], v[210:213], v[218:221], v[64:79]
	v_mfma_f32_32x32x16_bf16 v[32:47], v[210:213], v[234:237], v[32:47]
	v_mfma_f32_32x32x16_bf16 v[0:15], v[210:213], v[242:245], v[0:15]
	s_setprio 0
	ds_read_b128 v[210:213], v183 offset:18528
	ds_read_b128 v[218:221], v183 offset:23136
	ds_read_b128 v[234:237], v183 offset:27744
	ds_read_b128 v[242:245], v183 offset:32352
	s_setprio 2
	s_waitcnt vmcnt(11) lgkmcnt(7)
	v_mfma_f32_32x32x16_bf16 v[112:127], v[132:135], v[166:169], v[112:127]
	s_waitcnt lgkmcnt(6)
	v_mfma_f32_32x32x16_bf16 v[80:95], v[132:135], v[214:217], v[80:95]
	s_waitcnt lgkmcnt(5)
	v_mfma_f32_32x32x16_bf16 v[48:63], v[132:135], v[228:231], v[48:63]
	s_waitcnt lgkmcnt(4)
	v_mfma_f32_32x32x16_bf16 v[16:31], v[132:135], v[238:241], v[16:31]
	s_waitcnt vmcnt(10)
	v_mfma_f32_32x32x16_bf16 v[64:79], v[202:205], v[214:217], v[64:79]
	global_load_dwordx4 v[132:135], v[158:159], off offset:2048
	global_load_dwordx4 v[214:217], v[170:171], off offset:2048
	v_mfma_f32_32x32x16_bf16 v[96:111], v[202:205], v[166:169], v[96:111]
	v_mfma_f32_32x32x16_bf16 v[32:47], v[202:205], v[228:231], v[32:47]
	v_mfma_f32_32x32x16_bf16 v[0:15], v[202:205], v[238:241], v[0:15]
	s_setprio 0
	s_setprio 2
	s_waitcnt vmcnt(11) lgkmcnt(3)
	v_mfma_f32_32x32x16_bf16 v[112:127], v[128:131], v[210:213], v[112:127]
	s_waitcnt lgkmcnt(2)
	v_mfma_f32_32x32x16_bf16 v[80:95], v[128:131], v[218:221], v[80:95]
	s_waitcnt lgkmcnt(1)
	v_mfma_f32_32x32x16_bf16 v[48:63], v[128:131], v[234:237], v[48:63]
	s_waitcnt lgkmcnt(0)
	v_mfma_f32_32x32x16_bf16 v[16:31], v[128:131], v[242:245], v[16:31]
	global_load_dwordx4 v[128:131], v[158:159], off offset:3072
	global_load_dwordx4 v[202:205], v[170:171], off offset:3072
	s_waitcnt vmcnt(12)
	v_mfma_f32_32x32x16_bf16 v[96:111], v[188:191], v[210:213], v[96:111]
	v_mfma_f32_32x32x16_bf16 v[64:79], v[188:191], v[218:221], v[64:79]
	v_mfma_f32_32x32x16_bf16 v[32:47], v[188:191], v[234:237], v[32:47]
	v_mfma_f32_32x32x16_bf16 v[0:15], v[188:191], v[242:245], v[0:15]
	s_setprio 0
	s_waitcnt vmcnt(9)
	ds_write_b128 v184, v[148:151]
	ds_write_b128 v184, v[136:139] offset:4608
	ds_write_b128 v184, v[140:143] offset:9216
	s_waitcnt vmcnt(8)
	ds_write_b128 v184, v[152:155] offset:13824
	global_load_dwordx4 v[156:159], v[156:157], off offset:1920
	s_nop 0
	global_load_dwordx4 v[164:167], v[164:165], off offset:1920
	s_nop 0
	global_load_dwordx4 v[168:171], v[178:179], off offset:1920
	s_nop 0
	global_load_dwordx4 v[172:175], v[172:173], off offset:1920
	s_waitcnt lgkmcnt(0)
	s_barrier
	ds_read_b128 v[136:139], v183
	ds_read_b128 v[140:143], v183 offset:32
	ds_read_b128 v[148:151], v183 offset:4608
	ds_read_b128 v[188:191], v183 offset:4640
	ds_read_b128 v[152:155], v183 offset:9216
	ds_read_b128 v[210:213], v183 offset:9248
	ds_read_b128 v[218:221], v183 offset:13824
	ds_read_b128 v[228:231], v183 offset:13856
	s_setprio 2
	s_mov_b32 s8, 0xf000
	v_add_co_u32_e32 v234, vcc, s8, v176
	s_mov_b32 s8, 0x1f000
	s_nop 0
	v_addc_co_u32_e32 v235, vcc, 0, v177, vcc
	v_add_co_u32_e32 v236, vcc, s8, v176
	s_waitcnt vmcnt(11) lgkmcnt(7)
	v_mfma_f32_32x32x16_bf16 v[112:127], v[160:163], v[136:139], v[112:127]
	v_addc_co_u32_e32 v237, vcc, 0, v177, vcc
	s_waitcnt lgkmcnt(5)
	v_mfma_f32_32x32x16_bf16 v[80:95], v[160:163], v[148:151], v[80:95]
	s_waitcnt lgkmcnt(3)
	v_mfma_f32_32x32x16_bf16 v[48:63], v[160:163], v[152:155], v[48:63]
	s_waitcnt lgkmcnt(1)
	v_mfma_f32_32x32x16_bf16 v[16:31], v[160:163], v[218:221], v[16:31]
	s_waitcnt vmcnt(10)
	v_mfma_f32_32x32x16_bf16 v[32:47], v[198:201], v[152:155], v[32:47]
	global_load_dwordx4 v[160:163], v[234:235], off
	global_load_dwordx4 v[152:155], v[236:237], off
	v_mfma_f32_32x32x16_bf16 v[96:111], v[198:201], v[136:139], v[96:111]
	v_mfma_f32_32x32x16_bf16 v[64:79], v[198:201], v[148:151], v[64:79]
	v_mfma_f32_32x32x16_bf16 v[0:15], v[198:201], v[218:221], v[0:15]
	s_setprio 0
	ds_read_b128 v[136:139], v183 offset:64
	ds_read_b128 v[176:179], v183 offset:4672
	ds_read_b128 v[198:201], v183 offset:9280
	ds_read_b128 v[218:221], v183 offset:13888
	s_setprio 2
	s_waitcnt vmcnt(11)
	v_mfma_f32_32x32x16_bf16 v[112:127], v[144:147], v[140:143], v[112:127]
	v_mfma_f32_32x32x16_bf16 v[80:95], v[144:147], v[188:191], v[80:95]
	v_mfma_f32_32x32x16_bf16 v[48:63], v[144:147], v[210:213], v[48:63]
	s_waitcnt lgkmcnt(4)
	v_mfma_f32_32x32x16_bf16 v[16:31], v[144:147], v[228:231], v[16:31]
	global_load_dwordx4 v[144:147], v[234:235], off offset:1024
	global_load_dwordx4 v[148:151], v[236:237], off offset:1024
	s_waitcnt vmcnt(12)
	v_mfma_f32_32x32x16_bf16 v[96:111], v[206:209], v[140:143], v[96:111]
	v_mfma_f32_32x32x16_bf16 v[64:79], v[206:209], v[188:191], v[64:79]
	v_mfma_f32_32x32x16_bf16 v[32:47], v[206:209], v[210:213], v[32:47]
	v_mfma_f32_32x32x16_bf16 v[0:15], v[206:209], v[228:231], v[0:15]
	s_setprio 0
	ds_read_b128 v[188:191], v183 offset:96
	ds_read_b128 v[206:209], v183 offset:4704
	ds_read_b128 v[210:213], v183 offset:9312
	ds_read_b128 v[228:231], v183 offset:13920
	s_setprio 2
	s_waitcnt vmcnt(11) lgkmcnt(7)
	v_mfma_f32_32x32x16_bf16 v[112:127], v[132:135], v[136:139], v[112:127]
	s_waitcnt lgkmcnt(6)
	v_mfma_f32_32x32x16_bf16 v[80:95], v[132:135], v[176:179], v[80:95]
	s_waitcnt lgkmcnt(5)
	v_mfma_f32_32x32x16_bf16 v[48:63], v[132:135], v[198:201], v[48:63]
	s_waitcnt lgkmcnt(4)
	v_mfma_f32_32x32x16_bf16 v[16:31], v[132:135], v[218:221], v[16:31]
	global_load_dwordx4 v[132:135], v[234:235], off offset:2048
	global_load_dwordx4 v[140:143], v[236:237], off offset:2048
	s_waitcnt vmcnt(12)
	v_mfma_f32_32x32x16_bf16 v[96:111], v[214:217], v[136:139], v[96:111]
	v_mfma_f32_32x32x16_bf16 v[64:79], v[214:217], v[176:179], v[64:79]
	v_mfma_f32_32x32x16_bf16 v[32:47], v[214:217], v[198:201], v[32:47]
	v_mfma_f32_32x32x16_bf16 v[0:15], v[214:217], v[218:221], v[0:15]
	s_setprio 0
	s_setprio 2
	s_waitcnt vmcnt(11) lgkmcnt(3)
	v_mfma_f32_32x32x16_bf16 v[112:127], v[128:131], v[188:191], v[112:127]
	s_waitcnt lgkmcnt(2)
	v_mfma_f32_32x32x16_bf16 v[80:95], v[128:131], v[206:209], v[80:95]
	s_waitcnt lgkmcnt(1)
	v_mfma_f32_32x32x16_bf16 v[48:63], v[128:131], v[210:213], v[48:63]
	s_waitcnt lgkmcnt(0)
	v_mfma_f32_32x32x16_bf16 v[16:31], v[128:131], v[228:231], v[16:31]
	global_load_dwordx4 v[128:131], v[234:235], off offset:3072
	global_load_dwordx4 v[136:139], v[236:237], off offset:3072
	s_waitcnt vmcnt(12)
	v_mfma_f32_32x32x16_bf16 v[96:111], v[202:205], v[188:191], v[96:111]
	v_mfma_f32_32x32x16_bf16 v[64:79], v[202:205], v[206:209], v[64:79]
	v_mfma_f32_32x32x16_bf16 v[32:47], v[202:205], v[210:213], v[32:47]
	v_mfma_f32_32x32x16_bf16 v[0:15], v[202:205], v[228:231], v[0:15]
	s_setprio 0
	s_waitcnt vmcnt(9)
	ds_write_b128 v184, v[168:171] offset:18432
	ds_write_b128 v184, v[156:159] offset:23040
	ds_write_b128 v184, v[164:167] offset:27648
	s_waitcnt vmcnt(8)
	ds_write_b128 v184, v[172:175] offset:32256
	s_waitcnt lgkmcnt(0)
	s_barrier
	ds_read_b128 v[176:179], v183 offset:18432
	ds_read_b128 v[188:191], v183 offset:18464
	ds_read_b128 v[198:201], v183 offset:23040
	ds_read_b128 v[202:205], v183 offset:23072
	ds_read_b128 v[206:209], v183 offset:27648
	ds_read_b128 v[210:213], v183 offset:27680
	ds_read_b128 v[214:217], v183 offset:32256
	ds_read_b128 v[218:221], v183 offset:32288
	s_setprio 2
	s_waitcnt vmcnt(7) lgkmcnt(7)
	v_mfma_f32_32x32x16_bf16 v[112:127], v[160:163], v[176:179], v[112:127]
	s_waitcnt lgkmcnt(5)
	v_mfma_f32_32x32x16_bf16 v[80:95], v[160:163], v[198:201], v[80:95]
	s_waitcnt lgkmcnt(3)
	v_mfma_f32_32x32x16_bf16 v[48:63], v[160:163], v[206:209], v[48:63]
	s_waitcnt lgkmcnt(1)
	v_mfma_f32_32x32x16_bf16 v[16:31], v[160:163], v[214:217], v[16:31]
	s_waitcnt vmcnt(6)
	v_mfma_f32_32x32x16_bf16 v[96:111], v[152:155], v[176:179], v[96:111]
	v_mfma_f32_32x32x16_bf16 v[64:79], v[152:155], v[198:201], v[64:79]
	v_mfma_f32_32x32x16_bf16 v[32:47], v[152:155], v[206:209], v[32:47]
	v_mfma_f32_32x32x16_bf16 v[0:15], v[152:155], v[214:217], v[0:15]
	s_setprio 0
	ds_read_b128 v[176:179], v183 offset:18496
	ds_read_b128 v[198:201], v183 offset:23104
	ds_read_b128 v[206:209], v183 offset:27712
	ds_read_b128 v[214:217], v183 offset:32320
	s_setprio 2
	s_waitcnt vmcnt(5)
	v_mfma_f32_32x32x16_bf16 v[112:127], v[144:147], v[188:191], v[112:127]
	v_mfma_f32_32x32x16_bf16 v[80:95], v[144:147], v[202:205], v[80:95]
	v_mfma_f32_32x32x16_bf16 v[48:63], v[144:147], v[210:213], v[48:63]
	s_waitcnt lgkmcnt(4)
	v_mfma_f32_32x32x16_bf16 v[16:31], v[144:147], v[218:221], v[16:31]
	s_waitcnt vmcnt(4)
	v_mfma_f32_32x32x16_bf16 v[96:111], v[148:151], v[188:191], v[96:111]
	v_mfma_f32_32x32x16_bf16 v[64:79], v[148:151], v[202:205], v[64:79]
	v_mfma_f32_32x32x16_bf16 v[32:47], v[148:151], v[210:213], v[32:47]
	v_mfma_f32_32x32x16_bf16 v[0:15], v[148:151], v[218:221], v[0:15]
	s_setprio 0
	ds_read_b128 v[188:191], v183 offset:18528
	ds_read_b128 v[202:205], v183 offset:23136
	ds_read_b128 v[210:213], v183 offset:27744
	ds_read_b128 v[218:221], v183 offset:32352
	s_setprio 2
	s_waitcnt vmcnt(3) lgkmcnt(7)
	v_mfma_f32_32x32x16_bf16 v[112:127], v[132:135], v[176:179], v[112:127]
	s_waitcnt lgkmcnt(6)
	v_mfma_f32_32x32x16_bf16 v[80:95], v[132:135], v[198:201], v[80:95]
	s_waitcnt lgkmcnt(5)
	v_mfma_f32_32x32x16_bf16 v[48:63], v[132:135], v[206:209], v[48:63]
	s_waitcnt lgkmcnt(4)
	v_mfma_f32_32x32x16_bf16 v[16:31], v[132:135], v[214:217], v[16:31]
	s_waitcnt vmcnt(2)
	v_mfma_f32_32x32x16_bf16 v[96:111], v[140:143], v[176:179], v[96:111]
	v_mfma_f32_32x32x16_bf16 v[64:79], v[140:143], v[198:201], v[64:79]
	v_mfma_f32_32x32x16_bf16 v[32:47], v[140:143], v[206:209], v[32:47]
	v_mfma_f32_32x32x16_bf16 v[0:15], v[140:143], v[214:217], v[0:15]
	s_setprio 0
	s_setprio 2
	s_waitcnt vmcnt(1) lgkmcnt(3)
	v_mfma_f32_32x32x16_bf16 v[112:127], v[128:131], v[188:191], v[112:127]
	s_waitcnt lgkmcnt(2)
	v_mfma_f32_32x32x16_bf16 v[80:95], v[128:131], v[202:205], v[80:95]
	s_waitcnt lgkmcnt(1)
	v_mfma_f32_32x32x16_bf16 v[48:63], v[128:131], v[210:213], v[48:63]
	s_waitcnt lgkmcnt(0)
	v_mfma_f32_32x32x16_bf16 v[16:31], v[128:131], v[218:221], v[16:31]
	s_waitcnt vmcnt(0)
	v_mfma_f32_32x32x16_bf16 v[96:111], v[136:139], v[188:191], v[96:111]
	v_mfma_f32_32x32x16_bf16 v[64:79], v[136:139], v[202:205], v[64:79]
	v_mfma_f32_32x32x16_bf16 v[32:47], v[136:139], v[210:213], v[32:47]
	v_mfma_f32_32x32x16_bf16 v[0:15], v[136:139], v[218:221], v[0:15]
	s_setprio 0
	v_and_b32_e32 v176, 0xffffffc0, v181
	v_lshl_add_u32 v176, s1, 8, v176
	s_movk_i32 s1, 0xe80
	v_cmp_gt_i32_e32 vcc, s1, v176
	s_barrier
	s_and_saveexec_b64 s[20:21], vcc
	s_cbranch_execz .LBB0_294
	v_subrev_u32_e32 v177, s0, v182
	v_add_u32_e32 v178, s11, v177
	v_ashrrev_i32_e32 v179, 31, v178
	v_lshl_add_u64 v[182:183], v[178:179], 2, s[14:15]
	global_load_dword v184, v[182:183], off
	s_movk_i32 s0, 0x1ff
	v_cmp_lt_i32_e32 vcc, s0, v176
	v_add_u32_e32 v177, 0xfffff980, v176
	s_movk_i32 s0, 0x13f
	v_cmp_lt_u32_e64 s[0:1], s0, v177
	v_and_b32_e32 v177, 0xffffff40, v176
	s_movk_i32 s8, 0x800
	v_cmp_ne_u32_e64 s[8:9], s8, v177
	s_and_b64 s[0:1], s[0:1], s[8:9]
	s_and_b64 s[0:1], vcc, s[0:1]
	v_cmp_gt_u32_e32 vcc, 32, v180
	v_mov_b64_e32 v[180:181], s[16:17]
	s_movk_i32 s8, 0x1d00
	v_ashrrev_i32_e32 v177, 31, v176
	v_cndmask_b32_e64 v179, 8, 0, vcc
	v_mad_i64_i32 v[180:181], s[8:9], v178, s8, v[180:181]
	v_lshl_add_u64 v[182:183], v[176:177], 1, v[180:181]
	v_lshlrev_b32_e32 v192, 1, v179
	s_and_saveexec_b64 s[8:9], s[0:1]
	s_xor_b64 s[8:9], exec, s[8:9]
	s_cbranch_execz .LBB0_300
	s_waitcnt vmcnt(0) lgkmcnt(0)
	v_pk_mul_f32 v[112:113], v[112:113], v[184:185] op_sel_hi:[1,0]
	v_pk_mul_f32 v[114:115], v[114:115], v[184:185] op_sel_hi:[1,0]
	v_pk_mul_f32 v[116:117], v[116:117], v[184:185] op_sel_hi:[1,0]
	v_pk_mul_f32 v[118:119], v[118:119], v[184:185] op_sel_hi:[1,0]
	v_pk_mul_f32 v[96:97], v[96:97], v[184:185] op_sel_hi:[1,0]
	v_pk_mul_f32 v[98:99], v[98:99], v[184:185] op_sel_hi:[1,0]
	v_pk_mul_f32 v[100:101], v[100:101], v[184:185] op_sel_hi:[1,0]
	v_pk_mul_f32 v[102:103], v[102:103], v[184:185] op_sel_hi:[1,0]
	v_cvt_pk_bf16_f32 v112, v112, v113
	v_cvt_pk_bf16_f32 v113, v114, v115
	v_cvt_pk_bf16_f32 v114, v116, v117
	v_cvt_pk_bf16_f32 v115, v118, v119
	v_cvt_pk_bf16_f32 v96, v96, v97
	v_cvt_pk_bf16_f32 v97, v98, v99
	v_cvt_pk_bf16_f32 v98, v100, v101
	v_cvt_pk_bf16_f32 v99, v102, v103
	v_lshl_add_u64 v[180:181], v[182:183], 0, v[192:193]
	v_permlane32_swap_b32_e32 v112, v114
	v_permlane32_swap_b32_e32 v113, v115
	v_permlane32_swap_b32_e32 v96, v98
	v_permlane32_swap_b32_e32 v97, v99
	global_store_dwordx4 v[180:181], v[112:115], off
	v_pk_mul_f32 v[116:117], v[124:125], v[184:185] op_sel_hi:[1,0]
	v_pk_mul_f32 v[118:119], v[126:127], v[184:185] op_sel_hi:[1,0]
	v_pk_mul_f32 v[112:113], v[120:121], v[184:185] op_sel_hi:[1,0]
	v_pk_mul_f32 v[114:115], v[122:123], v[184:185] op_sel_hi:[1,0]
	global_store_dwordx4 v[180:181], v[96:99], off offset:64
	v_pk_mul_f32 v[100:101], v[108:109], v[184:185] op_sel_hi:[1,0]
	v_pk_mul_f32 v[102:103], v[110:111], v[184:185] op_sel_hi:[1,0]
	v_pk_mul_f32 v[96:97], v[104:105], v[184:185] op_sel_hi:[1,0]
	v_pk_mul_f32 v[98:99], v[106:107], v[184:185] op_sel_hi:[1,0]
	v_cvt_pk_bf16_f32 v112, v112, v113
	v_cvt_pk_bf16_f32 v113, v114, v115
	v_cvt_pk_bf16_f32 v114, v116, v117
	v_cvt_pk_bf16_f32 v115, v118, v119
	v_cvt_pk_bf16_f32 v96, v96, v97
	v_cvt_pk_bf16_f32 v97, v98, v99
	v_cvt_pk_bf16_f32 v98, v100, v101
	v_cvt_pk_bf16_f32 v99, v102, v103
	v_permlane32_swap_b32_e32 v112, v114
	v_permlane32_swap_b32_e32 v113, v115
	v_permlane32_swap_b32_e32 v96, v98
	v_permlane32_swap_b32_e32 v97, v99
	global_store_dwordx4 v[180:181], v[112:115], off offset:32
	global_store_dwordx4 v[180:181], v[96:99], off offset:96
.LBB0_300:
	s_or_saveexec_b64 s[8:9], s[8:9]
	v_lshlrev_b32_e32 v179, 2, v186
	v_lshlrev_b32_e32 v180, 2, v179
	s_xor_b64 exec, exec, s[8:9]
	s_cbranch_execz .LBB0_302
	v_lshlrev_b32_e32 v186, 5, v178
	v_ashrrev_i32_e32 v187, 31, v186
	v_lshl_add_u64 v[186:187], v[186:187], 2, s[18:19]
	v_mov_b32_e32 v181, v193
	v_lshl_add_u64 v[186:187], v[186:187], 0, v[180:181]
	global_load_dwordx4 v[188:191], v[186:187], off
	s_waitcnt vmcnt(1) lgkmcnt(0)
	v_pk_mul_f32 v[96:97], v[96:97], v[184:185] op_sel_hi:[1,0]
	v_pk_mul_f32 v[200:201], v[112:113], v[184:185] op_sel_hi:[1,0]
	v_pk_mul_f32 v[98:99], v[98:99], v[184:185] op_sel_hi:[1,0]
	v_pk_mul_f32 v[100:101], v[100:101], v[184:185] op_sel_hi:[1,0]
	v_pk_mul_f32 v[116:117], v[116:117], v[184:185] op_sel_hi:[1,0]
	v_pk_mul_f32 v[102:103], v[102:103], v[184:185] op_sel_hi:[1,0]
	v_pk_mul_f32 v[118:119], v[118:119], v[184:185] op_sel_hi:[1,0]
	v_lshl_add_u64 v[182:183], v[182:183], 0, v[192:193]
	v_pk_mul_f32 v[104:105], v[104:105], v[184:185] op_sel_hi:[1,0]
	v_pk_mul_f32 v[106:107], v[106:107], v[184:185] op_sel_hi:[1,0]
	v_pk_mul_f32 v[108:109], v[108:109], v[184:185] op_sel_hi:[1,0]
	v_pk_mul_f32 v[110:111], v[110:111], v[184:185] op_sel_hi:[1,0]
	s_waitcnt vmcnt(0)
	v_lshlrev_b32_e32 v199, 16, v189
	v_lshlrev_b32_e32 v198, 16, v188
	v_and_b32_e32 v189, 0xffff0000, v189
	v_and_b32_e32 v188, 0xffff0000, v188
	v_pk_mul_f32 v[112:113], v[96:97], v[188:189]
	v_pk_mul_f32 v[96:97], v[96:97], v[198:199]
	v_pk_fma_f32 v[112:113], v[200:201], v[198:199], v[112:113] neg_lo:[0,0,1] neg_hi:[0,0,1]
	v_pk_fma_f32 v[96:97], v[200:201], v[188:189], v[96:97]
	v_lshlrev_b32_e32 v189, 16, v191
	v_lshlrev_b32_e32 v188, 16, v190
	v_and_b32_e32 v191, 0xffff0000, v191
	v_and_b32_e32 v190, 0xffff0000, v190
	v_pk_mul_f32 v[198:199], v[114:115], v[184:185] op_sel_hi:[1,0]
	v_pk_mul_f32 v[114:115], v[98:99], v[190:191]
	v_pk_mul_f32 v[98:99], v[98:99], v[188:189]
	v_pk_fma_f32 v[114:115], v[198:199], v[188:189], v[114:115] neg_lo:[0,0,1] neg_hi:[0,0,1]
	v_pk_fma_f32 v[98:99], v[198:199], v[190:191], v[98:99]
	global_load_dwordx4 v[188:191], v[186:187], off offset:32
	v_cvt_pk_bf16_f32 v96, v96, v97
	v_cvt_pk_bf16_f32 v97, v98, v99
	s_waitcnt vmcnt(0)
	v_lshlrev_b32_e32 v199, 16, v189
	v_lshlrev_b32_e32 v198, 16, v188
	v_and_b32_e32 v189, 0xffff0000, v189
	v_and_b32_e32 v188, 0xffff0000, v188
	v_pk_mul_f32 v[200:201], v[100:101], v[188:189]
	v_pk_mul_f32 v[100:101], v[100:101], v[198:199]
	v_pk_fma_f32 v[200:201], v[116:117], v[198:199], v[200:201] neg_lo:[0,0,1] neg_hi:[0,0,1]
	v_pk_fma_f32 v[116:117], v[116:117], v[188:189], v[100:101]
	v_and_b32_e32 v189, 0xffff0000, v191
	v_and_b32_e32 v188, 0xffff0000, v190
	v_lshlrev_b32_e32 v101, 16, v191
	v_lshlrev_b32_e32 v100, 16, v190
	v_pk_mul_f32 v[190:191], v[102:103], v[188:189]
	v_cvt_pk_bf16_f32 v98, v116, v117
	v_pk_fma_f32 v[190:191], v[118:119], v[100:101], v[190:191] neg_lo:[0,0,1] neg_hi:[0,0,1]
	v_pk_mul_f32 v[100:101], v[102:103], v[100:101]
	v_cvt_pk_bf16_f32 v102, v200, v201
	v_pk_fma_f32 v[118:119], v[118:119], v[188:189], v[100:101]
	v_cvt_pk_bf16_f32 v100, v112, v113
	v_cvt_pk_bf16_f32 v101, v114, v115
	v_cvt_pk_bf16_f32 v103, v190, v191
	v_cvt_pk_bf16_f32 v99, v118, v119
	v_permlane32_swap_b32_e32 v100, v102
	v_permlane32_swap_b32_e32 v101, v103
	v_permlane32_swap_b32_e32 v96, v98
	v_permlane32_swap_b32_e32 v97, v99
	global_store_dwordx4 v[182:183], v[100:103], off
	global_store_dwordx4 v[182:183], v[96:99], off offset:64
	global_load_dwordx4 v[96:99], v[186:187], off offset:64
	v_pk_mul_f32 v[112:113], v[120:121], v[184:185] op_sel_hi:[1,0]
	v_pk_mul_f32 v[114:115], v[124:125], v[184:185] op_sel_hi:[1,0]
	s_waitcnt vmcnt(0)
	v_lshlrev_b32_e32 v103, 16, v97
	v_lshlrev_b32_e32 v102, 16, v96
	v_and_b32_e32 v97, 0xffff0000, v97
	v_and_b32_e32 v96, 0xffff0000, v96
	v_pk_mul_f32 v[100:101], v[104:105], v[96:97]
	s_nop 0
	v_pk_fma_f32 v[100:101], v[112:113], v[102:103], v[100:101] neg_lo:[0,0,1] neg_hi:[0,0,1]
	v_pk_mul_f32 v[102:103], v[104:105], v[102:103]
	v_lshlrev_b32_e32 v105, 16, v99
	v_lshlrev_b32_e32 v104, 16, v98
	v_and_b32_e32 v99, 0xffff0000, v99
	v_and_b32_e32 v98, 0xffff0000, v98
	v_pk_fma_f32 v[96:97], v[112:113], v[96:97], v[102:103]
	v_pk_mul_f32 v[112:113], v[122:123], v[184:185] op_sel_hi:[1,0]
	v_pk_mul_f32 v[102:103], v[106:107], v[98:99]
	v_cvt_pk_bf16_f32 v100, v100, v101
	v_pk_fma_f32 v[102:103], v[112:113], v[104:105], v[102:103] neg_lo:[0,0,1] neg_hi:[0,0,1]
	v_pk_mul_f32 v[104:105], v[106:107], v[104:105]
	v_cvt_pk_bf16_f32 v101, v102, v103
	v_pk_fma_f32 v[98:99], v[112:113], v[98:99], v[104:105]
	global_load_dwordx4 v[104:107], v[186:187], off offset:96
	v_cvt_pk_bf16_f32 v96, v96, v97
	v_cvt_pk_bf16_f32 v97, v98, v99
	s_waitcnt vmcnt(0)
	v_lshlrev_b32_e32 v113, 16, v105
	v_lshlrev_b32_e32 v112, 16, v104
	v_and_b32_e32 v105, 0xffff0000, v105
	v_and_b32_e32 v104, 0xffff0000, v104
	v_pk_mul_f32 v[116:117], v[108:109], v[104:105]
	v_pk_mul_f32 v[108:109], v[108:109], v[112:113]
	v_pk_fma_f32 v[116:117], v[114:115], v[112:113], v[116:117] neg_lo:[0,0,1] neg_hi:[0,0,1]
	v_pk_fma_f32 v[104:105], v[114:115], v[104:105], v[108:109]
	v_lshlrev_b32_e32 v109, 16, v107
	v_lshlrev_b32_e32 v108, 16, v106
	v_and_b32_e32 v107, 0xffff0000, v107
	v_and_b32_e32 v106, 0xffff0000, v106
	v_pk_mul_f32 v[112:113], v[126:127], v[184:185] op_sel_hi:[1,0]
	v_pk_mul_f32 v[114:115], v[110:111], v[106:107]
	v_cvt_pk_bf16_f32 v102, v116, v117
	v_pk_fma_f32 v[114:115], v[112:113], v[108:109], v[114:115] neg_lo:[0,0,1] neg_hi:[0,0,1]
	v_pk_mul_f32 v[108:109], v[110:111], v[108:109]
	v_cvt_pk_bf16_f32 v103, v114, v115
	v_pk_fma_f32 v[106:107], v[112:113], v[106:107], v[108:109]
	v_cvt_pk_bf16_f32 v98, v104, v105
	v_cvt_pk_bf16_f32 v99, v106, v107
	v_permlane32_swap_b32_e32 v100, v102
	v_permlane32_swap_b32_e32 v101, v103
	v_permlane32_swap_b32_e32 v96, v98
	v_permlane32_swap_b32_e32 v97, v99
	global_store_dwordx4 v[182:183], v[100:103], off offset:32
	global_store_dwordx4 v[182:183], v[96:99], off offset:96
.LBB0_302:
	s_or_b64 exec, exec, s[8:9]
	s_nop 0
	v_add_u32_e32 v96, 32, v178
	v_ashrrev_i32_e32 v97, 31, v96
	v_lshl_add_u64 v[98:99], v[96:97], 2, s[14:15]
	global_load_dword v98, v[98:99], off
	v_mov_b64_e32 v[100:101], s[16:17]
	s_movk_i32 s8, 0x1d00
	v_mad_i64_i32 v[100:101], s[8:9], v96, s8, v[100:101]
	v_lshl_add_u64 v[100:101], v[176:177], 1, v[100:101]
	s_and_saveexec_b64 s[8:9], s[0:1]
	s_xor_b64 s[8:9], exec, s[8:9]
	s_cbranch_execz .LBB0_304
	s_waitcnt vmcnt(0) lgkmcnt(0)
	v_pk_mul_f32 v[80:81], v[80:81], v[98:99] op_sel_hi:[1,0]
	v_pk_mul_f32 v[82:83], v[82:83], v[98:99] op_sel_hi:[1,0]
	v_pk_mul_f32 v[84:85], v[84:85], v[98:99] op_sel_hi:[1,0]
	v_pk_mul_f32 v[86:87], v[86:87], v[98:99] op_sel_hi:[1,0]
	v_pk_mul_f32 v[64:65], v[64:65], v[98:99] op_sel_hi:[1,0]
	v_pk_mul_f32 v[66:67], v[66:67], v[98:99] op_sel_hi:[1,0]
	v_pk_mul_f32 v[68:69], v[68:69], v[98:99] op_sel_hi:[1,0]
	v_pk_mul_f32 v[70:71], v[70:71], v[98:99] op_sel_hi:[1,0]
	v_cvt_pk_bf16_f32 v80, v80, v81
	v_cvt_pk_bf16_f32 v81, v82, v83
	v_cvt_pk_bf16_f32 v82, v84, v85
	v_cvt_pk_bf16_f32 v83, v86, v87
	v_cvt_pk_bf16_f32 v64, v64, v65
	v_cvt_pk_bf16_f32 v65, v66, v67
	v_cvt_pk_bf16_f32 v66, v68, v69
	v_cvt_pk_bf16_f32 v67, v70, v71
	v_lshl_add_u64 v[96:97], v[100:101], 0, v[192:193]
	v_permlane32_swap_b32_e32 v80, v82
	v_permlane32_swap_b32_e32 v81, v83
	v_permlane32_swap_b32_e32 v64, v66
	v_permlane32_swap_b32_e32 v65, v67
	global_store_dwordx4 v[96:97], v[80:83], off
	v_pk_mul_f32 v[84:85], v[92:93], v[98:99] op_sel_hi:[1,0]
	v_pk_mul_f32 v[86:87], v[94:95], v[98:99] op_sel_hi:[1,0]
	v_pk_mul_f32 v[80:81], v[88:89], v[98:99] op_sel_hi:[1,0]
	v_pk_mul_f32 v[82:83], v[90:91], v[98:99] op_sel_hi:[1,0]
	global_store_dwordx4 v[96:97], v[64:67], off offset:64
	v_pk_mul_f32 v[68:69], v[76:77], v[98:99] op_sel_hi:[1,0]
	v_pk_mul_f32 v[70:71], v[78:79], v[98:99] op_sel_hi:[1,0]
	v_pk_mul_f32 v[64:65], v[72:73], v[98:99] op_sel_hi:[1,0]
	v_pk_mul_f32 v[66:67], v[74:75], v[98:99] op_sel_hi:[1,0]
	v_cvt_pk_bf16_f32 v80, v80, v81
	v_cvt_pk_bf16_f32 v81, v82, v83
	v_cvt_pk_bf16_f32 v82, v84, v85
	v_cvt_pk_bf16_f32 v83, v86, v87
	v_cvt_pk_bf16_f32 v64, v64, v65
	v_cvt_pk_bf16_f32 v65, v66, v67
	v_cvt_pk_bf16_f32 v66, v68, v69
	v_cvt_pk_bf16_f32 v67, v70, v71
	v_permlane32_swap_b32_e32 v80, v82
	v_permlane32_swap_b32_e32 v81, v83
	v_permlane32_swap_b32_e32 v64, v66
	v_permlane32_swap_b32_e32 v65, v67
	global_store_dwordx4 v[96:97], v[80:83], off offset:32
	global_store_dwordx4 v[96:97], v[64:67], off offset:96
.LBB0_304:
	s_andn2_saveexec_b64 s[8:9], s[8:9]
	s_cbranch_execz .LBB0_306
	v_lshlrev_b32_e32 v102, 5, v96
	v_ashrrev_i32_e32 v103, 31, v102
	v_lshl_add_u64 v[96:97], v[100:101], 0, v[192:193]
	v_lshl_add_u64 v[100:101], v[102:103], 2, s[18:19]
	v_mov_b32_e32 v181, v193
	v_lshl_add_u64 v[100:101], v[100:101], 0, v[180:181]
	global_load_dwordx4 v[102:105], v[100:101], off
	s_waitcnt vmcnt(1) lgkmcnt(0)
	v_pk_mul_f32 v[64:65], v[64:65], v[98:99] op_sel_hi:[1,0]
	v_pk_mul_f32 v[108:109], v[80:81], v[98:99] op_sel_hi:[1,0]
	v_pk_mul_f32 v[66:67], v[66:67], v[98:99] op_sel_hi:[1,0]
	v_pk_mul_f32 v[68:69], v[68:69], v[98:99] op_sel_hi:[1,0]
	v_pk_mul_f32 v[84:85], v[84:85], v[98:99] op_sel_hi:[1,0]
	v_pk_mul_f32 v[70:71], v[70:71], v[98:99] op_sel_hi:[1,0]
	v_pk_mul_f32 v[86:87], v[86:87], v[98:99] op_sel_hi:[1,0]
	v_pk_mul_f32 v[72:73], v[72:73], v[98:99] op_sel_hi:[1,0]
	v_pk_mul_f32 v[74:75], v[74:75], v[98:99] op_sel_hi:[1,0]
	v_pk_mul_f32 v[76:77], v[76:77], v[98:99] op_sel_hi:[1,0]
	v_pk_mul_f32 v[78:79], v[78:79], v[98:99] op_sel_hi:[1,0]
	s_waitcnt vmcnt(0)
	v_lshlrev_b32_e32 v107, 16, v103
	v_lshlrev_b32_e32 v106, 16, v102
	v_and_b32_e32 v103, 0xffff0000, v103
	v_and_b32_e32 v102, 0xffff0000, v102
	v_pk_mul_f32 v[80:81], v[64:65], v[102:103]
	v_pk_mul_f32 v[64:65], v[64:65], v[106:107]
	v_pk_fma_f32 v[80:81], v[108:109], v[106:107], v[80:81] neg_lo:[0,0,1] neg_hi:[0,0,1]
	v_pk_fma_f32 v[64:65], v[108:109], v[102:103], v[64:65]
	v_lshlrev_b32_e32 v103, 16, v105
	v_lshlrev_b32_e32 v102, 16, v104
	v_and_b32_e32 v105, 0xffff0000, v105
	v_and_b32_e32 v104, 0xffff0000, v104
	v_pk_mul_f32 v[106:107], v[82:83], v[98:99] op_sel_hi:[1,0]
	v_pk_mul_f32 v[82:83], v[66:67], v[104:105]
	v_pk_mul_f32 v[66:67], v[66:67], v[102:103]
	v_pk_fma_f32 v[82:83], v[106:107], v[102:103], v[82:83] neg_lo:[0,0,1] neg_hi:[0,0,1]
	v_pk_fma_f32 v[66:67], v[106:107], v[104:105], v[66:67]
	global_load_dwordx4 v[102:105], v[100:101], off offset:32
	v_cvt_pk_bf16_f32 v64, v64, v65
	v_cvt_pk_bf16_f32 v65, v66, v67
	s_waitcnt vmcnt(0)
	v_lshlrev_b32_e32 v107, 16, v103
	v_lshlrev_b32_e32 v106, 16, v102
	v_and_b32_e32 v103, 0xffff0000, v103
	v_and_b32_e32 v102, 0xffff0000, v102
	v_pk_mul_f32 v[108:109], v[68:69], v[102:103]
	v_pk_mul_f32 v[68:69], v[68:69], v[106:107]
	v_pk_fma_f32 v[108:109], v[84:85], v[106:107], v[108:109] neg_lo:[0,0,1] neg_hi:[0,0,1]
	v_pk_fma_f32 v[84:85], v[84:85], v[102:103], v[68:69]
	v_and_b32_e32 v103, 0xffff0000, v105
	v_and_b32_e32 v102, 0xffff0000, v104
	v_lshlrev_b32_e32 v69, 16, v105
	v_lshlrev_b32_e32 v68, 16, v104
	v_pk_mul_f32 v[104:105], v[70:71], v[102:103]
	v_cvt_pk_bf16_f32 v66, v84, v85
	v_pk_fma_f32 v[104:105], v[86:87], v[68:69], v[104:105] neg_lo:[0,0,1] neg_hi:[0,0,1]
	v_pk_mul_f32 v[68:69], v[70:71], v[68:69]
	v_cvt_pk_bf16_f32 v70, v108, v109
	v_pk_fma_f32 v[86:87], v[86:87], v[102:103], v[68:69]
	v_cvt_pk_bf16_f32 v68, v80, v81
	v_cvt_pk_bf16_f32 v69, v82, v83
	v_cvt_pk_bf16_f32 v71, v104, v105
	v_cvt_pk_bf16_f32 v67, v86, v87
	v_permlane32_swap_b32_e32 v68, v70
	v_permlane32_swap_b32_e32 v69, v71
	v_permlane32_swap_b32_e32 v64, v66
	v_permlane32_swap_b32_e32 v65, v67
	global_store_dwordx4 v[96:97], v[68:71], off
	global_store_dwordx4 v[96:97], v[64:67], off offset:64
	global_load_dwordx4 v[64:67], v[100:101], off offset:64
	v_pk_mul_f32 v[80:81], v[88:89], v[98:99] op_sel_hi:[1,0]
	v_pk_mul_f32 v[82:83], v[92:93], v[98:99] op_sel_hi:[1,0]
	s_waitcnt vmcnt(0)
	v_lshlrev_b32_e32 v71, 16, v65
	v_lshlrev_b32_e32 v70, 16, v64
	v_and_b32_e32 v65, 0xffff0000, v65
	v_and_b32_e32 v64, 0xffff0000, v64
	v_pk_mul_f32 v[68:69], v[72:73], v[64:65]
	s_nop 0
	v_pk_fma_f32 v[68:69], v[80:81], v[70:71], v[68:69] neg_lo:[0,0,1] neg_hi:[0,0,1]
	v_pk_mul_f32 v[70:71], v[72:73], v[70:71]
	v_lshlrev_b32_e32 v73, 16, v67
	v_lshlrev_b32_e32 v72, 16, v66
	v_and_b32_e32 v67, 0xffff0000, v67
	v_and_b32_e32 v66, 0xffff0000, v66
	v_pk_fma_f32 v[64:65], v[80:81], v[64:65], v[70:71]
	v_pk_mul_f32 v[80:81], v[90:91], v[98:99] op_sel_hi:[1,0]
	v_pk_mul_f32 v[70:71], v[74:75], v[66:67]
	v_cvt_pk_bf16_f32 v68, v68, v69
	v_pk_fma_f32 v[70:71], v[80:81], v[72:73], v[70:71] neg_lo:[0,0,1] neg_hi:[0,0,1]
	v_pk_mul_f32 v[72:73], v[74:75], v[72:73]
	v_cvt_pk_bf16_f32 v69, v70, v71
	v_pk_fma_f32 v[66:67], v[80:81], v[66:67], v[72:73]
	global_load_dwordx4 v[72:75], v[100:101], off offset:96
	v_cvt_pk_bf16_f32 v64, v64, v65
	v_cvt_pk_bf16_f32 v65, v66, v67
	s_waitcnt vmcnt(0)
	v_lshlrev_b32_e32 v81, 16, v73
	v_lshlrev_b32_e32 v80, 16, v72
	v_and_b32_e32 v73, 0xffff0000, v73
	v_and_b32_e32 v72, 0xffff0000, v72
	v_pk_mul_f32 v[84:85], v[76:77], v[72:73]
	v_pk_mul_f32 v[76:77], v[76:77], v[80:81]
	v_pk_fma_f32 v[84:85], v[82:83], v[80:81], v[84:85] neg_lo:[0,0,1] neg_hi:[0,0,1]
	v_pk_fma_f32 v[72:73], v[82:83], v[72:73], v[76:77]
	v_lshlrev_b32_e32 v77, 16, v75
	v_lshlrev_b32_e32 v76, 16, v74
	v_and_b32_e32 v75, 0xffff0000, v75
	v_and_b32_e32 v74, 0xffff0000, v74
	v_pk_mul_f32 v[80:81], v[94:95], v[98:99] op_sel_hi:[1,0]
	v_pk_mul_f32 v[82:83], v[78:79], v[74:75]
	v_cvt_pk_bf16_f32 v70, v84, v85
	v_pk_fma_f32 v[82:83], v[80:81], v[76:77], v[82:83] neg_lo:[0,0,1] neg_hi:[0,0,1]
	v_pk_mul_f32 v[76:77], v[78:79], v[76:77]
	v_cvt_pk_bf16_f32 v71, v82, v83
	v_pk_fma_f32 v[74:75], v[80:81], v[74:75], v[76:77]
	v_cvt_pk_bf16_f32 v66, v72, v73
	v_cvt_pk_bf16_f32 v67, v74, v75
	v_permlane32_swap_b32_e32 v68, v70
	v_permlane32_swap_b32_e32 v69, v71
	v_permlane32_swap_b32_e32 v64, v66
	v_permlane32_swap_b32_e32 v65, v67
	global_store_dwordx4 v[96:97], v[68:71], off offset:32
	global_store_dwordx4 v[96:97], v[64:67], off offset:96
.LBB0_306:
	s_or_b64 exec, exec, s[8:9]
	s_nop 0
	v_add_u32_e32 v64, 64, v178
	v_ashrrev_i32_e32 v65, 31, v64
	v_lshl_add_u64 v[66:67], v[64:65], 2, s[14:15]
	global_load_dword v66, v[66:67], off
	v_mov_b64_e32 v[68:69], s[16:17]
	s_movk_i32 s8, 0x1d00
	v_mad_i64_i32 v[68:69], s[8:9], v64, s8, v[68:69]
	v_lshl_add_u64 v[68:69], v[176:177], 1, v[68:69]
	s_and_saveexec_b64 s[8:9], s[0:1]
	s_xor_b64 s[8:9], exec, s[8:9]
	s_cbranch_execz .LBB0_308
	s_waitcnt vmcnt(0) lgkmcnt(0)
	v_pk_mul_f32 v[48:49], v[48:49], v[66:67] op_sel_hi:[1,0]
	v_pk_mul_f32 v[50:51], v[50:51], v[66:67] op_sel_hi:[1,0]
	v_pk_mul_f32 v[52:53], v[52:53], v[66:67] op_sel_hi:[1,0]
	v_pk_mul_f32 v[54:55], v[54:55], v[66:67] op_sel_hi:[1,0]
	v_pk_mul_f32 v[32:33], v[32:33], v[66:67] op_sel_hi:[1,0]
	v_pk_mul_f32 v[34:35], v[34:35], v[66:67] op_sel_hi:[1,0]
	v_pk_mul_f32 v[36:37], v[36:37], v[66:67] op_sel_hi:[1,0]
	v_pk_mul_f32 v[38:39], v[38:39], v[66:67] op_sel_hi:[1,0]
	v_cvt_pk_bf16_f32 v48, v48, v49
	v_cvt_pk_bf16_f32 v49, v50, v51
	v_cvt_pk_bf16_f32 v50, v52, v53
	v_cvt_pk_bf16_f32 v51, v54, v55
	v_cvt_pk_bf16_f32 v32, v32, v33
	v_cvt_pk_bf16_f32 v33, v34, v35
	v_cvt_pk_bf16_f32 v34, v36, v37
	v_cvt_pk_bf16_f32 v35, v38, v39
	v_lshl_add_u64 v[64:65], v[68:69], 0, v[192:193]
	v_permlane32_swap_b32_e32 v48, v50
	v_permlane32_swap_b32_e32 v49, v51
	v_permlane32_swap_b32_e32 v32, v34
	v_permlane32_swap_b32_e32 v33, v35
	global_store_dwordx4 v[64:65], v[48:51], off
	v_pk_mul_f32 v[52:53], v[60:61], v[66:67] op_sel_hi:[1,0]
	v_pk_mul_f32 v[54:55], v[62:63], v[66:67] op_sel_hi:[1,0]
	v_pk_mul_f32 v[48:49], v[56:57], v[66:67] op_sel_hi:[1,0]
	v_pk_mul_f32 v[50:51], v[58:59], v[66:67] op_sel_hi:[1,0]
	global_store_dwordx4 v[64:65], v[32:35], off offset:64
	v_pk_mul_f32 v[36:37], v[44:45], v[66:67] op_sel_hi:[1,0]
	v_pk_mul_f32 v[38:39], v[46:47], v[66:67] op_sel_hi:[1,0]
	v_pk_mul_f32 v[32:33], v[40:41], v[66:67] op_sel_hi:[1,0]
	v_pk_mul_f32 v[34:35], v[42:43], v[66:67] op_sel_hi:[1,0]
	v_cvt_pk_bf16_f32 v48, v48, v49
	v_cvt_pk_bf16_f32 v49, v50, v51
	v_cvt_pk_bf16_f32 v50, v52, v53
	v_cvt_pk_bf16_f32 v51, v54, v55
	v_cvt_pk_bf16_f32 v32, v32, v33
	v_cvt_pk_bf16_f32 v33, v34, v35
	v_cvt_pk_bf16_f32 v34, v36, v37
	v_cvt_pk_bf16_f32 v35, v38, v39
	v_permlane32_swap_b32_e32 v48, v50
	v_permlane32_swap_b32_e32 v49, v51
	v_permlane32_swap_b32_e32 v32, v34
	v_permlane32_swap_b32_e32 v33, v35
	global_store_dwordx4 v[64:65], v[48:51], off offset:32
	global_store_dwordx4 v[64:65], v[32:35], off offset:96
.LBB0_308:
	s_andn2_saveexec_b64 s[8:9], s[8:9]
	s_cbranch_execz .LBB0_310
	v_lshlrev_b32_e32 v70, 5, v64
	v_ashrrev_i32_e32 v71, 31, v70
	v_lshl_add_u64 v[64:65], v[68:69], 0, v[192:193]
	v_lshl_add_u64 v[68:69], v[70:71], 2, s[18:19]
	v_mov_b32_e32 v181, v193
	v_lshl_add_u64 v[68:69], v[68:69], 0, v[180:181]
	global_load_dwordx4 v[70:73], v[68:69], off
	s_waitcnt vmcnt(1) lgkmcnt(0)
	v_pk_mul_f32 v[32:33], v[32:33], v[66:67] op_sel_hi:[1,0]
	v_pk_mul_f32 v[76:77], v[48:49], v[66:67] op_sel_hi:[1,0]
	v_pk_mul_f32 v[34:35], v[34:35], v[66:67] op_sel_hi:[1,0]
	v_pk_mul_f32 v[36:37], v[36:37], v[66:67] op_sel_hi:[1,0]
	v_pk_mul_f32 v[52:53], v[52:53], v[66:67] op_sel_hi:[1,0]
	v_pk_mul_f32 v[38:39], v[38:39], v[66:67] op_sel_hi:[1,0]
	v_pk_mul_f32 v[54:55], v[54:55], v[66:67] op_sel_hi:[1,0]
	v_pk_mul_f32 v[40:41], v[40:41], v[66:67] op_sel_hi:[1,0]
	v_pk_mul_f32 v[42:43], v[42:43], v[66:67] op_sel_hi:[1,0]
	v_pk_mul_f32 v[44:45], v[44:45], v[66:67] op_sel_hi:[1,0]
	v_pk_mul_f32 v[46:47], v[46:47], v[66:67] op_sel_hi:[1,0]
	s_waitcnt vmcnt(0)
	v_lshlrev_b32_e32 v75, 16, v71
	v_lshlrev_b32_e32 v74, 16, v70
	v_and_b32_e32 v71, 0xffff0000, v71
	v_and_b32_e32 v70, 0xffff0000, v70
	v_pk_mul_f32 v[48:49], v[32:33], v[70:71]
	v_pk_mul_f32 v[32:33], v[32:33], v[74:75]
	v_pk_fma_f32 v[48:49], v[76:77], v[74:75], v[48:49] neg_lo:[0,0,1] neg_hi:[0,0,1]
	v_pk_fma_f32 v[32:33], v[76:77], v[70:71], v[32:33]
	v_lshlrev_b32_e32 v71, 16, v73
	v_lshlrev_b32_e32 v70, 16, v72
	v_and_b32_e32 v73, 0xffff0000, v73
	v_and_b32_e32 v72, 0xffff0000, v72
	v_pk_mul_f32 v[74:75], v[50:51], v[66:67] op_sel_hi:[1,0]
	v_pk_mul_f32 v[50:51], v[34:35], v[72:73]
	v_pk_mul_f32 v[34:35], v[34:35], v[70:71]
	v_pk_fma_f32 v[50:51], v[74:75], v[70:71], v[50:51] neg_lo:[0,0,1] neg_hi:[0,0,1]
	v_pk_fma_f32 v[34:35], v[74:75], v[72:73], v[34:35]
	global_load_dwordx4 v[70:73], v[68:69], off offset:32
	v_cvt_pk_bf16_f32 v32, v32, v33
	v_cvt_pk_bf16_f32 v33, v34, v35
	s_waitcnt vmcnt(0)
	v_lshlrev_b32_e32 v75, 16, v71
	v_lshlrev_b32_e32 v74, 16, v70
	v_and_b32_e32 v71, 0xffff0000, v71
	v_and_b32_e32 v70, 0xffff0000, v70
	v_pk_mul_f32 v[76:77], v[36:37], v[70:71]
	v_pk_mul_f32 v[36:37], v[36:37], v[74:75]
	v_pk_fma_f32 v[76:77], v[52:53], v[74:75], v[76:77] neg_lo:[0,0,1] neg_hi:[0,0,1]
	v_pk_fma_f32 v[52:53], v[52:53], v[70:71], v[36:37]
	v_and_b32_e32 v71, 0xffff0000, v73
	v_and_b32_e32 v70, 0xffff0000, v72
	v_lshlrev_b32_e32 v37, 16, v73
	v_lshlrev_b32_e32 v36, 16, v72
	v_pk_mul_f32 v[72:73], v[38:39], v[70:71]
	v_cvt_pk_bf16_f32 v34, v52, v53
	v_pk_fma_f32 v[72:73], v[54:55], v[36:37], v[72:73] neg_lo:[0,0,1] neg_hi:[0,0,1]
	v_pk_mul_f32 v[36:37], v[38:39], v[36:37]
	v_cvt_pk_bf16_f32 v38, v76, v77
	v_pk_fma_f32 v[54:55], v[54:55], v[70:71], v[36:37]
	v_cvt_pk_bf16_f32 v36, v48, v49
	v_cvt_pk_bf16_f32 v37, v50, v51
	v_cvt_pk_bf16_f32 v39, v72, v73
	v_cvt_pk_bf16_f32 v35, v54, v55
	v_permlane32_swap_b32_e32 v36, v38
	v_permlane32_swap_b32_e32 v37, v39
	v_permlane32_swap_b32_e32 v32, v34
	v_permlane32_swap_b32_e32 v33, v35
	global_store_dwordx4 v[64:65], v[36:39], off
	global_store_dwordx4 v[64:65], v[32:35], off offset:64
	global_load_dwordx4 v[32:35], v[68:69], off offset:64
	v_pk_mul_f32 v[48:49], v[56:57], v[66:67] op_sel_hi:[1,0]
	v_pk_mul_f32 v[50:51], v[60:61], v[66:67] op_sel_hi:[1,0]
	s_waitcnt vmcnt(0)
	v_lshlrev_b32_e32 v39, 16, v33
	v_lshlrev_b32_e32 v38, 16, v32
	v_and_b32_e32 v33, 0xffff0000, v33
	v_and_b32_e32 v32, 0xffff0000, v32
	v_pk_mul_f32 v[36:37], v[40:41], v[32:33]
	s_nop 0
	v_pk_fma_f32 v[36:37], v[48:49], v[38:39], v[36:37] neg_lo:[0,0,1] neg_hi:[0,0,1]
	v_pk_mul_f32 v[38:39], v[40:41], v[38:39]
	v_lshlrev_b32_e32 v41, 16, v35
	v_lshlrev_b32_e32 v40, 16, v34
	v_and_b32_e32 v35, 0xffff0000, v35
	v_and_b32_e32 v34, 0xffff0000, v34
	v_pk_fma_f32 v[32:33], v[48:49], v[32:33], v[38:39]
	v_pk_mul_f32 v[48:49], v[58:59], v[66:67] op_sel_hi:[1,0]
	v_pk_mul_f32 v[38:39], v[42:43], v[34:35]
	v_cvt_pk_bf16_f32 v36, v36, v37
	v_pk_fma_f32 v[38:39], v[48:49], v[40:41], v[38:39] neg_lo:[0,0,1] neg_hi:[0,0,1]
	v_pk_mul_f32 v[40:41], v[42:43], v[40:41]
	v_cvt_pk_bf16_f32 v37, v38, v39
	v_pk_fma_f32 v[34:35], v[48:49], v[34:35], v[40:41]
	global_load_dwordx4 v[40:43], v[68:69], off offset:96
	v_cvt_pk_bf16_f32 v32, v32, v33
	v_cvt_pk_bf16_f32 v33, v34, v35
	s_waitcnt vmcnt(0)
	v_lshlrev_b32_e32 v49, 16, v41
	v_lshlrev_b32_e32 v48, 16, v40
	v_and_b32_e32 v41, 0xffff0000, v41
	v_and_b32_e32 v40, 0xffff0000, v40
	v_pk_mul_f32 v[52:53], v[44:45], v[40:41]
	v_pk_mul_f32 v[44:45], v[44:45], v[48:49]
	v_pk_fma_f32 v[52:53], v[50:51], v[48:49], v[52:53] neg_lo:[0,0,1] neg_hi:[0,0,1]
	v_pk_fma_f32 v[40:41], v[50:51], v[40:41], v[44:45]
	v_lshlrev_b32_e32 v45, 16, v43
	v_lshlrev_b32_e32 v44, 16, v42
	v_and_b32_e32 v43, 0xffff0000, v43
	v_and_b32_e32 v42, 0xffff0000, v42
	v_pk_mul_f32 v[48:49], v[62:63], v[66:67] op_sel_hi:[1,0]
	v_pk_mul_f32 v[50:51], v[46:47], v[42:43]
	v_cvt_pk_bf16_f32 v38, v52, v53
	v_pk_fma_f32 v[50:51], v[48:49], v[44:45], v[50:51] neg_lo:[0,0,1] neg_hi:[0,0,1]
	v_pk_mul_f32 v[44:45], v[46:47], v[44:45]
	v_cvt_pk_bf16_f32 v39, v50, v51
	v_pk_fma_f32 v[42:43], v[48:49], v[42:43], v[44:45]
	v_cvt_pk_bf16_f32 v34, v40, v41
	v_cvt_pk_bf16_f32 v35, v42, v43
	v_permlane32_swap_b32_e32 v36, v38
	v_permlane32_swap_b32_e32 v37, v39
	v_permlane32_swap_b32_e32 v32, v34
	v_permlane32_swap_b32_e32 v33, v35
	global_store_dwordx4 v[64:65], v[36:39], off offset:32
	global_store_dwordx4 v[64:65], v[32:35], off offset:96
.LBB0_310:
	s_or_b64 exec, exec, s[8:9]
	s_nop 0
	v_add_u32_e32 v32, 0x60, v178
	v_ashrrev_i32_e32 v33, 31, v32
	v_lshl_add_u64 v[34:35], v[32:33], 2, s[14:15]
	global_load_dword v34, v[34:35], off
	v_mov_b64_e32 v[36:37], s[16:17]
	s_movk_i32 s8, 0x1d00
	v_mad_i64_i32 v[36:37], s[8:9], v32, s8, v[36:37]
	v_lshl_add_u64 v[36:37], v[176:177], 1, v[36:37]
	s_and_saveexec_b64 s[8:9], s[0:1]
	s_xor_b64 s[0:1], exec, s[8:9]
	s_cbranch_execz .LBB0_312
	s_waitcnt vmcnt(0) lgkmcnt(0)
	v_pk_mul_f32 v[16:17], v[16:17], v[34:35] op_sel_hi:[1,0]
	v_pk_mul_f32 v[18:19], v[18:19], v[34:35] op_sel_hi:[1,0]
	v_pk_mul_f32 v[20:21], v[20:21], v[34:35] op_sel_hi:[1,0]
	v_pk_mul_f32 v[22:23], v[22:23], v[34:35] op_sel_hi:[1,0]
	v_pk_mul_f32 v[0:1], v[0:1], v[34:35] op_sel_hi:[1,0]
	v_pk_mul_f32 v[2:3], v[2:3], v[34:35] op_sel_hi:[1,0]
	v_pk_mul_f32 v[4:5], v[4:5], v[34:35] op_sel_hi:[1,0]
	v_pk_mul_f32 v[6:7], v[6:7], v[34:35] op_sel_hi:[1,0]
	v_cvt_pk_bf16_f32 v16, v16, v17
	v_cvt_pk_bf16_f32 v17, v18, v19
	v_cvt_pk_bf16_f32 v18, v20, v21
	v_cvt_pk_bf16_f32 v19, v22, v23
	v_cvt_pk_bf16_f32 v0, v0, v1
	v_cvt_pk_bf16_f32 v1, v2, v3
	v_cvt_pk_bf16_f32 v2, v4, v5
	v_cvt_pk_bf16_f32 v3, v6, v7
	v_lshl_add_u64 v[32:33], v[36:37], 0, v[192:193]
	v_permlane32_swap_b32_e32 v16, v18
	v_permlane32_swap_b32_e32 v17, v19
	v_permlane32_swap_b32_e32 v0, v2
	v_permlane32_swap_b32_e32 v1, v3
	global_store_dwordx4 v[32:33], v[16:19], off
	v_pk_mul_f32 v[20:21], v[28:29], v[34:35] op_sel_hi:[1,0]
	v_pk_mul_f32 v[22:23], v[30:31], v[34:35] op_sel_hi:[1,0]
	v_pk_mul_f32 v[16:17], v[24:25], v[34:35] op_sel_hi:[1,0]
	v_pk_mul_f32 v[18:19], v[26:27], v[34:35] op_sel_hi:[1,0]
	global_store_dwordx4 v[32:33], v[0:3], off offset:64
	v_pk_mul_f32 v[4:5], v[12:13], v[34:35] op_sel_hi:[1,0]
	v_pk_mul_f32 v[6:7], v[14:15], v[34:35] op_sel_hi:[1,0]
	v_pk_mul_f32 v[0:1], v[8:9], v[34:35] op_sel_hi:[1,0]
	v_pk_mul_f32 v[2:3], v[10:11], v[34:35] op_sel_hi:[1,0]
	v_cvt_pk_bf16_f32 v16, v16, v17
	v_cvt_pk_bf16_f32 v17, v18, v19
	v_cvt_pk_bf16_f32 v18, v20, v21
	v_cvt_pk_bf16_f32 v19, v22, v23
	v_cvt_pk_bf16_f32 v0, v0, v1
	v_cvt_pk_bf16_f32 v1, v2, v3
	v_cvt_pk_bf16_f32 v2, v4, v5
	v_cvt_pk_bf16_f32 v3, v6, v7
	v_permlane32_swap_b32_e32 v16, v18
	v_permlane32_swap_b32_e32 v17, v19
	v_permlane32_swap_b32_e32 v0, v2
	v_permlane32_swap_b32_e32 v1, v3
	global_store_dwordx4 v[32:33], v[16:19], off offset:32
	global_store_dwordx4 v[32:33], v[0:3], off offset:96
.LBB0_312:
	s_andn2_saveexec_b64 s[0:1], s[0:1]
	s_cbranch_execz .LBB0_294
	v_lshlrev_b32_e32 v38, 5, v32
	v_ashrrev_i32_e32 v39, 31, v38
	v_lshl_add_u64 v[32:33], v[36:37], 0, v[192:193]
	v_lshl_add_u64 v[36:37], v[38:39], 2, s[18:19]
	v_mov_b32_e32 v181, v193
	v_lshl_add_u64 v[36:37], v[36:37], 0, v[180:181]
	global_load_dwordx4 v[38:41], v[36:37], off
	s_waitcnt vmcnt(1) lgkmcnt(0)
	v_pk_mul_f32 v[0:1], v[0:1], v[34:35] op_sel_hi:[1,0]
	v_pk_mul_f32 v[44:45], v[16:17], v[34:35] op_sel_hi:[1,0]
	v_pk_mul_f32 v[2:3], v[2:3], v[34:35] op_sel_hi:[1,0]
	v_pk_mul_f32 v[4:5], v[4:5], v[34:35] op_sel_hi:[1,0]
	v_pk_mul_f32 v[20:21], v[20:21], v[34:35] op_sel_hi:[1,0]
	v_pk_mul_f32 v[6:7], v[6:7], v[34:35] op_sel_hi:[1,0]
	v_pk_mul_f32 v[22:23], v[22:23], v[34:35] op_sel_hi:[1,0]
	v_pk_mul_f32 v[8:9], v[8:9], v[34:35] op_sel_hi:[1,0]
	v_pk_mul_f32 v[10:11], v[10:11], v[34:35] op_sel_hi:[1,0]
	v_pk_mul_f32 v[12:13], v[12:13], v[34:35] op_sel_hi:[1,0]
	v_pk_mul_f32 v[14:15], v[14:15], v[34:35] op_sel_hi:[1,0]
	s_waitcnt vmcnt(0)
	v_lshlrev_b32_e32 v43, 16, v39
	v_lshlrev_b32_e32 v42, 16, v38
	v_and_b32_e32 v39, 0xffff0000, v39
	v_and_b32_e32 v38, 0xffff0000, v38
	v_pk_mul_f32 v[16:17], v[0:1], v[38:39]
	v_pk_mul_f32 v[0:1], v[0:1], v[42:43]
	v_pk_fma_f32 v[16:17], v[44:45], v[42:43], v[16:17] neg_lo:[0,0,1] neg_hi:[0,0,1]
	v_pk_fma_f32 v[0:1], v[44:45], v[38:39], v[0:1]
	v_lshlrev_b32_e32 v39, 16, v41
	v_lshlrev_b32_e32 v38, 16, v40
	v_and_b32_e32 v41, 0xffff0000, v41
	v_and_b32_e32 v40, 0xffff0000, v40
	v_pk_mul_f32 v[42:43], v[18:19], v[34:35] op_sel_hi:[1,0]
	v_pk_mul_f32 v[18:19], v[2:3], v[40:41]
	v_pk_mul_f32 v[2:3], v[2:3], v[38:39]
	v_pk_fma_f32 v[18:19], v[42:43], v[38:39], v[18:19] neg_lo:[0,0,1] neg_hi:[0,0,1]
	v_pk_fma_f32 v[2:3], v[42:43], v[40:41], v[2:3]
	global_load_dwordx4 v[38:41], v[36:37], off offset:32
	v_cvt_pk_bf16_f32 v0, v0, v1
	v_cvt_pk_bf16_f32 v1, v2, v3
	s_waitcnt vmcnt(0)
	v_lshlrev_b32_e32 v43, 16, v39
	v_lshlrev_b32_e32 v42, 16, v38
	v_and_b32_e32 v39, 0xffff0000, v39
	v_and_b32_e32 v38, 0xffff0000, v38
	v_pk_mul_f32 v[44:45], v[4:5], v[38:39]
	v_pk_mul_f32 v[4:5], v[4:5], v[42:43]
	v_pk_fma_f32 v[44:45], v[20:21], v[42:43], v[44:45] neg_lo:[0,0,1] neg_hi:[0,0,1]
	v_pk_fma_f32 v[20:21], v[20:21], v[38:39], v[4:5]
	v_and_b32_e32 v39, 0xffff0000, v41
	v_and_b32_e32 v38, 0xffff0000, v40
	v_lshlrev_b32_e32 v5, 16, v41
	v_lshlrev_b32_e32 v4, 16, v40
	v_pk_mul_f32 v[40:41], v[6:7], v[38:39]
	v_cvt_pk_bf16_f32 v2, v20, v21
	v_pk_fma_f32 v[40:41], v[22:23], v[4:5], v[40:41] neg_lo:[0,0,1] neg_hi:[0,0,1]
	v_pk_mul_f32 v[4:5], v[6:7], v[4:5]
	v_cvt_pk_bf16_f32 v6, v44, v45
	v_pk_fma_f32 v[22:23], v[22:23], v[38:39], v[4:5]
	v_cvt_pk_bf16_f32 v4, v16, v17
	v_cvt_pk_bf16_f32 v5, v18, v19
	v_cvt_pk_bf16_f32 v7, v40, v41
	v_cvt_pk_bf16_f32 v3, v22, v23
	v_permlane32_swap_b32_e32 v4, v6
	v_permlane32_swap_b32_e32 v5, v7
	v_permlane32_swap_b32_e32 v0, v2
	v_permlane32_swap_b32_e32 v1, v3
	global_store_dwordx4 v[32:33], v[4:7], off
	global_store_dwordx4 v[32:33], v[0:3], off offset:64
	global_load_dwordx4 v[0:3], v[36:37], off offset:64
	v_pk_mul_f32 v[16:17], v[24:25], v[34:35] op_sel_hi:[1,0]
	v_pk_mul_f32 v[18:19], v[28:29], v[34:35] op_sel_hi:[1,0]
	s_waitcnt vmcnt(0)
	v_lshlrev_b32_e32 v7, 16, v1
	v_lshlrev_b32_e32 v6, 16, v0
	v_and_b32_e32 v1, 0xffff0000, v1
	v_and_b32_e32 v0, 0xffff0000, v0
	v_pk_mul_f32 v[4:5], v[8:9], v[0:1]
	s_nop 0
	v_pk_fma_f32 v[4:5], v[16:17], v[6:7], v[4:5] neg_lo:[0,0,1] neg_hi:[0,0,1]
	v_pk_mul_f32 v[6:7], v[8:9], v[6:7]
	v_lshlrev_b32_e32 v9, 16, v3
	v_lshlrev_b32_e32 v8, 16, v2
	v_and_b32_e32 v3, 0xffff0000, v3
	v_and_b32_e32 v2, 0xffff0000, v2
	v_pk_fma_f32 v[0:1], v[16:17], v[0:1], v[6:7]
	v_pk_mul_f32 v[16:17], v[26:27], v[34:35] op_sel_hi:[1,0]
	v_pk_mul_f32 v[6:7], v[10:11], v[2:3]
	v_cvt_pk_bf16_f32 v4, v4, v5
	v_pk_fma_f32 v[6:7], v[16:17], v[8:9], v[6:7] neg_lo:[0,0,1] neg_hi:[0,0,1]
	v_pk_mul_f32 v[8:9], v[10:11], v[8:9]
	v_cvt_pk_bf16_f32 v5, v6, v7
	v_pk_fma_f32 v[2:3], v[16:17], v[2:3], v[8:9]
	global_load_dwordx4 v[8:11], v[36:37], off offset:96
	v_cvt_pk_bf16_f32 v0, v0, v1
	v_cvt_pk_bf16_f32 v1, v2, v3
	s_waitcnt vmcnt(0)
	v_lshlrev_b32_e32 v17, 16, v9
	v_lshlrev_b32_e32 v16, 16, v8
	v_and_b32_e32 v9, 0xffff0000, v9
	v_and_b32_e32 v8, 0xffff0000, v8
	v_pk_mul_f32 v[20:21], v[12:13], v[8:9]
	v_pk_mul_f32 v[12:13], v[12:13], v[16:17]
	v_pk_fma_f32 v[20:21], v[18:19], v[16:17], v[20:21] neg_lo:[0,0,1] neg_hi:[0,0,1]
	v_pk_fma_f32 v[8:9], v[18:19], v[8:9], v[12:13]
	v_lshlrev_b32_e32 v13, 16, v11
	v_lshlrev_b32_e32 v12, 16, v10
	v_and_b32_e32 v11, 0xffff0000, v11
	v_and_b32_e32 v10, 0xffff0000, v10
	v_pk_mul_f32 v[16:17], v[30:31], v[34:35] op_sel_hi:[1,0]
	v_pk_mul_f32 v[18:19], v[14:15], v[10:11]
	v_cvt_pk_bf16_f32 v6, v20, v21
	v_pk_fma_f32 v[18:19], v[16:17], v[12:13], v[18:19] neg_lo:[0,0,1] neg_hi:[0,0,1]
	v_pk_mul_f32 v[12:13], v[14:15], v[12:13]
	v_cvt_pk_bf16_f32 v7, v18, v19
	v_pk_fma_f32 v[10:11], v[16:17], v[10:11], v[12:13]
	v_cvt_pk_bf16_f32 v2, v8, v9
	v_cvt_pk_bf16_f32 v3, v10, v11
	v_permlane32_swap_b32_e32 v4, v6
	v_permlane32_swap_b32_e32 v5, v7
	v_permlane32_swap_b32_e32 v0, v2
	v_permlane32_swap_b32_e32 v1, v3
	global_store_dwordx4 v[32:33], v[4:7], off offset:32
	global_store_dwordx4 v[32:33], v[0:3], off offset:96
	s_branch .LBB0_294

.LBB0_316:
	v_mov_b32_e32 v21, v185
	s_ashr_i32 s11, s10, 31
	s_lshl_b64 s[14:15], s[10:11], 11
	v_and_b32_e32 v86, 63, v21
	v_lshlrev_b32_e32 v0, 4, v21
	v_lshlrev_b32_e32 v192, 4, v86
	v_ashrrev_i32_e32 v24, 3, v21
	s_add_u32 s14, s12, s14
	v_and_b32_e32 v20, 0x70, v0
	v_lshl_add_u64 v[72:73], s[0:1], 0, v[192:193]
	s_addc_u32 s15, s13, s15
	v_lshl_or_b32 v192, v24, 11, v20
	v_lshl_add_u64 v[76:77], s[14:15], 0, v[192:193]
	v_add_co_u32_e32 v78, vcc, s17, v76
	s_waitcnt lgkmcnt(0)
	s_nop 0
	v_addc_co_u32_e32 v79, vcc, 0, v77, vcc
	v_add_co_u32_e32 v80, vcc, s18, v76
	s_barrier
	global_load_dwordx4 v[0:3], v[76:77], off
	global_load_dwordx4 v[4:7], v[78:79], off
	v_addc_co_u32_e32 v81, vcc, 0, v77, vcc
	v_add_co_u32_e32 v82, vcc, s19, v76
	global_load_dwordx4 v[8:11], v[80:81], off
	s_nop 0
	v_addc_co_u32_e32 v83, vcc, 0, v77, vcc
	global_load_dwordx4 v[12:15], v[82:83], off
	s_mov_b32 s11, 0x700000
	v_add_co_u32_e32 v22, vcc, s11, v72
	s_mov_b32 s11, 0x710000
	s_nop 0
	v_addc_co_u32_e32 v23, vcc, 0, v73, vcc
	global_load_dwordx4 v[16:19], v[22:23], off
	s_waitcnt vmcnt(0)
	global_load_dwordx4 v[64:67], v[22:23], off offset:1024
	global_load_dwordx4 v[56:59], v[22:23], off offset:2048
	global_load_dwordx4 v[32:35], v[22:23], off offset:3072
	v_add_co_u32_e32 v22, vcc, s11, v72
	v_mad_u64_u32 v[74:75], s[14:15], v24, s21, v[20:21]
	s_nop 0
	v_addc_co_u32_e32 v23, vcc, 0, v73, vcc
	global_load_dwordx4 v[88:91], v[22:23], off
	global_load_dwordx4 v[68:71], v[22:23], off offset:1024
	global_load_dwordx4 v[60:63], v[22:23], off offset:2048
	global_load_dwordx4 v[52:55], v[22:23], off offset:3072
	s_movk_i32 s11, 0xffe0
	s_waitcnt lgkmcnt(0)
	ds_write_b128 v74, v[0:3]
	ds_write_b128 v74, v[4:7] offset:4608
	ds_write_b128 v74, v[8:11] offset:9216
	ds_write_b128 v74, v[12:15] offset:13824
	v_ashrrev_i32_e32 v0, 1, v21
	v_bfi_b32 v75, s11, v0, v21
	v_lshrrev_b32_e32 v0, 1, v21
	v_and_b32_e32 v0, 16, v0
	v_mad_u64_u32 v[84:85], s[14:15], v75, s21, v[0:1]
	global_load_dwordx4 v[36:39], v[76:77], off offset:128
	global_load_dwordx4 v[40:43], v[78:79], off offset:128
	global_load_dwordx4 v[44:47], v[80:81], off offset:128
	global_load_dwordx4 v[48:51], v[82:83], off offset:128
	s_waitcnt lgkmcnt(0)
	s_barrier
	ds_read_b128 v[0:3], v84
	s_mov_b32 s11, 0x701000
	v_add_co_u32_e32 v100, vcc, s11, v72
	s_mov_b32 s11, 0x711000
	s_nop 0
	v_addc_co_u32_e32 v101, vcc, 0, v73, vcc
	v_add_co_u32_e32 v102, vcc, s11, v72
	s_waitcnt lgkmcnt(0)
	v_mfma_f32_32x32x16_bf16 v[16:31], v[16:19], v[0:3], 0
	v_addc_co_u32_e32 v103, vcc, 0, v73, vcc
	global_load_dwordx4 v[92:95], v[100:101], off
	s_waitcnt vmcnt(0)
	v_mfma_f32_32x32x16_bf16 v[0:15], v[88:91], v[0:3], 0
	global_load_dwordx4 v[88:91], v[102:103], off
	ds_read_b128 v[96:99], v84 offset:32
	s_waitcnt lgkmcnt(0)
	v_mfma_f32_32x32x16_bf16 v[16:31], v[64:67], v[96:99], v[16:31]
	global_load_dwordx4 v[64:67], v[100:101], off offset:1024
	v_mfma_f32_32x32x16_bf16 v[0:15], v[68:71], v[96:99], v[0:15]
	global_load_dwordx4 v[68:71], v[102:103], off offset:1024
	ds_read_b128 v[96:99], v84 offset:64
	s_waitcnt lgkmcnt(0)
	v_mfma_f32_32x32x16_bf16 v[16:31], v[56:59], v[96:99], v[16:31]
	global_load_dwordx4 v[56:59], v[100:101], off offset:2048
	v_mfma_f32_32x32x16_bf16 v[0:15], v[60:63], v[96:99], v[0:15]
	global_load_dwordx4 v[60:63], v[102:103], off offset:2048
	ds_read_b128 v[96:99], v84 offset:96
	s_waitcnt lgkmcnt(0)
	v_mfma_f32_32x32x16_bf16 v[16:31], v[32:35], v[96:99], v[16:31]
	global_load_dwordx4 v[32:35], v[100:101], off offset:3072
	v_mfma_f32_32x32x16_bf16 v[0:15], v[52:55], v[96:99], v[0:15]
	global_load_dwordx4 v[52:55], v[102:103], off offset:3072
	ds_write_b128 v74, v[36:39] offset:18432
	ds_write_b128 v74, v[40:43] offset:23040
	ds_write_b128 v74, v[44:47] offset:27648
	ds_write_b128 v74, v[48:51] offset:32256
	global_load_dwordx4 v[36:39], v[76:77], off offset:256
	global_load_dwordx4 v[40:43], v[78:79], off offset:256
	global_load_dwordx4 v[44:47], v[80:81], off offset:256
	global_load_dwordx4 v[48:51], v[82:83], off offset:256
	s_waitcnt lgkmcnt(0)
	s_barrier
	ds_read_b128 v[96:99], v84 offset:18432
	s_mov_b32 s11, 0x702000
	v_add_co_u32_e32 v100, vcc, s11, v72
	s_mov_b32 s11, 0x712000
	s_nop 0
	v_addc_co_u32_e32 v101, vcc, 0, v73, vcc
	v_add_co_u32_e32 v102, vcc, s11, v72
	s_waitcnt lgkmcnt(0)
	v_mfma_f32_32x32x16_bf16 v[16:31], v[92:95], v[96:99], v[16:31]
	v_addc_co_u32_e32 v103, vcc, 0, v73, vcc
	global_load_dwordx4 v[92:95], v[100:101], off
	s_waitcnt vmcnt(0)
	v_mfma_f32_32x32x16_bf16 v[0:15], v[88:91], v[96:99], v[0:15]
	global_load_dwordx4 v[88:91], v[102:103], off
	ds_read_b128 v[96:99], v84 offset:18464
	s_waitcnt lgkmcnt(0)
	v_mfma_f32_32x32x16_bf16 v[16:31], v[64:67], v[96:99], v[16:31]
	global_load_dwordx4 v[64:67], v[100:101], off offset:1024
	v_mfma_f32_32x32x16_bf16 v[0:15], v[68:71], v[96:99], v[0:15]
	global_load_dwordx4 v[68:71], v[102:103], off offset:1024
	ds_read_b128 v[96:99], v84 offset:18496
	s_waitcnt lgkmcnt(0)
	v_mfma_f32_32x32x16_bf16 v[16:31], v[56:59], v[96:99], v[16:31]
	global_load_dwordx4 v[56:59], v[100:101], off offset:2048
	v_mfma_f32_32x32x16_bf16 v[0:15], v[60:63], v[96:99], v[0:15]
	global_load_dwordx4 v[60:63], v[102:103], off offset:2048
	ds_read_b128 v[96:99], v84 offset:18528
	s_waitcnt lgkmcnt(0)
	v_mfma_f32_32x32x16_bf16 v[16:31], v[32:35], v[96:99], v[16:31]
	global_load_dwordx4 v[32:35], v[100:101], off offset:3072
	v_mfma_f32_32x32x16_bf16 v[0:15], v[52:55], v[96:99], v[0:15]
	global_load_dwordx4 v[52:55], v[102:103], off offset:3072
	ds_write_b128 v74, v[36:39]
	ds_write_b128 v74, v[40:43] offset:4608
	ds_write_b128 v74, v[44:47] offset:9216
	ds_write_b128 v74, v[48:51] offset:13824
	global_load_dwordx4 v[36:39], v[82:83], off offset:384
	global_load_dwordx4 v[40:43], v[80:81], off offset:384
	global_load_dwordx4 v[44:47], v[78:79], off offset:384
	global_load_dwordx4 v[48:51], v[76:77], off offset:384
	s_waitcnt lgkmcnt(0)
	s_barrier
	ds_read_b128 v[96:99], v84
	s_mov_b32 s11, 0x703000
	v_add_co_u32_e32 v100, vcc, s11, v72
	s_mov_b32 s11, 0x713000
	s_nop 0
	v_addc_co_u32_e32 v101, vcc, 0, v73, vcc
	v_add_co_u32_e32 v102, vcc, s11, v72
	s_waitcnt lgkmcnt(0)
	v_mfma_f32_32x32x16_bf16 v[16:31], v[92:95], v[96:99], v[16:31]
	v_addc_co_u32_e32 v103, vcc, 0, v73, vcc
	global_load_dwordx4 v[92:95], v[100:101], off
	s_waitcnt vmcnt(0)
	v_mfma_f32_32x32x16_bf16 v[0:15], v[88:91], v[96:99], v[0:15]
	global_load_dwordx4 v[88:91], v[102:103], off
	ds_read_b128 v[96:99], v84 offset:32
	s_waitcnt lgkmcnt(0)
	v_mfma_f32_32x32x16_bf16 v[16:31], v[64:67], v[96:99], v[16:31]
	global_load_dwordx4 v[64:67], v[100:101], off offset:1024
	v_mfma_f32_32x32x16_bf16 v[0:15], v[68:71], v[96:99], v[0:15]
	global_load_dwordx4 v[68:71], v[102:103], off offset:1024
	ds_read_b128 v[96:99], v84 offset:64
	s_waitcnt lgkmcnt(0)
	v_mfma_f32_32x32x16_bf16 v[16:31], v[56:59], v[96:99], v[16:31]
	global_load_dwordx4 v[56:59], v[100:101], off offset:2048
	v_mfma_f32_32x32x16_bf16 v[0:15], v[60:63], v[96:99], v[0:15]
	global_load_dwordx4 v[60:63], v[102:103], off offset:2048
	ds_read_b128 v[96:99], v84 offset:96
	s_waitcnt lgkmcnt(0)
	v_mfma_f32_32x32x16_bf16 v[16:31], v[32:35], v[96:99], v[16:31]
	global_load_dwordx4 v[32:35], v[100:101], off offset:3072
	v_mfma_f32_32x32x16_bf16 v[0:15], v[52:55], v[96:99], v[0:15]
	global_load_dwordx4 v[52:55], v[102:103], off offset:3072
	ds_write_b128 v74, v[48:51] offset:18432
	ds_write_b128 v74, v[44:47] offset:23040
	ds_write_b128 v74, v[40:43] offset:27648
	ds_write_b128 v74, v[36:39] offset:32256
	global_load_dwordx4 v[36:39], v[76:77], off offset:512
	global_load_dwordx4 v[40:43], v[78:79], off offset:512
	global_load_dwordx4 v[44:47], v[80:81], off offset:512
	global_load_dwordx4 v[48:51], v[82:83], off offset:512
	s_waitcnt lgkmcnt(0)
	s_barrier
	ds_read_b128 v[96:99], v84 offset:18432
	s_mov_b32 s11, 0x704000
	v_add_co_u32_e32 v100, vcc, s11, v72
	s_mov_b32 s11, 0x714000
	s_nop 0
	v_addc_co_u32_e32 v101, vcc, 0, v73, vcc
	v_add_co_u32_e32 v102, vcc, s11, v72
	s_waitcnt lgkmcnt(0)
	v_mfma_f32_32x32x16_bf16 v[16:31], v[92:95], v[96:99], v[16:31]
	v_addc_co_u32_e32 v103, vcc, 0, v73, vcc
	global_load_dwordx4 v[92:95], v[100:101], off
	s_waitcnt vmcnt(0)
	v_mfma_f32_32x32x16_bf16 v[0:15], v[88:91], v[96:99], v[0:15]
	global_load_dwordx4 v[88:91], v[102:103], off
	ds_read_b128 v[96:99], v84 offset:18464
	s_waitcnt lgkmcnt(0)
	v_mfma_f32_32x32x16_bf16 v[16:31], v[64:67], v[96:99], v[16:31]
	global_load_dwordx4 v[64:67], v[100:101], off offset:1024
	v_mfma_f32_32x32x16_bf16 v[0:15], v[68:71], v[96:99], v[0:15]
	global_load_dwordx4 v[68:71], v[102:103], off offset:1024
	ds_read_b128 v[96:99], v84 offset:18496
	s_waitcnt lgkmcnt(0)
	v_mfma_f32_32x32x16_bf16 v[16:31], v[56:59], v[96:99], v[16:31]
	global_load_dwordx4 v[56:59], v[100:101], off offset:2048
	v_mfma_f32_32x32x16_bf16 v[0:15], v[60:63], v[96:99], v[0:15]
	global_load_dwordx4 v[60:63], v[102:103], off offset:2048
	ds_read_b128 v[96:99], v84 offset:18528
	s_waitcnt lgkmcnt(0)
	v_mfma_f32_32x32x16_bf16 v[16:31], v[32:35], v[96:99], v[16:31]
	global_load_dwordx4 v[32:35], v[100:101], off offset:3072
	v_mfma_f32_32x32x16_bf16 v[0:15], v[52:55], v[96:99], v[0:15]
	global_load_dwordx4 v[52:55], v[102:103], off offset:3072
	ds_write_b128 v74, v[36:39]
	ds_write_b128 v74, v[40:43] offset:4608
	ds_write_b128 v74, v[44:47] offset:9216
	ds_write_b128 v74, v[48:51] offset:13824
	global_load_dwordx4 v[36:39], v[82:83], off offset:640
	global_load_dwordx4 v[40:43], v[80:81], off offset:640
	global_load_dwordx4 v[44:47], v[78:79], off offset:640
	global_load_dwordx4 v[48:51], v[76:77], off offset:640
	s_waitcnt lgkmcnt(0)
	s_barrier
	ds_read_b128 v[96:99], v84
	s_mov_b32 s11, 0x705000
	v_add_co_u32_e32 v100, vcc, s11, v72
	s_mov_b32 s11, 0x715000
	s_nop 0
	v_addc_co_u32_e32 v101, vcc, 0, v73, vcc
	v_add_co_u32_e32 v102, vcc, s11, v72
	s_waitcnt lgkmcnt(0)
	v_mfma_f32_32x32x16_bf16 v[16:31], v[92:95], v[96:99], v[16:31]
	v_addc_co_u32_e32 v103, vcc, 0, v73, vcc
	global_load_dwordx4 v[92:95], v[100:101], off
	s_waitcnt vmcnt(0)
	v_mfma_f32_32x32x16_bf16 v[0:15], v[88:91], v[96:99], v[0:15]
	global_load_dwordx4 v[88:91], v[102:103], off
	ds_read_b128 v[96:99], v84 offset:32
	s_waitcnt lgkmcnt(0)
	v_mfma_f32_32x32x16_bf16 v[16:31], v[64:67], v[96:99], v[16:31]
	global_load_dwordx4 v[64:67], v[100:101], off offset:1024
	v_mfma_f32_32x32x16_bf16 v[0:15], v[68:71], v[96:99], v[0:15]
	global_load_dwordx4 v[68:71], v[102:103], off offset:1024
	ds_read_b128 v[96:99], v84 offset:64
	s_waitcnt lgkmcnt(0)
	v_mfma_f32_32x32x16_bf16 v[16:31], v[56:59], v[96:99], v[16:31]
	global_load_dwordx4 v[56:59], v[100:101], off offset:2048
	v_mfma_f32_32x32x16_bf16 v[0:15], v[60:63], v[96:99], v[0:15]
	global_load_dwordx4 v[60:63], v[102:103], off offset:2048
	ds_read_b128 v[96:99], v84 offset:96
	s_waitcnt lgkmcnt(0)
	v_mfma_f32_32x32x16_bf16 v[16:31], v[32:35], v[96:99], v[16:31]
	global_load_dwordx4 v[32:35], v[100:101], off offset:3072
	v_mfma_f32_32x32x16_bf16 v[0:15], v[52:55], v[96:99], v[0:15]
	global_load_dwordx4 v[52:55], v[102:103], off offset:3072
	ds_write_b128 v74, v[48:51] offset:18432
	ds_write_b128 v74, v[44:47] offset:23040
	ds_write_b128 v74, v[40:43] offset:27648
	ds_write_b128 v74, v[36:39] offset:32256
	global_load_dwordx4 v[36:39], v[76:77], off offset:768
	global_load_dwordx4 v[40:43], v[78:79], off offset:768
	global_load_dwordx4 v[44:47], v[80:81], off offset:768
	global_load_dwordx4 v[48:51], v[82:83], off offset:768
	s_waitcnt lgkmcnt(0)
	s_barrier
	ds_read_b128 v[96:99], v84 offset:18432
	s_mov_b32 s11, 0x706000
	v_add_co_u32_e32 v100, vcc, s11, v72
	s_mov_b32 s11, 0x716000
	s_nop 0
	v_addc_co_u32_e32 v101, vcc, 0, v73, vcc
	v_add_co_u32_e32 v102, vcc, s11, v72
	s_waitcnt lgkmcnt(0)
	v_mfma_f32_32x32x16_bf16 v[16:31], v[92:95], v[96:99], v[16:31]
	v_addc_co_u32_e32 v103, vcc, 0, v73, vcc
	global_load_dwordx4 v[92:95], v[100:101], off
	s_waitcnt vmcnt(0)
	v_mfma_f32_32x32x16_bf16 v[0:15], v[88:91], v[96:99], v[0:15]
	global_load_dwordx4 v[88:91], v[102:103], off
	ds_read_b128 v[96:99], v84 offset:18464
	s_waitcnt lgkmcnt(0)
	v_mfma_f32_32x32x16_bf16 v[16:31], v[64:67], v[96:99], v[16:31]
	global_load_dwordx4 v[64:67], v[100:101], off offset:1024
	v_mfma_f32_32x32x16_bf16 v[0:15], v[68:71], v[96:99], v[0:15]
	global_load_dwordx4 v[68:71], v[102:103], off offset:1024
	ds_read_b128 v[96:99], v84 offset:18496
	s_waitcnt lgkmcnt(0)
	v_mfma_f32_32x32x16_bf16 v[16:31], v[56:59], v[96:99], v[16:31]
	global_load_dwordx4 v[56:59], v[100:101], off offset:2048
	v_mfma_f32_32x32x16_bf16 v[0:15], v[60:63], v[96:99], v[0:15]
	global_load_dwordx4 v[60:63], v[102:103], off offset:2048
	ds_read_b128 v[96:99], v84 offset:18528
	s_waitcnt lgkmcnt(0)
	v_mfma_f32_32x32x16_bf16 v[16:31], v[32:35], v[96:99], v[16:31]
	global_load_dwordx4 v[32:35], v[100:101], off offset:3072
	v_mfma_f32_32x32x16_bf16 v[0:15], v[52:55], v[96:99], v[0:15]
	global_load_dwordx4 v[52:55], v[102:103], off offset:3072
	ds_write_b128 v74, v[36:39]
	ds_write_b128 v74, v[40:43] offset:4608
	ds_write_b128 v74, v[44:47] offset:9216
	ds_write_b128 v74, v[48:51] offset:13824
	global_load_dwordx4 v[36:39], v[82:83], off offset:896
	global_load_dwordx4 v[40:43], v[80:81], off offset:896
	global_load_dwordx4 v[44:47], v[78:79], off offset:896
	global_load_dwordx4 v[48:51], v[76:77], off offset:896
	s_waitcnt lgkmcnt(0)
	s_barrier
	ds_read_b128 v[96:99], v84
	s_mov_b32 s11, 0x707000
	v_add_co_u32_e32 v100, vcc, s11, v72
	s_mov_b32 s11, 0x717000
	s_nop 0
	v_addc_co_u32_e32 v101, vcc, 0, v73, vcc
	v_add_co_u32_e32 v102, vcc, s11, v72
	s_waitcnt lgkmcnt(0)
	v_mfma_f32_32x32x16_bf16 v[16:31], v[92:95], v[96:99], v[16:31]
	v_addc_co_u32_e32 v103, vcc, 0, v73, vcc
	global_load_dwordx4 v[92:95], v[100:101], off
	s_waitcnt vmcnt(0)
	v_mfma_f32_32x32x16_bf16 v[0:15], v[88:91], v[96:99], v[0:15]
	global_load_dwordx4 v[88:91], v[102:103], off
	ds_read_b128 v[96:99], v84 offset:32
	s_waitcnt lgkmcnt(0)
	v_mfma_f32_32x32x16_bf16 v[16:31], v[64:67], v[96:99], v[16:31]
	global_load_dwordx4 v[64:67], v[100:101], off offset:1024
	v_mfma_f32_32x32x16_bf16 v[0:15], v[68:71], v[96:99], v[0:15]
	global_load_dwordx4 v[68:71], v[102:103], off offset:1024
	ds_read_b128 v[96:99], v84 offset:64
	s_waitcnt lgkmcnt(0)
	v_mfma_f32_32x32x16_bf16 v[16:31], v[56:59], v[96:99], v[16:31]
	global_load_dwordx4 v[56:59], v[100:101], off offset:2048
	v_mfma_f32_32x32x16_bf16 v[0:15], v[60:63], v[96:99], v[0:15]
	global_load_dwordx4 v[60:63], v[102:103], off offset:2048
	ds_read_b128 v[96:99], v84 offset:96
	s_waitcnt lgkmcnt(0)
	v_mfma_f32_32x32x16_bf16 v[16:31], v[32:35], v[96:99], v[16:31]
	global_load_dwordx4 v[32:35], v[100:101], off offset:3072
	v_mfma_f32_32x32x16_bf16 v[0:15], v[52:55], v[96:99], v[0:15]
	global_load_dwordx4 v[52:55], v[102:103], off offset:3072
	ds_write_b128 v74, v[48:51] offset:18432
	ds_write_b128 v74, v[44:47] offset:23040
	ds_write_b128 v74, v[40:43] offset:27648
	ds_write_b128 v74, v[36:39] offset:32256
	global_load_dwordx4 v[36:39], v[76:77], off offset:1024
	global_load_dwordx4 v[40:43], v[78:79], off offset:1024
	global_load_dwordx4 v[44:47], v[80:81], off offset:1024
	global_load_dwordx4 v[48:51], v[82:83], off offset:1024
	s_waitcnt lgkmcnt(0)
	s_barrier
	ds_read_b128 v[96:99], v84 offset:18432
	s_mov_b32 s11, 0x708000
	v_add_co_u32_e32 v100, vcc, s11, v72
	s_mov_b32 s11, 0x718000
	s_nop 0
	v_addc_co_u32_e32 v101, vcc, 0, v73, vcc
	v_add_co_u32_e32 v102, vcc, s11, v72
	s_waitcnt lgkmcnt(0)
	v_mfma_f32_32x32x16_bf16 v[16:31], v[92:95], v[96:99], v[16:31]
	v_addc_co_u32_e32 v103, vcc, 0, v73, vcc
	global_load_dwordx4 v[92:95], v[100:101], off
	s_waitcnt vmcnt(0)
	v_mfma_f32_32x32x16_bf16 v[0:15], v[88:91], v[96:99], v[0:15]
	global_load_dwordx4 v[88:91], v[102:103], off
	ds_read_b128 v[96:99], v84 offset:18464
	s_waitcnt lgkmcnt(0)
	v_mfma_f32_32x32x16_bf16 v[16:31], v[64:67], v[96:99], v[16:31]
	global_load_dwordx4 v[64:67], v[100:101], off offset:1024
	v_mfma_f32_32x32x16_bf16 v[0:15], v[68:71], v[96:99], v[0:15]
	global_load_dwordx4 v[68:71], v[102:103], off offset:1024
	ds_read_b128 v[96:99], v84 offset:18496
	s_waitcnt lgkmcnt(0)
	v_mfma_f32_32x32x16_bf16 v[16:31], v[56:59], v[96:99], v[16:31]
	global_load_dwordx4 v[56:59], v[100:101], off offset:2048
	v_mfma_f32_32x32x16_bf16 v[0:15], v[60:63], v[96:99], v[0:15]
	global_load_dwordx4 v[60:63], v[102:103], off offset:2048
	ds_read_b128 v[96:99], v84 offset:18528
	s_waitcnt lgkmcnt(0)
	v_mfma_f32_32x32x16_bf16 v[16:31], v[32:35], v[96:99], v[16:31]
	global_load_dwordx4 v[32:35], v[100:101], off offset:3072
	v_mfma_f32_32x32x16_bf16 v[0:15], v[52:55], v[96:99], v[0:15]
	global_load_dwordx4 v[52:55], v[102:103], off offset:3072
	ds_write_b128 v74, v[36:39]
	ds_write_b128 v74, v[40:43] offset:4608
	ds_write_b128 v74, v[44:47] offset:9216
	ds_write_b128 v74, v[48:51] offset:13824
	global_load_dwordx4 v[36:39], v[82:83], off offset:1152
	global_load_dwordx4 v[40:43], v[80:81], off offset:1152
	global_load_dwordx4 v[44:47], v[78:79], off offset:1152
	global_load_dwordx4 v[48:51], v[76:77], off offset:1152
	s_waitcnt lgkmcnt(0)
	s_barrier
	ds_read_b128 v[96:99], v84
	s_mov_b32 s11, 0x709000
	v_add_co_u32_e32 v100, vcc, s11, v72
	s_mov_b32 s11, 0x719000
	s_nop 0
	v_addc_co_u32_e32 v101, vcc, 0, v73, vcc
	v_add_co_u32_e32 v102, vcc, s11, v72
	s_waitcnt lgkmcnt(0)
	v_mfma_f32_32x32x16_bf16 v[16:31], v[92:95], v[96:99], v[16:31]
	v_addc_co_u32_e32 v103, vcc, 0, v73, vcc
	global_load_dwordx4 v[92:95], v[100:101], off
	s_waitcnt vmcnt(0)
	v_mfma_f32_32x32x16_bf16 v[0:15], v[88:91], v[96:99], v[0:15]
	global_load_dwordx4 v[88:91], v[102:103], off
	ds_read_b128 v[96:99], v84 offset:32
	s_waitcnt lgkmcnt(0)
	v_mfma_f32_32x32x16_bf16 v[16:31], v[64:67], v[96:99], v[16:31]
	global_load_dwordx4 v[64:67], v[100:101], off offset:1024
	v_mfma_f32_32x32x16_bf16 v[0:15], v[68:71], v[96:99], v[0:15]
	global_load_dwordx4 v[68:71], v[102:103], off offset:1024
	ds_read_b128 v[96:99], v84 offset:64
	s_waitcnt lgkmcnt(0)
	v_mfma_f32_32x32x16_bf16 v[16:31], v[56:59], v[96:99], v[16:31]
	global_load_dwordx4 v[56:59], v[100:101], off offset:2048
	v_mfma_f32_32x32x16_bf16 v[0:15], v[60:63], v[96:99], v[0:15]
	global_load_dwordx4 v[60:63], v[102:103], off offset:2048
	ds_read_b128 v[96:99], v84 offset:96
	s_waitcnt lgkmcnt(0)
	v_mfma_f32_32x32x16_bf16 v[16:31], v[32:35], v[96:99], v[16:31]
	global_load_dwordx4 v[32:35], v[100:101], off offset:3072
	v_mfma_f32_32x32x16_bf16 v[0:15], v[52:55], v[96:99], v[0:15]
	global_load_dwordx4 v[52:55], v[102:103], off offset:3072
	ds_write_b128 v74, v[48:51] offset:18432
	ds_write_b128 v74, v[44:47] offset:23040
	ds_write_b128 v74, v[40:43] offset:27648
	ds_write_b128 v74, v[36:39] offset:32256
	global_load_dwordx4 v[36:39], v[76:77], off offset:1280
	global_load_dwordx4 v[40:43], v[78:79], off offset:1280
	global_load_dwordx4 v[44:47], v[80:81], off offset:1280
	global_load_dwordx4 v[48:51], v[82:83], off offset:1280
	s_waitcnt lgkmcnt(0)
	s_barrier
	ds_read_b128 v[96:99], v84 offset:18432
	s_mov_b32 s11, 0x70a000
	v_add_co_u32_e32 v100, vcc, s11, v72
	s_mov_b32 s11, 0x71a000
	s_nop 0
	v_addc_co_u32_e32 v101, vcc, 0, v73, vcc
	v_add_co_u32_e32 v102, vcc, s11, v72
	s_waitcnt lgkmcnt(0)
	v_mfma_f32_32x32x16_bf16 v[16:31], v[92:95], v[96:99], v[16:31]
	v_addc_co_u32_e32 v103, vcc, 0, v73, vcc
	global_load_dwordx4 v[92:95], v[100:101], off
	s_waitcnt vmcnt(0)
	v_mfma_f32_32x32x16_bf16 v[0:15], v[88:91], v[96:99], v[0:15]
	global_load_dwordx4 v[88:91], v[102:103], off
	ds_read_b128 v[96:99], v84 offset:18464
	s_waitcnt lgkmcnt(0)
	v_mfma_f32_32x32x16_bf16 v[16:31], v[64:67], v[96:99], v[16:31]
	global_load_dwordx4 v[64:67], v[100:101], off offset:1024
	v_mfma_f32_32x32x16_bf16 v[0:15], v[68:71], v[96:99], v[0:15]
	global_load_dwordx4 v[68:71], v[102:103], off offset:1024
	ds_read_b128 v[96:99], v84 offset:18496
	s_waitcnt lgkmcnt(0)
	v_mfma_f32_32x32x16_bf16 v[16:31], v[56:59], v[96:99], v[16:31]
	global_load_dwordx4 v[56:59], v[100:101], off offset:2048
	v_mfma_f32_32x32x16_bf16 v[0:15], v[60:63], v[96:99], v[0:15]
	global_load_dwordx4 v[60:63], v[102:103], off offset:2048
	ds_read_b128 v[96:99], v84 offset:18528
	s_waitcnt lgkmcnt(0)
	v_mfma_f32_32x32x16_bf16 v[16:31], v[32:35], v[96:99], v[16:31]
	global_load_dwordx4 v[32:35], v[100:101], off offset:3072
	v_mfma_f32_32x32x16_bf16 v[0:15], v[52:55], v[96:99], v[0:15]
	global_load_dwordx4 v[52:55], v[102:103], off offset:3072
	ds_write_b128 v74, v[36:39]
	ds_write_b128 v74, v[40:43] offset:4608
	ds_write_b128 v74, v[44:47] offset:9216
	ds_write_b128 v74, v[48:51] offset:13824
	global_load_dwordx4 v[36:39], v[82:83], off offset:1408
	global_load_dwordx4 v[40:43], v[80:81], off offset:1408
	global_load_dwordx4 v[44:47], v[78:79], off offset:1408
	global_load_dwordx4 v[48:51], v[76:77], off offset:1408
	s_waitcnt lgkmcnt(0)
	s_barrier
	ds_read_b128 v[96:99], v84
	s_mov_b32 s11, 0x70b000
	v_add_co_u32_e32 v100, vcc, s11, v72
	s_mov_b32 s11, 0x71b000
	s_nop 0
	v_addc_co_u32_e32 v101, vcc, 0, v73, vcc
	v_add_co_u32_e32 v102, vcc, s11, v72
	s_waitcnt lgkmcnt(0)
	v_mfma_f32_32x32x16_bf16 v[16:31], v[92:95], v[96:99], v[16:31]
	v_addc_co_u32_e32 v103, vcc, 0, v73, vcc
	global_load_dwordx4 v[92:95], v[100:101], off
	s_waitcnt vmcnt(0)
	v_mfma_f32_32x32x16_bf16 v[0:15], v[88:91], v[96:99], v[0:15]
	global_load_dwordx4 v[88:91], v[102:103], off
	ds_read_b128 v[96:99], v84 offset:32
	s_waitcnt lgkmcnt(0)
	v_mfma_f32_32x32x16_bf16 v[16:31], v[64:67], v[96:99], v[16:31]
	global_load_dwordx4 v[64:67], v[100:101], off offset:1024
	v_mfma_f32_32x32x16_bf16 v[0:15], v[68:71], v[96:99], v[0:15]
	global_load_dwordx4 v[68:71], v[102:103], off offset:1024
	ds_read_b128 v[96:99], v84 offset:64
	s_waitcnt lgkmcnt(0)
	v_mfma_f32_32x32x16_bf16 v[16:31], v[56:59], v[96:99], v[16:31]
	global_load_dwordx4 v[56:59], v[100:101], off offset:2048
	v_mfma_f32_32x32x16_bf16 v[0:15], v[60:63], v[96:99], v[0:15]
	global_load_dwordx4 v[60:63], v[102:103], off offset:2048
	ds_read_b128 v[96:99], v84 offset:96
	s_waitcnt lgkmcnt(0)
	v_mfma_f32_32x32x16_bf16 v[16:31], v[32:35], v[96:99], v[16:31]
	global_load_dwordx4 v[32:35], v[100:101], off offset:3072
	v_mfma_f32_32x32x16_bf16 v[0:15], v[52:55], v[96:99], v[0:15]
	global_load_dwordx4 v[52:55], v[102:103], off offset:3072
	ds_write_b128 v74, v[48:51] offset:18432
	ds_write_b128 v74, v[44:47] offset:23040
	ds_write_b128 v74, v[40:43] offset:27648
	ds_write_b128 v74, v[36:39] offset:32256
	global_load_dwordx4 v[36:39], v[76:77], off offset:1536
	global_load_dwordx4 v[40:43], v[78:79], off offset:1536
	global_load_dwordx4 v[44:47], v[80:81], off offset:1536
	global_load_dwordx4 v[48:51], v[82:83], off offset:1536
	s_waitcnt lgkmcnt(0)
	s_barrier
	ds_read_b128 v[96:99], v84 offset:18432
	s_mov_b32 s11, 0x70c000
	v_add_co_u32_e32 v100, vcc, s11, v72
	s_mov_b32 s11, 0x71c000
	s_nop 0
	v_addc_co_u32_e32 v101, vcc, 0, v73, vcc
	v_add_co_u32_e32 v102, vcc, s11, v72
	s_waitcnt lgkmcnt(0)
	v_mfma_f32_32x32x16_bf16 v[16:31], v[92:95], v[96:99], v[16:31]
	v_addc_co_u32_e32 v103, vcc, 0, v73, vcc
	global_load_dwordx4 v[92:95], v[100:101], off
	s_waitcnt vmcnt(0)
	v_mfma_f32_32x32x16_bf16 v[0:15], v[88:91], v[96:99], v[0:15]
	global_load_dwordx4 v[88:91], v[102:103], off
	ds_read_b128 v[96:99], v84 offset:18464
	s_waitcnt lgkmcnt(0)
	v_mfma_f32_32x32x16_bf16 v[16:31], v[64:67], v[96:99], v[16:31]
	global_load_dwordx4 v[64:67], v[100:101], off offset:1024
	v_mfma_f32_32x32x16_bf16 v[0:15], v[68:71], v[96:99], v[0:15]
	global_load_dwordx4 v[68:71], v[102:103], off offset:1024
	ds_read_b128 v[96:99], v84 offset:18496
	s_waitcnt lgkmcnt(0)
	v_mfma_f32_32x32x16_bf16 v[16:31], v[56:59], v[96:99], v[16:31]
	global_load_dwordx4 v[56:59], v[100:101], off offset:2048
	v_mfma_f32_32x32x16_bf16 v[0:15], v[60:63], v[96:99], v[0:15]
	global_load_dwordx4 v[60:63], v[102:103], off offset:2048
	ds_read_b128 v[96:99], v84 offset:18528
	s_waitcnt lgkmcnt(0)
	v_mfma_f32_32x32x16_bf16 v[16:31], v[32:35], v[96:99], v[16:31]
	global_load_dwordx4 v[32:35], v[100:101], off offset:3072
	v_mfma_f32_32x32x16_bf16 v[0:15], v[52:55], v[96:99], v[0:15]
	global_load_dwordx4 v[52:55], v[102:103], off offset:3072
	ds_write_b128 v74, v[36:39]
	ds_write_b128 v74, v[40:43] offset:4608
	ds_write_b128 v74, v[44:47] offset:9216
	ds_write_b128 v74, v[48:51] offset:13824
	global_load_dwordx4 v[36:39], v[82:83], off offset:1664
	global_load_dwordx4 v[40:43], v[80:81], off offset:1664
	global_load_dwordx4 v[44:47], v[78:79], off offset:1664
	global_load_dwordx4 v[48:51], v[76:77], off offset:1664
	s_waitcnt lgkmcnt(0)
	s_barrier
	ds_read_b128 v[96:99], v84
	s_mov_b32 s11, 0x70d000
	v_add_co_u32_e32 v100, vcc, s11, v72
	s_mov_b32 s11, 0x71d000
	s_nop 0
	v_addc_co_u32_e32 v101, vcc, 0, v73, vcc
	v_add_co_u32_e32 v102, vcc, s11, v72
	s_waitcnt lgkmcnt(0)
	v_mfma_f32_32x32x16_bf16 v[16:31], v[92:95], v[96:99], v[16:31]
	v_addc_co_u32_e32 v103, vcc, 0, v73, vcc
	global_load_dwordx4 v[92:95], v[100:101], off
	s_waitcnt vmcnt(0)
	v_mfma_f32_32x32x16_bf16 v[0:15], v[88:91], v[96:99], v[0:15]
	global_load_dwordx4 v[88:91], v[102:103], off
	ds_read_b128 v[96:99], v84 offset:32
	s_waitcnt lgkmcnt(0)
	v_mfma_f32_32x32x16_bf16 v[16:31], v[64:67], v[96:99], v[16:31]
	global_load_dwordx4 v[64:67], v[100:101], off offset:1024
	v_mfma_f32_32x32x16_bf16 v[0:15], v[68:71], v[96:99], v[0:15]
	global_load_dwordx4 v[68:71], v[102:103], off offset:1024
	ds_read_b128 v[96:99], v84 offset:64
	s_waitcnt lgkmcnt(0)
	v_mfma_f32_32x32x16_bf16 v[16:31], v[56:59], v[96:99], v[16:31]
	global_load_dwordx4 v[56:59], v[100:101], off offset:2048
	v_mfma_f32_32x32x16_bf16 v[0:15], v[60:63], v[96:99], v[0:15]
	global_load_dwordx4 v[60:63], v[102:103], off offset:2048
	ds_read_b128 v[96:99], v84 offset:96
	s_waitcnt lgkmcnt(0)
	v_mfma_f32_32x32x16_bf16 v[16:31], v[32:35], v[96:99], v[16:31]
	global_load_dwordx4 v[32:35], v[100:101], off offset:3072
	v_mfma_f32_32x32x16_bf16 v[0:15], v[52:55], v[96:99], v[0:15]
	global_load_dwordx4 v[52:55], v[102:103], off offset:3072
	ds_write_b128 v74, v[48:51] offset:18432
	ds_write_b128 v74, v[44:47] offset:23040
	ds_write_b128 v74, v[40:43] offset:27648
	ds_write_b128 v74, v[36:39] offset:32256
	global_load_dwordx4 v[36:39], v[76:77], off offset:1792
	global_load_dwordx4 v[40:43], v[78:79], off offset:1792
	global_load_dwordx4 v[44:47], v[80:81], off offset:1792
	global_load_dwordx4 v[48:51], v[82:83], off offset:1792
	s_waitcnt lgkmcnt(0)
	s_barrier
	ds_read_b128 v[96:99], v84 offset:18432
	s_mov_b32 s11, 0x70e000
	v_add_co_u32_e32 v100, vcc, s11, v72
	s_mov_b32 s11, 0x71e000
	s_nop 0
	v_addc_co_u32_e32 v101, vcc, 0, v73, vcc
	v_add_co_u32_e32 v102, vcc, s11, v72
	s_waitcnt lgkmcnt(0)
	v_mfma_f32_32x32x16_bf16 v[16:31], v[92:95], v[96:99], v[16:31]
	v_addc_co_u32_e32 v103, vcc, 0, v73, vcc
	global_load_dwordx4 v[92:95], v[100:101], off
	s_waitcnt vmcnt(0)
	v_mfma_f32_32x32x16_bf16 v[0:15], v[88:91], v[96:99], v[0:15]
	global_load_dwordx4 v[88:91], v[102:103], off
	ds_read_b128 v[96:99], v84 offset:18464
	s_waitcnt lgkmcnt(0)
	v_mfma_f32_32x32x16_bf16 v[16:31], v[64:67], v[96:99], v[16:31]
	global_load_dwordx4 v[64:67], v[100:101], off offset:1024
	v_mfma_f32_32x32x16_bf16 v[0:15], v[68:71], v[96:99], v[0:15]
	global_load_dwordx4 v[68:71], v[102:103], off offset:1024
	ds_read_b128 v[96:99], v84 offset:18496
	s_waitcnt lgkmcnt(0)
	v_mfma_f32_32x32x16_bf16 v[16:31], v[56:59], v[96:99], v[16:31]
	global_load_dwordx4 v[56:59], v[100:101], off offset:2048
	v_mfma_f32_32x32x16_bf16 v[0:15], v[60:63], v[96:99], v[0:15]
	global_load_dwordx4 v[60:63], v[102:103], off offset:2048
	ds_read_b128 v[96:99], v84 offset:18528
	s_waitcnt lgkmcnt(0)
	v_mfma_f32_32x32x16_bf16 v[16:31], v[32:35], v[96:99], v[16:31]
	global_load_dwordx4 v[32:35], v[100:101], off offset:3072
	v_mfma_f32_32x32x16_bf16 v[0:15], v[52:55], v[96:99], v[0:15]
	global_load_dwordx4 v[52:55], v[102:103], off offset:3072
	ds_write_b128 v74, v[36:39]
	ds_write_b128 v74, v[40:43] offset:4608
	ds_write_b128 v74, v[44:47] offset:9216
	ds_write_b128 v74, v[48:51] offset:13824
	global_load_dwordx4 v[36:39], v[82:83], off offset:1920
	global_load_dwordx4 v[40:43], v[80:81], off offset:1920
	global_load_dwordx4 v[44:47], v[78:79], off offset:1920
	global_load_dwordx4 v[48:51], v[76:77], off offset:1920
	s_waitcnt lgkmcnt(0)
	s_barrier
	ds_read_b128 v[76:79], v84
	s_mov_b32 s11, 0x70f000
	s_waitcnt lgkmcnt(0)
	v_mfma_f32_32x32x16_bf16 v[16:31], v[92:95], v[76:79], v[16:31]
	v_add_co_u32_e32 v92, vcc, s11, v72
	s_mov_b32 s11, 0x71f000
	s_nop 0
	v_addc_co_u32_e32 v93, vcc, 0, v73, vcc
	v_add_co_u32_e32 v72, vcc, s11, v72
	global_load_dwordx4 v[80:83], v[92:93], off
	s_nop 0
	v_addc_co_u32_e32 v73, vcc, 0, v73, vcc
	s_waitcnt vmcnt(0)
	v_mfma_f32_32x32x16_bf16 v[0:15], v[88:91], v[76:79], v[0:15]
	global_load_dwordx4 v[76:79], v[72:73], off
	ds_read_b128 v[88:91], v84 offset:32
	s_waitcnt lgkmcnt(0)
	v_mfma_f32_32x32x16_bf16 v[16:31], v[64:67], v[88:91], v[16:31]
	global_load_dwordx4 v[64:67], v[92:93], off offset:1024
	v_mfma_f32_32x32x16_bf16 v[0:15], v[68:71], v[88:91], v[0:15]
	global_load_dwordx4 v[68:71], v[72:73], off offset:1024
	ds_read_b128 v[88:91], v84 offset:64
	s_waitcnt lgkmcnt(0)
	v_mfma_f32_32x32x16_bf16 v[16:31], v[56:59], v[88:91], v[16:31]
	global_load_dwordx4 v[56:59], v[92:93], off offset:2048
	v_mfma_f32_32x32x16_bf16 v[0:15], v[60:63], v[88:91], v[0:15]
	global_load_dwordx4 v[60:63], v[72:73], off offset:2048
	ds_read_b128 v[88:91], v84 offset:96
	s_waitcnt lgkmcnt(0)
	v_mfma_f32_32x32x16_bf16 v[16:31], v[32:35], v[88:91], v[16:31]
	global_load_dwordx4 v[32:35], v[92:93], off offset:3072
	v_mfma_f32_32x32x16_bf16 v[0:15], v[52:55], v[88:91], v[0:15]
	global_load_dwordx4 v[52:55], v[72:73], off offset:3072
	ds_write_b128 v74, v[48:51] offset:18432
	ds_write_b128 v74, v[44:47] offset:23040
	ds_write_b128 v74, v[40:43] offset:27648
	ds_write_b128 v74, v[36:39] offset:32256
	s_waitcnt lgkmcnt(0)
	s_barrier
	ds_read_b128 v[36:39], v84 offset:18432
	s_waitcnt lgkmcnt(0)
	v_mfma_f32_32x32x16_bf16 v[16:31], v[80:83], v[36:39], v[16:31]
	s_waitcnt vmcnt(0)
	v_mfma_f32_32x32x16_bf16 v[0:15], v[76:79], v[36:39], v[0:15]
	ds_read_b128 v[36:39], v84 offset:18464
	s_waitcnt lgkmcnt(0)
	v_mfma_f32_32x32x16_bf16 v[16:31], v[64:67], v[36:39], v[16:31]
	v_mfma_f32_32x32x16_bf16 v[0:15], v[68:71], v[36:39], v[0:15]
	ds_read_b128 v[36:39], v84 offset:18496
	s_waitcnt lgkmcnt(0)
	v_mfma_f32_32x32x16_bf16 v[16:31], v[56:59], v[36:39], v[16:31]
	v_mfma_f32_32x32x16_bf16 v[0:15], v[60:63], v[36:39], v[0:15]
	ds_read_b128 v[36:39], v84 offset:18528
	s_waitcnt lgkmcnt(0)
	v_mfma_f32_32x32x16_bf16 v[16:31], v[32:35], v[36:39], v[16:31]
	v_mfma_f32_32x32x16_bf16 v[0:15], v[52:55], v[36:39], v[0:15]
	v_add_u32_e32 v32, s10, v75
	v_ashrrev_i32_e32 v33, 31, v32
	v_lshl_add_u64 v[34:35], v[32:33], 2, s[8:9]
	s_barrier
	global_load_dword v34, v[34:35], off
	v_mov_b64_e32 v[36:37], s[2:3]
	v_cmp_gt_u32_e32 vcc, 32, v86
	v_mad_i64_i32 v[32:33], s[14:15], v32, s23, v[36:37]
	s_nop 0
	v_cndmask_b32_e64 v192, 16, 0, vcc
	v_lshl_add_u64 v[32:33], v[32:33], 0, v[192:193]
	s_mov_b32 s11, 0x3dd1000
	s_mov_b64 s[14:15], 0x3dd1c00
	v_lshl_add_u64 v[36:37], v[32:33], 0, s[14:15]
	s_add_i32 s20, s20, s22
	s_add_i32 s10, s10, s16
	s_cmpk_lt_i32 s20, 0x180
	s_waitcnt vmcnt(0) lgkmcnt(0)
	v_pk_mul_f32 v[16:17], v[16:17], v[34:35] op_sel_hi:[1,0]
	v_pk_mul_f32 v[18:19], v[18:19], v[34:35] op_sel_hi:[1,0]
	v_pk_mul_f32 v[20:21], v[20:21], v[34:35] op_sel_hi:[1,0]
	v_pk_mul_f32 v[22:23], v[22:23], v[34:35] op_sel_hi:[1,0]
	v_pk_mul_f32 v[0:1], v[0:1], v[34:35] op_sel_hi:[1,0]
	v_pk_mul_f32 v[2:3], v[2:3], v[34:35] op_sel_hi:[1,0]
	v_pk_mul_f32 v[4:5], v[4:5], v[34:35] op_sel_hi:[1,0]
	v_pk_mul_f32 v[6:7], v[6:7], v[34:35] op_sel_hi:[1,0]
	v_cvt_pk_bf16_f32 v16, v16, v17
	v_cvt_pk_bf16_f32 v17, v18, v19
	v_cvt_pk_bf16_f32 v18, v20, v21
	v_cvt_pk_bf16_f32 v19, v22, v23
	v_add_co_u32_e32 v20, vcc, s11, v32
	v_cvt_pk_bf16_f32 v0, v0, v1
	v_cvt_pk_bf16_f32 v1, v2, v3
	v_cvt_pk_bf16_f32 v2, v4, v5
	v_cvt_pk_bf16_f32 v3, v6, v7
	v_permlane32_swap_b32_e32 v16, v18
	v_permlane32_swap_b32_e32 v17, v19
	v_addc_co_u32_e32 v21, vcc, 0, v33, vcc
	v_permlane32_swap_b32_e32 v0, v2
	v_permlane32_swap_b32_e32 v1, v3
	global_store_dwordx4 v[20:21], v[16:19], off offset:3072
	v_pk_mul_f32 v[20:21], v[28:29], v[34:35] op_sel_hi:[1,0]
	v_pk_mul_f32 v[22:23], v[30:31], v[34:35] op_sel_hi:[1,0]
	v_pk_mul_f32 v[16:17], v[24:25], v[34:35] op_sel_hi:[1,0]
	v_pk_mul_f32 v[18:19], v[26:27], v[34:35] op_sel_hi:[1,0]
	global_store_dwordx4 v[36:37], v[0:3], off offset:64
	v_pk_mul_f32 v[4:5], v[12:13], v[34:35] op_sel_hi:[1,0]
	v_pk_mul_f32 v[6:7], v[14:15], v[34:35] op_sel_hi:[1,0]
	v_pk_mul_f32 v[0:1], v[8:9], v[34:35] op_sel_hi:[1,0]
	v_pk_mul_f32 v[2:3], v[10:11], v[34:35] op_sel_hi:[1,0]
	v_cvt_pk_bf16_f32 v16, v16, v17
	v_cvt_pk_bf16_f32 v17, v18, v19
	v_cvt_pk_bf16_f32 v18, v20, v21
	v_cvt_pk_bf16_f32 v19, v22, v23
	v_cvt_pk_bf16_f32 v0, v0, v1
	v_cvt_pk_bf16_f32 v1, v2, v3
	v_cvt_pk_bf16_f32 v2, v4, v5
	v_cvt_pk_bf16_f32 v3, v6, v7
	v_permlane32_swap_b32_e32 v16, v18
	v_permlane32_swap_b32_e32 v17, v19
	v_permlane32_swap_b32_e32 v0, v2
	v_permlane32_swap_b32_e32 v1, v3
	global_store_dwordx4 v[36:37], v[16:19], off offset:32
	global_store_dwordx4 v[36:37], v[0:3], off offset:96
	s_cbranch_scc1 .LBB0_316

.LBB0_374:
	v_mov_b32_e32 v198, v234
	s_nop 0
	v_cmp_eq_u32_e64 s[0:1], 0, v198
	s_barrier
	s_and_saveexec_b64 s[8:9], s[0:1]
	s_cbranch_execz .LBB0_376
	v_readlane_b32 s10, v253, 59
	v_readlane_b32 s11, v253, 60
	s_nop 1
	v_mov_b64_e32 v[0:1], s[10:11]
	global_atomic_add v0, v[0:1], v251, off sc0
	s_waitcnt vmcnt(0) lgkmcnt(0)
	ds_write_b32 v222, v0
.LBB0_376:
	s_or_b64 exec, exec, s[8:9]
	s_waitcnt lgkmcnt(0)
	s_barrier
	ds_read_b32 v0, v222
	s_waitcnt lgkmcnt(0)
	v_readfirstlane_b32 s8, v0
	s_nop 1
	v_writelane_b32 v254, s8, 45
	s_movk_i32 s8, 0x400
	v_cmp_gt_i32_e32 vcc, s8, v0
	v_readlane_b32 s8, v254, 41
	v_readlane_b32 s9, v254, 42
	s_or_b64 s[8:9], vcc, s[8:9]
	s_and_b64 vcc, exec, s[8:9]
	s_cbranch_vccnz .LBB0_381
	s_waitcnt vmcnt(0)
	s_barrier
	s_and_saveexec_b64 s[8:9], s[0:1]
	s_cbranch_execz .LBB0_380
	ds_read_b32 v1, v227
	ds_read_b32 v192, v223
	v_readlane_b32 s10, v253, 49
	v_readlane_b32 s11, v253, 50
	s_waitcnt lgkmcnt(0)
	v_lshlrev_b64 v[2:3], 2, v[192:193]
	v_lshl_add_u64 v[2:3], s[10:11], 0, v[2:3]
	global_atomic_add v2, v[2:3], v251, off sc0
	s_waitcnt vmcnt(0) lgkmcnt(0)
	v_add_u32_e32 v2, 1, v2
	v_cmp_eq_u32_e32 vcc, v2, v1
	s_and_b64 exec, exec, vcc
	s_cbranch_execz .LBB0_380
	v_readlane_b32 s10, v253, 51
	v_readlane_b32 s11, v253, 52
	buffer_wbl2 sc1
	s_waitcnt vmcnt(0)
	s_nop 0
	v_mov_b64_e32 v[2:3], s[10:11]
	global_atomic_add v[2:3], v251, off

.LBB0_398:
	v_readlane_b32 s12, v254, 50
	v_ashrrev_i32_e32 v0, 1, v198
	s_lshl_b32 s13, s12, 7
	v_and_b32_e32 v11, 0xffffffe0, v0
	v_and_b32_e32 v10, 31, v198
	v_add_u32_e32 v0, s13, v11
	s_lshl_b32 s1, s10, 9
	s_and_b32 s0, s10, 3
	v_or_b32_e32 v0, v0, v10
	s_and_b32 s1, s1, 0x7ffff800
	s_mov_b64 s[10:11], 0x3e38aa3b
	v_bfe_u32 v12, v198, 5, 1
	s_add_i32 s8, s1, 0xffffc000
	s_mov_b32 s9, s11
	v_ashrrev_i32_e32 v1, 31, v0
	s_waitcnt vmcnt(0)
	v_lshl_add_u64 v[142:143], v[0:1], 0, s[8:9]
	s_lshl_b32 s10, s0, 6
	v_lshlrev_b32_e32 v1, 3, v12
	v_mov_b32_e32 v63, 0
	v_readfirstlane_b32 s11, v0
	s_cmp_lt_i32 s12, 0
	v_lshlrev_b32_e32 v140, 1, v1
	v_mov_b32_e32 v62, v63
	v_mov_b32_e32 v61, v63
	v_mov_b32_e32 v60, v63
	v_mov_b32_e32 v59, v63
	v_mov_b32_e32 v58, v63
	v_mov_b32_e32 v57, v63
	v_mov_b32_e32 v56, v63
	v_mov_b32_e32 v55, v63
	v_mov_b32_e32 v54, v63
	v_mov_b32_e32 v53, v63
	v_mov_b32_e32 v52, v63
	v_mov_b32_e32 v51, v63
	v_mov_b32_e32 v50, v63
	v_mov_b32_e32 v49, v63
	v_mov_b32_e32 v48, v63
	v_mov_b32_e32 v47, v63
	v_mov_b32_e32 v46, v63
	v_mov_b32_e32 v45, v63
	v_mov_b32_e32 v44, v63
	v_mov_b32_e32 v43, v63
	v_mov_b32_e32 v42, v63
	v_mov_b32_e32 v41, v63
	v_mov_b32_e32 v40, v63
	v_mov_b32_e32 v39, v63
	v_mov_b32_e32 v38, v63
	v_mov_b32_e32 v37, v63
	v_mov_b32_e32 v36, v63
	v_mov_b32_e32 v35, v63
	v_mov_b32_e32 v34, v63
	v_mov_b32_e32 v33, v63
	v_mov_b32_e32 v32, v63
	v_mov_b32_e32 v163, v63
	s_cbranch_scc1 .LBB0_411
	v_readlane_b32 s14, v253, 61
	v_readlane_b32 s15, v253, 62
	s_movk_i32 s18, 0x300
	v_readlane_b32 s16, v253, 63
	v_mov_b64_e32 v[0:1], s[14:15]
	v_mad_u64_u32 v[0:1], s[14:15], v142, s18, v[0:1]
	s_mul_i32 s14, s0, 0xc0
	s_mov_b64 s[0:1], 0x3e38aa3b
	s_mov_b32 s15, s1
	s_lshl_b64 s[0:1], s[8:9], 9
	v_readlane_b32 s17, v254, 0
	s_add_u32 s0, s16, s0
	v_mad_i32_i24 v1, v143, s18, v1
	s_addc_u32 s1, s17, s1
	s_lshl_b32 s9, s10, 1
	v_lshl_add_u64 v[0:1], v[0:1], 0, s[14:15]
	v_mov_b32_e32 v141, v193
	s_add_u32 s0, s0, s9
	v_lshl_add_u64 v[0:1], v[0:1], 0, v[140:141]
	s_addc_u32 s1, s1, 0
	s_mul_hi_u32 s9, s8, 0x300
	s_mulk_i32 s8, 0x300
	v_readlane_b32 s16, v254, 1
	s_mov_b32 s15, 0x2aaaaaab
	global_load_dwordx4 v[96:99], v[0:1], off
	global_load_dwordx4 v[100:103], v[0:1], off offset:32
	global_load_dwordx4 v[104:107], v[0:1], off offset:64
	global_load_dwordx4 v[108:111], v[0:1], off offset:96
	global_load_dwordx4 v[112:115], v[0:1], off offset:128
	global_load_dwordx4 v[116:119], v[0:1], off offset:160
	v_readlane_b32 s17, v254, 2
	s_add_u32 s8, s16, s8
	v_mul_hi_i32 v0, v198, s15
	s_addc_u32 s9, s17, s9
	v_lshrrev_b32_e32 v1, 31, v0
	v_ashrrev_i32_e32 v0, 1, v0
	s_add_u32 s8, s8, s14
	v_readlane_b32 s12, v254, 50
	v_add_u32_e32 v141, v0, v1
	s_addc_u32 s9, s9, 0
	s_lshl_b32 s14, s12, 1
	s_or_b32 s12, s13, 64
	v_mul_lo_u32 v0, v141, 12
	v_sub_u32_e32 v13, v198, v0
	v_add_u32_e32 v0, s12, v141
	v_mov_b64_e32 v[8:9], s[8:9]
	v_mad_i64_i32 v[2:3], s[16:17], v0, s18, v[8:9]
	v_lshlrev_b32_e32 v0, 3, v13
	v_ashrrev_i32_e32 v1, 31, v0
	v_lshlrev_b64 v[0:1], 1, v[0:1]
	v_lshl_add_u64 v[2:3], v[2:3], 0, v[0:1]
	global_load_dwordx4 v[14:17], v[2:3], off
	v_add_u32_e32 v2, 0x100, v198
	v_mul_hi_i32 v3, v2, s15
	v_lshrrev_b32_e32 v4, 31, v3
	v_ashrrev_i32_e32 v3, 1, v3
	v_add_u32_e32 v152, v3, v4
	v_mul_lo_u32 v3, v152, 12
	v_sub_u32_e32 v36, v2, v3
	v_add_u32_e32 v2, s12, v152
	v_mad_i64_i32 v[4:5], s[16:17], v2, s18, v[8:9]
	v_lshlrev_b32_e32 v2, 3, v36
	v_ashrrev_i32_e32 v3, 31, v2
	v_lshlrev_b64 v[2:3], 1, v[2:3]
	v_lshl_add_u64 v[4:5], v[4:5], 0, v[2:3]
	global_load_dwordx4 v[18:21], v[4:5], off
	v_add_u32_e32 v4, 0x200, v198
	v_mul_hi_i32 v5, v4, s15
	v_lshrrev_b32_e32 v6, 31, v5
	v_ashrrev_i32_e32 v5, 1, v5
	v_add_u32_e32 v153, v5, v6
	v_mul_lo_u32 v5, v153, 12
	v_sub_u32_e32 v37, v4, v5
	v_add_u32_e32 v4, s12, v153
	v_mad_i64_i32 v[6:7], s[16:17], v4, s18, v[8:9]
	v_lshlrev_b32_e32 v4, 3, v37
	v_ashrrev_i32_e32 v5, 31, v4
	v_lshlrev_b64 v[4:5], 1, v[4:5]
	v_lshlrev_b32_e32 v154, 1, v10
	v_lshl_add_u64 v[6:7], v[6:7], 0, v[4:5]
	v_or_b32_e32 v192, s12, v154
	global_load_dwordx4 v[22:25], v[6:7], off
	v_lshlrev_b64 v[6:7], 9, v[192:193]
	v_lshl_add_u64 v[26:27], s[0:1], 0, v[6:7]
	v_ashrrev_i32_e32 v6, 2, v198
	v_and_b32_e32 v34, -8, v6
	v_ashrrev_i32_e32 v35, 31, v34
	v_or_b32_e32 v192, 1, v192
	v_lshlrev_b64 v[6:7], 1, v[34:35]
	v_lshlrev_b64 v[30:31], 9, v[192:193]
	v_lshl_add_u64 v[26:27], v[26:27], 0, v[6:7]
	v_lshl_add_u64 v[30:31], s[0:1], 0, v[30:31]
	global_load_dwordx4 v[26:29], v[26:27], off
	v_lshl_add_u64 v[30:31], v[30:31], 0, v[6:7]
	global_load_dwordx4 v[30:33], v[30:31], off
	s_movk_i32 s12, 0xd0
	v_mul_lo_u32 v156, v141, s12
	v_lshlrev_b32_e32 v157, 4, v13
	v_add_u32_e32 v13, v156, v157
	v_mul_lo_u32 v158, v152, s12
	v_lshlrev_b32_e32 v159, 4, v36
	s_waitcnt lgkmcnt(0)
	s_barrier
	v_mul_lo_u32 v160, v153, s12
	v_lshlrev_b32_e32 v161, 4, v37
	v_mul_lo_u32 v155, v34, 34
	v_lshlrev_b32_e32 v162, 2, v10
	s_mov_b32 s12, 0xffff0000
	v_or_b32_e32 v192, s13, v154
	v_lshlrev_b32_e32 v165, 2, v12
	v_lshl_add_u64 v[146:147], s[8:9], 0, v[0:1]
	v_mov_b32_e32 v163, 0
	v_lshl_add_u64 v[144:145], s[0:1], 0, v[6:7]
	v_mul_u32_u24_e32 v164, 0xd0, v10
	v_mul_u32_u24_e32 v166, 0x88, v10
	v_lshl_add_u64 v[148:149], s[8:9], 0, v[2:3]
	v_lshl_add_u64 v[150:151], s[8:9], 0, v[4:5]
	s_add_i32 s8, s13, 0x7f
	s_mov_b32 s9, 0
	v_mov_b32_e32 v169, 0xf149f2ca
	v_mov_b32_e32 v167, s14
	v_mov_b32_e32 v34, v163
	v_mov_b32_e32 v35, v163
	v_mov_b32_e32 v36, v163
	v_mov_b32_e32 v37, v163
	v_mov_b32_e32 v38, v163
	v_mov_b32_e32 v39, v163
	v_mov_b32_e32 v40, v163
	s_waitcnt vmcnt(4)
	ds_write_b128 v13, v[14:17]
	v_add_u32_e32 v13, v158, v159
	v_mov_b32_e32 v41, v163
	v_mov_b32_e32 v42, v163
	v_mov_b32_e32 v43, v163
	v_mov_b32_e32 v44, v163
	v_mov_b32_e32 v45, v163
	v_mov_b32_e32 v46, v163
	v_mov_b32_e32 v47, v163
	v_mov_b32_e32 v48, 0
	v_mov_b32_e32 v49, v163
	v_mov_b32_e32 v50, v163
	v_mov_b32_e32 v51, v163
	v_mov_b32_e32 v52, v163
	v_mov_b32_e32 v53, v163
	s_waitcnt vmcnt(3)
	ds_write_b128 v13, v[18:21]
	v_add_u32_e32 v13, v160, v161
	v_mov_b32_e32 v54, v163
	v_mov_b32_e32 v55, v163
	v_mov_b32_e32 v56, v163
	v_mov_b32_e32 v57, v163
	v_mov_b32_e32 v58, v163
	v_mov_b32_e32 v59, v163
	v_mov_b32_e32 v60, v163
	v_mov_b32_e32 v61, v163
	v_mov_b32_e32 v62, v163
	v_mov_b32_e32 v63, v163
	s_waitcnt vmcnt(2)
	ds_write_b128 v13, v[22:25]
	v_lshl_add_u32 v13, v155, 2, v162
	v_add_u32_e32 v13, 0x3400, v13
	s_waitcnt vmcnt(1)
	v_and_b32_e32 v14, 0xffff, v26
	v_lshrrev_b32_e32 v15, 16, v26
	s_waitcnt vmcnt(0)
	v_lshl_or_b32 v14, v30, 16, v14
	v_and_or_b32 v15, v30, s12, v15
	ds_write2_b32 v13, v14, v15 offset1:34
	v_and_b32_e32 v14, 0xffff, v27
	v_lshrrev_b32_e32 v15, 16, v27
	v_lshl_or_b32 v14, v31, 16, v14
	v_and_or_b32 v15, v31, s12, v15
	ds_write2_b32 v13, v14, v15 offset0:68 offset1:102
	v_and_b32_e32 v14, 0xffff, v28
	v_lshrrev_b32_e32 v15, 16, v28
	v_lshl_or_b32 v14, v32, 16, v14
	v_and_or_b32 v15, v32, s12, v15
	ds_write2_b32 v13, v14, v15 offset0:136 offset1:170
	v_and_b32_e32 v14, 0xffff, v29
	v_lshrrev_b32_e32 v15, 16, v29
	v_lshl_or_b32 v14, v33, 16, v14
	v_and_or_b32 v15, v33, s12, v15
	ds_write2_b32 v13, v14, v15 offset0:204 offset1:238
	v_add_u32_e32 v13, s13, v141
	v_mad_i64_i32 v[14:15], s[16:17], v13, s18, v[8:9]
	v_lshl_add_u64 v[14:15], v[14:15], 0, v[0:1]
	v_add_u32_e32 v13, s13, v152
	global_load_dwordx4 v[120:123], v[14:15], off
	v_mad_i64_i32 v[14:15], s[16:17], v13, s18, v[8:9]
	v_add_u32_e32 v13, s13, v153
	v_mad_i64_i32 v[8:9], s[16:17], v13, s18, v[8:9]
	v_lshl_add_u64 v[14:15], v[14:15], 0, v[2:3]
	v_lshl_add_u64 v[8:9], v[8:9], 0, v[4:5]
	global_load_dwordx4 v[124:127], v[14:15], off
	global_load_dwordx4 v[128:131], v[8:9], off
	v_lshlrev_b64 v[8:9], 9, v[192:193]
	v_lshl_add_u64 v[8:9], s[0:1], 0, v[8:9]
	v_lshl_add_u64 v[8:9], v[8:9], 0, v[6:7]
	v_or_b32_e32 v192, 1, v192
	global_load_dwordx4 v[132:135], v[8:9], off
	v_lshlrev_b64 v[8:9], 9, v[192:193]
	v_lshl_add_u64 v[8:9], s[0:1], 0, v[8:9]
	v_lshl_add_u64 v[8:9], v[8:9], 0, v[6:7]
	global_load_dwordx4 v[136:139], v[8:9], off
	v_add_u32_e32 v0, v11, v10
	v_sub_u32_e32 v0, v0, v165
	s_add_i32 s12, s11, 31
	v_subrev_u32_e32 v168, 64, v0
	v_mov_b32_e32 v32, 0
	v_mov_b32_e32 v33, v163
	s_waitcnt lgkmcnt(0)
	s_barrier
	s_branch .LBB0_401

.LBB0_401:
	s_sub_i32 s0, s8, 63
	s_cmp_gt_i32 s0, s12
	s_cbranch_scc1 .LBB0_407
	s_mul_i32 s13, s9, 0x9000
	v_add3_u32 v12, s13, v164, v140
	ds_read_b128 v[0:3], v12 offset:6656
	ds_read_b128 v[4:7], v12
	ds_read_b128 v[8:11], v12 offset:32
	s_cmp_gt_i32 s8, s11
	s_mov_b64 s[0:1], -1
	s_waitcnt lgkmcnt(2)
	v_mfma_f32_32x32x16_bf16 v[64:79], v[0:3], v[96:99], 0
	ds_read_b128 v[0:3], v12 offset:6688
	s_waitcnt lgkmcnt(2)
	v_mfma_f32_32x32x16_bf16 v[80:95], v[4:7], v[96:99], 0
	s_waitcnt lgkmcnt(1)
	v_mfma_f32_32x32x16_bf16 v[80:95], v[8:11], v[100:103], v[80:95]
	s_waitcnt lgkmcnt(0)
	v_mfma_f32_32x32x16_bf16 v[64:79], v[0:3], v[100:103], v[64:79]
	ds_read_b128 v[0:3], v12 offset:64
	ds_read_b128 v[4:7], v12 offset:6720
	s_waitcnt lgkmcnt(1)
	v_mfma_f32_32x32x16_bf16 v[80:95], v[0:3], v[104:107], v[80:95]
	s_waitcnt lgkmcnt(0)
	v_mfma_f32_32x32x16_bf16 v[64:79], v[4:7], v[104:107], v[64:79]
	ds_read_b128 v[0:3], v12 offset:96
	ds_read_b128 v[4:7], v12 offset:6752
	s_waitcnt lgkmcnt(1)
	v_mfma_f32_32x32x16_bf16 v[80:95], v[0:3], v[108:111], v[80:95]
	s_waitcnt lgkmcnt(0)
	v_mfma_f32_32x32x16_bf16 v[64:79], v[4:7], v[108:111], v[64:79]
	ds_read_b128 v[0:3], v12 offset:128
	ds_read_b128 v[4:7], v12 offset:6784
	s_waitcnt lgkmcnt(1)
	v_mfma_f32_32x32x16_bf16 v[80:95], v[0:3], v[112:115], v[80:95]
	s_waitcnt lgkmcnt(0)
	v_mfma_f32_32x32x16_bf16 v[64:79], v[4:7], v[112:115], v[64:79]
	ds_read_b128 v[0:3], v12 offset:160
	ds_read_b128 v[4:7], v12 offset:6816
	s_waitcnt lgkmcnt(1)
	v_mfma_f32_32x32x16_bf16 v[80:95], v[0:3], v[116:119], v[80:95]
	s_waitcnt lgkmcnt(0)
	v_mfma_f32_32x32x16_bf16 v[64:79], v[4:7], v[116:119], v[64:79]
	s_cbranch_scc1 .LBB0_404
	s_mov_b32 s0, 0xff61b1e6
	s_nop 8
	v_max3_f32 v0, v80, s0, v81
	v_max3_f32 v0, v0, v82, v83
	v_max3_f32 v0, v0, v84, v85
	v_max3_f32 v0, v0, v86, v87
	v_max3_f32 v0, v0, v88, v89
	v_max3_f32 v0, v0, v90, v91
	v_max3_f32 v0, v0, v92, v93
	v_max3_f32 v0, v0, v94, v95
	v_max3_f32 v0, v0, v64, v65
	v_max3_f32 v0, v0, v66, v67
	v_max3_f32 v0, v0, v68, v69
	v_max3_f32 v0, v0, v70, v71
	v_and_b32_e32 v2, 64, v225
	v_max3_f32 v0, v0, v72, v73
	v_xor_b32_e32 v1, 32, v225
	v_add_u32_e32 v2, 64, v2
	v_max3_f32 v0, v0, v74, v75
	v_cmp_lt_i32_e32 vcc, v1, v2
	v_max3_f32 v0, v0, v76, v77
	v_max3_f32 v0, v0, v78, v79
	v_cndmask_b32_e32 v1, v225, v1, vcc
	v_lshlrev_b32_e32 v1, 2, v1
	ds_bpermute_b32 v1, v1, v0
	s_mov_b32 s0, 0x3e16c740
	s_waitcnt lgkmcnt(0)
	v_max_f32_e32 v1, v1, v1
	v_max_f32_e32 v0, v0, v1
	v_mul_f32_e32 v0, 0x3e16c740, v0
	v_max_f32_e32 v1, v169, v169
	v_max_f32_e32 v170, v1, v0
	v_fma_f32 v0, v80, s0, -v170
	v_exp_f32_e32 v0, v0
	v_fma_f32 v1, v81, s0, -v170
	v_exp_f32_e32 v1, v1
	v_fma_f32 v2, v82, s0, -v170
	v_exp_f32_e32 v2, v2
	v_fma_f32 v3, v83, s0, -v170
	v_exp_f32_e32 v3, v3
	v_add_f32_e32 v4, 0, v0
	v_add_f32_e32 v4, v1, v4
	v_add_f32_e32 v4, v2, v4
	v_add_f32_e32 v8, v3, v4
	v_fma_f32 v4, v84, s0, -v170
	v_exp_f32_e32 v4, v4
	v_fma_f32 v5, v85, s0, -v170
	v_exp_f32_e32 v5, v5
	v_fma_f32 v6, v86, s0, -v170
	v_exp_f32_e32 v6, v6
	v_fma_f32 v7, v87, s0, -v170
	v_exp_f32_e32 v7, v7
	v_add_f32_e32 v8, v4, v8
	v_add_f32_e32 v8, v5, v8
	v_add_f32_e32 v8, v6, v8
	v_add_f32_e32 v12, v7, v8
	v_fma_f32 v8, v88, s0, -v170
	v_exp_f32_e32 v8, v8
	v_fma_f32 v9, v89, s0, -v170
	v_exp_f32_e32 v9, v9
	v_fma_f32 v10, v90, s0, -v170
	v_exp_f32_e32 v10, v10
	v_fma_f32 v11, v91, s0, -v170
	v_exp_f32_e32 v11, v11
	v_add_f32_e32 v12, v8, v12
	v_add_f32_e32 v12, v9, v12
	v_add_f32_e32 v12, v10, v12
	v_add_f32_e32 v16, v11, v12
	v_fma_f32 v12, v92, s0, -v170
	v_exp_f32_e32 v12, v12
	v_fma_f32 v13, v93, s0, -v170
	v_exp_f32_e32 v13, v13
	v_fma_f32 v14, v94, s0, -v170
	v_exp_f32_e32 v14, v14
	v_fma_f32 v15, v95, s0, -v170
	v_exp_f32_e32 v15, v15
	v_add_f32_e32 v16, v12, v16
	v_add_f32_e32 v16, v13, v16
	v_add_f32_e32 v16, v14, v16
	v_add_f32_e32 v20, v15, v16
	v_fma_f32 v16, v64, s0, -v170
	v_exp_f32_e32 v16, v16
	v_fma_f32 v17, v65, s0, -v170
	v_exp_f32_e32 v17, v17
	v_fma_f32 v18, v66, s0, -v170
	v_exp_f32_e32 v18, v18
	v_fma_f32 v19, v67, s0, -v170
	v_exp_f32_e32 v19, v19
	v_add_f32_e32 v20, v16, v20
	v_add_f32_e32 v20, v17, v20
	v_add_f32_e32 v20, v18, v20
	v_add_f32_e32 v24, v19, v20
	v_fma_f32 v20, v68, s0, -v170
	v_exp_f32_e32 v20, v20
	v_fma_f32 v21, v69, s0, -v170
	v_exp_f32_e32 v21, v21
	v_fma_f32 v22, v70, s0, -v170
	v_exp_f32_e32 v22, v22
	v_fma_f32 v23, v71, s0, -v170
	v_exp_f32_e32 v23, v23
	v_add_f32_e32 v24, v20, v24
	v_add_f32_e32 v24, v21, v24
	v_add_f32_e32 v24, v22, v24
	v_add_f32_e32 v28, v23, v24
	v_fma_f32 v24, v72, s0, -v170
	v_exp_f32_e32 v24, v24
	v_fma_f32 v25, v73, s0, -v170
	v_exp_f32_e32 v25, v25
	v_fma_f32 v26, v74, s0, -v170
	v_exp_f32_e32 v26, v26
	v_fma_f32 v27, v75, s0, -v170
	v_exp_f32_e32 v27, v27
	v_add_f32_e32 v28, v24, v28
	v_add_f32_e32 v28, v25, v28
	v_add_f32_e32 v28, v26, v28
	v_add_f32_e32 v171, v27, v28
	v_fma_f32 v28, v76, s0, -v170
	v_exp_f32_e32 v28, v28
	v_fma_f32 v29, v77, s0, -v170
	v_exp_f32_e32 v29, v29
	v_fma_f32 v30, v78, s0, -v170
	v_exp_f32_e32 v30, v30
	v_fma_f32 v31, v79, s0, -v170
	v_exp_f32_e32 v31, v31
	v_add_f32_e32 v171, v28, v171
	v_add_f32_e32 v171, v29, v171
	v_add_f32_e32 v171, v30, v171
	v_add_f32_e32 v171, v31, v171
	s_mov_b64 s[0:1], 0

.LBB0_406:
	s_nop 8
	v_sub_f32_e32 v64, v169, v170
	v_exp_f32_e32 v68, v64
	v_lshlrev_b32_e32 v64, 1, v165
	v_cvt_pk_bf16_f32 v0, v0, v1
	v_cvt_pk_bf16_f32 v1, v2, v3
	v_pk_mul_f32 v[62:63], v[62:63], v[68:69] op_sel_hi:[1,0]
	v_pk_mul_f32 v[60:61], v[60:61], v[68:69] op_sel_hi:[1,0]
	v_pk_mul_f32 v[58:59], v[58:59], v[68:69] op_sel_hi:[1,0]
	v_pk_mul_f32 v[56:57], v[56:57], v[68:69] op_sel_hi:[1,0]
	v_pk_mul_f32 v[54:55], v[54:55], v[68:69] op_sel_hi:[1,0]
	v_pk_mul_f32 v[52:53], v[52:53], v[68:69] op_sel_hi:[1,0]
	v_pk_mul_f32 v[50:51], v[50:51], v[68:69] op_sel_hi:[1,0]
	v_add3_u32 v69, s13, v166, v64
	v_add_u32_e32 v70, 0x3000, v69
	v_pk_mul_f32 v[48:49], v[48:49], v[68:69] op_sel_hi:[1,0]
	v_pk_mul_f32 v[46:47], v[46:47], v[68:69] op_sel_hi:[1,0]
	v_add_u32_e32 v69, 0x4000, v69
	ds_read2_b64 v[64:67], v70 offset0:128 offset1:130
	v_cvt_pk_bf16_f32 v2, v4, v5
	v_cvt_pk_bf16_f32 v3, v6, v7
	ds_read2_b64 v[4:7], v69 offset0:160 offset1:162
	v_pk_mul_f32 v[44:45], v[44:45], v[68:69] op_sel_hi:[1,0]
	v_pk_mul_f32 v[42:43], v[42:43], v[68:69] op_sel_hi:[1,0]
	v_pk_mul_f32 v[40:41], v[40:41], v[68:69] op_sel_hi:[1,0]
	v_pk_mul_f32 v[38:39], v[38:39], v[68:69] op_sel_hi:[1,0]
	v_pk_mul_f32 v[36:37], v[36:37], v[68:69] op_sel_hi:[1,0]
	v_pk_mul_f32 v[34:35], v[34:35], v[68:69] op_sel_hi:[1,0]
	v_pk_mul_f32 v[32:33], v[32:33], v[68:69] op_sel_hi:[1,0]
	s_waitcnt lgkmcnt(1)
	v_mfma_f32_32x32x16_bf16 v[48:63], v[64:67], v[0:3], v[48:63]
	v_fmac_f32_e32 v171, v163, v68
	v_mov_b32_e32 v169, v170
	v_mov_b32_e32 v163, v171
	s_waitcnt lgkmcnt(0)
	v_mfma_f32_32x32x16_bf16 v[32:47], v[4:7], v[0:3], v[32:47]
	ds_read2_b64 v[0:3], v70 offset0:132 offset1:134
	v_cvt_pk_bf16_f32 v4, v8, v9
	v_cvt_pk_bf16_f32 v5, v10, v11
	v_cvt_pk_bf16_f32 v6, v12, v13
	v_cvt_pk_bf16_f32 v7, v14, v15
	s_nop 0
	s_nop 0
	s_waitcnt lgkmcnt(0)
	v_mfma_f32_32x32x16_bf16 v[48:63], v[0:3], v[4:7], v[48:63]
	ds_read2_b64 v[0:3], v69 offset0:164 offset1:166
	s_waitcnt lgkmcnt(0)
	v_mfma_f32_32x32x16_bf16 v[32:47], v[0:3], v[4:7], v[32:47]
	ds_read2_b64 v[0:3], v70 offset0:136 offset1:138
	v_cvt_pk_bf16_f32 v4, v16, v17
	v_cvt_pk_bf16_f32 v5, v18, v19
	v_cvt_pk_bf16_f32 v6, v20, v21
	v_cvt_pk_bf16_f32 v7, v22, v23
	s_nop 0
	s_nop 0
	s_waitcnt lgkmcnt(0)
	v_mfma_f32_32x32x16_bf16 v[48:63], v[0:3], v[4:7], v[48:63]
	ds_read2_b64 v[0:3], v69 offset0:168 offset1:170
	s_waitcnt lgkmcnt(0)
	v_mfma_f32_32x32x16_bf16 v[32:47], v[0:3], v[4:7], v[32:47]
	ds_read2_b64 v[0:3], v70 offset0:140 offset1:142
	v_cvt_pk_bf16_f32 v4, v24, v25
	v_cvt_pk_bf16_f32 v5, v26, v27
	v_cvt_pk_bf16_f32 v6, v28, v29
	v_cvt_pk_bf16_f32 v7, v30, v31
	s_nop 0
	s_nop 0
	s_waitcnt lgkmcnt(0)
	v_mfma_f32_32x32x16_bf16 v[48:63], v[0:3], v[4:7], v[48:63]
	ds_read2_b64 v[0:3], v69 offset0:172 offset1:174
	s_waitcnt lgkmcnt(0)
	v_mfma_f32_32x32x16_bf16 v[32:47], v[0:3], v[4:7], v[32:47]
.LBB0_407:
	v_cmp_gt_i32_e32 vcc, 0, v167
	s_cbranch_vccnz .LBB0_410
	s_xor_b32 s9, s9, 1
	s_mul_i32 s0, s9, 0x9000
	v_add3_u32 v1, s0, v156, v157
	s_waitcnt vmcnt(0)
	ds_write_b128 v1, v[120:123]
	v_add3_u32 v1, s0, v158, v159
	v_lshlrev_b32_e32 v0, 2, v155
	ds_write_b128 v1, v[124:127]
	v_add3_u32 v1, s0, v160, v161
	ds_write_b128 v1, v[128:131]
	v_add3_u32 v0, s0, v0, v162
	v_lshlrev_b32_e32 v1, 16, v136
	s_mov_b32 s1, 0xffff
	v_lshrrev_b32_e32 v2, 16, v132
	s_mov_b32 s0, 0xffff0000
	v_and_or_b32 v1, v132, s1, v1
	v_and_or_b32 v2, v136, s0, v2
	v_add_u32_e32 v0, 0x3400, v0
	ds_write2_b32 v0, v1, v2 offset1:34
	v_lshlrev_b32_e32 v1, 16, v137
	v_lshrrev_b32_e32 v2, 16, v133
	v_and_or_b32 v1, v133, s1, v1
	v_and_or_b32 v2, v137, s0, v2
	ds_write2_b32 v0, v1, v2 offset0:68 offset1:102
	v_lshlrev_b32_e32 v1, 16, v138
	v_lshrrev_b32_e32 v2, 16, v134
	v_and_or_b32 v1, v134, s1, v1
	v_and_or_b32 v2, v138, s0, v2
	ds_write2_b32 v0, v1, v2 offset0:136 offset1:170
	v_lshlrev_b32_e32 v1, 16, v139
	v_lshrrev_b32_e32 v2, 16, v135
	v_subrev_co_u32_e32 v167, vcc, 1, v167
	v_and_or_b32 v1, v135, s1, v1
	v_and_or_b32 v2, v139, s0, v2
	s_and_b64 vcc, exec, vcc
	ds_write2_b32 v0, v1, v2 offset0:204 offset1:238
	s_cbranch_vccnz .LBB0_400
	v_add_u32_e32 v0, s8, v141
	v_add_u32_e32 v0, 0xffffff41, v0
	s_movk_i32 s13, 0x300
	v_add_u32_e32 v2, s8, v152
	v_mad_i64_i32 v[0:1], s[0:1], v0, s13, v[146:147]
	v_add_u32_e32 v2, 0xffffff41, v2
	v_mad_i64_i32 v[2:3], s[0:1], v2, s13, v[148:149]
	global_load_dwordx4 v[120:123], v[0:1], off
	global_load_dwordx4 v[124:127], v[2:3], off
	v_add_u32_e32 v0, s8, v153
	v_add_u32_e32 v4, s8, v154
	v_add_u32_e32 v0, 0xffffff41, v0
	v_add_u32_e32 v192, 0xffffff41, v4
	v_mad_i64_i32 v[0:1], s[0:1], v0, s13, v[150:151]
	v_lshlrev_b64 v[2:3], 9, v[192:193]
	v_add_u32_e32 v192, 0xffffff42, v4
	v_lshl_add_u64 v[2:3], v[144:145], 0, v[2:3]
	global_load_dwordx4 v[128:131], v[0:1], off
	global_load_dwordx4 v[132:135], v[2:3], off
	v_lshlrev_b64 v[0:1], 9, v[192:193]
	v_lshl_add_u64 v[0:1], v[144:145], 0, v[0:1]
	global_load_dwordx4 v[136:139], v[0:1], off
	s_branch .LBB0_400

.LBB0_411:
	v_mbcnt_lo_u32_b32 v0, -1, 0
	v_mbcnt_hi_u32_b32 v0, -1, v0
	v_and_b32_e32 v2, 64, v0
	v_xor_b32_e32 v1, 32, v0
	v_add_u32_e32 v2, 64, v2
	v_cmp_lt_i32_e32 vcc, v1, v2
	s_movk_i32 s8, 0x1d00
	v_mov_b32_e32 v141, v193
	v_cndmask_b32_e32 v0, v0, v1, vcc
	v_lshlrev_b32_e32 v0, 2, v0
	ds_bpermute_b32 v0, v0, v163
	s_waitcnt lgkmcnt(0)
	v_add_f32_e32 v0, v163, v0
	v_div_scale_f32 v1, s[0:1], v0, v0, 1.0
	v_rcp_f32_e32 v2, v1
	v_readlane_b32 s0, v254, 43
	v_readlane_b32 s1, v254, 44
	v_fma_f32 v3, -v1, v2, 1.0
	v_fmac_f32_e32 v2, v3, v2
	v_div_scale_f32 v3, vcc, 1.0, v0, 1.0
	v_mul_f32_e32 v4, v3, v2
	v_fma_f32 v5, -v1, v4, v3
	v_fmac_f32_e32 v4, v5, v2
	v_fma_f32 v1, -v1, v4, v3
	v_div_fmas_f32 v1, v1, v2, v4
	v_div_fixup_f32 v4, v1, v0, 1.0
	v_mov_b64_e32 v[0:1], s[0:1]
	v_mad_u64_u32 v[0:1], s[0:1], v142, s8, v[0:1]
	v_mad_i32_i24 v1, v143, s8, v1
	s_mov_b64 s[8:9], 0x3e38aa3b
	s_lshl_b32 s0, s10, 1
	s_mov_b32 s1, s9
	s_movk_i32 s10, 0xeb00
	v_lshl_add_u64 v[2:3], v[0:1], 0, s[0:1]
	v_mad_u64_u32 v[0:1], s[8:9], v142, s10, v[0:1]
	v_mad_i32_i24 v1, v143, s10, v1
	v_sub_u32_e32 v1, v1, v142
	v_lshl_add_u64 v[6:7], v[0:1], 0, s[0:1]
	v_lshl_add_u64 v[2:3], v[2:3], 0, v[140:141]
	s_mov_b64 s[0:1], 0x3dd0b00
	v_lshl_add_u64 v[0:1], v[2:3], 0, s[0:1]
	v_lshl_add_u64 v[12:13], v[6:7], 0, v[140:141]
	s_mov_b64 s[0:1], 0xd210200
	v_lshl_add_u64 v[6:7], v[12:13], 0, s[0:1]
	s_mov_b32 s0, 0x3dd0000
	v_add_co_u32_e32 v2, vcc, s0, v2
	v_readlane_b32 s10, v254, 51
	s_nop 0
	v_addc_co_u32_e32 v3, vcc, 0, v3, vcc
	global_load_dwordx4 v[8:11], v[2:3], off offset:2816
	s_waitcnt vmcnt(0)
	v_mov_b32_e32 v5, v10
	s_nop 1
	v_permlane32_swap_b32_e32 v8, v5
	v_lshlrev_b32_e32 v14, 16, v8
	v_and_b32_e32 v8, 0xffff0000, v8
	v_mov_b32_e32 v16, v11
	v_mul_f32_e32 v10, 0xbfb8aa3b, v14
	v_mul_f32_e32 v11, 0xbfb8aa3b, v8
	v_exp_f32_e32 v10, v10
	v_exp_f32_e32 v11, v11
	v_permlane32_swap_b32_e32 v9, v16
	v_pk_mul_f32 v[2:3], v[48:49], v[4:5] op_sel_hi:[1,0]
	v_pk_add_f32 v[10:11], v[10:11], 1.0 op_sel_hi:[1,0]
	s_nop 0
	v_div_scale_f32 v15, s[0:1], v11, v11, v8
	v_rcp_f32_e32 v17, v15
	s_nop 0
	v_fma_f32 v18, -v15, v17, 1.0
	v_fmac_f32_e32 v17, v18, v17
	v_div_scale_f32 v18, vcc, v8, v11, v8
	v_mul_f32_e32 v19, v18, v17
	v_fma_f32 v20, -v15, v19, v18
	v_fmac_f32_e32 v19, v20, v17
	v_fma_f32 v15, -v15, v19, v18
	v_div_fmas_f32 v15, v15, v17, v19
	v_div_fixup_f32 v11, v15, v11, v8
	v_div_scale_f32 v8, s[0:1], v10, v10, v14
	v_rcp_f32_e32 v15, v8
	s_nop 0
	v_fma_f32 v17, -v8, v15, 1.0
	v_fmac_f32_e32 v15, v17, v15
	v_div_scale_f32 v17, vcc, v14, v10, v14
	v_mul_f32_e32 v18, v17, v15
	v_fma_f32 v19, -v8, v18, v17
	v_fmac_f32_e32 v18, v19, v15
	v_fma_f32 v8, -v8, v18, v17
	v_div_fmas_f32 v8, v8, v15, v18
	v_div_fixup_f32 v10, v8, v10, v14
	v_lshlrev_b32_e32 v14, 16, v9
	v_and_b32_e32 v15, 0xffff0000, v9
	v_pk_mul_f32 v[2:3], v[2:3], v[10:11]
	v_mul_f32_e32 v10, 0xbfb8aa3b, v14
	v_mul_f32_e32 v11, 0xbfb8aa3b, v15
	v_exp_f32_e32 v10, v10
	v_exp_f32_e32 v11, v11
	v_pk_mul_f32 v[8:9], v[50:51], v[4:5] op_sel_hi:[1,0]
	v_pk_add_f32 v[10:11], v[10:11], 1.0 op_sel_hi:[1,0]
	s_nop 0
	v_div_scale_f32 v17, s[0:1], v11, v11, v15
	v_rcp_f32_e32 v18, v17
	s_nop 0
	v_fma_f32 v19, -v17, v18, 1.0
	v_fmac_f32_e32 v18, v19, v18
	v_div_scale_f32 v19, vcc, v15, v11, v15
	v_mul_f32_e32 v20, v19, v18
	v_fma_f32 v21, -v17, v20, v19
	v_fmac_f32_e32 v20, v21, v18
	v_fma_f32 v17, -v17, v20, v19
	v_div_fmas_f32 v17, v17, v18, v20
	v_div_fixup_f32 v11, v17, v11, v15
	v_div_scale_f32 v15, s[0:1], v10, v10, v14
	v_rcp_f32_e32 v17, v15
	s_nop 0
	v_fma_f32 v18, -v15, v17, 1.0
	v_fmac_f32_e32 v17, v18, v17
	v_div_scale_f32 v18, vcc, v14, v10, v14
	v_mul_f32_e32 v19, v18, v17
	v_fma_f32 v20, -v15, v19, v18
	v_fmac_f32_e32 v19, v20, v17
	v_fma_f32 v15, -v15, v19, v18
	v_div_fmas_f32 v15, v15, v17, v19
	v_lshlrev_b32_e32 v17, 16, v5
	v_and_b32_e32 v5, 0xffff0000, v5
	v_div_fixup_f32 v10, v15, v10, v14
	v_mul_f32_e32 v14, 0xbfb8aa3b, v17
	v_mul_f32_e32 v15, 0xbfb8aa3b, v5
	v_exp_f32_e32 v14, v14
	v_exp_f32_e32 v15, v15
	v_pk_mul_f32 v[10:11], v[8:9], v[10:11]
	v_pk_mul_f32 v[8:9], v[52:53], v[4:5] op_sel_hi:[1,0]
	v_pk_add_f32 v[14:15], v[14:15], 1.0 op_sel_hi:[1,0]
	s_nop 0
	v_div_scale_f32 v18, s[0:1], v15, v15, v5
	v_rcp_f32_e32 v19, v18
	s_nop 0
	v_fma_f32 v20, -v18, v19, 1.0
	v_fmac_f32_e32 v19, v20, v19
	v_div_scale_f32 v20, vcc, v5, v15, v5
	v_mul_f32_e32 v21, v20, v19
	v_fma_f32 v22, -v18, v21, v20
	v_fmac_f32_e32 v21, v22, v19
	v_fma_f32 v18, -v18, v21, v20
	v_div_fmas_f32 v18, v18, v19, v21
	v_div_fixup_f32 v15, v18, v15, v5
	v_div_scale_f32 v5, s[0:1], v14, v14, v17
	v_rcp_f32_e32 v18, v5
	s_nop 0
	v_fma_f32 v19, -v5, v18, 1.0
	v_fmac_f32_e32 v18, v19, v18
	v_div_scale_f32 v19, vcc, v17, v14, v17
	v_mul_f32_e32 v20, v19, v18
	v_fma_f32 v21, -v5, v20, v19
	v_fmac_f32_e32 v20, v21, v18
	v_fma_f32 v5, -v5, v20, v19
	v_div_fmas_f32 v5, v5, v18, v20
	v_div_fixup_f32 v14, v5, v14, v17
	v_lshlrev_b32_e32 v5, 16, v16
	v_and_b32_e32 v18, 0xffff0000, v16
	v_mul_f32_e32 v16, 0xbfb8aa3b, v5
	v_mul_f32_e32 v17, 0xbfb8aa3b, v18
	v_exp_f32_e32 v16, v16
	v_exp_f32_e32 v17, v17
	v_pk_mul_f32 v[14:15], v[8:9], v[14:15]
	v_pk_mul_f32 v[8:9], v[54:55], v[4:5] op_sel_hi:[1,0]
	v_pk_add_f32 v[16:17], v[16:17], 1.0 op_sel_hi:[1,0]
	s_nop 0
	v_div_scale_f32 v19, s[0:1], v17, v17, v18
	v_rcp_f32_e32 v20, v19
	s_nop 0
	v_fma_f32 v21, -v19, v20, 1.0
	v_fmac_f32_e32 v20, v21, v20
	v_div_scale_f32 v21, vcc, v18, v17, v18
	v_mul_f32_e32 v22, v21, v20
	v_fma_f32 v23, -v19, v22, v21
	v_fmac_f32_e32 v22, v23, v20
	v_fma_f32 v19, -v19, v22, v21
	v_div_fmas_f32 v19, v19, v20, v22
	v_div_fixup_f32 v17, v19, v17, v18
	v_div_scale_f32 v18, s[0:1], v16, v16, v5
	v_rcp_f32_e32 v19, v18
	s_mov_b32 s0, 0xd210000
	v_fma_f32 v20, -v18, v19, 1.0
	v_fmac_f32_e32 v19, v20, v19
	v_div_scale_f32 v20, vcc, v5, v16, v5
	v_mul_f32_e32 v21, v20, v19
	v_fma_f32 v22, -v18, v21, v20
	v_fmac_f32_e32 v21, v22, v19
	v_fma_f32 v18, -v18, v21, v20
	v_div_fmas_f32 v18, v18, v19, v21
	v_div_fixup_f32 v16, v18, v16, v5
	v_pk_mul_f32 v[16:17], v[8:9], v[16:17]
	v_cvt_pk_bf16_f32 v8, v2, v3
	v_cvt_pk_bf16_f32 v9, v10, v11
	v_cvt_pk_bf16_f32 v10, v14, v15
	v_cvt_pk_bf16_f32 v11, v16, v17
	v_add_co_u32_e32 v2, vcc, s0, v12
	v_permlane32_swap_b32_e32 v8, v10
	v_permlane32_swap_b32_e32 v9, v11
	v_addc_co_u32_e32 v3, vcc, 0, v13, vcc
	global_store_dwordx4 v[2:3], v[8:11], off offset:512
	global_load_dwordx4 v[8:11], v[0:1], off offset:32
	s_waitcnt vmcnt(0)
	v_mov_b32_e32 v5, v10
	s_nop 1
	v_permlane32_swap_b32_e32 v8, v5
	v_lshlrev_b32_e32 v12, 16, v8
	v_and_b32_e32 v8, 0xffff0000, v8
	v_mov_b32_e32 v14, v11
	v_mul_f32_e32 v10, 0xbfb8aa3b, v12
	v_mul_f32_e32 v11, 0xbfb8aa3b, v8
	v_exp_f32_e32 v10, v10
	v_exp_f32_e32 v11, v11
	v_permlane32_swap_b32_e32 v9, v14
	v_pk_mul_f32 v[2:3], v[56:57], v[4:5] op_sel_hi:[1,0]
	v_pk_add_f32 v[10:11], v[10:11], 1.0 op_sel_hi:[1,0]
	s_nop 0
	v_div_scale_f32 v13, s[0:1], v11, v11, v8
	v_rcp_f32_e32 v15, v13
	s_nop 0
	v_fma_f32 v16, -v13, v15, 1.0
	v_fmac_f32_e32 v15, v16, v15
	v_div_scale_f32 v16, vcc, v8, v11, v8
	v_mul_f32_e32 v17, v16, v15
	v_fma_f32 v18, -v13, v17, v16
	v_fmac_f32_e32 v17, v18, v15
	v_fma_f32 v13, -v13, v17, v16
	v_div_fmas_f32 v13, v13, v15, v17
	v_div_fixup_f32 v11, v13, v11, v8
	v_div_scale_f32 v8, s[0:1], v10, v10, v12
	v_rcp_f32_e32 v13, v8
	s_nop 0
	v_fma_f32 v15, -v8, v13, 1.0
	v_fmac_f32_e32 v13, v15, v13
	v_div_scale_f32 v15, vcc, v12, v10, v12
	v_mul_f32_e32 v16, v15, v13
	v_fma_f32 v17, -v8, v16, v15
	v_fmac_f32_e32 v16, v17, v13
	v_fma_f32 v8, -v8, v16, v15
	v_div_fmas_f32 v8, v8, v13, v16
	v_div_fixup_f32 v10, v8, v10, v12
	v_lshlrev_b32_e32 v12, 16, v9
	v_and_b32_e32 v13, 0xffff0000, v9
	v_pk_mul_f32 v[2:3], v[2:3], v[10:11]
	v_mul_f32_e32 v10, 0xbfb8aa3b, v12
	v_mul_f32_e32 v11, 0xbfb8aa3b, v13
	v_exp_f32_e32 v10, v10
	v_exp_f32_e32 v11, v11
	v_pk_mul_f32 v[8:9], v[58:59], v[4:5] op_sel_hi:[1,0]
	v_pk_add_f32 v[10:11], v[10:11], 1.0 op_sel_hi:[1,0]
	s_nop 0
	v_div_scale_f32 v15, s[0:1], v11, v11, v13
	v_rcp_f32_e32 v16, v15
	s_nop 0
	v_fma_f32 v17, -v15, v16, 1.0
	v_fmac_f32_e32 v16, v17, v16
	v_div_scale_f32 v17, vcc, v13, v11, v13
	v_mul_f32_e32 v18, v17, v16
	v_fma_f32 v19, -v15, v18, v17
	v_fmac_f32_e32 v18, v19, v16
	v_fma_f32 v15, -v15, v18, v17
	v_div_fmas_f32 v15, v15, v16, v18
	v_div_fixup_f32 v11, v15, v11, v13
	v_div_scale_f32 v13, s[0:1], v10, v10, v12
	v_rcp_f32_e32 v15, v13
	s_nop 0
	v_fma_f32 v16, -v13, v15, 1.0
	v_fmac_f32_e32 v15, v16, v15
	v_div_scale_f32 v16, vcc, v12, v10, v12
	v_mul_f32_e32 v17, v16, v15
	v_fma_f32 v18, -v13, v17, v16
	v_fmac_f32_e32 v17, v18, v15
	v_fma_f32 v13, -v13, v17, v16
	v_div_fmas_f32 v13, v13, v15, v17
	v_lshlrev_b32_e32 v15, 16, v5
	v_and_b32_e32 v5, 0xffff0000, v5
	v_div_fixup_f32 v10, v13, v10, v12
	v_mul_f32_e32 v12, 0xbfb8aa3b, v15
	v_mul_f32_e32 v13, 0xbfb8aa3b, v5
	v_exp_f32_e32 v12, v12
	v_exp_f32_e32 v13, v13
	v_pk_mul_f32 v[10:11], v[8:9], v[10:11]
	v_pk_mul_f32 v[8:9], v[60:61], v[4:5] op_sel_hi:[1,0]
	v_pk_add_f32 v[12:13], v[12:13], 1.0 op_sel_hi:[1,0]
	s_nop 0
	v_div_scale_f32 v16, s[0:1], v13, v13, v5
	v_rcp_f32_e32 v17, v16
	s_nop 0
	v_fma_f32 v18, -v16, v17, 1.0
	v_fmac_f32_e32 v17, v18, v17
	v_div_scale_f32 v18, vcc, v5, v13, v5
	v_mul_f32_e32 v19, v18, v17
	v_fma_f32 v20, -v16, v19, v18
	v_fmac_f32_e32 v19, v20, v17
	v_fma_f32 v16, -v16, v19, v18
	v_div_fmas_f32 v16, v16, v17, v19
	v_div_fixup_f32 v13, v16, v13, v5
	v_div_scale_f32 v5, s[0:1], v12, v12, v15
	v_rcp_f32_e32 v16, v5
	s_nop 0
	v_fma_f32 v17, -v5, v16, 1.0
	v_fmac_f32_e32 v16, v17, v16
	v_div_scale_f32 v17, vcc, v15, v12, v15
	v_mul_f32_e32 v18, v17, v16
	v_fma_f32 v19, -v5, v18, v17
	v_fmac_f32_e32 v18, v19, v16
	v_fma_f32 v5, -v5, v18, v17
	v_div_fmas_f32 v5, v5, v16, v18
	v_div_fixup_f32 v12, v5, v12, v15
	v_lshlrev_b32_e32 v5, 16, v14
	v_and_b32_e32 v16, 0xffff0000, v14
	v_mul_f32_e32 v14, 0xbfb8aa3b, v5
	v_mul_f32_e32 v15, 0xbfb8aa3b, v16
	v_exp_f32_e32 v14, v14
	v_exp_f32_e32 v15, v15
	v_pk_mul_f32 v[12:13], v[8:9], v[12:13]
	v_pk_mul_f32 v[8:9], v[62:63], v[4:5] op_sel_hi:[1,0]
	v_pk_add_f32 v[14:15], v[14:15], 1.0 op_sel_hi:[1,0]
	s_nop 0
	v_div_scale_f32 v17, s[0:1], v15, v15, v16
	v_rcp_f32_e32 v18, v17
	s_nop 0
	v_fma_f32 v19, -v17, v18, 1.0
	v_fmac_f32_e32 v18, v19, v18
	v_div_scale_f32 v19, vcc, v16, v15, v16
	v_mul_f32_e32 v20, v19, v18
	v_fma_f32 v21, -v17, v20, v19
	v_fmac_f32_e32 v20, v21, v18
	v_fma_f32 v17, -v17, v20, v19
	v_div_fmas_f32 v17, v17, v18, v20
	v_div_fixup_f32 v15, v17, v15, v16
	v_div_scale_f32 v16, s[0:1], v14, v14, v5
	v_rcp_f32_e32 v17, v16
	s_nop 0
	v_fma_f32 v18, -v16, v17, 1.0
	v_fmac_f32_e32 v17, v18, v17
	v_div_scale_f32 v18, vcc, v5, v14, v5
	v_mul_f32_e32 v19, v18, v17
	v_fma_f32 v20, -v16, v19, v18
	v_fmac_f32_e32 v19, v20, v17
	v_fma_f32 v16, -v16, v19, v18
	v_div_fmas_f32 v16, v16, v17, v19
	v_div_fixup_f32 v14, v16, v14, v5
	v_pk_mul_f32 v[14:15], v[8:9], v[14:15]
	v_cvt_pk_bf16_f32 v8, v2, v3
	v_cvt_pk_bf16_f32 v9, v10, v11
	v_cvt_pk_bf16_f32 v10, v12, v13
	v_cvt_pk_bf16_f32 v11, v14, v15
	s_nop 0
	v_permlane32_swap_b32_e32 v8, v10
	v_permlane32_swap_b32_e32 v9, v11
	global_store_dwordx4 v[6:7], v[8:11], off offset:32
	global_load_dwordx4 v[8:11], v[0:1], off offset:64
	s_waitcnt vmcnt(0)
	v_mov_b32_e32 v5, v10
	s_nop 1
	v_permlane32_swap_b32_e32 v8, v5
	v_lshlrev_b32_e32 v12, 16, v8
	v_and_b32_e32 v8, 0xffff0000, v8
	v_mov_b32_e32 v14, v11
	v_mul_f32_e32 v10, 0xbfb8aa3b, v12
	v_mul_f32_e32 v11, 0xbfb8aa3b, v8
	v_exp_f32_e32 v10, v10
	v_exp_f32_e32 v11, v11
	v_permlane32_swap_b32_e32 v9, v14
	v_pk_mul_f32 v[2:3], v[32:33], v[4:5] op_sel_hi:[1,0]
	v_pk_add_f32 v[10:11], v[10:11], 1.0 op_sel_hi:[1,0]
	s_nop 0
	v_div_scale_f32 v13, s[0:1], v11, v11, v8
	v_rcp_f32_e32 v15, v13
	s_nop 0
	v_fma_f32 v16, -v13, v15, 1.0
	v_fmac_f32_e32 v15, v16, v15
	v_div_scale_f32 v16, vcc, v8, v11, v8
	v_mul_f32_e32 v17, v16, v15
	v_fma_f32 v18, -v13, v17, v16
	v_fmac_f32_e32 v17, v18, v15
	v_fma_f32 v13, -v13, v17, v16
	v_div_fmas_f32 v13, v13, v15, v17
	v_div_fixup_f32 v11, v13, v11, v8
	v_div_scale_f32 v8, s[0:1], v10, v10, v12
	v_rcp_f32_e32 v13, v8
	s_nop 0
	v_fma_f32 v15, -v8, v13, 1.0
	v_fmac_f32_e32 v13, v15, v13
	v_div_scale_f32 v15, vcc, v12, v10, v12
	v_mul_f32_e32 v16, v15, v13
	v_fma_f32 v17, -v8, v16, v15
	v_fmac_f32_e32 v16, v17, v13
	v_fma_f32 v8, -v8, v16, v15
	v_div_fmas_f32 v8, v8, v13, v16
	v_div_fixup_f32 v10, v8, v10, v12
	v_lshlrev_b32_e32 v12, 16, v9
	v_and_b32_e32 v13, 0xffff0000, v9
	v_pk_mul_f32 v[2:3], v[2:3], v[10:11]
	v_mul_f32_e32 v10, 0xbfb8aa3b, v12
	v_mul_f32_e32 v11, 0xbfb8aa3b, v13
	v_exp_f32_e32 v10, v10
	v_exp_f32_e32 v11, v11
	v_pk_mul_f32 v[8:9], v[34:35], v[4:5] op_sel_hi:[1,0]
	v_pk_add_f32 v[10:11], v[10:11], 1.0 op_sel_hi:[1,0]
	s_nop 0
	v_div_scale_f32 v15, s[0:1], v11, v11, v13
	v_rcp_f32_e32 v16, v15
	s_nop 0
	v_fma_f32 v17, -v15, v16, 1.0
	v_fmac_f32_e32 v16, v17, v16
	v_div_scale_f32 v17, vcc, v13, v11, v13
	v_mul_f32_e32 v18, v17, v16
	v_fma_f32 v19, -v15, v18, v17
	v_fmac_f32_e32 v18, v19, v16
	v_fma_f32 v15, -v15, v18, v17
	v_div_fmas_f32 v15, v15, v16, v18
	v_div_fixup_f32 v11, v15, v11, v13
	v_div_scale_f32 v13, s[0:1], v10, v10, v12
	v_rcp_f32_e32 v15, v13
	s_nop 0
	v_fma_f32 v16, -v13, v15, 1.0
	v_fmac_f32_e32 v15, v16, v15
	v_div_scale_f32 v16, vcc, v12, v10, v12
	v_mul_f32_e32 v17, v16, v15
	v_fma_f32 v18, -v13, v17, v16
	v_fmac_f32_e32 v17, v18, v15
	v_fma_f32 v13, -v13, v17, v16
	v_div_fmas_f32 v13, v13, v15, v17
	v_lshlrev_b32_e32 v15, 16, v5
	v_and_b32_e32 v5, 0xffff0000, v5
	v_div_fixup_f32 v10, v13, v10, v12
	v_mul_f32_e32 v12, 0xbfb8aa3b, v15
	v_mul_f32_e32 v13, 0xbfb8aa3b, v5
	v_exp_f32_e32 v12, v12
	v_exp_f32_e32 v13, v13
	v_pk_mul_f32 v[10:11], v[8:9], v[10:11]
	v_pk_mul_f32 v[8:9], v[36:37], v[4:5] op_sel_hi:[1,0]
	v_pk_add_f32 v[12:13], v[12:13], 1.0 op_sel_hi:[1,0]
	s_nop 0
	v_div_scale_f32 v16, s[0:1], v13, v13, v5
	v_rcp_f32_e32 v17, v16
	s_nop 0
	v_fma_f32 v18, -v16, v17, 1.0
	v_fmac_f32_e32 v17, v18, v17
	v_div_scale_f32 v18, vcc, v5, v13, v5
	v_mul_f32_e32 v19, v18, v17
	v_fma_f32 v20, -v16, v19, v18
	v_fmac_f32_e32 v19, v20, v17
	v_fma_f32 v16, -v16, v19, v18
	v_div_fmas_f32 v16, v16, v17, v19
	v_div_fixup_f32 v13, v16, v13, v5
	v_div_scale_f32 v5, s[0:1], v12, v12, v15
	v_rcp_f32_e32 v16, v5
	s_nop 0
	v_fma_f32 v17, -v5, v16, 1.0
	v_fmac_f32_e32 v16, v17, v16
	v_div_scale_f32 v17, vcc, v15, v12, v15
	v_mul_f32_e32 v18, v17, v16
	v_fma_f32 v19, -v5, v18, v17
	v_fmac_f32_e32 v18, v19, v16
	v_fma_f32 v5, -v5, v18, v17
	v_div_fmas_f32 v5, v5, v16, v18
	v_div_fixup_f32 v12, v5, v12, v15
	v_lshlrev_b32_e32 v5, 16, v14
	v_and_b32_e32 v16, 0xffff0000, v14
	v_mul_f32_e32 v14, 0xbfb8aa3b, v5
	v_mul_f32_e32 v15, 0xbfb8aa3b, v16
	v_exp_f32_e32 v14, v14
	v_exp_f32_e32 v15, v15
	v_pk_mul_f32 v[12:13], v[8:9], v[12:13]
	v_pk_mul_f32 v[8:9], v[38:39], v[4:5] op_sel_hi:[1,0]
	v_pk_add_f32 v[14:15], v[14:15], 1.0 op_sel_hi:[1,0]
	s_nop 0
	v_div_scale_f32 v17, s[0:1], v15, v15, v16
	v_rcp_f32_e32 v18, v17
	s_nop 0
	v_fma_f32 v19, -v17, v18, 1.0
	v_fmac_f32_e32 v18, v19, v18
	v_div_scale_f32 v19, vcc, v16, v15, v16
	v_mul_f32_e32 v20, v19, v18
	v_fma_f32 v21, -v17, v20, v19
	v_fmac_f32_e32 v20, v21, v18
	v_fma_f32 v17, -v17, v20, v19
	v_div_fmas_f32 v17, v17, v18, v20
	v_div_fixup_f32 v15, v17, v15, v16
	v_div_scale_f32 v16, s[0:1], v14, v14, v5
	v_rcp_f32_e32 v17, v16
	s_nop 0
	v_fma_f32 v18, -v16, v17, 1.0
	v_fmac_f32_e32 v17, v18, v17
	v_div_scale_f32 v18, vcc, v5, v14, v5
	v_mul_f32_e32 v19, v18, v17
	v_fma_f32 v20, -v16, v19, v18
	v_fmac_f32_e32 v19, v20, v17
	v_fma_f32 v16, -v16, v19, v18
	v_div_fmas_f32 v16, v16, v17, v19
	v_div_fixup_f32 v14, v16, v14, v5
	v_pk_mul_f32 v[14:15], v[8:9], v[14:15]
	v_cvt_pk_bf16_f32 v8, v2, v3
	global_load_dwordx4 v[0:3], v[0:1], off offset:96
	v_cvt_pk_bf16_f32 v9, v10, v11
	v_cvt_pk_bf16_f32 v10, v12, v13
	v_cvt_pk_bf16_f32 v11, v14, v15
	s_nop 0
	v_permlane32_swap_b32_e32 v8, v10
	v_permlane32_swap_b32_e32 v9, v11
	global_store_dwordx4 v[6:7], v[8:11], off offset:64
	s_waitcnt vmcnt(1)
	v_mov_b32_e32 v5, v2
	s_nop 1
	v_permlane32_swap_b32_e32 v0, v5
	v_lshlrev_b32_e32 v10, 16, v0
	v_and_b32_e32 v0, 0xffff0000, v0
	v_mul_f32_e32 v8, 0xbfb8aa3b, v10
	v_mul_f32_e32 v9, 0xbfb8aa3b, v0
	v_exp_f32_e32 v8, v8
	v_exp_f32_e32 v9, v9
	v_mov_b32_e32 v12, v3
	s_nop 1
	v_permlane32_swap_b32_e32 v1, v12
	v_pk_add_f32 v[8:9], v[8:9], 1.0 op_sel_hi:[1,0]
	v_pk_mul_f32 v[2:3], v[40:41], v[4:5] op_sel_hi:[1,0]
	v_div_scale_f32 v11, s[0:1], v9, v9, v0
	v_rcp_f32_e32 v13, v11
	s_nop 0
	v_fma_f32 v14, -v11, v13, 1.0
	v_fmac_f32_e32 v13, v14, v13
	v_div_scale_f32 v14, vcc, v0, v9, v0
	v_mul_f32_e32 v15, v14, v13
	v_fma_f32 v16, -v11, v15, v14
	v_fmac_f32_e32 v15, v16, v13
	v_fma_f32 v11, -v11, v15, v14
	v_div_fmas_f32 v11, v11, v13, v15
	v_div_fixup_f32 v9, v11, v9, v0
	v_div_scale_f32 v0, s[0:1], v8, v8, v10
	v_rcp_f32_e32 v11, v0
	s_nop 0
	v_fma_f32 v13, -v0, v11, 1.0
	v_fmac_f32_e32 v11, v13, v11
	v_div_scale_f32 v13, vcc, v10, v8, v10
	v_mul_f32_e32 v14, v13, v11
	v_fma_f32 v15, -v0, v14, v13
	v_fmac_f32_e32 v14, v15, v11
	v_fma_f32 v0, -v0, v14, v13
	v_div_fmas_f32 v0, v0, v11, v14
	v_div_fixup_f32 v8, v0, v8, v10
	v_lshlrev_b32_e32 v10, 16, v1
	v_and_b32_e32 v11, 0xffff0000, v1
	v_pk_mul_f32 v[2:3], v[2:3], v[8:9]
	v_mul_f32_e32 v8, 0xbfb8aa3b, v10
	v_mul_f32_e32 v9, 0xbfb8aa3b, v11
	v_exp_f32_e32 v8, v8
	v_exp_f32_e32 v9, v9
	v_pk_mul_f32 v[0:1], v[42:43], v[4:5] op_sel_hi:[1,0]
	v_pk_add_f32 v[8:9], v[8:9], 1.0 op_sel_hi:[1,0]
	s_nop 0
	v_div_scale_f32 v13, s[0:1], v9, v9, v11
	v_rcp_f32_e32 v14, v13
	s_nop 0
	v_fma_f32 v15, -v13, v14, 1.0
	v_fmac_f32_e32 v14, v15, v14
	v_div_scale_f32 v15, vcc, v11, v9, v11
	v_mul_f32_e32 v16, v15, v14
	v_fma_f32 v17, -v13, v16, v15
	v_fmac_f32_e32 v16, v17, v14
	v_fma_f32 v13, -v13, v16, v15
	v_div_fmas_f32 v13, v13, v14, v16
	v_div_fixup_f32 v9, v13, v9, v11
	v_div_scale_f32 v11, s[0:1], v8, v8, v10
	v_rcp_f32_e32 v13, v11
	s_nop 0
	v_fma_f32 v14, -v11, v13, 1.0
	v_fmac_f32_e32 v13, v14, v13
	v_div_scale_f32 v14, vcc, v10, v8, v10
	v_mul_f32_e32 v15, v14, v13
	v_fma_f32 v16, -v11, v15, v14
	v_fmac_f32_e32 v15, v16, v13
	v_fma_f32 v11, -v11, v15, v14
	v_div_fmas_f32 v11, v11, v13, v15
	v_lshlrev_b32_e32 v13, 16, v5
	v_and_b32_e32 v5, 0xffff0000, v5
	v_div_fixup_f32 v8, v11, v8, v10
	v_mul_f32_e32 v10, 0xbfb8aa3b, v13
	v_mul_f32_e32 v11, 0xbfb8aa3b, v5
	v_exp_f32_e32 v10, v10
	v_exp_f32_e32 v11, v11
	v_pk_mul_f32 v[8:9], v[0:1], v[8:9]
	v_pk_mul_f32 v[0:1], v[44:45], v[4:5] op_sel_hi:[1,0]
	v_pk_add_f32 v[10:11], v[10:11], 1.0 op_sel_hi:[1,0]
	s_nop 0
	v_div_scale_f32 v14, s[0:1], v11, v11, v5
	v_rcp_f32_e32 v15, v14
	s_nop 0
	v_fma_f32 v16, -v14, v15, 1.0
	v_fmac_f32_e32 v15, v16, v15
	v_div_scale_f32 v16, vcc, v5, v11, v5
	v_mul_f32_e32 v17, v16, v15
	v_fma_f32 v18, -v14, v17, v16
	v_fmac_f32_e32 v17, v18, v15
	v_fma_f32 v14, -v14, v17, v16
	v_div_fmas_f32 v14, v14, v15, v17
	v_div_fixup_f32 v11, v14, v11, v5
	v_div_scale_f32 v5, s[0:1], v10, v10, v13
	v_rcp_f32_e32 v14, v5
	s_nop 0
	v_fma_f32 v15, -v5, v14, 1.0
	v_fmac_f32_e32 v14, v15, v14
	v_div_scale_f32 v15, vcc, v13, v10, v13
	v_mul_f32_e32 v16, v15, v14
	v_fma_f32 v17, -v5, v16, v15
	v_fmac_f32_e32 v16, v17, v14
	v_fma_f32 v5, -v5, v16, v15
	v_div_fmas_f32 v5, v5, v14, v16
	v_div_fixup_f32 v10, v5, v10, v13
	v_lshlrev_b32_e32 v13, 16, v12
	v_and_b32_e32 v12, 0xffff0000, v12
	v_pk_mul_f32 v[10:11], v[0:1], v[10:11]
	v_pk_mul_f32 v[0:1], v[46:47], v[4:5] op_sel_hi:[1,0]
	v_mul_f32_e32 v4, 0xbfb8aa3b, v13
	v_mul_f32_e32 v5, 0xbfb8aa3b, v12
	v_exp_f32_e32 v4, v4
	v_exp_f32_e32 v5, v5
	s_nop 0
	v_pk_add_f32 v[4:5], v[4:5], 1.0 op_sel_hi:[1,0]
	s_nop 0
	v_div_scale_f32 v14, s[0:1], v5, v5, v12
	v_rcp_f32_e32 v15, v14
	s_nop 0
	v_fma_f32 v16, -v14, v15, 1.0
	v_fmac_f32_e32 v15, v16, v15
	v_div_scale_f32 v16, vcc, v12, v5, v12
	v_mul_f32_e32 v17, v16, v15
	v_fma_f32 v18, -v14, v17, v16
	v_fmac_f32_e32 v17, v18, v15
	v_fma_f32 v14, -v14, v17, v16
	v_div_fmas_f32 v14, v14, v15, v17
	v_div_fixup_f32 v5, v14, v5, v12
	v_div_scale_f32 v12, s[0:1], v4, v4, v13
	v_rcp_f32_e32 v14, v12
	s_nop 0
	v_fma_f32 v15, -v12, v14, 1.0
	v_fmac_f32_e32 v14, v15, v14
	v_div_scale_f32 v15, vcc, v13, v4, v13
	v_mul_f32_e32 v16, v15, v14
	v_fma_f32 v17, -v12, v16, v15
	v_fmac_f32_e32 v16, v17, v14
	v_fma_f32 v12, -v12, v16, v15
	v_div_fmas_f32 v12, v12, v14, v16
	v_div_fixup_f32 v4, v12, v4, v13
	v_pk_mul_f32 v[4:5], v[0:1], v[4:5]
	v_cvt_pk_bf16_f32 v0, v2, v3
	v_cvt_pk_bf16_f32 v1, v8, v9
	v_cvt_pk_bf16_f32 v2, v10, v11
	v_cvt_pk_bf16_f32 v3, v4, v5
	s_nop 0
	v_permlane32_swap_b32_e32 v0, v2
	v_permlane32_swap_b32_e32 v1, v3
	global_store_dwordx4 v[6:7], v[0:3], off offset:96
	s_branch .LBB0_476

.LBB0_417:
	v_readlane_b32 s12, v253, 51
	v_readlane_b32 s13, v253, 52
	s_or_b64 s[10:11], s[10:11], exec
	s_nop 0
	v_mov_b64_e32 v[2:3], s[12:13]
	global_load_dword v1, v[2:3], off sc1
	s_waitcnt vmcnt(0) lgkmcnt(0)
	v_cmp_lt_u32_e32 vcc, v1, v0
	s_and_saveexec_b64 s[12:13], vcc
	s_cbranch_execz .LBB0_416
	v_readlane_b32 s14, v253, 51
	v_readlane_b32 s15, v253, 52
	s_sleep 2
	s_mov_b64 s[16:17], -1
	v_mov_b64_e32 v[2:3], s[14:15]
	global_load_dword v1, v[2:3], off sc1
	s_waitcnt vmcnt(0) lgkmcnt(0)
	v_cmp_lt_u32_e32 vcc, v1, v0
	s_and_saveexec_b64 s[14:15], vcc
	s_cbranch_execz .LBB0_415
	v_readlane_b32 s16, v253, 51
	v_readlane_b32 s17, v253, 52
	s_sleep 2
	s_mov_b64 s[18:19], -1
	v_mov_b64_e32 v[2:3], s[16:17]
	global_load_dword v1, v[2:3], off sc1
	s_waitcnt vmcnt(0) lgkmcnt(0)
	v_cmp_lt_u32_e32 vcc, v1, v0
	s_and_saveexec_b64 s[16:17], vcc
	s_cbranch_execz .LBB0_414
	v_readlane_b32 s18, v253, 51
	v_readlane_b32 s19, v253, 52
	s_sleep 2
	s_mov_b64 s[22:23], -1
	v_mov_b64_e32 v[2:3], s[18:19]
	global_load_dword v1, v[2:3], off sc1
	s_waitcnt vmcnt(0) lgkmcnt(0)
	v_cmp_lt_u32_e32 vcc, v1, v0
	s_and_saveexec_b64 s[18:19], vcc
	s_cbranch_execz .LBB0_413
	v_readlane_b32 s22, v253, 51
	v_readlane_b32 s23, v253, 52
	s_sleep 2
	s_nop 0
	v_mov_b64_e32 v[2:3], s[22:23]
	global_load_dword v1, v[2:3], off sc1
	s_mov_b64 s[22:23], -1
	s_waitcnt vmcnt(0) lgkmcnt(0)
	v_cmp_lt_u32_e32 vcc, v1, v0
	s_and_saveexec_b64 s[24:25], vcc
	s_cbranch_execz .LBB0_412
	s_add_i32 s26, s26, -5
	s_cmp_eq_u32 s26, 0
	s_cselect_b64 s[22:23], -1, 0
	s_orn2_b64 s[22:23], s[22:23], exec
	s_sleep 2
	s_branch .LBB0_412

.LBB0_425:
	s_and_b64 vcc, exec, s[0:1]
	s_cbranch_vccz .LBB0_476
	v_readlane_b32 s0, v254, 50
	s_lshl_b32 s0, s0, 2
	s_and_b32 s1, s10, 3
	s_or_b32 s0, s0, s1
	s_ashr_i32 s14, s10, 2
	s_waitcnt vmcnt(0)
	v_and_b32_e32 v150, 31, v198
	s_lshl_b32 s12, s0, 5
	v_or_b32_e32 v206, s12, v150
	s_ashr_i32 s15, s14, 31
	v_writelane_b32 v254, s0, 52
	s_lshl_b64 s[0:1], s[14:15], 11
	v_ashrrev_i32_e32 v207, 31, v206
	v_lshl_add_u64 v[200:201], s[0:1], 0, v[206:207]
	v_readlane_b32 s0, v254, 3
	v_readlane_b32 s1, v254, 4
	s_movk_i32 s8, 0x1d00
	v_and_b32_e32 v204, 0xffffffc0, v198
	v_mov_b64_e32 v[0:1], s[0:1]
	v_mad_u64_u32 v[202:203], s[0:1], v200, s8, v[0:1]
	v_bfe_u32 v64, v198, 5, 1
	v_mad_i32_i24 v203, v201, s8, v203
	v_ashrrev_i32_e32 v205, 31, v204
	v_lshl_add_u64 v[0:1], v[204:205], 1, v[202:203]
	v_lshlrev_b32_e32 v192, 4, v64
	v_lshl_add_u64 v[0:1], v[0:1], 0, v[192:193]
	v_ashrrev_i32_e32 v66, 6, v198
	global_load_dwordx4 v[160:163], v[0:1], off offset:3328
	global_load_dwordx4 v[164:167], v[0:1], off offset:3360
	global_load_dwordx4 v[168:171], v[0:1], off offset:3392
	global_load_dwordx4 v[172:175], v[0:1], off offset:3424
	v_lshl_add_u32 v0, v66, 1, v66
	v_ashrrev_i32_e32 v1, 31, v0
	v_lshl_add_u64 v[0:1], v[0:1], 1, v[202:203]
	s_mov_b64 s[0:1], 0x1c40
	v_lshl_add_u64 v[2:3], v[0:1], 0, s[0:1]
	s_movk_i32 s0, 0x1000
	v_add_co_u32_e32 v0, vcc, s0, v0
	s_mov_b32 s0, s14
	v_writelane_b32 v254, s0, 53
	v_addc_co_u32_e32 v1, vcc, 0, v1, vcc
	s_nop 0
	v_writelane_b32 v254, s1, 54
	s_lshl_b64 s[0:1], s[14:15], 14
	v_readlane_b32 s8, v254, 5
	global_load_dword v199, v[0:1], off offset:3136
	global_load_ushort v197, v[2:3], off offset:4
	s_add_u32 s8, s8, s0
	v_readlane_b32 s9, v254, 6
	v_lshlrev_b32_e32 v0, 4, v198
	v_ashrrev_i32_e32 v65, 3, v198
	s_addc_u32 s9, s9, s1
	v_and_b32_e32 v192, 0x70, v0
	v_lshlrev_b32_e32 v0, 6, v65
	v_lshl_add_u64 v[4:5], s[8:9], 0, v[192:193]
	v_ashrrev_i32_e32 v1, 31, v0
	v_lshl_add_u64 v[0:1], v[0:1], 1, v[4:5]
	s_waitcnt lgkmcnt(0)
	s_barrier
	global_load_dwordx4 v[0:3], v[0:1], off
	s_movk_i32 s10, 0x90
	v_mad_u64_u32 v[6:7], s[8:9], v65, s10, v[192:193]
	v_add_u32_e32 v151, 0x100, v198
	v_add_u32_e32 v10, 0x200, v198
	v_add_u32_e32 v11, 0x300, v198
	v_cmp_gt_i32_e32 vcc, 32, v198
	s_waitcnt vmcnt(0)
	ds_write_b128 v6, v[0:3]
	v_ashrrev_i32_e32 v6, 3, v151
	v_lshlrev_b32_e32 v0, 6, v6
	v_ashrrev_i32_e32 v1, 31, v0
	v_lshl_add_u64 v[0:1], v[0:1], 1, v[4:5]
	global_load_dwordx4 v[0:3], v[0:1], off
	v_mad_u64_u32 v[6:7], s[8:9], v6, s10, v[192:193]
	s_waitcnt vmcnt(0)
	ds_write_b128 v6, v[0:3]
	v_ashrrev_i32_e32 v6, 3, v10
	v_lshlrev_b32_e32 v0, 6, v6
	v_ashrrev_i32_e32 v1, 31, v0
	v_lshl_add_u64 v[0:1], v[0:1], 1, v[4:5]
	global_load_dwordx4 v[0:3], v[0:1], off
	v_mad_u64_u32 v[6:7], s[8:9], v6, s10, v[192:193]
	s_waitcnt vmcnt(0)
	ds_write_b128 v6, v[0:3]
	v_ashrrev_i32_e32 v6, 3, v11
	v_lshlrev_b32_e32 v0, 6, v6
	v_ashrrev_i32_e32 v1, 31, v0
	v_lshl_add_u64 v[0:1], v[0:1], 1, v[4:5]
	global_load_dwordx4 v[0:3], v[0:1], off
	v_mad_u64_u32 v[4:5], s[8:9], v6, s10, v[192:193]
	v_readlane_b32 s8, v254, 7
	s_add_u32 s0, s8, s0
	v_readlane_b32 s8, v254, 8
	s_addc_u32 s1, s8, s1
	s_movk_i32 s8, 0x108
	s_movk_i32 s10, 0x108
	s_waitcnt vmcnt(0)
	ds_write_b128 v4, v[0:3]
	v_and_b32_e32 v0, 0x7f, v198
	v_ashrrev_i32_e32 v1, 4, v198
	v_lshlrev_b32_e32 v192, 7, v0
	v_and_b32_e32 v4, -8, v1
	v_lshl_add_u64 v[2:3], s[0:1], 0, v[192:193]
	v_ashrrev_i32_e32 v5, 31, v4
	v_lshlrev_b32_e32 v0, 1, v0
	v_lshl_add_u64 v[6:7], v[4:5], 1, v[2:3]
	v_mad_u64_u32 v[8:9], s[0:1], v4, s8, v[0:1]
	global_load_dwordx4 v[4:7], v[6:7], off
	v_ashrrev_i32_e32 v1, 4, v151
	s_waitcnt vmcnt(0)
	ds_write_b16 v8, v4 offset:18432
	ds_write_b16_d16_hi v8, v4 offset:18696
	ds_write_b16 v8, v5 offset:18960
	ds_write_b16_d16_hi v8, v5 offset:19224
	ds_write_b16 v8, v6 offset:19488
	ds_write_b16_d16_hi v8, v6 offset:19752
	ds_write_b16 v8, v7 offset:20016
	ds_write_b16_d16_hi v8, v7 offset:20280
	v_and_b32_e32 v4, -8, v1
	v_ashrrev_i32_e32 v5, 31, v4
	v_lshl_add_u64 v[6:7], v[4:5], 1, v[2:3]
	v_mad_u64_u32 v[8:9], s[0:1], v4, s8, v[0:1]
	global_load_dwordx4 v[4:7], v[6:7], off
	v_ashrrev_i32_e32 v1, 4, v10
	s_waitcnt vmcnt(0)
	ds_write_b16 v8, v4 offset:18432
	ds_write_b16_d16_hi v8, v4 offset:18696
	ds_write_b16 v8, v5 offset:18960
	ds_write_b16_d16_hi v8, v5 offset:19224
	ds_write_b16 v8, v6 offset:19488
	ds_write_b16_d16_hi v8, v6 offset:19752
	ds_write_b16 v8, v7 offset:20016
	ds_write_b16_d16_hi v8, v7 offset:20280
	v_and_b32_e32 v4, -8, v1
	v_ashrrev_i32_e32 v5, 31, v4
	v_lshl_add_u64 v[6:7], v[4:5], 1, v[2:3]
	v_mad_u64_u32 v[8:9], s[0:1], v4, s8, v[0:1]
	global_load_dwordx4 v[4:7], v[6:7], off
	v_ashrrev_i32_e32 v1, 4, v11
	s_waitcnt vmcnt(0)
	ds_write_b16 v8, v4 offset:18432
	ds_write_b16_d16_hi v8, v4 offset:18696
	ds_write_b16 v8, v5 offset:18960
	ds_write_b16_d16_hi v8, v5 offset:19224
	ds_write_b16 v8, v6 offset:19488
	ds_write_b16_d16_hi v8, v6 offset:19752
	ds_write_b16 v8, v7 offset:20016
	ds_write_b16_d16_hi v8, v7 offset:20280
	v_and_b32_e32 v4, -8, v1
	v_ashrrev_i32_e32 v5, 31, v4
	v_lshl_add_u64 v[2:3], v[4:5], 1, v[2:3]
	v_mad_u64_u32 v[4:5], s[0:1], v4, s8, v[0:1]
	global_load_dwordx4 v[0:3], v[2:3], off
	s_waitcnt vmcnt(0)
	ds_write_b16 v4, v0 offset:18432
	ds_write_b16_d16_hi v4, v0 offset:18696
	ds_write_b16 v4, v1 offset:18960
	ds_write_b16_d16_hi v4, v1 offset:19224
	ds_write_b16 v4, v2 offset:19488
	ds_write_b16_d16_hi v4, v2 offset:19752
	ds_write_b16 v4, v3 offset:20016
	ds_write_b16_d16_hi v4, v3 offset:20280
	s_and_saveexec_b64 s[0:1], vcc
	v_mov_b32_e32 v0, 0x11400
	v_lshl_add_u32 v0, v198, 2, v0
	ds_write_b32 v0, v193
	s_or_b64 exec, exec, s[0:1]
	v_cmp_eq_u32_e32 vcc, 32, v198
	s_and_saveexec_b64 s[0:1], vcc
	v_mov_b32_e32 v0, 0x11480
	ds_write_b32 v0, v193
	s_or_b64 exec, exec, s[0:1]
	v_mul_u32_u24_e32 v208, 0x90, v150
	v_lshl_add_u32 v67, v64, 4, v208
	s_waitcnt lgkmcnt(0)
	s_barrier
	ds_read_b128 v[0:3], v67
	ds_read_b128 v[4:7], v67 offset:32
	s_waitcnt lgkmcnt(1)
	v_mfma_f32_32x32x16_bf16 v[48:63], v[0:3], v[160:163], 0
	ds_read_b128 v[0:3], v67 offset:64
	ds_read_b128 v[68:71], v67 offset:13856
	s_mov_b32 s8, 0x3e000000
	s_mov_b32 s0, 0xff61b1e6
	v_lshlrev_b32_e32 v235, 3, v64
	s_waitcnt lgkmcnt(2)
	v_mfma_f32_32x32x16_bf16 v[48:63], v[4:7], v[164:167], v[48:63]
	s_waitcnt lgkmcnt(1)
	v_mfma_f32_32x32x16_bf16 v[48:63], v[0:3], v[168:171], v[48:63]
	ds_read_b128 v[0:3], v67 offset:96
	s_waitcnt lgkmcnt(0)
	v_mfma_f32_32x32x16_bf16 v[48:63], v[0:3], v[172:175], v[48:63]
	ds_read_b128 v[0:3], v67 offset:4608
	s_waitcnt lgkmcnt(0)
	v_mfma_f32_32x32x16_bf16 v[32:47], v[0:3], v[160:163], 0
	ds_read_b128 v[0:3], v67 offset:4640
	s_nop 7
	v_mul_f32_e32 v50, 0x3e000000, v50
	v_mul_f32_e32 v51, 0x3e000000, v51
	v_mul_f32_e32 v54, 0x3e000000, v54
	v_mul_f32_e32 v55, 0x3e000000, v55
	v_mul_f32_e32 v58, 0x3e000000, v58
	v_mul_f32_e32 v59, 0x3e000000, v59
	s_waitcnt lgkmcnt(0)
	v_mfma_f32_32x32x16_bf16 v[32:47], v[0:3], v[164:167], v[32:47]
	ds_read_b128 v[0:3], v67 offset:4672
	v_mul_f32_e32 v62, 0x3e000000, v62
	v_mul_f32_e32 v63, 0x3e000000, v63
	s_waitcnt lgkmcnt(0)
	v_mfma_f32_32x32x16_bf16 v[32:47], v[0:3], v[168:171], v[32:47]
	ds_read_b128 v[0:3], v67 offset:4704
	s_waitcnt lgkmcnt(0)
	v_mfma_f32_32x32x16_bf16 v[32:47], v[0:3], v[172:175], v[32:47]
	ds_read_b128 v[0:3], v67 offset:9216
	s_waitcnt lgkmcnt(0)
	v_mfma_f32_32x32x16_bf16 v[16:31], v[0:3], v[160:163], 0
	ds_read_b128 v[0:3], v67 offset:9248
	s_nop 7
	v_mul_f32_e32 v34, 0x3e000000, v34
	v_mul_f32_e32 v35, 0x3e000000, v35
	v_mul_f32_e32 v38, 0x3e000000, v38
	v_mul_f32_e32 v39, 0x3e000000, v39
	v_mul_f32_e32 v42, 0x3e000000, v42
	v_mul_f32_e32 v43, 0x3e000000, v43
	s_waitcnt lgkmcnt(0)
	v_mfma_f32_32x32x16_bf16 v[16:31], v[0:3], v[164:167], v[16:31]
	ds_read_b128 v[0:3], v67 offset:9280
	v_mul_f32_e32 v46, 0x3e000000, v46
	v_mul_f32_e32 v47, 0x3e000000, v47
	s_waitcnt lgkmcnt(0)
	v_mfma_f32_32x32x16_bf16 v[16:31], v[0:3], v[168:171], v[16:31]
	ds_read_b128 v[0:3], v67 offset:9312
	s_waitcnt lgkmcnt(0)
	v_mfma_f32_32x32x16_bf16 v[16:31], v[0:3], v[172:175], v[16:31]
	ds_read_b128 v[0:3], v67 offset:13824
	s_waitcnt lgkmcnt(0)
	v_mfma_f32_32x32x16_bf16 v[0:15], v[0:3], v[160:163], 0
	s_nop 8
	v_mul_f32_e32 v18, 0x3e000000, v18
	v_mul_f32_e32 v22, 0x3e000000, v22
	v_mul_f32_e32 v23, 0x3e000000, v23
	v_mul_f32_e32 v26, 0x3e000000, v26
	v_mul_f32_e32 v27, 0x3e000000, v27
	v_mul_f32_e32 v30, 0x3e000000, v30
	v_mul_f32_e32 v31, 0x3e000000, v31
	v_mfma_f32_32x32x16_bf16 v[0:15], v[68:71], v[164:167], v[0:15]
	ds_read_b128 v[68:71], v67 offset:13888
	s_waitcnt lgkmcnt(0)
	v_mfma_f32_32x32x16_bf16 v[0:15], v[68:71], v[168:171], v[0:15]
	ds_read_b128 v[68:71], v67 offset:13920
	v_lshlrev_b32_e32 v67, 6, v64
	v_or_b32_e32 v72, 0x600, v67
	s_waitcnt lgkmcnt(0)
	v_mfma_f32_32x32x16_bf16 v[0:15], v[68:71], v[172:175], v[0:15]
	v_mul_f32_e32 v69, 0x3e000000, v19
	v_or_b32_e32 v19, 0x3bf, v67
	v_or_b32_e32 v68, 0x200, v67
	v_or_b32_e32 v71, 0x400, v67
	s_nop 7
	v_mul_f32_e32 v70, 0x3e000000, v2
	v_mbcnt_lo_u32_b32 v2, -1, 0
	v_mbcnt_hi_u32_b32 v2, -1, v2
	v_mul_f32_e32 v74, 0x3e000000, v6
	v_and_b32_e32 v6, 64, v2
	v_mul_f32_e32 v73, 0x3e000000, v3
	v_xor_b32_e32 v3, 32, v2
	v_add_u32_e32 v6, 64, v6
	v_mul_f32_e32 v77, 0x3e000000, v11
	v_cmp_lt_i32_e32 vcc, v3, v6
	v_or_b32_e32 v11, 63, v67
	v_mul_f32_e32 v76, 0x3e000000, v10
	v_cndmask_b32_e32 v2, v2, v3, vcc
	v_cmp_le_i32_e32 vcc, v11, v206
	v_add_u32_e32 v11, 0x4f, v67
	v_mul_f32_e32 v78, 0x3e000000, v14
	v_cndmask_b32_e32 v50, v226, v50, vcc
	v_cmp_le_i32_e32 vcc, v11, v206
	v_or_b32_e32 v11, 0xbf, v67
	v_or_b32_e32 v10, 0x100, v67
	v_cndmask_b32_e32 v51, v226, v51, vcc
	v_cmp_le_i32_e32 vcc, v11, v206
	v_add_u32_e32 v11, 0xcf, v67
	v_or_b32_e32 v14, 0x12f, v67
	v_cndmask_b32_e32 v54, v226, v54, vcc
	v_cmp_le_i32_e32 vcc, v11, v206
	v_mul_f32_e32 v79, 0x3e000000, v15
	v_or_b32_e32 v15, 31, v10
	v_cndmask_b32_e32 v80, v226, v55, vcc
	v_pk_mul_f32 v[10:11], v[56:57], s[8:9] op_sel_hi:[1,0]
	v_cmp_le_i32_e32 vcc, v14, v206
	v_or_b32_e32 v14, 0x2bf, v67
	v_mul_f32_e32 v75, 0x3e000000, v7
	v_cndmask_b32_e32 v57, v226, v11, vcc
	v_cmp_le_i32_e32 vcc, v15, v206
	v_pk_mul_f32 v[6:7], v[48:49], s[8:9] op_sel_hi:[1,0]
	v_pk_mul_f32 v[48:49], v[60:61], s[8:9] op_sel_hi:[1,0]
	v_cndmask_b32_e32 v81, v226, v10, vcc
	v_or_b32_e32 v10, 0x13f, v67
	v_cmp_le_i32_e32 vcc, v10, v206
	v_add_u32_e32 v10, 0x14f, v67
	v_lshlrev_b32_e32 v236, 2, v2
	v_cndmask_b32_e32 v82, v226, v58, vcc
	v_cmp_le_i32_e32 vcc, v10, v206
	v_or_b32_e32 v10, 0x1bf, v67
	v_pk_mul_f32 v[2:3], v[52:53], s[8:9] op_sel_hi:[1,0]
	v_cndmask_b32_e32 v83, v226, v59, vcc
	v_cmp_le_i32_e32 vcc, v10, v206
	v_add_u32_e32 v10, 0x1cf, v67
	v_pk_mul_f32 v[0:1], v[0:1], s[8:9] op_sel_hi:[1,0]
	v_cndmask_b32_e32 v62, v226, v62, vcc
	v_cmp_le_i32_e32 vcc, v10, v206
	v_or_b32_e32 v10, 0x23f, v67
	s_nop 0
	v_cndmask_b32_e32 v84, v226, v63, vcc
	v_cmp_le_i32_e32 vcc, v10, v206
	v_add_u32_e32 v10, 0x24f, v67
	s_nop 0
	v_cndmask_b32_e32 v11, v226, v34, vcc
	v_cmp_le_i32_e32 vcc, v10, v206
	v_or_b32_e32 v34, 0x4bf, v67
	s_nop 0
	v_cndmask_b32_e32 v10, v226, v35, vcc
	v_cmp_le_i32_e32 vcc, v14, v206
	v_add_u32_e32 v14, 0x2cf, v67
	s_nop 0
	v_cndmask_b32_e32 v55, v226, v38, vcc
	v_cmp_le_i32_e32 vcc, v14, v206
	v_or_b32_e32 v14, 0x33f, v67
	s_nop 0
	v_cndmask_b32_e32 v58, v226, v39, vcc
	v_cmp_le_i32_e32 vcc, v14, v206
	v_add_u32_e32 v14, 0x34f, v67
	s_nop 0
	v_cndmask_b32_e32 v15, v226, v42, vcc
	v_cmp_le_i32_e32 vcc, v14, v206
	s_nop 1
	v_cndmask_b32_e32 v14, v226, v43, vcc
	v_cmp_le_i32_e32 vcc, v19, v206
	v_add_u32_e32 v19, 0x3cf, v67
	s_nop 0
	v_cndmask_b32_e32 v61, v226, v46, vcc
	v_cmp_le_i32_e32 vcc, v19, v206
	v_or_b32_e32 v19, 0x43f, v67
	v_or_b32_e32 v46, 0x9f, v67
	v_cndmask_b32_e32 v59, v226, v47, vcc
	v_cmp_le_i32_e32 vcc, v19, v206
	s_nop 1
	v_cndmask_b32_e32 v19, v226, v18, vcc
	v_add_u32_e32 v18, 0x44f, v67
	v_cmp_le_i32_e32 vcc, v18, v206
	s_nop 1
	v_cndmask_b32_e32 v18, v226, v69, vcc
	v_cmp_le_i32_e32 vcc, v34, v206
	v_or_b32_e32 v34, 0xaf, v67
	s_nop 0
	v_cndmask_b32_e32 v53, v226, v22, vcc
	v_add_u32_e32 v22, 0x4cf, v67
	v_cmp_le_i32_e32 vcc, v22, v206
	v_or_b32_e32 v22, 0x53f, v67
	s_nop 0
	v_cndmask_b32_e32 v52, v226, v23, vcc
	v_cmp_le_i32_e32 vcc, v22, v206
	v_add_u32_e32 v22, 0x54f, v67
	s_nop 0
	v_cndmask_b32_e32 v23, v226, v26, vcc
	v_cmp_le_i32_e32 vcc, v22, v206
	v_or_b32_e32 v26, 0x5bf, v67
	s_nop 0
	v_cndmask_b32_e32 v22, v226, v27, vcc
	v_cmp_le_i32_e32 vcc, v26, v206
	v_add_u32_e32 v26, 0x5cf, v67
	s_nop 0
	v_cndmask_b32_e32 v47, v226, v30, vcc
	v_cmp_le_i32_e32 vcc, v26, v206
	v_or_b32_e32 v26, 0x63f, v67
	s_nop 0
	v_cndmask_b32_e32 v43, v226, v31, vcc
	v_cmp_le_i32_e32 vcc, v26, v206
	v_add_u32_e32 v26, 0x64f, v67
	s_nop 0
	v_cndmask_b32_e32 v42, v226, v70, vcc
	v_cmp_le_i32_e32 vcc, v26, v206
	v_or_b32_e32 v26, 0x6bf, v67
	s_nop 0
	v_cndmask_b32_e32 v39, v226, v73, vcc
	v_cmp_le_i32_e32 vcc, v26, v206
	v_add_u32_e32 v26, 0x6cf, v67
	s_nop 0
	v_cndmask_b32_e32 v38, v226, v74, vcc
	v_cmp_le_i32_e32 vcc, v26, v206
	v_or_b32_e32 v26, 0x73f, v67
	s_nop 0
	v_cndmask_b32_e32 v35, v226, v75, vcc
	v_cmp_le_i32_e32 vcc, v26, v206
	v_add_u32_e32 v26, 0x74f, v67
	s_nop 0
	v_cndmask_b32_e32 v31, v226, v76, vcc
	v_cmp_le_i32_e32 vcc, v26, v206
	v_or_b32_e32 v26, 0x7bf, v67
	s_nop 0
	v_cndmask_b32_e32 v30, v226, v77, vcc
	v_cmp_le_i32_e32 vcc, v26, v206
	v_add_u32_e32 v26, 0x7cf, v67
	s_nop 0
	v_cndmask_b32_e32 v27, v226, v78, vcc
	v_cmp_le_i32_e32 vcc, v26, v206
	s_nop 1
	v_cndmask_b32_e32 v26, v226, v79, vcc
	v_cmp_le_i32_e32 vcc, v34, v206
	v_or_b32_e32 v34, 0x19f, v67
	s_nop 0
	v_cndmask_b32_e32 v73, v226, v3, vcc
	v_cmp_le_i32_e32 vcc, v46, v206
	v_or_b32_e32 v3, 31, v67
	s_nop 0
	v_cndmask_b32_e32 v46, v226, v2, vcc
	v_or_b32_e32 v2, 47, v67
	v_cmp_le_i32_e32 vcc, v2, v206
	s_nop 1
	v_cndmask_b32_e32 v7, v226, v7, vcc
	v_cmp_le_i32_e32 vcc, v3, v206
	v_or_b32_e32 v3, 0x1af, v67
	s_nop 0
	v_cndmask_b32_e32 v6, v226, v6, vcc
	v_max3_f32 v2, v6, s0, v7
	v_max3_f32 v2, v2, v50, v51
	v_max3_f32 v2, v2, v46, v73
	v_max3_f32 v2, v2, v54, v80
	v_cmp_le_i32_e32 vcc, v3, v206
	v_max3_f32 v2, v2, v81, v57
	v_max3_f32 v2, v2, v82, v83
	v_cndmask_b32_e32 v74, v226, v49, vcc
	v_cmp_le_i32_e32 vcc, v34, v206
	s_nop 1
	v_cndmask_b32_e32 v75, v226, v48, vcc
	v_max3_f32 v2, v2, v75, v74
	v_max3_f32 v34, v2, v62, v84
	v_pk_mul_f32 v[2:3], v[36:37], s[8:9] op_sel_hi:[1,0]
	v_or_b32_e32 v36, 0x2af, v67
	v_or_b32_e32 v37, 0x29f, v67
	v_cmp_le_i32_e32 vcc, v36, v206
	s_nop 1
	v_cndmask_b32_e32 v76, v226, v3, vcc
	v_cmp_le_i32_e32 vcc, v37, v206
	s_nop 1
	v_cndmask_b32_e32 v77, v226, v2, vcc
	v_pk_mul_f32 v[2:3], v[32:33], s[8:9] op_sel_hi:[1,0]
	v_or_b32_e32 v32, 0x22f, v67
	v_or_b32_e32 v33, 31, v68
	v_cmp_le_i32_e32 vcc, v32, v206
	s_nop 1
	v_cndmask_b32_e32 v78, v226, v3, vcc
	v_cmp_le_i32_e32 vcc, v33, v206
	v_or_b32_e32 v33, 0x3af, v67
	s_nop 0
	v_cndmask_b32_e32 v79, v226, v2, vcc
	v_max3_f32 v2, v34, v79, v78
	v_max3_f32 v2, v2, v11, v10
	v_max3_f32 v2, v2, v77, v76
	v_max3_f32 v32, v2, v55, v58
	v_pk_mul_f32 v[2:3], v[44:45], s[8:9] op_sel_hi:[1,0]
	v_or_b32_e32 v34, 0x39f, v67
	v_cmp_le_i32_e32 vcc, v33, v206
	v_or_b32_e32 v33, 0x32f, v67
	s_nop 0
	v_cndmask_b32_e32 v69, v226, v3, vcc
	v_cmp_le_i32_e32 vcc, v34, v206
	v_or_b32_e32 v34, 0x31f, v67
	s_nop 0
	v_cndmask_b32_e32 v70, v226, v2, vcc
	v_pk_mul_f32 v[2:3], v[40:41], s[8:9] op_sel_hi:[1,0]
	v_cmp_le_i32_e32 vcc, v33, v206
	v_or_b32_e32 v33, 0x49f, v67
	s_nop 0
	v_cndmask_b32_e32 v85, v226, v3, vcc
	v_cmp_le_i32_e32 vcc, v34, v206
	s_nop 1
	v_cndmask_b32_e32 v86, v226, v2, vcc
	v_max3_f32 v2, v32, v86, v85
	v_max3_f32 v2, v2, v15, v14
	v_max3_f32 v2, v2, v70, v69
	v_max3_f32 v32, v2, v61, v59
	v_pk_mul_f32 v[2:3], v[20:21], s[8:9] op_sel_hi:[1,0]
	v_or_b32_e32 v20, 0x4af, v67
	v_cmp_le_i32_e32 vcc, v20, v206
	v_or_b32_e32 v20, 0x5af, v67
	s_nop 0
	v_cndmask_b32_e32 v21, v226, v3, vcc
	v_cmp_le_i32_e32 vcc, v33, v206
	s_nop 1
	v_cndmask_b32_e32 v63, v226, v2, vcc
	v_pk_mul_f32 v[2:3], v[16:17], s[8:9] op_sel_hi:[1,0]
	v_or_b32_e32 v16, 0x42f, v67
	v_or_b32_e32 v17, 31, v71
	v_cmp_le_i32_e32 vcc, v16, v206
	s_nop 1
	v_cndmask_b32_e32 v16, v226, v3, vcc
	v_cmp_le_i32_e32 vcc, v17, v206
	s_nop 1
	v_cndmask_b32_e32 v68, v226, v2, vcc
	v_max3_f32 v2, v32, v68, v16
	v_max3_f32 v2, v2, v19, v18
	v_max3_f32 v2, v2, v63, v21
	v_max3_f32 v17, v2, v53, v52
	v_pk_mul_f32 v[2:3], v[28:29], s[8:9] op_sel_hi:[1,0]
	v_or_b32_e32 v28, 0x59f, v67
	v_cmp_le_i32_e32 vcc, v20, v206
	v_or_b32_e32 v20, 0x52f, v67
	s_nop 0
	v_cndmask_b32_e32 v29, v226, v3, vcc
	v_cmp_le_i32_e32 vcc, v28, v206
	s_nop 1
	v_cndmask_b32_e32 v56, v226, v2, vcc
	v_pk_mul_f32 v[2:3], v[24:25], s[8:9] op_sel_hi:[1,0]
	v_or_b32_e32 v24, 0x51f, v67
	v_cmp_le_i32_e32 vcc, v20, v206
	s_nop 1
	v_cndmask_b32_e32 v20, v226, v3, vcc
	v_cmp_le_i32_e32 vcc, v24, v206
	s_nop 1
	v_cndmask_b32_e32 v60, v226, v2, vcc
	v_max3_f32 v2, v17, v60, v20
	v_max3_f32 v2, v2, v23, v22
	v_max3_f32 v2, v2, v56, v29
	v_max3_f32 v17, v2, v47, v43
	v_pk_mul_f32 v[2:3], v[4:5], s[8:9] op_sel_hi:[1,0]
	v_or_b32_e32 v4, 0x6af, v67
	v_or_b32_e32 v5, 0x69f, v67
	v_cmp_le_i32_e32 vcc, v4, v206
	v_or_b32_e32 v4, 0x79f, v67
	s_nop 0
	v_cndmask_b32_e32 v32, v226, v3, vcc
	v_cmp_le_i32_e32 vcc, v5, v206
	v_or_b32_e32 v3, 31, v72
	s_nop 0
	v_cndmask_b32_e32 v48, v226, v2, vcc
	v_or_b32_e32 v2, 0x62f, v67
	v_cmp_le_i32_e32 vcc, v2, v206
	s_nop 1
	v_cndmask_b32_e32 v28, v226, v1, vcc
	v_cmp_le_i32_e32 vcc, v3, v206
	v_or_b32_e32 v3, 0x7af, v67
	s_nop 0
	v_cndmask_b32_e32 v33, v226, v0, vcc
	v_max3_f32 v0, v17, v33, v28
	v_max3_f32 v0, v0, v42, v39
	v_max3_f32 v0, v0, v48, v32
	v_max3_f32 v2, v0, v38, v35
	v_pk_mul_f32 v[0:1], v[12:13], s[8:9] op_sel_hi:[1,0]
	v_cmp_le_i32_e32 vcc, v3, v206
	v_or_b32_e32 v3, 0x72f, v67
	s_nop 0
	v_cndmask_b32_e32 v25, v226, v1, vcc
	v_cmp_le_i32_e32 vcc, v4, v206
	v_or_b32_e32 v4, 0x71f, v67
	s_nop 0
	v_cndmask_b32_e32 v37, v226, v0, vcc
	v_pk_mul_f32 v[0:1], v[8:9], s[8:9] op_sel_hi:[1,0]
	v_cmp_le_i32_e32 vcc, v3, v206
	s_nop 1
	v_cndmask_b32_e32 v44, v226, v1, vcc
	v_cmp_le_i32_e32 vcc, v4, v206
	s_nop 1
	v_cndmask_b32_e32 v45, v226, v0, vcc
	v_max3_f32 v0, v2, v45, v44
	v_max3_f32 v0, v0, v31, v30
	v_max3_f32 v0, v0, v37, v25
	v_max3_f32 v0, v0, v27, v26
	ds_bpermute_b32 v1, v236, v0
	v_cmp_neq_f32_e32 vcc, s0, v7
	s_waitcnt lgkmcnt(0)
	v_max_f32_e32 v1, v1, v1
	v_max_f32_e32 v24, v0, v1
	v_sub_f32_e32 v1, v7, v24
	v_sub_f32_e32 v0, v6, v24
	v_mul_f32_e32 v1, 0x3fb8aa3b, v1
	v_mul_f32_e32 v0, 0x3fb8aa3b, v0
	v_exp_f32_e32 v1, v1
	v_sub_f32_e32 v3, v50, v24
	v_exp_f32_e32 v0, v0
	v_mul_f32_e32 v3, 0x3fb8aa3b, v3
	v_exp_f32_e32 v3, v3
	v_cndmask_b32_e32 v1, 0, v1, vcc
	v_cmp_neq_f32_e32 vcc, s0, v6
	v_sub_f32_e32 v5, v54, v24
	v_mul_f32_e32 v5, 0x3fb8aa3b, v5
	v_cndmask_b32_e32 v0, 0, v0, vcc
	v_cmp_neq_f32_e32 vcc, s0, v50
	v_add_f32_e32 v2, 0, v0
	v_add_f32_e32 v2, v1, v2
	v_cndmask_b32_e32 v34, 0, v3, vcc
	v_sub_f32_e32 v3, v51, v24
	v_mul_f32_e32 v3, 0x3fb8aa3b, v3
	v_exp_f32_e32 v3, v3
	v_cmp_neq_f32_e32 vcc, s0, v51
	v_add_f32_e32 v2, v34, v2
	v_exp_f32_e32 v5, v5
	v_cndmask_b32_e32 v40, 0, v3, vcc
	v_sub_f32_e32 v3, v73, v24
	v_add_f32_e32 v4, v40, v2
	v_sub_f32_e32 v2, v46, v24
	v_mul_f32_e32 v3, 0x3fb8aa3b, v3
	v_mul_f32_e32 v2, 0x3fb8aa3b, v2
	v_exp_f32_e32 v3, v3
	v_exp_f32_e32 v2, v2
	v_cmp_neq_f32_e32 vcc, s0, v73
	v_sub_f32_e32 v7, v82, v24
	v_mul_f32_e32 v7, 0x3fb8aa3b, v7
	v_cndmask_b32_e32 v3, 0, v3, vcc
	v_cmp_neq_f32_e32 vcc, s0, v46
	v_exp_f32_e32 v7, v7
	v_sub_f32_e32 v9, v62, v24
	v_cndmask_b32_e32 v2, 0, v2, vcc
	v_cmp_neq_f32_e32 vcc, s0, v54
	v_add_f32_e32 v4, v2, v4
	v_add_f32_e32 v4, v3, v4
	v_cndmask_b32_e32 v36, 0, v5, vcc
	v_sub_f32_e32 v5, v80, v24
	v_mul_f32_e32 v5, 0x3fb8aa3b, v5
	v_exp_f32_e32 v5, v5
	v_cmp_neq_f32_e32 vcc, s0, v80
	v_add_f32_e32 v4, v36, v4
	v_mul_f32_e32 v9, 0x3fb8aa3b, v9
	v_cndmask_b32_e32 v46, 0, v5, vcc
	v_sub_f32_e32 v5, v57, v24
	v_add_f32_e32 v6, v46, v4
	v_sub_f32_e32 v4, v81, v24
	v_mul_f32_e32 v5, 0x3fb8aa3b, v5
	v_mul_f32_e32 v4, 0x3fb8aa3b, v4
	v_exp_f32_e32 v5, v5
	v_exp_f32_e32 v4, v4
	v_cmp_neq_f32_e32 vcc, s0, v57
	v_exp_f32_e32 v9, v9
	v_sub_f32_e32 v13, v11, v24
	v_cndmask_b32_e32 v5, 0, v5, vcc
	v_cmp_neq_f32_e32 vcc, s0, v81
	v_mul_f32_e32 v13, 0x3fb8aa3b, v13
	v_exp_f32_e32 v13, v13
	v_cndmask_b32_e32 v4, 0, v4, vcc
	v_cmp_neq_f32_e32 vcc, s0, v82
	v_add_f32_e32 v6, v4, v6
	v_add_f32_e32 v6, v5, v6
	v_cndmask_b32_e32 v41, 0, v7, vcc
	v_sub_f32_e32 v7, v83, v24
	v_mul_f32_e32 v7, 0x3fb8aa3b, v7
	v_exp_f32_e32 v7, v7
	v_cmp_neq_f32_e32 vcc, s0, v83
	v_add_f32_e32 v6, v41, v6
	s_nop 0
	v_cndmask_b32_e32 v49, 0, v7, vcc
	v_sub_f32_e32 v7, v74, v24
	v_add_f32_e32 v8, v49, v6
	v_sub_f32_e32 v6, v75, v24
	v_mul_f32_e32 v7, 0x3fb8aa3b, v7
	v_mul_f32_e32 v6, 0x3fb8aa3b, v6
	v_exp_f32_e32 v7, v7
	v_exp_f32_e32 v6, v6
	v_cmp_neq_f32_e32 vcc, s0, v74
	s_nop 1
	v_cndmask_b32_e32 v7, 0, v7, vcc
	v_cmp_neq_f32_e32 vcc, s0, v75
	s_nop 1
	v_cndmask_b32_e32 v6, 0, v6, vcc
	v_cmp_neq_f32_e32 vcc, s0, v62
	v_add_f32_e32 v8, v6, v8
	v_add_f32_e32 v8, v7, v8
	v_cndmask_b32_e32 v50, 0, v9, vcc
	v_sub_f32_e32 v9, v84, v24
	v_mul_f32_e32 v9, 0x3fb8aa3b, v9
	v_exp_f32_e32 v9, v9
	v_cmp_neq_f32_e32 vcc, s0, v84
	v_add_f32_e32 v8, v50, v8
	s_nop 0
	v_cndmask_b32_e32 v54, 0, v9, vcc
	v_sub_f32_e32 v9, v78, v24
	v_add_f32_e32 v12, v54, v8
	v_sub_f32_e32 v8, v79, v24
	v_mul_f32_e32 v9, 0x3fb8aa3b, v9
	v_mul_f32_e32 v8, 0x3fb8aa3b, v8
	v_exp_f32_e32 v9, v9
	v_exp_f32_e32 v8, v8
	v_cmp_neq_f32_e32 vcc, s0, v78
	s_nop 1
	v_cndmask_b32_e32 v9, 0, v9, vcc
	v_cmp_neq_f32_e32 vcc, s0, v79
	s_nop 1
	v_cndmask_b32_e32 v8, 0, v8, vcc
	v_add_f32_e32 v12, v8, v12
	v_cmp_neq_f32_e32 vcc, s0, v11
	v_add_f32_e32 v12, v9, v12
	s_nop 0
	v_cndmask_b32_e32 v51, 0, v13, vcc
	v_add_f32_e32 v11, v51, v12
	v_sub_f32_e32 v12, v10, v24
	v_mul_f32_e32 v12, 0x3fb8aa3b, v12
	v_exp_f32_e32 v12, v12
	v_cmp_neq_f32_e32 vcc, s0, v10
	v_sub_f32_e32 v10, v77, v24
	v_mul_f32_e32 v10, 0x3fb8aa3b, v10
	v_cndmask_b32_e32 v57, 0, v12, vcc
	v_add_f32_e32 v12, v57, v11
	v_sub_f32_e32 v11, v76, v24
	v_mul_f32_e32 v11, 0x3fb8aa3b, v11
	v_exp_f32_e32 v11, v11
	v_sub_f32_e32 v13, v55, v24
	v_exp_f32_e32 v10, v10
	v_mul_f32_e32 v13, 0x3fb8aa3b, v13
	v_exp_f32_e32 v13, v13
	v_cmp_neq_f32_e32 vcc, s0, v76
	s_nop 1
	v_cndmask_b32_e32 v11, 0, v11, vcc
	v_cmp_neq_f32_e32 vcc, s0, v77
	s_nop 1
	v_cndmask_b32_e32 v10, 0, v10, vcc
	v_cmp_neq_f32_e32 vcc, s0, v55
	v_add_f32_e32 v12, v10, v12
	v_add_f32_e32 v12, v11, v12
	v_cndmask_b32_e32 v55, 0, v13, vcc
	v_sub_f32_e32 v13, v58, v24
	v_mul_f32_e32 v13, 0x3fb8aa3b, v13
	v_exp_f32_e32 v13, v13
	v_cmp_neq_f32_e32 vcc, s0, v58
	v_add_f32_e32 v12, v55, v12
	v_sub_f32_e32 v58, v15, v24
	v_cndmask_b32_e32 v62, 0, v13, vcc
	v_sub_f32_e32 v13, v85, v24
	v_add_f32_e32 v17, v62, v12
	v_sub_f32_e32 v12, v86, v24
	v_mul_f32_e32 v13, 0x3fb8aa3b, v13
	v_mul_f32_e32 v12, 0x3fb8aa3b, v12
	v_exp_f32_e32 v13, v13
	v_exp_f32_e32 v12, v12
	v_mul_f32_e32 v58, 0x3fb8aa3b, v58
	v_cmp_neq_f32_e32 vcc, s0, v85
	v_exp_f32_e32 v58, v58
	s_nop 0
	v_cndmask_b32_e32 v13, 0, v13, vcc
	v_cmp_neq_f32_e32 vcc, s0, v86
	s_nop 1
	v_cndmask_b32_e32 v12, 0, v12, vcc
	v_add_f32_e32 v17, v12, v17
	v_cmp_neq_f32_e32 vcc, s0, v15
	v_add_f32_e32 v17, v13, v17
	s_nop 0
	v_cndmask_b32_e32 v58, 0, v58, vcc
	v_add_f32_e32 v15, v58, v17
	v_sub_f32_e32 v17, v14, v24
	v_mul_f32_e32 v17, 0x3fb8aa3b, v17
	v_exp_f32_e32 v17, v17
	v_cmp_neq_f32_e32 vcc, s0, v14
	v_sub_f32_e32 v14, v70, v24
	v_mul_f32_e32 v14, 0x3fb8aa3b, v14
	v_cndmask_b32_e32 v67, 0, v17, vcc
	v_add_f32_e32 v17, v67, v15
	v_sub_f32_e32 v15, v69, v24
	v_mul_f32_e32 v15, 0x3fb8aa3b, v15
	v_exp_f32_e32 v15, v15
	v_cmp_neq_f32_e32 vcc, s0, v69
	v_sub_f32_e32 v69, v61, v24
	v_exp_f32_e32 v14, v14
	v_mul_f32_e32 v69, 0x3fb8aa3b, v69
	v_exp_f32_e32 v69, v69
	v_cndmask_b32_e32 v15, 0, v15, vcc
	v_cmp_neq_f32_e32 vcc, s0, v70
	s_nop 1
	v_cndmask_b32_e32 v14, 0, v14, vcc
	v_cmp_neq_f32_e32 vcc, s0, v61
	v_add_f32_e32 v17, v14, v17
	v_add_f32_e32 v17, v15, v17
	v_cndmask_b32_e32 v61, 0, v69, vcc
	v_sub_f32_e32 v69, v59, v24
	v_mul_f32_e32 v69, 0x3fb8aa3b, v69
	v_exp_f32_e32 v69, v69
	v_cmp_neq_f32_e32 vcc, s0, v59
	v_add_f32_e32 v17, v61, v17
	s_nop 0
	v_cndmask_b32_e32 v69, 0, v69, vcc
	v_add_f32_e32 v59, v69, v17
	v_sub_f32_e32 v17, v68, v24
	v_mul_f32_e32 v17, 0x3fb8aa3b, v17
	v_exp_f32_e32 v70, v17
	v_sub_f32_e32 v17, v16, v24
	v_mul_f32_e32 v17, 0x3fb8aa3b, v17
	v_exp_f32_e32 v17, v17
	v_cmp_neq_f32_e32 vcc, s0, v16
	s_nop 1
	v_cndmask_b32_e32 v17, 0, v17, vcc
	v_cmp_neq_f32_e32 vcc, s0, v68
	s_nop 1
	v_cndmask_b32_e32 v16, 0, v70, vcc
	v_add_f32_e32 v59, v16, v59
	v_add_f32_e32 v68, v17, v59
	v_sub_f32_e32 v59, v19, v24
	v_mul_f32_e32 v59, 0x3fb8aa3b, v59
	v_exp_f32_e32 v59, v59
	v_cmp_neq_f32_e32 vcc, s0, v19
	s_nop 1
	v_cndmask_b32_e32 v59, 0, v59, vcc
	v_add_f32_e32 v19, v59, v68
	v_sub_f32_e32 v68, v18, v24
	v_mul_f32_e32 v68, 0x3fb8aa3b, v68
	v_exp_f32_e32 v68, v68
	v_cmp_neq_f32_e32 vcc, s0, v18
	v_sub_f32_e32 v18, v63, v24
	v_mul_f32_e32 v18, 0x3fb8aa3b, v18
	v_cndmask_b32_e32 v68, 0, v68, vcc
	v_add_f32_e32 v70, v68, v19
	v_sub_f32_e32 v19, v21, v24
	v_mul_f32_e32 v19, 0x3fb8aa3b, v19
	v_exp_f32_e32 v19, v19
	v_cmp_neq_f32_e32 vcc, s0, v21
	v_exp_f32_e32 v18, v18
	s_nop 0
	v_cndmask_b32_e32 v19, 0, v19, vcc
	v_cmp_neq_f32_e32 vcc, s0, v63
	v_sub_f32_e32 v63, v53, v24
	v_mul_f32_e32 v63, 0x3fb8aa3b, v63
	v_exp_f32_e32 v63, v63
	v_cndmask_b32_e32 v18, 0, v18, vcc
	v_cmp_neq_f32_e32 vcc, s0, v53
	v_add_f32_e32 v21, v18, v70
	v_add_f32_e32 v21, v19, v21
	v_cndmask_b32_e32 v53, 0, v63, vcc
	v_sub_f32_e32 v63, v52, v24
	v_mul_f32_e32 v63, 0x3fb8aa3b, v63
	v_exp_f32_e32 v63, v63
	v_cmp_neq_f32_e32 vcc, s0, v52
	v_add_f32_e32 v21, v53, v21
	s_nop 0
	v_cndmask_b32_e32 v52, 0, v63, vcc
	v_add_f32_e32 v63, v52, v21
	v_sub_f32_e32 v21, v60, v24
	v_mul_f32_e32 v21, 0x3fb8aa3b, v21
	v_exp_f32_e32 v70, v21
	v_sub_f32_e32 v21, v20, v24
	v_mul_f32_e32 v21, 0x3fb8aa3b, v21
	v_exp_f32_e32 v21, v21
	v_cmp_neq_f32_e32 vcc, s0, v20
	s_nop 1
	v_cndmask_b32_e32 v21, 0, v21, vcc
	v_cmp_neq_f32_e32 vcc, s0, v60
	s_nop 1
	v_cndmask_b32_e32 v20, 0, v70, vcc
	v_add_f32_e32 v60, v20, v63
	v_sub_f32_e32 v63, v23, v24
	v_mul_f32_e32 v63, 0x3fb8aa3b, v63
	v_exp_f32_e32 v63, v63
	v_cmp_neq_f32_e32 vcc, s0, v23
	v_add_f32_e32 v60, v21, v60
	s_nop 0
	v_cndmask_b32_e32 v63, 0, v63, vcc
	v_add_f32_e32 v23, v63, v60
	v_sub_f32_e32 v60, v22, v24
	v_mul_f32_e32 v60, 0x3fb8aa3b, v60
	v_exp_f32_e32 v60, v60
	v_cmp_neq_f32_e32 vcc, s0, v22
	v_sub_f32_e32 v22, v56, v24
	v_mul_f32_e32 v22, 0x3fb8aa3b, v22
	v_cndmask_b32_e32 v60, 0, v60, vcc
	v_add_f32_e32 v70, v60, v23
	v_sub_f32_e32 v23, v29, v24
	v_mul_f32_e32 v23, 0x3fb8aa3b, v23
	v_exp_f32_e32 v23, v23
	v_cmp_neq_f32_e32 vcc, s0, v29
	v_exp_f32_e32 v22, v22
	s_nop 0
	v_cndmask_b32_e32 v23, 0, v23, vcc
	v_cmp_neq_f32_e32 vcc, s0, v56
	v_sub_f32_e32 v56, v47, v24
	v_mul_f32_e32 v56, 0x3fb8aa3b, v56
	v_exp_f32_e32 v56, v56
	v_cndmask_b32_e32 v22, 0, v22, vcc
	v_cmp_neq_f32_e32 vcc, s0, v47
	v_add_f32_e32 v29, v22, v70
	v_add_f32_e32 v29, v23, v29
	v_cndmask_b32_e32 v47, 0, v56, vcc
	v_sub_f32_e32 v56, v43, v24
	v_mul_f32_e32 v56, 0x3fb8aa3b, v56
	v_exp_f32_e32 v56, v56
	v_cmp_neq_f32_e32 vcc, s0, v43
	v_add_f32_e32 v29, v47, v29
	s_nop 0
	v_cndmask_b32_e32 v56, 0, v56, vcc
	v_add_f32_e32 v43, v56, v29
	v_sub_f32_e32 v29, v33, v24
	v_mul_f32_e32 v29, 0x3fb8aa3b, v29
	v_exp_f32_e32 v70, v29
	v_sub_f32_e32 v29, v28, v24
	v_mul_f32_e32 v29, 0x3fb8aa3b, v29
	v_exp_f32_e32 v29, v29
	v_cmp_neq_f32_e32 vcc, s0, v28
	s_nop 1
	v_cndmask_b32_e32 v29, 0, v29, vcc
	v_cmp_neq_f32_e32 vcc, s0, v33
	s_nop 1
	v_cndmask_b32_e32 v28, 0, v70, vcc
	v_add_f32_e32 v33, v28, v43
	v_sub_f32_e32 v43, v42, v24
	v_mul_f32_e32 v43, 0x3fb8aa3b, v43
	v_cmp_neq_f32_e32 vcc, s0, v42
	v_sub_f32_e32 v42, v39, v24
	v_exp_f32_e32 v43, v43
	v_mul_f32_e32 v42, 0x3fb8aa3b, v42
	v_exp_f32_e32 v42, v42
	v_add_f32_e32 v33, v29, v33
	v_cndmask_b32_e32 v78, 0, v43, vcc
	v_cmp_neq_f32_e32 vcc, s0, v39
	v_add_f32_e32 v33, v78, v33
	v_sub_f32_e32 v43, v31, v24
	v_cndmask_b32_e32 v79, 0, v42, vcc
	v_add_f32_e32 v39, v79, v33
	v_sub_f32_e32 v33, v48, v24
	v_mul_f32_e32 v33, 0x3fb8aa3b, v33
	v_exp_f32_e32 v42, v33
	v_sub_f32_e32 v33, v32, v24
	v_mul_f32_e32 v33, 0x3fb8aa3b, v33
	v_exp_f32_e32 v33, v33
	v_cmp_neq_f32_e32 vcc, s0, v32
	v_mul_f32_e32 v43, 0x3fb8aa3b, v43
	v_exp_f32_e32 v43, v43
	v_cndmask_b32_e32 v33, 0, v33, vcc
	v_cmp_neq_f32_e32 vcc, s0, v48
	s_nop 1
	v_cndmask_b32_e32 v32, 0, v42, vcc
	v_sub_f32_e32 v42, v38, v24
	v_mul_f32_e32 v42, 0x3fb8aa3b, v42
	v_exp_f32_e32 v42, v42
	v_add_f32_e32 v39, v32, v39
	v_cmp_neq_f32_e32 vcc, s0, v38
	v_add_f32_e32 v39, v33, v39
	s_nop 0
	v_cndmask_b32_e32 v80, 0, v42, vcc
	v_add_f32_e32 v38, v80, v39
	v_sub_f32_e32 v39, v35, v24
	v_mul_f32_e32 v39, 0x3fb8aa3b, v39
	v_exp_f32_e32 v39, v39
	v_cmp_neq_f32_e32 vcc, s0, v35
	s_nop 1
	v_cndmask_b32_e32 v35, 0, v39, vcc
	v_sub_f32_e32 v39, v44, v24
	v_add_f32_e32 v42, v35, v38
	v_sub_f32_e32 v38, v45, v24
	v_mul_f32_e32 v39, 0x3fb8aa3b, v39
	v_mul_f32_e32 v38, 0x3fb8aa3b, v38
	v_exp_f32_e32 v39, v39
	v_exp_f32_e32 v38, v38
	v_cmp_neq_f32_e32 vcc, s0, v44
	s_nop 1
	v_cndmask_b32_e32 v39, 0, v39, vcc
	v_cmp_neq_f32_e32 vcc, s0, v45
	s_nop 1
	v_cndmask_b32_e32 v38, 0, v38, vcc
	v_add_f32_e32 v42, v38, v42
	v_cmp_neq_f32_e32 vcc, s0, v31
	v_add_f32_e32 v42, v39, v42
	s_nop 0
	v_cndmask_b32_e32 v45, 0, v43, vcc
	v_add_f32_e32 v31, v45, v42
	v_sub_f32_e32 v42, v30, v24
	v_mul_f32_e32 v42, 0x3fb8aa3b, v42
	v_exp_f32_e32 v42, v42
	v_cmp_neq_f32_e32 vcc, s0, v30
	s_nop 1
	v_cndmask_b32_e32 v81, 0, v42, vcc
	v_sub_f32_e32 v42, v25, v24
	v_add_f32_e32 v30, v81, v31
	v_sub_f32_e32 v31, v37, v24
	v_mul_f32_e32 v42, 0x3fb8aa3b, v42
	v_mul_f32_e32 v31, 0x3fb8aa3b, v31
	v_exp_f32_e32 v42, v42
	v_exp_f32_e32 v31, v31
	v_cmp_neq_f32_e32 vcc, s0, v25
	s_nop 1
	v_cndmask_b32_e32 v43, 0, v42, vcc
	v_cmp_neq_f32_e32 vcc, s0, v37
	s_nop 1
	v_cndmask_b32_e32 v42, 0, v31, vcc
	v_add_f32_e32 v25, v42, v30
	v_sub_f32_e32 v30, v27, v24
	v_mul_f32_e32 v30, 0x3fb8aa3b, v30
	v_sub_f32_e32 v24, v26, v24
	v_exp_f32_e32 v30, v30
	v_mul_f32_e32 v24, 0x3fb8aa3b, v24
	v_exp_f32_e32 v24, v24
	v_cmp_neq_f32_e32 vcc, s0, v27
	v_add_f32_e32 v25, v43, v25
	s_nop 0
	v_cndmask_b32_e32 v37, 0, v30, vcc
	v_cmp_neq_f32_e32 vcc, s0, v26
	v_add_f32_e32 v25, v37, v25
	s_nop 0
	v_cndmask_b32_e32 v82, 0, v24, vcc
	v_add_f32_e32 v24, v82, v25
	ds_bpermute_b32 v25, v236, v24
	s_waitcnt lgkmcnt(0)
	v_add_f32_e32 v24, v24, v25
	v_max_f32_e32 v24, 0xda24260, v24
	v_div_scale_f32 v25, s[0:1], v24, v24, 1.0
	v_rcp_f32_e32 v26, v25
	s_nop 0
	v_fma_f32 v27, -v25, v26, 1.0
	v_fmac_f32_e32 v26, v27, v26
	v_div_scale_f32 v27, vcc, 1.0, v24, 1.0
	v_mul_f32_e32 v30, v27, v26
	v_fma_f32 v31, -v25, v30, v27
	v_fmac_f32_e32 v30, v31, v26
	v_fma_f32 v25, -v25, v30, v27
	v_div_fmas_f32 v25, v25, v26, v30
	v_div_fixup_f32 v44, v25, v24, 1.0
	v_pk_mul_f32 v[70:71], v[0:1], v[44:45] op_sel_hi:[1,0]
	v_mul_f32_e32 v40, v40, v44
	v_pk_mul_f32 v[74:75], v[4:5], v[44:45] op_sel_hi:[1,0]
	v_pk_mul_f32 v[4:5], v[28:29], v[44:45] op_sel_hi:[1,0]
	v_lshl_or_b32 v28, v66, 5, v150
	v_pk_mul_f32 v[72:73], v[2:3], v[44:45] op_sel_hi:[1,0]
	v_mul_f32_e32 v46, v46, v44
	v_pk_mul_f32 v[76:77], v[6:7], v[44:45] op_sel_hi:[1,0]
	v_pk_mul_f32 v[6:7], v[32:33], v[44:45] op_sel_hi:[1,0]
	v_lshl_add_u32 v28, v28, 5, v28
	v_add_f32_e32 v29, v70, v71
	v_fma_f32 v32, v34, v44, v40
	v_add_f32_e32 v29, v29, v32
	v_add_lshl_u32 v28, v28, v64, 2
	v_add_f32_e32 v32, v72, v73
	v_fma_f32 v33, v36, v44, v46
	v_mul_f32_e32 v97, v49, v44
	v_add_f32_e32 v32, v32, v33
	v_add_u32_e32 v33, 0x9000, v28
	v_mul_f32_e32 v54, v54, v44
	ds_write2_b32 v33, v29, v32 offset1:2
	v_add_f32_e32 v29, v74, v75
	v_fma_f32 v32, v41, v44, v97
	v_mul_f32_e32 v83, v34, v44
	v_add_f32_e32 v29, v29, v32
	v_add_f32_e32 v32, v76, v77
	v_fma_f32 v34, v50, v44, v54
	v_pk_mul_f32 v[30:31], v[8:9], v[44:45] op_sel_hi:[1,0]
	v_mul_f32_e32 v100, v57, v44
	v_add_u32_e32 v28, 0xd000, v28
	v_add_f32_e32 v32, v32, v34
	v_pk_mul_f32 v[48:49], v[10:11], v[44:45] op_sel_hi:[1,0]
	v_mul_f32_e32 v62, v62, v44
	ds_write2_b32 v28, v40, v46 offset0:128 offset1:130
	ds_write2_b32 v33, v29, v32 offset0:4 offset1:6
	ds_write2_b32 v28, v97, v54 offset0:132 offset1:134
	v_add_f32_e32 v29, v30, v31
	v_fma_f32 v32, v51, v44, v100
	v_add_f32_e32 v29, v29, v32
	v_add_f32_e32 v32, v48, v49
	v_fma_f32 v34, v55, v44, v62
	v_pk_mul_f32 v[24:25], v[12:13], v[44:45] op_sel_hi:[1,0]
	v_mul_f32_e32 v67, v67, v44
	v_add_f32_e32 v32, v32, v34
	v_pk_mul_f32 v[26:27], v[14:15], v[44:45] op_sel_hi:[1,0]
	v_mul_f32_e32 v69, v69, v44
	ds_write2_b32 v33, v29, v32 offset0:8 offset1:10
	ds_write2_b32 v28, v100, v62 offset0:136 offset1:138
	v_add_f32_e32 v29, v24, v25
	v_fma_f32 v32, v58, v44, v67
	v_add_f32_e32 v29, v29, v32
	v_add_f32_e32 v32, v26, v27
	v_fma_f32 v34, v61, v44, v69
	v_pk_mul_f32 v[12:13], v[16:17], v[44:45] op_sel_hi:[1,0]
	v_mul_f32_e32 v68, v68, v44
	v_add_f32_e32 v32, v32, v34
	v_pk_mul_f32 v[14:15], v[18:19], v[44:45] op_sel_hi:[1,0]
	v_mul_f32_e32 v106, v52, v44
	ds_write2_b32 v33, v29, v32 offset0:12 offset1:14
	ds_write2_b32 v28, v67, v69 offset0:140 offset1:142
	v_add_f32_e32 v29, v12, v13
	v_fma_f32 v32, v59, v44, v68
	v_add_f32_e32 v29, v29, v32
	v_add_f32_e32 v32, v14, v15
	v_fma_f32 v34, v53, v44, v106
	v_pk_mul_f32 v[8:9], v[20:21], v[44:45] op_sel_hi:[1,0]
	v_mul_f32_e32 v108, v60, v44
	v_add_f32_e32 v32, v32, v34
	v_pk_mul_f32 v[10:11], v[22:23], v[44:45] op_sel_hi:[1,0]
	v_mul_f32_e32 v110, v56, v44
	ds_write2_b32 v33, v29, v32 offset0:16 offset1:18
	ds_write2_b32 v28, v68, v106 offset0:144 offset1:146
	v_add_f32_e32 v29, v8, v9
	v_fma_f32 v32, v63, v44, v108
	v_add_f32_e32 v29, v29, v32
	v_add_f32_e32 v32, v10, v11
	v_fma_f32 v34, v47, v44, v110
	v_mul_f32_e32 v21, v79, v44
	v_add_f32_e32 v32, v32, v34
	v_mul_f32_e32 v23, v35, v44
	ds_write2_b32 v33, v29, v32 offset0:20 offset1:22
	ds_write2_b32 v28, v108, v110 offset0:148 offset1:150
	v_add_f32_e32 v29, v4, v5
	v_fma_f32 v32, v78, v44, v21
	v_add_f32_e32 v29, v29, v32
	v_add_f32_e32 v32, v6, v7
	v_fma_f32 v34, v80, v44, v23
	v_pk_mul_f32 v[0:1], v[38:39], v[44:45] op_sel_hi:[1,0]
	v_mul_f32_e32 v17, v81, v44
	v_add_f32_e32 v32, v32, v34
	v_pk_mul_f32 v[2:3], v[42:43], v[44:45] op_sel_hi:[1,0]
	v_mul_f32_e32 v19, v82, v44
	ds_write2_b32 v33, v29, v32 offset0:24 offset1:26
	ds_write2_b32 v28, v21, v23 offset0:152 offset1:154
	v_add_f32_e32 v29, v0, v1
	v_fma_f32 v32, v45, v44, v17
	v_add_f32_e32 v29, v29, v32
	v_add_f32_e32 v32, v2, v3
	v_fma_f32 v34, v37, v44, v19
	v_add_f32_e32 v32, v32, v34
	ds_write2_b32 v33, v29, v32 offset0:28 offset1:30
	ds_write2_b32 v28, v17, v19 offset0:156 offset1:158
	v_mad_u32_u24 v28, v150, s10, v235
	v_mul_f32_e32 v107, v63, v44
	v_add_u32_e32 v63, 0x4800, v28
	v_add_u32_e32 v66, 0x6800, v28
	v_mul_f32_e32 v84, v36, v44
	v_mul_f32_e32 v96, v41, v44
	v_mul_f32_e32 v18, v37, v44
	v_cvt_pk_bf16_f32 v33, v83, v40
	ds_read2_b64 v[36:39], v63 offset1:2
	ds_read2_b64 v[40:43], v66 offset0:32 offset1:34
	v_cvt_pk_bf16_f32 v32, v70, v71
	v_cvt_pk_bf16_f32 v34, v72, v73
	v_cvt_pk_bf16_f32 v35, v84, v46
	v_mul_f32_e32 v98, v50, v44
	v_mul_f32_e32 v99, v51, v44
	v_mul_f32_e32 v101, v55, v44
	v_mul_f32_e32 v102, v58, v44
	v_mul_f32_e32 v103, v61, v44
	v_mul_f32_e32 v104, v59, v44
	v_mul_f32_e32 v105, v53, v44
	v_mul_f32_e32 v109, v47, v44
	v_mul_f32_e32 v20, v78, v44
	v_mul_f32_e32 v22, v80, v44
	v_mul_f32_e32 v16, v45, v44
	s_waitcnt lgkmcnt(1)
	v_mfma_f32_32x32x16_bf16 v[80:95], v[36:39], v[32:35], 0
	s_waitcnt lgkmcnt(0)
	v_mfma_f32_32x32x16_bf16 v[32:47], v[40:43], v[32:35], 0
	v_cvt_pk_bf16_f32 v53, v98, v54
	ds_read2_b64 v[54:57], v63 offset0:4 offset1:6
	ds_read2_b64 v[58:61], v66 offset0:36 offset1:38
	v_cvt_pk_bf16_f32 v50, v74, v75
	v_cvt_pk_bf16_f32 v51, v96, v97
	v_cvt_pk_bf16_f32 v52, v76, v77
	s_nop 0
	s_nop 0
	s_waitcnt lgkmcnt(1)
	v_mfma_f32_32x32x16_bf16 v[80:95], v[54:57], v[50:53], v[80:95]
	s_waitcnt lgkmcnt(0)
	v_mfma_f32_32x32x16_bf16 v[32:47], v[58:61], v[50:53], v[32:47]
	v_cvt_pk_bf16_f32 v28, v30, v31
	v_cvt_pk_bf16_f32 v30, v48, v49
	ds_read2_b64 v[48:51], v63 offset0:8 offset1:10
	ds_read2_b64 v[52:55], v66 offset0:40 offset1:42
	v_cvt_pk_bf16_f32 v29, v99, v100
	v_cvt_pk_bf16_f32 v31, v101, v62
	s_nop 0
	s_nop 0
	s_waitcnt lgkmcnt(1)
	v_mfma_f32_32x32x16_bf16 v[80:95], v[48:51], v[28:31], v[80:95]
	s_waitcnt lgkmcnt(0)
	v_mfma_f32_32x32x16_bf16 v[32:47], v[52:55], v[28:31], v[32:47]
	ds_read2_b64 v[28:31], v63 offset0:12 offset1:14
	ds_read2_b64 v[48:51], v66 offset0:44 offset1:46
	v_cvt_pk_bf16_f32 v24, v24, v25
	v_cvt_pk_bf16_f32 v25, v102, v67
	v_cvt_pk_bf16_f32 v26, v26, v27
	v_cvt_pk_bf16_f32 v27, v103, v69
	s_nop 0
	s_nop 0
	s_waitcnt lgkmcnt(1)
	v_mfma_f32_32x32x16_bf16 v[80:95], v[28:31], v[24:27], v[80:95]
	s_waitcnt lgkmcnt(0)
	v_mfma_f32_32x32x16_bf16 v[32:47], v[48:51], v[24:27], v[32:47]
	ds_read2_b64 v[24:27], v63 offset0:16 offset1:18
	ds_read2_b64 v[28:31], v66 offset0:48 offset1:50
	v_cvt_pk_bf16_f32 v12, v12, v13
	v_cvt_pk_bf16_f32 v13, v104, v68
	v_cvt_pk_bf16_f32 v14, v14, v15
	v_cvt_pk_bf16_f32 v15, v105, v106
	s_nop 0
	s_nop 0
	s_waitcnt lgkmcnt(1)
	v_mfma_f32_32x32x16_bf16 v[80:95], v[24:27], v[12:15], v[80:95]
	s_waitcnt lgkmcnt(0)
	v_mfma_f32_32x32x16_bf16 v[32:47], v[28:31], v[12:15], v[32:47]
	ds_read2_b64 v[12:15], v63 offset0:20 offset1:22
	ds_read2_b64 v[24:27], v66 offset0:52 offset1:54
	v_cvt_pk_bf16_f32 v8, v8, v9
	v_cvt_pk_bf16_f32 v9, v107, v108
	v_cvt_pk_bf16_f32 v10, v10, v11
	v_cvt_pk_bf16_f32 v11, v109, v110
	s_nop 0
	s_nop 0
	s_waitcnt lgkmcnt(1)
	v_mfma_f32_32x32x16_bf16 v[80:95], v[12:15], v[8:11], v[80:95]
	s_waitcnt lgkmcnt(0)
	v_mfma_f32_32x32x16_bf16 v[32:47], v[24:27], v[8:11], v[32:47]
	ds_read2_b64 v[8:11], v63 offset0:24 offset1:26
	ds_read2_b64 v[12:15], v66 offset0:56 offset1:58
	v_cvt_pk_bf16_f32 v4, v4, v5
	v_cvt_pk_bf16_f32 v5, v20, v21
	v_cvt_pk_bf16_f32 v6, v6, v7
	v_cvt_pk_bf16_f32 v7, v22, v23
	s_nop 0
	s_nop 0
	s_waitcnt lgkmcnt(1)
	v_mfma_f32_32x32x16_bf16 v[80:95], v[8:11], v[4:7], v[80:95]
	s_waitcnt lgkmcnt(0)
	v_mfma_f32_32x32x16_bf16 v[32:47], v[12:15], v[4:7], v[32:47]
	ds_read2_b64 v[4:7], v63 offset0:28 offset1:30
	ds_read2_b64 v[8:11], v66 offset0:60 offset1:62
	v_cvt_pk_bf16_f32 v0, v0, v1
	v_cvt_pk_bf16_f32 v1, v16, v17
	v_cvt_pk_bf16_f32 v2, v2, v3
	v_cvt_pk_bf16_f32 v3, v18, v19
	s_nop 0
	s_nop 0
	s_waitcnt lgkmcnt(1)
	v_mfma_f32_32x32x16_bf16 v[80:95], v[4:7], v[0:3], v[80:95]
	s_waitcnt lgkmcnt(0)
	v_mfma_f32_32x32x16_bf16 v[32:47], v[8:11], v[0:3], v[32:47]
	v_lshlrev_b32_e32 v0, 2, v198
	s_movk_i32 s0, 0x84
	v_and_b32_e32 v52, 28, v0
	v_mul_lo_u32 v1, v65, s0
	v_lshl_add_u32 v2, v52, 2, v1
	s_barrier
	ds_read_b32 v0, v2 offset:36864
	v_cmp_eq_u32_e32 vcc, 0, v52
	v_cmp_ne_u32_e64 s[0:1], 0, v52
	s_waitcnt lgkmcnt(0)
	v_add_f32_e32 v0, 0, v0
	s_and_saveexec_b64 s[8:9], s[0:1]
	s_cbranch_execz .LBB0_432
	ds_read_b32 v3, v2 offset:53756
	s_waitcnt lgkmcnt(0)
	v_add_f32_e32 v0, v0, v3

.LBB0_439:
	s_ff1_i32_b64 s0, s[72:73]
	v_readlane_b32 s1, v0, s0
	s_or_b32 s8, s8, s1
	s_lshl_b64 s[0:1], 1, s0
	s_andn2_b64 s[72:73], s[72:73], s[0:1]
	s_cmp_lg_u64 s[72:73], 0
	s_cbranch_scc1 .LBB0_439
	v_mbcnt_lo_u32_b32 v0, exec_lo, 0
	v_mbcnt_hi_u32_b32 v0, exec_hi, v0
	v_cmp_eq_u32_e32 vcc, 0, v0
	s_and_saveexec_b64 s[0:1], vcc
	s_xor_b64 s[0:1], exec, s[0:1]
	v_mov_b32_e32 v0, s8
	v_mov_b32_e32 v1, 0x11480
	ds_or_b32 v1, v0
	s_or_b64 exec, exec, s[0:1]
	v_readlane_b32 s0, v254, 52
	s_ashr_i32 s10, s0, 1
	v_readlane_b32 s0, v254, 53
	v_mov_b32_e32 v0, 0x11480
	v_readlane_b32 s1, v254, 54
	s_mov_b32 s8, s0
	s_waitcnt lgkmcnt(0)
	s_barrier
	ds_read_b32 v0, v0
	s_mul_i32 s1, s8, 0xe80000
	v_readlane_b32 s8, v254, 3
	s_mul_hi_i32 s0, s0, 0xe80000
	v_readlane_b32 s9, v254, 4
	s_add_u32 s13, s8, s1
	s_addc_u32 s14, s9, s0
	s_lshl_b32 s0, 2, s10
	s_add_i32 s0, s0, -1
	s_cmp_lt_i32 s10, 31
	s_cselect_b32 s0, s0, -1
	s_waitcnt lgkmcnt(0)
	v_readfirstlane_b32 s1, v0
	s_and_b32 s12, s1, s0
	v_ashrrev_i32_e32 v0, 31, v151
	v_readfirstlane_b32 s11, v206
	s_cmp_eq_u32 s12, 0
	v_lshlrev_b32_e32 v238, 2, v150
	v_lshlrev_b32_e32 v239, 1, v150
	v_lshrrev_b32_e32 v152, 29, v0
	s_cbranch_scc1 .LBB0_457
	v_or_b32_e32 v0, 0x11400, v238
	s_add_u32 s0, s13, 0x1000
	ds_read_b32 v153, v0
	s_addc_u32 s1, s14, 0
	v_ashrrev_i32_e32 v0, 31, v198
	s_add_u32 s8, s13, 0x1080
	s_flbit_i32_b32 s15, s12
	v_lshrrev_b32_e32 v0, 29, v0
	s_addc_u32 s9, s14, 0
	s_xor_b32 s19, s15, 31
	v_add_u32_e32 v0, v198, v0
	s_lshl_b32 s15, s19, 6
	v_ashrrev_i32_e32 v154, 3, v0
	v_and_b32_e32 v0, -8, v0
	v_sub_u32_e32 v8, v198, v0
	v_add_u32_e32 v0, s15, v154
	v_mov_b64_e32 v[2:3], s[0:1]
	s_movk_i32 s22, 0x1d00
	v_mad_i64_i32 v[4:5], s[16:17], v0, s22, v[2:3]
	v_lshlrev_b32_e32 v0, 3, v8
	v_ashrrev_i32_e32 v1, 31, v0
	v_lshl_add_u64 v[4:5], v[0:1], 1, v[4:5]
	global_load_dwordx4 v[128:131], v[4:5], off
	v_add_u32_e32 v4, v151, v152
	v_ashrrev_i32_e32 v155, 3, v4
	v_and_b32_e32 v4, -8, v4
	v_sub_u32_e32 v9, v151, v4
	v_add_u32_e32 v4, s15, v155
	v_mad_i64_i32 v[4:5], s[16:17], v4, s22, v[2:3]
	v_lshlrev_b32_e32 v2, 3, v9
	v_ashrrev_i32_e32 v3, 31, v2
	v_lshl_add_u64 v[4:5], v[2:3], 1, v[4:5]
	global_load_dwordx4 v[132:135], v[4:5], off
	v_or_b32_e32 v4, s15, v239
	v_mul_u32_u24_e32 v192, 0x1d00, v4
	v_ashrrev_i32_e32 v4, 2, v198
	v_and_b32_e32 v4, -8, v4
	v_lshl_add_u64 v[6:7], s[8:9], 0, v[192:193]
	v_ashrrev_i32_e32 v5, 31, v4
	v_lshl_add_u64 v[6:7], v[4:5], 1, v[6:7]
	s_movk_i32 s15, 0x1000
	global_load_dwordx4 v[136:139], v[6:7], off
	v_add_co_u32_e32 v6, vcc, s15, v6
	s_movk_i32 s15, 0x90
	s_nop 0
	v_addc_co_u32_e32 v7, vcc, 0, v7, vcc
	global_load_dwordx4 v[140:143], v[6:7], off offset:3328
	v_mul_lo_u32 v157, v154, s15
	v_lshlrev_b32_e32 v158, 4, v8
	v_add_u32_e32 v6, v157, v158
	v_mul_lo_u32 v159, v155, s15
	v_lshlrev_b32_e32 v176, 4, v9
	s_waitcnt lgkmcnt(0)
	s_barrier
	v_mul_lo_u32 v156, v4, 34
	s_mov_b32 s15, 0xffff0000
	s_waitcnt vmcnt(3)
	ds_write_b128 v6, v[128:131]
	v_add_u32_e32 v6, v159, v176
	s_waitcnt vmcnt(2)
	ds_write_b128 v6, v[132:135]
	v_lshl_add_u32 v6, v156, 2, v238
	v_add_u32_e32 v6, 0x3400, v6
	s_waitcnt vmcnt(1)
	v_and_b32_e32 v7, 0xffff, v136
	v_lshrrev_b32_e32 v8, 16, v136
	s_waitcnt vmcnt(0)
	v_lshl_or_b32 v7, v140, 16, v7
	v_and_or_b32 v8, v140, s15, v8
	ds_write2_b32 v6, v7, v8 offset1:34
	v_and_b32_e32 v7, 0xffff, v137
	v_lshrrev_b32_e32 v8, 16, v137
	v_lshl_or_b32 v7, v141, 16, v7
	v_and_or_b32 v8, v141, s15, v8
	ds_write2_b32 v6, v7, v8 offset0:68 offset1:102
	v_and_b32_e32 v7, 0xffff, v138
	v_lshrrev_b32_e32 v8, 16, v138
	v_lshl_or_b32 v7, v142, 16, v7
	v_and_or_b32 v8, v142, s15, v8
	ds_write2_b32 v6, v7, v8 offset0:136 offset1:170
	v_lshrrev_b32_e32 v8, 16, v139
	v_and_or_b32 v8, v143, s15, v8
	s_lshl_b32 s15, -1, s19
	s_andn2_b32 s15, s12, s15
	s_flbit_i32_b32 s16, s15
	s_xor_b32 s16, s16, 31
	s_cmp_lg_u32 s15, 0
	v_and_b32_e32 v7, 0xffff, v139
	s_cselect_b32 s18, s16, -1
	v_lshl_or_b32 v7, v143, 16, v7
	s_cmp_lt_i32 s18, 0
	ds_write2_b32 v6, v7, v8 offset0:204 offset1:238
	s_cbranch_scc1 .LBB0_445
	s_lshl_b32 s15, s18, 6
	v_add_u32_e32 v8, s15, v154
	v_mov_b64_e32 v[6:7], s[0:1]
	v_add_u32_e32 v10, s15, v155
	v_mad_i64_i32 v[8:9], s[16:17], v8, s22, v[6:7]
	v_mad_i64_i32 v[6:7], s[16:17], v10, s22, v[6:7]
	v_lshl_add_u64 v[8:9], v[0:1], 1, v[8:9]
	v_lshl_add_u64 v[6:7], v[2:3], 1, v[6:7]
	global_load_dwordx4 v[128:131], v[8:9], off
	global_load_dwordx4 v[132:135], v[6:7], off
	v_or_b32_e32 v12, s15, v239
	v_mov_b64_e32 v[6:7], s[8:9]
	v_mad_u64_u32 v[8:9], s[16:17], v12, s22, v[6:7]
	v_lshlrev_b64 v[10:11], 1, v[4:5]
	v_or_b32_e32 v12, 1, v12
	v_lshl_add_u64 v[8:9], v[8:9], 0, v[10:11]
	v_mad_u64_u32 v[6:7], s[16:17], v12, s22, v[6:7]
	v_lshl_add_u64 v[6:7], v[6:7], 0, v[10:11]
	global_load_dwordx4 v[136:139], v[8:9], off
	global_load_dwordx4 v[140:143], v[6:7], off

.LBB0_448:
	s_mul_i32 s18, s16, 0x9000
	v_lshlrev_b32_e32 v0, 1, v235
	v_add3_u32 v12, s18, v208, v0
	ds_read_b128 v[0:3], v12 offset:4608
	ds_read_b128 v[4:7], v12
	ds_read_b128 v[8:11], v12 offset:32
	s_or_b32 s0, s22, 63
	s_waitcnt lgkmcnt(2)
	v_mfma_f32_32x32x16_bf16 v[64:79], v[0:3], v[160:163], 0
	ds_read_b128 v[0:3], v12 offset:4640
	s_cmp_gt_i32 s0, s11
	s_mov_b64 s[8:9], -1
	s_waitcnt lgkmcnt(2)
	v_mfma_f32_32x32x16_bf16 v[112:127], v[4:7], v[160:163], 0
	s_waitcnt lgkmcnt(1)
	v_mfma_f32_32x32x16_bf16 v[112:127], v[8:11], v[164:167], v[112:127]
	s_waitcnt lgkmcnt(0)
	v_mfma_f32_32x32x16_bf16 v[64:79], v[0:3], v[164:167], v[64:79]
	ds_read_b128 v[0:3], v12 offset:64
	ds_read_b128 v[4:7], v12 offset:4672
	s_waitcnt lgkmcnt(1)
	v_mfma_f32_32x32x16_bf16 v[112:127], v[0:3], v[168:171], v[112:127]
	s_waitcnt lgkmcnt(0)
	v_mfma_f32_32x32x16_bf16 v[64:79], v[4:7], v[168:171], v[64:79]
	ds_read_b128 v[0:3], v12 offset:96
	ds_read_b128 v[4:7], v12 offset:4704
	s_waitcnt lgkmcnt(1)
	v_mfma_f32_32x32x16_bf16 v[112:127], v[0:3], v[172:175], v[112:127]
	v_lshrrev_b32_e32 v0, s19, v153
	v_and_b32_e32 v0, 1, v0
	v_cmp_eq_u32_e64 s[0:1], 1, v0
	s_waitcnt lgkmcnt(0)
	v_mfma_f32_32x32x16_bf16 v[64:79], v[4:7], v[172:175], v[64:79]
	s_cbranch_scc1 .LBB0_450
	s_mov_b32 s8, 0xff61b1e6
	s_nop 5
	v_max3_f32 v0, v112, s8, v113
	v_max3_f32 v0, v0, v114, v115
	v_max3_f32 v0, v0, v116, v117
	v_max3_f32 v0, v0, v118, v119
	v_max3_f32 v0, v0, v120, v121
	v_max3_f32 v0, v0, v122, v123
	v_max3_f32 v0, v0, v124, v125
	v_max3_f32 v0, v0, v126, v127
	v_max3_f32 v0, v0, v64, v65
	v_max3_f32 v0, v0, v66, v67
	v_max3_f32 v0, v0, v68, v69
	v_max3_f32 v0, v0, v70, v71
	v_max3_f32 v0, v0, v72, v73
	v_max3_f32 v0, v0, v74, v75
	v_max3_f32 v0, v0, v76, v77
	v_max3_f32 v0, v0, v78, v79
	ds_bpermute_b32 v1, v236, v0
	v_max_f32_e32 v2, v178, v178
	s_mov_b64 s[8:9], 0
	s_waitcnt lgkmcnt(0)
	v_max_f32_e32 v1, v1, v1
	v_max_f32_e32 v0, v0, v1
	v_mul_f32_e32 v0, 0x3e38aa3b, v0
	v_max_f32_e32 v0, v2, v0
	v_cndmask_b32_e64 v179, v178, v0, s[0:1]
	v_cndmask_b32_e64 v31, v226, -v179, s[0:1]
	v_fmamk_f32 v0, v112, 0x3e38aa3b, v31
	v_fmamk_f32 v1, v113, 0x3e38aa3b, v31
	v_exp_f32_e32 v0, v0
	v_fmamk_f32 v2, v114, 0x3e38aa3b, v31
	v_exp_f32_e32 v1, v1
	v_fmamk_f32 v3, v115, 0x3e38aa3b, v31
	v_exp_f32_e32 v2, v2
	v_exp_f32_e32 v3, v3
	v_add_f32_e32 v4, 0, v0
	v_add_f32_e32 v4, v1, v4
	v_add_f32_e32 v4, v2, v4
	v_add_f32_e32 v8, v3, v4
	v_fmamk_f32 v4, v116, 0x3e38aa3b, v31
	v_exp_f32_e32 v4, v4
	v_fmamk_f32 v5, v117, 0x3e38aa3b, v31
	v_exp_f32_e32 v5, v5
	v_fmamk_f32 v6, v118, 0x3e38aa3b, v31
	v_exp_f32_e32 v6, v6
	v_fmamk_f32 v7, v119, 0x3e38aa3b, v31
	v_exp_f32_e32 v7, v7
	v_add_f32_e32 v8, v4, v8
	v_add_f32_e32 v8, v5, v8
	v_add_f32_e32 v8, v6, v8
	v_add_f32_e32 v12, v7, v8
	v_fmamk_f32 v8, v120, 0x3e38aa3b, v31
	v_exp_f32_e32 v8, v8
	v_fmamk_f32 v9, v121, 0x3e38aa3b, v31
	v_exp_f32_e32 v9, v9
	v_fmamk_f32 v10, v122, 0x3e38aa3b, v31
	v_exp_f32_e32 v10, v10
	v_fmamk_f32 v11, v123, 0x3e38aa3b, v31
	v_exp_f32_e32 v11, v11
	v_add_f32_e32 v12, v8, v12
	v_add_f32_e32 v12, v9, v12
	v_add_f32_e32 v12, v10, v12
	v_add_f32_e32 v16, v11, v12
	v_fmamk_f32 v12, v124, 0x3e38aa3b, v31
	v_exp_f32_e32 v12, v12
	v_fmamk_f32 v13, v125, 0x3e38aa3b, v31
	v_exp_f32_e32 v13, v13
	v_fmamk_f32 v14, v126, 0x3e38aa3b, v31
	v_exp_f32_e32 v14, v14
	v_fmamk_f32 v15, v127, 0x3e38aa3b, v31
	v_exp_f32_e32 v15, v15
	v_add_f32_e32 v16, v12, v16
	v_add_f32_e32 v16, v13, v16
	v_add_f32_e32 v16, v14, v16
	v_add_f32_e32 v20, v15, v16
	v_fmamk_f32 v16, v64, 0x3e38aa3b, v31
	v_exp_f32_e32 v16, v16
	v_fmamk_f32 v17, v65, 0x3e38aa3b, v31
	v_exp_f32_e32 v17, v17
	v_fmamk_f32 v18, v66, 0x3e38aa3b, v31
	v_exp_f32_e32 v18, v18
	v_fmamk_f32 v19, v67, 0x3e38aa3b, v31
	v_exp_f32_e32 v19, v19
	v_add_f32_e32 v20, v16, v20
	v_add_f32_e32 v20, v17, v20
	v_add_f32_e32 v20, v18, v20
	v_add_f32_e32 v24, v19, v20
	v_fmamk_f32 v20, v68, 0x3e38aa3b, v31
	v_exp_f32_e32 v20, v20
	v_fmamk_f32 v21, v69, 0x3e38aa3b, v31
	v_exp_f32_e32 v21, v21
	v_fmamk_f32 v22, v70, 0x3e38aa3b, v31
	v_exp_f32_e32 v22, v22
	v_fmamk_f32 v23, v71, 0x3e38aa3b, v31
	v_exp_f32_e32 v23, v23
	v_add_f32_e32 v24, v20, v24
	v_add_f32_e32 v24, v21, v24
	v_add_f32_e32 v24, v22, v24
	v_add_f32_e32 v28, v23, v24
	v_fmamk_f32 v24, v72, 0x3e38aa3b, v31
	v_exp_f32_e32 v24, v24
	v_fmamk_f32 v25, v73, 0x3e38aa3b, v31
	v_exp_f32_e32 v25, v25
	v_fmamk_f32 v26, v74, 0x3e38aa3b, v31
	v_exp_f32_e32 v26, v26
	v_fmamk_f32 v27, v75, 0x3e38aa3b, v31
	v_exp_f32_e32 v27, v27
	v_add_f32_e32 v28, v24, v28
	v_add_f32_e32 v28, v25, v28
	v_add_f32_e32 v28, v26, v28
	v_add_f32_e32 v180, v27, v28
	v_fmamk_f32 v28, v76, 0x3e38aa3b, v31
	v_exp_f32_e32 v28, v28
	v_fmamk_f32 v29, v77, 0x3e38aa3b, v31
	v_exp_f32_e32 v29, v29
	v_fmamk_f32 v30, v78, 0x3e38aa3b, v31
	v_exp_f32_e32 v30, v30
	v_fmac_f32_e32 v31, 0x3e38aa3b, v79
	v_exp_f32_e32 v31, v31
	v_add_f32_e32 v180, v28, v180
	v_add_f32_e32 v180, v29, v180
	v_add_f32_e32 v180, v30, v180
	v_add_f32_e32 v180, v31, v180

.LBB0_452:
	s_nop 8
	v_sub_f32_e32 v64, v178, v179
	v_exp_f32_e32 v68, v64
	v_lshlrev_b32_e32 v64, 1, v237
	v_cvt_pk_bf16_f32 v0, v0, v1
	v_cvt_pk_bf16_f32 v1, v2, v3
	v_pk_mul_f32 v[110:111], v[110:111], v[68:69] op_sel_hi:[1,0]
	v_pk_mul_f32 v[108:109], v[108:109], v[68:69] op_sel_hi:[1,0]
	v_pk_mul_f32 v[106:107], v[106:107], v[68:69] op_sel_hi:[1,0]
	v_pk_mul_f32 v[104:105], v[104:105], v[68:69] op_sel_hi:[1,0]
	v_pk_mul_f32 v[102:103], v[102:103], v[68:69] op_sel_hi:[1,0]
	v_pk_mul_f32 v[100:101], v[100:101], v[68:69] op_sel_hi:[1,0]
	v_pk_mul_f32 v[98:99], v[98:99], v[68:69] op_sel_hi:[1,0]
	v_add3_u32 v69, s18, v177, v64
	v_add_u32_e32 v70, 0x3000, v69
	v_pk_mul_f32 v[96:97], v[96:97], v[68:69] op_sel_hi:[1,0]
	v_pk_mul_f32 v[62:63], v[62:63], v[68:69] op_sel_hi:[1,0]
	v_add_u32_e32 v69, 0x4000, v69
	ds_read2_b64 v[64:67], v70 offset0:128 offset1:130
	v_cvt_pk_bf16_f32 v2, v4, v5
	v_cvt_pk_bf16_f32 v3, v6, v7
	ds_read2_b64 v[4:7], v69 offset0:160 offset1:162
	v_pk_mul_f32 v[60:61], v[60:61], v[68:69] op_sel_hi:[1,0]
	v_pk_mul_f32 v[58:59], v[58:59], v[68:69] op_sel_hi:[1,0]
	v_pk_mul_f32 v[56:57], v[56:57], v[68:69] op_sel_hi:[1,0]
	v_pk_mul_f32 v[54:55], v[54:55], v[68:69] op_sel_hi:[1,0]
	v_pk_mul_f32 v[52:53], v[52:53], v[68:69] op_sel_hi:[1,0]
	v_pk_mul_f32 v[50:51], v[50:51], v[68:69] op_sel_hi:[1,0]
	v_pk_mul_f32 v[48:49], v[48:49], v[68:69] op_sel_hi:[1,0]
	s_waitcnt lgkmcnt(1)
	v_mfma_f32_32x32x16_bf16 v[96:111], v[64:67], v[0:3], v[96:111]
	v_fmac_f32_e32 v180, v207, v68
	v_mov_b32_e32 v207, v180
	v_mov_b32_e32 v178, v179
	s_waitcnt lgkmcnt(0)
	v_mfma_f32_32x32x16_bf16 v[48:63], v[4:7], v[0:3], v[48:63]
	ds_read2_b64 v[0:3], v70 offset0:132 offset1:134
	v_cvt_pk_bf16_f32 v4, v8, v9
	v_cvt_pk_bf16_f32 v5, v10, v11
	v_cvt_pk_bf16_f32 v6, v12, v13
	v_cvt_pk_bf16_f32 v7, v14, v15
	s_nop 0
	s_nop 0
	s_waitcnt lgkmcnt(0)
	v_mfma_f32_32x32x16_bf16 v[96:111], v[0:3], v[4:7], v[96:111]
	ds_read2_b64 v[0:3], v69 offset0:164 offset1:166
	s_waitcnt lgkmcnt(0)
	v_mfma_f32_32x32x16_bf16 v[48:63], v[0:3], v[4:7], v[48:63]
	ds_read2_b64 v[0:3], v70 offset0:136 offset1:138
	v_cvt_pk_bf16_f32 v4, v16, v17
	v_cvt_pk_bf16_f32 v5, v18, v19
	v_cvt_pk_bf16_f32 v6, v20, v21
	v_cvt_pk_bf16_f32 v7, v22, v23
	s_nop 0
	s_nop 0
	s_waitcnt lgkmcnt(0)
	v_mfma_f32_32x32x16_bf16 v[96:111], v[0:3], v[4:7], v[96:111]
	ds_read2_b64 v[0:3], v69 offset0:168 offset1:170
	s_waitcnt lgkmcnt(0)
	v_mfma_f32_32x32x16_bf16 v[48:63], v[0:3], v[4:7], v[48:63]
	ds_read2_b64 v[0:3], v70 offset0:140 offset1:142
	v_cvt_pk_bf16_f32 v4, v24, v25
	v_cvt_pk_bf16_f32 v5, v26, v27
	v_cvt_pk_bf16_f32 v6, v28, v29
	v_cvt_pk_bf16_f32 v7, v30, v31
	s_nop 0
	s_nop 0
	s_waitcnt lgkmcnt(0)
	v_mfma_f32_32x32x16_bf16 v[96:111], v[0:3], v[4:7], v[96:111]
	ds_read2_b64 v[0:3], v69 offset0:172 offset1:174
	s_waitcnt lgkmcnt(0)
	v_mfma_f32_32x32x16_bf16 v[48:63], v[0:3], v[4:7], v[48:63]
.LBB0_453:
	s_cmp_lt_i32 s17, 0
	s_cbranch_scc1 .LBB0_446
	s_xor_b32 s16, s16, 1
	s_mul_i32 s0, s16, 0x9000
	v_add3_u32 v1, s0, v157, v158
	v_lshlrev_b32_e32 v0, 2, v156
	s_waitcnt vmcnt(0)
	ds_write_b128 v1, v[128:131]
	v_add3_u32 v1, s0, v159, v176
	ds_write_b128 v1, v[132:135]
	v_add3_u32 v0, s0, v0, v238
	v_lshlrev_b32_e32 v1, 16, v140
	s_mov_b32 s1, 0xffff
	v_lshrrev_b32_e32 v2, 16, v136
	s_mov_b32 s0, 0xffff0000
	v_and_or_b32 v1, v136, s1, v1
	v_and_or_b32 v2, v140, s0, v2
	v_add_u32_e32 v0, 0x3400, v0
	ds_write2_b32 v0, v1, v2 offset1:34
	v_lshlrev_b32_e32 v1, 16, v141
	v_lshrrev_b32_e32 v2, 16, v137
	v_and_or_b32 v1, v137, s1, v1
	v_and_or_b32 v2, v141, s0, v2
	ds_write2_b32 v0, v1, v2 offset0:68 offset1:102
	v_lshlrev_b32_e32 v1, 16, v142
	v_lshrrev_b32_e32 v2, 16, v138
	v_and_or_b32 v1, v138, s1, v1
	v_and_or_b32 v2, v142, s0, v2
	ds_write2_b32 v0, v1, v2 offset0:136 offset1:170
	v_lshrrev_b32_e32 v2, 16, v139
	v_and_or_b32 v2, v143, s0, v2
	s_lshl_b32 s0, -1, s17
	v_lshlrev_b32_e32 v1, 16, v143
	s_andn2_b32 s0, s12, s0
	v_and_or_b32 v1, v139, s1, v1
	s_flbit_i32_b32 s1, s0
	s_xor_b32 s1, s1, 31
	s_cmp_lg_u32 s0, 0
	s_cselect_b32 s18, s1, -1
	s_cmp_lt_i32 s18, 0
	ds_write2_b32 v0, v1, v2 offset0:204 offset1:238
	s_cbranch_scc1 .LBB0_456
	s_lshl_b32 s8, s18, 6
	v_add_u32_e32 v0, s8, v154
	s_movk_i32 s9, 0x1d00
	v_add_u32_e32 v2, s8, v155
	v_mad_i64_i32 v[0:1], s[0:1], v0, s9, v[146:147]
	v_mad_i64_i32 v[2:3], s[0:1], v2, s9, v[148:149]
	global_load_dwordx4 v[128:131], v[0:1], off
	global_load_dwordx4 v[132:135], v[2:3], off
	v_or_b32_e32 v2, s8, v239
	v_mad_u64_u32 v[0:1], s[0:1], v2, s9, v[144:145]
	v_or_b32_e32 v2, 1, v2
	v_mad_u64_u32 v[2:3], s[0:1], v2, s9, v[144:145]
	global_load_dwordx4 v[136:139], v[0:1], off
	global_load_dwordx4 v[140:143], v[2:3], off

.LBB0_458:
	ds_bpermute_b32 v195, v236, v207
	v_readlane_b32 s0, v254, 55
	s_addk_i32 s0, 0xfe01
	s_ashr_i32 s0, s0, 6
	s_max_i32 s11, s0, 0
	v_mov_b32_e32 v127, 0
	v_readfirstlane_b32 s12, v206
	s_cmp_lt_i32 s10, s11
	v_mov_b32_e32 v126, v127
	v_mov_b32_e32 v125, v127
	v_mov_b32_e32 v124, v127
	v_mov_b32_e32 v123, v127
	v_mov_b32_e32 v122, v127
	v_mov_b32_e32 v121, v127
	v_mov_b32_e32 v120, v127
	v_mov_b32_e32 v119, v127
	v_mov_b32_e32 v118, v127
	v_mov_b32_e32 v117, v127
	v_mov_b32_e32 v116, v127
	v_mov_b32_e32 v115, v127
	v_mov_b32_e32 v114, v127
	v_mov_b32_e32 v113, v127
	v_mov_b32_e32 v112, v127
	v_mov_b32_e32 v79, v127
	v_mov_b32_e32 v78, v127
	v_mov_b32_e32 v77, v127
	v_mov_b32_e32 v76, v127
	v_mov_b32_e32 v75, v127
	v_mov_b32_e32 v74, v127
	v_mov_b32_e32 v73, v127
	v_mov_b32_e32 v72, v127
	v_mov_b32_e32 v71, v127
	v_mov_b32_e32 v70, v127
	v_mov_b32_e32 v69, v127
	v_mov_b32_e32 v68, v127
	v_mov_b32_e32 v67, v127
	v_mov_b32_e32 v66, v127
	v_mov_b32_e32 v65, v127
	v_mov_b32_e32 v64, v127
	v_mov_b32_e32 v209, v127
	s_cbranch_scc1 .LBB0_475
	s_add_u32 s0, s13, 0x1100
	v_ashrrev_i32_e32 v0, 31, v198
	s_addc_u32 s1, s14, 0
	v_lshrrev_b32_e32 v0, 29, v0
	s_add_u32 s8, s13, 0x1180
	v_add_u32_e32 v0, v198, v0
	s_addc_u32 s9, s14, 0
	s_lshl_b32 s13, s10, 6
	v_ashrrev_i32_e32 v192, 3, v0
	v_and_b32_e32 v0, -8, v0
	v_sub_u32_e32 v12, v198, v0
	v_add_u32_e32 v0, s13, v192
	v_mov_b64_e32 v[2:3], s[0:1]
	s_movk_i32 s18, 0x1d00
	v_mad_i64_i32 v[4:5], s[14:15], v0, s18, v[2:3]
	v_lshlrev_b32_e32 v0, 3, v12
	v_ashrrev_i32_e32 v1, 31, v0
	v_lshl_add_u64 v[4:5], v[0:1], 1, v[4:5]
	global_load_dwordx4 v[176:179], v[4:5], off
	v_add_u32_e32 v4, v151, v152
	v_ashrrev_i32_e32 v240, 3, v4
	v_and_b32_e32 v4, -8, v4
	v_sub_u32_e32 v13, v151, v4
	v_add_u32_e32 v4, s13, v240
	v_mad_i64_i32 v[4:5], s[14:15], v4, s18, v[2:3]
	v_lshlrev_b32_e32 v2, 3, v13
	v_ashrrev_i32_e32 v3, 31, v2
	v_lshl_add_u64 v[4:5], v[2:3], 1, v[4:5]
	global_load_dwordx4 v[180:183], v[4:5], off
	v_ashrrev_i32_e32 v4, 2, v198
	v_and_b32_e32 v4, -8, v4
	v_or_b32_e32 v14, s13, v239
	v_mov_b64_e32 v[8:9], s[8:9]
	v_ashrrev_i32_e32 v5, 31, v4
	v_mad_u64_u32 v[10:11], s[14:15], v14, s18, v[8:9]
	v_lshlrev_b64 v[6:7], 1, v[4:5]
	v_lshl_add_u64 v[10:11], v[10:11], 0, v[6:7]
	global_load_dwordx4 v[184:187], v[10:11], off
	v_or_b32_e32 v10, 1, v14
	v_mad_u64_u32 v[8:9], s[14:15], v10, s18, v[8:9]
	v_lshl_add_u64 v[8:9], v[8:9], 0, v[6:7]
	global_load_dwordx4 v[188:191], v[8:9], off
	s_movk_i32 s13, 0x90
	v_mul_lo_u32 v242, v192, s13
	v_lshlrev_b32_e32 v243, 4, v12
	v_add_u32_e32 v8, v242, v243
	v_mul_lo_u32 v244, v240, s13
	v_lshlrev_b32_e32 v245, 4, v13
	s_waitcnt lgkmcnt(0)
	s_barrier
	v_mul_lo_u32 v241, v4, 34
	s_mov_b32 s13, 0xffff0000
	s_waitcnt vmcnt(3)
	ds_write_b128 v8, v[176:179]
	v_add_u32_e32 v8, v244, v245
	s_waitcnt vmcnt(2)
	ds_write_b128 v8, v[180:183]
	v_lshl_add_u32 v8, v241, 2, v238
	v_add_u32_e32 v8, 0x3400, v8
	s_waitcnt vmcnt(1)
	v_and_b32_e32 v9, 0xffff, v184
	v_lshrrev_b32_e32 v10, 16, v184
	s_waitcnt vmcnt(0)
	v_lshl_or_b32 v9, v188, 16, v9
	v_and_or_b32 v10, v188, s13, v10
	ds_write2_b32 v8, v9, v10 offset1:34
	v_and_b32_e32 v9, 0xffff, v185
	v_lshrrev_b32_e32 v10, 16, v185
	v_lshl_or_b32 v9, v189, 16, v9
	v_and_or_b32 v10, v189, s13, v10
	ds_write2_b32 v8, v9, v10 offset0:68 offset1:102
	v_and_b32_e32 v9, 0xffff, v186
	v_lshrrev_b32_e32 v10, 16, v186
	v_lshl_or_b32 v9, v190, 16, v9
	v_and_or_b32 v10, v190, s13, v10
	ds_write2_b32 v8, v9, v10 offset0:136 offset1:170
	v_lshrrev_b32_e32 v10, 16, v187
	v_and_or_b32 v10, v191, s13, v10
	s_add_i32 s13, s10, -1
	s_cmp_gt_u32 s10, s11
	v_and_b32_e32 v9, 0xffff, v187
	s_cselect_b32 s14, s13, -1
	v_lshl_or_b32 v9, v191, 16, v9
	s_cmp_lt_i32 s14, 0
	ds_write2_b32 v8, v9, v10 offset0:204 offset1:238
	s_cbranch_scc1 .LBB0_461
	s_lshl_b32 s13, s14, 6
	v_add_u32_e32 v10, s13, v192
	v_mov_b64_e32 v[8:9], s[0:1]
	v_add_u32_e32 v12, s13, v240
	v_mad_i64_i32 v[10:11], s[16:17], v10, s18, v[8:9]
	v_mad_i64_i32 v[8:9], s[16:17], v12, s18, v[8:9]
	v_lshl_add_u64 v[10:11], v[0:1], 1, v[10:11]
	v_lshl_add_u64 v[8:9], v[2:3], 1, v[8:9]
	global_load_dwordx4 v[176:179], v[10:11], off
	global_load_dwordx4 v[180:183], v[8:9], off
	v_or_b32_e32 v12, s13, v239
	v_mov_b64_e32 v[8:9], s[8:9]
	v_mad_u64_u32 v[10:11], s[16:17], v12, s18, v[8:9]
	v_or_b32_e32 v12, 1, v12
	v_lshl_add_u64 v[10:11], v[10:11], 0, v[6:7]
	v_mad_u64_u32 v[8:9], s[16:17], v12, s18, v[8:9]
	v_lshl_add_u64 v[6:7], v[8:9], 0, v[6:7]
	global_load_dwordx4 v[184:187], v[10:11], off
	global_load_dwordx4 v[188:191], v[6:7], off

.LBB0_465:
	s_cmp_eq_u32 s15, 0
	s_cbranch_scc1 .LBB0_471
	s_mul_i32 s9, s8, 0x9000
	v_lshlrev_b32_e32 v0, 1, v235
	v_add3_u32 v12, s9, v208, v0
	ds_read_b128 v[0:3], v12 offset:4608
	ds_read_b128 v[4:7], v12
	ds_read_b128 v[8:11], v12 offset:32
	s_mov_b64 s[0:1], -1
	s_waitcnt lgkmcnt(2)
	v_mfma_f32_32x32x16_bf16 v[128:143], v[0:3], v[160:163], 0
	ds_read_b128 v[0:3], v12 offset:4640
	s_cmp_lg_u32 s15, 1
	s_waitcnt lgkmcnt(2)
	v_mfma_f32_32x32x16_bf16 v[144:159], v[4:7], v[160:163], 0
	s_waitcnt lgkmcnt(1)
	v_mfma_f32_32x32x16_bf16 v[144:159], v[8:11], v[164:167], v[144:159]
	s_waitcnt lgkmcnt(0)
	v_mfma_f32_32x32x16_bf16 v[128:143], v[0:3], v[164:167], v[128:143]
	ds_read_b128 v[0:3], v12 offset:64
	ds_read_b128 v[4:7], v12 offset:4672
	s_waitcnt lgkmcnt(1)
	v_mfma_f32_32x32x16_bf16 v[144:159], v[0:3], v[168:171], v[144:159]
	s_waitcnt lgkmcnt(0)
	v_mfma_f32_32x32x16_bf16 v[128:143], v[4:7], v[168:171], v[128:143]
	ds_read_b128 v[0:3], v12 offset:96
	ds_read_b128 v[4:7], v12 offset:4704
	s_waitcnt lgkmcnt(1)
	v_mfma_f32_32x32x16_bf16 v[144:159], v[0:3], v[172:175], v[144:159]
	s_waitcnt lgkmcnt(0)
	v_mfma_f32_32x32x16_bf16 v[128:143], v[4:7], v[172:175], v[128:143]
	s_cbranch_scc0 .LBB0_468
	v_or_b32_e32 v0, s14, v237
	v_sub_u32_e32 v0, v206, v0
	s_movk_i32 s0, 0x200
	s_nop 6
	v_mul_f32_e32 v1, 0x3e38aa3b, v144
	v_cmp_gt_u32_e32 vcc, s0, v0
	v_add_u32_e32 v2, -1, v0
	v_mul_f32_e32 v3, 0x3e38aa3b, v145
	v_cndmask_b32_e32 v1, v226, v1, vcc
	v_cmp_gt_u32_e32 vcc, s0, v2
	v_add_u32_e32 v4, -2, v0
	v_mul_f32_e32 v5, 0x3e38aa3b, v146
	v_cndmask_b32_e32 v2, v226, v3, vcc
	v_cmp_gt_u32_e32 vcc, s0, v4
	v_mul_f32_e32 v6, 0x3e38aa3b, v147
	v_mul_f32_e32 v7, 0x3e38aa3b, v148
	v_cndmask_b32_e32 v4, v226, v5, vcc
	v_add_u32_e32 v5, -3, v0
	v_cmp_gt_u32_e32 vcc, s0, v5
	v_mul_f32_e32 v8, 0x3e38aa3b, v149
	v_mul_f32_e32 v9, 0x3e38aa3b, v150
	v_cndmask_b32_e32 v5, v226, v6, vcc
	v_add_u32_e32 v6, -8, v0
	v_cmp_gt_u32_e32 vcc, s0, v6
	v_mul_f32_e32 v10, 0x3e38aa3b, v151
	v_mul_f32_e32 v11, 0x3e38aa3b, v152
	v_cndmask_b32_e32 v6, v226, v7, vcc
	v_add_u32_e32 v7, -9, v0
	v_cmp_gt_u32_e32 vcc, s0, v7
	v_mul_f32_e32 v12, 0x3e38aa3b, v153
	v_mul_f32_e32 v13, 0x3e38aa3b, v154
	v_cndmask_b32_e32 v7, v226, v8, vcc
	v_add_u32_e32 v8, -10, v0
	v_cmp_gt_u32_e32 vcc, s0, v8
	v_mul_f32_e32 v14, 0x3e38aa3b, v155
	v_mul_f32_e32 v15, 0x3e38aa3b, v156
	v_cndmask_b32_e32 v8, v226, v9, vcc
	v_add_u32_e32 v9, -11, v0
	v_cmp_gt_u32_e32 vcc, s0, v9
	v_mul_f32_e32 v16, 0x3e38aa3b, v157
	v_mul_f32_e32 v17, 0x3e38aa3b, v158
	v_cndmask_b32_e32 v9, v226, v10, vcc
	v_add_u32_e32 v10, -16, v0
	v_cmp_gt_u32_e32 vcc, s0, v10
	v_mul_f32_e32 v18, 0x3e38aa3b, v159
	v_mul_f32_e32 v19, 0x3e38aa3b, v128
	v_cndmask_b32_e32 v10, v226, v11, vcc
	v_subrev_u32_e32 v11, 17, v0
	v_cmp_gt_u32_e32 vcc, s0, v11
	v_mul_f32_e32 v20, 0x3e38aa3b, v129
	v_mul_f32_e32 v21, 0x3e38aa3b, v130
	v_cndmask_b32_e32 v11, v226, v12, vcc
	v_subrev_u32_e32 v12, 18, v0
	v_cmp_gt_u32_e32 vcc, s0, v12
	v_mul_f32_e32 v22, 0x3e38aa3b, v131
	v_mul_f32_e32 v23, 0x3e38aa3b, v132
	v_cndmask_b32_e32 v12, v226, v13, vcc
	v_subrev_u32_e32 v13, 19, v0
	v_cmp_gt_u32_e32 vcc, s0, v13
	v_mul_f32_e32 v24, 0x3e38aa3b, v133
	v_mul_f32_e32 v25, 0x3e38aa3b, v134
	v_cndmask_b32_e32 v13, v226, v14, vcc
	v_subrev_u32_e32 v14, 24, v0
	v_cmp_gt_u32_e32 vcc, s0, v14
	v_mul_f32_e32 v26, 0x3e38aa3b, v135
	v_max3_f32 v3, v247, v1, v2
	v_cndmask_b32_e32 v14, v226, v15, vcc
	v_subrev_u32_e32 v15, 25, v0
	v_cmp_gt_u32_e32 vcc, s0, v15
	v_mul_f32_e32 v27, 0x3e38aa3b, v136
	v_max3_f32 v3, v3, v4, v5
	v_cndmask_b32_e32 v15, v226, v16, vcc
	v_subrev_u32_e32 v16, 26, v0
	v_cmp_gt_u32_e32 vcc, s0, v16
	v_max3_f32 v3, v3, v6, v7
	v_mul_f32_e32 v28, 0x3e38aa3b, v137
	v_cndmask_b32_e32 v16, v226, v17, vcc
	v_subrev_u32_e32 v17, 27, v0
	v_cmp_gt_u32_e32 vcc, s0, v17
	v_max3_f32 v3, v3, v8, v9
	v_max3_f32 v3, v3, v10, v11
	v_cndmask_b32_e32 v17, v226, v18, vcc
	v_subrev_u32_e32 v18, 32, v0
	v_cmp_gt_u32_e32 vcc, s0, v18
	v_mul_f32_e32 v29, 0x3e38aa3b, v138
	v_max3_f32 v3, v3, v12, v13
	v_cndmask_b32_e32 v18, v226, v19, vcc
	v_subrev_u32_e32 v19, 33, v0
	v_cmp_gt_u32_e32 vcc, s0, v19
	v_max3_f32 v3, v3, v14, v15
	v_mul_f32_e32 v30, 0x3e38aa3b, v139
	v_cndmask_b32_e32 v19, v226, v20, vcc
	v_subrev_u32_e32 v20, 34, v0
	v_cmp_gt_u32_e32 vcc, s0, v20
	v_max3_f32 v3, v3, v16, v17
	v_max3_f32 v3, v3, v18, v19
	v_cndmask_b32_e32 v20, v226, v21, vcc
	v_subrev_u32_e32 v21, 35, v0
	v_cmp_gt_u32_e32 vcc, s0, v21
	v_mul_f32_e32 v31, 0x3e38aa3b, v140
	v_mul_f32_e32 v216, 0x3e38aa3b, v141
	v_cndmask_b32_e32 v21, v226, v22, vcc
	v_subrev_u32_e32 v22, 40, v0
	v_cmp_gt_u32_e32 vcc, s0, v22
	v_max3_f32 v3, v3, v20, v21
	v_mul_f32_e32 v217, 0x3e38aa3b, v142
	v_cndmask_b32_e32 v22, v226, v23, vcc
	v_subrev_u32_e32 v23, 41, v0
	v_cmp_gt_u32_e32 vcc, s0, v23
	s_nop 1
	v_cndmask_b32_e32 v23, v226, v24, vcc
	v_subrev_u32_e32 v24, 42, v0
	v_cmp_gt_u32_e32 vcc, s0, v24
	v_max3_f32 v3, v3, v22, v23
	s_nop 0
	v_cndmask_b32_e32 v24, v226, v25, vcc
	v_subrev_u32_e32 v25, 43, v0
	v_cmp_gt_u32_e32 vcc, s0, v25
	s_nop 1
	v_cndmask_b32_e32 v25, v226, v26, vcc
	v_subrev_u32_e32 v26, 48, v0
	v_cmp_gt_u32_e32 vcc, s0, v26
	v_max3_f32 v3, v3, v24, v25
	s_nop 0
	v_cndmask_b32_e32 v26, v226, v27, vcc
	v_subrev_u32_e32 v27, 49, v0
	v_cmp_gt_u32_e32 vcc, s0, v27
	s_nop 1
	v_cndmask_b32_e32 v27, v226, v28, vcc
	v_subrev_u32_e32 v28, 50, v0
	v_cmp_gt_u32_e32 vcc, s0, v28
	v_max3_f32 v3, v3, v26, v27
	s_nop 0
	v_cndmask_b32_e32 v28, v226, v29, vcc
	v_subrev_u32_e32 v29, 51, v0
	v_cmp_gt_u32_e32 vcc, s0, v29
	s_nop 1
	v_cndmask_b32_e32 v29, v226, v30, vcc
	v_subrev_u32_e32 v30, 56, v0
	v_cmp_gt_u32_e32 vcc, s0, v30
	v_max3_f32 v3, v3, v28, v29
	s_nop 0
	v_cndmask_b32_e32 v30, v226, v31, vcc
	v_subrev_u32_e32 v31, 57, v0
	v_cmp_gt_u32_e32 vcc, s0, v31
	s_nop 1
	v_cndmask_b32_e32 v31, v226, v216, vcc
	v_subrev_u32_e32 v216, 58, v0
	v_cmp_gt_u32_e32 vcc, s0, v216
	v_subrev_u32_e32 v0, 59, v0
	v_max3_f32 v3, v3, v30, v31
	v_cndmask_b32_e32 v216, v226, v217, vcc
	v_mul_f32_e32 v217, 0x3e38aa3b, v143
	v_cmp_gt_u32_e32 vcc, s0, v0
	s_mov_b64 s[0:1], 0
	s_nop 0
	v_cndmask_b32_e32 v217, v226, v217, vcc
	v_max3_f32 v0, v3, v216, v217
	ds_bpermute_b32 v3, v236, v0
	s_waitcnt lgkmcnt(0)
	v_max_f32_e32 v3, v3, v3
	v_max_f32_e32 v248, v0, v3
	v_sub_f32_e32 v0, v1, v248
	v_exp_f32_e32 v0, v0
	v_sub_f32_e32 v1, v2, v248
	v_exp_f32_e32 v1, v1
	v_sub_f32_e32 v2, v4, v248
	v_exp_f32_e32 v2, v2
	v_sub_f32_e32 v3, v5, v248
	v_exp_f32_e32 v3, v3
	v_add_f32_e32 v4, 0, v0
	v_add_f32_e32 v4, v1, v4
	v_add_f32_e32 v4, v2, v4
	v_add_f32_e32 v218, v3, v4
	v_sub_f32_e32 v4, v6, v248
	v_exp_f32_e32 v4, v4
	v_sub_f32_e32 v5, v7, v248
	v_exp_f32_e32 v5, v5
	v_sub_f32_e32 v6, v8, v248
	v_exp_f32_e32 v6, v6
	v_sub_f32_e32 v7, v9, v248
	v_exp_f32_e32 v7, v7
	v_add_f32_e32 v8, v4, v218
	v_add_f32_e32 v8, v5, v8
	v_add_f32_e32 v8, v6, v8
	v_add_f32_e32 v218, v7, v8
	v_sub_f32_e32 v8, v10, v248
	v_exp_f32_e32 v8, v8
	v_sub_f32_e32 v9, v11, v248
	v_exp_f32_e32 v9, v9
	v_sub_f32_e32 v10, v12, v248
	v_exp_f32_e32 v10, v10
	v_sub_f32_e32 v11, v13, v248
	v_exp_f32_e32 v11, v11
	v_add_f32_e32 v12, v8, v218
	v_add_f32_e32 v12, v9, v12
	v_add_f32_e32 v12, v10, v12
	v_add_f32_e32 v218, v11, v12
	v_sub_f32_e32 v12, v14, v248
	v_exp_f32_e32 v12, v12
	v_sub_f32_e32 v13, v15, v248
	v_exp_f32_e32 v13, v13
	v_sub_f32_e32 v14, v16, v248
	v_exp_f32_e32 v14, v14
	v_sub_f32_e32 v15, v17, v248
	v_exp_f32_e32 v15, v15
	v_add_f32_e32 v16, v12, v218
	v_add_f32_e32 v16, v13, v16
	v_add_f32_e32 v16, v14, v16
	v_add_f32_e32 v218, v15, v16
	v_sub_f32_e32 v16, v18, v248
	v_exp_f32_e32 v16, v16
	v_sub_f32_e32 v17, v19, v248
	v_exp_f32_e32 v17, v17
	v_sub_f32_e32 v18, v20, v248
	v_exp_f32_e32 v18, v18
	v_sub_f32_e32 v19, v21, v248
	v_exp_f32_e32 v19, v19
	v_add_f32_e32 v20, v16, v218
	v_add_f32_e32 v20, v17, v20
	v_add_f32_e32 v20, v18, v20
	v_add_f32_e32 v218, v19, v20
	v_sub_f32_e32 v20, v22, v248
	v_exp_f32_e32 v20, v20
	v_sub_f32_e32 v21, v23, v248
	v_exp_f32_e32 v21, v21
	v_sub_f32_e32 v22, v24, v248
	v_exp_f32_e32 v22, v22
	v_sub_f32_e32 v23, v25, v248
	v_exp_f32_e32 v23, v23
	v_add_f32_e32 v24, v20, v218
	v_add_f32_e32 v24, v21, v24
	v_add_f32_e32 v24, v22, v24
	v_add_f32_e32 v218, v23, v24
	v_sub_f32_e32 v24, v26, v248
	v_exp_f32_e32 v24, v24
	v_sub_f32_e32 v25, v27, v248
	v_exp_f32_e32 v25, v25
	v_sub_f32_e32 v26, v28, v248
	v_exp_f32_e32 v26, v26
	v_sub_f32_e32 v27, v29, v248
	v_exp_f32_e32 v27, v27
	v_add_f32_e32 v28, v24, v218
	v_add_f32_e32 v28, v25, v28
	v_add_f32_e32 v28, v26, v28
	v_add_f32_e32 v218, v27, v28
	v_sub_f32_e32 v28, v30, v248
	v_exp_f32_e32 v28, v28
	v_sub_f32_e32 v29, v31, v248
	v_exp_f32_e32 v29, v29
	v_sub_f32_e32 v30, v216, v248
	v_exp_f32_e32 v30, v30
	v_sub_f32_e32 v31, v217, v248
	v_exp_f32_e32 v31, v31
	v_add_f32_e32 v216, v28, v218
	v_add_f32_e32 v216, v29, v216
	v_add_f32_e32 v216, v30, v216
	v_add_f32_e32 v249, v31, v216

.LBB0_470:
	s_nop 8
	v_sub_f32_e32 v128, v247, v248
	v_exp_f32_e32 v132, v128
	v_lshlrev_b32_e32 v128, 1, v237
	v_cvt_pk_bf16_f32 v0, v0, v1
	v_cvt_pk_bf16_f32 v1, v2, v3
	v_pk_mul_f32 v[126:127], v[126:127], v[132:133] op_sel_hi:[1,0]
	v_pk_mul_f32 v[124:125], v[124:125], v[132:133] op_sel_hi:[1,0]
	v_pk_mul_f32 v[122:123], v[122:123], v[132:133] op_sel_hi:[1,0]
	v_pk_mul_f32 v[120:121], v[120:121], v[132:133] op_sel_hi:[1,0]
	v_pk_mul_f32 v[118:119], v[118:119], v[132:133] op_sel_hi:[1,0]
	v_pk_mul_f32 v[116:117], v[116:117], v[132:133] op_sel_hi:[1,0]
	v_pk_mul_f32 v[114:115], v[114:115], v[132:133] op_sel_hi:[1,0]
	v_add3_u32 v133, s9, v246, v128
	v_add_u32_e32 v134, 0x3000, v133
	v_pk_mul_f32 v[112:113], v[112:113], v[132:133] op_sel_hi:[1,0]
	v_pk_mul_f32 v[78:79], v[78:79], v[132:133] op_sel_hi:[1,0]
	v_add_u32_e32 v133, 0x4000, v133
	ds_read2_b64 v[128:131], v134 offset0:128 offset1:130
	v_cvt_pk_bf16_f32 v2, v4, v5
	v_cvt_pk_bf16_f32 v3, v6, v7
	ds_read2_b64 v[4:7], v133 offset0:160 offset1:162
	v_pk_mul_f32 v[76:77], v[76:77], v[132:133] op_sel_hi:[1,0]
	v_pk_mul_f32 v[74:75], v[74:75], v[132:133] op_sel_hi:[1,0]
	v_pk_mul_f32 v[72:73], v[72:73], v[132:133] op_sel_hi:[1,0]
	v_pk_mul_f32 v[70:71], v[70:71], v[132:133] op_sel_hi:[1,0]
	v_pk_mul_f32 v[68:69], v[68:69], v[132:133] op_sel_hi:[1,0]
	v_pk_mul_f32 v[66:67], v[66:67], v[132:133] op_sel_hi:[1,0]
	v_pk_mul_f32 v[64:65], v[64:65], v[132:133] op_sel_hi:[1,0]
	s_waitcnt lgkmcnt(1)
	v_mfma_f32_32x32x16_bf16 v[112:127], v[128:131], v[0:3], v[112:127]
	v_fmac_f32_e32 v249, v209, v132
	v_mov_b32_e32 v209, v249
	v_mov_b32_e32 v247, v248
	s_waitcnt lgkmcnt(0)
	v_mfma_f32_32x32x16_bf16 v[64:79], v[4:7], v[0:3], v[64:79]
	ds_read2_b64 v[0:3], v134 offset0:132 offset1:134
	v_cvt_pk_bf16_f32 v4, v8, v9
	v_cvt_pk_bf16_f32 v5, v10, v11
	v_cvt_pk_bf16_f32 v6, v12, v13
	v_cvt_pk_bf16_f32 v7, v14, v15
	s_nop 0
	s_nop 0
	s_waitcnt lgkmcnt(0)
	v_mfma_f32_32x32x16_bf16 v[112:127], v[0:3], v[4:7], v[112:127]
	ds_read2_b64 v[0:3], v133 offset0:164 offset1:166
	s_waitcnt lgkmcnt(0)
	v_mfma_f32_32x32x16_bf16 v[64:79], v[0:3], v[4:7], v[64:79]
	ds_read2_b64 v[0:3], v134 offset0:136 offset1:138
	v_cvt_pk_bf16_f32 v4, v16, v17
	v_cvt_pk_bf16_f32 v5, v18, v19
	v_cvt_pk_bf16_f32 v6, v20, v21
	v_cvt_pk_bf16_f32 v7, v22, v23
	s_nop 0
	s_nop 0
	s_waitcnt lgkmcnt(0)
	v_mfma_f32_32x32x16_bf16 v[112:127], v[0:3], v[4:7], v[112:127]
	ds_read2_b64 v[0:3], v133 offset0:168 offset1:170
	s_waitcnt lgkmcnt(0)
	v_mfma_f32_32x32x16_bf16 v[64:79], v[0:3], v[4:7], v[64:79]
	ds_read2_b64 v[0:3], v134 offset0:140 offset1:142
	v_cvt_pk_bf16_f32 v4, v24, v25
	v_cvt_pk_bf16_f32 v5, v26, v27
	v_cvt_pk_bf16_f32 v6, v28, v29
	v_cvt_pk_bf16_f32 v7, v30, v31
	s_nop 0
	s_nop 0
	s_waitcnt lgkmcnt(0)
	v_mfma_f32_32x32x16_bf16 v[112:127], v[0:3], v[4:7], v[112:127]
	ds_read2_b64 v[0:3], v133 offset0:172 offset1:174
	s_waitcnt lgkmcnt(0)
	v_mfma_f32_32x32x16_bf16 v[64:79], v[0:3], v[4:7], v[64:79]
.LBB0_471:
	s_cmp_lt_i32 s10, 0
	s_cbranch_scc1 .LBB0_462
	s_xor_b32 s8, s8, 1
	s_mul_i32 s0, s8, 0x9000
	v_add3_u32 v1, s0, v242, v243
	v_lshlrev_b32_e32 v0, 2, v241
	s_waitcnt vmcnt(0)
	ds_write_b128 v1, v[176:179]
	v_add3_u32 v1, s0, v244, v245
	ds_write_b128 v1, v[180:183]
	v_add3_u32 v0, s0, v0, v238
	v_lshlrev_b32_e32 v1, 16, v188
	s_mov_b32 s1, 0xffff
	v_lshrrev_b32_e32 v2, 16, v184
	s_mov_b32 s0, 0xffff0000
	v_and_or_b32 v1, v184, s1, v1
	v_and_or_b32 v2, v188, s0, v2
	v_add_u32_e32 v0, 0x3400, v0
	ds_write2_b32 v0, v1, v2 offset1:34
	v_lshlrev_b32_e32 v1, 16, v189
	v_lshrrev_b32_e32 v2, 16, v185
	v_and_or_b32 v1, v185, s1, v1
	v_and_or_b32 v2, v189, s0, v2
	ds_write2_b32 v0, v1, v2 offset0:68 offset1:102
	v_lshlrev_b32_e32 v1, 16, v190
	v_lshrrev_b32_e32 v2, 16, v186
	v_and_or_b32 v1, v186, s1, v1
	v_and_or_b32 v2, v190, s0, v2
	ds_write2_b32 v0, v1, v2 offset0:136 offset1:170
	v_lshrrev_b32_e32 v2, 16, v187
	v_and_or_b32 v2, v191, s0, v2
	s_add_i32 s0, s10, -1
	s_cmp_gt_i32 s10, s11
	v_lshlrev_b32_e32 v1, 16, v191
	s_cselect_b32 s14, s0, -1
	v_and_or_b32 v1, v187, s1, v1
	s_cmp_lt_i32 s14, 0
	ds_write2_b32 v0, v1, v2 offset0:204 offset1:238
	s_cbranch_scc1 .LBB0_474
	s_lshl_b32 s9, s14, 6
	v_add_u32_e32 v0, s9, v192
	s_movk_i32 s15, 0x1d00
	v_add_u32_e32 v2, s9, v240
	v_mad_i64_i32 v[0:1], s[0:1], v0, s15, v[212:213]
	v_mad_i64_i32 v[2:3], s[0:1], v2, s15, v[214:215]
	global_load_dwordx4 v[176:179], v[0:1], off
	global_load_dwordx4 v[180:183], v[2:3], off
	v_or_b32_e32 v2, s9, v239
	v_mad_u64_u32 v[0:1], s[0:1], v2, s15, v[210:211]
	v_or_b32_e32 v2, 1, v2
	v_mad_u64_u32 v[2:3], s[0:1], v2, s15, v[210:211]
	global_load_dwordx4 v[184:187], v[0:1], off
	global_load_dwordx4 v[188:191], v[2:3], off

.LBB0_475:
	v_lshlrev_b32_e32 v0, 16, v199
	v_mul_f32_e32 v0, 0xbfb8aa3b, v0
	v_exp_f32_e32 v0, v0
	v_lshlrev_b64 v[10:11], 11, v[200:201]
	v_lshlrev_b32_e32 v192, 1, v235
	v_readlane_b32 s10, v254, 51
	v_add_f32_e32 v0, 1.0, v0
	v_div_scale_f32 v1, s[0:1], v0, v0, 1.0
	v_rcp_f32_e32 v2, v1
	s_nop 0
	v_fma_f32 v3, -v1, v2, 1.0
	v_fmac_f32_e32 v2, v3, v2
	v_div_scale_f32 v3, vcc, 1.0, v0, 1.0
	v_mul_f32_e32 v4, v3, v2
	v_fma_f32 v5, -v1, v4, v3
	v_fmac_f32_e32 v4, v5, v2
	v_fma_f32 v1, -v1, v4, v3
	v_div_fmas_f32 v1, v1, v2, v4
	v_div_fixup_f32 v4, v1, v0, 1.0
	v_and_b32_e32 v0, 0xffff0000, v199
	v_mul_f32_e32 v0, 0xbfb8aa3b, v0
	v_exp_f32_e32 v206, v0
	s_waitcnt lgkmcnt(0)
	v_pk_add_f32 v[0:1], v[206:207], v[194:195]
	s_nop 0
	v_div_scale_f32 v2, s[0:1], v0, v0, 1.0
	v_rcp_f32_e32 v3, v2
	ds_bpermute_b32 v195, v236, v209
	v_fma_f32 v5, -v2, v3, 1.0
	v_fmac_f32_e32 v3, v5, v3
	v_div_scale_f32 v5, vcc, 1.0, v0, 1.0
	v_mul_f32_e32 v6, v5, v3
	v_fma_f32 v7, -v2, v6, v5
	v_fmac_f32_e32 v6, v7, v3
	v_fma_f32 v2, -v2, v6, v5
	v_div_fmas_f32 v2, v2, v3, v6
	v_div_fixup_f32 v0, v2, v0, 1.0
	v_div_scale_f32 v2, s[0:1], v1, v1, v0
	v_rcp_f32_e32 v3, v2
	s_nop 0
	v_fma_f32 v5, -v2, v3, 1.0
	v_fmac_f32_e32 v3, v5, v3
	v_div_scale_f32 v5, vcc, v0, v1, v0
	v_mul_f32_e32 v6, v5, v3
	v_fma_f32 v7, -v2, v6, v5
	v_fmac_f32_e32 v6, v7, v3
	v_fma_f32 v2, -v2, v6, v5
	v_div_fmas_f32 v2, v2, v3, v6
	v_div_fixup_f32 v6, v2, v1, v0
	v_lshlrev_b32_e32 v0, 16, v197
	v_mul_f32_e32 v0, 0xbfb8aa3b, v0
	v_exp_f32_e32 v208, v0
	s_waitcnt lgkmcnt(0)
	v_pk_add_f32 v[0:1], v[208:209], v[194:195]
	s_nop 0
	v_div_scale_f32 v2, s[0:1], v0, v0, 1.0
	v_rcp_f32_e32 v3, v2
	s_nop 0
	v_fma_f32 v5, -v2, v3, 1.0
	v_fmac_f32_e32 v3, v5, v3
	v_div_scale_f32 v5, vcc, 1.0, v0, 1.0
	v_mul_f32_e32 v7, v5, v3
	v_fma_f32 v8, -v2, v7, v5
	v_fmac_f32_e32 v7, v8, v3
	v_fma_f32 v2, -v2, v7, v5
	v_div_fmas_f32 v2, v2, v3, v7
	v_div_fixup_f32 v0, v2, v0, 1.0
	v_div_scale_f32 v2, s[0:1], v1, v1, v0
	v_rcp_f32_e32 v3, v2
	v_readlane_b32 s0, v254, 43
	v_readlane_b32 s1, v254, 44
	v_fma_f32 v5, -v2, v3, 1.0
	v_fmac_f32_e32 v3, v5, v3
	v_div_scale_f32 v5, vcc, v0, v1, v0
	v_mul_f32_e32 v7, v5, v3
	v_fma_f32 v8, -v2, v7, v5
	v_fmac_f32_e32 v7, v8, v3
	v_fma_f32 v2, -v2, v7, v5
	v_div_fmas_f32 v2, v2, v3, v7
	v_div_fixup_f32 v8, v2, v1, v0
	v_lshlrev_b64 v[0:1], 1, v[204:205]
	v_lshl_add_u64 v[2:3], v[202:203], 0, v[0:1]
	v_lshl_add_u64 v[10:11], s[0:1], 0, v[10:11]
	v_lshl_add_u64 v[10:11], v[10:11], 0, v[0:1]
	v_lshl_add_u64 v[2:3], v[2:3], 0, v[192:193]
	s_mov_b64 s[0:1], 0x1200
	v_lshl_add_u64 v[0:1], v[2:3], 0, s[0:1]
	v_lshl_add_u64 v[16:17], v[10:11], 0, v[192:193]
	s_mov_b64 s[0:1], 0xd210400
	v_lshl_add_u64 v[10:11], v[16:17], 0, s[0:1]
	s_movk_i32 s0, 0x1000
	v_add_co_u32_e32 v2, vcc, s0, v2
	s_nop 1
	v_addc_co_u32_e32 v3, vcc, 0, v3, vcc
	global_load_dwordx4 v[12:15], v[2:3], off offset:512
	s_waitcnt vmcnt(0)
	v_mov_b32_e32 v5, v14
	s_nop 1
	v_permlane32_swap_b32_e32 v12, v5
	v_lshlrev_b32_e32 v9, 16, v12
	v_and_b32_e32 v12, 0xffff0000, v12
	v_mov_b32_e32 v7, v15
	v_mul_f32_e32 v14, 0xbfb8aa3b, v9
	v_mul_f32_e32 v15, 0xbfb8aa3b, v12
	v_exp_f32_e32 v14, v14
	v_exp_f32_e32 v15, v15
	v_permlane32_swap_b32_e32 v13, v7
	v_pk_mul_f32 v[2:3], v[96:97], v[6:7] op_sel_hi:[1,0]
	v_pk_add_f32 v[14:15], v[14:15], 1.0 op_sel_hi:[1,0]
	v_pk_fma_f32 v[2:3], v[4:5], v[80:81], v[2:3] op_sel_hi:[0,1,1]
	v_div_scale_f32 v18, s[0:1], v15, v15, v12
	v_rcp_f32_e32 v19, v18
	v_pk_fma_f32 v[2:3], v[112:113], v[8:9], v[2:3] op_sel_hi:[1,0,1]
	v_fma_f32 v20, -v18, v19, 1.0
	v_fmac_f32_e32 v19, v20, v19
	v_div_scale_f32 v20, vcc, v12, v15, v12
	v_mul_f32_e32 v21, v20, v19
	v_fma_f32 v22, -v18, v21, v20
	v_fmac_f32_e32 v21, v22, v19
	v_fma_f32 v18, -v18, v21, v20
	v_div_fmas_f32 v18, v18, v19, v21
	v_div_fixup_f32 v15, v18, v15, v12
	v_div_scale_f32 v12, s[0:1], v14, v14, v9
	v_rcp_f32_e32 v18, v12
	s_nop 0
	v_fma_f32 v19, -v12, v18, 1.0
	v_fmac_f32_e32 v18, v19, v18
	v_div_scale_f32 v19, vcc, v9, v14, v9
	v_mul_f32_e32 v20, v19, v18
	v_fma_f32 v21, -v12, v20, v19
	v_fmac_f32_e32 v20, v21, v18
	v_fma_f32 v12, -v12, v20, v19
	v_div_fmas_f32 v12, v12, v18, v20
	v_div_fixup_f32 v14, v12, v14, v9
	v_lshlrev_b32_e32 v9, 16, v13
	v_and_b32_e32 v18, 0xffff0000, v13
	v_pk_mul_f32 v[2:3], v[2:3], v[14:15]
	v_mul_f32_e32 v14, 0xbfb8aa3b, v9
	v_mul_f32_e32 v15, 0xbfb8aa3b, v18
	v_exp_f32_e32 v14, v14
	v_exp_f32_e32 v15, v15
	v_pk_mul_f32 v[12:13], v[98:99], v[6:7] op_sel_hi:[1,0]
	v_pk_add_f32 v[14:15], v[14:15], 1.0 op_sel_hi:[1,0]
	s_nop 0
	v_div_scale_f32 v19, s[0:1], v15, v15, v18
	v_rcp_f32_e32 v20, v19
	v_pk_fma_f32 v[12:13], v[4:5], v[82:83], v[12:13] op_sel_hi:[0,1,1]
	v_pk_fma_f32 v[12:13], v[114:115], v[8:9], v[12:13] op_sel_hi:[1,0,1]
	v_fma_f32 v21, -v19, v20, 1.0
	v_fmac_f32_e32 v20, v21, v20
	v_div_scale_f32 v21, vcc, v18, v15, v18
	v_mul_f32_e32 v22, v21, v20
	v_fma_f32 v23, -v19, v22, v21
	v_fmac_f32_e32 v22, v23, v20
	v_fma_f32 v19, -v19, v22, v21
	v_div_fmas_f32 v19, v19, v20, v22
	v_div_fixup_f32 v15, v19, v15, v18
	v_div_scale_f32 v18, s[0:1], v14, v14, v9
	v_rcp_f32_e32 v19, v18
	s_nop 0
	v_fma_f32 v20, -v18, v19, 1.0
	v_fmac_f32_e32 v19, v20, v19
	v_div_scale_f32 v20, vcc, v9, v14, v9
	v_mul_f32_e32 v21, v20, v19
	v_fma_f32 v22, -v18, v21, v20
	v_fmac_f32_e32 v21, v22, v19
	v_fma_f32 v18, -v18, v21, v20
	v_div_fmas_f32 v18, v18, v19, v21
	v_div_fixup_f32 v14, v18, v14, v9
	v_lshlrev_b32_e32 v9, 16, v5
	v_and_b32_e32 v5, 0xffff0000, v5
	v_mul_f32_e32 v18, 0xbfb8aa3b, v9
	v_mul_f32_e32 v19, 0xbfb8aa3b, v5
	v_exp_f32_e32 v18, v18
	v_exp_f32_e32 v19, v19
	v_pk_mul_f32 v[14:15], v[12:13], v[14:15]
	v_pk_mul_f32 v[12:13], v[100:101], v[6:7] op_sel_hi:[1,0]
	v_pk_add_f32 v[18:19], v[18:19], 1.0 op_sel_hi:[1,0]
	s_nop 0
	v_div_scale_f32 v20, s[0:1], v19, v19, v5
	v_rcp_f32_e32 v21, v20
	v_pk_fma_f32 v[12:13], v[4:5], v[84:85], v[12:13] op_sel_hi:[0,1,1]
	v_pk_fma_f32 v[12:13], v[116:117], v[8:9], v[12:13] op_sel_hi:[1,0,1]
	v_fma_f32 v22, -v20, v21, 1.0
	v_fmac_f32_e32 v21, v22, v21
	v_div_scale_f32 v22, vcc, v5, v19, v5
	v_mul_f32_e32 v23, v22, v21
	v_fma_f32 v24, -v20, v23, v22
	v_fmac_f32_e32 v23, v24, v21
	v_fma_f32 v20, -v20, v23, v22
	v_div_fmas_f32 v20, v20, v21, v23
	v_div_fixup_f32 v19, v20, v19, v5
	v_div_scale_f32 v5, s[0:1], v18, v18, v9
	v_rcp_f32_e32 v20, v5
	s_nop 0
	v_fma_f32 v21, -v5, v20, 1.0
	v_fmac_f32_e32 v20, v21, v20
	v_div_scale_f32 v21, vcc, v9, v18, v9
	v_mul_f32_e32 v22, v21, v20
	v_fma_f32 v23, -v5, v22, v21
	v_fmac_f32_e32 v22, v23, v20
	v_fma_f32 v5, -v5, v22, v21
	v_div_fmas_f32 v5, v5, v20, v22
	v_div_fixup_f32 v18, v5, v18, v9
	v_lshlrev_b32_e32 v5, 16, v7
	v_and_b32_e32 v7, 0xffff0000, v7
	v_pk_mul_f32 v[18:19], v[12:13], v[18:19]
	v_pk_mul_f32 v[12:13], v[102:103], v[6:7] op_sel_hi:[1,0]
	s_nop 0
	v_pk_fma_f32 v[12:13], v[4:5], v[86:87], v[12:13] op_sel_hi:[0,1,1]
	v_pk_fma_f32 v[12:13], v[118:119], v[8:9], v[12:13] op_sel_hi:[1,0,1]
	v_mul_f32_e32 v9, 0xbfb8aa3b, v5
	v_exp_f32_e32 v20, v9
	v_mul_f32_e32 v9, 0xbfb8aa3b, v7
	v_exp_f32_e32 v21, v9
	s_nop 0
	v_pk_add_f32 v[20:21], v[20:21], 1.0 op_sel_hi:[1,0]
	s_nop 0
	v_div_scale_f32 v9, s[0:1], v21, v21, v7
	v_rcp_f32_e32 v22, v9
	s_nop 0
	v_fma_f32 v23, -v9, v22, 1.0
	v_fmac_f32_e32 v22, v23, v22
	v_div_scale_f32 v23, vcc, v7, v21, v7
	v_mul_f32_e32 v24, v23, v22
	v_fma_f32 v25, -v9, v24, v23
	v_fmac_f32_e32 v24, v25, v22
	v_fma_f32 v9, -v9, v24, v23
	v_div_fmas_f32 v9, v9, v22, v24
	v_div_fixup_f32 v21, v9, v21, v7
	v_div_scale_f32 v7, s[0:1], v20, v20, v5
	v_rcp_f32_e32 v9, v7
	s_mov_b32 s0, 0xd210000
	v_fma_f32 v22, -v7, v9, 1.0
	v_fmac_f32_e32 v9, v22, v9
	v_div_scale_f32 v22, vcc, v5, v20, v5
	v_mul_f32_e32 v23, v22, v9
	v_fma_f32 v24, -v7, v23, v22
	v_fmac_f32_e32 v23, v24, v9
	v_fma_f32 v7, -v7, v23, v22
	v_div_fmas_f32 v7, v7, v9, v23
	v_div_fixup_f32 v20, v7, v20, v5
	v_pk_mul_f32 v[20:21], v[12:13], v[20:21]
	v_cvt_pk_bf16_f32 v12, v2, v3
	v_cvt_pk_bf16_f32 v13, v14, v15
	v_cvt_pk_bf16_f32 v14, v18, v19
	v_cvt_pk_bf16_f32 v15, v20, v21
	v_add_co_u32_e32 v2, vcc, s0, v16
	v_permlane32_swap_b32_e32 v12, v14
	v_permlane32_swap_b32_e32 v13, v15
	v_addc_co_u32_e32 v3, vcc, 0, v17, vcc
	global_store_dwordx4 v[2:3], v[12:15], off offset:1024
	global_load_dwordx4 v[12:15], v[0:1], off offset:32
	s_waitcnt vmcnt(0)
	v_mov_b32_e32 v5, v14
	s_nop 1
	v_permlane32_swap_b32_e32 v12, v5
	v_lshlrev_b32_e32 v9, 16, v12
	v_and_b32_e32 v12, 0xffff0000, v12
	v_mov_b32_e32 v7, v15
	v_mul_f32_e32 v14, 0xbfb8aa3b, v9
	v_mul_f32_e32 v15, 0xbfb8aa3b, v12
	v_exp_f32_e32 v14, v14
	v_exp_f32_e32 v15, v15
	v_permlane32_swap_b32_e32 v13, v7
	v_pk_mul_f32 v[2:3], v[104:105], v[6:7] op_sel_hi:[1,0]
	v_pk_add_f32 v[14:15], v[14:15], 1.0 op_sel_hi:[1,0]
	v_pk_fma_f32 v[2:3], v[4:5], v[88:89], v[2:3] op_sel_hi:[0,1,1]
	v_div_scale_f32 v16, s[0:1], v15, v15, v12
	v_rcp_f32_e32 v17, v16
	v_pk_fma_f32 v[2:3], v[120:121], v[8:9], v[2:3] op_sel_hi:[1,0,1]
	v_fma_f32 v18, -v16, v17, 1.0
	v_fmac_f32_e32 v17, v18, v17
	v_div_scale_f32 v18, vcc, v12, v15, v12
	v_mul_f32_e32 v19, v18, v17
	v_fma_f32 v20, -v16, v19, v18
	v_fmac_f32_e32 v19, v20, v17
	v_fma_f32 v16, -v16, v19, v18
	v_div_fmas_f32 v16, v16, v17, v19
	v_div_fixup_f32 v15, v16, v15, v12
	v_div_scale_f32 v12, s[0:1], v14, v14, v9
	v_rcp_f32_e32 v16, v12
	s_nop 0
	v_fma_f32 v17, -v12, v16, 1.0
	v_fmac_f32_e32 v16, v17, v16
	v_div_scale_f32 v17, vcc, v9, v14, v9
	v_mul_f32_e32 v18, v17, v16
	v_fma_f32 v19, -v12, v18, v17
	v_fmac_f32_e32 v18, v19, v16
	v_fma_f32 v12, -v12, v18, v17
	v_div_fmas_f32 v12, v12, v16, v18
	v_div_fixup_f32 v14, v12, v14, v9
	v_lshlrev_b32_e32 v9, 16, v13
	v_and_b32_e32 v16, 0xffff0000, v13
	v_pk_mul_f32 v[2:3], v[2:3], v[14:15]
	v_mul_f32_e32 v14, 0xbfb8aa3b, v9
	v_mul_f32_e32 v15, 0xbfb8aa3b, v16
	v_exp_f32_e32 v14, v14
	v_exp_f32_e32 v15, v15
	v_pk_mul_f32 v[12:13], v[106:107], v[6:7] op_sel_hi:[1,0]
	v_pk_add_f32 v[14:15], v[14:15], 1.0 op_sel_hi:[1,0]
	s_nop 0
	v_div_scale_f32 v17, s[0:1], v15, v15, v16
	v_rcp_f32_e32 v18, v17
	v_pk_fma_f32 v[12:13], v[4:5], v[90:91], v[12:13] op_sel_hi:[0,1,1]
	v_pk_fma_f32 v[12:13], v[122:123], v[8:9], v[12:13] op_sel_hi:[1,0,1]
	v_fma_f32 v19, -v17, v18, 1.0
	v_fmac_f32_e32 v18, v19, v18
	v_div_scale_f32 v19, vcc, v16, v15, v16
	v_mul_f32_e32 v20, v19, v18
	v_fma_f32 v21, -v17, v20, v19
	v_fmac_f32_e32 v20, v21, v18
	v_fma_f32 v17, -v17, v20, v19
	v_div_fmas_f32 v17, v17, v18, v20
	v_div_fixup_f32 v15, v17, v15, v16
	v_div_scale_f32 v16, s[0:1], v14, v14, v9
	v_rcp_f32_e32 v17, v16
	s_nop 0
	v_fma_f32 v18, -v16, v17, 1.0
	v_fmac_f32_e32 v17, v18, v17
	v_div_scale_f32 v18, vcc, v9, v14, v9
	v_mul_f32_e32 v19, v18, v17
	v_fma_f32 v20, -v16, v19, v18
	v_fmac_f32_e32 v19, v20, v17
	v_fma_f32 v16, -v16, v19, v18
	v_div_fmas_f32 v16, v16, v17, v19
	v_div_fixup_f32 v14, v16, v14, v9
	v_lshlrev_b32_e32 v9, 16, v5
	v_and_b32_e32 v5, 0xffff0000, v5
	v_mul_f32_e32 v16, 0xbfb8aa3b, v9
	v_mul_f32_e32 v17, 0xbfb8aa3b, v5
	v_exp_f32_e32 v16, v16
	v_exp_f32_e32 v17, v17
	v_pk_mul_f32 v[14:15], v[12:13], v[14:15]
	v_pk_mul_f32 v[12:13], v[108:109], v[6:7] op_sel_hi:[1,0]
	v_pk_add_f32 v[16:17], v[16:17], 1.0 op_sel_hi:[1,0]
	s_nop 0
	v_div_scale_f32 v18, s[0:1], v17, v17, v5
	v_rcp_f32_e32 v19, v18
	v_pk_fma_f32 v[12:13], v[4:5], v[92:93], v[12:13] op_sel_hi:[0,1,1]
	v_pk_fma_f32 v[12:13], v[124:125], v[8:9], v[12:13] op_sel_hi:[1,0,1]
	v_fma_f32 v20, -v18, v19, 1.0
	v_fmac_f32_e32 v19, v20, v19
	v_div_scale_f32 v20, vcc, v5, v17, v5
	v_mul_f32_e32 v21, v20, v19
	v_fma_f32 v22, -v18, v21, v20
	v_fmac_f32_e32 v21, v22, v19
	v_fma_f32 v18, -v18, v21, v20
	v_div_fmas_f32 v18, v18, v19, v21
	v_div_fixup_f32 v17, v18, v17, v5
	v_div_scale_f32 v5, s[0:1], v16, v16, v9
	v_rcp_f32_e32 v18, v5
	s_nop 0
	v_fma_f32 v19, -v5, v18, 1.0
	v_fmac_f32_e32 v18, v19, v18
	v_div_scale_f32 v19, vcc, v9, v16, v9
	v_mul_f32_e32 v20, v19, v18
	v_fma_f32 v21, -v5, v20, v19
	v_fmac_f32_e32 v20, v21, v18
	v_fma_f32 v5, -v5, v20, v19
	v_div_fmas_f32 v5, v5, v18, v20
	v_div_fixup_f32 v16, v5, v16, v9
	v_lshlrev_b32_e32 v5, 16, v7
	v_and_b32_e32 v7, 0xffff0000, v7
	v_pk_mul_f32 v[16:17], v[12:13], v[16:17]
	v_pk_mul_f32 v[12:13], v[110:111], v[6:7] op_sel_hi:[1,0]
	s_nop 0
	v_pk_fma_f32 v[12:13], v[4:5], v[94:95], v[12:13] op_sel_hi:[0,1,1]
	v_pk_fma_f32 v[12:13], v[126:127], v[8:9], v[12:13] op_sel_hi:[1,0,1]
	v_mul_f32_e32 v9, 0xbfb8aa3b, v5
	v_exp_f32_e32 v18, v9
	v_mul_f32_e32 v9, 0xbfb8aa3b, v7
	v_exp_f32_e32 v19, v9
	s_nop 0
	v_pk_add_f32 v[18:19], v[18:19], 1.0 op_sel_hi:[1,0]
	s_nop 0
	v_div_scale_f32 v9, s[0:1], v19, v19, v7
	v_rcp_f32_e32 v20, v9
	s_nop 0
	v_fma_f32 v21, -v9, v20, 1.0
	v_fmac_f32_e32 v20, v21, v20
	v_div_scale_f32 v21, vcc, v7, v19, v7
	v_mul_f32_e32 v22, v21, v20
	v_fma_f32 v23, -v9, v22, v21
	v_fmac_f32_e32 v22, v23, v20
	v_fma_f32 v9, -v9, v22, v21
	v_div_fmas_f32 v9, v9, v20, v22
	v_div_fixup_f32 v19, v9, v19, v7
	v_div_scale_f32 v7, s[0:1], v18, v18, v5
	v_rcp_f32_e32 v9, v7
	s_nop 0
	v_fma_f32 v20, -v7, v9, 1.0
	v_fmac_f32_e32 v9, v20, v9
	v_div_scale_f32 v20, vcc, v5, v18, v5
	v_mul_f32_e32 v21, v20, v9
	v_fma_f32 v22, -v7, v21, v20
	v_fmac_f32_e32 v21, v22, v9
	v_fma_f32 v7, -v7, v21, v20
	v_div_fmas_f32 v7, v7, v9, v21
	v_div_fixup_f32 v18, v7, v18, v5
	v_pk_mul_f32 v[18:19], v[12:13], v[18:19]
	v_cvt_pk_bf16_f32 v12, v2, v3
	v_cvt_pk_bf16_f32 v13, v14, v15
	v_cvt_pk_bf16_f32 v14, v16, v17
	v_cvt_pk_bf16_f32 v15, v18, v19
	s_nop 0
	v_permlane32_swap_b32_e32 v12, v14
	v_permlane32_swap_b32_e32 v13, v15
	global_store_dwordx4 v[10:11], v[12:15], off offset:32
	global_load_dwordx4 v[12:15], v[0:1], off offset:64
	s_waitcnt vmcnt(0)
	v_mov_b32_e32 v5, v14
	s_nop 1
	v_permlane32_swap_b32_e32 v12, v5
	v_lshlrev_b32_e32 v9, 16, v12
	v_and_b32_e32 v12, 0xffff0000, v12
	v_mov_b32_e32 v7, v15
	v_mul_f32_e32 v14, 0xbfb8aa3b, v9
	v_mul_f32_e32 v15, 0xbfb8aa3b, v12
	v_exp_f32_e32 v14, v14
	v_exp_f32_e32 v15, v15
	v_permlane32_swap_b32_e32 v13, v7
	v_pk_mul_f32 v[2:3], v[48:49], v[6:7] op_sel_hi:[1,0]
	v_pk_add_f32 v[14:15], v[14:15], 1.0 op_sel_hi:[1,0]
	v_pk_fma_f32 v[2:3], v[4:5], v[32:33], v[2:3] op_sel_hi:[0,1,1]
	v_div_scale_f32 v16, s[0:1], v15, v15, v12
	v_rcp_f32_e32 v17, v16
	v_pk_fma_f32 v[2:3], v[64:65], v[8:9], v[2:3] op_sel_hi:[1,0,1]
	v_fma_f32 v18, -v16, v17, 1.0
	v_fmac_f32_e32 v17, v18, v17
	v_div_scale_f32 v18, vcc, v12, v15, v12
	v_mul_f32_e32 v19, v18, v17
	v_fma_f32 v20, -v16, v19, v18
	v_fmac_f32_e32 v19, v20, v17
	v_fma_f32 v16, -v16, v19, v18
	v_div_fmas_f32 v16, v16, v17, v19
	v_div_fixup_f32 v15, v16, v15, v12
	v_div_scale_f32 v12, s[0:1], v14, v14, v9
	v_rcp_f32_e32 v16, v12
	s_nop 0
	v_fma_f32 v17, -v12, v16, 1.0
	v_fmac_f32_e32 v16, v17, v16
	v_div_scale_f32 v17, vcc, v9, v14, v9
	v_mul_f32_e32 v18, v17, v16
	v_fma_f32 v19, -v12, v18, v17
	v_fmac_f32_e32 v18, v19, v16
	v_fma_f32 v12, -v12, v18, v17
	v_div_fmas_f32 v12, v12, v16, v18
	v_div_fixup_f32 v14, v12, v14, v9
	v_lshlrev_b32_e32 v9, 16, v13
	v_and_b32_e32 v16, 0xffff0000, v13
	v_pk_mul_f32 v[2:3], v[2:3], v[14:15]
	v_mul_f32_e32 v14, 0xbfb8aa3b, v9
	v_mul_f32_e32 v15, 0xbfb8aa3b, v16
	v_exp_f32_e32 v14, v14
	v_exp_f32_e32 v15, v15
	v_pk_mul_f32 v[12:13], v[50:51], v[6:7] op_sel_hi:[1,0]
	v_pk_add_f32 v[14:15], v[14:15], 1.0 op_sel_hi:[1,0]
	s_nop 0
	v_div_scale_f32 v17, s[0:1], v15, v15, v16
	v_rcp_f32_e32 v18, v17
	v_pk_fma_f32 v[12:13], v[4:5], v[34:35], v[12:13] op_sel_hi:[0,1,1]
	v_pk_fma_f32 v[12:13], v[66:67], v[8:9], v[12:13] op_sel_hi:[1,0,1]
	v_fma_f32 v19, -v17, v18, 1.0
	v_fmac_f32_e32 v18, v19, v18
	v_div_scale_f32 v19, vcc, v16, v15, v16
	v_mul_f32_e32 v20, v19, v18
	v_fma_f32 v21, -v17, v20, v19
	v_fmac_f32_e32 v20, v21, v18
	v_fma_f32 v17, -v17, v20, v19
	v_div_fmas_f32 v17, v17, v18, v20
	v_div_fixup_f32 v15, v17, v15, v16
	v_div_scale_f32 v16, s[0:1], v14, v14, v9
	v_rcp_f32_e32 v17, v16
	s_nop 0
	v_fma_f32 v18, -v16, v17, 1.0
	v_fmac_f32_e32 v17, v18, v17
	v_div_scale_f32 v18, vcc, v9, v14, v9
	v_mul_f32_e32 v19, v18, v17
	v_fma_f32 v20, -v16, v19, v18
	v_fmac_f32_e32 v19, v20, v17
	v_fma_f32 v16, -v16, v19, v18
	v_div_fmas_f32 v16, v16, v17, v19
	v_div_fixup_f32 v14, v16, v14, v9
	v_lshlrev_b32_e32 v9, 16, v5
	v_and_b32_e32 v5, 0xffff0000, v5
	v_mul_f32_e32 v16, 0xbfb8aa3b, v9
	v_mul_f32_e32 v17, 0xbfb8aa3b, v5
	v_exp_f32_e32 v16, v16
	v_exp_f32_e32 v17, v17
	v_pk_mul_f32 v[14:15], v[12:13], v[14:15]
	v_pk_mul_f32 v[12:13], v[52:53], v[6:7] op_sel_hi:[1,0]
	v_pk_add_f32 v[16:17], v[16:17], 1.0 op_sel_hi:[1,0]
	s_nop 0
	v_div_scale_f32 v18, s[0:1], v17, v17, v5
	v_rcp_f32_e32 v19, v18
	v_pk_fma_f32 v[12:13], v[4:5], v[36:37], v[12:13] op_sel_hi:[0,1,1]
	v_pk_fma_f32 v[12:13], v[68:69], v[8:9], v[12:13] op_sel_hi:[1,0,1]
	v_fma_f32 v20, -v18, v19, 1.0
	v_fmac_f32_e32 v19, v20, v19
	v_div_scale_f32 v20, vcc, v5, v17, v5
	v_mul_f32_e32 v21, v20, v19
	v_fma_f32 v22, -v18, v21, v20
	v_fmac_f32_e32 v21, v22, v19
	v_fma_f32 v18, -v18, v21, v20
	v_div_fmas_f32 v18, v18, v19, v21
	v_div_fixup_f32 v17, v18, v17, v5
	v_div_scale_f32 v5, s[0:1], v16, v16, v9
	v_rcp_f32_e32 v18, v5
	s_nop 0
	v_fma_f32 v19, -v5, v18, 1.0
	v_fmac_f32_e32 v18, v19, v18
	v_div_scale_f32 v19, vcc, v9, v16, v9
	v_mul_f32_e32 v20, v19, v18
	v_fma_f32 v21, -v5, v20, v19
	v_fmac_f32_e32 v20, v21, v18
	v_fma_f32 v5, -v5, v20, v19
	v_div_fmas_f32 v5, v5, v18, v20
	v_div_fixup_f32 v16, v5, v16, v9
	v_lshlrev_b32_e32 v5, 16, v7
	v_and_b32_e32 v7, 0xffff0000, v7
	v_pk_mul_f32 v[16:17], v[12:13], v[16:17]
	v_pk_mul_f32 v[12:13], v[54:55], v[6:7] op_sel_hi:[1,0]
	s_nop 0
	v_pk_fma_f32 v[12:13], v[4:5], v[38:39], v[12:13] op_sel_hi:[0,1,1]
	v_pk_fma_f32 v[12:13], v[70:71], v[8:9], v[12:13] op_sel_hi:[1,0,1]
	v_mul_f32_e32 v9, 0xbfb8aa3b, v5
	v_exp_f32_e32 v18, v9
	v_mul_f32_e32 v9, 0xbfb8aa3b, v7
	v_exp_f32_e32 v19, v9
	s_nop 0
	v_pk_add_f32 v[18:19], v[18:19], 1.0 op_sel_hi:[1,0]
	s_nop 0
	v_div_scale_f32 v9, s[0:1], v19, v19, v7
	v_rcp_f32_e32 v20, v9
	s_nop 0
	v_fma_f32 v21, -v9, v20, 1.0
	v_fmac_f32_e32 v20, v21, v20
	v_div_scale_f32 v21, vcc, v7, v19, v7
	v_mul_f32_e32 v22, v21, v20
	v_fma_f32 v23, -v9, v22, v21
	v_fmac_f32_e32 v22, v23, v20
	v_fma_f32 v9, -v9, v22, v21
	v_div_fmas_f32 v9, v9, v20, v22
	v_div_fixup_f32 v19, v9, v19, v7
	v_div_scale_f32 v7, s[0:1], v18, v18, v5
	v_rcp_f32_e32 v9, v7
	s_nop 0
	v_fma_f32 v20, -v7, v9, 1.0
	v_fmac_f32_e32 v9, v20, v9
	v_div_scale_f32 v20, vcc, v5, v18, v5
	v_mul_f32_e32 v21, v20, v9
	v_fma_f32 v22, -v7, v21, v20
	v_fmac_f32_e32 v21, v22, v9
	v_fma_f32 v7, -v7, v21, v20
	v_div_fmas_f32 v7, v7, v9, v21
	v_div_fixup_f32 v18, v7, v18, v5
	v_pk_mul_f32 v[18:19], v[12:13], v[18:19]
	v_cvt_pk_bf16_f32 v12, v2, v3
	global_load_dwordx4 v[0:3], v[0:1], off offset:96
	v_cvt_pk_bf16_f32 v13, v14, v15
	v_cvt_pk_bf16_f32 v14, v16, v17
	v_cvt_pk_bf16_f32 v15, v18, v19
	s_nop 0
	v_permlane32_swap_b32_e32 v12, v14
	v_permlane32_swap_b32_e32 v13, v15
	global_store_dwordx4 v[10:11], v[12:15], off offset:64
	s_waitcnt vmcnt(1)
	v_mov_b32_e32 v5, v2
	s_nop 1
	v_permlane32_swap_b32_e32 v0, v5
	v_lshlrev_b32_e32 v9, 16, v0
	v_and_b32_e32 v0, 0xffff0000, v0
	v_mul_f32_e32 v12, 0xbfb8aa3b, v9
	v_mul_f32_e32 v13, 0xbfb8aa3b, v0
	v_exp_f32_e32 v12, v12
	v_exp_f32_e32 v13, v13
	v_mov_b32_e32 v7, v3
	s_nop 1
	v_permlane32_swap_b32_e32 v1, v7
	v_pk_add_f32 v[12:13], v[12:13], 1.0 op_sel_hi:[1,0]
	v_pk_mul_f32 v[2:3], v[56:57], v[6:7] op_sel_hi:[1,0]
	v_div_scale_f32 v14, s[0:1], v13, v13, v0
	v_rcp_f32_e32 v15, v14
	v_pk_fma_f32 v[2:3], v[4:5], v[40:41], v[2:3] op_sel_hi:[0,1,1]
	v_pk_fma_f32 v[2:3], v[72:73], v[8:9], v[2:3] op_sel_hi:[1,0,1]
	v_fma_f32 v16, -v14, v15, 1.0
	v_fmac_f32_e32 v15, v16, v15
	v_div_scale_f32 v16, vcc, v0, v13, v0
	v_mul_f32_e32 v17, v16, v15
	v_fma_f32 v18, -v14, v17, v16
	v_fmac_f32_e32 v17, v18, v15
	v_fma_f32 v14, -v14, v17, v16
	v_div_fmas_f32 v14, v14, v15, v17
	v_div_fixup_f32 v13, v14, v13, v0
	v_div_scale_f32 v0, s[0:1], v12, v12, v9
	v_rcp_f32_e32 v14, v0
	s_nop 0
	v_fma_f32 v15, -v0, v14, 1.0
	v_fmac_f32_e32 v14, v15, v14
	v_div_scale_f32 v15, vcc, v9, v12, v9
	v_mul_f32_e32 v16, v15, v14
	v_fma_f32 v17, -v0, v16, v15
	v_fmac_f32_e32 v16, v17, v14
	v_fma_f32 v0, -v0, v16, v15
	v_div_fmas_f32 v0, v0, v14, v16
	v_div_fixup_f32 v12, v0, v12, v9
	v_lshlrev_b32_e32 v9, 16, v1
	v_and_b32_e32 v14, 0xffff0000, v1
	v_pk_mul_f32 v[2:3], v[2:3], v[12:13]
	v_mul_f32_e32 v12, 0xbfb8aa3b, v9
	v_mul_f32_e32 v13, 0xbfb8aa3b, v14
	v_exp_f32_e32 v12, v12
	v_exp_f32_e32 v13, v13
	v_pk_mul_f32 v[0:1], v[58:59], v[6:7] op_sel_hi:[1,0]
	v_cvt_pk_bf16_f32 v2, v2, v3
	v_pk_fma_f32 v[0:1], v[4:5], v[42:43], v[0:1] op_sel_hi:[0,1,1]
	v_pk_add_f32 v[12:13], v[12:13], 1.0 op_sel_hi:[1,0]
	v_pk_fma_f32 v[0:1], v[74:75], v[8:9], v[0:1] op_sel_hi:[1,0,1]
	v_div_scale_f32 v15, s[0:1], v13, v13, v14
	v_rcp_f32_e32 v16, v15
	s_nop 0
	v_fma_f32 v17, -v15, v16, 1.0
	v_fmac_f32_e32 v16, v17, v16
	v_div_scale_f32 v17, vcc, v14, v13, v14
	v_mul_f32_e32 v18, v17, v16
	v_fma_f32 v19, -v15, v18, v17
	v_fmac_f32_e32 v18, v19, v16
	v_fma_f32 v15, -v15, v18, v17
	v_div_fmas_f32 v15, v15, v16, v18
	v_div_fixup_f32 v13, v15, v13, v14
	v_div_scale_f32 v14, s[0:1], v12, v12, v9
	v_rcp_f32_e32 v15, v14
	s_nop 0
	v_fma_f32 v16, -v14, v15, 1.0
	v_fmac_f32_e32 v15, v16, v15
	v_div_scale_f32 v16, vcc, v9, v12, v9
	v_mul_f32_e32 v17, v16, v15
	v_fma_f32 v18, -v14, v17, v16
	v_fmac_f32_e32 v17, v18, v15
	v_fma_f32 v14, -v14, v17, v16
	v_div_fmas_f32 v14, v14, v15, v17
	v_div_fixup_f32 v12, v14, v12, v9
	v_lshlrev_b32_e32 v9, 16, v5
	v_and_b32_e32 v5, 0xffff0000, v5
	v_mul_f32_e32 v14, 0xbfb8aa3b, v9
	v_mul_f32_e32 v15, 0xbfb8aa3b, v5
	v_exp_f32_e32 v14, v14
	v_exp_f32_e32 v15, v15
	v_pk_mul_f32 v[0:1], v[0:1], v[12:13]
	v_pk_mul_f32 v[12:13], v[60:61], v[6:7] op_sel_hi:[1,0]
	v_cvt_pk_bf16_f32 v3, v0, v1
	v_pk_add_f32 v[14:15], v[14:15], 1.0 op_sel_hi:[1,0]
	v_pk_fma_f32 v[12:13], v[4:5], v[44:45], v[12:13] op_sel_hi:[0,1,1]
	v_div_scale_f32 v16, s[0:1], v15, v15, v5
	v_rcp_f32_e32 v17, v16
	v_pk_fma_f32 v[12:13], v[76:77], v[8:9], v[12:13] op_sel_hi:[1,0,1]
	v_fma_f32 v18, -v16, v17, 1.0
	v_fmac_f32_e32 v17, v18, v17
	v_div_scale_f32 v18, vcc, v5, v15, v5
	v_mul_f32_e32 v19, v18, v17
	v_fma_f32 v20, -v16, v19, v18
	v_fmac_f32_e32 v19, v20, v17
	v_fma_f32 v16, -v16, v19, v18
	v_div_fmas_f32 v16, v16, v17, v19
	v_div_fixup_f32 v15, v16, v15, v5
	v_div_scale_f32 v5, s[0:1], v14, v14, v9
	v_rcp_f32_e32 v16, v5
	s_nop 0
	v_fma_f32 v17, -v5, v16, 1.0
	v_fmac_f32_e32 v16, v17, v16
	v_div_scale_f32 v17, vcc, v9, v14, v9
	v_mul_f32_e32 v18, v17, v16
	v_fma_f32 v19, -v5, v18, v17
	v_fmac_f32_e32 v18, v19, v16
	v_fma_f32 v5, -v5, v18, v17
	v_div_fmas_f32 v5, v5, v16, v18
	v_div_fixup_f32 v14, v5, v14, v9
	v_pk_mul_f32 v[12:13], v[12:13], v[14:15]
	v_lshlrev_b32_e32 v9, 16, v7
	v_and_b32_e32 v14, 0xffff0000, v7
	v_pk_mul_f32 v[6:7], v[62:63], v[6:7] op_sel_hi:[1,0]
	s_nop 0
	v_pk_fma_f32 v[4:5], v[4:5], v[46:47], v[6:7] op_sel_hi:[0,1,1]
	v_mul_f32_e32 v6, 0xbfb8aa3b, v9
	v_mul_f32_e32 v7, 0xbfb8aa3b, v14
	v_exp_f32_e32 v6, v6
	v_exp_f32_e32 v7, v7
	v_pk_fma_f32 v[4:5], v[78:79], v[8:9], v[4:5] op_sel_hi:[1,0,1]
	v_pk_add_f32 v[6:7], v[6:7], 1.0 op_sel_hi:[1,0]
	s_nop 0
	v_div_scale_f32 v8, s[0:1], v7, v7, v14
	v_rcp_f32_e32 v15, v8
	s_nop 0
	v_fma_f32 v16, -v8, v15, 1.0
	v_fmac_f32_e32 v15, v16, v15
	v_div_scale_f32 v16, vcc, v14, v7, v14
	v_mul_f32_e32 v17, v16, v15
	v_fma_f32 v18, -v8, v17, v16
	v_fmac_f32_e32 v17, v18, v15
	v_fma_f32 v8, -v8, v17, v16
	v_div_fmas_f32 v8, v8, v15, v17
	v_div_fixup_f32 v7, v8, v7, v14
	v_div_scale_f32 v8, s[0:1], v6, v6, v9
	v_rcp_f32_e32 v14, v8
	s_nop 0
	v_fma_f32 v15, -v8, v14, 1.0
	v_fmac_f32_e32 v14, v15, v14
	v_div_scale_f32 v15, vcc, v9, v6, v9
	v_mul_f32_e32 v16, v15, v14
	v_fma_f32 v17, -v8, v16, v15
	v_fmac_f32_e32 v16, v17, v14
	v_fma_f32 v8, -v8, v16, v15
	v_div_fmas_f32 v8, v8, v14, v16
	v_div_fixup_f32 v6, v8, v6, v9
	v_pk_mul_f32 v[6:7], v[4:5], v[6:7]
	v_cvt_pk_bf16_f32 v4, v12, v13
	v_cvt_pk_bf16_f32 v5, v6, v7
	s_nop 0
	v_permlane32_swap_b32_e32 v2, v4
	v_permlane32_swap_b32_e32 v3, v5
	global_store_dwordx4 v[10:11], v[2:5], off offset:96

.LBB0_477:
	s_and_b64 vcc, exec, s[8:9]
	s_cbranch_vccz .LBB0_495
	v_readlane_b32 s30, v254, 50
	v_ashrrev_i32_e32 v4, 1, v198
	s_lshl_b32 s26, s30, 7
	v_and_b32_e32 v0, 0xffffffe0, v4
	s_lshl_b32 s0, s10, 9
	v_and_b32_e32 v5, 31, v198
	v_add_u32_e32 v0, s26, v0
	s_and_b32 s0, s0, 0x7ffff800
	v_or_b32_e32 v0, v0, v5
	s_add_i32 s16, s0, 0xffff8000
	s_mov_b64 s[14:15], 0x3e38aa3b
	v_readlane_b32 s0, v254, 3
	s_mov_b32 s17, s15
	v_ashrrev_i32_e32 v1, 31, v0
	v_readlane_b32 s1, v254, 4
	s_waitcnt vmcnt(0)
	v_lshl_add_u64 v[98:99], v[0:1], 0, s[16:17]
	s_movk_i32 s17, 0x1d00
	v_mov_b64_e32 v[0:1], s[0:1]
	v_mad_u64_u32 v[0:1], s[0:1], v98, s17, v[0:1]
	s_lshl_b32 s0, s10, 6
	s_and_b32 s0, s0, 0xc0
	v_bfe_u32 v6, v198, 5, 1
	v_mad_i32_i24 v1, v99, s17, v1
	s_lshl_b32 s14, s0, 1
	v_lshl_add_u64 v[0:1], v[0:1], 0, s[14:15]
	v_lshlrev_b32_e32 v192, 4, v6
	v_lshl_add_u64 v[96:97], v[0:1], 0, v[192:193]
	global_load_dwordx4 v[64:67], v[96:97], off
	global_load_dwordx4 v[68:71], v[96:97], off offset:32
	global_load_dwordx4 v[72:75], v[96:97], off offset:64
	global_load_dwordx4 v[76:79], v[96:97], off offset:96
	s_movk_i32 s0, 0x880
	v_cmp_gt_i32_e32 vcc, s0, v198
	s_waitcnt lgkmcnt(0)
	s_barrier
	s_and_saveexec_b64 s[18:19], vcc
	s_movk_i32 s15, 0x90
	s_movk_i32 s27, 0x7f
	s_movk_i32 s28, 0x101
	s_movk_i32 s29, 0x281
	s_cbranch_execz .LBB0_486
	v_and_b32_e32 v1, 3, v198
	v_and_b32_e32 v0, 15, v198
	v_cmp_eq_u32_e32 vcc, 0, v1
	v_max_i32_e32 v1, 0x780, v198
	v_cmp_eq_u32_e64 s[0:1], 0, v0
	v_sub_u32_e32 v1, v1, v198
	v_add_u32_e32 v2, 0xff, v1
	v_cndmask_b32_e64 v0, 0, 1, s[0:1]
	s_movk_i32 s0, 0xff
	v_cmp_lt_u32_e64 s[0:1], s0, v2
	s_mov_b64 s[8:9], -1
	v_mov_b32_e32 v1, v198
	s_and_saveexec_b64 s[22:23], s[0:1]
	s_cbranch_execz .LBB0_483
	v_lshrrev_b32_e32 v1, 8, v2
	v_add_u32_e32 v7, 1, v1
	v_and_b32_e32 v8, 0x1fffffe, v7
	v_add_u32_e32 v199, 0x100, v198
	v_mov_b32_e32 v2, 0xe800
	v_mov_b32_e32 v1, v0
	v_lshl_add_u32 v9, v198, 2, v2
	s_mov_b64 s[24:25], 0
	v_mov_b32_e32 v10, v8
	v_mov_b64_e32 v[2:3], v[198:199]

.LBB0_486:
	s_or_b64 exec, exec, s[18:19]
	v_lshlrev_b32_e32 v108, 3, v6
	s_cmp_gt_i32 s30, -1
	s_mov_b64 s[0:1], -1
	s_cbranch_scc0 .LBB0_712
	s_mul_i32 s1, s16, 0x1d00
	v_readlane_b32 s8, v254, 3
	v_add_u32_e32 v8, 0x100, v198
	s_mul_hi_u32 s0, s16, 0x1d00
	v_readlane_b32 s9, v254, 4
	s_add_u32 s1, s8, s1
	v_ashrrev_i32_e32 v0, 31, v198
	v_ashrrev_i32_e32 v9, 31, v8
	s_addc_u32 s8, s9, s0
	v_lshrrev_b32_e32 v0, 29, v0
	v_lshrrev_b32_e32 v9, 29, v9
	s_add_u32 s0, s1, s14
	v_add_u32_e32 v0, v198, v0
	v_add_u32_e32 v9, v8, v9
	s_addc_u32 s1, s8, 0
	s_or_b32 s10, s26, 64
	v_and_b32_e32 v1, -8, v0
	v_ashrrev_i32_e32 v35, 3, v9
	v_and_b32_e32 v9, -8, v9
	v_sub_u32_e32 v7, v198, v1
	v_mov_b64_e32 v[20:21], s[0:1]
	v_sub_u32_e32 v30, v8, v9
	v_add_u32_e32 v8, s10, v35
	v_ashrrev_i32_e32 v10, 2, v198
	v_ashrrev_i32_e32 v34, 3, v0
	v_lshlrev_b32_e32 v2, 3, v7
	v_mad_i64_i32 v[16:17], s[8:9], v8, s17, v[20:21]
	v_lshlrev_b32_e32 v8, 3, v30
	v_lshlrev_b32_e32 v36, 1, v5
	v_and_b32_e32 v26, -8, v10
	v_add_u32_e32 v0, s10, v34
	v_ashrrev_i32_e32 v3, 31, v2
	v_ashrrev_i32_e32 v9, 31, v8
	v_or_b32_e32 v12, s10, v36
	v_ashrrev_i32_e32 v27, 31, v26
	v_mad_i64_i32 v[0:1], s[8:9], v0, s17, v[20:21]
	v_lshlrev_b64 v[22:23], 1, v[2:3]
	v_lshlrev_b64 v[24:25], 1, v[8:9]
	v_mad_u64_u32 v[8:9], s[8:9], v12, s17, v[20:21]
	v_lshlrev_b64 v[28:29], 1, v[26:27]
	v_or_b32_e32 v12, 1, v12
	v_lshl_add_u64 v[0:1], v[0:1], 0, v[22:23]
	v_lshl_add_u64 v[8:9], v[8:9], 0, v[28:29]
	v_mad_u64_u32 v[12:13], s[8:9], v12, s17, v[20:21]
	global_load_dwordx4 v[0:3], v[0:1], off offset:512
	v_lshl_add_u64 v[12:13], v[12:13], 0, v[28:29]
	global_load_dwordx4 v[8:11], v[8:9], off offset:1024
	v_lshl_add_u64 v[16:17], v[16:17], 0, v[24:25]
	global_load_dwordx4 v[12:15], v[12:13], off offset:1024
	v_or_b32_e32 v32, s26, v36
	global_load_dwordx4 v[16:19], v[16:17], off offset:512
	v_mul_lo_u32 v113, v26, 34
	v_add_u32_e32 v26, s26, v34
	v_or_b32_e32 v37, 1, v32
	v_lshlrev_b32_e32 v115, 4, v7
	v_add_u32_e32 v7, s26, v35
	v_mad_i64_i32 v[26:27], s[8:9], v26, s17, v[20:21]
	v_lshlrev_b32_e32 v117, 4, v30
	v_mad_i64_i32 v[30:31], s[8:9], v7, s17, v[20:21]
	v_mad_u64_u32 v[32:33], s[8:9], v32, s17, v[20:21]
	v_mad_u64_u32 v[20:21], s[8:9], v37, s17, v[20:21]
	v_lshl_add_u64 v[26:27], v[26:27], 0, v[22:23]
	v_lshl_add_u64 v[32:33], v[32:33], 0, v[28:29]
	v_lshl_add_u64 v[20:21], v[20:21], 0, v[28:29]
	v_lshl_add_u64 v[30:31], v[30:31], 0, v[24:25]
	s_waitcnt lgkmcnt(0)
	s_barrier
	global_load_dwordx4 v[80:83], v[26:27], off offset:512
	global_load_dwordx4 v[84:87], v[30:31], off offset:512
	global_load_dwordx4 v[88:91], v[32:33], off offset:1024
	global_load_dwordx4 v[92:95], v[20:21], off offset:1024
	v_lshlrev_b32_e32 v112, 2, v5
	v_mul_lo_u32 v114, v34, s15
	v_lshl_add_u32 v38, v113, 2, v112
	v_mul_lo_u32 v116, v35, s15
	v_add_u32_e32 v39, v114, v115
	s_mov_b32 s8, 0xffff0000
	v_add_u32_e32 v7, v116, v117
	v_lshl_add_u64 v[100:101], s[0:1], 0, v[28:29]
	v_lshl_add_u64 v[102:103], s[0:1], 0, v[22:23]
	v_lshl_add_u64 v[104:105], s[0:1], 0, v[24:25]
	s_sub_i32 s0, s26, 64
	v_add_u32_e32 v123, s0, v36
	v_add_u32_e32 v124, s0, v35
	v_add_u32_e32 v125, s0, v34
	s_movk_i32 s0, 0xff80
	s_lshl_b32 s10, s30, 1
	v_mov_b32_e32 v122, 0
	v_mul_u32_u24_e32 v118, 0x90, v5
	v_mul_u32_u24_e32 v120, 0x88, v5
	v_mov_b32_e32 v33, 0xf149f2ca
	v_mov_b32_e32 v126, s10
	v_mov_b32_e32 v5, v122
	v_mov_b32_e32 v21, v122
	v_mov_b32_e32 v22, v122
	v_mov_b32_e32 v23, v122
	v_mov_b32_e32 v24, v122
	v_mov_b32_e32 v25, v122
	v_mov_b32_e32 v26, v122
	v_mov_b32_e32 v27, v122
	v_mov_b32_e32 v28, v122
	v_mov_b32_e32 v29, v122
	v_mov_b32_e32 v30, v122
	v_mov_b32_e32 v31, v122
	s_waitcnt vmcnt(7)
	ds_write_b128 v39, v[0:3]
	v_add_u32_e32 v2, 0x3400, v38
	s_waitcnt vmcnt(6)
	v_and_b32_e32 v20, 0xffff, v8
	v_lshrrev_b32_e32 v8, 16, v8
	s_waitcnt vmcnt(5)
	v_lshl_or_b32 v0, v12, 16, v20
	v_and_or_b32 v1, v12, s8, v8
	s_waitcnt vmcnt(4)
	ds_write_b128 v7, v[16:19]
	ds_write2_b32 v2, v0, v1 offset1:34
	v_and_b32_e32 v0, 0xffff, v9
	v_lshrrev_b32_e32 v1, 16, v9
	v_lshl_or_b32 v0, v13, 16, v0
	v_and_or_b32 v1, v13, s8, v1
	ds_write2_b32 v2, v0, v1 offset0:68 offset1:102
	v_and_b32_e32 v0, 0xffff, v10
	v_lshrrev_b32_e32 v1, 16, v10
	v_lshl_or_b32 v0, v14, 16, v0
	v_and_or_b32 v1, v14, s8, v1
	ds_write2_b32 v2, v0, v1 offset0:136 offset1:170
	v_and_b32_e32 v0, 0xffff, v11
	v_lshrrev_b32_e32 v1, 16, v11
	v_lshl_or_b32 v0, v15, 16, v0
	v_and_or_b32 v1, v15, s8, v1
	ds_write2_b32 v2, v0, v1 offset0:204 offset1:238
	v_mbcnt_lo_u32_b32 v1, -1, 0
	v_mbcnt_hi_u32_b32 v110, -1, v1
	v_and_b32_e32 v1, 64, v110
	v_xor_b32_e32 v109, 32, v110
	v_add_u32_e32 v111, 64, v1
	v_cmp_lt_i32_e32 vcc, v109, v111
	v_lshlrev_b32_e32 v0, 2, v6
	s_mov_b32 s8, 0
	v_cndmask_b32_e32 v1, v110, v109, vcc
	v_lshlrev_b32_e32 v119, 2, v1
	v_lshlrev_b32_e32 v1, 2, v4
	v_and_or_b32 v1, v1, s0, v112
	v_sub_u32_e32 v1, v1, v192
	v_add_u32_e32 v127, 0xe814, v1
	v_lshlrev_b32_e32 v121, 1, v0
	v_mov_b32_e32 v0, 0
	v_mov_b32_e32 v1, v122
	v_mov_b32_e32 v2, v122
	v_mov_b32_e32 v3, v122
	v_mov_b32_e32 v4, v122
	v_mov_b32_e32 v6, v122
	v_mov_b32_e32 v7, v122
	v_mov_b32_e32 v8, v122
	v_mov_b32_e32 v9, v122
	v_mov_b32_e32 v10, v122
	v_mov_b32_e32 v11, v122
	v_mov_b32_e32 v12, v122
	v_mov_b32_e32 v13, v122
	v_mov_b32_e32 v14, v122
	v_mov_b32_e32 v15, v122
	v_mov_b32_e32 v16, 0
	v_mov_b32_e32 v17, v122
	v_mov_b32_e32 v18, v122
	v_mov_b32_e32 v19, v122
	v_mov_b32_e32 v20, v122
	s_waitcnt lgkmcnt(0)
	s_barrier
.LBB0_488:
	s_mul_i32 s0, s8, 0x9000
	v_lshlrev_b32_e32 v32, 1, v108
	v_add3_u32 v106, s0, v118, v32
	v_mov_b32_e32 v128, v33
	ds_read_b128 v[32:35], v106 offset:4608
	ds_read_b128 v[36:39], v106
	ds_read_b128 v[130:133], v106 offset:32
	ds_read_b128 v[134:137], v106 offset:4640
	s_waitcnt lgkmcnt(2)
	v_mfma_f32_32x32x16_bf16 v[48:63], v[36:39], v[64:67], 0
	v_cmp_gt_i32_e32 vcc, 0, v126
	s_and_b64 vcc, exec, vcc
	v_mfma_f32_32x32x16_bf16 v[32:47], v[32:35], v[64:67], 0
	s_waitcnt lgkmcnt(1)
	v_mfma_f32_32x32x16_bf16 v[48:63], v[130:133], v[68:71], v[48:63]
	s_waitcnt lgkmcnt(0)
	v_mfma_f32_32x32x16_bf16 v[32:47], v[134:137], v[68:71], v[32:47]
	ds_read_b128 v[130:133], v106 offset:64
	ds_read_b128 v[134:137], v106 offset:4672
	s_waitcnt lgkmcnt(1)
	v_mfma_f32_32x32x16_bf16 v[48:63], v[130:133], v[72:75], v[48:63]
	s_waitcnt lgkmcnt(0)
	v_mfma_f32_32x32x16_bf16 v[32:47], v[134:137], v[72:75], v[32:47]
	ds_read_b128 v[130:133], v106 offset:96
	ds_read_b128 v[134:137], v106 offset:4704
	ds_read2_b32 v[106:107], v127 offset0:58 offset1:59
	ds_read2_b32 v[138:139], v127 offset0:2 offset1:3
	ds_read2_b32 v[140:141], v127 offset1:1
	s_waitcnt lgkmcnt(4)
	v_mfma_f32_32x32x16_bf16 v[48:63], v[130:133], v[76:79], v[48:63]
	ds_read2_b32 v[130:131], v127 offset0:18 offset1:19
	ds_read2_b32 v[132:133], v127 offset0:16 offset1:17
	s_waitcnt lgkmcnt(5)
	v_mfma_f32_32x32x16_bf16 v[32:47], v[134:137], v[76:79], v[32:47]
	s_nop 0
	s_nop 6
	s_waitcnt lgkmcnt(4)
	v_fmamk_f32 v107, v48, 0x3e38aa3b, v107
	v_fmac_f32_e32 v106, 0x3e38aa3b, v49
	ds_read2_b32 v[48:49], v127 offset0:56 offset1:57
	v_max3_f32 v129, v128, v107, v106
	ds_read2_b32 v[134:135], v127 offset0:10 offset1:11
	ds_read2_b32 v[136:137], v127 offset0:8 offset1:9
	s_waitcnt lgkmcnt(2)
	v_fmamk_f32 v49, v50, 0x3e38aa3b, v49
	v_fmac_f32_e32 v48, 0x3e38aa3b, v51
	ds_read2_b32 v[50:51], v127 offset0:50 offset1:51
	v_max3_f32 v129, v129, v49, v48
	s_waitcnt lgkmcnt(2)
	v_fmac_f32_e32 v134, 0x3e38aa3b, v41
	s_waitcnt lgkmcnt(1)
	v_fmac_f32_e32 v136, 0x3e38aa3b, v43
	v_fmac_f32_e32 v138, 0x3e38aa3b, v45
	s_waitcnt lgkmcnt(0)
	v_fmamk_f32 v51, v52, 0x3e38aa3b, v51
	v_fmac_f32_e32 v50, 0x3e38aa3b, v53
	ds_read2_b32 v[52:53], v127 offset0:48 offset1:49
	v_max3_f32 v129, v129, v51, v50
	v_fmac_f32_e32 v130, 0x3e38aa3b, v37
	v_fmac_f32_e32 v132, 0x3e38aa3b, v39
	v_fmac_f32_e32 v140, 0x3e38aa3b, v47
	s_waitcnt lgkmcnt(0)
	v_fmamk_f32 v53, v54, 0x3e38aa3b, v53
	v_fmac_f32_e32 v52, 0x3e38aa3b, v55
	ds_read2_b32 v[54:55], v127 offset0:42 offset1:43
	v_max3_f32 v129, v129, v53, v52
	s_waitcnt lgkmcnt(0)
	v_fmamk_f32 v55, v56, 0x3e38aa3b, v55
	v_fmac_f32_e32 v54, 0x3e38aa3b, v57
	ds_read2_b32 v[56:57], v127 offset0:40 offset1:41
	v_max3_f32 v129, v129, v55, v54
	s_waitcnt lgkmcnt(0)
	v_fmamk_f32 v57, v58, 0x3e38aa3b, v57
	v_fmac_f32_e32 v56, 0x3e38aa3b, v59
	ds_read2_b32 v[58:59], v127 offset0:34 offset1:35
	v_max3_f32 v129, v129, v57, v56
	s_waitcnt lgkmcnt(0)
	v_fmamk_f32 v59, v60, 0x3e38aa3b, v59
	v_fmac_f32_e32 v58, 0x3e38aa3b, v61
	ds_read2_b32 v[60:61], v127 offset0:32 offset1:33
	v_max3_f32 v129, v129, v59, v58
	s_waitcnt lgkmcnt(0)
	v_fmamk_f32 v61, v62, 0x3e38aa3b, v61
	v_fmac_f32_e32 v60, 0x3e38aa3b, v63
	ds_read2_b32 v[62:63], v127 offset0:26 offset1:27
	v_max3_f32 v129, v129, v61, v60
	s_waitcnt lgkmcnt(0)
	v_fmamk_f32 v63, v32, 0x3e38aa3b, v63
	v_fmac_f32_e32 v62, 0x3e38aa3b, v33
	ds_read2_b32 v[32:33], v127 offset0:24 offset1:25
	v_max3_f32 v129, v129, v63, v62
	s_waitcnt lgkmcnt(0)
	v_fmamk_f32 v142, v34, 0x3e38aa3b, v33
	v_fmac_f32_e32 v32, 0x3e38aa3b, v35
	v_max3_f32 v33, v129, v142, v32
	v_fmamk_f32 v129, v36, 0x3e38aa3b, v131
	v_max3_f32 v33, v33, v129, v130
	v_fmamk_f32 v131, v38, 0x3e38aa3b, v133
	v_max3_f32 v33, v33, v131, v132
	v_fmamk_f32 v133, v40, 0x3e38aa3b, v135
	v_max3_f32 v33, v33, v133, v134
	v_fmamk_f32 v135, v42, 0x3e38aa3b, v137
	v_max3_f32 v33, v33, v135, v136
	v_fmamk_f32 v137, v44, 0x3e38aa3b, v139
	v_max3_f32 v33, v33, v137, v138
	v_fmamk_f32 v139, v46, 0x3e38aa3b, v141
	v_max3_f32 v33, v33, v139, v140
	ds_bpermute_b32 v34, v119, v33
	s_waitcnt lgkmcnt(0)
	v_max_f32_e32 v34, v34, v34
	v_max_f32_e32 v33, v33, v34
	v_sub_f32_e32 v32, v32, v33
	v_sub_f32_e32 v40, v53, v33
	v_exp_f32_e32 v53, v32
	v_sub_f32_e32 v32, v129, v33
	v_sub_f32_e32 v43, v54, v33
	v_exp_f32_e32 v54, v32
	v_sub_f32_e32 v32, v130, v33
	v_sub_f32_e32 v42, v55, v33
	v_exp_f32_e32 v55, v32
	v_sub_f32_e32 v32, v131, v33
	v_sub_f32_e32 v45, v56, v33
	v_exp_f32_e32 v56, v32
	v_sub_f32_e32 v32, v132, v33
	v_sub_f32_e32 v44, v57, v33
	v_exp_f32_e32 v57, v32
	v_sub_f32_e32 v32, v133, v33
	v_sub_f32_e32 v47, v58, v33
	v_exp_f32_e32 v58, v32
	v_sub_f32_e32 v32, v134, v33
	v_sub_f32_e32 v46, v59, v33
	v_exp_f32_e32 v59, v32
	v_sub_f32_e32 v32, v135, v33
	v_sub_f32_e32 v36, v49, v33
	v_sub_f32_e32 v49, v60, v33
	v_exp_f32_e32 v60, v32
	v_sub_f32_e32 v32, v136, v33
	v_sub_f32_e32 v37, v48, v33
	v_sub_f32_e32 v48, v61, v33
	v_exp_f32_e32 v61, v32
	v_sub_f32_e32 v32, v137, v33
	v_sub_f32_e32 v38, v51, v33
	v_sub_f32_e32 v51, v62, v33
	v_exp_f32_e32 v62, v32
	v_sub_f32_e32 v32, v138, v33
	v_sub_f32_e32 v39, v50, v33
	v_sub_f32_e32 v50, v63, v33
	v_exp_f32_e32 v63, v32
	v_sub_f32_e32 v32, v139, v33
	v_sub_f32_e32 v35, v106, v33
	v_exp_f32_e32 v106, v32
	v_sub_f32_e32 v32, v140, v33
	v_add3_u32 v140, s0, v120, v121
	v_add_u32_e32 v144, 0x3000, v140
	v_add_u32_e32 v145, 0x4000, v140
	v_sub_f32_e32 v41, v52, v33
	v_sub_f32_e32 v52, v142, v33
	ds_read2_b64 v[132:135], v144 offset0:128 offset1:130
	ds_read2_b64 v[136:139], v144 offset0:132 offset1:134
	ds_read2_b64 v[140:143], v145 offset0:160 offset1:162
	v_sub_f32_e32 v128, v128, v33
	v_sub_f32_e32 v34, v107, v33
	v_exp_f32_e32 v34, v34
	v_exp_f32_e32 v35, v35
	v_exp_f32_e32 v36, v36
	v_exp_f32_e32 v37, v37
	v_exp_f32_e32 v38, v38
	v_exp_f32_e32 v39, v39
	v_exp_f32_e32 v40, v40
	v_exp_f32_e32 v41, v41
	v_exp_f32_e32 v107, v32
	v_exp_f32_e32 v32, v128
	v_cvt_pk_bf16_f32 v128, v34, v35
	v_cvt_pk_bf16_f32 v129, v36, v37
	v_cvt_pk_bf16_f32 v130, v38, v39
	v_pk_mul_f32 v[30:31], v[30:31], v[32:33] op_sel_hi:[1,0]
	v_pk_mul_f32 v[28:29], v[28:29], v[32:33] op_sel_hi:[1,0]
	v_pk_mul_f32 v[26:27], v[26:27], v[32:33] op_sel_hi:[1,0]
	v_pk_mul_f32 v[24:25], v[24:25], v[32:33] op_sel_hi:[1,0]
	v_pk_mul_f32 v[22:23], v[22:23], v[32:33] op_sel_hi:[1,0]
	v_pk_mul_f32 v[20:21], v[20:21], v[32:33] op_sel_hi:[1,0]
	v_pk_mul_f32 v[18:19], v[18:19], v[32:33] op_sel_hi:[1,0]
	v_pk_mul_f32 v[16:17], v[16:17], v[32:33] op_sel_hi:[1,0]
	v_cvt_pk_bf16_f32 v131, v40, v41
	v_pk_mul_f32 v[14:15], v[14:15], v[32:33] op_sel_hi:[1,0]
	v_pk_mul_f32 v[12:13], v[12:13], v[32:33] op_sel_hi:[1,0]
	v_pk_mul_f32 v[10:11], v[10:11], v[32:33] op_sel_hi:[1,0]
	v_pk_mul_f32 v[8:9], v[8:9], v[32:33] op_sel_hi:[1,0]
	v_pk_mul_f32 v[6:7], v[6:7], v[32:33] op_sel_hi:[1,0]
	v_pk_mul_f32 v[4:5], v[4:5], v[32:33] op_sel_hi:[1,0]
	v_pk_mul_f32 v[2:3], v[2:3], v[32:33] op_sel_hi:[1,0]
	v_pk_mul_f32 v[0:1], v[0:1], v[32:33] op_sel_hi:[1,0]
	s_waitcnt lgkmcnt(2)
	v_mfma_f32_32x32x16_bf16 v[16:31], v[132:135], v[128:131], v[16:31]
	ds_read2_b64 v[132:135], v145 offset0:164 offset1:166
	v_exp_f32_e32 v42, v42
	v_exp_f32_e32 v43, v43
	v_exp_f32_e32 v44, v44
	v_exp_f32_e32 v45, v45
	v_exp_f32_e32 v46, v46
	v_exp_f32_e32 v47, v47
	s_waitcnt lgkmcnt(1)
	v_mfma_f32_32x32x16_bf16 v[0:15], v[140:143], v[128:131], v[0:15]
	v_exp_f32_e32 v48, v48
	v_exp_f32_e32 v49, v49
	v_cvt_pk_bf16_f32 v128, v42, v43
	v_cvt_pk_bf16_f32 v129, v44, v45
	v_cvt_pk_bf16_f32 v130, v46, v47
	v_cvt_pk_bf16_f32 v131, v48, v49
	v_exp_f32_e32 v50, v50
	v_exp_f32_e32 v51, v51
	v_mfma_f32_32x32x16_bf16 v[16:31], v[136:139], v[128:131], v[16:31]
	v_exp_f32_e32 v52, v52
	s_waitcnt lgkmcnt(0)
	v_mfma_f32_32x32x16_bf16 v[0:15], v[132:135], v[128:131], v[0:15]
	ds_read2_b64 v[132:135], v144 offset0:136 offset1:138
	ds_read2_b64 v[136:139], v145 offset0:168 offset1:170
	v_cvt_pk_bf16_f32 v128, v50, v51
	v_cvt_pk_bf16_f32 v129, v52, v53
	v_cvt_pk_bf16_f32 v130, v54, v55
	v_cvt_pk_bf16_f32 v131, v56, v57
	s_nop 0
	s_nop 0
	s_waitcnt lgkmcnt(1)
	v_mfma_f32_32x32x16_bf16 v[16:31], v[132:135], v[128:131], v[16:31]
	s_waitcnt lgkmcnt(0)
	v_mfma_f32_32x32x16_bf16 v[0:15], v[136:139], v[128:131], v[0:15]
	ds_read2_b64 v[132:135], v144 offset0:140 offset1:142
	ds_read2_b64 v[136:139], v145 offset0:172 offset1:174
	v_cvt_pk_bf16_f32 v128, v58, v59
	v_cvt_pk_bf16_f32 v129, v60, v61
	v_cvt_pk_bf16_f32 v130, v62, v63
	v_cvt_pk_bf16_f32 v131, v106, v107
	s_nop 0
	s_nop 0
	s_waitcnt lgkmcnt(1)
	v_mfma_f32_32x32x16_bf16 v[16:31], v[132:135], v[128:131], v[16:31]
	s_waitcnt lgkmcnt(0)
	v_mfma_f32_32x32x16_bf16 v[0:15], v[136:139], v[128:131], v[0:15]
	s_cbranch_vccnz .LBB0_492
	s_xor_b32 s8, s8, 1
	s_mul_i32 s0, s8, 0x9000
	v_add3_u32 v129, s0, v114, v115
	v_lshlrev_b32_e32 v128, 2, v113
	s_waitcnt vmcnt(0)
	ds_write_b128 v129, v[80:83]
	v_add3_u32 v129, s0, v116, v117
	ds_write_b128 v129, v[84:87]
	v_add3_u32 v128, s0, v128, v112
	v_lshlrev_b32_e32 v129, 16, v92
	s_mov_b32 s1, 0xffff
	v_lshrrev_b32_e32 v130, 16, v88
	s_mov_b32 s0, 0xffff0000
	v_and_or_b32 v129, v88, s1, v129
	v_and_or_b32 v130, v92, s0, v130
	v_add_u32_e32 v128, 0x3400, v128
	ds_write2_b32 v128, v129, v130 offset1:34
	v_lshlrev_b32_e32 v129, 16, v93
	v_lshrrev_b32_e32 v130, 16, v89
	v_and_or_b32 v129, v89, s1, v129
	v_and_or_b32 v130, v93, s0, v130
	ds_write2_b32 v128, v129, v130 offset0:68 offset1:102
	v_lshlrev_b32_e32 v129, 16, v94
	v_lshrrev_b32_e32 v130, 16, v90
	v_and_or_b32 v129, v90, s1, v129
	v_and_or_b32 v130, v94, s0, v130
	ds_write2_b32 v128, v129, v130 offset0:136 offset1:170
	v_lshlrev_b32_e32 v129, 16, v95
	v_lshrrev_b32_e32 v130, 16, v91
	v_subrev_co_u32_e32 v126, vcc, 1, v126
	v_and_or_b32 v129, v91, s1, v129
	v_and_or_b32 v130, v95, s0, v130
	s_and_b64 vcc, exec, vcc
	ds_write2_b32 v128, v129, v130 offset0:204 offset1:238
	s_cbranch_vccnz .LBB0_491
	v_add_u32_e32 v90, 1, v123
	v_mad_i64_i32 v[80:81], s[0:1], v125, s17, v[102:103]
	v_mad_i64_i32 v[84:85], s[0:1], v124, s17, v[104:105]
	v_mad_u64_u32 v[88:89], s[0:1], v123, s17, v[100:101]
	v_mad_u64_u32 v[92:93], s[0:1], v90, s17, v[100:101]
	global_load_dwordx4 v[80:83], v[80:81], off offset:512
	s_nop 0
	global_load_dwordx4 v[84:87], v[84:85], off offset:512
	s_nop 0
	global_load_dwordx4 v[88:91], v[88:89], off offset:1024
	s_nop 0
	global_load_dwordx4 v[92:95], v[92:93], off offset:1024

.LBB0_496:
	s_and_b64 vcc, exec, s[8:9]
	s_cbranch_vccz .LBB0_715
	v_readlane_b32 s0, v253, 57
	v_readlane_b32 s9, v254, 45
	s_add_i32 s0, s0, s9
	s_ashr_i32 s10, s0, 5
	s_sub_i32 s8, 15, s10
	v_ashrrev_i32_e32 v0, 1, v198
	s_lshl_b32 s11, s8, 7
	v_and_b32_e32 v11, 0xffffffe0, v0
	v_and_b32_e32 v10, 31, v198
	v_add_u32_e32 v0, s11, v11
	s_mov_b64 s[12:13], 0x3e38aa3b
	v_or_b32_e32 v0, v0, v10
	s_lshl_b32 s0, s9, 9
	s_mov_b32 s1, s13
	v_readlane_b32 s12, v254, 3
	s_and_b32 s0, s0, 0x3800
	v_ashrrev_i32_e32 v1, 31, v0
	v_readlane_b32 s13, v254, 4
	s_waitcnt vmcnt(0)
	v_lshl_add_u64 v[130:131], v[0:1], 0, s[0:1]
	s_movk_i32 s76, 0x1d00
	v_mov_b64_e32 v[2:3], s[12:13]
	s_lshl_b32 s1, s9, 6
	v_lshrrev_b32_e32 v1, 2, v198
	v_mad_u64_u32 v[132:133], s[12:13], v130, s76, v[2:3]
	s_and_b32 s1, s1, 0xc0
	v_and_b32_e32 v1, 8, v1
	v_mov_b32_e32 v63, 0
	v_mad_i32_i24 v133, v131, s76, v133
	v_readfirstlane_b32 s83, v0
	s_cmp_gt_i32 s10, 15
	v_lshlrev_b32_e32 v128, 1, v1
	v_mov_b32_e32 v62, v63
	v_mov_b32_e32 v61, v63
	v_mov_b32_e32 v60, v63
	v_mov_b32_e32 v59, v63
	v_mov_b32_e32 v58, v63
	v_mov_b32_e32 v57, v63
	v_mov_b32_e32 v56, v63
	v_mov_b32_e32 v55, v63
	v_mov_b32_e32 v54, v63
	v_mov_b32_e32 v53, v63
	v_mov_b32_e32 v52, v63
	v_mov_b32_e32 v51, v63
	v_mov_b32_e32 v50, v63
	v_mov_b32_e32 v49, v63
	v_mov_b32_e32 v48, v63
	v_mov_b32_e32 v47, v63
	v_mov_b32_e32 v46, v63
	v_mov_b32_e32 v45, v63
	v_mov_b32_e32 v44, v63
	v_mov_b32_e32 v43, v63
	v_mov_b32_e32 v42, v63
	v_mov_b32_e32 v41, v63
	v_mov_b32_e32 v40, v63
	v_mov_b32_e32 v39, v63
	v_mov_b32_e32 v38, v63
	v_mov_b32_e32 v37, v63
	v_mov_b32_e32 v36, v63
	v_mov_b32_e32 v35, v63
	v_mov_b32_e32 v34, v63
	v_mov_b32_e32 v33, v63
	v_mov_b32_e32 v32, v63
	s_cbranch_scc1 .LBB0_513
	s_mov_b64 s[12:13], 0x3e38aa3b
	s_lshl_b32 s14, s1, 1
	s_mov_b32 s15, s13
	v_lshl_add_u64 v[0:1], v[132:133], 0, s[14:15]
	v_mov_b32_e32 v129, v193
	v_writelane_b32 v254, s1, 46
	v_lshl_add_u64 v[0:1], v[0:1], 0, v[128:129]
	s_mov_b64 s[12:13], 0x1400
	v_lshl_add_u64 v[2:3], v[0:1], 0, s[12:13]
	s_lshl_b32 s12, s8, 1
	s_mulk_i32 s0, 0x1d00
	v_readlane_b32 s8, v254, 3
	v_readlane_b32 s9, v254, 4
	s_add_u32 s0, s8, s0
	s_addc_u32 s1, s9, 0
	v_add_co_u32_e32 v0, vcc, 0x1000, v0
	s_add_u32 s8, s0, s14
	s_nop 0
	v_addc_co_u32_e32 v1, vcc, 0, v1, vcc
	s_addc_u32 s9, s1, 0
	global_load_dwordx4 v[96:99], v[0:1], off offset:1024
	global_load_dwordx4 v[100:103], v[2:3], off offset:32
	global_load_dwordx4 v[104:107], v[2:3], off offset:64
	global_load_dwordx4 v[108:111], v[2:3], off offset:96
	s_add_u32 s0, s8, 0x1600
	v_ashrrev_i32_e32 v0, 31, v198
	s_addc_u32 s1, s9, 0
	v_lshrrev_b32_e32 v0, 29, v0
	s_add_u32 s8, s8, 0x1800
	v_add_u32_e32 v0, v198, v0
	s_addc_u32 s9, s9, 0
	s_or_b32 s13, s11, 64
	v_ashrrev_i32_e32 v129, 3, v0
	v_and_b32_e32 v0, -8, v0
	v_sub_u32_e32 v33, v198, v0
	v_add_u32_e32 v0, s13, v129
	v_mov_b64_e32 v[6:7], s[0:1]
	v_mad_i64_i32 v[2:3], s[14:15], v0, s76, v[6:7]
	v_lshlrev_b32_e32 v0, 3, v33
	v_ashrrev_i32_e32 v1, 31, v0
	v_lshlrev_b64 v[0:1], 1, v[0:1]
	v_lshl_add_u64 v[2:3], v[2:3], 0, v[0:1]
	global_load_dwordx4 v[14:17], v[2:3], off
	v_add_u32_e32 v2, 0x100, v198
	v_ashrrev_i32_e32 v3, 31, v2
	v_lshrrev_b32_e32 v3, 29, v3
	v_add_u32_e32 v3, v2, v3
	v_ashrrev_i32_e32 v195, 3, v3
	v_and_b32_e32 v3, -8, v3
	v_sub_u32_e32 v34, v2, v3
	v_add_u32_e32 v2, s13, v195
	v_mad_i64_i32 v[4:5], s[14:15], v2, s76, v[6:7]
	v_lshlrev_b32_e32 v2, 3, v34
	v_ashrrev_i32_e32 v3, 31, v2
	v_lshlrev_b64 v[2:3], 1, v[2:3]
	v_lshl_add_u64 v[4:5], v[4:5], 0, v[2:3]
	global_load_dwordx4 v[18:21], v[4:5], off
	v_ashrrev_i32_e32 v4, 2, v198
	v_lshlrev_b32_e32 v199, 1, v10
	v_and_b32_e32 v30, -8, v4
	v_or_b32_e32 v26, s13, v199
	v_mov_b64_e32 v[8:9], s[8:9]
	v_ashrrev_i32_e32 v31, 31, v30
	v_mad_u64_u32 v[22:23], s[14:15], v26, s76, v[8:9]
	v_lshlrev_b64 v[4:5], 1, v[30:31]
	v_or_b32_e32 v26, 1, v26
	v_lshl_add_u64 v[22:23], v[22:23], 0, v[4:5]
	v_mad_u64_u32 v[26:27], s[14:15], v26, s76, v[8:9]
	global_load_dwordx4 v[22:25], v[22:23], off
	v_lshl_add_u64 v[26:27], v[26:27], 0, v[4:5]
	global_load_dwordx4 v[26:29], v[26:27], off
	s_movk_i32 s13, 0x90
	v_mul_lo_u32 v203, v129, s13
	v_lshlrev_b32_e32 v204, 4, v33
	v_mul_lo_u32 v202, v30, 34
	v_add_u32_e32 v30, v203, v204
	v_mul_lo_u32 v205, v195, s13
	v_lshlrev_b32_e32 v206, 4, v34
	s_waitcnt lgkmcnt(0)
	s_barrier
	v_lshlrev_b32_e32 v207, 2, v10
	s_mov_b32 s13, 0xffff0000
	v_bfe_u32 v32, v198, 5, 1
	v_lshlrev_b32_e32 v210, 2, v32
	v_lshl_add_u64 v[136:137], s[0:1], 0, v[0:1]
	v_ashrrev_i32_e32 v13, 6, v198
	v_and_b32_e32 v12, 63, v198
	v_lshl_add_u64 v[134:135], s[8:9], 0, v[4:5]
	v_lshl_add_u64 v[138:139], s[0:1], 0, v[2:3]
	s_lshl_b32 s0, s10, 7
	v_mov_b32_e32 v141, 0
	s_mov_b32 s3, 0
	v_mul_u32_u24_e32 v209, 0x90, v10
	v_cmp_gt_u32_e64 s[8:9], 32, v12
	v_mul_u32_u24_e32 v211, 0x88, v10
	v_cmp_eq_u32_e64 s[18:19], 0, v12
	s_sub_i32 s82, 0x7ff, s0
	v_mov_b32_e32 v213, s12
	s_mov_b32 s2, 0
	v_mov_b32_e32 v33, v141
	v_mov_b32_e32 v34, v141
	v_mov_b32_e32 v35, v141
	v_mov_b32_e32 v36, v141
	v_mov_b32_e32 v37, v141
	v_mov_b32_e32 v38, v141
	v_mov_b32_e32 v39, v141
	v_mov_b32_e32 v40, v141
	v_mov_b32_e32 v41, v141
	v_mov_b32_e32 v42, v141
	v_mov_b32_e32 v43, v141
	v_mov_b32_e32 v44, v141
	v_mov_b32_e32 v45, v141
	v_mov_b32_e32 v46, v141
	v_mov_b32_e32 v47, v141
	v_mov_b32_e32 v48, v141
	v_mov_b32_e32 v49, v141
	v_mov_b32_e32 v50, v141
	v_mov_b32_e32 v51, v141
	s_waitcnt vmcnt(3)
	ds_write_b128 v30, v[14:17]
	v_add_u32_e32 v14, v205, v206
	v_mov_b32_e32 v52, v141
	v_mov_b32_e32 v53, v141
	v_mov_b32_e32 v54, v141
	v_mov_b32_e32 v55, v141
	v_mov_b32_e32 v56, v141
	v_mov_b32_e32 v57, v141
	v_mov_b32_e32 v58, v141
	v_mov_b32_e32 v59, v141
	v_mov_b32_e32 v60, v141
	v_mov_b32_e32 v61, v141
	v_mov_b32_e32 v62, v141
	v_mov_b32_e32 v63, v141
	s_waitcnt vmcnt(2)
	ds_write_b128 v14, v[18:21]
	v_lshl_add_u32 v14, v202, 2, v207
	v_add_u32_e32 v14, 0x3400, v14
	s_waitcnt vmcnt(1)
	v_and_b32_e32 v15, 0xffff, v22
	v_lshrrev_b32_e32 v16, 16, v22
	s_waitcnt vmcnt(0)
	v_lshl_or_b32 v15, v26, 16, v15
	v_and_or_b32 v16, v26, s13, v16
	ds_write2_b32 v14, v15, v16 offset1:34
	v_and_b32_e32 v15, 0xffff, v23
	v_lshrrev_b32_e32 v16, 16, v23
	v_lshl_or_b32 v15, v27, 16, v15
	v_and_or_b32 v16, v27, s13, v16
	ds_write2_b32 v14, v15, v16 offset0:68 offset1:102
	v_and_b32_e32 v15, 0xffff, v24
	v_lshrrev_b32_e32 v16, 16, v24
	v_lshl_or_b32 v15, v28, 16, v15
	v_and_or_b32 v16, v28, s13, v16
	ds_write2_b32 v14, v15, v16 offset0:136 offset1:170
	v_and_b32_e32 v15, 0xffff, v25
	v_lshrrev_b32_e32 v16, 16, v25
	v_lshl_or_b32 v15, v29, 16, v15
	v_and_or_b32 v16, v29, s13, v16
	ds_write2_b32 v14, v15, v16 offset0:204 offset1:238
	v_add_u32_e32 v14, s11, v129
	v_mad_i64_i32 v[14:15], s[14:15], v14, s76, v[6:7]
	v_lshl_add_u64 v[14:15], v[14:15], 0, v[0:1]
	global_load_dwordx4 v[112:115], v[14:15], off
	v_add_u32_e32 v14, s11, v195
	v_mad_i64_i32 v[6:7], s[14:15], v14, s76, v[6:7]
	v_lshl_add_u64 v[6:7], v[6:7], 0, v[2:3]
	v_or_b32_e32 v14, s11, v199
	global_load_dwordx4 v[116:119], v[6:7], off
	v_mad_u64_u32 v[6:7], s[14:15], v14, s76, v[8:9]
	v_lshl_add_u64 v[6:7], v[6:7], 0, v[4:5]
	global_load_dwordx4 v[120:123], v[6:7], off
	v_or_b32_e32 v6, 1, v14
	v_mad_u64_u32 v[6:7], s[14:15], v6, s76, v[8:9]
	v_lshl_add_u64 v[6:7], v[6:7], 0, v[4:5]
	global_load_dwordx4 v[124:127], v[6:7], off
	v_add_u32_e32 v0, v11, v10
	s_add_i32 s14, s83, 31
	v_mov_b32_e32 v6, 0x11490
	v_lshlrev_b32_e32 v4, 3, v32
	v_sub_u32_e32 v0, v0, v210
	v_lshl_add_u32 v208, v13, 2, v6
	v_subrev_u32_e32 v214, 64, v0
	s_mov_b64 s[10:11], 0
	v_lshlrev_b32_e32 v212, 1, v4
	v_mov_b32_e32 v32, v141
	v_writelane_b32 v254, s14, 48
	s_waitcnt lgkmcnt(0)
	s_barrier
	s_branch .LBB0_500

.LBB0_500:
	s_sub_i32 s0, s82, 63
	s_cmp_ge_i32 s0, s14
	s_cbranch_scc1 .LBB0_506
	s_mul_i32 s12, s2, 0x9000
	v_add3_u32 v12, s12, v209, v212
	ds_read_b128 v[0:3], v12
	ds_read_b128 v[4:7], v12 offset:32
	s_cmp_ge_i32 s82, s83
	s_mov_b64 s[0:1], -1
	s_waitcnt lgkmcnt(1)
	v_mfma_f32_32x32x16_bf16 v[64:79], v[0:3], v[96:99], 0
	ds_read_b128 v[0:3], v12 offset:4608
	ds_read_b128 v[8:11], v12 offset:4640
	s_waitcnt lgkmcnt(2)
	v_mfma_f32_32x32x16_bf16 v[64:79], v[4:7], v[100:103], v[64:79]
	s_waitcnt lgkmcnt(1)
	v_mfma_f32_32x32x16_bf16 v[80:95], v[0:3], v[96:99], 0
	ds_read_b128 v[0:3], v12 offset:64
	ds_read_b128 v[4:7], v12 offset:96
	s_waitcnt lgkmcnt(1)
	v_mfma_f32_32x32x16_bf16 v[64:79], v[0:3], v[104:107], v[64:79]
	ds_read_b128 v[0:3], v12 offset:4672
	v_mfma_f32_32x32x16_bf16 v[80:95], v[8:11], v[100:103], v[80:95]
	s_waitcnt lgkmcnt(1)
	v_mfma_f32_32x32x16_bf16 v[64:79], v[4:7], v[108:111], v[64:79]
	ds_read_b128 v[4:7], v12 offset:4704
	s_waitcnt lgkmcnt(1)
	v_mfma_f32_32x32x16_bf16 v[80:95], v[0:3], v[104:107], v[80:95]
	s_nop 8
	v_mul_f32_e32 v142, 0x3e38aa3b, v67
	v_mul_f32_e32 v148, 0x3e38aa3b, v68
	v_mul_f32_e32 v146, 0x3e38aa3b, v69
	v_mul_f32_e32 v144, 0x3e38aa3b, v71
	v_mul_f32_e32 v72, 0x3e38aa3b, v72
	v_mul_f32_e32 v152, 0x3e38aa3b, v73
	v_mul_f32_e32 v150, 0x3e38aa3b, v75
	s_waitcnt lgkmcnt(0)
	v_mfma_f32_32x32x16_bf16 v[80:95], v[4:7], v[108:111], v[80:95]
	v_mul_f32_e32 v154, 0x3e38aa3b, v79
	s_nop 10
	v_mul_f32_e32 v156, 0x3e38aa3b, v80
	v_mul_f32_e32 v158, 0x3e38aa3b, v81
	v_mul_f32_e32 v84, 0x3e38aa3b, v84
	v_mul_f32_e32 v160, 0x3e38aa3b, v85
	v_mul_f32_e32 v164, 0x3e38aa3b, v90
	v_mul_f32_e32 v162, 0x3e38aa3b, v91
	v_mul_f32_e32 v166, 0x3e38aa3b, v92
	v_mul_f32_e32 v192, 0x3e38aa3b, v94
	s_cbranch_scc0 .LBB0_503
	v_mul_f32_e32 v0, 0x3e38aa3b, v64
	v_exp_f32_e64 v1, -|v0|
	v_mul_f32_e32 v2, 0x3e38aa3b, v65
	v_exp_f32_e64 v3, -|v2|
	v_mul_f32_e32 v170, 0x3e38aa3b, v66
	v_add_f32_e32 v1, 1.0, v1
	v_log_f32_e32 v1, v1
	v_min_f32_e64 v4, -v0, 0
	v_add_f32_e32 v3, 1.0, v3
	v_log_f32_e32 v3, v3
	v_sub_f32_e32 v1, v4, v1
	v_exp_f32_e64 v4, -|v170|
	v_cmp_lt_i32_e32 vcc, 0, v214
	v_cmp_lt_i32_e64 s[0:1], 1, v214
	v_writelane_b32 v254, s12, 50
	v_cndmask_b32_e32 v168, 0, v1, vcc
	v_min_f32_e64 v1, -v2, 0
	v_sub_f32_e32 v1, v1, v3
	v_add_f32_e32 v3, 1.0, v4
	v_log_f32_e32 v3, v3
	v_exp_f32_e64 v4, -|v142|
	v_cndmask_b32_e64 v172, 0, v1, s[0:1]
	v_min_f32_e64 v1, -v170, 0
	v_sub_f32_e32 v1, v1, v3
	v_add_f32_e32 v3, 1.0, v4
	v_log_f32_e32 v3, v3
	v_exp_f32_e64 v4, -|v148|
	v_cmp_lt_i32_e64 s[12:13], 2, v214
	v_cmp_lt_i32_e64 s[14:15], 3, v214
	v_mul_f32_e32 v5, 0x3e38aa3b, v70
	v_cndmask_b32_e64 v174, 0, v1, s[12:13]
	v_min_f32_e64 v1, -v142, 0
	v_sub_f32_e32 v1, v1, v3
	v_add_f32_e32 v3, 1.0, v4
	v_log_f32_e32 v3, v3
	v_exp_f32_e64 v4, -|v146|
	v_cndmask_b32_e64 v176, 0, v1, s[14:15]
	v_min_f32_e64 v1, -v148, 0
	v_sub_f32_e32 v1, v1, v3
	v_add_f32_e32 v3, 1.0, v4
	v_log_f32_e32 v3, v3
	v_exp_f32_e64 v6, -|v5|
	v_cmp_lt_i32_e64 s[16:17], 8, v214
	v_exp_f32_e64 v7, -|v144|
	v_writelane_b32 v254, s3, 51
	v_cndmask_b32_e64 v4, 0, v1, s[16:17]
	v_min_f32_e64 v1, -v146, 0
	v_sub_f32_e32 v1, v1, v3
	v_add_f32_e32 v3, 1.0, v6
	v_log_f32_e32 v3, v3
	s_mov_b32 s33, s2
	s_mov_b64 s[2:3], s[18:19]
	v_cmp_lt_i32_e64 s[18:19], 9, v214
	v_cmp_lt_i32_e64 s[22:23], 10, v214
	v_exp_f32_e64 v8, -|v152|
	v_cndmask_b32_e64 v6, 0, v1, s[18:19]
	v_min_f32_e64 v1, -v5, 0
	v_sub_f32_e32 v1, v1, v3
	v_add_f32_e32 v3, 1.0, v7
	v_log_f32_e32 v3, v3
	v_exp_f32_e64 v7, -|v72|
	v_cndmask_b32_e64 v5, 0, v1, s[22:23]
	v_min_f32_e64 v1, -v144, 0
	v_sub_f32_e32 v1, v1, v3
	v_add_f32_e32 v3, 1.0, v7
	v_log_f32_e32 v3, v3
	v_cmp_lt_i32_e64 s[24:25], 11, v214
	v_mul_f32_e32 v178, 0x3e38aa3b, v74
	v_exp_f32_e64 v9, -|v178|
	v_cndmask_b32_e64 v7, 0, v1, s[24:25]
	v_min_f32_e64 v1, -v72, 0
	v_sub_f32_e32 v1, v1, v3
	v_add_f32_e32 v3, 1.0, v8
	v_log_f32_e32 v3, v3
	v_cmp_lt_i32_e64 s[26:27], 16, v214
	v_cmp_lt_i32_e64 s[28:29], 17, v214
	v_mul_f32_e32 v12, 0x3e38aa3b, v76
	v_cndmask_b32_e64 v8, 0, v1, s[26:27]
	v_min_f32_e64 v1, -v152, 0
	v_sub_f32_e32 v1, v1, v3
	v_add_f32_e32 v3, 1.0, v9
	v_log_f32_e32 v3, v3
	v_exp_f32_e64 v9, -|v150|
	v_cndmask_b32_e64 v10, 0, v1, s[28:29]
	v_min_f32_e64 v1, -v178, 0
	v_sub_f32_e32 v1, v1, v3
	v_add_f32_e32 v3, 1.0, v9
	v_log_f32_e32 v3, v3
	v_exp_f32_e64 v11, -|v12|
	v_cmp_lt_i32_e64 s[30:31], 18, v214
	v_mul_f32_e32 v14, 0x3e38aa3b, v77
	v_exp_f32_e64 v13, -|v14|
	v_cndmask_b32_e64 v9, 0, v1, s[30:31]
	v_min_f32_e64 v1, -v150, 0
	v_sub_f32_e32 v1, v1, v3
	v_add_f32_e32 v3, 1.0, v11
	v_log_f32_e32 v3, v3
	v_cmp_lt_i32_e64 s[34:35], 19, v214
	v_mul_f32_e32 v184, 0x3e38aa3b, v78
	v_cmp_lt_i32_e64 s[36:37], 24, v214
	v_cndmask_b32_e64 v11, 0, v1, s[34:35]
	v_min_f32_e64 v1, -v12, 0
	v_sub_f32_e32 v1, v1, v3
	v_add_f32_e32 v3, 1.0, v13
	v_log_f32_e32 v3, v3
	v_exp_f32_e64 v13, -|v184|
	v_cndmask_b32_e64 v180, 0, v1, s[36:37]
	v_min_f32_e64 v1, -v14, 0
	v_sub_f32_e32 v1, v1, v3
	v_add_f32_e32 v3, 1.0, v13
	v_log_f32_e32 v3, v3
	v_exp_f32_e64 v13, -|v154|
	v_cmp_lt_i32_e64 s[38:39], 25, v214
	v_cmp_lt_i32_e64 s[40:41], 26, v214
	v_cmp_lt_i32_e64 s[42:43], 27, v214
	v_cndmask_b32_e64 v182, 0, v1, s[38:39]
	v_min_f32_e64 v1, -v184, 0
	v_sub_f32_e32 v1, v1, v3
	v_add_f32_e32 v3, 1.0, v13
	v_log_f32_e32 v3, v3
	v_exp_f32_e64 v13, -|v156|
	v_cndmask_b32_e64 v186, 0, v1, s[40:41]
	v_min_f32_e64 v1, -v154, 0
	v_sub_f32_e32 v1, v1, v3
	v_add_f32_e32 v3, 1.0, v13
	v_log_f32_e32 v3, v3
	v_exp_f32_e64 v13, -|v158|
	v_cndmask_b32_e64 v188, 0, v1, s[42:43]
	v_min_f32_e64 v1, -v156, 0
	v_sub_f32_e32 v1, v1, v3
	v_add_f32_e32 v3, 1.0, v13
	v_mul_f32_e32 v13, 0x3e38aa3b, v82
	v_log_f32_e32 v3, v3
	v_exp_f32_e64 v15, -|v13|
	v_cmp_lt_i32_e64 s[44:45], 32, v214
	v_cmp_lt_i32_e64 s[46:47], 33, v214
	v_cmp_lt_i32_e64 s[48:49], 34, v214
	v_cndmask_b32_e64 v16, 0, v1, s[44:45]
	v_min_f32_e64 v1, -v158, 0
	v_sub_f32_e32 v1, v1, v3
	v_add_f32_e32 v3, 1.0, v15
	v_mul_f32_e32 v15, 0x3e38aa3b, v83
	v_log_f32_e32 v3, v3
	v_exp_f32_e64 v17, -|v15|
	v_cndmask_b32_e64 v18, 0, v1, s[46:47]
	v_min_f32_e64 v1, -v13, 0
	v_sub_f32_e32 v1, v1, v3
	v_add_f32_e32 v3, 1.0, v17
	v_log_f32_e32 v3, v3
	v_exp_f32_e64 v13, -|v84|
	v_cndmask_b32_e64 v17, 0, v1, s[48:49]
	v_min_f32_e64 v1, -v15, 0
	v_sub_f32_e32 v1, v1, v3
	v_add_f32_e32 v3, 1.0, v13
	v_log_f32_e32 v3, v3
	v_exp_f32_e64 v13, -|v160|
	v_cmp_lt_i32_e64 s[50:51], 35, v214
	v_mul_f32_e32 v200, 0x3e38aa3b, v86
	v_cmp_lt_i32_e64 s[52:53], 40, v214
	v_cndmask_b32_e64 v19, 0, v1, s[50:51]
	v_min_f32_e64 v1, -v84, 0
	v_sub_f32_e32 v1, v1, v3
	v_add_f32_e32 v3, 1.0, v13
	v_log_f32_e32 v3, v3
	v_exp_f32_e64 v13, -|v200|
	v_cndmask_b32_e64 v20, 0, v1, s[52:53]
	v_min_f32_e64 v1, -v160, 0
	v_sub_f32_e32 v1, v1, v3
	v_add_f32_e32 v3, 1.0, v13
	v_mul_f32_e32 v216, 0x3e38aa3b, v87
	v_log_f32_e32 v3, v3
	v_exp_f32_e64 v13, -|v216|
	v_cmp_lt_i32_e64 s[54:55], 41, v214
	v_cmp_lt_i32_e64 s[56:57], 42, v214
	v_mul_f32_e32 v24, 0x3e38aa3b, v89
	v_cndmask_b32_e64 v22, 0, v1, s[54:55]
	v_min_f32_e64 v1, -v200, 0
	v_sub_f32_e32 v1, v1, v3
	v_add_f32_e32 v3, 1.0, v13
	v_mul_f32_e32 v13, 0x3e38aa3b, v88
	v_log_f32_e32 v3, v3
	v_exp_f32_e64 v15, -|v13|
	v_cndmask_b32_e64 v21, 0, v1, s[56:57]
	v_min_f32_e64 v1, -v216, 0
	v_sub_f32_e32 v1, v1, v3
	v_add_f32_e32 v3, 1.0, v15
	v_log_f32_e32 v3, v3
	v_exp_f32_e64 v15, -|v24|
	v_cmp_lt_i32_e64 s[58:59], 43, v214
	v_cmp_lt_i32_e64 s[60:61], 48, v214
	v_cmp_lt_i32_e64 s[62:63], 49, v214
	v_cndmask_b32_e64 v23, 0, v1, s[58:59]
	v_min_f32_e64 v1, -v13, 0
	v_sub_f32_e32 v1, v1, v3
	v_add_f32_e32 v3, 1.0, v15
	v_log_f32_e32 v3, v3
	v_exp_f32_e64 v13, -|v164|
	v_cndmask_b32_e64 v26, 0, v1, s[60:61]
	v_min_f32_e64 v1, -v24, 0
	v_sub_f32_e32 v1, v1, v3
	v_add_f32_e32 v3, 1.0, v13
	v_log_f32_e32 v3, v3
	v_exp_f32_e64 v13, -|v162|
	v_cndmask_b32_e64 v28, 0, v1, s[62:63]
	v_min_f32_e64 v1, -v164, 0
	v_sub_f32_e32 v1, v1, v3
	v_add_f32_e32 v3, 1.0, v13
	v_log_f32_e32 v3, v3
	v_exp_f32_e64 v13, -|v166|
	v_cmp_lt_i32_e64 s[64:65], 50, v214
	v_min_f32_e64 v25, -v166, 0
	v_and_b32_e32 v27, 64, v225
	v_cndmask_b32_e64 v29, 0, v1, s[64:65]
	v_min_f32_e64 v1, -v162, 0
	v_sub_f32_e32 v1, v1, v3
	v_add_f32_e32 v3, 1.0, v13
	v_mul_f32_e32 v13, 0x3e38aa3b, v93
	v_exp_f32_e64 v15, -|v13|
	v_log_f32_e32 v3, v3
	v_min_f32_e64 v13, -v13, 0
	v_pk_add_f32 v[30:31], v[4:5], v[6:7]
	v_add_f32_e32 v15, 1.0, v15
	v_sub_f32_e32 v3, v25, v3
	v_log_f32_e32 v15, v15
	v_exp_f32_e64 v25, -|v192|
	v_cmp_lt_i32_e64 s[68:69], 56, v214
	v_cmp_lt_i32_e64 s[70:71], 57, v214
	v_sub_f32_e32 v13, v13, v15
	v_add_f32_e32 v15, 1.0, v25
	v_log_f32_e32 v15, v15
	v_min_f32_e64 v25, -v192, 0
	v_add_u32_e32 v27, 64, v27
	v_pk_add_f32 v[190:191], v[30:31], v[30:31] op_sel:[0,1] op_sel_hi:[1,0]
	v_sub_f32_e32 v15, v25, v15
	v_xor_b32_e32 v25, 32, v225
	v_pk_add_f32 v[30:31], v[8:9], v[10:11]
	v_cmp_lt_i32_e64 s[66:67], 51, v214
	v_cndmask_b32_e64 v3, 0, v3, s[68:69]
	v_cndmask_b32_e64 v13, 0, v13, s[70:71]
	v_cmp_lt_i32_e64 s[76:77], v25, v27
	v_add_f32_e32 v69, v30, v31
	v_pk_add_f32 v[30:31], v[16:17], v[18:19]
	v_cndmask_b32_e64 v1, 0, v1, s[66:67]
	v_cndmask_b32_e64 v25, v225, v25, s[76:77]
	v_pk_add_f32 v[218:219], v[30:31], v[30:31] op_sel:[0,1] op_sel_hi:[1,0]
	v_pk_add_f32 v[30:31], v[20:21], v[22:23]
	v_add_f32_e32 v27, v3, v13
	v_fmac_f32_e32 v3, 0x3e38aa3b, v92
	v_mov_b32_e32 v92, v29
	v_mov_b32_e32 v140, v95
	s_mov_b64 s[76:77], 0x3e38aa3b
	v_lshlrev_b32_e32 v67, 2, v25
	v_add_f32_e32 v73, v30, v31
	v_add_f32_e32 v30, v29, v1
	v_add_f32_e32 v25, 0, v1
	v_fmac_f32_e32 v1, 0x3e38aa3b, v91
	v_fmac_f32_e32 v92, 0x3e38aa3b, v90
	v_pk_mul_f32 v[90:91], v[140:141], s[76:77]
	v_pk_add_f32 v[220:221], v[24:25], v[28:29]
	v_exp_f32_e64 v31, -|v90|
	v_cmp_lt_i32_e64 s[72:73], 58, v214
	v_pk_add_f32 v[228:229], v[140:141], s[76:77]
	v_cmp_lt_i32_e64 s[76:77], 59, v214
	v_add_f32_e32 v29, 1.0, v31
	v_log_f32_e32 v29, v29
	v_min_f32_e64 v31, -v90, 0
	v_cndmask_b32_e64 v15, 0, v15, s[72:73]
	v_fmamk_f32 v81, v94, 0x3e38aa3b, v15
	v_sub_f32_e32 v29, v31, v29
	v_cndmask_b32_e64 v228, 0, v29, s[76:77]
	v_add_f32_e32 v29, v15, v228
	v_mov_b32_e32 v94, v26
	v_pk_add_f32 v[26:27], v[26:27], v[28:29]
	ds_bpermute_b32 v31, v67, v27
	v_add_f32_e32 v140, 0, v228
	v_mov_b32_e32 v91, v229
	v_add_f32_e32 v15, v15, v140
	v_fmamk_f32 v85, v93, 0x3e38aa3b, v13
	s_waitcnt lgkmcnt(0)
	v_cndmask_b32_e64 v229, 0, v31, s[8:9]
	v_add_f32_e32 v24, v28, v221
	v_add_f32_e32 v13, v13, v15
	v_pk_add_f32 v[26:27], v[26:27], v[30:31]
	v_pk_add_f32 v[28:29], v[90:91], v[228:229]
	ds_bpermute_b32 v230, v67, v26
	v_add_f32_e32 v13, v13, v29
	v_add_f32_e32 v28, v28, v29
	v_add_f32_e32 v3, v3, v13
	v_exp_f32_e32 v28, v28
	v_add_f32_e32 v15, v15, v29
	v_exp_f32_e32 v3, v3
	v_add_f32_e32 v15, v85, v15
	v_exp_f32_e32 v15, v15
	v_mov_b32_e32 v231, v193
	s_waitcnt lgkmcnt(0)
	v_pk_add_f32 v[90:91], v[26:27], v[230:231]
	ds_bpermute_b32 v79, v67, v73
	v_cndmask_b32_e64 v31, 0, v28, s[76:77]
	v_cndmask_b32_e64 v28, 0, v3, s[68:69]
	v_add_f32_e32 v3, v141, v91
	v_cndmask_b32_e64 v13, 0, v230, s[8:9]
	v_add_f32_e32 v3, v13, v3
	v_fmac_f32_e32 v94, 0x3e38aa3b, v88
	v_add_f32_e32 v30, v140, v29
	v_cndmask_b32_e64 v29, 0, v15, s[70:71]
	v_add_f32_e32 v1, v1, v3
	v_add_f32_e32 v13, v25, v3
	v_add_f32_e32 v15, v221, v3
	v_add_f32_e32 v3, v24, v3
	v_add_f32_e32 v3, v94, v3
	v_exp_f32_e32 v3, v3
	v_pk_add_f32 v[90:91], v[90:91], v[90:91] op_sel:[0,1] op_sel_hi:[1,0]
	v_add_f32_e32 v13, v92, v13
	v_add_f32_e32 v15, v220, v15
	v_add_f32_e32 v217, v141, v90
	s_waitcnt lgkmcnt(0)
	v_cndmask_b32_e64 v221, 0, v79, s[8:9]
	v_mov_b32_e32 v220, v23
	v_exp_f32_e32 v13, v13
	v_pk_add_f32 v[216:217], v[216:217], v[220:221]
	v_mov_b32_e32 v201, v193
	v_mov_b32_e32 v220, v21
	v_mov_b32_e32 v221, v23
	v_exp_f32_e32 v1, v1
	v_pk_add_f32 v[200:201], v[200:201], v[220:221]
	v_exp_f32_e32 v15, v15
	v_cndmask_b32_e64 v24, 0, v3, s[60:61]
	v_add_f32_e32 v3, v201, v217
	v_mov_b32_e32 v161, v201
	v_mov_b32_e32 v23, v21
	v_add_f32_e32 v3, v200, v3
	v_pk_add_f32 v[200:201], v[160:161], v[22:23]
	v_cndmask_b32_e64 v26, 0, v13, s[64:65]
	v_add_f32_e32 v13, v201, v217
	v_mov_b32_e32 v85, v201
	v_mov_b32_e32 v21, v22
	ds_bpermute_b32 v183, v67, v218
	v_cndmask_b32_e64 v27, 0, v1, s[66:67]
	v_add_f32_e32 v1, v216, v217
	v_add_f32_e32 v13, v200, v13
	v_pk_add_f32 v[20:21], v[84:85], v[20:21]
	v_cndmask_b32_e64 v25, 0, v15, s[62:63]
	v_exp_f32_e32 v1, v1
	v_exp_f32_e32 v13, v13
	v_add_f32_e32 v15, v21, v217
	v_add_f32_e32 v15, v20, v15
	v_exp_f32_e32 v3, v3
	v_exp_f32_e32 v15, v15
	v_add_f32_e32 v187, v73, v79
	v_mov_b32_e32 v189, v90
	v_add_f32_e32 v30, v81, v30
	v_fmac_f32_e32 v16, 0x3e38aa3b, v80
	v_pk_add_f32 v[80:81], v[186:187], v[188:189]
	v_mov_b32_e32 v181, v218
	v_cndmask_b32_e64 v23, 0, v1, s[58:59]
	v_cndmask_b32_e64 v21, 0, v13, s[54:55]
	s_waitcnt lgkmcnt(0)
	v_cndmask_b32_e64 v1, 0, v183, s[8:9]
	v_add_f32_e32 v159, 0, v19
	v_mov_b32_e32 v200, v18
	v_mov_b32_e32 v201, v17
	v_pk_add_f32 v[90:91], v[180:181], v[182:183]
	v_add_f32_e32 v13, v141, v81
	v_pk_add_f32 v[200:201], v[158:159], v[200:201]
	v_pk_add_f32 v[90:91], v[90:91], v[80:81]
	v_add_f32_e32 v1, v1, v13
	v_cndmask_b32_e64 v22, 0, v3, s[56:57]
	v_cndmask_b32_e64 v20, 0, v15, s[52:53]
	v_fmac_f32_e32 v19, 0x3e38aa3b, v83
	v_fmac_f32_e32 v17, 0x3e38aa3b, v82
	v_add_f32_e32 v3, v18, v201
	ds_bpermute_b32 v73, v67, v90
	v_add_f32_e32 v15, v159, v1
	v_add_f32_e32 v13, v19, v1
	v_add_f32_e32 v15, v17, v15
	v_add_f32_e32 v17, v201, v1
	v_add_f32_e32 v1, v3, v1
	v_add_f32_e32 v1, v16, v1
	v_exp_f32_e32 v1, v1
	v_exp_f32_e32 v15, v15
	v_add_f32_e32 v155, v141, v91
	s_waitcnt lgkmcnt(0)
	v_cndmask_b32_e64 v189, 0, v73, s[8:9]
	v_exp_f32_e32 v13, v13
	v_pk_add_f32 v[80:81], v[154:155], v[188:189]
	v_mov_b32_e32 v185, v193
	v_mov_b32_e32 v187, v188
	v_cndmask_b32_e64 v16, 0, v1, s[44:45]
	v_add_f32_e32 v1, v80, v81
	v_pk_add_f32 v[184:185], v[184:185], v[186:187]
	v_cndmask_b32_e64 v18, 0, v15, s[48:49]
	v_exp_f32_e32 v1, v1
	v_mov_b32_e32 v15, v185
	v_mov_b32_e32 v183, v186
	ds_bpermute_b32 v75, v67, v69
	v_pk_add_f32 v[14:15], v[14:15], v[182:183]
	v_cndmask_b32_e64 v19, 0, v13, s[50:51]
	v_add_f32_e32 v3, v185, v81
	v_add_f32_e32 v13, v15, v81
	v_add_f32_e32 v3, v184, v3
	v_add_f32_e32 v13, v14, v13
	v_exp_f32_e32 v3, v3
	v_exp_f32_e32 v79, v13
	v_mov_b32_e32 v13, v15
	v_mov_b32_e32 v181, v182
	v_cndmask_b32_e64 v15, 0, v1, s[42:43]
	v_add_f32_e32 v1, v90, v73
	v_pk_add_f32 v[12:13], v[12:13], v[180:181]
	v_add_f32_e32 v177, v1, v91
	v_add_f32_e32 v13, v13, v81
	v_add_f32_e32 v151, v141, v177
	s_waitcnt lgkmcnt(0)
	v_cndmask_b32_e64 v81, 0, v75, s[8:9]
	v_mov_b32_e32 v80, v11
	v_mov_b32_e32 v179, v193
	v_mov_b32_e32 v90, v9
	v_mov_b32_e32 v91, v11
	v_pk_add_f32 v[80:81], v[150:151], v[80:81]
	v_pk_add_f32 v[90:91], v[178:179], v[90:91]
	v_cndmask_b32_e64 v14, 0, v3, s[40:41]
	v_add_f32_e32 v3, v91, v81
	v_mov_b32_e32 v153, v91
	v_mov_b32_e32 v11, v9
	v_add_f32_e32 v3, v90, v3
	v_pk_add_f32 v[90:91], v[152:153], v[10:11]
	v_add_f32_e32 v1, 0, v81
	v_add_f32_e32 v9, v91, v81
	ds_bpermute_b32 v173, v67, v190
	v_add_f32_e32 v1, v80, v1
	v_add_f32_e32 v9, v90, v9
	v_add_f32_e32 v12, v12, v13
	v_cndmask_b32_e64 v13, 0, v79, s[38:39]
	v_exp_f32_e32 v1, v1
	v_exp_f32_e32 v3, v3
	v_exp_f32_e32 v79, v9
	v_mov_b32_e32 v73, v91
	v_mov_b32_e32 v9, v10
	v_pk_add_f32 v[8:9], v[72:73], v[8:9]
	v_add_f32_e32 v175, v69, v75
	v_add_f32_e32 v9, v9, v81
	v_add_f32_e32 v147, 0, v7
	v_mov_b32_e32 v80, v6
	v_mov_b32_e32 v81, v5
	v_pk_add_f32 v[80:81], v[146:147], v[80:81]
	v_fmac_f32_e32 v4, 0x3e38aa3b, v68
	v_pk_add_f32 v[68:69], v[174:175], v[176:177]
	v_cndmask_b32_e64 v11, 0, v1, s[34:35]
	v_cndmask_b32_e64 v10, 0, v3, s[30:31]
	s_waitcnt lgkmcnt(0)
	v_cndmask_b32_e64 v1, 0, v173, s[8:9]
	v_add_f32_e32 v3, v6, v81
	v_add_f32_e32 v6, v141, v69
	v_mov_b32_e32 v169, v190
	v_add_f32_e32 v1, v1, v6
	v_fmac_f32_e32 v7, 0x3e38aa3b, v71
	v_pk_add_f32 v[90:91], v[168:169], v[172:173]
	v_add_f32_e32 v6, 0, v1
	v_fmac_f32_e32 v5, 0x3e38aa3b, v70
	v_pk_add_f32 v[90:91], v[90:91], v[68:69]
	v_add_f32_e32 v6, v7, v6
	v_add_f32_e32 v7, v147, v1
	ds_bpermute_b32 v67, v67, v90
	v_add_f32_e32 v5, v5, v7
	v_add_f32_e32 v7, v81, v1
	v_add_f32_e32 v7, v80, v7
	v_add_f32_e32 v1, v3, v1
	v_exp_f32_e32 v6, v6
	v_exp_f32_e32 v5, v5
	v_exp_f32_e32 v68, v7
	v_add_f32_e32 v1, v4, v1
	v_exp_f32_e32 v1, v1
	s_waitcnt lgkmcnt(0)
	v_cndmask_b32_e64 v177, 0, v67, s[8:9]
	v_add_f32_e32 v143, v141, v91
	v_cndmask_b32_e64 v7, 0, v6, s[24:25]
	v_cndmask_b32_e64 v6, 0, v5, s[22:23]
	v_cndmask_b32_e64 v5, 0, v68, s[18:19]
	v_pk_add_f32 v[68:69], v[142:143], v[176:177]
	v_cndmask_b32_e64 v4, 0, v1, s[16:17]
	v_add_f32_e32 v1, 0, v69
	v_mov_b32_e32 v171, v193
	v_mov_b32_e32 v175, v176
	v_add_f32_e32 v1, v68, v1
	v_pk_add_f32 v[80:81], v[170:171], v[174:175]
	v_exp_f32_e32 v68, v1
	v_add_f32_e32 v1, v81, v69
	v_mov_b32_e32 v3, v81
	v_mov_b32_e32 v173, v174
	v_add_f32_e32 v1, v80, v1
	v_pk_add_f32 v[2:3], v[2:3], v[172:173]
	v_exp_f32_e32 v71, v1
	v_add_f32_e32 v1, v3, v69
	v_add_f32_e32 v1, v2, v1
	v_exp_f32_e32 v73, v1
	v_mov_b32_e32 v1, v3
	v_mov_b32_e32 v169, v172
	v_pk_add_f32 v[0:1], v[0:1], v[168:169]
	v_add_f32_e32 v17, v200, v17
	v_add_f32_e32 v1, v1, v69
	v_add_f32_e32 v8, v8, v9
	v_add_f32_e32 v0, v0, v1
	v_exp_f32_e32 v30, v30
	v_exp_f32_e32 v17, v17
	v_exp_f32_e32 v12, v12
	v_exp_f32_e32 v8, v8
	v_exp_f32_e32 v0, v0
	v_add_f32_e32 v67, v90, v67
	s_movk_i32 s76, 0x1d00
	v_cndmask_b32_e64 v30, 0, v30, s[72:73]
	v_cndmask_b32_e64 v17, 0, v17, s[46:47]
	v_cndmask_b32_e64 v12, 0, v12, s[36:37]
	v_cndmask_b32_e64 v9, 0, v79, s[28:29]
	v_cndmask_b32_e64 v8, 0, v8, s[26:27]
	s_mov_b64 s[18:19], s[2:3]
	s_mov_b32 s2, s33
	s_movk_i32 s33, 0x600
	v_cndmask_b32_e64 v3, 0, v68, s[14:15]
	v_readlane_b32 s14, v254, 48
	v_readlane_b32 s3, v254, 51
	v_cndmask_b32_e64 v2, 0, v71, s[12:13]
	v_readlane_b32 s12, v254, 50
	v_cndmask_b32_e64 v1, 0, v73, s[0:1]
	v_cndmask_b32_e32 v0, 0, v0, vcc
	v_add_f32_e32 v67, v67, v91
	s_mov_b64 s[0:1], 0

.LBB0_505:
	v_lshlrev_b32_e32 v64, 1, v210
	v_add3_u32 v64, s12, v211, v64
	v_add_u32_e32 v65, 0x3000, v64
	v_add_u32_e32 v64, 0x4000, v64
	ds_read2_b64 v[68:71], v65 offset0:128 offset1:130
	v_cvt_pk_bf16_f32 v0, v0, v1
	v_cvt_pk_bf16_f32 v1, v2, v3
	v_cvt_pk_bf16_f32 v2, v4, v5
	v_cvt_pk_bf16_f32 v3, v6, v7
	ds_read2_b64 v[4:7], v64 offset0:160 offset1:162
	v_add_f32_e32 v141, v141, v67
	s_waitcnt lgkmcnt(1)
	v_mfma_f32_32x32x16_bf16 v[48:63], v[68:71], v[0:3], v[48:63]
	s_waitcnt lgkmcnt(0)
	v_mfma_f32_32x32x16_bf16 v[32:47], v[4:7], v[0:3], v[32:47]
	ds_read2_b64 v[0:3], v65 offset0:132 offset1:134
	v_cvt_pk_bf16_f32 v4, v8, v9
	v_cvt_pk_bf16_f32 v5, v10, v11
	v_cvt_pk_bf16_f32 v6, v12, v13
	v_cvt_pk_bf16_f32 v7, v14, v15
	s_nop 0
	s_nop 0
	s_waitcnt lgkmcnt(0)
	v_mfma_f32_32x32x16_bf16 v[48:63], v[0:3], v[4:7], v[48:63]
	ds_read2_b64 v[0:3], v64 offset0:164 offset1:166
	s_waitcnt lgkmcnt(0)
	v_mfma_f32_32x32x16_bf16 v[32:47], v[0:3], v[4:7], v[32:47]
	ds_read2_b64 v[0:3], v65 offset0:136 offset1:138
	v_cvt_pk_bf16_f32 v4, v16, v17
	v_cvt_pk_bf16_f32 v5, v18, v19
	v_cvt_pk_bf16_f32 v6, v20, v21
	v_cvt_pk_bf16_f32 v7, v22, v23
	s_nop 0
	s_nop 0
	s_waitcnt lgkmcnt(0)
	v_mfma_f32_32x32x16_bf16 v[48:63], v[0:3], v[4:7], v[48:63]
	ds_read2_b64 v[0:3], v64 offset0:168 offset1:170
	s_waitcnt lgkmcnt(0)
	v_mfma_f32_32x32x16_bf16 v[32:47], v[0:3], v[4:7], v[32:47]
	ds_read2_b64 v[0:3], v65 offset0:140 offset1:142
	v_cvt_pk_bf16_f32 v4, v24, v25
	v_cvt_pk_bf16_f32 v5, v26, v27
	v_cvt_pk_bf16_f32 v6, v28, v29
	v_cvt_pk_bf16_f32 v7, v30, v31
	s_nop 0
	s_nop 0
	s_waitcnt lgkmcnt(0)
	v_mfma_f32_32x32x16_bf16 v[48:63], v[0:3], v[4:7], v[48:63]
	ds_read2_b64 v[0:3], v64 offset0:172 offset1:174
	s_waitcnt lgkmcnt(0)
	v_mfma_f32_32x32x16_bf16 v[32:47], v[0:3], v[4:7], v[32:47]

.LBB0_509:
	s_or_b64 exec, exec, s[0:1]
	s_xor_b32 s2, s2, 1
	s_mul_i32 s0, s2, 0x9000
	v_add3_u32 v1, s0, v203, v204
	v_lshlrev_b32_e32 v0, 2, v202
	s_waitcnt vmcnt(0)
	ds_write_b128 v1, v[112:115]
	v_add3_u32 v1, s0, v205, v206
	ds_write_b128 v1, v[116:119]
	v_add3_u32 v0, s0, v0, v207
	v_lshlrev_b32_e32 v1, 16, v124
	s_mov_b32 s1, 0xffff
	v_lshrrev_b32_e32 v2, 16, v120
	s_mov_b32 s0, 0xffff0000
	v_and_or_b32 v1, v120, s1, v1
	v_and_or_b32 v2, v124, s0, v2
	v_add_u32_e32 v0, 0x3400, v0
	ds_write2_b32 v0, v1, v2 offset1:34
	v_lshlrev_b32_e32 v1, 16, v125
	v_lshrrev_b32_e32 v2, 16, v121
	v_and_or_b32 v1, v121, s1, v1
	v_and_or_b32 v2, v125, s0, v2
	ds_write2_b32 v0, v1, v2 offset0:68 offset1:102
	v_lshlrev_b32_e32 v1, 16, v126
	v_lshrrev_b32_e32 v2, 16, v122
	v_and_or_b32 v1, v122, s1, v1
	v_and_or_b32 v2, v126, s0, v2
	ds_write2_b32 v0, v1, v2 offset0:136 offset1:170
	v_lshlrev_b32_e32 v1, 16, v127
	v_lshrrev_b32_e32 v2, 16, v123
	v_subrev_co_u32_e32 v213, vcc, 1, v213
	v_and_or_b32 v1, v123, s1, v1
	v_and_or_b32 v2, v127, s0, v2
	s_and_b64 vcc, exec, vcc
	ds_write2_b32 v0, v1, v2 offset0:204 offset1:238
	s_cbranch_vccnz .LBB0_499
	v_add_u32_e32 v0, s82, v129
	v_add_u32_e32 v2, s82, v195
	v_add_u32_e32 v0, 0xffffff41, v0
	v_add_u32_e32 v2, 0xffffff41, v2
	v_mad_i64_i32 v[0:1], s[0:1], v0, s76, v[136:137]
	v_mad_i64_i32 v[2:3], s[0:1], v2, s76, v[138:139]
	global_load_dwordx4 v[112:115], v[0:1], off
	global_load_dwordx4 v[116:119], v[2:3], off
	v_add_u32_e32 v2, s82, v199
	v_add_u32_e32 v0, 0xffffff41, v2
	v_mad_u64_u32 v[0:1], s[0:1], v0, s76, v[134:135]
	v_add_u32_e32 v2, 0xffffff42, v2
	v_mad_u64_u32 v[2:3], s[0:1], v2, s76, v[134:135]
	global_load_dwordx4 v[120:123], v[0:1], off
	global_load_dwordx4 v[124:127], v[2:3], off
	s_branch .LBB0_499

.LBB0_513:
	s_mov_b64 s[8:9], 0x3e38aa3b
	s_lshl_b32 s0, s1, 1
	s_mov_b32 s1, s9
	v_readlane_b32 s8, v254, 43
	v_lshlrev_b64 v[2:3], 11, v[130:131]
	v_readlane_b32 s9, v254, 44
	v_lshl_add_u64 v[0:1], v[132:133], 0, s[0:1]
	v_mov_b32_e32 v129, v193
	v_lshl_add_u64 v[2:3], s[8:9], 0, v[2:3]
	v_lshl_add_u64 v[2:3], v[2:3], 0, s[0:1]
	v_lshl_add_u64 v[6:7], v[0:1], 0, v[128:129]
	s_mov_b64 s[0:1], 0x1a00
	v_lshl_add_u64 v[0:1], v[6:7], 0, s[0:1]
	v_add_co_u32_e32 v6, vcc, 0x1000, v6
	v_lshl_add_u64 v[2:3], v[2:3], 0, v[128:129]
	s_nop 0
	v_addc_co_u32_e32 v7, vcc, 0, v7, vcc
	global_load_dwordx4 v[6:9], v[6:7], off offset:2560
	s_mov_b64 s[0:1], 0xd210600
	v_lshl_add_u64 v[4:5], v[2:3], 0, s[0:1]
	v_readlane_b32 s76, v254, 37
	v_readlane_b32 s77, v254, 38
	s_mov_b64 s[8:9], 0
	s_waitcnt vmcnt(0) lgkmcnt(0)
	v_mov_b32_e32 v12, v8
	s_nop 1
	v_permlane32_swap_b32_e32 v6, v12
	v_lshlrev_b32_e32 v10, 16, v6
	v_and_b32_e32 v6, 0xffff0000, v6
	v_mov_b32_e32 v14, v9
	v_mul_f32_e32 v8, 0xbfb8aa3b, v10
	v_mul_f32_e32 v9, 0xbfb8aa3b, v6
	v_exp_f32_e32 v8, v8
	v_exp_f32_e32 v9, v9
	v_permlane32_swap_b32_e32 v7, v14
	v_pk_add_f32 v[8:9], v[8:9], 1.0 op_sel_hi:[1,0]
	s_nop 0
	v_div_scale_f32 v11, s[0:1], v9, v9, v6
	v_rcp_f32_e32 v13, v11
	s_nop 0
	v_fma_f32 v15, -v11, v13, 1.0
	v_fmac_f32_e32 v13, v15, v13
	v_div_scale_f32 v15, vcc, v6, v9, v6
	v_mul_f32_e32 v16, v15, v13
	v_fma_f32 v17, -v11, v16, v15
	v_fmac_f32_e32 v16, v17, v13
	v_fma_f32 v11, -v11, v16, v15
	v_div_fmas_f32 v11, v11, v13, v16
	v_div_fixup_f32 v9, v11, v9, v6
	v_div_scale_f32 v6, s[0:1], v8, v8, v10
	v_rcp_f32_e32 v11, v6
	s_nop 0
	v_fma_f32 v13, -v6, v11, 1.0
	v_fmac_f32_e32 v11, v13, v11
	v_div_scale_f32 v13, vcc, v10, v8, v10
	v_mul_f32_e32 v15, v13, v11
	v_fma_f32 v16, -v6, v15, v13
	v_fmac_f32_e32 v15, v16, v11
	v_fma_f32 v6, -v6, v15, v13
	v_div_fmas_f32 v6, v6, v11, v15
	v_div_fixup_f32 v8, v6, v8, v10
	v_lshlrev_b32_e32 v10, 16, v7
	v_and_b32_e32 v11, 0xffff0000, v7
	v_mul_f32_e32 v6, 0xbfb8aa3b, v10
	v_mul_f32_e32 v7, 0xbfb8aa3b, v11
	v_exp_f32_e32 v6, v6
	v_exp_f32_e32 v7, v7
	v_pk_mul_f32 v[8:9], v[48:49], v[8:9]
	v_pk_add_f32 v[6:7], v[6:7], 1.0 op_sel_hi:[1,0]
	s_nop 0
	v_div_scale_f32 v13, s[0:1], v7, v7, v11
	v_rcp_f32_e32 v15, v13
	s_nop 0
	v_fma_f32 v16, -v13, v15, 1.0
	v_fmac_f32_e32 v15, v16, v15
	v_div_scale_f32 v16, vcc, v11, v7, v11
	v_mul_f32_e32 v17, v16, v15
	v_fma_f32 v18, -v13, v17, v16
	v_fmac_f32_e32 v17, v18, v15
	v_fma_f32 v13, -v13, v17, v16
	v_div_fmas_f32 v13, v13, v15, v17
	v_div_fixup_f32 v7, v13, v7, v11
	v_div_scale_f32 v11, s[0:1], v6, v6, v10
	v_rcp_f32_e32 v13, v11
	s_nop 0
	v_fma_f32 v15, -v11, v13, 1.0
	v_fmac_f32_e32 v13, v15, v13
	v_div_scale_f32 v15, vcc, v10, v6, v10
	v_mul_f32_e32 v16, v15, v13
	v_fma_f32 v17, -v11, v16, v15
	v_fmac_f32_e32 v16, v17, v13
	v_fma_f32 v11, -v11, v16, v15
	v_div_fmas_f32 v11, v11, v13, v16
	v_div_fixup_f32 v6, v11, v6, v10
	v_lshlrev_b32_e32 v13, 16, v12
	v_and_b32_e32 v12, 0xffff0000, v12
	v_pk_mul_f32 v[10:11], v[50:51], v[6:7]
	v_mul_f32_e32 v6, 0xbfb8aa3b, v13
	v_mul_f32_e32 v7, 0xbfb8aa3b, v12
	v_exp_f32_e32 v6, v6
	v_exp_f32_e32 v7, v7
	s_nop 0
	v_pk_add_f32 v[6:7], v[6:7], 1.0 op_sel_hi:[1,0]
	s_nop 0
	v_div_scale_f32 v15, s[0:1], v7, v7, v12
	v_rcp_f32_e32 v16, v15
	s_nop 0
	v_fma_f32 v17, -v15, v16, 1.0
	v_fmac_f32_e32 v16, v17, v16
	v_div_scale_f32 v17, vcc, v12, v7, v12
	v_mul_f32_e32 v18, v17, v16
	v_fma_f32 v19, -v15, v18, v17
	v_fmac_f32_e32 v18, v19, v16
	v_fma_f32 v15, -v15, v18, v17
	v_div_fmas_f32 v15, v15, v16, v18
	v_div_fixup_f32 v7, v15, v7, v12
	v_div_scale_f32 v12, s[0:1], v6, v6, v13
	v_rcp_f32_e32 v15, v12
	s_nop 0
	v_fma_f32 v16, -v12, v15, 1.0
	v_fmac_f32_e32 v15, v16, v15
	v_div_scale_f32 v16, vcc, v13, v6, v13
	v_mul_f32_e32 v17, v16, v15
	v_fma_f32 v18, -v12, v17, v16
	v_fmac_f32_e32 v17, v18, v15
	v_fma_f32 v12, -v12, v17, v16
	v_div_fmas_f32 v12, v12, v15, v17
	v_div_fixup_f32 v6, v12, v6, v13
	v_lshlrev_b32_e32 v15, 16, v14
	v_and_b32_e32 v14, 0xffff0000, v14
	v_pk_mul_f32 v[12:13], v[52:53], v[6:7]
	v_mul_f32_e32 v6, 0xbfb8aa3b, v15
	v_mul_f32_e32 v7, 0xbfb8aa3b, v14
	v_exp_f32_e32 v6, v6
	v_exp_f32_e32 v7, v7
	s_nop 0
	v_pk_add_f32 v[6:7], v[6:7], 1.0 op_sel_hi:[1,0]
	s_nop 0
	v_div_scale_f32 v16, s[0:1], v7, v7, v14
	v_rcp_f32_e32 v17, v16
	s_nop 0
	v_fma_f32 v18, -v16, v17, 1.0
	v_fmac_f32_e32 v17, v18, v17
	v_div_scale_f32 v18, vcc, v14, v7, v14
	v_mul_f32_e32 v19, v18, v17
	v_fma_f32 v20, -v16, v19, v18
	v_fmac_f32_e32 v19, v20, v17
	v_fma_f32 v16, -v16, v19, v18
	v_div_fmas_f32 v16, v16, v17, v19
	v_div_fixup_f32 v7, v16, v7, v14
	v_div_scale_f32 v14, s[0:1], v6, v6, v15
	v_rcp_f32_e32 v16, v14
	s_mov_b32 s0, 0xd210000
	v_fma_f32 v17, -v14, v16, 1.0
	v_fmac_f32_e32 v16, v17, v16
	v_div_scale_f32 v17, vcc, v15, v6, v15
	v_mul_f32_e32 v18, v17, v16
	v_fma_f32 v19, -v14, v18, v17
	v_fmac_f32_e32 v18, v19, v16
	v_fma_f32 v14, -v14, v18, v17
	v_div_fmas_f32 v14, v14, v16, v18
	v_div_fixup_f32 v6, v14, v6, v15
	v_pk_mul_f32 v[14:15], v[54:55], v[6:7]
	v_cvt_pk_bf16_f32 v6, v8, v9
	v_cvt_pk_bf16_f32 v7, v10, v11
	v_cvt_pk_bf16_f32 v8, v12, v13
	v_cvt_pk_bf16_f32 v9, v14, v15
	v_add_co_u32_e32 v2, vcc, s0, v2
	v_permlane32_swap_b32_e32 v6, v8
	v_permlane32_swap_b32_e32 v7, v9
	v_addc_co_u32_e32 v3, vcc, 0, v3, vcc
	global_store_dwordx4 v[2:3], v[6:9], off offset:1536
	global_load_dwordx4 v[6:9], v[0:1], off offset:32
	s_waitcnt vmcnt(0)
	v_mov_b32_e32 v10, v8
	s_nop 1
	v_permlane32_swap_b32_e32 v6, v10
	v_lshlrev_b32_e32 v8, 16, v6
	v_and_b32_e32 v6, 0xffff0000, v6
	v_mul_f32_e32 v2, 0xbfb8aa3b, v8
	v_mul_f32_e32 v3, 0xbfb8aa3b, v6
	v_exp_f32_e32 v2, v2
	v_exp_f32_e32 v3, v3
	v_mov_b32_e32 v12, v9
	s_nop 1
	v_permlane32_swap_b32_e32 v7, v12
	v_pk_add_f32 v[2:3], v[2:3], 1.0 op_sel_hi:[1,0]
	s_nop 0
	v_div_scale_f32 v9, s[0:1], v3, v3, v6
	v_rcp_f32_e32 v11, v9
	s_nop 0
	v_fma_f32 v13, -v9, v11, 1.0
	v_fmac_f32_e32 v11, v13, v11
	v_div_scale_f32 v13, vcc, v6, v3, v6
	v_mul_f32_e32 v14, v13, v11
	v_fma_f32 v15, -v9, v14, v13
	v_fmac_f32_e32 v14, v15, v11
	v_fma_f32 v9, -v9, v14, v13
	v_div_fmas_f32 v9, v9, v11, v14
	v_div_fixup_f32 v3, v9, v3, v6
	v_div_scale_f32 v6, s[0:1], v2, v2, v8
	v_rcp_f32_e32 v9, v6
	s_nop 0
	v_fma_f32 v11, -v6, v9, 1.0
	v_fmac_f32_e32 v9, v11, v9
	v_div_scale_f32 v11, vcc, v8, v2, v8
	v_mul_f32_e32 v13, v11, v9
	v_fma_f32 v14, -v6, v13, v11
	v_fmac_f32_e32 v13, v14, v9
	v_fma_f32 v6, -v6, v13, v11
	v_div_fmas_f32 v6, v6, v9, v13
	v_div_fixup_f32 v2, v6, v2, v8
	v_lshlrev_b32_e32 v8, 16, v7
	v_and_b32_e32 v9, 0xffff0000, v7
	v_mul_f32_e32 v6, 0xbfb8aa3b, v8
	v_mul_f32_e32 v7, 0xbfb8aa3b, v9
	v_exp_f32_e32 v6, v6
	v_exp_f32_e32 v7, v7
	v_pk_mul_f32 v[2:3], v[56:57], v[2:3]
	v_pk_add_f32 v[6:7], v[6:7], 1.0 op_sel_hi:[1,0]
	s_nop 0
	v_div_scale_f32 v11, s[0:1], v7, v7, v9
	v_rcp_f32_e32 v13, v11
	s_nop 0
	v_fma_f32 v14, -v11, v13, 1.0
	v_fmac_f32_e32 v13, v14, v13
	v_div_scale_f32 v14, vcc, v9, v7, v9
	v_mul_f32_e32 v15, v14, v13
	v_fma_f32 v16, -v11, v15, v14
	v_fmac_f32_e32 v15, v16, v13
	v_fma_f32 v11, -v11, v15, v14
	v_div_fmas_f32 v11, v11, v13, v15
	v_div_fixup_f32 v7, v11, v7, v9
	v_div_scale_f32 v9, s[0:1], v6, v6, v8
	v_rcp_f32_e32 v11, v9
	s_nop 0
	v_fma_f32 v13, -v9, v11, 1.0
	v_fmac_f32_e32 v11, v13, v11
	v_div_scale_f32 v13, vcc, v8, v6, v8
	v_mul_f32_e32 v14, v13, v11
	v_fma_f32 v15, -v9, v14, v13
	v_fmac_f32_e32 v14, v15, v11
	v_fma_f32 v9, -v9, v14, v13
	v_div_fmas_f32 v9, v9, v11, v14
	v_div_fixup_f32 v6, v9, v6, v8
	v_lshlrev_b32_e32 v11, 16, v10
	v_and_b32_e32 v10, 0xffff0000, v10
	v_pk_mul_f32 v[8:9], v[58:59], v[6:7]
	v_mul_f32_e32 v6, 0xbfb8aa3b, v11
	v_mul_f32_e32 v7, 0xbfb8aa3b, v10
	v_exp_f32_e32 v6, v6
	v_exp_f32_e32 v7, v7
	s_nop 0
	v_pk_add_f32 v[6:7], v[6:7], 1.0 op_sel_hi:[1,0]
	s_nop 0
	v_div_scale_f32 v13, s[0:1], v7, v7, v10
	v_rcp_f32_e32 v14, v13
	s_nop 0
	v_fma_f32 v15, -v13, v14, 1.0
	v_fmac_f32_e32 v14, v15, v14
	v_div_scale_f32 v15, vcc, v10, v7, v10
	v_mul_f32_e32 v16, v15, v14
	v_fma_f32 v17, -v13, v16, v15
	v_fmac_f32_e32 v16, v17, v14
	v_fma_f32 v13, -v13, v16, v15
	v_div_fmas_f32 v13, v13, v14, v16
	v_div_fixup_f32 v7, v13, v7, v10
	v_div_scale_f32 v10, s[0:1], v6, v6, v11
	v_rcp_f32_e32 v13, v10
	s_nop 0
	v_fma_f32 v14, -v10, v13, 1.0
	v_fmac_f32_e32 v13, v14, v13
	v_div_scale_f32 v14, vcc, v11, v6, v11
	v_mul_f32_e32 v15, v14, v13
	v_fma_f32 v16, -v10, v15, v14
	v_fmac_f32_e32 v15, v16, v13
	v_fma_f32 v10, -v10, v15, v14
	v_div_fmas_f32 v10, v10, v13, v15
	v_div_fixup_f32 v6, v10, v6, v11
	v_lshlrev_b32_e32 v13, 16, v12
	v_and_b32_e32 v12, 0xffff0000, v12
	v_pk_mul_f32 v[10:11], v[60:61], v[6:7]
	v_mul_f32_e32 v6, 0xbfb8aa3b, v13
	v_mul_f32_e32 v7, 0xbfb8aa3b, v12
	v_exp_f32_e32 v6, v6
	v_exp_f32_e32 v7, v7
	s_nop 0
	v_pk_add_f32 v[6:7], v[6:7], 1.0 op_sel_hi:[1,0]
	s_nop 0
	v_div_scale_f32 v14, s[0:1], v7, v7, v12
	v_rcp_f32_e32 v15, v14
	s_nop 0
	v_fma_f32 v16, -v14, v15, 1.0
	v_fmac_f32_e32 v15, v16, v15
	v_div_scale_f32 v16, vcc, v12, v7, v12
	v_mul_f32_e32 v17, v16, v15
	v_fma_f32 v18, -v14, v17, v16
	v_fmac_f32_e32 v17, v18, v15
	v_fma_f32 v14, -v14, v17, v16
	v_div_fmas_f32 v14, v14, v15, v17
	v_div_fixup_f32 v7, v14, v7, v12
	v_div_scale_f32 v12, s[0:1], v6, v6, v13
	v_rcp_f32_e32 v14, v12
	s_nop 0
	v_fma_f32 v15, -v12, v14, 1.0
	v_fmac_f32_e32 v14, v15, v14
	v_div_scale_f32 v15, vcc, v13, v6, v13
	v_mul_f32_e32 v16, v15, v14
	v_fma_f32 v17, -v12, v16, v15
	v_fmac_f32_e32 v16, v17, v14
	v_fma_f32 v12, -v12, v16, v15
	v_div_fmas_f32 v12, v12, v14, v16
	v_div_fixup_f32 v6, v12, v6, v13
	v_pk_mul_f32 v[12:13], v[62:63], v[6:7]
	v_cvt_pk_bf16_f32 v6, v2, v3
	v_cvt_pk_bf16_f32 v7, v8, v9
	v_cvt_pk_bf16_f32 v8, v10, v11
	v_cvt_pk_bf16_f32 v9, v12, v13
	s_nop 0
	v_permlane32_swap_b32_e32 v6, v8
	v_permlane32_swap_b32_e32 v7, v9
	global_store_dwordx4 v[4:5], v[6:9], off offset:32
	global_load_dwordx4 v[6:9], v[0:1], off offset:64
	s_waitcnt vmcnt(0)
	v_mov_b32_e32 v10, v8
	s_nop 1
	v_permlane32_swap_b32_e32 v6, v10
	v_lshlrev_b32_e32 v8, 16, v6
	v_and_b32_e32 v6, 0xffff0000, v6
	v_mul_f32_e32 v2, 0xbfb8aa3b, v8
	v_mul_f32_e32 v3, 0xbfb8aa3b, v6
	v_exp_f32_e32 v2, v2
	v_exp_f32_e32 v3, v3
	v_mov_b32_e32 v12, v9
	s_nop 1
	v_permlane32_swap_b32_e32 v7, v12
	v_pk_add_f32 v[2:3], v[2:3], 1.0 op_sel_hi:[1,0]
	s_nop 0
	v_div_scale_f32 v9, s[0:1], v3, v3, v6
	v_rcp_f32_e32 v11, v9
	s_nop 0
	v_fma_f32 v13, -v9, v11, 1.0
	v_fmac_f32_e32 v11, v13, v11
	v_div_scale_f32 v13, vcc, v6, v3, v6
	v_mul_f32_e32 v14, v13, v11
	v_fma_f32 v15, -v9, v14, v13
	v_fmac_f32_e32 v14, v15, v11
	v_fma_f32 v9, -v9, v14, v13
	v_div_fmas_f32 v9, v9, v11, v14
	v_div_fixup_f32 v3, v9, v3, v6
	v_div_scale_f32 v6, s[0:1], v2, v2, v8
	v_rcp_f32_e32 v9, v6
	s_nop 0
	v_fma_f32 v11, -v6, v9, 1.0
	v_fmac_f32_e32 v9, v11, v9
	v_div_scale_f32 v11, vcc, v8, v2, v8
	v_mul_f32_e32 v13, v11, v9
	v_fma_f32 v14, -v6, v13, v11
	v_fmac_f32_e32 v13, v14, v9
	v_fma_f32 v6, -v6, v13, v11
	v_div_fmas_f32 v6, v6, v9, v13
	v_div_fixup_f32 v2, v6, v2, v8
	v_lshlrev_b32_e32 v8, 16, v7
	v_and_b32_e32 v9, 0xffff0000, v7
	v_mul_f32_e32 v6, 0xbfb8aa3b, v8
	v_mul_f32_e32 v7, 0xbfb8aa3b, v9
	v_exp_f32_e32 v6, v6
	v_exp_f32_e32 v7, v7
	v_pk_mul_f32 v[2:3], v[32:33], v[2:3]
	v_pk_add_f32 v[6:7], v[6:7], 1.0 op_sel_hi:[1,0]
	s_nop 0
	v_div_scale_f32 v11, s[0:1], v7, v7, v9
	v_rcp_f32_e32 v13, v11
	s_nop 0
	v_fma_f32 v14, -v11, v13, 1.0
	v_fmac_f32_e32 v13, v14, v13
	v_div_scale_f32 v14, vcc, v9, v7, v9
	v_mul_f32_e32 v15, v14, v13
	v_fma_f32 v16, -v11, v15, v14
	v_fmac_f32_e32 v15, v16, v13
	v_fma_f32 v11, -v11, v15, v14
	v_div_fmas_f32 v11, v11, v13, v15
	v_div_fixup_f32 v7, v11, v7, v9
	v_div_scale_f32 v9, s[0:1], v6, v6, v8
	v_rcp_f32_e32 v11, v9
	s_nop 0
	v_fma_f32 v13, -v9, v11, 1.0
	v_fmac_f32_e32 v11, v13, v11
	v_div_scale_f32 v13, vcc, v8, v6, v8
	v_mul_f32_e32 v14, v13, v11
	v_fma_f32 v15, -v9, v14, v13
	v_fmac_f32_e32 v14, v15, v11
	v_fma_f32 v9, -v9, v14, v13
	v_div_fmas_f32 v9, v9, v11, v14
	v_div_fixup_f32 v6, v9, v6, v8
	v_lshlrev_b32_e32 v11, 16, v10
	v_and_b32_e32 v10, 0xffff0000, v10
	v_pk_mul_f32 v[8:9], v[34:35], v[6:7]
	v_mul_f32_e32 v6, 0xbfb8aa3b, v11
	v_mul_f32_e32 v7, 0xbfb8aa3b, v10
	v_exp_f32_e32 v6, v6
	v_exp_f32_e32 v7, v7
	s_nop 0
	v_pk_add_f32 v[6:7], v[6:7], 1.0 op_sel_hi:[1,0]
	s_nop 0
	v_div_scale_f32 v13, s[0:1], v7, v7, v10
	v_rcp_f32_e32 v14, v13
	s_nop 0
	v_fma_f32 v15, -v13, v14, 1.0
	v_fmac_f32_e32 v14, v15, v14
	v_div_scale_f32 v15, vcc, v10, v7, v10
	v_mul_f32_e32 v16, v15, v14
	v_fma_f32 v17, -v13, v16, v15
	v_fmac_f32_e32 v16, v17, v14
	v_fma_f32 v13, -v13, v16, v15
	v_div_fmas_f32 v13, v13, v14, v16
	v_div_fixup_f32 v7, v13, v7, v10
	v_div_scale_f32 v10, s[0:1], v6, v6, v11
	v_rcp_f32_e32 v13, v10
	s_nop 0
	v_fma_f32 v14, -v10, v13, 1.0
	v_fmac_f32_e32 v13, v14, v13
	v_div_scale_f32 v14, vcc, v11, v6, v11
	v_mul_f32_e32 v15, v14, v13
	v_fma_f32 v16, -v10, v15, v14
	v_fmac_f32_e32 v15, v16, v13
	v_fma_f32 v10, -v10, v15, v14
	v_div_fmas_f32 v10, v10, v13, v15
	v_div_fixup_f32 v6, v10, v6, v11
	v_lshlrev_b32_e32 v13, 16, v12
	v_and_b32_e32 v12, 0xffff0000, v12
	v_pk_mul_f32 v[10:11], v[36:37], v[6:7]
	v_mul_f32_e32 v6, 0xbfb8aa3b, v13
	v_mul_f32_e32 v7, 0xbfb8aa3b, v12
	v_exp_f32_e32 v6, v6
	v_exp_f32_e32 v7, v7
	s_nop 0
	v_pk_add_f32 v[6:7], v[6:7], 1.0 op_sel_hi:[1,0]
	s_nop 0
	v_div_scale_f32 v14, s[0:1], v7, v7, v12
	v_rcp_f32_e32 v15, v14
	s_nop 0
	v_fma_f32 v16, -v14, v15, 1.0
	v_fmac_f32_e32 v15, v16, v15
	v_div_scale_f32 v16, vcc, v12, v7, v12
	v_mul_f32_e32 v17, v16, v15
	v_fma_f32 v18, -v14, v17, v16
	v_fmac_f32_e32 v17, v18, v15
	v_fma_f32 v14, -v14, v17, v16
	v_div_fmas_f32 v14, v14, v15, v17
	v_div_fixup_f32 v7, v14, v7, v12
	v_div_scale_f32 v12, s[0:1], v6, v6, v13
	v_rcp_f32_e32 v14, v12
	s_nop 0
	v_fma_f32 v15, -v12, v14, 1.0
	v_fmac_f32_e32 v14, v15, v14
	v_div_scale_f32 v15, vcc, v13, v6, v13
	v_mul_f32_e32 v16, v15, v14
	v_fma_f32 v17, -v12, v16, v15
	v_fmac_f32_e32 v16, v17, v14
	v_fma_f32 v12, -v12, v16, v15
	v_div_fmas_f32 v12, v12, v14, v16
	v_div_fixup_f32 v6, v12, v6, v13
	v_pk_mul_f32 v[12:13], v[38:39], v[6:7]
	v_cvt_pk_bf16_f32 v6, v2, v3
	global_load_dwordx4 v[0:3], v[0:1], off offset:96
	v_cvt_pk_bf16_f32 v7, v8, v9
	v_cvt_pk_bf16_f32 v8, v10, v11
	v_cvt_pk_bf16_f32 v9, v12, v13
	s_nop 0
	v_permlane32_swap_b32_e32 v6, v8
	v_permlane32_swap_b32_e32 v7, v9
	global_store_dwordx4 v[4:5], v[6:9], off offset:64
	s_waitcnt vmcnt(1)
	v_mov_b32_e32 v10, v3
	v_mov_b32_e32 v8, v2
	s_nop 1
	v_permlane32_swap_b32_e32 v0, v8
	v_lshlrev_b32_e32 v6, 16, v0
	v_and_b32_e32 v0, 0xffff0000, v0
	v_mul_f32_e32 v2, 0xbfb8aa3b, v6
	v_mul_f32_e32 v3, 0xbfb8aa3b, v0
	v_exp_f32_e32 v2, v2
	v_exp_f32_e32 v3, v3
	v_permlane32_swap_b32_e32 v1, v10
	v_pk_add_f32 v[2:3], v[2:3], 1.0 op_sel_hi:[1,0]
	s_nop 0
	v_div_scale_f32 v7, s[0:1], v3, v3, v0
	v_rcp_f32_e32 v9, v7
	s_nop 0
	v_fma_f32 v11, -v7, v9, 1.0
	v_fmac_f32_e32 v9, v11, v9
	v_div_scale_f32 v11, vcc, v0, v3, v0
	v_mul_f32_e32 v12, v11, v9
	v_fma_f32 v13, -v7, v12, v11
	v_fmac_f32_e32 v12, v13, v9
	v_fma_f32 v7, -v7, v12, v11
	v_div_fmas_f32 v7, v7, v9, v12
	v_div_fixup_f32 v3, v7, v3, v0
	v_div_scale_f32 v0, s[0:1], v2, v2, v6
	v_rcp_f32_e32 v7, v0
	s_nop 0
	v_fma_f32 v9, -v0, v7, 1.0
	v_fmac_f32_e32 v7, v9, v7
	v_div_scale_f32 v9, vcc, v6, v2, v6
	v_mul_f32_e32 v11, v9, v7
	v_fma_f32 v12, -v0, v11, v9
	v_fmac_f32_e32 v11, v12, v7
	v_fma_f32 v0, -v0, v11, v9
	v_div_fmas_f32 v0, v0, v7, v11
	v_div_fixup_f32 v2, v0, v2, v6
	v_lshlrev_b32_e32 v6, 16, v1
	v_and_b32_e32 v7, 0xffff0000, v1
	v_mul_f32_e32 v0, 0xbfb8aa3b, v6
	v_mul_f32_e32 v1, 0xbfb8aa3b, v7
	v_exp_f32_e32 v0, v0
	v_exp_f32_e32 v1, v1
	v_pk_mul_f32 v[2:3], v[40:41], v[2:3]
	v_pk_add_f32 v[0:1], v[0:1], 1.0 op_sel_hi:[1,0]
	s_nop 0
	v_div_scale_f32 v9, s[0:1], v1, v1, v7
	v_rcp_f32_e32 v11, v9
	s_nop 0
	v_fma_f32 v12, -v9, v11, 1.0
	v_fmac_f32_e32 v11, v12, v11
	v_div_scale_f32 v12, vcc, v7, v1, v7
	v_mul_f32_e32 v13, v12, v11
	v_fma_f32 v14, -v9, v13, v12
	v_fmac_f32_e32 v13, v14, v11
	v_fma_f32 v9, -v9, v13, v12
	v_div_fmas_f32 v9, v9, v11, v13
	v_div_fixup_f32 v1, v9, v1, v7
	v_div_scale_f32 v7, s[0:1], v0, v0, v6
	v_rcp_f32_e32 v9, v7
	s_nop 0
	v_fma_f32 v11, -v7, v9, 1.0
	v_fmac_f32_e32 v9, v11, v9
	v_div_scale_f32 v11, vcc, v6, v0, v6
	v_mul_f32_e32 v12, v11, v9
	v_fma_f32 v13, -v7, v12, v11
	v_fmac_f32_e32 v12, v13, v9
	v_fma_f32 v7, -v7, v12, v11
	v_div_fmas_f32 v7, v7, v9, v12
	v_div_fixup_f32 v0, v7, v0, v6
	v_lshlrev_b32_e32 v9, 16, v8
	v_and_b32_e32 v8, 0xffff0000, v8
	v_pk_mul_f32 v[6:7], v[42:43], v[0:1]
	v_mul_f32_e32 v0, 0xbfb8aa3b, v9
	v_mul_f32_e32 v1, 0xbfb8aa3b, v8
	v_exp_f32_e32 v0, v0
	v_exp_f32_e32 v1, v1
	s_nop 0
	v_pk_add_f32 v[0:1], v[0:1], 1.0 op_sel_hi:[1,0]
	s_nop 0
	v_div_scale_f32 v11, s[0:1], v1, v1, v8
	v_rcp_f32_e32 v12, v11
	s_nop 0
	v_fma_f32 v13, -v11, v12, 1.0
	v_fmac_f32_e32 v12, v13, v12
	v_div_scale_f32 v13, vcc, v8, v1, v8
	v_mul_f32_e32 v14, v13, v12
	v_fma_f32 v15, -v11, v14, v13
	v_fmac_f32_e32 v14, v15, v12
	v_fma_f32 v11, -v11, v14, v13
	v_div_fmas_f32 v11, v11, v12, v14
	v_div_fixup_f32 v1, v11, v1, v8
	v_div_scale_f32 v8, s[0:1], v0, v0, v9
	v_rcp_f32_e32 v11, v8
	s_nop 0
	v_fma_f32 v12, -v8, v11, 1.0
	v_fmac_f32_e32 v11, v12, v11
	v_div_scale_f32 v12, vcc, v9, v0, v9
	v_mul_f32_e32 v13, v12, v11
	v_fma_f32 v14, -v8, v13, v12
	v_fmac_f32_e32 v13, v14, v11
	v_fma_f32 v8, -v8, v13, v12
	v_div_fmas_f32 v8, v8, v11, v13
	v_div_fixup_f32 v0, v8, v0, v9
	v_lshlrev_b32_e32 v11, 16, v10
	v_and_b32_e32 v10, 0xffff0000, v10
	v_pk_mul_f32 v[8:9], v[44:45], v[0:1]
	v_mul_f32_e32 v0, 0xbfb8aa3b, v11
	v_mul_f32_e32 v1, 0xbfb8aa3b, v10
	v_exp_f32_e32 v0, v0
	v_exp_f32_e32 v1, v1
	s_nop 0
	v_pk_add_f32 v[0:1], v[0:1], 1.0 op_sel_hi:[1,0]
	s_nop 0
	v_div_scale_f32 v12, s[0:1], v1, v1, v10
	v_rcp_f32_e32 v13, v12
	s_nop 0
	v_fma_f32 v14, -v12, v13, 1.0
	v_fmac_f32_e32 v13, v14, v13
	v_div_scale_f32 v14, vcc, v10, v1, v10
	v_mul_f32_e32 v15, v14, v13
	v_fma_f32 v16, -v12, v15, v14
	v_fmac_f32_e32 v15, v16, v13
	v_fma_f32 v12, -v12, v15, v14
	v_div_fmas_f32 v12, v12, v13, v15
	v_div_fixup_f32 v1, v12, v1, v10
	v_div_scale_f32 v10, s[0:1], v0, v0, v11
	v_rcp_f32_e32 v12, v10
	s_nop 0
	v_fma_f32 v13, -v10, v12, 1.0
	v_fmac_f32_e32 v12, v13, v12
	v_div_scale_f32 v13, vcc, v11, v0, v11
	v_mul_f32_e32 v14, v13, v12
	v_fma_f32 v15, -v10, v14, v13
	v_fmac_f32_e32 v14, v15, v12
	v_fma_f32 v10, -v10, v14, v13
	v_div_fmas_f32 v10, v10, v12, v14
	v_div_fixup_f32 v0, v10, v0, v11
	v_pk_mul_f32 v[10:11], v[46:47], v[0:1]
	v_cvt_pk_bf16_f32 v0, v2, v3
	v_cvt_pk_bf16_f32 v1, v6, v7
	v_cvt_pk_bf16_f32 v2, v8, v9
	v_cvt_pk_bf16_f32 v3, v10, v11
	s_nop 0
	v_permlane32_swap_b32_e32 v0, v2
	v_permlane32_swap_b32_e32 v1, v3
	global_store_dwordx4 v[4:5], v[0:3], off offset:96

.LBB0_521:
	s_or_b64 exec, exec, s[34:35]
	v_lshlrev_b32_e32 v32, 3, v40
	v_sub_u32_e32 v32, v37, v32
	v_and_b32_e32 v32, 0xffffffc0, v32
	v_ashrrev_i32_e32 v33, 1, v39
	v_add_u32_e32 v32, v32, v33
	v_ashrrev_i32_e32 v33, 31, v32
	v_lshlrev_b64 v[40:41], 6, v[32:33]
	v_lshlrev_b32_e32 v32, 5, v39
	v_and_b32_e32 v39, 32, v32
	v_and_b32_e32 v44, 28, v192
	v_or3_b32 v40, v40, v39, v44
	s_waitcnt vmcnt(0)
	v_cvt_pk_bf16_f32 v32, v0, v4
	v_cvt_pk_bf16_f32 v33, v12, v8
	v_cvt_pk_bf16_f32 v34, v20, v16
	v_cvt_pk_bf16_f32 v35, v28, v24
	v_lshl_add_u64 v[44:45], v[40:41], 4, s[26:27]
	global_store_dwordx4 v[44:45], v[32:35], off
	v_or_b32_e32 v0, 1, v40
	v_add_u32_e32 v38, s79, v38
	v_cvt_pk_bf16_f32 v32, v1, v5
	v_mov_b32_e32 v1, v41
	v_cvt_pk_bf16_f32 v33, v13, v9
	v_cvt_pk_bf16_f32 v34, v21, v17
	v_cvt_pk_bf16_f32 v35, v29, v25
	v_lshl_add_u64 v[0:1], v[0:1], 4, s[26:27]
	global_store_dwordx4 v[0:1], v[32:35], off
	v_or_b32_e32 v0, 2, v40
	v_mov_b32_e32 v1, v41
	s_movk_i32 s34, 0x7fff
	v_cvt_pk_bf16_f32 v32, v2, v6
	v_cvt_pk_bf16_f32 v33, v14, v10
	v_cvt_pk_bf16_f32 v34, v22, v18
	v_cvt_pk_bf16_f32 v35, v30, v26
	v_lshl_add_u64 v[0:1], v[0:1], 4, s[26:27]
	v_or_b32_e32 v40, 3, v40
	v_cmp_lt_i32_e32 vcc, s34, v38
	global_store_dwordx4 v[0:1], v[32:35], off
	v_cvt_pk_bf16_f32 v0, v3, v7
	v_cvt_pk_bf16_f32 v1, v15, v11
	v_cvt_pk_bf16_f32 v2, v23, v19
	v_cvt_pk_bf16_f32 v3, v31, v27
	v_lshl_add_u64 v[4:5], v[40:41], 4, s[26:27]
	v_add_u32_e32 v36, s36, v36
	s_or_b64 s[30:31], vcc, s[30:31]
	v_add_u32_e32 v37, s37, v37
	global_store_dwordx4 v[4:5], v[0:3], off
	s_andn2_b64 exec, exec, s[30:31]
	s_cbranch_execz .LBB0_538

.LBB0_541:
	s_or_b64 exec, exec, s[28:29]
	v_lshlrev_b32_e32 v32, 3, v41
	v_sub_u32_e32 v32, v37, v32
	v_and_b32_e32 v32, 0xffffffc0, v32
	v_ashrrev_i32_e32 v33, 1, v39
	v_add_u32_e32 v32, v32, v33
	v_ashrrev_i32_e32 v33, 31, v32
	v_lshlrev_b64 v[44:45], 6, v[32:33]
	v_lshlrev_b32_e32 v32, 5, v39
	v_and_b32_e32 v39, 32, v32
	v_and_b32_e32 v40, 28, v40
	v_or3_b32 v44, v44, v39, v40
	s_waitcnt vmcnt(0)
	v_cvt_pk_bf16_f32 v32, v0, v4
	v_cvt_pk_bf16_f32 v33, v12, v8
	v_cvt_pk_bf16_f32 v34, v20, v16
	v_cvt_pk_bf16_f32 v35, v28, v24
	v_lshl_add_u64 v[40:41], v[44:45], 4, s[94:95]
	global_store_dwordx4 v[40:41], v[32:35], off
	v_or_b32_e32 v0, 1, v44
	v_add_u32_e32 v38, s79, v38
	v_cvt_pk_bf16_f32 v32, v1, v5
	v_mov_b32_e32 v1, v45
	v_cvt_pk_bf16_f32 v33, v13, v9
	v_cvt_pk_bf16_f32 v34, v21, v17
	v_cvt_pk_bf16_f32 v35, v29, v25
	v_lshl_add_u64 v[0:1], v[0:1], 4, s[94:95]
	global_store_dwordx4 v[0:1], v[32:35], off
	v_or_b32_e32 v0, 2, v44
	v_mov_b32_e32 v1, v45
	s_mov_b32 s0, 0x1dfff
	v_cvt_pk_bf16_f32 v32, v2, v6
	v_cvt_pk_bf16_f32 v33, v14, v10
	v_cvt_pk_bf16_f32 v34, v22, v18
	v_cvt_pk_bf16_f32 v35, v30, v26
	v_lshl_add_u64 v[0:1], v[0:1], 4, s[94:95]
	v_or_b32_e32 v44, 3, v44
	v_cmp_lt_i32_e32 vcc, s0, v38
	global_store_dwordx4 v[0:1], v[32:35], off
	v_cvt_pk_bf16_f32 v0, v3, v7
	v_cvt_pk_bf16_f32 v1, v15, v11
	v_cvt_pk_bf16_f32 v2, v23, v19
	v_cvt_pk_bf16_f32 v3, v31, v27
	v_lshl_add_u64 v[4:5], v[44:45], 4, s[94:95]
	v_add_u32_e32 v36, s36, v36
	s_or_b64 s[26:27], vcc, s[26:27]
	v_add_u32_e32 v37, s37, v37
	global_store_dwordx4 v[4:5], v[0:3], off
	s_andn2_b64 exec, exec, s[26:27]
	s_cbranch_execz .LBB0_580

.LBB0_582:
	s_or_b64 exec, exec, s[28:29]
	v_readlane_b32 s0, v254, 13
	v_readlane_b32 s1, v254, 14
	v_ashrrev_i32_e32 v37, 31, v36
	v_lshlrev_b64 v[46:47], 9, v[36:37]
	v_lshl_add_u64 v[44:45], v[38:39], 1, s[0:1]
	s_waitcnt vmcnt(0)
	v_cvt_pk_bf16_f32 v38, v4, v0
	v_cvt_pk_bf16_f32 v39, v12, v8
	v_cvt_pk_bf16_f32 v40, v20, v16
	v_cvt_pk_bf16_f32 v41, v28, v24
	v_lshl_add_u64 v[46:47], v[44:45], 0, v[46:47]
	v_add_u32_e32 v0, 1, v36
	global_store_dwordx4 v[46:47], v[38:41], off
	v_add_u32_e32 v4, 3, v36
	v_add_u32_e32 v34, s79, v34
	v_cvt_pk_bf16_f32 v38, v5, v1
	v_ashrrev_i32_e32 v1, 31, v0
	v_lshlrev_b64 v[0:1], 9, v[0:1]
	v_cvt_pk_bf16_f32 v39, v13, v9
	v_cvt_pk_bf16_f32 v40, v21, v17
	v_cvt_pk_bf16_f32 v41, v29, v25
	v_lshl_add_u64 v[0:1], v[44:45], 0, v[0:1]
	global_store_dwordx4 v[0:1], v[38:41], off
	v_add_u32_e32 v0, 2, v36
	v_ashrrev_i32_e32 v1, 31, v0
	v_lshlrev_b64 v[0:1], 9, v[0:1]
	v_ashrrev_i32_e32 v5, 31, v4
	s_movk_i32 s0, 0xbff
	v_cvt_pk_bf16_f32 v38, v6, v2
	v_cvt_pk_bf16_f32 v39, v14, v10
	v_cvt_pk_bf16_f32 v40, v22, v18
	v_cvt_pk_bf16_f32 v41, v30, v26
	v_lshl_add_u64 v[0:1], v[44:45], 0, v[0:1]
	v_lshlrev_b64 v[4:5], 9, v[4:5]
	v_cmp_lt_i32_e32 vcc, s0, v34
	global_store_dwordx4 v[0:1], v[38:41], off
	v_cvt_pk_bf16_f32 v0, v7, v3
	v_cvt_pk_bf16_f32 v1, v15, v11
	v_cvt_pk_bf16_f32 v2, v23, v19
	v_cvt_pk_bf16_f32 v3, v31, v27
	v_lshl_add_u64 v[4:5], v[44:45], 0, v[4:5]
	s_or_b64 s[26:27], vcc, s[26:27]
	v_add_u32_e32 v32, s30, v32
	global_store_dwordx4 v[4:5], v[0:3], off
	s_andn2_b64 exec, exec, s[26:27]
	s_cbranch_execz .LBB0_607

.LBB0_609:
	s_or_b64 exec, exec, s[28:29]
	v_readlane_b32 s0, v254, 15
	v_readlane_b32 s1, v254, 16
	v_ashrrev_i32_e32 v41, 31, v192
	v_mov_b32_e32 v40, v192
	v_lshl_add_u64 v[38:39], v[32:33], 1, s[0:1]
	v_lshlrev_b64 v[40:41], 8, v[40:41]
	s_waitcnt vmcnt(0)
	v_cvt_pk_bf16_f32 v32, v0, v4
	v_cvt_pk_bf16_f32 v33, v12, v8
	v_cvt_pk_bf16_f32 v34, v20, v16
	v_cvt_pk_bf16_f32 v35, v28, v24
	v_lshl_add_u64 v[40:41], v[38:39], 0, v[40:41]
	v_add_u32_e32 v0, 1, v192
	global_store_dwordx4 v[40:41], v[32:35], off
	v_add_u32_e32 v4, 3, v192
	v_add_u32_e32 v37, s79, v37
	v_cvt_pk_bf16_f32 v32, v1, v5
	v_ashrrev_i32_e32 v1, 31, v0
	v_lshlrev_b64 v[0:1], 8, v[0:1]
	v_cvt_pk_bf16_f32 v33, v13, v9
	v_cvt_pk_bf16_f32 v34, v21, v17
	v_cvt_pk_bf16_f32 v35, v29, v25
	v_lshl_add_u64 v[0:1], v[38:39], 0, v[0:1]
	global_store_dwordx4 v[0:1], v[32:35], off
	v_add_u32_e32 v0, 2, v192
	v_ashrrev_i32_e32 v1, 31, v0
	v_lshlrev_b64 v[0:1], 8, v[0:1]
	v_ashrrev_i32_e32 v5, 31, v4
	s_movk_i32 s0, 0x7ff
	v_cvt_pk_bf16_f32 v32, v2, v6
	v_cvt_pk_bf16_f32 v33, v14, v10
	v_cvt_pk_bf16_f32 v34, v22, v18
	v_cvt_pk_bf16_f32 v35, v30, v26
	v_lshl_add_u64 v[0:1], v[38:39], 0, v[0:1]
	v_lshlrev_b64 v[4:5], 8, v[4:5]
	v_cmp_lt_i32_e32 vcc, s0, v37
	global_store_dwordx4 v[0:1], v[32:35], off
	v_cvt_pk_bf16_f32 v0, v3, v7
	v_cvt_pk_bf16_f32 v1, v15, v11
	v_cvt_pk_bf16_f32 v2, v23, v19
	v_cvt_pk_bf16_f32 v3, v31, v27
	v_lshl_add_u64 v[4:5], v[38:39], 0, v[4:5]
	s_or_b64 s[26:27], vcc, s[26:27]
	v_add_u32_e32 v36, s30, v36
	global_store_dwordx4 v[4:5], v[0:3], off
	s_andn2_b64 exec, exec, s[26:27]
	s_cbranch_execz .LBB0_634

.LBB0_636:
	s_or_b64 exec, exec, s[26:27]
	v_lshlrev_b32_e32 v32, 10, v41
	v_sub_u32_e32 v32, v38, v32
	v_and_b32_e32 v32, 0xffffff80, v32
	v_ashrrev_i32_e32 v33, 1, v41
	v_add_u32_e32 v32, v32, v33
	v_ashrrev_i32_e32 v33, 31, v32
	v_lshlrev_b64 v[44:45], 6, v[32:33]
	v_lshlrev_b32_e32 v32, 5, v41
	v_and_b32_e32 v41, 32, v32
	v_and_b32_e32 v46, 28, v192
	v_or3_b32 v44, v44, v41, v46
	s_waitcnt vmcnt(0)
	v_cvt_pk_bf16_f32 v32, v0, v4
	v_cvt_pk_bf16_f32 v33, v12, v8
	v_cvt_pk_bf16_f32 v34, v20, v16
	v_cvt_pk_bf16_f32 v35, v28, v24
	v_lshl_add_u64 v[46:47], v[44:45], 4, s[20:21]
	global_store_dwordx4 v[46:47], v[32:35], off
	v_or_b32_e32 v0, 1, v44
	v_add_u32_e32 v40, s79, v40
	v_cvt_pk_bf16_f32 v32, v1, v5
	v_mov_b32_e32 v1, v45
	v_cvt_pk_bf16_f32 v33, v13, v9
	v_cvt_pk_bf16_f32 v34, v21, v17
	v_cvt_pk_bf16_f32 v35, v29, v25
	v_lshl_add_u64 v[0:1], v[0:1], 4, s[20:21]
	global_store_dwordx4 v[0:1], v[32:35], off
	v_or_b32_e32 v0, 2, v44
	v_mov_b32_e32 v1, v45
	v_cvt_pk_bf16_f32 v32, v2, v6
	v_cvt_pk_bf16_f32 v33, v14, v10
	v_cvt_pk_bf16_f32 v34, v22, v18
	v_cvt_pk_bf16_f32 v35, v30, v26
	v_lshl_add_u64 v[0:1], v[0:1], 4, s[20:21]
	v_or_b32_e32 v44, 3, v44
	v_cmp_lt_i32_e32 vcc, s55, v40
	global_store_dwordx4 v[0:1], v[32:35], off
	v_cvt_pk_bf16_f32 v0, v3, v7
	v_cvt_pk_bf16_f32 v1, v15, v11
	v_cvt_pk_bf16_f32 v2, v23, v19
	v_cvt_pk_bf16_f32 v3, v31, v27
	v_lshl_add_u64 v[4:5], v[44:45], 4, s[20:21]
	v_add_u32_e32 v39, s28, v39
	s_or_b64 s[24:25], vcc, s[24:25]
	v_add_u32_e32 v38, s29, v38
	global_store_dwordx4 v[4:5], v[0:3], off
	s_andn2_b64 exec, exec, s[24:25]
	s_cbranch_execz .LBB0_655

.LBB0_656:
	s_or_b64 exec, exec, s[26:27]
	v_lshlrev_b32_e32 v32, 10, v39
	v_sub_u32_e32 v32, v37, v32
	v_and_b32_e32 v32, 0xffffff80, v32
	v_ashrrev_i32_e32 v33, 1, v39
	v_add_u32_e32 v32, v32, v33
	v_ashrrev_i32_e32 v33, 31, v32
	v_lshlrev_b64 v[40:41], 6, v[32:33]
	v_lshlrev_b32_e32 v32, 5, v39
	v_and_b32_e32 v39, 32, v32
	v_and_b32_e32 v44, 28, v192
	v_or3_b32 v40, v40, v39, v44
	s_waitcnt vmcnt(0)
	v_cvt_pk_bf16_f32 v32, v0, v4
	v_cvt_pk_bf16_f32 v33, v12, v8
	v_cvt_pk_bf16_f32 v34, v20, v16
	v_cvt_pk_bf16_f32 v35, v28, v24
	v_lshl_add_u64 v[44:45], v[40:41], 4, s[96:97]
	global_store_dwordx4 v[44:45], v[32:35], off
	v_or_b32_e32 v0, 1, v40
	v_add_u32_e32 v38, s79, v38
	v_cvt_pk_bf16_f32 v32, v1, v5
	v_mov_b32_e32 v1, v41
	v_cvt_pk_bf16_f32 v33, v13, v9
	v_cvt_pk_bf16_f32 v34, v21, v17
	v_cvt_pk_bf16_f32 v35, v29, v25
	v_lshl_add_u64 v[0:1], v[0:1], 4, s[96:97]
	global_store_dwordx4 v[0:1], v[32:35], off
	v_or_b32_e32 v0, 2, v40
	v_mov_b32_e32 v1, v41
	v_cvt_pk_bf16_f32 v32, v2, v6
	v_cvt_pk_bf16_f32 v33, v14, v10
	v_cvt_pk_bf16_f32 v34, v22, v18
	v_cvt_pk_bf16_f32 v35, v30, v26
	v_lshl_add_u64 v[0:1], v[0:1], 4, s[96:97]
	v_or_b32_e32 v40, 3, v40
	v_cmp_lt_i32_e32 vcc, s55, v38
	global_store_dwordx4 v[0:1], v[32:35], off
	v_cvt_pk_bf16_f32 v0, v3, v7
	v_cvt_pk_bf16_f32 v1, v15, v11
	v_cvt_pk_bf16_f32 v2, v23, v19
	v_cvt_pk_bf16_f32 v3, v31, v27
	v_lshl_add_u64 v[4:5], v[40:41], 4, s[96:97]
	v_add_u32_e32 v36, s28, v36
	s_or_b64 s[24:25], vcc, s[24:25]
	v_add_u32_e32 v37, s29, v37
	global_store_dwordx4 v[4:5], v[0:3], off
	s_andn2_b64 exec, exec, s[24:25]
	s_cbranch_execz .LBB0_673

.LBB0_676:
	s_or_b64 exec, exec, s[26:27]
	v_readlane_b32 s26, v254, 17
	v_readlane_b32 s27, v254, 18
	v_ashrrev_i32_e32 v41, 31, v192
	v_mov_b32_e32 v40, v192
	v_lshl_add_u64 v[38:39], v[32:33], 1, s[26:27]
	v_lshlrev_b64 v[40:41], 9, v[40:41]
	s_waitcnt vmcnt(0)
	v_cvt_pk_bf16_f32 v32, v0, v4
	v_cvt_pk_bf16_f32 v33, v12, v8
	v_cvt_pk_bf16_f32 v34, v20, v16
	v_cvt_pk_bf16_f32 v35, v28, v24
	v_lshl_add_u64 v[40:41], v[38:39], 0, v[40:41]
	v_add_u32_e32 v0, 1, v192
	global_store_dwordx4 v[40:41], v[32:35], off
	v_add_u32_e32 v4, 3, v192
	v_add_u32_e32 v37, s79, v37
	v_cvt_pk_bf16_f32 v32, v1, v5
	v_ashrrev_i32_e32 v1, 31, v0
	v_lshlrev_b64 v[0:1], 9, v[0:1]
	v_cvt_pk_bf16_f32 v33, v13, v9
	v_cvt_pk_bf16_f32 v34, v21, v17
	v_cvt_pk_bf16_f32 v35, v29, v25
	v_lshl_add_u64 v[0:1], v[38:39], 0, v[0:1]
	global_store_dwordx4 v[0:1], v[32:35], off
	v_add_u32_e32 v0, 2, v192
	v_ashrrev_i32_e32 v1, 31, v0
	v_lshlrev_b64 v[0:1], 9, v[0:1]
	v_ashrrev_i32_e32 v5, 31, v4
	v_cvt_pk_bf16_f32 v32, v2, v6
	v_cvt_pk_bf16_f32 v33, v14, v10
	v_cvt_pk_bf16_f32 v34, v22, v18
	v_cvt_pk_bf16_f32 v35, v30, v26
	v_lshl_add_u64 v[0:1], v[38:39], 0, v[0:1]
	v_lshlrev_b64 v[4:5], 9, v[4:5]
	v_cmp_lt_i32_e32 vcc, s29, v37
	global_store_dwordx4 v[0:1], v[32:35], off
	v_cvt_pk_bf16_f32 v0, v3, v7
	v_cvt_pk_bf16_f32 v1, v15, v11
	v_cvt_pk_bf16_f32 v2, v23, v19
	v_cvt_pk_bf16_f32 v3, v31, v27
	v_lshl_add_u64 v[4:5], v[38:39], 0, v[4:5]
	s_or_b64 s[24:25], vcc, s[24:25]
	v_add_u32_e32 v36, s28, v36
	global_store_dwordx4 v[4:5], v[0:3], off
	s_andn2_b64 exec, exec, s[24:25]
	s_cbranch_execz .LBB0_693

.LBB0_694:
	s_or_b64 exec, exec, s[26:27]
	v_readlane_b32 s2, v254, 19
	v_readlane_b32 s3, v254, 20
	v_ashrrev_i32_e32 v41, 31, v192
	v_mov_b32_e32 v40, v192
	v_lshl_add_u64 v[38:39], v[32:33], 1, s[2:3]
	v_lshlrev_b64 v[40:41], 9, v[40:41]
	s_waitcnt vmcnt(0)
	v_cvt_pk_bf16_f32 v32, v0, v4
	v_cvt_pk_bf16_f32 v33, v12, v8
	v_cvt_pk_bf16_f32 v34, v20, v16
	v_cvt_pk_bf16_f32 v35, v28, v24
	v_lshl_add_u64 v[40:41], v[38:39], 0, v[40:41]
	v_add_u32_e32 v0, 1, v192
	global_store_dwordx4 v[40:41], v[32:35], off
	v_add_u32_e32 v4, 3, v192
	v_add_u32_e32 v36, s79, v36
	v_cvt_pk_bf16_f32 v32, v1, v5
	v_ashrrev_i32_e32 v1, 31, v0
	v_lshlrev_b64 v[0:1], 9, v[0:1]
	v_cvt_pk_bf16_f32 v33, v13, v9
	v_cvt_pk_bf16_f32 v34, v21, v17
	v_cvt_pk_bf16_f32 v35, v29, v25
	v_lshl_add_u64 v[0:1], v[38:39], 0, v[0:1]
	global_store_dwordx4 v[0:1], v[32:35], off
	v_add_u32_e32 v0, 2, v192
	v_ashrrev_i32_e32 v1, 31, v0
	v_lshlrev_b64 v[0:1], 9, v[0:1]
	v_ashrrev_i32_e32 v5, 31, v4
	v_cvt_pk_bf16_f32 v32, v2, v6
	v_cvt_pk_bf16_f32 v33, v14, v10
	v_cvt_pk_bf16_f32 v34, v22, v18
	v_cvt_pk_bf16_f32 v35, v30, v26
	v_lshl_add_u64 v[0:1], v[38:39], 0, v[0:1]
	v_lshlrev_b64 v[4:5], 9, v[4:5]
	v_cmp_lt_i32_e32 vcc, s29, v36
	global_store_dwordx4 v[0:1], v[32:35], off
	v_cvt_pk_bf16_f32 v0, v3, v7
	v_cvt_pk_bf16_f32 v1, v15, v11
	v_cvt_pk_bf16_f32 v2, v23, v19
	v_cvt_pk_bf16_f32 v3, v31, v27
	v_lshl_add_u64 v[4:5], v[38:39], 0, v[4:5]
	s_or_b64 s[24:25], vcc, s[24:25]
	v_add_u32_e32 v43, s28, v43
	global_store_dwordx4 v[4:5], v[0:3], off
	s_andn2_b64 exec, exec, s[24:25]
	s_cbranch_execz .LBB0_516

.LBB0_714:
	v_cmp_lt_i32_e32 vcc, v109, v111
	v_lshlrev_b32_e32 v192, 1, v108
	v_readlane_b32 s76, v254, 37
	v_cndmask_b32_e32 v32, v110, v109, vcc
	v_lshlrev_b32_e32 v32, 2, v32
	ds_bpermute_b32 v32, v32, v34
	v_readlane_b32 s77, v254, 38
	s_waitcnt lgkmcnt(0)
	v_add_f32_e32 v32, v34, v32
	v_div_scale_f32 v33, s[0:1], v32, v32, 1.0
	v_rcp_f32_e32 v34, v33
	v_readlane_b32 s0, v254, 9
	v_readlane_b32 s1, v254, 10
	v_fma_f32 v35, -v33, v34, 1.0
	v_fmac_f32_e32 v34, v35, v34
	v_div_scale_f32 v35, vcc, 1.0, v32, 1.0
	v_mul_f32_e32 v36, v35, v34
	v_fma_f32 v37, -v33, v36, v35
	v_fmac_f32_e32 v36, v37, v34
	v_fma_f32 v33, -v33, v36, v35
	v_div_fmas_f32 v33, v33, v34, v36
	global_load_dwordx4 v[36:39], v[96:97], off offset:1536
	v_div_fixup_f32 v34, v33, v32, 1.0
	v_lshlrev_b64 v[32:33], 11, v[98:99]
	v_lshl_add_u64 v[32:33], s[0:1], 0, v[32:33]
	s_mov_b64 s[0:1], 0x3e38aa3b
	s_mov_b32 s15, s1
	v_lshl_add_u64 v[32:33], v[32:33], 0, s[14:15]
	v_lshl_add_u64 v[32:33], v[32:33], 0, v[192:193]
	s_waitcnt vmcnt(0)
	v_mov_b32_e32 v35, v38
	s_nop 1
	v_permlane32_swap_b32_e32 v36, v35
	v_lshlrev_b32_e32 v41, 16, v36
	v_and_b32_e32 v36, 0xffff0000, v36
	v_mov_b32_e32 v40, v39
	v_mul_f32_e32 v38, 0xbfb8aa3b, v41
	v_mul_f32_e32 v39, 0xbfb8aa3b, v36
	v_exp_f32_e32 v38, v38
	v_exp_f32_e32 v39, v39
	v_permlane32_swap_b32_e32 v37, v40
	v_pk_mul_f32 v[16:17], v[16:17], v[34:35] op_sel_hi:[1,0]
	v_pk_add_f32 v[38:39], v[38:39], 1.0 op_sel_hi:[1,0]
	v_pk_mul_f32 v[18:19], v[18:19], v[34:35] op_sel_hi:[1,0]
	v_div_scale_f32 v42, s[0:1], v39, v39, v36
	v_rcp_f32_e32 v43, v42
	s_nop 0
	v_fma_f32 v44, -v42, v43, 1.0
	v_fmac_f32_e32 v43, v44, v43
	v_div_scale_f32 v44, vcc, v36, v39, v36
	v_mul_f32_e32 v45, v44, v43
	v_fma_f32 v46, -v42, v45, v44
	v_fmac_f32_e32 v45, v46, v43
	v_fma_f32 v42, -v42, v45, v44
	v_div_fmas_f32 v42, v42, v43, v45
	v_div_fixup_f32 v39, v42, v39, v36
	v_div_scale_f32 v36, s[0:1], v38, v38, v41
	v_rcp_f32_e32 v42, v36
	s_nop 0
	v_fma_f32 v43, -v36, v42, 1.0
	v_fmac_f32_e32 v42, v43, v42
	v_div_scale_f32 v43, vcc, v41, v38, v41
	v_mul_f32_e32 v44, v43, v42
	v_fma_f32 v45, -v36, v44, v43
	v_fmac_f32_e32 v44, v45, v42
	v_fma_f32 v36, -v36, v44, v43
	v_div_fmas_f32 v36, v36, v42, v44
	v_div_fixup_f32 v38, v36, v38, v41
	v_pk_mul_f32 v[16:17], v[16:17], v[38:39]
	v_lshlrev_b32_e32 v38, 16, v37
	v_and_b32_e32 v39, 0xffff0000, v37
	v_mul_f32_e32 v36, 0xbfb8aa3b, v38
	v_mul_f32_e32 v37, 0xbfb8aa3b, v39
	v_exp_f32_e32 v36, v36
	v_exp_f32_e32 v37, v37
	v_cvt_pk_bf16_f32 v16, v16, v17
	v_pk_add_f32 v[36:37], v[36:37], 1.0 op_sel_hi:[1,0]
	s_nop 0
	v_div_scale_f32 v41, s[0:1], v37, v37, v39
	v_rcp_f32_e32 v42, v41
	s_nop 0
	v_fma_f32 v43, -v41, v42, 1.0
	v_fmac_f32_e32 v42, v43, v42
	v_div_scale_f32 v43, vcc, v39, v37, v39
	v_mul_f32_e32 v44, v43, v42
	v_fma_f32 v45, -v41, v44, v43
	v_fmac_f32_e32 v44, v45, v42
	v_fma_f32 v41, -v41, v44, v43
	v_div_fmas_f32 v41, v41, v42, v44
	v_div_fixup_f32 v37, v41, v37, v39
	v_div_scale_f32 v39, s[0:1], v36, v36, v38
	v_rcp_f32_e32 v41, v39
	s_nop 0
	v_fma_f32 v42, -v39, v41, 1.0
	v_fmac_f32_e32 v41, v42, v41
	v_div_scale_f32 v42, vcc, v38, v36, v38
	v_mul_f32_e32 v43, v42, v41
	v_fma_f32 v44, -v39, v43, v42
	v_fmac_f32_e32 v43, v44, v41
	v_fma_f32 v39, -v39, v43, v42
	v_div_fmas_f32 v39, v39, v41, v43
	v_div_fixup_f32 v36, v39, v36, v38
	v_lshlrev_b32_e32 v38, 16, v35
	v_and_b32_e32 v35, 0xffff0000, v35
	v_pk_mul_f32 v[18:19], v[18:19], v[36:37]
	v_mul_f32_e32 v36, 0xbfb8aa3b, v38
	v_mul_f32_e32 v37, 0xbfb8aa3b, v35
	v_exp_f32_e32 v36, v36
	v_exp_f32_e32 v37, v37
	v_pk_mul_f32 v[20:21], v[20:21], v[34:35] op_sel_hi:[1,0]
	v_cvt_pk_bf16_f32 v17, v18, v19
	v_pk_add_f32 v[36:37], v[36:37], 1.0 op_sel_hi:[1,0]
	s_nop 0
	v_div_scale_f32 v39, s[0:1], v37, v37, v35
	v_rcp_f32_e32 v41, v39
	s_nop 0
	v_fma_f32 v42, -v39, v41, 1.0
	v_fmac_f32_e32 v41, v42, v41
	v_div_scale_f32 v42, vcc, v35, v37, v35
	v_mul_f32_e32 v43, v42, v41
	v_fma_f32 v44, -v39, v43, v42
	v_fmac_f32_e32 v43, v44, v41
	v_fma_f32 v39, -v39, v43, v42
	v_div_fmas_f32 v39, v39, v41, v43
	v_div_fixup_f32 v37, v39, v37, v35
	v_div_scale_f32 v35, s[0:1], v36, v36, v38
	v_rcp_f32_e32 v39, v35
	s_nop 0
	v_fma_f32 v41, -v35, v39, 1.0
	v_fmac_f32_e32 v39, v41, v39
	v_div_scale_f32 v41, vcc, v38, v36, v38
	v_mul_f32_e32 v42, v41, v39
	v_fma_f32 v43, -v35, v42, v41
	v_fmac_f32_e32 v42, v43, v39
	v_fma_f32 v35, -v35, v42, v41
	v_div_fmas_f32 v35, v35, v39, v42
	v_div_fixup_f32 v36, v35, v36, v38
	v_lshlrev_b32_e32 v35, 16, v40
	v_and_b32_e32 v38, 0xffff0000, v40
	v_pk_mul_f32 v[20:21], v[20:21], v[36:37]
	v_mul_f32_e32 v36, 0xbfb8aa3b, v35
	v_mul_f32_e32 v37, 0xbfb8aa3b, v38
	v_exp_f32_e32 v36, v36
	v_exp_f32_e32 v37, v37
	v_pk_mul_f32 v[22:23], v[22:23], v[34:35] op_sel_hi:[1,0]
	v_cvt_pk_bf16_f32 v18, v20, v21
	s_nop 1
	v_permlane32_swap_b32_e32 v16, v18
	v_pk_add_f32 v[36:37], v[36:37], 1.0 op_sel_hi:[1,0]
	s_nop 0
	v_div_scale_f32 v39, s[0:1], v37, v37, v38
	v_rcp_f32_e32 v40, v39
	s_nop 0
	v_fma_f32 v41, -v39, v40, 1.0
	v_fmac_f32_e32 v40, v41, v40
	v_div_scale_f32 v41, vcc, v38, v37, v38
	v_mul_f32_e32 v42, v41, v40
	v_fma_f32 v43, -v39, v42, v41
	v_fmac_f32_e32 v42, v43, v40
	v_fma_f32 v39, -v39, v42, v41
	v_div_fmas_f32 v39, v39, v40, v42
	v_div_fixup_f32 v37, v39, v37, v38
	v_div_scale_f32 v38, s[0:1], v36, v36, v35
	v_rcp_f32_e32 v39, v38
	s_nop 0
	v_fma_f32 v40, -v38, v39, 1.0
	v_fmac_f32_e32 v39, v40, v39
	v_div_scale_f32 v40, vcc, v35, v36, v35
	v_mul_f32_e32 v41, v40, v39
	v_fma_f32 v42, -v38, v41, v40
	v_fmac_f32_e32 v41, v42, v39
	v_fma_f32 v38, -v38, v41, v40
	v_div_fmas_f32 v38, v38, v39, v41
	v_div_fixup_f32 v36, v38, v36, v35
	v_pk_mul_f32 v[22:23], v[22:23], v[36:37]
	s_nop 0
	v_cvt_pk_bf16_f32 v19, v22, v23
	s_nop 1
	v_permlane32_swap_b32_e32 v17, v19
	global_store_dwordx4 v[32:33], v[16:19], off
	global_load_dwordx4 v[16:19], v[96:97], off offset:1568
	s_waitcnt vmcnt(0)
	v_mov_b32_e32 v22, v18
	s_nop 1
	v_permlane32_swap_b32_e32 v16, v22
	v_lshlrev_b32_e32 v23, 16, v16
	v_and_b32_e32 v16, 0xffff0000, v16
	v_mul_f32_e32 v20, 0xbfb8aa3b, v23
	v_mul_f32_e32 v21, 0xbfb8aa3b, v16
	v_exp_f32_e32 v20, v20
	v_exp_f32_e32 v21, v21
	v_mov_b32_e32 v35, v19
	s_nop 1
	v_permlane32_swap_b32_e32 v17, v35
	v_pk_add_f32 v[20:21], v[20:21], 1.0 op_sel_hi:[1,0]
	v_pk_mul_f32 v[18:19], v[24:25], v[34:35] op_sel_hi:[1,0]
	v_div_scale_f32 v24, s[0:1], v21, v21, v16
	v_rcp_f32_e32 v25, v24
	s_nop 0
	v_fma_f32 v36, -v24, v25, 1.0
	v_fmac_f32_e32 v25, v36, v25
	v_div_scale_f32 v36, vcc, v16, v21, v16
	v_mul_f32_e32 v37, v36, v25
	v_fma_f32 v38, -v24, v37, v36
	v_fmac_f32_e32 v37, v38, v25
	v_fma_f32 v24, -v24, v37, v36
	v_div_fmas_f32 v24, v24, v25, v37
	v_div_fixup_f32 v21, v24, v21, v16
	v_div_scale_f32 v16, s[0:1], v20, v20, v23
	v_rcp_f32_e32 v24, v16
	s_nop 0
	v_fma_f32 v25, -v16, v24, 1.0
	v_fmac_f32_e32 v24, v25, v24
	v_div_scale_f32 v25, vcc, v23, v20, v23
	v_mul_f32_e32 v36, v25, v24
	v_fma_f32 v37, -v16, v36, v25
	v_fmac_f32_e32 v36, v37, v24
	v_fma_f32 v16, -v16, v36, v25
	v_div_fmas_f32 v16, v16, v24, v36
	v_div_fixup_f32 v20, v16, v20, v23
	v_lshlrev_b32_e32 v23, 16, v17
	v_and_b32_e32 v24, 0xffff0000, v17
	v_pk_mul_f32 v[18:19], v[18:19], v[20:21]
	v_mul_f32_e32 v20, 0xbfb8aa3b, v23
	v_mul_f32_e32 v21, 0xbfb8aa3b, v24
	v_exp_f32_e32 v20, v20
	v_exp_f32_e32 v21, v21
	v_pk_mul_f32 v[16:17], v[26:27], v[34:35] op_sel_hi:[1,0]
	v_pk_add_f32 v[20:21], v[20:21], 1.0 op_sel_hi:[1,0]
	s_nop 0
	v_div_scale_f32 v25, s[0:1], v21, v21, v24
	v_rcp_f32_e32 v26, v25
	s_nop 0
	v_fma_f32 v27, -v25, v26, 1.0
	v_fmac_f32_e32 v26, v27, v26
	v_div_scale_f32 v27, vcc, v24, v21, v24
	v_mul_f32_e32 v36, v27, v26
	v_fma_f32 v37, -v25, v36, v27
	v_fmac_f32_e32 v36, v37, v26
	v_fma_f32 v25, -v25, v36, v27
	v_div_fmas_f32 v25, v25, v26, v36
	v_div_fixup_f32 v21, v25, v21, v24
	v_div_scale_f32 v24, s[0:1], v20, v20, v23
	v_rcp_f32_e32 v25, v24
	s_nop 0
	v_fma_f32 v26, -v24, v25, 1.0
	v_fmac_f32_e32 v25, v26, v25
	v_div_scale_f32 v26, vcc, v23, v20, v23
	v_mul_f32_e32 v27, v26, v25
	v_fma_f32 v36, -v24, v27, v26
	v_fmac_f32_e32 v27, v36, v25
	v_fma_f32 v24, -v24, v27, v26
	v_div_fmas_f32 v24, v24, v25, v27
	v_div_fixup_f32 v20, v24, v20, v23
	v_lshlrev_b32_e32 v24, 16, v22
	v_and_b32_e32 v25, 0xffff0000, v22
	v_mul_f32_e32 v22, 0xbfb8aa3b, v24
	v_mul_f32_e32 v23, 0xbfb8aa3b, v25
	v_exp_f32_e32 v22, v22
	v_exp_f32_e32 v23, v23
	v_pk_mul_f32 v[20:21], v[16:17], v[20:21]
	v_pk_mul_f32 v[16:17], v[28:29], v[34:35] op_sel_hi:[1,0]
	v_pk_add_f32 v[22:23], v[22:23], 1.0 op_sel_hi:[1,0]
	s_nop 0
	v_div_scale_f32 v26, s[0:1], v23, v23, v25
	v_rcp_f32_e32 v27, v26
	s_nop 0
	v_fma_f32 v28, -v26, v27, 1.0
	v_fmac_f32_e32 v27, v28, v27
	v_div_scale_f32 v28, vcc, v25, v23, v25
	v_mul_f32_e32 v29, v28, v27
	v_fma_f32 v36, -v26, v29, v28
	v_fmac_f32_e32 v29, v36, v27
	v_fma_f32 v26, -v26, v29, v28
	v_div_fmas_f32 v26, v26, v27, v29
	v_div_fixup_f32 v23, v26, v23, v25
	v_div_scale_f32 v25, s[0:1], v22, v22, v24
	v_rcp_f32_e32 v26, v25
	s_nop 0
	v_fma_f32 v27, -v25, v26, 1.0
	v_fmac_f32_e32 v26, v27, v26
	v_div_scale_f32 v27, vcc, v24, v22, v24
	v_mul_f32_e32 v28, v27, v26
	v_fma_f32 v29, -v25, v28, v27
	v_fmac_f32_e32 v28, v29, v26
	v_fma_f32 v25, -v25, v28, v27
	v_div_fmas_f32 v25, v25, v26, v28
	v_lshlrev_b32_e32 v26, 16, v35
	v_and_b32_e32 v27, 0xffff0000, v35
	v_div_fixup_f32 v22, v25, v22, v24
	v_mul_f32_e32 v24, 0xbfb8aa3b, v26
	v_mul_f32_e32 v25, 0xbfb8aa3b, v27
	v_exp_f32_e32 v24, v24
	v_exp_f32_e32 v25, v25
	v_pk_mul_f32 v[22:23], v[16:17], v[22:23]
	v_pk_mul_f32 v[16:17], v[30:31], v[34:35] op_sel_hi:[1,0]
	v_pk_add_f32 v[24:25], v[24:25], 1.0 op_sel_hi:[1,0]
	s_nop 0
	v_div_scale_f32 v28, s[0:1], v25, v25, v27
	v_rcp_f32_e32 v29, v28
	s_nop 0
	v_fma_f32 v30, -v28, v29, 1.0
	v_fmac_f32_e32 v29, v30, v29
	v_div_scale_f32 v30, vcc, v27, v25, v27
	v_mul_f32_e32 v31, v30, v29
	v_fma_f32 v35, -v28, v31, v30
	v_fmac_f32_e32 v31, v35, v29
	v_fma_f32 v28, -v28, v31, v30
	v_div_fmas_f32 v28, v28, v29, v31
	v_div_fixup_f32 v25, v28, v25, v27
	v_div_scale_f32 v27, s[0:1], v24, v24, v26
	v_rcp_f32_e32 v28, v27
	v_pk_mul_f32 v[0:1], v[0:1], v[34:35] op_sel_hi:[1,0]
	v_pk_mul_f32 v[2:3], v[2:3], v[34:35] op_sel_hi:[1,0]
	v_pk_mul_f32 v[4:5], v[4:5], v[34:35] op_sel_hi:[1,0]
	v_fma_f32 v29, -v27, v28, 1.0
	v_fmac_f32_e32 v28, v29, v28
	v_div_scale_f32 v29, vcc, v26, v24, v26
	v_mul_f32_e32 v30, v29, v28
	v_fma_f32 v31, -v27, v30, v29
	v_fmac_f32_e32 v30, v31, v28
	v_fma_f32 v27, -v27, v30, v29
	v_div_fmas_f32 v27, v27, v28, v30
	v_div_fixup_f32 v24, v27, v24, v26
	v_pk_mul_f32 v[24:25], v[16:17], v[24:25]
	v_cvt_pk_bf16_f32 v16, v18, v19
	v_cvt_pk_bf16_f32 v17, v20, v21
	v_cvt_pk_bf16_f32 v18, v22, v23
	v_cvt_pk_bf16_f32 v19, v24, v25
	s_nop 0
	v_permlane32_swap_b32_e32 v16, v18
	v_permlane32_swap_b32_e32 v17, v19
	global_store_dwordx4 v[32:33], v[16:19], off offset:32
	global_load_dwordx4 v[16:19], v[96:97], off offset:1600
	v_pk_mul_f32 v[6:7], v[6:7], v[34:35] op_sel_hi:[1,0]
	s_waitcnt vmcnt(0)
	v_mov_b32_e32 v20, v18
	s_nop 1
	v_permlane32_swap_b32_e32 v16, v20
	v_lshlrev_b32_e32 v22, 16, v16
	v_and_b32_e32 v16, 0xffff0000, v16
	v_mov_b32_e32 v21, v19
	v_mul_f32_e32 v18, 0xbfb8aa3b, v22
	v_mul_f32_e32 v19, 0xbfb8aa3b, v16
	v_exp_f32_e32 v18, v18
	v_exp_f32_e32 v19, v19
	v_permlane32_swap_b32_e32 v17, v21
	v_pk_add_f32 v[18:19], v[18:19], 1.0 op_sel_hi:[1,0]
	s_nop 0
	v_div_scale_f32 v23, s[0:1], v19, v19, v16
	v_rcp_f32_e32 v24, v23
	s_nop 0
	v_fma_f32 v25, -v23, v24, 1.0
	v_fmac_f32_e32 v24, v25, v24
	v_div_scale_f32 v25, vcc, v16, v19, v16
	v_mul_f32_e32 v26, v25, v24
	v_fma_f32 v27, -v23, v26, v25
	v_fmac_f32_e32 v26, v27, v24
	v_fma_f32 v23, -v23, v26, v25
	v_div_fmas_f32 v23, v23, v24, v26
	v_div_fixup_f32 v19, v23, v19, v16
	v_div_scale_f32 v16, s[0:1], v18, v18, v22
	v_rcp_f32_e32 v23, v16
	s_nop 0
	v_fma_f32 v24, -v16, v23, 1.0
	v_fmac_f32_e32 v23, v24, v23
	v_div_scale_f32 v24, vcc, v22, v18, v22
	v_mul_f32_e32 v25, v24, v23
	v_fma_f32 v26, -v16, v25, v24
	v_fmac_f32_e32 v25, v26, v23
	v_fma_f32 v16, -v16, v25, v24
	v_div_fmas_f32 v16, v16, v23, v25
	v_div_fixup_f32 v18, v16, v18, v22
	v_pk_mul_f32 v[0:1], v[0:1], v[18:19]
	v_lshlrev_b32_e32 v18, 16, v17
	v_and_b32_e32 v19, 0xffff0000, v17
	v_mul_f32_e32 v16, 0xbfb8aa3b, v18
	v_mul_f32_e32 v17, 0xbfb8aa3b, v19
	v_exp_f32_e32 v16, v16
	v_exp_f32_e32 v17, v17
	v_cvt_pk_bf16_f32 v0, v0, v1
	v_pk_add_f32 v[16:17], v[16:17], 1.0 op_sel_hi:[1,0]
	s_nop 0
	v_div_scale_f32 v22, s[0:1], v17, v17, v19
	v_rcp_f32_e32 v23, v22
	s_nop 0
	v_fma_f32 v24, -v22, v23, 1.0
	v_fmac_f32_e32 v23, v24, v23
	v_div_scale_f32 v24, vcc, v19, v17, v19
	v_mul_f32_e32 v25, v24, v23
	v_fma_f32 v26, -v22, v25, v24
	v_fmac_f32_e32 v25, v26, v23
	v_fma_f32 v22, -v22, v25, v24
	v_div_fmas_f32 v22, v22, v23, v25
	v_div_fixup_f32 v17, v22, v17, v19
	v_div_scale_f32 v19, s[0:1], v16, v16, v18
	v_rcp_f32_e32 v22, v19
	s_nop 0
	v_fma_f32 v23, -v19, v22, 1.0
	v_fmac_f32_e32 v22, v23, v22
	v_div_scale_f32 v23, vcc, v18, v16, v18
	v_mul_f32_e32 v24, v23, v22
	v_fma_f32 v25, -v19, v24, v23
	v_fmac_f32_e32 v24, v25, v22
	v_fma_f32 v19, -v19, v24, v23
	v_div_fmas_f32 v19, v19, v22, v24
	v_div_fixup_f32 v16, v19, v16, v18
	v_lshlrev_b32_e32 v18, 16, v20
	v_and_b32_e32 v19, 0xffff0000, v20
	v_pk_mul_f32 v[2:3], v[2:3], v[16:17]
	v_mul_f32_e32 v16, 0xbfb8aa3b, v18
	v_mul_f32_e32 v17, 0xbfb8aa3b, v19
	v_exp_f32_e32 v16, v16
	v_exp_f32_e32 v17, v17
	v_cvt_pk_bf16_f32 v1, v2, v3
	v_pk_add_f32 v[16:17], v[16:17], 1.0 op_sel_hi:[1,0]
	s_nop 0
	v_div_scale_f32 v20, s[0:1], v17, v17, v19
	v_rcp_f32_e32 v22, v20
	s_nop 0
	v_fma_f32 v23, -v20, v22, 1.0
	v_fmac_f32_e32 v22, v23, v22
	v_div_scale_f32 v23, vcc, v19, v17, v19
	v_mul_f32_e32 v24, v23, v22
	v_fma_f32 v25, -v20, v24, v23
	v_fmac_f32_e32 v24, v25, v22
	v_fma_f32 v20, -v20, v24, v23
	v_div_fmas_f32 v20, v20, v22, v24
	v_div_fixup_f32 v17, v20, v17, v19
	v_div_scale_f32 v19, s[0:1], v16, v16, v18
	v_rcp_f32_e32 v20, v19
	s_nop 0
	v_fma_f32 v22, -v19, v20, 1.0
	v_fmac_f32_e32 v20, v22, v20
	v_div_scale_f32 v22, vcc, v18, v16, v18
	v_mul_f32_e32 v23, v22, v20
	v_fma_f32 v24, -v19, v23, v22
	v_fmac_f32_e32 v23, v24, v20
	v_fma_f32 v19, -v19, v23, v22
	v_div_fmas_f32 v19, v19, v20, v23
	v_div_fixup_f32 v16, v19, v16, v18
	v_lshlrev_b32_e32 v18, 16, v21
	v_and_b32_e32 v19, 0xffff0000, v21
	v_pk_mul_f32 v[4:5], v[4:5], v[16:17]
	v_mul_f32_e32 v16, 0xbfb8aa3b, v18
	v_mul_f32_e32 v17, 0xbfb8aa3b, v19
	v_exp_f32_e32 v16, v16
	v_exp_f32_e32 v17, v17
	v_cvt_pk_bf16_f32 v2, v4, v5
	s_nop 1
	v_permlane32_swap_b32_e32 v0, v2
	v_pk_add_f32 v[16:17], v[16:17], 1.0 op_sel_hi:[1,0]
	s_nop 0
	v_div_scale_f32 v20, s[0:1], v17, v17, v19
	v_rcp_f32_e32 v21, v20
	s_nop 0
	v_fma_f32 v22, -v20, v21, 1.0
	v_fmac_f32_e32 v21, v22, v21
	v_div_scale_f32 v22, vcc, v19, v17, v19
	v_mul_f32_e32 v23, v22, v21
	v_fma_f32 v24, -v20, v23, v22
	v_fmac_f32_e32 v23, v24, v21
	v_fma_f32 v20, -v20, v23, v22
	v_div_fmas_f32 v20, v20, v21, v23
	v_div_fixup_f32 v17, v20, v17, v19
	v_div_scale_f32 v19, s[0:1], v16, v16, v18
	v_rcp_f32_e32 v20, v19
	s_nop 0
	v_fma_f32 v21, -v19, v20, 1.0
	v_fmac_f32_e32 v20, v21, v20
	v_div_scale_f32 v21, vcc, v18, v16, v18
	v_mul_f32_e32 v22, v21, v20
	v_fma_f32 v23, -v19, v22, v21
	v_fmac_f32_e32 v22, v23, v20
	v_fma_f32 v19, -v19, v22, v21
	v_div_fmas_f32 v19, v19, v20, v22
	v_div_fixup_f32 v16, v19, v16, v18
	v_pk_mul_f32 v[6:7], v[6:7], v[16:17]
	s_nop 0
	v_cvt_pk_bf16_f32 v3, v6, v7
	s_nop 1
	v_permlane32_swap_b32_e32 v1, v3
	global_store_dwordx4 v[32:33], v[0:3], off offset:64
	global_load_dwordx4 v[0:3], v[96:97], off offset:1632
	s_waitcnt vmcnt(0)
	v_mov_b32_e32 v6, v2
	s_nop 1
	v_permlane32_swap_b32_e32 v0, v6
	v_lshlrev_b32_e32 v7, 16, v0
	v_and_b32_e32 v0, 0xffff0000, v0
	v_mul_f32_e32 v4, 0xbfb8aa3b, v7
	v_mul_f32_e32 v5, 0xbfb8aa3b, v0
	v_exp_f32_e32 v4, v4
	v_exp_f32_e32 v5, v5
	v_mov_b32_e32 v16, v3
	v_pk_mul_f32 v[2:3], v[8:9], v[34:35] op_sel_hi:[1,0]
	s_nop 0
	v_permlane32_swap_b32_e32 v1, v16
	v_pk_add_f32 v[4:5], v[4:5], 1.0 op_sel_hi:[1,0]
	s_nop 0
	v_div_scale_f32 v8, s[0:1], v5, v5, v0
	v_rcp_f32_e32 v9, v8
	s_nop 0
	v_fma_f32 v17, -v8, v9, 1.0
	v_fmac_f32_e32 v9, v17, v9
	v_div_scale_f32 v17, vcc, v0, v5, v0
	v_mul_f32_e32 v18, v17, v9
	v_fma_f32 v19, -v8, v18, v17
	v_fmac_f32_e32 v18, v19, v9
	v_fma_f32 v8, -v8, v18, v17
	v_div_fmas_f32 v8, v8, v9, v18
	v_div_fixup_f32 v5, v8, v5, v0
	v_div_scale_f32 v0, s[0:1], v4, v4, v7
	v_rcp_f32_e32 v8, v0
	s_nop 0
	v_fma_f32 v9, -v0, v8, 1.0
	v_fmac_f32_e32 v8, v9, v8
	v_div_scale_f32 v9, vcc, v7, v4, v7
	v_mul_f32_e32 v17, v9, v8
	v_fma_f32 v18, -v0, v17, v9
	v_fmac_f32_e32 v17, v18, v8
	v_fma_f32 v0, -v0, v17, v9
	v_div_fmas_f32 v0, v0, v8, v17
	v_div_fixup_f32 v4, v0, v4, v7
	v_lshlrev_b32_e32 v7, 16, v1
	v_and_b32_e32 v8, 0xffff0000, v1
	v_pk_mul_f32 v[2:3], v[2:3], v[4:5]
	v_mul_f32_e32 v4, 0xbfb8aa3b, v7
	v_mul_f32_e32 v5, 0xbfb8aa3b, v8
	v_exp_f32_e32 v4, v4
	v_exp_f32_e32 v5, v5
	v_pk_mul_f32 v[0:1], v[10:11], v[34:35] op_sel_hi:[1,0]
	v_pk_add_f32 v[4:5], v[4:5], 1.0 op_sel_hi:[1,0]
	s_nop 0
	v_div_scale_f32 v9, s[0:1], v5, v5, v8
	v_rcp_f32_e32 v10, v9
	s_nop 0
	v_fma_f32 v11, -v9, v10, 1.0
	v_fmac_f32_e32 v10, v11, v10
	v_div_scale_f32 v11, vcc, v8, v5, v8
	v_mul_f32_e32 v17, v11, v10
	v_fma_f32 v18, -v9, v17, v11
	v_fmac_f32_e32 v17, v18, v10
	v_fma_f32 v9, -v9, v17, v11
	v_div_fmas_f32 v9, v9, v10, v17
	v_div_fixup_f32 v5, v9, v5, v8
	v_div_scale_f32 v8, s[0:1], v4, v4, v7
	v_rcp_f32_e32 v9, v8
	s_nop 0
	v_fma_f32 v10, -v8, v9, 1.0
	v_fmac_f32_e32 v9, v10, v9
	v_div_scale_f32 v10, vcc, v7, v4, v7
	v_mul_f32_e32 v11, v10, v9
	v_fma_f32 v17, -v8, v11, v10
	v_fmac_f32_e32 v11, v17, v9
	v_fma_f32 v8, -v8, v11, v10
	v_div_fmas_f32 v8, v8, v9, v11
	v_div_fixup_f32 v4, v8, v4, v7
	v_lshlrev_b32_e32 v8, 16, v6
	v_and_b32_e32 v9, 0xffff0000, v6
	v_mul_f32_e32 v6, 0xbfb8aa3b, v8
	v_mul_f32_e32 v7, 0xbfb8aa3b, v9
	v_exp_f32_e32 v6, v6
	v_exp_f32_e32 v7, v7
	v_pk_mul_f32 v[4:5], v[0:1], v[4:5]
	v_pk_mul_f32 v[0:1], v[12:13], v[34:35] op_sel_hi:[1,0]
	v_pk_add_f32 v[6:7], v[6:7], 1.0 op_sel_hi:[1,0]
	s_nop 0
	v_div_scale_f32 v10, s[0:1], v7, v7, v9
	v_rcp_f32_e32 v11, v10
	s_nop 0
	v_fma_f32 v12, -v10, v11, 1.0
	v_fmac_f32_e32 v11, v12, v11
	v_div_scale_f32 v12, vcc, v9, v7, v9
	v_mul_f32_e32 v13, v12, v11
	v_fma_f32 v17, -v10, v13, v12
	v_fmac_f32_e32 v13, v17, v11
	v_fma_f32 v10, -v10, v13, v12
	v_div_fmas_f32 v10, v10, v11, v13
	v_div_fixup_f32 v7, v10, v7, v9
	v_div_scale_f32 v9, s[0:1], v6, v6, v8
	v_rcp_f32_e32 v10, v9
	s_nop 0
	v_fma_f32 v11, -v9, v10, 1.0
	v_fmac_f32_e32 v10, v11, v10
	v_div_scale_f32 v11, vcc, v8, v6, v8
	v_mul_f32_e32 v12, v11, v10
	v_fma_f32 v13, -v9, v12, v11
	v_fmac_f32_e32 v12, v13, v10
	v_fma_f32 v9, -v9, v12, v11
	v_div_fmas_f32 v9, v9, v10, v12
	v_lshlrev_b32_e32 v10, 16, v16
	v_and_b32_e32 v11, 0xffff0000, v16
	v_div_fixup_f32 v6, v9, v6, v8
	v_mul_f32_e32 v8, 0xbfb8aa3b, v10
	v_mul_f32_e32 v9, 0xbfb8aa3b, v11
	v_exp_f32_e32 v8, v8
	v_exp_f32_e32 v9, v9
	v_pk_mul_f32 v[6:7], v[0:1], v[6:7]
	v_pk_mul_f32 v[0:1], v[14:15], v[34:35] op_sel_hi:[1,0]
	v_pk_add_f32 v[8:9], v[8:9], 1.0 op_sel_hi:[1,0]
	s_nop 0
	v_div_scale_f32 v12, s[0:1], v9, v9, v11
	v_rcp_f32_e32 v13, v12
	s_nop 0
	v_fma_f32 v14, -v12, v13, 1.0
	v_fmac_f32_e32 v13, v14, v13
	v_div_scale_f32 v14, vcc, v11, v9, v11
	v_mul_f32_e32 v15, v14, v13
	v_fma_f32 v16, -v12, v15, v14
	v_fmac_f32_e32 v15, v16, v13
	v_fma_f32 v12, -v12, v15, v14
	v_div_fmas_f32 v12, v12, v13, v15
	v_div_fixup_f32 v9, v12, v9, v11
	v_div_scale_f32 v11, s[0:1], v8, v8, v10
	v_rcp_f32_e32 v12, v11
	s_nop 0
	v_fma_f32 v13, -v11, v12, 1.0
	v_fmac_f32_e32 v12, v13, v12
	v_div_scale_f32 v13, vcc, v10, v8, v10
	v_mul_f32_e32 v14, v13, v12
	v_fma_f32 v15, -v11, v14, v13
	v_fmac_f32_e32 v14, v15, v12
	v_fma_f32 v11, -v11, v14, v13
	v_div_fmas_f32 v11, v11, v12, v14
	v_div_fixup_f32 v8, v11, v8, v10
	v_pk_mul_f32 v[8:9], v[0:1], v[8:9]
	v_cvt_pk_bf16_f32 v0, v2, v3
	v_cvt_pk_bf16_f32 v1, v4, v5
	v_cvt_pk_bf16_f32 v2, v6, v7
	v_cvt_pk_bf16_f32 v3, v8, v9
	s_nop 0
	v_permlane32_swap_b32_e32 v0, v2
	v_permlane32_swap_b32_e32 v1, v3
	global_store_dwordx4 v[32:33], v[0:3], off offset:96

.LBB0_723:
	v_add_u32_e32 v2, s10, v0
	v_add_u32_e32 v2, 0xfff10100, v2
	v_ashrrev_i32_e32 v20, 2, v2
	v_and_b32_e32 v4, 12, v1
	v_mov_b64_e32 v[2:3], s[14:15]
	v_mad_i64_i32 v[2:3], s[12:13], v20, s16, v[2:3]
	v_lshlrev_b32_e32 v192, 1, v4
	v_lshl_add_u64 v[2:3], v[2:3], 0, v[192:193]
	v_add_co_u32_e32 v2, vcc, 0x1000, v2
	v_lshlrev_b32_e32 v8, 2, v4
	s_nop 0
	v_addc_co_u32_e32 v3, vcc, 0, v3, vcc
	global_load_dwordx2 v[10:11], v[2:3], off offset:3072
	global_load_dwordx2 v[12:13], v[2:3], off offset:3104
	v_lshlrev_b32_e32 v2, 4, v20
	v_ashrrev_i32_e32 v3, 31, v2
	v_lshlrev_b64 v[6:7], 2, v[2:3]
	v_lshl_add_u64 v[2:3], s[24:25], 0, v[6:7]
	v_mov_b32_e32 v9, v193
	v_lshl_add_u64 v[6:7], s[26:27], 0, v[6:7]
	v_lshl_add_u64 v[2:3], v[2:3], 0, v[8:9]
	v_lshl_add_u64 v[6:7], v[6:7], 0, v[8:9]
	global_load_dwordx4 v[2:5], v[2:3], off
	s_mov_b32 s11, 0xbdd0000
	global_load_dwordx4 v[6:9], v[6:7], off
	v_add_u32_e32 v0, 0x100, v0
	v_add_u32_e32 v1, 0x400, v1
	s_waitcnt vmcnt(3) lgkmcnt(0)
	v_lshlrev_b32_e32 v14, 16, v10
	s_waitcnt vmcnt(2)
	v_lshlrev_b32_e32 v16, 16, v12
	v_and_b32_e32 v17, 0xffff0000, v12
	v_and_b32_e32 v15, 0xffff0000, v10
	v_lshlrev_b32_e32 v12, 16, v13
	v_and_b32_e32 v13, 0xffff0000, v13
	s_waitcnt vmcnt(0)
	v_pk_mul_f32 v[18:19], v[6:7], v[16:17]
	s_nop 0
	v_pk_fma_f32 v[18:19], v[2:3], v[14:15], v[18:19] neg_lo:[0,0,1] neg_hi:[0,0,1]
	v_pk_mul_f32 v[2:3], v[2:3], v[16:17]
	v_cvt_pk_bf16_f32 v10, v18, v19
	v_pk_fma_f32 v[2:3], v[6:7], v[14:15], v[2:3]
	v_lshlrev_b32_e32 v6, 16, v11
	v_and_b32_e32 v7, 0xffff0000, v11
	v_pk_mul_f32 v[14:15], v[8:9], v[12:13]
	v_cvt_pk_bf16_f32 v2, v2, v3
	v_pk_fma_f32 v[14:15], v[4:5], v[6:7], v[14:15] neg_lo:[0,0,1] neg_hi:[0,0,1]
	v_pk_mul_f32 v[4:5], v[4:5], v[12:13]
	v_cvt_pk_bf16_f32 v11, v14, v15
	v_pk_fma_f32 v[4:5], v[8:9], v[6:7], v[4:5]
	s_nop 0
	v_cvt_pk_bf16_f32 v3, v4, v5
	v_mov_b64_e32 v[4:5], s[52:53]
	v_mad_i64_i32 v[4:5], s[12:13], v20, s17, v[4:5]
	v_lshl_add_u64 v[4:5], v[4:5], 0, v[192:193]
	s_mov_b64 s[12:13], 0xbdd0080
	v_add_co_u32_e32 v8, vcc, s11, v4
	v_lshl_add_u64 v[6:7], v[4:5], 0, s[12:13]
	s_nop 0
	v_addc_co_u32_e32 v9, vcc, 0, v5, vcc
	s_mov_b64 s[12:13], 0xbdd0140
	s_movk_i32 s11, 0x2ff
	global_store_dwordx2 v[8:9], v[10:11], off offset:128
	global_store_dwordx2 v[6:7], v[2:3], off offset:32
	v_lshl_add_u64 v[6:7], v[4:5], 0, s[12:13]
	s_mov_b64 s[12:13], 0xbdd0200
	v_cmp_lt_i32_e32 vcc, s11, v0
	global_store_dwordx2 v[8:9], v[10:11], off offset:320
	global_store_dwordx2 v[6:7], v[2:3], off offset:32
	v_lshl_add_u64 v[6:7], v[4:5], 0, s[12:13]
	s_mov_b64 s[12:13], 0xbdd02c0
	s_or_b64 s[8:9], vcc, s[8:9]
	global_store_dwordx2 v[8:9], v[10:11], off offset:512
	global_store_dwordx2 v[6:7], v[2:3], off offset:32
	v_lshl_add_u64 v[4:5], v[4:5], 0, s[12:13]
	global_store_dwordx2 v[8:9], v[10:11], off offset:704
	global_store_dwordx2 v[4:5], v[2:3], off offset:32
	s_andn2_b64 exec, exec, s[8:9]
	s_cbranch_execnz .LBB0_723

.LBB0_725:
	s_andn2_b64 vcc, exec, s[0:1]
	s_cbranch_vccnz .LBB0_737
	v_readlane_b32 s0, v254, 45
	s_add_i32 s8, s0, 0xfffffe40
	s_lshl_b32 s0, s8, 7
	s_and_b32 s10, s0, 0x3f80
	v_readlane_b32 s0, v254, 25
	v_ashrrev_i32_e32 v2, 1, v198
	v_readlane_b32 s1, v254, 26
	v_and_b32_e32 v3, 1, v198
	v_add_u32_e32 v4, s10, v2
	v_mov_b64_e32 v[0:1], s[0:1]
	v_mad_i64_i32 v[0:1], s[0:1], v4, s16, v[0:1]
	v_lshlrev_b32_e32 v192, 7, v3
	v_lshl_add_u64 v[0:1], v[0:1], 0, v[192:193]
	s_waitcnt lgkmcnt(0)
	s_barrier
	global_load_dwordx4 v[6:9], v[0:1], off
	s_waitcnt vmcnt(0)
	v_lshlrev_b32_e32 v4, 16, v6
	v_mul_f32_e32 v4, v4, v4
	v_and_b32_e32 v5, 0xffff0000, v6
	v_fmac_f32_e32 v4, v5, v5
	v_lshlrev_b32_e32 v5, 16, v7
	v_fmac_f32_e32 v4, v5, v5
	v_and_b32_e32 v5, 0xffff0000, v7
	v_fmac_f32_e32 v4, v5, v5
	v_lshlrev_b32_e32 v5, 16, v8
	v_fmac_f32_e32 v4, v5, v5
	v_and_b32_e32 v5, 0xffff0000, v8
	v_fmac_f32_e32 v4, v5, v5
	v_lshlrev_b32_e32 v5, 16, v9
	v_fmac_f32_e32 v4, v5, v5
	v_and_b32_e32 v5, 0xffff0000, v9
	global_load_dwordx4 v[6:9], v[0:1], off offset:16
	v_fmac_f32_e32 v4, v5, v5
	s_waitcnt vmcnt(0)
	v_lshlrev_b32_e32 v5, 16, v6
	v_fmac_f32_e32 v4, v5, v5
	v_and_b32_e32 v5, 0xffff0000, v6
	v_fmac_f32_e32 v4, v5, v5
	v_lshlrev_b32_e32 v5, 16, v7
	v_fmac_f32_e32 v4, v5, v5
	v_and_b32_e32 v5, 0xffff0000, v7
	v_fmac_f32_e32 v4, v5, v5
	v_lshlrev_b32_e32 v5, 16, v8
	v_fmac_f32_e32 v4, v5, v5
	v_and_b32_e32 v5, 0xffff0000, v8
	v_fmac_f32_e32 v4, v5, v5
	v_lshlrev_b32_e32 v5, 16, v9
	v_fmac_f32_e32 v4, v5, v5
	v_and_b32_e32 v5, 0xffff0000, v9
	global_load_dwordx4 v[6:9], v[0:1], off offset:32
	v_fmac_f32_e32 v4, v5, v5
	s_waitcnt vmcnt(0)
	v_lshlrev_b32_e32 v5, 16, v6
	v_fmac_f32_e32 v4, v5, v5
	v_and_b32_e32 v5, 0xffff0000, v6
	v_fmac_f32_e32 v4, v5, v5
	v_lshlrev_b32_e32 v5, 16, v7
	v_fmac_f32_e32 v4, v5, v5
	v_and_b32_e32 v5, 0xffff0000, v7
	v_fmac_f32_e32 v4, v5, v5
	v_lshlrev_b32_e32 v5, 16, v8
	v_fmac_f32_e32 v4, v5, v5
	v_and_b32_e32 v5, 0xffff0000, v8
	v_fmac_f32_e32 v4, v5, v5
	v_lshlrev_b32_e32 v5, 16, v9
	v_fmac_f32_e32 v4, v5, v5
	v_and_b32_e32 v5, 0xffff0000, v9
	global_load_dwordx4 v[6:9], v[0:1], off offset:48
	v_fmac_f32_e32 v4, v5, v5
	s_waitcnt vmcnt(0)
	v_lshlrev_b32_e32 v5, 16, v6
	v_fmac_f32_e32 v4, v5, v5
	v_and_b32_e32 v5, 0xffff0000, v6
	v_fmac_f32_e32 v4, v5, v5
	v_lshlrev_b32_e32 v5, 16, v7
	v_fmac_f32_e32 v4, v5, v5
	v_and_b32_e32 v5, 0xffff0000, v7
	v_fmac_f32_e32 v4, v5, v5
	v_lshlrev_b32_e32 v5, 16, v8
	v_fmac_f32_e32 v4, v5, v5
	v_and_b32_e32 v5, 0xffff0000, v8
	v_fmac_f32_e32 v4, v5, v5
	v_lshlrev_b32_e32 v5, 16, v9
	v_fmac_f32_e32 v4, v5, v5
	v_and_b32_e32 v5, 0xffff0000, v9
	global_load_dwordx4 v[6:9], v[0:1], off offset:64
	v_fmac_f32_e32 v4, v5, v5
	s_waitcnt vmcnt(0)
	v_lshlrev_b32_e32 v5, 16, v6
	v_fmac_f32_e32 v4, v5, v5
	v_and_b32_e32 v5, 0xffff0000, v6
	v_fmac_f32_e32 v4, v5, v5
	v_lshlrev_b32_e32 v5, 16, v7
	v_fmac_f32_e32 v4, v5, v5
	v_and_b32_e32 v5, 0xffff0000, v7
	v_fmac_f32_e32 v4, v5, v5
	v_lshlrev_b32_e32 v5, 16, v8
	v_fmac_f32_e32 v4, v5, v5
	v_and_b32_e32 v5, 0xffff0000, v8
	v_fmac_f32_e32 v4, v5, v5
	v_lshlrev_b32_e32 v5, 16, v9
	v_fmac_f32_e32 v4, v5, v5
	v_and_b32_e32 v5, 0xffff0000, v9
	global_load_dwordx4 v[6:9], v[0:1], off offset:80
	v_fmac_f32_e32 v4, v5, v5
	s_waitcnt vmcnt(0)
	v_lshlrev_b32_e32 v5, 16, v6
	v_fmac_f32_e32 v4, v5, v5
	v_and_b32_e32 v5, 0xffff0000, v6
	v_fmac_f32_e32 v4, v5, v5
	v_lshlrev_b32_e32 v5, 16, v7
	v_fmac_f32_e32 v4, v5, v5
	v_and_b32_e32 v5, 0xffff0000, v7
	v_fmac_f32_e32 v4, v5, v5
	v_lshlrev_b32_e32 v5, 16, v8
	v_fmac_f32_e32 v4, v5, v5
	v_and_b32_e32 v5, 0xffff0000, v8
	v_fmac_f32_e32 v4, v5, v5
	v_lshlrev_b32_e32 v5, 16, v9
	v_fmac_f32_e32 v4, v5, v5
	v_and_b32_e32 v5, 0xffff0000, v9
	global_load_dwordx4 v[6:9], v[0:1], off offset:96
	v_fmac_f32_e32 v4, v5, v5
	s_waitcnt vmcnt(0)
	v_lshlrev_b32_e32 v5, 16, v6
	v_fmac_f32_e32 v4, v5, v5
	v_and_b32_e32 v5, 0xffff0000, v6
	v_fmac_f32_e32 v4, v5, v5
	v_lshlrev_b32_e32 v5, 16, v7
	v_fmac_f32_e32 v4, v5, v5
	v_and_b32_e32 v5, 0xffff0000, v7
	v_fmac_f32_e32 v4, v5, v5
	v_lshlrev_b32_e32 v5, 16, v8
	v_fmac_f32_e32 v4, v5, v5
	v_and_b32_e32 v5, 0xffff0000, v8
	v_fmac_f32_e32 v4, v5, v5
	v_lshlrev_b32_e32 v5, 16, v9
	v_fmac_f32_e32 v4, v5, v5
	v_and_b32_e32 v5, 0xffff0000, v9
	global_load_dwordx4 v[6:9], v[0:1], off offset:112
	v_fmac_f32_e32 v4, v5, v5
	v_and_b32_e32 v1, 64, v225
	v_add_u32_e32 v1, 64, v1
	s_waitcnt vmcnt(0)
	v_lshlrev_b32_e32 v0, 16, v6
	v_fmac_f32_e32 v4, v0, v0
	v_and_b32_e32 v0, 0xffff0000, v6
	v_fmac_f32_e32 v4, v0, v0
	v_lshlrev_b32_e32 v0, 16, v7
	v_fmac_f32_e32 v4, v0, v0
	v_and_b32_e32 v0, 0xffff0000, v7
	v_fmac_f32_e32 v4, v0, v0
	v_lshlrev_b32_e32 v0, 16, v8
	v_fmac_f32_e32 v4, v0, v0
	v_and_b32_e32 v0, 0xffff0000, v8
	v_fmac_f32_e32 v4, v0, v0
	v_lshlrev_b32_e32 v0, 16, v9
	v_fmac_f32_e32 v4, v0, v0
	v_and_b32_e32 v0, 0xffff0000, v9
	v_fmac_f32_e32 v4, v0, v0
	v_xor_b32_e32 v0, 1, v225
	v_cmp_lt_i32_e32 vcc, v0, v1
	s_nop 1
	v_cndmask_b32_e32 v0, v225, v0, vcc
	v_lshlrev_b32_e32 v0, 2, v0
	ds_bpermute_b32 v0, v0, v4
	v_cmp_eq_u32_e32 vcc, 0, v3
	s_and_saveexec_b64 s[0:1], vcc
	s_movk_i32 s9, 0x90
	s_cbranch_execz .LBB0_728
	s_waitcnt lgkmcnt(0)
	v_add_f32_e32 v0, v4, v0
	v_fmamk_f32 v0, v0, 0x3c000000, v224
	s_mov_b32 s11, 0x800000
	v_mul_f32_e32 v1, 0x4b800000, v0
	v_cmp_gt_f32_e32 vcc, s11, v0
	s_nop 1
	v_cndmask_b32_e32 v0, v0, v1, vcc
	v_rsq_f32_e32 v0, v0
	s_nop 0
	v_mul_f32_e32 v1, 0x45800000, v0
	v_cndmask_b32_e32 v0, v0, v1, vcc
	v_lshl_add_u32 v1, v2, 2, v232
	ds_write_b32 v1, v0
.LBB0_728:
	s_or_b64 exec, exec, s[0:1]
	v_ashrrev_i32_e32 v3, 3, v198
	s_waitcnt lgkmcnt(0)
	v_lshlrev_b32_e32 v0, 4, v198
	v_readlane_b32 s12, v254, 25
	s_and_b32 s0, s8, 0xffffff80
	v_add_u32_e32 v44, s10, v3
	v_and_b32_e32 v192, 0x70, v0
	v_readlane_b32 s13, v254, 26
	v_add_u32_e32 v8, s0, v3
	v_add_u32_e32 v46, 32, v44
	v_lshl_add_u64 v[0:1], s[12:13], 0, v[192:193]
	v_mad_i64_i32 v[4:5], s[0:1], v44, s16, v[0:1]
	v_ashrrev_i32_e32 v9, 31, v8
	v_mad_i64_i32 v[12:13], s[0:1], v46, s16, v[0:1]
	v_lshlrev_b64 v[36:37], 8, v[8:9]
	s_mov_b64 s[0:1], 0x2000
	v_add_u32_e32 v48, 64, v44
	v_readlane_b32 s14, v254, 29
	v_lshl_add_u64 v[38:39], v[36:37], 0, s[0:1]
	v_mad_i64_i32 v[20:21], s[0:1], v48, s16, v[0:1]
	v_readlane_b32 s15, v254, 30
	s_mov_b64 s[0:1], 0x4000
	v_lshl_add_u64 v[40:41], v[36:37], 0, s[0:1]
	v_lshl_add_u64 v[32:33], s[14:15], 0, v[192:193]
	v_add_u32_e32 v50, 0x60, v44
	v_lshl_add_u64 v[8:9], v[32:33], 0, v[36:37]
	v_lshl_add_u64 v[16:17], v[32:33], 0, v[38:39]
	v_lshl_add_u64 v[28:29], v[32:33], 0, v[40:41]
	v_mad_i64_i32 v[0:1], s[0:1], v50, s16, v[0:1]
	global_load_dwordx4 v[4:7], v[4:5], off
	s_mov_b64 s[0:1], 0x6000
	global_load_dwordx4 v[8:11], v[8:9], off
	v_mov_b64_e32 v[42:43], s[12:13]
	global_load_dwordx4 v[12:15], v[12:13], off
	v_lshl_add_u64 v[38:39], s[14:15], 0, v[38:39]
	global_load_dwordx4 v[16:19], v[16:17], off
	v_lshl_add_u64 v[40:41], s[14:15], 0, v[40:41]
	global_load_dwordx4 v[20:23], v[20:21], off
	s_nop 0
	global_load_dwordx4 v[24:27], v[0:1], off
	s_nop 0
	global_load_dwordx4 v[28:31], v[28:29], off
	v_lshl_add_u64 v[0:1], v[36:37], 0, s[0:1]
	v_lshl_add_u64 v[32:33], v[32:33], 0, v[0:1]
	global_load_dwordx4 v[32:35], v[32:33], off
	v_mad_i64_i32 v[44:45], s[0:1], v44, s16, v[42:43]
	v_mad_i64_i32 v[46:47], s[0:1], v46, s16, v[42:43]
	v_mad_i64_i32 v[48:49], s[0:1], v48, s16, v[42:43]
	v_mad_i64_i32 v[42:43], s[0:1], v50, s16, v[42:43]
	v_lshl_add_u64 v[36:37], s[14:15], 0, v[36:37]
	v_lshl_add_u64 v[44:45], v[44:45], 0, v[192:193]
	v_lshl_add_u64 v[42:43], v[42:43], 0, v[192:193]
	v_lshl_add_u64 v[36:37], v[36:37], 0, v[192:193]
	global_load_dwordx4 v[72:75], v[44:45], off offset:128
	global_load_dwordx4 v[84:87], v[42:43], off offset:128
	v_lshl_add_u64 v[44:45], v[46:47], 0, v[192:193]
	v_lshl_add_u64 v[46:47], v[48:49], 0, v[192:193]
	v_lshl_add_u64 v[0:1], s[14:15], 0, v[0:1]
	global_load_dwordx4 v[88:91], v[36:37], off offset:128
	v_lshl_add_u64 v[36:37], v[38:39], 0, v[192:193]
	global_load_dwordx4 v[76:79], v[44:45], off offset:128
	global_load_dwordx4 v[80:83], v[46:47], off offset:128
	v_lshl_add_u64 v[38:39], v[40:41], 0, v[192:193]
	v_lshl_add_u64 v[0:1], v[0:1], 0, v[192:193]
	global_load_dwordx4 v[92:95], v[36:37], off offset:128
	global_load_dwordx4 v[96:99], v[38:39], off offset:128
	global_load_dwordx4 v[100:103], v[0:1], off offset:128
	v_bfe_u32 v70, v198, 5, 1
	v_and_b32_e32 v52, 0x5f, v198
	v_mad_u64_u32 v[66:67], s[0:1], v3, s9, v[192:193]
	v_lshlrev_b32_e32 v192, 4, v70
	v_mad_u32_u24 v116, v52, s9, v192
	v_and_b32_e32 v51, 31, v198
	s_movk_i32 s0, 0xffc0
	v_and_or_b32 v71, v2, s0, v51
	v_mad_u64_u32 v[64:65], s[0:1], v71, s9, v[192:193]
	v_add_u32_e32 v65, 0xd800, v66
	s_lshr_b32 s12, s8, 7
	s_lshl_b32 s11, s12, 6
	s_waitcnt vmcnt(15)
	ds_write_b128 v66, v[4:7]
	s_waitcnt vmcnt(13)
	ds_write_b128 v66, v[12:15] offset:4608
	s_waitcnt vmcnt(11)
	ds_write_b128 v66, v[20:23] offset:9216
	s_waitcnt vmcnt(10)
	ds_write_b128 v66, v[24:27] offset:13824
	ds_write_b128 v66, v[8:11] offset:18432
	ds_write_b128 v66, v[16:19] offset:23040
	s_waitcnt vmcnt(9)
	ds_write_b128 v66, v[28:31] offset:27648
	s_waitcnt vmcnt(8)
	ds_write_b128 v66, v[32:35] offset:32256
	s_waitcnt lgkmcnt(0)
	s_barrier
	ds_read_b128 v[4:7], v116 offset:18432
	ds_read_b128 v[0:3], v64
	ds_read_b128 v[8:11], v64 offset:4608
	s_waitcnt lgkmcnt(1)
	v_mfma_f32_32x32x16_bf16 v[48:63], v[4:7], v[0:3], 0
	s_waitcnt lgkmcnt(0)
	v_mfma_f32_32x32x16_bf16 v[16:31], v[4:7], v[8:11], 0
	ds_read_b128 v[4:7], v116 offset:23040
	ds_read_b128 v[104:107], v116 offset:18464
	ds_read_b128 v[108:111], v64 offset:32
	ds_read_b128 v[112:115], v64 offset:4640
	s_waitcnt lgkmcnt(1)
	v_mfma_f32_32x32x16_bf16 v[48:63], v[104:107], v[108:111], v[48:63]
	s_waitcnt lgkmcnt(0)
	v_mfma_f32_32x32x16_bf16 v[16:31], v[104:107], v[112:115], v[16:31]
	ds_read_b128 v[104:107], v116 offset:23072
	v_mfma_f32_32x32x16_bf16 v[32:47], v[4:7], v[0:3], 0
	v_mfma_f32_32x32x16_bf16 v[0:15], v[4:7], v[8:11], 0
	s_waitcnt lgkmcnt(0)
	v_mfma_f32_32x32x16_bf16 v[32:47], v[104:107], v[108:111], v[32:47]
	v_mfma_f32_32x32x16_bf16 v[0:15], v[104:107], v[112:115], v[0:15]
	ds_read_b128 v[104:107], v116 offset:18496
	ds_read_b128 v[108:111], v64 offset:64
	ds_read_b128 v[112:115], v64 offset:4672
	s_waitcnt lgkmcnt(1)
	v_mfma_f32_32x32x16_bf16 v[48:63], v[104:107], v[108:111], v[48:63]
	s_waitcnt lgkmcnt(0)
	v_mfma_f32_32x32x16_bf16 v[16:31], v[104:107], v[112:115], v[16:31]
	ds_read_b128 v[104:107], v116 offset:23104
	s_waitcnt lgkmcnt(0)
	v_mfma_f32_32x32x16_bf16 v[32:47], v[104:107], v[108:111], v[32:47]
	v_mfma_f32_32x32x16_bf16 v[0:15], v[104:107], v[112:115], v[0:15]
	ds_read_b128 v[104:107], v116 offset:18528
	ds_read_b128 v[108:111], v64 offset:96
	ds_read_b128 v[112:115], v64 offset:4704
	s_waitcnt lgkmcnt(1)
	v_mfma_f32_32x32x16_bf16 v[48:63], v[104:107], v[108:111], v[48:63]
	s_waitcnt lgkmcnt(0)
	v_mfma_f32_32x32x16_bf16 v[16:31], v[104:107], v[112:115], v[16:31]
	ds_read_b128 v[104:107], v116 offset:23136
	s_waitcnt vmcnt(7)
	ds_write_b128 v66, v[72:75] offset:36864
	s_waitcnt vmcnt(5)
	ds_write_b128 v66, v[88:91] offset:55296
	s_waitcnt vmcnt(4)
	ds_write_b128 v66, v[76:79] offset:41472
	s_waitcnt vmcnt(2)
	ds_write_b128 v66, v[92:95] offset:59904
	ds_write_b128 v66, v[80:83] offset:46080
	s_waitcnt vmcnt(1)
	ds_write_b128 v66, v[96:99] offset:64512
	ds_write_b128 v66, v[84:87] offset:50688
	s_waitcnt vmcnt(0)
	ds_write_b128 v65, v[100:103] offset:13824
	s_waitcnt lgkmcnt(0)
	s_barrier
	ds_read_b128 v[66:69], v116 offset:55296
	ds_read_b128 v[72:75], v64 offset:36864
	ds_read_b128 v[76:79], v64 offset:41472
	s_waitcnt lgkmcnt(1)
	v_mfma_f32_32x32x16_bf16 v[48:63], v[66:69], v[72:75], v[48:63]
	s_waitcnt lgkmcnt(0)
	v_mfma_f32_32x32x16_bf16 v[16:31], v[66:69], v[76:79], v[16:31]
	ds_read_b128 v[66:69], v116 offset:59904
	v_mfma_f32_32x32x16_bf16 v[32:47], v[104:107], v[108:111], v[32:47]
	v_mfma_f32_32x32x16_bf16 v[0:15], v[104:107], v[112:115], v[0:15]
	s_waitcnt lgkmcnt(0)
	v_mfma_f32_32x32x16_bf16 v[32:47], v[66:69], v[72:75], v[32:47]
	v_mfma_f32_32x32x16_bf16 v[0:15], v[66:69], v[76:79], v[0:15]
	ds_read_b128 v[66:69], v116 offset:55328
	ds_read_b128 v[72:75], v64 offset:36896
	ds_read_b128 v[76:79], v64 offset:41504
	s_waitcnt lgkmcnt(1)
	v_mfma_f32_32x32x16_bf16 v[48:63], v[66:69], v[72:75], v[48:63]
	s_waitcnt lgkmcnt(0)
	v_mfma_f32_32x32x16_bf16 v[16:31], v[66:69], v[76:79], v[16:31]
	ds_read_b128 v[66:69], v116 offset:59936
	s_waitcnt lgkmcnt(0)
	v_mfma_f32_32x32x16_bf16 v[32:47], v[66:69], v[72:75], v[32:47]
	v_mfma_f32_32x32x16_bf16 v[0:15], v[66:69], v[76:79], v[0:15]
	ds_read_b128 v[66:69], v116 offset:55360
	ds_read_b128 v[72:75], v64 offset:36928
	ds_read_b128 v[76:79], v64 offset:41536
	s_waitcnt lgkmcnt(1)
	v_mfma_f32_32x32x16_bf16 v[48:63], v[66:69], v[72:75], v[48:63]
	s_waitcnt lgkmcnt(0)
	v_mfma_f32_32x32x16_bf16 v[16:31], v[66:69], v[76:79], v[16:31]
	ds_read_b128 v[66:69], v116 offset:59968
	s_waitcnt lgkmcnt(0)
	v_mfma_f32_32x32x16_bf16 v[32:47], v[66:69], v[72:75], v[32:47]
	v_mfma_f32_32x32x16_bf16 v[0:15], v[66:69], v[76:79], v[0:15]
	ds_read_b128 v[66:69], v116 offset:55392
	ds_read_b128 v[72:75], v64 offset:36960
	ds_read_b128 v[76:79], v64 offset:41568
	ds_read_b128 v[80:83], v116 offset:60000
	v_and_b32_e32 v64, 64, v198
	v_cmp_ne_u32_e32 vcc, 0, v64
	v_lshl_add_u32 v64, v71, 2, v232
	s_waitcnt lgkmcnt(0)
	v_mfma_f32_32x32x16_bf16 v[48:63], v[66:69], v[72:75], v[48:63]
	s_barrier
	ds_read_b32 v64, v64
	v_mfma_f32_32x32x16_bf16 v[16:31], v[66:69], v[76:79], v[16:31]
	v_add_u32_e32 v66, s10, v71
	v_ashrrev_i32_e32 v67, 31, v66
	v_mfma_f32_32x32x16_bf16 v[32:47], v[80:83], v[72:75], v[32:47]
	v_mfma_f32_32x32x16_bf16 v[0:15], v[80:83], v[76:79], v[0:15]
	s_and_saveexec_b64 s[0:1], vcc
	s_xor_b64 s[0:1], exec, s[0:1]
	s_cbranch_execz .LBB0_730
	v_readlane_b32 s8, v253, 63
	v_lshlrev_b64 v[66:67], 9, v[66:67]
	v_readlane_b32 s9, v254, 0
	s_mov_b64 s[14:15], 0x3e38aa3b
	s_nop 0
	v_lshl_add_u64 v[66:67], s[8:9], 0, v[66:67]
	s_lshl_b32 s8, s11, 1
	s_mov_b32 s9, s15
	v_lshl_add_u64 v[68:69], v[66:67], 0, s[8:9]

.LBB0_732:
	s_or_b64 exec, exec, s[8:9]
	v_or_b32_e32 v65, 32, v71
	s_waitcnt lgkmcnt(0)
	v_pk_mul_f32 v[48:49], v[48:49], v[64:65] op_sel_hi:[1,0]
	v_pk_mul_f32 v[50:51], v[50:51], v[64:65] op_sel_hi:[1,0]
	v_pk_mul_f32 v[52:53], v[52:53], v[64:65] op_sel_hi:[1,0]
	v_pk_mul_f32 v[54:55], v[54:55], v[64:65] op_sel_hi:[1,0]
	v_pk_mul_f32 v[32:33], v[32:33], v[64:65] op_sel_hi:[1,0]
	v_pk_mul_f32 v[34:35], v[34:35], v[64:65] op_sel_hi:[1,0]
	v_pk_mul_f32 v[36:37], v[36:37], v[64:65] op_sel_hi:[1,0]
	v_pk_mul_f32 v[38:39], v[38:39], v[64:65] op_sel_hi:[1,0]
	v_cvt_pk_bf16_f32 v48, v48, v49
	v_cvt_pk_bf16_f32 v49, v50, v51
	v_cvt_pk_bf16_f32 v50, v52, v53
	v_cvt_pk_bf16_f32 v51, v54, v55
	v_cvt_pk_bf16_f32 v32, v32, v33
	v_cvt_pk_bf16_f32 v33, v34, v35
	v_cvt_pk_bf16_f32 v34, v36, v37
	v_cvt_pk_bf16_f32 v35, v38, v39
	v_lshl_add_u64 v[66:67], v[68:69], 0, v[192:193]
	v_permlane32_swap_b32_e32 v48, v50
	v_permlane32_swap_b32_e32 v49, v51
	v_permlane32_swap_b32_e32 v32, v34
	v_permlane32_swap_b32_e32 v33, v35
	global_store_dwordx4 v[66:67], v[48:51], off
	v_pk_mul_f32 v[52:53], v[60:61], v[64:65] op_sel_hi:[1,0]
	v_pk_mul_f32 v[54:55], v[62:63], v[64:65] op_sel_hi:[1,0]
	v_pk_mul_f32 v[48:49], v[56:57], v[64:65] op_sel_hi:[1,0]
	v_pk_mul_f32 v[50:51], v[58:59], v[64:65] op_sel_hi:[1,0]
	global_store_dwordx4 v[66:67], v[32:35], off offset:64
	v_pk_mul_f32 v[36:37], v[44:45], v[64:65] op_sel_hi:[1,0]
	v_pk_mul_f32 v[38:39], v[46:47], v[64:65] op_sel_hi:[1,0]
	v_pk_mul_f32 v[32:33], v[40:41], v[64:65] op_sel_hi:[1,0]
	v_pk_mul_f32 v[34:35], v[42:43], v[64:65] op_sel_hi:[1,0]
	v_cvt_pk_bf16_f32 v48, v48, v49
	v_cvt_pk_bf16_f32 v49, v50, v51
	v_cvt_pk_bf16_f32 v50, v52, v53
	v_cvt_pk_bf16_f32 v51, v54, v55
	v_cvt_pk_bf16_f32 v32, v32, v33
	v_cvt_pk_bf16_f32 v33, v34, v35
	v_cvt_pk_bf16_f32 v34, v36, v37
	v_cvt_pk_bf16_f32 v35, v38, v39
	v_permlane32_swap_b32_e32 v48, v50
	v_permlane32_swap_b32_e32 v49, v51
	v_permlane32_swap_b32_e32 v32, v34
	v_permlane32_swap_b32_e32 v33, v35
	global_store_dwordx4 v[66:67], v[48:51], off offset:32
	global_store_dwordx4 v[66:67], v[32:35], off offset:96
	v_add_u32_e32 v36, s10, v65
	v_ashrrev_i32_e32 v37, 31, v36
	v_lshl_add_u32 v32, v65, 2, v232
	ds_read_b32 v32, v32
	s_and_saveexec_b64 s[8:9], vcc
	s_xor_b64 s[8:9], exec, s[8:9]
	s_cbranch_execz .LBB0_734
	v_readlane_b32 s12, v253, 63
	v_lshlrev_b64 v[34:35], 9, v[36:37]
	v_readlane_b32 s13, v254, 0
	s_lshl_b32 s10, s11, 1
	s_nop 0
	v_lshl_add_u64 v[34:35], s[12:13], 0, v[34:35]
	s_mov_b64 s[12:13], 0x3e38aa3b
	s_mov_b32 s11, s13
	v_lshl_add_u64 v[34:35], v[34:35], 0, s[10:11]

.LBB0_736:
	s_or_b64 exec, exec, s[8:9]
	v_lshlrev_b32_e32 v33, 3, v70
	s_waitcnt lgkmcnt(0)
	v_pk_mul_f32 v[16:17], v[16:17], v[32:33] op_sel_hi:[1,0]
	v_pk_mul_f32 v[18:19], v[18:19], v[32:33] op_sel_hi:[1,0]
	v_pk_mul_f32 v[20:21], v[20:21], v[32:33] op_sel_hi:[1,0]
	v_pk_mul_f32 v[22:23], v[22:23], v[32:33] op_sel_hi:[1,0]
	v_pk_mul_f32 v[0:1], v[0:1], v[32:33] op_sel_hi:[1,0]
	v_pk_mul_f32 v[2:3], v[2:3], v[32:33] op_sel_hi:[1,0]
	v_pk_mul_f32 v[4:5], v[4:5], v[32:33] op_sel_hi:[1,0]
	v_pk_mul_f32 v[6:7], v[6:7], v[32:33] op_sel_hi:[1,0]
	v_lshlrev_b32_e32 v192, 1, v33
	v_cvt_pk_bf16_f32 v16, v16, v17
	v_cvt_pk_bf16_f32 v17, v18, v19
	v_cvt_pk_bf16_f32 v18, v20, v21
	v_cvt_pk_bf16_f32 v19, v22, v23
	v_cvt_pk_bf16_f32 v0, v0, v1
	v_cvt_pk_bf16_f32 v1, v2, v3
	v_cvt_pk_bf16_f32 v2, v4, v5
	v_cvt_pk_bf16_f32 v3, v6, v7
	v_lshl_add_u64 v[34:35], v[34:35], 0, v[192:193]
	v_permlane32_swap_b32_e32 v16, v18
	v_permlane32_swap_b32_e32 v17, v19
	v_permlane32_swap_b32_e32 v0, v2
	v_permlane32_swap_b32_e32 v1, v3
	global_store_dwordx4 v[34:35], v[16:19], off
	v_pk_mul_f32 v[20:21], v[28:29], v[32:33] op_sel_hi:[1,0]
	v_pk_mul_f32 v[22:23], v[30:31], v[32:33] op_sel_hi:[1,0]
	v_pk_mul_f32 v[16:17], v[24:25], v[32:33] op_sel_hi:[1,0]
	v_pk_mul_f32 v[18:19], v[26:27], v[32:33] op_sel_hi:[1,0]
	global_store_dwordx4 v[34:35], v[0:3], off offset:64
	v_pk_mul_f32 v[4:5], v[12:13], v[32:33] op_sel_hi:[1,0]
	v_pk_mul_f32 v[6:7], v[14:15], v[32:33] op_sel_hi:[1,0]
	v_pk_mul_f32 v[0:1], v[8:9], v[32:33] op_sel_hi:[1,0]
	v_pk_mul_f32 v[2:3], v[10:11], v[32:33] op_sel_hi:[1,0]
	v_cvt_pk_bf16_f32 v16, v16, v17
	v_cvt_pk_bf16_f32 v17, v18, v19
	v_cvt_pk_bf16_f32 v18, v20, v21
	v_cvt_pk_bf16_f32 v19, v22, v23
	v_cvt_pk_bf16_f32 v0, v0, v1
	v_cvt_pk_bf16_f32 v1, v2, v3
	v_cvt_pk_bf16_f32 v2, v4, v5
	v_cvt_pk_bf16_f32 v3, v6, v7
	v_permlane32_swap_b32_e32 v16, v18
	v_permlane32_swap_b32_e32 v17, v19
	v_permlane32_swap_b32_e32 v0, v2
	v_permlane32_swap_b32_e32 v1, v3
	global_store_dwordx4 v[34:35], v[16:19], off offset:32
	global_store_dwordx4 v[34:35], v[0:3], off offset:96

.LBB0_740:
	v_lshl_add_u64 v[2:3], v[0:1], 0, s[0:1]
	v_add_co_u32_e32 v2, vcc, 0x3dd0000, v2
	s_add_u32 s0, s0, 64
	s_nop 0
	v_addc_co_u32_e32 v3, vcc, 0, v3, vcc
	global_load_dwordx4 v[8:11], v[2:3], off offset:2048
	s_addc_u32 s1, s1, 0
	s_cmpk_eq_i32 s0, 0x100
	s_waitcnt vmcnt(0) lgkmcnt(0)
	v_lshlrev_b32_e32 v7, 16, v8
	v_lshlrev_b32_e32 v13, 16, v9
	v_and_b32_e32 v12, 0xffff0000, v8
	v_fmac_f32_e32 v6, v7, v7
	v_pk_mul_f32 v[12:13], v[12:13], v[12:13]
	v_lshlrev_b32_e32 v7, 16, v10
	v_add_f32_e32 v6, v12, v6
	v_add_f32_e32 v8, v13, v6
	v_and_b32_e32 v6, 0xffff0000, v9
	v_pk_mul_f32 v[6:7], v[6:7], v[6:7]
	s_nop 0
	v_add_f32_e32 v6, v6, v8
	v_add_f32_e32 v8, v7, v6
	v_lshlrev_b32_e32 v7, 16, v11
	v_and_b32_e32 v6, 0xffff0000, v10
	v_pk_mul_f32 v[6:7], v[6:7], v[6:7]
	s_nop 0
	v_add_f32_e32 v6, v6, v8
	v_add_f32_e32 v12, v7, v6
	v_and_b32_e32 v6, 0xffff0000, v11
	v_fmac_f32_e32 v12, v6, v6
	global_load_dwordx4 v[6:9], v[2:3], off offset:2064
	s_waitcnt vmcnt(0)
	v_lshlrev_b32_e32 v10, 16, v6
	v_fmac_f32_e32 v12, v10, v10
	v_lshlrev_b32_e32 v11, 16, v7
	v_and_b32_e32 v10, 0xffff0000, v6
	v_pk_mul_f32 v[10:11], v[10:11], v[10:11]
	s_nop 0
	v_add_f32_e32 v6, v10, v12
	v_add_f32_e32 v12, v11, v6
	v_lshlrev_b32_e32 v11, 16, v8
	v_and_b32_e32 v10, 0xffff0000, v7
	v_pk_mul_f32 v[6:7], v[10:11], v[10:11]
	s_nop 0
	v_add_f32_e32 v6, v6, v12
	v_add_f32_e32 v10, v7, v6
	v_lshlrev_b32_e32 v7, 16, v9
	v_and_b32_e32 v6, 0xffff0000, v8
	v_pk_mul_f32 v[6:7], v[6:7], v[6:7]
	s_nop 0
	v_add_f32_e32 v6, v6, v10
	v_add_f32_e32 v12, v7, v6
	v_and_b32_e32 v6, 0xffff0000, v9
	v_fmac_f32_e32 v12, v6, v6
	global_load_dwordx4 v[6:9], v[2:3], off offset:2080
	s_waitcnt vmcnt(0)
	v_lshlrev_b32_e32 v10, 16, v6
	v_fmac_f32_e32 v12, v10, v10
	v_lshlrev_b32_e32 v11, 16, v7
	v_and_b32_e32 v10, 0xffff0000, v6
	v_pk_mul_f32 v[10:11], v[10:11], v[10:11]
	s_nop 0
	v_add_f32_e32 v6, v10, v12
	v_add_f32_e32 v12, v11, v6
	v_lshlrev_b32_e32 v11, 16, v8
	v_and_b32_e32 v10, 0xffff0000, v7
	v_pk_mul_f32 v[6:7], v[10:11], v[10:11]
	s_nop 0
	v_add_f32_e32 v6, v6, v12
	v_add_f32_e32 v10, v7, v6
	v_lshlrev_b32_e32 v7, 16, v9
	v_and_b32_e32 v6, 0xffff0000, v8
	v_pk_mul_f32 v[6:7], v[6:7], v[6:7]
	s_nop 0
	v_add_f32_e32 v6, v6, v10
	v_add_f32_e32 v10, v7, v6
	v_and_b32_e32 v6, 0xffff0000, v9
	v_fmac_f32_e32 v10, v6, v6
	global_load_dwordx4 v[6:9], v[2:3], off offset:2096
	s_waitcnt vmcnt(0)
	v_lshlrev_b32_e32 v2, 16, v6
	v_fmac_f32_e32 v10, v2, v2
	v_lshlrev_b32_e32 v3, 16, v7
	v_and_b32_e32 v2, 0xffff0000, v6
	v_pk_mul_f32 v[2:3], v[2:3], v[2:3]
	s_nop 0
	v_add_f32_e32 v2, v2, v10
	v_add_f32_e32 v6, v3, v2
	v_lshlrev_b32_e32 v3, 16, v8
	v_and_b32_e32 v2, 0xffff0000, v7
	v_pk_mul_f32 v[2:3], v[2:3], v[2:3]
	s_nop 0
	v_add_f32_e32 v2, v2, v6
	v_add_f32_e32 v6, v3, v2
	v_lshlrev_b32_e32 v3, 16, v9
	v_and_b32_e32 v2, 0xffff0000, v8
	v_pk_mul_f32 v[2:3], v[2:3], v[2:3]
	s_nop 0
	v_add_f32_e32 v2, v2, v6
	v_add_f32_e32 v6, v3, v2
	v_and_b32_e32 v2, 0xffff0000, v9
	v_fmac_f32_e32 v6, v2, v2
	s_cbranch_scc0 .LBB0_740
	v_and_b32_e32 v1, 64, v225
	v_xor_b32_e32 v0, 1, v225
	v_add_u32_e32 v1, 64, v1
	v_cmp_lt_i32_e32 vcc, v0, v1
	s_nop 1
	v_cndmask_b32_e32 v0, v225, v0, vcc
	v_lshlrev_b32_e32 v0, 2, v0
	ds_bpermute_b32 v0, v0, v6
	v_cmp_eq_u32_e32 vcc, 0, v5
	s_and_saveexec_b64 s[0:1], vcc
	s_movk_i32 s12, 0x90
	s_cbranch_execz .LBB0_743
	s_waitcnt lgkmcnt(0)
	v_add_f32_e32 v0, v6, v0
	v_fmamk_f32 v0, v0, 0x3b800000, v224
	s_mov_b32 s9, 0x800000
	v_mul_f32_e32 v1, 0x4b800000, v0
	v_cmp_gt_f32_e32 vcc, s9, v0
	s_nop 1
	v_cndmask_b32_e32 v0, v0, v1, vcc
	v_rsq_f32_e32 v0, v0
	s_nop 0
	v_mul_f32_e32 v1, 0x45800000, v0
	v_cndmask_b32_e32 v0, v0, v1, vcc
	v_lshl_add_u32 v1, v4, 2, v232
	ds_write_b32 v1, v0
.LBB0_743:
	s_or_b64 exec, exec, s[0:1]
	s_lshl_b32 s1, s8, 7
	s_and_b32 s10, s1, 0x3f80
	v_ashrrev_i32_e32 v5, 3, v198
	s_waitcnt lgkmcnt(0)
	v_lshlrev_b32_e32 v0, 4, v198
	v_readlane_b32 s14, v254, 31
	s_and_b32 s0, s8, 0xffffff80
	v_add_u32_e32 v44, s10, v5
	v_and_b32_e32 v192, 0x70, v0
	v_readlane_b32 s15, v254, 32
	v_add_u32_e32 v0, s0, v5
	v_add_u32_e32 v46, 32, v44
	v_lshl_add_u64 v[26:27], s[14:15], 0, v[192:193]
	v_mad_i64_i32 v[2:3], s[8:9], v44, s16, v[26:27]
	v_ashrrev_i32_e32 v1, 31, v0
	v_mad_i64_i32 v[10:11], s[8:9], v46, s16, v[26:27]
	v_lshlrev_b64 v[34:35], 9, v[0:1]
	s_mov_b64 s[8:9], 0x4000
	v_add_u32_e32 v47, 64, v44
	v_readlane_b32 s24, v254, 33
	v_lshl_add_u64 v[36:37], v[34:35], 0, s[8:9]
	v_mad_i64_i32 v[18:19], s[8:9], v47, s16, v[26:27]
	v_readlane_b32 s25, v254, 34
	s_mov_b64 s[8:9], 0x8000
	v_lshl_add_u64 v[38:39], v[34:35], 0, s[8:9]
	v_lshl_add_u64 v[30:31], s[24:25], 0, v[192:193]
	v_lshl_add_u64 v[6:7], v[30:31], 0, v[34:35]
	v_lshl_add_u64 v[14:15], v[30:31], 0, v[36:37]
	v_lshl_add_u64 v[22:23], v[30:31], 0, v[38:39]
	global_load_dwordx4 v[0:3], v[2:3], off
	s_nop 0
	global_load_dwordx4 v[6:9], v[6:7], off
	s_nop 0
	global_load_dwordx4 v[10:13], v[10:11], off
	s_nop 0
	global_load_dwordx4 v[14:17], v[14:15], off
	s_nop 0
	global_load_dwordx4 v[18:21], v[18:19], off
	s_nop 0
	global_load_dwordx4 v[22:25], v[22:23], off
	v_add_u32_e32 v48, 0x60, v44
	v_mad_i64_i32 v[26:27], s[8:9], v48, s16, v[26:27]
	global_load_dwordx4 v[26:29], v[26:27], off
	s_mov_b64 s[8:9], 0xc000
	v_lshl_add_u64 v[40:41], v[34:35], 0, s[8:9]
	v_lshl_add_u64 v[30:31], v[30:31], 0, v[40:41]
	global_load_dwordx4 v[30:33], v[30:31], off
	v_bfe_u32 v78, v198, 5, 1
	v_mov_b64_e32 v[42:43], s[14:15]
	v_and_b32_e32 v45, 0x5f, v198
	v_lshlrev_b32_e32 v64, 4, v78
	v_mad_u32_u24 v65, v45, s12, v64
	v_mad_i64_i32 v[44:45], s[8:9], v44, s16, v[42:43]
	v_lshl_add_u64 v[144:145], v[44:45], 0, v[192:193]
	v_lshl_add_u64 v[34:35], s[24:25], 0, v[34:35]
	v_mad_i64_i32 v[44:45], s[8:9], v46, s16, v[42:43]
	v_mad_i64_i32 v[46:47], s[8:9], v47, s16, v[42:43]
	v_mad_i64_i32 v[42:43], s[8:9], v48, s16, v[42:43]
	v_lshl_add_u64 v[146:147], v[34:35], 0, v[192:193]
	v_lshl_add_u64 v[148:149], v[44:45], 0, v[192:193]
	v_lshl_add_u64 v[34:35], s[24:25], 0, v[36:37]
	v_lshl_add_u64 v[36:37], s[24:25], 0, v[38:39]
	v_lshl_add_u64 v[38:39], s[24:25], 0, v[40:41]
	v_lshl_add_u64 v[150:151], v[46:47], 0, v[192:193]
	v_lshl_add_u64 v[152:153], v[42:43], 0, v[192:193]
	global_load_dwordx4 v[70:73], v[144:145], off offset:128
	global_load_dwordx4 v[74:77], v[146:147], off offset:128
	v_lshl_add_u64 v[154:155], v[34:35], 0, v[192:193]
	v_lshl_add_u64 v[156:157], v[36:37], 0, v[192:193]
	v_lshl_add_u64 v[158:159], v[38:39], 0, v[192:193]
	global_load_dwordx4 v[80:83], v[148:149], off offset:128
	global_load_dwordx4 v[84:87], v[154:155], off offset:128
	global_load_dwordx4 v[88:91], v[150:151], off offset:128
	global_load_dwordx4 v[92:95], v[156:157], off offset:128
	global_load_dwordx4 v[96:99], v[152:153], off offset:128
	global_load_dwordx4 v[100:103], v[158:159], off offset:128
	v_mad_u64_u32 v[68:69], s[8:9], v5, s12, v[192:193]
	v_and_b32_e32 v49, 31, v198
	s_movk_i32 s1, 0xffc0
	v_and_or_b32 v79, v4, s1, v49
	v_mad_u64_u32 v[66:67], s[8:9], v79, s12, v[64:65]
	v_add_u32_e32 v67, 0xd800, v68
	v_and_or_b32 v192, v198, 64, s0
	s_movk_i32 s0, 0xffab
	s_waitcnt vmcnt(15)
	ds_write_b128 v68, v[0:3]
	s_waitcnt vmcnt(14)
	ds_write_b128 v68, v[6:9] offset:18432
	s_waitcnt vmcnt(13)
	ds_write_b128 v68, v[10:13] offset:4608
	s_waitcnt vmcnt(11)
	ds_write_b128 v68, v[18:21] offset:9216
	s_waitcnt vmcnt(9)
	ds_write_b128 v68, v[26:29] offset:13824
	ds_write_b128 v68, v[14:17] offset:23040
	ds_write_b128 v68, v[22:25] offset:27648
	s_waitcnt vmcnt(8)
	ds_write_b128 v68, v[30:33] offset:32256
	s_waitcnt lgkmcnt(0)
	s_barrier
	ds_read_b128 v[0:3], v65 offset:18432
	ds_read_b128 v[4:7], v66
	ds_read_b128 v[104:107], v65 offset:18464
	ds_read_b128 v[108:111], v66 offset:32
	ds_read_b128 v[8:11], v66 offset:4608
	ds_read_b128 v[112:115], v66 offset:4640
	s_waitcnt lgkmcnt(4)
	v_mfma_f32_32x32x16_bf16 v[48:63], v[0:3], v[4:7], 0
	s_waitcnt lgkmcnt(1)
	v_mfma_f32_32x32x16_bf16 v[16:31], v[0:3], v[8:11], 0
	ds_read_b128 v[0:3], v65 offset:23040
	ds_read_b128 v[116:119], v65 offset:23072
	s_waitcnt lgkmcnt(1)
	v_mfma_f32_32x32x16_bf16 v[32:47], v[0:3], v[4:7], 0
	v_mfma_f32_32x32x16_bf16 v[0:15], v[0:3], v[8:11], 0
	v_mfma_f32_32x32x16_bf16 v[48:63], v[104:107], v[108:111], v[48:63]
	v_mfma_f32_32x32x16_bf16 v[16:31], v[104:107], v[112:115], v[16:31]
	s_waitcnt lgkmcnt(0)
	v_mfma_f32_32x32x16_bf16 v[32:47], v[116:119], v[108:111], v[32:47]
	v_mfma_f32_32x32x16_bf16 v[0:15], v[116:119], v[112:115], v[0:15]
	ds_read_b128 v[104:107], v65 offset:18496
	ds_read_b128 v[108:111], v66 offset:64
	ds_read_b128 v[112:115], v65 offset:18528
	ds_read_b128 v[116:119], v66 offset:96
	ds_read_b128 v[120:123], v66 offset:4672
	ds_read_b128 v[124:127], v66 offset:4704
	s_waitcnt lgkmcnt(4)
	v_mfma_f32_32x32x16_bf16 v[48:63], v[104:107], v[108:111], v[48:63]
	s_waitcnt lgkmcnt(1)
	v_mfma_f32_32x32x16_bf16 v[16:31], v[104:107], v[120:123], v[16:31]
	ds_read_b128 v[104:107], v65 offset:23104
	ds_read_b128 v[128:131], v65 offset:23136
	s_waitcnt lgkmcnt(1)
	v_mfma_f32_32x32x16_bf16 v[32:47], v[104:107], v[108:111], v[32:47]
	v_mfma_f32_32x32x16_bf16 v[0:15], v[104:107], v[120:123], v[0:15]
	v_mfma_f32_32x32x16_bf16 v[48:63], v[112:115], v[116:119], v[48:63]
	v_mfma_f32_32x32x16_bf16 v[16:31], v[112:115], v[124:127], v[16:31]
	s_waitcnt lgkmcnt(0)
	v_mfma_f32_32x32x16_bf16 v[32:47], v[128:131], v[116:119], v[32:47]
	global_load_dwordx4 v[104:107], v[144:145], off offset:256
	global_load_dwordx4 v[108:111], v[146:147], off offset:256
	global_load_dwordx4 v[112:115], v[148:149], off offset:256
	global_load_dwordx4 v[116:119], v[154:155], off offset:256
	global_load_dwordx4 v[120:123], v[150:151], off offset:256
	global_load_dwordx4 v[132:135], v[156:157], off offset:256
	global_load_dwordx4 v[136:139], v[152:153], off offset:256
	global_load_dwordx4 v[140:143], v[158:159], off offset:256
	s_waitcnt vmcnt(15)
	ds_write_b128 v68, v[70:73] offset:36864
	s_waitcnt vmcnt(14)
	ds_write_b128 v68, v[74:77] offset:55296
	s_waitcnt vmcnt(13)
	ds_write_b128 v68, v[80:83] offset:41472
	s_waitcnt vmcnt(12)
	ds_write_b128 v68, v[84:87] offset:59904
	s_waitcnt vmcnt(11)
	ds_write_b128 v68, v[88:91] offset:46080
	s_waitcnt vmcnt(10)
	ds_write_b128 v68, v[92:95] offset:64512
	s_waitcnt vmcnt(9)
	ds_write_b128 v68, v[96:99] offset:50688
	s_waitcnt vmcnt(8)
	ds_write_b128 v67, v[100:103] offset:13824
	s_waitcnt lgkmcnt(0)
	s_barrier
	ds_read_b128 v[70:73], v65 offset:55296
	ds_read_b128 v[74:77], v66 offset:36864
	ds_read_b128 v[80:83], v65 offset:55328
	ds_read_b128 v[84:87], v66 offset:36896
	v_mfma_f32_32x32x16_bf16 v[0:15], v[128:131], v[124:127], v[0:15]
	ds_read_b128 v[88:91], v66 offset:41472
	ds_read_b128 v[92:95], v66 offset:41504
	s_waitcnt lgkmcnt(4)
	v_mfma_f32_32x32x16_bf16 v[48:63], v[70:73], v[74:77], v[48:63]
	s_waitcnt lgkmcnt(1)
	v_mfma_f32_32x32x16_bf16 v[16:31], v[70:73], v[88:91], v[16:31]
	ds_read_b128 v[70:73], v65 offset:59904
	ds_read_b128 v[96:99], v65 offset:59936
	s_waitcnt lgkmcnt(1)
	v_mfma_f32_32x32x16_bf16 v[32:47], v[70:73], v[74:77], v[32:47]
	v_mfma_f32_32x32x16_bf16 v[0:15], v[70:73], v[88:91], v[0:15]
	v_mfma_f32_32x32x16_bf16 v[48:63], v[80:83], v[84:87], v[48:63]
	v_mfma_f32_32x32x16_bf16 v[16:31], v[80:83], v[92:95], v[16:31]
	s_waitcnt lgkmcnt(0)
	v_mfma_f32_32x32x16_bf16 v[32:47], v[96:99], v[84:87], v[32:47]
	ds_read_b128 v[70:73], v65 offset:55360
	ds_read_b128 v[74:77], v66 offset:36928
	ds_read_b128 v[80:83], v65 offset:55392
	ds_read_b128 v[84:87], v66 offset:36960
	v_mfma_f32_32x32x16_bf16 v[0:15], v[96:99], v[92:95], v[0:15]
	ds_read_b128 v[88:91], v66 offset:41536
	ds_read_b128 v[92:95], v66 offset:41568
	s_waitcnt lgkmcnt(4)
	v_mfma_f32_32x32x16_bf16 v[48:63], v[70:73], v[74:77], v[48:63]
	s_waitcnt lgkmcnt(1)
	v_mfma_f32_32x32x16_bf16 v[16:31], v[70:73], v[88:91], v[16:31]
	ds_read_b128 v[70:73], v65 offset:59968
	ds_read_b128 v[96:99], v65 offset:60000
	s_waitcnt lgkmcnt(1)
	v_mfma_f32_32x32x16_bf16 v[32:47], v[70:73], v[74:77], v[32:47]
	v_mfma_f32_32x32x16_bf16 v[0:15], v[70:73], v[88:91], v[0:15]
	v_mfma_f32_32x32x16_bf16 v[48:63], v[80:83], v[84:87], v[48:63]
	v_mfma_f32_32x32x16_bf16 v[16:31], v[80:83], v[92:95], v[16:31]
	s_waitcnt lgkmcnt(0)
	v_mfma_f32_32x32x16_bf16 v[32:47], v[96:99], v[84:87], v[32:47]
	global_load_dwordx4 v[70:73], v[144:145], off offset:384
	global_load_dwordx4 v[74:77], v[146:147], off offset:384
	global_load_dwordx4 v[80:83], v[148:149], off offset:384
	global_load_dwordx4 v[84:87], v[154:155], off offset:384
	global_load_dwordx4 v[88:91], v[150:151], off offset:384
	global_load_dwordx4 v[100:103], v[156:157], off offset:384
	global_load_dwordx4 v[124:127], v[152:153], off offset:384
	global_load_dwordx4 v[128:131], v[158:159], off offset:384
	s_waitcnt vmcnt(15)
	ds_write_b128 v68, v[104:107]
	s_waitcnt vmcnt(14)
	ds_write_b128 v68, v[108:111] offset:18432
	s_waitcnt vmcnt(13)
	ds_write_b128 v68, v[112:115] offset:4608
	s_waitcnt vmcnt(12)
	ds_write_b128 v68, v[116:119] offset:23040
	s_waitcnt vmcnt(11)
	ds_write_b128 v68, v[120:123] offset:9216
	s_waitcnt vmcnt(10)
	ds_write_b128 v68, v[132:135] offset:27648
	s_waitcnt vmcnt(9)
	ds_write_b128 v68, v[136:139] offset:13824
	s_waitcnt vmcnt(8)
	ds_write_b128 v68, v[140:143] offset:32256
	s_waitcnt lgkmcnt(0)
	s_barrier
	v_mfma_f32_32x32x16_bf16 v[0:15], v[96:99], v[92:95], v[0:15]
	ds_read_b128 v[92:95], v65 offset:18432
	ds_read_b128 v[96:99], v66
	ds_read_b128 v[104:107], v65 offset:18464
	ds_read_b128 v[108:111], v66 offset:32
	ds_read_b128 v[112:115], v66 offset:4608
	ds_read_b128 v[116:119], v66 offset:4640
	s_waitcnt lgkmcnt(4)
	v_mfma_f32_32x32x16_bf16 v[48:63], v[92:95], v[96:99], v[48:63]
	s_waitcnt lgkmcnt(1)
	v_mfma_f32_32x32x16_bf16 v[16:31], v[92:95], v[112:115], v[16:31]
	ds_read_b128 v[92:95], v65 offset:23040
	ds_read_b128 v[120:123], v65 offset:23072
	s_waitcnt lgkmcnt(1)
	v_mfma_f32_32x32x16_bf16 v[32:47], v[92:95], v[96:99], v[32:47]
	v_mfma_f32_32x32x16_bf16 v[0:15], v[92:95], v[112:115], v[0:15]
	v_mfma_f32_32x32x16_bf16 v[48:63], v[104:107], v[108:111], v[48:63]
	v_mfma_f32_32x32x16_bf16 v[16:31], v[104:107], v[116:119], v[16:31]
	s_waitcnt lgkmcnt(0)
	v_mfma_f32_32x32x16_bf16 v[32:47], v[120:123], v[108:111], v[32:47]
	ds_read_b128 v[92:95], v65 offset:18496
	ds_read_b128 v[96:99], v66 offset:64
	ds_read_b128 v[104:107], v65 offset:18528
	ds_read_b128 v[108:111], v66 offset:96
	v_mfma_f32_32x32x16_bf16 v[0:15], v[120:123], v[116:119], v[0:15]
	ds_read_b128 v[112:115], v66 offset:4672
	ds_read_b128 v[116:119], v66 offset:4704
	s_waitcnt lgkmcnt(4)
	v_mfma_f32_32x32x16_bf16 v[48:63], v[92:95], v[96:99], v[48:63]
	s_waitcnt lgkmcnt(1)
	v_mfma_f32_32x32x16_bf16 v[16:31], v[92:95], v[112:115], v[16:31]
	ds_read_b128 v[92:95], v65 offset:23104
	ds_read_b128 v[120:123], v65 offset:23136
	s_waitcnt vmcnt(7)
	ds_write_b128 v68, v[70:73] offset:36864
	s_waitcnt vmcnt(6)
	ds_write_b128 v68, v[74:77] offset:55296
	s_waitcnt vmcnt(5)
	ds_write_b128 v68, v[80:83] offset:41472
	s_waitcnt vmcnt(4)
	ds_write_b128 v68, v[84:87] offset:59904
	s_waitcnt vmcnt(3)
	ds_write_b128 v68, v[88:91] offset:46080
	s_waitcnt vmcnt(2)
	ds_write_b128 v68, v[100:103] offset:64512
	s_waitcnt vmcnt(1)
	ds_write_b128 v68, v[124:127] offset:50688
	s_waitcnt vmcnt(0)
	ds_write_b128 v67, v[128:131] offset:13824
	s_waitcnt lgkmcnt(0)
	s_barrier
	ds_read_b128 v[68:71], v65 offset:55296
	ds_read_b128 v[72:75], v66 offset:36864
	ds_read_b128 v[80:83], v65 offset:55328
	ds_read_b128 v[84:87], v66 offset:36896
	v_mfma_f32_32x32x16_bf16 v[32:47], v[92:95], v[96:99], v[32:47]
	v_mfma_f32_32x32x16_bf16 v[0:15], v[92:95], v[112:115], v[0:15]
	ds_read_b128 v[88:91], v66 offset:41472
	ds_read_b128 v[92:95], v66 offset:41504
	v_mfma_f32_32x32x16_bf16 v[48:63], v[104:107], v[108:111], v[48:63]
	v_mfma_f32_32x32x16_bf16 v[16:31], v[104:107], v[116:119], v[16:31]
	v_mfma_f32_32x32x16_bf16 v[32:47], v[120:123], v[108:111], v[32:47]
	v_mfma_f32_32x32x16_bf16 v[0:15], v[120:123], v[116:119], v[0:15]
	s_waitcnt lgkmcnt(4)
	v_mfma_f32_32x32x16_bf16 v[48:63], v[68:71], v[72:75], v[48:63]
	s_waitcnt lgkmcnt(1)
	v_mfma_f32_32x32x16_bf16 v[16:31], v[68:71], v[88:91], v[16:31]
	ds_read_b128 v[68:71], v65 offset:59904
	ds_read_b128 v[96:99], v65 offset:59936
	s_waitcnt lgkmcnt(1)
	v_mfma_f32_32x32x16_bf16 v[32:47], v[68:71], v[72:75], v[32:47]
	v_mfma_f32_32x32x16_bf16 v[0:15], v[68:71], v[88:91], v[0:15]
	v_mfma_f32_32x32x16_bf16 v[48:63], v[80:83], v[84:87], v[48:63]
	v_mfma_f32_32x32x16_bf16 v[16:31], v[80:83], v[92:95], v[16:31]
	s_waitcnt lgkmcnt(0)
	v_mfma_f32_32x32x16_bf16 v[32:47], v[96:99], v[84:87], v[32:47]
	ds_read_b128 v[68:71], v65 offset:55360
	ds_read_b128 v[72:75], v66 offset:36928
	ds_read_b128 v[80:83], v65 offset:55392
	ds_read_b128 v[84:87], v66 offset:36960
	v_mfma_f32_32x32x16_bf16 v[0:15], v[96:99], v[92:95], v[0:15]
	ds_read_b128 v[88:91], v66 offset:41536
	ds_read_b128 v[92:95], v66 offset:41568
	s_waitcnt lgkmcnt(4)
	v_mfma_f32_32x32x16_bf16 v[48:63], v[68:71], v[72:75], v[48:63]
	s_waitcnt lgkmcnt(1)
	v_mfma_f32_32x32x16_bf16 v[16:31], v[68:71], v[88:91], v[16:31]
	ds_read_b128 v[66:69], v65 offset:59968
	ds_read_b128 v[96:99], v65 offset:60000
	v_lshl_add_u32 v65, v79, 2, v232
	s_waitcnt lgkmcnt(0)
	s_barrier
	v_mfma_f32_32x32x16_bf16 v[32:47], v[66:69], v[72:75], v[32:47]
	v_mfma_f32_32x32x16_bf16 v[0:15], v[66:69], v[88:91], v[0:15]
	ds_read_b32 v66, v65
	v_lshlrev_b32_e32 v67, 2, v78
	v_add_u32_e32 v65, s10, v79
	v_lshlrev_b32_e32 v88, 4, v65
	v_ashrrev_i32_e32 v89, 31, v88
	v_mfma_f32_32x32x16_bf16 v[48:63], v[80:83], v[84:87], v[48:63]
	v_mfma_f32_32x32x16_bf16 v[16:31], v[80:83], v[92:95], v[16:31]
	s_nop 0
	s_nop 9
	s_waitcnt lgkmcnt(0)
	v_mul_f32_e64 v74, v48, v66
	v_mul_f32_e64 v75, v49, v66
	v_lshrrev_b32_e32 v48, 5, v192
	v_mov_b32_e32 v49, 0xffffffaa
	v_mad_legacy_u16 v48, v48, s0, v49
	v_and_b32_e32 v48, 0xfe, v48
	s_movk_i32 s0, 0x55
	v_cmp_gt_u16_e32 vcc, s0, v48
	v_mfma_f32_32x32x16_bf16 v[32:47], v[96:99], v[84:87], v[32:47]
	v_readlane_b32 s0, v254, 21
	v_mul_f32_e64 v76, v50, v66
	v_mul_f32_e64 v77, v51, v66
	v_lshlrev_b64 v[50:51], 2, v[88:89]
	v_readlane_b32 s1, v254, 22
	v_pk_mul_f32 v[72:73], v[52:53], v[66:67] op_sel_hi:[1,0]
	v_mul_f32_e32 v68, v54, v66
	v_lshl_add_u64 v[52:53], s[0:1], 0, v[50:51]
	v_mfma_f32_32x32x16_bf16 v[0:15], v[96:99], v[92:95], v[0:15]
	v_readlane_b32 s0, v254, 23
	v_mov_b32_e32 v54, v63
	v_readlane_b32 s1, v254, 24
	v_mul_f32_e64 v56, v56, v66
	v_mul_f32_e64 v57, v57, v66
	v_pk_mul_f32 v[58:59], v[58:59], v[66:67] op_sel_hi:[1,0]
	v_pk_mul_f32 v[60:61], v[60:61], v[66:67] op_sel_hi:[1,0]
	v_mul_f32_e32 v70, v62, v66
	v_pk_mul_f32 v[62:63], v[54:55], v[66:67] op_sel_hi:[1,0]
	v_lshlrev_b32_e32 v48, 2, v67
	v_lshl_add_u64 v[50:51], s[0:1], 0, v[50:51]
	s_and_saveexec_b64 s[0:1], vcc
	s_cbranch_execz .LBB0_745
	v_mov_b32_e32 v49, v193
	v_lshl_add_u64 v[54:55], v[52:53], 0, v[48:49]
	v_lshl_add_u64 v[88:89], v[50:51], 0, v[48:49]
	global_load_dwordx4 v[80:83], v[54:55], off
	global_load_dwordx4 v[84:87], v[88:89], off
	v_mov_b32_e32 v71, v62
	v_mov_b32_e32 v69, v63
	s_waitcnt vmcnt(0) lgkmcnt(0)
	v_pk_mul_f32 v[90:91], v[56:57], v[84:85]
	s_nop 0
	v_pk_fma_f32 v[90:91], v[74:75], v[80:81], v[90:91] neg_lo:[0,0,1] neg_hi:[0,0,1]
	v_pk_mul_f32 v[74:75], v[74:75], v[84:85]
	s_nop 0
	v_pk_fma_f32 v[56:57], v[56:57], v[80:81], v[74:75]
	v_pk_mul_f32 v[74:75], v[58:59], v[86:87]
	s_nop 0
	v_pk_fma_f32 v[84:85], v[76:77], v[82:83], v[74:75] neg_lo:[0,0,1] neg_hi:[0,0,1]
	v_pk_mul_f32 v[74:75], v[76:77], v[86:87]
	s_nop 0
	v_pk_fma_f32 v[58:59], v[58:59], v[82:83], v[74:75]
	global_load_dwordx4 v[74:77], v[54:55], off offset:32
	global_load_dwordx4 v[80:83], v[88:89], off offset:32
	s_waitcnt vmcnt(0)
	v_pk_mul_f32 v[54:55], v[60:61], v[80:81]
	s_nop 0
	v_pk_fma_f32 v[54:55], v[72:73], v[74:75], v[54:55] neg_lo:[0,0,1] neg_hi:[0,0,1]
	v_pk_mul_f32 v[72:73], v[72:73], v[80:81]
	s_nop 0
	v_pk_fma_f32 v[60:61], v[60:61], v[74:75], v[72:73]
	v_mul_f32_e32 v72, v68, v82
	v_mul_f32_e32 v74, v70, v76
	v_pk_mul_f32 v[70:71], v[70:71], v[82:83]
	v_mov_b32_e32 v82, v77
	v_pk_mul_f32 v[62:63], v[62:63], v[82:83]
	v_pk_fma_f32 v[68:69], v[68:69], v[76:77], v[70:71] neg_lo:[0,0,1] neg_hi:[0,0,1]
	v_mov_b32_e32 v75, v62
	v_mov_b32_e32 v73, v63
	v_pk_add_f32 v[70:71], v[74:75], v[72:73]
	v_mov_b32_e32 v74, v90
	v_mov_b32_e32 v75, v91
	v_mov_b32_e32 v76, v84
	v_mov_b32_e32 v77, v85
	v_mov_b32_e32 v72, v54
	v_mov_b32_e32 v73, v55
	v_mov_b32_e32 v63, v69
	v_mov_b32_e32 v62, v71
.LBB0_745:
	s_or_b64 exec, exec, s[0:1]
	v_readlane_b32 s0, v253, 61
	v_readlane_b32 s1, v253, 62
	v_cvt_pk_bf16_f32 v56, v56, v57
	v_cvt_pk_bf16_f32 v57, v58, v59
	v_mov_b64_e32 v[54:55], s[0:1]
	v_mad_i64_i32 v[54:55], s[0:1], v65, s17, v[54:55]
	v_lshl_add_u64 v[54:55], v[192:193], 1, v[54:55]
	v_mov_b32_e32 v65, v193
	v_cvt_pk_bf16_f32 v58, v60, v61
	v_cvt_pk_bf16_f32 v59, v70, v62
	v_mov_b32_e32 v67, v66
	v_lshl_add_u64 v[54:55], v[54:55], 0, v[64:65]
	v_permlane32_swap_b32_e32 v56, v58
	v_permlane32_swap_b32_e32 v57, v59
	v_or_b32_e32 v49, 32, v192
	global_store_dwordx4 v[54:55], v[56:59], off offset:32
	v_pk_mul_f32 v[60:61], v[34:35], v[66:67]
	v_pk_mul_f32 v[34:35], v[42:43], v[66:67]
	v_pk_mul_f32 v[58:59], v[32:33], v[66:67]
	v_pk_mul_f32 v[32:33], v[40:41], v[66:67]
	v_pk_mul_f32 v[42:43], v[36:37], v[66:67]
	v_pk_mul_f32 v[36:37], v[44:45], v[66:67]
	v_lshrrev_b32_e32 v41, 5, v49
	s_movk_i32 s0, 0xffab
	v_mov_b32_e32 v44, 0xffffffaa
	v_cvt_pk_bf16_f32 v74, v74, v75
	v_cvt_pk_bf16_f32 v75, v76, v77
	v_cvt_pk_bf16_f32 v76, v72, v73
	v_cvt_pk_bf16_f32 v77, v68, v63
	v_mul_f32_e32 v56, v38, v66
	v_mov_b32_e32 v38, v47
	v_mad_legacy_u16 v41, v41, s0, v44
	s_movk_i32 s0, 0x55
	v_permlane32_swap_b32_e32 v74, v76
	v_permlane32_swap_b32_e32 v75, v77
	v_mul_f32_e32 v40, v46, v66
	v_pk_mul_f32 v[38:39], v[38:39], v[66:67]
	v_cmp_lt_u16_sdwa s[0:1], v41, s0 src0_sel:BYTE_0 src1_sel:DWORD
	global_store_dwordx4 v[54:55], v[74:77], off
	s_and_saveexec_b64 s[8:9], s[0:1]
	s_cbranch_execz .LBB0_747
	v_mov_b32_e32 v49, v193
	v_lshl_add_u64 v[62:63], v[52:53], 0, v[48:49]
	v_lshl_add_u64 v[64:65], v[50:51], 0, v[48:49]
	global_load_dwordx4 v[44:47], v[62:63], off
	global_load_dwordx4 v[50:53], v[64:65], off
	v_mov_b32_e32 v41, v38
	v_mov_b32_e32 v57, v39
	s_waitcnt vmcnt(0) lgkmcnt(0)
	v_pk_mul_f32 v[66:67], v[32:33], v[50:51]
	v_pk_mul_f32 v[50:51], v[58:59], v[50:51]
	v_pk_fma_f32 v[66:67], v[58:59], v[44:45], v[66:67] neg_lo:[0,0,1] neg_hi:[0,0,1]
	v_pk_fma_f32 v[32:33], v[32:33], v[44:45], v[50:51]
	v_pk_mul_f32 v[44:45], v[34:35], v[52:53]
	s_nop 0
	v_pk_fma_f32 v[68:69], v[60:61], v[46:47], v[44:45] neg_lo:[0,0,1] neg_hi:[0,0,1]
	v_pk_mul_f32 v[44:45], v[60:61], v[52:53]
	v_mov_b32_e32 v60, v68
	v_pk_fma_f32 v[34:35], v[34:35], v[46:47], v[44:45]
	global_load_dwordx4 v[44:47], v[62:63], off offset:32
	global_load_dwordx4 v[50:53], v[64:65], off offset:32
	v_mov_b32_e32 v61, v69
	s_waitcnt vmcnt(0)
	v_pk_mul_f32 v[58:59], v[36:37], v[50:51]
	s_nop 0
	v_pk_fma_f32 v[62:63], v[42:43], v[44:45], v[58:59] neg_lo:[0,0,1] neg_hi:[0,0,1]
	v_pk_mul_f32 v[42:43], v[42:43], v[50:51]
	v_mov_b32_e32 v58, v66
	v_pk_fma_f32 v[36:37], v[36:37], v[44:45], v[42:43]
	v_mul_f32_e32 v42, v56, v52
	v_mul_f32_e32 v44, v40, v46
	v_pk_mul_f32 v[40:41], v[40:41], v[52:53]
	v_mov_b32_e32 v52, v47
	v_pk_mul_f32 v[38:39], v[38:39], v[52:53]
	v_pk_fma_f32 v[56:57], v[56:57], v[46:47], v[40:41] neg_lo:[0,0,1] neg_hi:[0,0,1]
	v_mov_b32_e32 v45, v38
	v_mov_b32_e32 v43, v39
	v_pk_add_f32 v[40:41], v[44:45], v[42:43]
	v_mov_b32_e32 v59, v67
	v_mov_b32_e32 v42, v62
	v_mov_b32_e32 v43, v63
	v_mov_b32_e32 v39, v57
	v_mov_b32_e32 v38, v41
.LBB0_747:
	s_or_b64 exec, exec, s[8:9]
	v_cvt_pk_bf16_f32 v44, v58, v59
	v_cvt_pk_bf16_f32 v45, v60, v61
	v_cvt_pk_bf16_f32 v46, v42, v43
	v_cvt_pk_bf16_f32 v47, v56, v39
	v_cvt_pk_bf16_f32 v32, v32, v33
	v_cvt_pk_bf16_f32 v33, v34, v35
	v_cvt_pk_bf16_f32 v34, v36, v37
	v_cvt_pk_bf16_f32 v35, v40, v38
	v_or_b32_e32 v41, 32, v79
	v_permlane32_swap_b32_e32 v44, v46
	v_permlane32_swap_b32_e32 v45, v47
	v_permlane32_swap_b32_e32 v32, v34
	v_permlane32_swap_b32_e32 v33, v35
	global_store_dwordx4 v[54:55], v[44:47], off offset:64
	global_store_dwordx4 v[54:55], v[32:35], off offset:96
	v_add_u32_e32 v42, s10, v41
	v_lshlrev_b32_e32 v44, 4, v42
	v_lshl_add_u32 v32, v41, 2, v232
	ds_read_b32 v32, v32
	v_ashrrev_i32_e32 v45, 31, v44
	v_readlane_b32 s8, v254, 21
	v_readlane_b32 s9, v254, 22
	s_waitcnt lgkmcnt(0)
	v_pk_mul_f32 v[38:39], v[16:17], v[32:33] op_sel_hi:[1,0]
	v_lshlrev_b64 v[16:17], 2, v[44:45]
	v_pk_mul_f32 v[40:41], v[18:19], v[32:33] op_sel_hi:[1,0]
	v_lshl_add_u64 v[18:19], s[8:9], 0, v[16:17]
	v_readlane_b32 s8, v254, 23
	v_mul_f32_e32 v34, v22, v32
	v_mov_b32_e32 v22, v31
	v_readlane_b32 s9, v254, 24
	v_pk_mul_f32 v[24:25], v[24:25], v[32:33] op_sel_hi:[1,0]
	v_pk_mul_f32 v[26:27], v[26:27], v[32:33] op_sel_hi:[1,0]
	v_pk_mul_f32 v[36:37], v[20:21], v[32:33] op_sel_hi:[1,0]
	v_pk_mul_f32 v[28:29], v[28:29], v[32:33] op_sel_hi:[1,0]
	v_mul_f32_e32 v30, v30, v32
	v_pk_mul_f32 v[22:23], v[22:23], v[32:33] op_sel_hi:[1,0]
	v_lshl_add_u64 v[16:17], s[8:9], 0, v[16:17]
	s_and_saveexec_b64 s[8:9], vcc
	s_cbranch_execz .LBB0_749
	v_mov_b32_e32 v49, v193
	v_lshl_add_u64 v[20:21], v[18:19], 0, v[48:49]
	v_lshl_add_u64 v[54:55], v[16:17], 0, v[48:49]
	global_load_dwordx4 v[44:47], v[20:21], off
	global_load_dwordx4 v[50:53], v[54:55], off
	v_mov_b32_e32 v31, v22
	v_mov_b32_e32 v35, v23
	s_waitcnt vmcnt(0) lgkmcnt(0)
	v_pk_mul_f32 v[56:57], v[24:25], v[50:51]
	s_nop 0
	v_pk_fma_f32 v[56:57], v[38:39], v[44:45], v[56:57] neg_lo:[0,0,1] neg_hi:[0,0,1]
	v_pk_mul_f32 v[38:39], v[38:39], v[50:51]
	s_nop 0
	v_pk_fma_f32 v[24:25], v[24:25], v[44:45], v[38:39]
	v_pk_mul_f32 v[38:39], v[26:27], v[52:53]
	s_nop 0
	v_pk_fma_f32 v[50:51], v[40:41], v[46:47], v[38:39] neg_lo:[0,0,1] neg_hi:[0,0,1]
	v_pk_mul_f32 v[38:39], v[40:41], v[52:53]
	s_nop 0
	v_pk_fma_f32 v[26:27], v[26:27], v[46:47], v[38:39]
	global_load_dwordx4 v[38:41], v[20:21], off offset:32
	global_load_dwordx4 v[44:47], v[54:55], off offset:32
	s_waitcnt vmcnt(0)
	v_pk_mul_f32 v[20:21], v[28:29], v[44:45]
	s_nop 0
	v_pk_fma_f32 v[20:21], v[36:37], v[38:39], v[20:21] neg_lo:[0,0,1] neg_hi:[0,0,1]
	v_pk_mul_f32 v[36:37], v[36:37], v[44:45]
	s_nop 0
	v_pk_fma_f32 v[28:29], v[28:29], v[38:39], v[36:37]
	v_mul_f32_e32 v36, v34, v46
	v_mul_f32_e32 v38, v30, v40
	v_pk_mul_f32 v[30:31], v[30:31], v[46:47]
	v_mov_b32_e32 v46, v41
	v_pk_mul_f32 v[22:23], v[22:23], v[46:47]
	v_pk_fma_f32 v[34:35], v[34:35], v[40:41], v[30:31] neg_lo:[0,0,1] neg_hi:[0,0,1]
	v_mov_b32_e32 v39, v22
	v_mov_b32_e32 v37, v23
	v_pk_add_f32 v[30:31], v[38:39], v[36:37]
	v_mov_b32_e32 v38, v56
	v_mov_b32_e32 v39, v57
	v_mov_b32_e32 v40, v50
	v_mov_b32_e32 v41, v51
	v_mov_b32_e32 v36, v20
	v_mov_b32_e32 v37, v21
	v_mov_b32_e32 v23, v35
	v_mov_b32_e32 v22, v31
.LBB0_749:
	s_or_b64 exec, exec, s[8:9]
	v_readlane_b32 s8, v253, 61
	v_readlane_b32 s9, v253, 62
	v_lshlrev_b32_e32 v31, 3, v78
	v_cvt_pk_bf16_f32 v24, v24, v25
	v_mov_b64_e32 v[20:21], s[8:9]
	v_mad_i64_i32 v[20:21], s[8:9], v42, s17, v[20:21]
	v_lshl_add_u64 v[20:21], v[192:193], 1, v[20:21]
	v_lshlrev_b32_e32 v192, 1, v31
	v_cvt_pk_bf16_f32 v25, v26, v27
	v_cvt_pk_bf16_f32 v26, v28, v29
	v_cvt_pk_bf16_f32 v27, v30, v22
	v_mov_b32_e32 v33, v32
	v_lshl_add_u64 v[20:21], v[20:21], 0, v[192:193]
	v_cvt_pk_bf16_f32 v38, v38, v39
	v_cvt_pk_bf16_f32 v39, v40, v41
	v_cvt_pk_bf16_f32 v40, v36, v37
	v_cvt_pk_bf16_f32 v41, v34, v23
	v_permlane32_swap_b32_e32 v24, v26
	v_permlane32_swap_b32_e32 v25, v27
	v_mul_f32_e32 v22, v6, v32
	v_mov_b32_e32 v6, v15
	v_permlane32_swap_b32_e32 v38, v40
	v_permlane32_swap_b32_e32 v39, v41
	global_store_dwordx4 v[20:21], v[24:27], off offset:32
	v_pk_mul_f32 v[6:7], v[6:7], v[32:33]
	global_store_dwordx4 v[20:21], v[38:41], off
	v_pk_mul_f32 v[24:25], v[0:1], v[32:33]
	v_pk_mul_f32 v[0:1], v[8:9], v[32:33]
	v_pk_mul_f32 v[26:27], v[2:3], v[32:33]
	v_pk_mul_f32 v[2:3], v[10:11], v[32:33]
	v_pk_mul_f32 v[10:11], v[4:5], v[32:33]
	v_pk_mul_f32 v[4:5], v[12:13], v[32:33]
	v_mul_f32_e32 v8, v14, v32
	s_and_saveexec_b64 s[8:9], s[0:1]
	s_cbranch_execz .LBB0_751
	v_mov_b32_e32 v49, v193
	v_lshl_add_u64 v[28:29], v[18:19], 0, v[48:49]
	v_lshl_add_u64 v[30:31], v[16:17], 0, v[48:49]
	global_load_dwordx4 v[12:15], v[28:29], off
	global_load_dwordx4 v[16:19], v[30:31], off
	v_mov_b32_e32 v9, v6
	v_mov_b32_e32 v23, v7
	s_waitcnt vmcnt(0) lgkmcnt(0)
	v_pk_mul_f32 v[32:33], v[0:1], v[16:17]
	v_pk_mul_f32 v[16:17], v[24:25], v[16:17]
	v_pk_fma_f32 v[32:33], v[24:25], v[12:13], v[32:33] neg_lo:[0,0,1] neg_hi:[0,0,1]
	v_pk_fma_f32 v[0:1], v[0:1], v[12:13], v[16:17]
	v_pk_mul_f32 v[12:13], v[2:3], v[18:19]
	s_nop 0
	v_pk_fma_f32 v[34:35], v[26:27], v[14:15], v[12:13] neg_lo:[0,0,1] neg_hi:[0,0,1]
	v_pk_mul_f32 v[12:13], v[26:27], v[18:19]
	v_mov_b32_e32 v26, v34
	v_pk_fma_f32 v[2:3], v[2:3], v[14:15], v[12:13]
	global_load_dwordx4 v[12:15], v[28:29], off offset:32
	global_load_dwordx4 v[16:19], v[30:31], off offset:32
	v_mov_b32_e32 v27, v35
	s_waitcnt vmcnt(0)
	v_pk_mul_f32 v[24:25], v[4:5], v[16:17]
	s_nop 0
	v_pk_fma_f32 v[28:29], v[10:11], v[12:13], v[24:25] neg_lo:[0,0,1] neg_hi:[0,0,1]
	v_pk_mul_f32 v[10:11], v[10:11], v[16:17]
	v_mov_b32_e32 v24, v32
	v_pk_fma_f32 v[4:5], v[4:5], v[12:13], v[10:11]
	v_mul_f32_e32 v10, v22, v18
	v_mul_f32_e32 v12, v8, v14
	v_pk_mul_f32 v[8:9], v[8:9], v[18:19]
	v_mov_b32_e32 v18, v15
	v_pk_mul_f32 v[6:7], v[6:7], v[18:19]
	v_pk_fma_f32 v[22:23], v[22:23], v[14:15], v[8:9] neg_lo:[0,0,1] neg_hi:[0,0,1]
	v_mov_b32_e32 v13, v6
	v_mov_b32_e32 v11, v7
	v_pk_add_f32 v[8:9], v[12:13], v[10:11]
	v_mov_b32_e32 v25, v33
	v_mov_b32_e32 v10, v28
	v_mov_b32_e32 v11, v29
	v_mov_b32_e32 v7, v23
	v_mov_b32_e32 v6, v9
.LBB0_751:
	s_or_b64 exec, exec, s[8:9]
	v_cvt_pk_bf16_f32 v12, v24, v25
	v_cvt_pk_bf16_f32 v13, v26, v27
	v_cvt_pk_bf16_f32 v14, v10, v11
	v_cvt_pk_bf16_f32 v15, v22, v7
	v_cvt_pk_bf16_f32 v0, v0, v1
	v_cvt_pk_bf16_f32 v1, v2, v3
	v_cvt_pk_bf16_f32 v2, v4, v5
	v_cvt_pk_bf16_f32 v3, v8, v6
	v_permlane32_swap_b32_e32 v12, v14
	v_permlane32_swap_b32_e32 v13, v15
	v_permlane32_swap_b32_e32 v0, v2
	v_permlane32_swap_b32_e32 v1, v3
	global_store_dwordx4 v[20:21], v[12:15], off offset:64
	global_store_dwordx4 v[20:21], v[0:3], off offset:96

.LBB0_753:
	s_andn2_b64 vcc, exec, s[0:1]
	s_cbranch_vccnz .LBB0_371
	v_readlane_b32 s11, v254, 45
	s_ashr_i32 s0, s11, 5
	v_readlane_b32 s1, v253, 58
	s_add_i32 s8, s0, s1
	s_ashr_i32 s9, s8, 31
	s_lshl_b64 s[0:1], s[8:9], 20
	v_readlane_b32 s10, v254, 35
	s_add_u32 s14, s10, s0
	v_readlane_b32 s0, v254, 36
	s_addc_u32 s15, s0, s1
	s_lshl_b32 s0, s11, 5
	s_and_b32 s12, s0, 0x3e0
	s_cmp_lt_u32 s11, 32
	s_cselect_b64 s[0:1], -1, 0
	v_ashrrev_i32_e32 v14, 3, v198
	s_and_b64 s[10:11], s[0:1], exec
	v_add_u32_e32 v0, s12, v14
	v_min_i32_e32 v0, 0x3f7, v0
	s_mov_b32 s10, 0x81020409
	v_mul_hi_i32 v1, v0, s10
	v_add_u32_e32 v1, v1, v0
	v_lshrrev_b32_e32 v3, 31, v1
	v_ashrrev_i32_e32 v1, 6, v1
	v_readlane_b32 s10, v254, 3
	v_add_u32_e32 v1, v1, v3
	v_readlane_b32 s11, v254, 4
	v_add_lshl_u32 v3, v1, v0, 4
	v_ashrrev_i32_e32 v101, 6, v198
	v_mov_b64_e32 v[0:1], s[10:11]
	v_mad_i64_i32 v[0:1], s[10:11], v3, s16, v[0:1]
	s_movk_i32 s10, 0xf00
	v_lshlrev_b32_e32 v3, 3, v198
	s_cselect_b32 s16, s10, 0xf80
	s_mov_b64 s[10:11], 0x3e38aa3b
	v_and_b32_e32 v4, 56, v3
	s_mov_b32 s17, s11
	v_lshl_add_u64 v[0:1], v[0:1], 0, s[16:17]
	v_lshlrev_b32_e32 v192, 1, v4
	v_readlane_b32 s36, v252, 10
	v_lshl_add_u64 v[92:93], v[0:1], 0, v[192:193]
	v_lshlrev_b32_e32 v0, 1, v101
	v_readlane_b32 s38, v252, 12
	v_readlane_b32 s40, v252, 14
	v_ashrrev_i32_e32 v1, 31, v0
	v_and_b32_e32 v2, 63, v198
	v_readlane_b32 s39, v252, 13
	v_readlane_b32 s41, v252, 15
	s_cselect_b32 s18, s38, s40
	v_readlane_b32 s10, v254, 39
	v_lshlrev_b64 v[0:1], 17, v[0:1]
	s_cselect_b32 s13, s39, s41
	v_readlane_b32 s11, v254, 40
	s_add_u32 s10, s18, s10
	v_lshl_add_u64 v[0:1], s[14:15], 0, v[0:1]
	v_lshlrev_b32_e32 v2, 4, v2
	v_mov_b32_e32 v3, v193
	s_addc_u32 s11, s13, s11
	v_lshl_add_u64 v[90:91], v[0:1], 0, v[2:3]
	s_waitcnt lgkmcnt(0)
	s_barrier
	global_load_dwordx4 v[0:3], v[92:93], off
	v_lshlrev_b32_e32 v96, 2, v4
	global_load_dwordx4 v[4:7], v96, s[10:11] offset:16
	global_load_dwordx4 v[8:11], v96, s[10:11]
	s_movk_i32 s13, 0x90
	v_mad_u64_u32 v[88:89], s[14:15], v14, s13, v[192:193]
	s_movk_i32 s14, 0x1000
	v_bfe_u32 v102, v198, 5, 1
	v_and_b32_e32 v100, 31, v198
	v_lshlrev_b32_e32 v89, 4, v102
	v_mad_u32_u24 v103, v100, s13, v89
	s_mov_b32 s13, 0x21000
	s_movk_i32 s15, 0x3000
	s_mov_b32 s26, 0x22000
	s_movk_i32 s16, 0x5000
	s_mov_b32 s27, 0x24000
	s_mov_b32 s17, 0x9000
	s_mov_b32 s28, 0x26000
	s_mov_b32 s18, 0xc000
	s_mov_b32 s29, 0x27000
	s_mov_b32 s25, 0xe000
	s_mov_b32 s30, 0x29000
	s_mov_b32 s31, 0x2b000
	s_mov_b32 s34, 0x2d000
	s_mov_b32 s24, 0x19000
	v_mov_b32_e32 v97, v193
	v_lshl_add_u64 v[94:95], s[10:11], 0, v[96:97]
	s_mov_b32 s35, 0x2f000
	v_readlane_b32 s37, v252, 11
	v_readlane_b32 s42, v252, 16
	v_readlane_b32 s43, v252, 17
	v_readlane_b32 s44, v252, 18
	v_readlane_b32 s45, v252, 19
	v_readlane_b32 s46, v252, 20
	v_readlane_b32 s47, v252, 21
	v_readlane_b32 s48, v252, 22
	v_readlane_b32 s49, v252, 23
	v_readlane_b32 s50, v252, 24
	v_readlane_b32 s51, v252, 25
	s_waitcnt vmcnt(2)
	v_lshlrev_b32_e32 v12, 16, v0
	v_and_b32_e32 v13, 0xffff0000, v0
	s_waitcnt vmcnt(0)
	v_pk_add_f32 v[8:9], v[8:9], v[12:13]
	v_add_co_u32_e32 v12, vcc, s22, v90
	v_cvt_pk_bf16_f32 v0, v8, v9
	v_lshlrev_b32_e32 v8, 16, v1
	v_and_b32_e32 v9, 0xffff0000, v1
	v_pk_add_f32 v[8:9], v[10:11], v[8:9]
	v_addc_co_u32_e32 v13, vcc, 0, v91, vcc
	v_cvt_pk_bf16_f32 v1, v8, v9
	v_lshlrev_b32_e32 v8, 16, v2
	v_and_b32_e32 v9, 0xffff0000, v2
	v_pk_add_f32 v[4:5], v[4:5], v[8:9]
	s_nop 0
	v_cvt_pk_bf16_f32 v2, v4, v5
	v_lshlrev_b32_e32 v4, 16, v3
	v_and_b32_e32 v5, 0xffff0000, v3
	v_pk_add_f32 v[4:5], v[6:7], v[4:5]
	s_nop 0
	v_cvt_pk_bf16_f32 v3, v4, v5
	global_load_dwordx4 v[4:7], v[90:91], off
	global_load_dwordx4 v[40:43], v[90:91], off offset:1024
	global_load_dwordx4 v[36:39], v[90:91], off offset:2048
	global_load_dwordx4 v[32:35], v[90:91], off offset:3072
	global_load_dwordx4 v[8:11], v[12:13], off
	global_load_dwordx4 v[60:63], v[12:13], off offset:1024
	global_load_dwordx4 v[56:59], v[12:13], off offset:2048
	global_load_dwordx4 v[48:51], v[12:13], off offset:3072
	ds_write_b128 v88, v[0:3]
	v_add_co_u32_e32 v0, vcc, s14, v92
	s_nop 1
	v_addc_co_u32_e32 v1, vcc, 0, v93, vcc
	global_load_dwordx4 v[0:3], v[0:1], off offset:3328
	s_nop 0
	global_load_dwordx4 v[12:15], v96, s[10:11] offset:272
	global_load_dwordx4 v[16:19], v96, s[10:11] offset:256
	s_waitcnt lgkmcnt(0)
	s_barrier
	v_add_co_u32_e32 v68, vcc, s14, v90
	s_waitcnt vmcnt(2)
	v_lshlrev_b32_e32 v20, 16, v0
	v_and_b32_e32 v21, 0xffff0000, v0
	v_lshlrev_b32_e32 v0, 16, v1
	v_and_b32_e32 v1, 0xffff0000, v1
	s_waitcnt vmcnt(0)
	v_pk_add_f32 v[0:1], v[18:19], v[0:1]
	v_pk_add_f32 v[16:17], v[16:17], v[20:21]
	v_cvt_pk_bf16_f32 v77, v0, v1
	v_lshlrev_b32_e32 v0, 16, v2
	v_and_b32_e32 v1, 0xffff0000, v2
	v_pk_add_f32 v[0:1], v[12:13], v[0:1]
	v_cvt_pk_bf16_f32 v76, v16, v17
	v_cvt_pk_bf16_f32 v78, v0, v1
	v_lshlrev_b32_e32 v0, 16, v3
	v_and_b32_e32 v1, 0xffff0000, v3
	v_pk_add_f32 v[0:1], v[14:15], v[0:1]
	v_addc_co_u32_e32 v69, vcc, 0, v91, vcc
	v_cvt_pk_bf16_f32 v79, v0, v1
	ds_read_b128 v[0:3], v103
	ds_read_b128 v[64:67], v103 offset:32
	s_waitcnt lgkmcnt(1)
	v_mfma_f32_32x32x16_bf16 v[16:31], v[4:7], v[0:3], 0
	v_add_co_u32_e32 v72, vcc, s13, v90
	global_load_dwordx4 v[44:47], v[68:69], off
	s_nop 0
	v_addc_co_u32_e32 v73, vcc, 0, v91, vcc
	global_load_dwordx4 v[52:55], v[72:73], off
	s_movk_i32 s13, 0x2000
	v_mfma_f32_32x32x16_bf16 v[0:15], v[8:11], v[0:3], 0
	s_waitcnt lgkmcnt(0)
	v_mfma_f32_32x32x16_bf16 v[16:31], v[40:43], v[64:67], v[16:31]
	global_load_dwordx4 v[40:43], v[68:69], off offset:1024
	v_mfma_f32_32x32x16_bf16 v[0:15], v[60:63], v[64:67], v[0:15]
	ds_read_b128 v[64:67], v103 offset:64
	global_load_dwordx4 v[60:63], v[72:73], off offset:1024
	s_waitcnt lgkmcnt(0)
	v_mfma_f32_32x32x16_bf16 v[16:31], v[36:39], v[64:67], v[16:31]
	global_load_dwordx4 v[36:39], v[68:69], off offset:2048
	s_nop 0
	global_load_dwordx4 v[68:71], v[68:69], off offset:3072
	v_mfma_f32_32x32x16_bf16 v[0:15], v[56:59], v[64:67], v[0:15]
	ds_read_b128 v[56:59], v103 offset:96
	global_load_dwordx4 v[64:67], v[72:73], off offset:2048
	s_nop 0
	global_load_dwordx4 v[72:75], v[72:73], off offset:3072
	ds_write_b128 v88, v[76:79] offset:4608
	s_waitcnt lgkmcnt(1)
	v_mfma_f32_32x32x16_bf16 v[16:31], v[32:35], v[56:59], v[16:31]
	v_add_co_u32_e32 v32, vcc, s15, v92
	s_nop 1
	v_addc_co_u32_e32 v33, vcc, 0, v93, vcc
	v_add_co_u32_e32 v84, vcc, s13, v90
	v_mfma_f32_32x32x16_bf16 v[0:15], v[48:51], v[56:59], v[0:15]
	global_load_dwordx4 v[32:35], v[32:33], off offset:2560
	s_nop 0
	global_load_dwordx4 v[48:51], v96, s[10:11] offset:528
	global_load_dwordx4 v[56:59], v96, s[10:11] offset:512
	s_waitcnt lgkmcnt(0)
	s_barrier
	v_addc_co_u32_e32 v85, vcc, 0, v91, vcc
	v_add_co_u32_e32 v86, vcc, s26, v90
	s_mov_b32 s13, 0x23000
	s_nop 0
	v_addc_co_u32_e32 v87, vcc, 0, v91, vcc
	s_waitcnt vmcnt(2)
	v_lshlrev_b32_e32 v76, 16, v32
	v_and_b32_e32 v77, 0xffff0000, v32
	v_lshlrev_b32_e32 v32, 16, v33
	v_and_b32_e32 v33, 0xffff0000, v33
	s_waitcnt vmcnt(0)
	v_pk_add_f32 v[32:33], v[58:59], v[32:33]
	v_pk_add_f32 v[56:57], v[56:57], v[76:77]
	v_cvt_pk_bf16_f32 v77, v32, v33
	v_lshlrev_b32_e32 v32, 16, v34
	v_and_b32_e32 v33, 0xffff0000, v34
	v_pk_add_f32 v[32:33], v[48:49], v[32:33]
	v_cvt_pk_bf16_f32 v76, v56, v57
	v_cvt_pk_bf16_f32 v78, v32, v33
	v_lshlrev_b32_e32 v32, 16, v35
	v_and_b32_e32 v33, 0xffff0000, v35
	v_pk_add_f32 v[32:33], v[50:51], v[32:33]
	s_nop 0
	v_cvt_pk_bf16_f32 v79, v32, v33
	ds_read_b128 v[32:35], v103 offset:4608
	ds_read_b128 v[48:51], v103 offset:4640
	s_waitcnt lgkmcnt(1)
	v_mfma_f32_32x32x16_bf16 v[16:31], v[44:47], v[32:35], v[16:31]
	ds_read_b128 v[44:47], v103 offset:4704
	global_load_dwordx4 v[80:83], v[84:85], off
	global_load_dwordx4 v[56:59], v[84:85], off offset:1024
	v_mfma_f32_32x32x16_bf16 v[0:15], v[52:55], v[32:35], v[0:15]
	global_load_dwordx4 v[52:55], v[86:87], off
	global_load_dwordx4 v[32:35], v[84:85], off offset:2048
	s_waitcnt lgkmcnt(1)
	v_mfma_f32_32x32x16_bf16 v[16:31], v[40:43], v[48:51], v[16:31]
	ds_read_b128 v[40:43], v103 offset:4672
	v_mfma_f32_32x32x16_bf16 v[0:15], v[60:63], v[48:51], v[0:15]
	global_load_dwordx4 v[48:51], v[86:87], off offset:1024
	s_waitcnt lgkmcnt(0)
	v_mfma_f32_32x32x16_bf16 v[16:31], v[36:39], v[40:43], v[16:31]
	global_load_dwordx4 v[36:39], v[86:87], off offset:2048
	v_mfma_f32_32x32x16_bf16 v[0:15], v[64:67], v[40:43], v[0:15]
	global_load_dwordx4 v[40:43], v[84:85], off offset:3072
	v_mfma_f32_32x32x16_bf16 v[16:31], v[68:71], v[44:47], v[16:31]
	v_add_co_u32_e32 v68, vcc, s16, v92
	s_nop 1
	v_addc_co_u32_e32 v69, vcc, 0, v93, vcc
	v_mfma_f32_32x32x16_bf16 v[0:15], v[72:75], v[44:47], v[0:15]
	global_load_dwordx4 v[44:47], v[86:87], off offset:3072
	ds_write_b128 v88, v[76:79]
	global_load_dwordx4 v[60:63], v96, s[10:11] offset:784
	global_load_dwordx4 v[64:67], v96, s[10:11] offset:768
	v_add_co_u32_e32 v76, vcc, s15, v90
	global_load_dwordx4 v[68:71], v[68:69], off offset:1792
	s_waitcnt lgkmcnt(0)
	s_barrier
	v_addc_co_u32_e32 v77, vcc, 0, v91, vcc
	v_add_co_u32_e32 v78, vcc, s13, v90
	s_movk_i32 s15, 0x7000
	s_nop 0
	v_addc_co_u32_e32 v79, vcc, 0, v91, vcc
	s_movk_i32 s13, 0x4000
	s_waitcnt vmcnt(0)
	v_lshlrev_b32_e32 v72, 16, v68
	v_and_b32_e32 v73, 0xffff0000, v68
	v_lshlrev_b32_e32 v68, 16, v69
	v_and_b32_e32 v69, 0xffff0000, v69
	v_pk_add_f32 v[64:65], v[64:65], v[72:73]
	v_pk_add_f32 v[66:67], v[66:67], v[68:69]
	v_cvt_pk_bf16_f32 v64, v64, v65
	v_cvt_pk_bf16_f32 v65, v66, v67
	v_lshlrev_b32_e32 v66, 16, v70
	v_and_b32_e32 v67, 0xffff0000, v70
	v_pk_add_f32 v[60:61], v[60:61], v[66:67]
	s_nop 0
	v_cvt_pk_bf16_f32 v66, v60, v61
	v_lshlrev_b32_e32 v60, 16, v71
	v_and_b32_e32 v61, 0xffff0000, v71
	v_pk_add_f32 v[60:61], v[62:63], v[60:61]
	s_nop 0
	v_cvt_pk_bf16_f32 v67, v60, v61
	ds_read_b128 v[60:63], v103
	ds_read_b128 v[68:71], v103 offset:32
	s_waitcnt lgkmcnt(1)
	v_mfma_f32_32x32x16_bf16 v[16:31], v[80:83], v[60:63], v[16:31]
	global_load_dwordx4 v[72:75], v[76:77], off
	v_mfma_f32_32x32x16_bf16 v[0:15], v[52:55], v[60:63], v[0:15]
	ds_read_b128 v[60:63], v103 offset:64
	global_load_dwordx4 v[52:55], v[78:79], off
	s_waitcnt lgkmcnt(1)
	v_mfma_f32_32x32x16_bf16 v[16:31], v[56:59], v[68:71], v[16:31]
	global_load_dwordx4 v[56:59], v[76:77], off offset:1024
	v_mfma_f32_32x32x16_bf16 v[0:15], v[48:51], v[68:71], v[0:15]
	global_load_dwordx4 v[48:51], v[78:79], off offset:1024
	s_waitcnt lgkmcnt(0)
	v_mfma_f32_32x32x16_bf16 v[16:31], v[32:35], v[60:63], v[16:31]
	global_load_dwordx4 v[32:35], v[76:77], off offset:2048
	v_mfma_f32_32x32x16_bf16 v[0:15], v[36:39], v[60:63], v[0:15]
	ds_read_b128 v[60:63], v103 offset:96
	global_load_dwordx4 v[36:39], v[78:79], off offset:2048
	s_waitcnt lgkmcnt(0)
	v_mfma_f32_32x32x16_bf16 v[16:31], v[40:43], v[60:63], v[16:31]
	global_load_dwordx4 v[40:43], v[76:77], off offset:3072
	v_mfma_f32_32x32x16_bf16 v[0:15], v[44:47], v[60:63], v[0:15]
	v_add_co_u32_e32 v60, vcc, s15, v92
	global_load_dwordx4 v[44:47], v[78:79], off offset:3072
	ds_write_b128 v88, v[64:67] offset:4608
	v_addc_co_u32_e32 v61, vcc, 0, v93, vcc
	global_load_dwordx4 v[60:63], v[60:61], off offset:1024
	s_nop 0
	global_load_dwordx4 v[64:67], v96, s[10:11] offset:1040
	global_load_dwordx4 v[68:71], v96, s[10:11] offset:1024
	s_waitcnt lgkmcnt(0)
	s_barrier
	s_waitcnt vmcnt(2)
	v_lshlrev_b32_e32 v76, 16, v60
	v_and_b32_e32 v77, 0xffff0000, v60
	v_lshlrev_b32_e32 v60, 16, v61
	v_and_b32_e32 v61, 0xffff0000, v61
	s_waitcnt vmcnt(0)
	v_pk_add_f32 v[68:69], v[68:69], v[76:77]
	v_pk_add_f32 v[60:61], v[70:71], v[60:61]
	v_cvt_pk_bf16_f32 v68, v68, v69
	v_cvt_pk_bf16_f32 v69, v60, v61
	v_lshlrev_b32_e32 v60, 16, v62
	v_and_b32_e32 v61, 0xffff0000, v62
	v_pk_add_f32 v[60:61], v[64:65], v[60:61]
	v_add_co_u32_e32 v76, vcc, s13, v90
	v_cvt_pk_bf16_f32 v70, v60, v61
	v_lshlrev_b32_e32 v60, 16, v63
	v_and_b32_e32 v61, 0xffff0000, v63
	v_pk_add_f32 v[60:61], v[66:67], v[60:61]
	v_addc_co_u32_e32 v77, vcc, 0, v91, vcc
	v_cvt_pk_bf16_f32 v71, v60, v61
	ds_read_b128 v[60:63], v103 offset:4608
	ds_read_b128 v[64:67], v103 offset:4640
	s_waitcnt lgkmcnt(1)
	v_mfma_f32_32x32x16_bf16 v[16:31], v[72:75], v[60:63], v[16:31]
	v_add_co_u32_e32 v78, vcc, s27, v90
	global_load_dwordx4 v[72:75], v[76:77], off
	s_nop 0
	v_addc_co_u32_e32 v79, vcc, 0, v91, vcc
	s_mov_b32 s13, 0x25000
	v_mfma_f32_32x32x16_bf16 v[0:15], v[52:55], v[60:63], v[0:15]
	global_load_dwordx4 v[60:63], v[78:79], off
	global_load_dwordx4 v[52:55], v[76:77], off offset:1024
	s_waitcnt lgkmcnt(0)
	v_mfma_f32_32x32x16_bf16 v[16:31], v[56:59], v[64:67], v[16:31]
	ds_read_b128 v[56:59], v103 offset:4672
	v_mfma_f32_32x32x16_bf16 v[0:15], v[48:51], v[64:67], v[0:15]
	global_load_dwordx4 v[48:51], v[78:79], off offset:1024
	s_waitcnt lgkmcnt(0)
	v_mfma_f32_32x32x16_bf16 v[16:31], v[32:35], v[56:59], v[16:31]
	global_load_dwordx4 v[32:35], v[76:77], off offset:2048
	v_mfma_f32_32x32x16_bf16 v[0:15], v[36:39], v[56:59], v[0:15]
	ds_read_b128 v[56:59], v103 offset:4704
	global_load_dwordx4 v[36:39], v[78:79], off offset:2048
	s_waitcnt lgkmcnt(0)
	v_mfma_f32_32x32x16_bf16 v[16:31], v[40:43], v[56:59], v[16:31]
	global_load_dwordx4 v[40:43], v[76:77], off offset:3072
	v_mfma_f32_32x32x16_bf16 v[0:15], v[44:47], v[56:59], v[0:15]
	global_load_dwordx4 v[44:47], v[78:79], off offset:3072
	ds_write_b128 v88, v[68:71]
	v_add_co_u32_e32 v68, vcc, s17, v92
	global_load_dwordx4 v[56:59], v96, s[10:11] offset:1296
	global_load_dwordx4 v[64:67], v96, s[10:11] offset:1280
	v_addc_co_u32_e32 v69, vcc, 0, v93, vcc
	global_load_dwordx4 v[68:71], v[68:69], off offset:256
	s_waitcnt lgkmcnt(0)
	s_barrier
	s_waitcnt vmcnt(0)
	v_lshlrev_b32_e32 v76, 16, v68
	v_and_b32_e32 v77, 0xffff0000, v68
	v_lshlrev_b32_e32 v68, 16, v69
	v_and_b32_e32 v69, 0xffff0000, v69
	v_pk_add_f32 v[64:65], v[64:65], v[76:77]
	v_pk_add_f32 v[66:67], v[66:67], v[68:69]
	v_cvt_pk_bf16_f32 v64, v64, v65
	v_cvt_pk_bf16_f32 v65, v66, v67
	v_lshlrev_b32_e32 v66, 16, v70
	v_and_b32_e32 v67, 0xffff0000, v70
	v_pk_add_f32 v[56:57], v[56:57], v[66:67]
	s_nop 0
	v_cvt_pk_bf16_f32 v66, v56, v57
	v_lshlrev_b32_e32 v56, 16, v71
	v_and_b32_e32 v57, 0xffff0000, v71
	ds_read_b128 v[68:71], v103
	ds_read_b128 v[76:79], v103 offset:32
	s_waitcnt lgkmcnt(1)
	v_mfma_f32_32x32x16_bf16 v[16:31], v[72:75], v[68:71], v[16:31]
	v_add_co_u32_e32 v72, vcc, s16, v90
	v_add_f32_e64 v56, v58, v56
	v_add_f32_e64 v57, v59, v57
	v_addc_co_u32_e32 v73, vcc, 0, v91, vcc
	v_add_co_u32_e32 v74, vcc, s13, v90
	v_mfma_f32_32x32x16_bf16 v[0:15], v[60:63], v[68:71], v[0:15]
	ds_read_b128 v[68:71], v103 offset:64
	v_cvt_pk_bf16_f32 v67, v56, v57
	v_addc_co_u32_e32 v75, vcc, 0, v91, vcc
	s_mov_b32 s16, 0xa000
	global_load_dwordx4 v[56:59], v[72:73], off
	global_load_dwordx4 v[60:63], v[74:75], off
	s_waitcnt lgkmcnt(1)
	v_mfma_f32_32x32x16_bf16 v[16:31], v[52:55], v[76:79], v[16:31]
	global_load_dwordx4 v[52:55], v[72:73], off offset:1024
	s_movk_i32 s13, 0x6000
	v_mfma_f32_32x32x16_bf16 v[0:15], v[48:51], v[76:79], v[0:15]
	global_load_dwordx4 v[48:51], v[74:75], off offset:1024
	s_waitcnt lgkmcnt(0)
	v_mfma_f32_32x32x16_bf16 v[16:31], v[32:35], v[68:71], v[16:31]
	global_load_dwordx4 v[32:35], v[72:73], off offset:2048
	v_mfma_f32_32x32x16_bf16 v[0:15], v[36:39], v[68:71], v[0:15]
	ds_read_b128 v[68:71], v103 offset:96
	global_load_dwordx4 v[36:39], v[74:75], off offset:2048
	s_waitcnt lgkmcnt(0)
	v_mfma_f32_32x32x16_bf16 v[16:31], v[40:43], v[68:71], v[16:31]
	global_load_dwordx4 v[40:43], v[72:73], off offset:3072
	v_mfma_f32_32x32x16_bf16 v[0:15], v[44:47], v[68:71], v[0:15]
	global_load_dwordx4 v[44:47], v[74:75], off offset:3072
	ds_write_b128 v88, v[64:67] offset:4608
	v_add_co_u32_e32 v64, vcc, s16, v92
	s_nop 1
	v_addc_co_u32_e32 v65, vcc, 0, v93, vcc
	global_load_dwordx4 v[64:67], v[64:65], off offset:3584
	s_nop 0
	global_load_dwordx4 v[68:71], v96, s[10:11] offset:1552
	global_load_dwordx4 v[72:75], v96, s[10:11] offset:1536
	s_waitcnt lgkmcnt(0)
	s_barrier
	s_waitcnt vmcnt(2)
	v_lshlrev_b32_e32 v76, 16, v64
	v_and_b32_e32 v77, 0xffff0000, v64
	s_waitcnt vmcnt(0)
	v_pk_add_f32 v[72:73], v[72:73], v[76:77]
	v_add_co_u32_e32 v76, vcc, s13, v90
	v_cvt_pk_bf16_f32 v64, v72, v73
	v_lshlrev_b32_e32 v72, 16, v65
	v_and_b32_e32 v73, 0xffff0000, v65
	v_pk_add_f32 v[72:73], v[74:75], v[72:73]
	v_addc_co_u32_e32 v77, vcc, 0, v91, vcc
	v_cvt_pk_bf16_f32 v65, v72, v73
	v_lshlrev_b32_e32 v72, 16, v66
	v_and_b32_e32 v73, 0xffff0000, v66
	v_pk_add_f32 v[68:69], v[68:69], v[72:73]
	v_add_co_u32_e32 v78, vcc, s28, v90
	v_cvt_pk_bf16_f32 v66, v68, v69
	v_lshlrev_b32_e32 v68, 16, v67
	v_and_b32_e32 v69, 0xffff0000, v67
	v_pk_add_f32 v[68:69], v[70:71], v[68:69]
	v_addc_co_u32_e32 v79, vcc, 0, v91, vcc
	v_cvt_pk_bf16_f32 v67, v68, v69
	ds_read_b128 v[68:71], v103 offset:4608
	ds_read_b128 v[72:75], v103 offset:4640
	s_waitcnt lgkmcnt(1)
	v_mfma_f32_32x32x16_bf16 v[16:31], v[56:59], v[68:71], v[16:31]
	global_load_dwordx4 v[56:59], v[76:77], off
	s_mov_b32 s13, 0x8000
	v_mfma_f32_32x32x16_bf16 v[0:15], v[60:63], v[68:71], v[0:15]
	ds_read_b128 v[68:71], v103 offset:4672
	global_load_dwordx4 v[60:63], v[78:79], off
	s_waitcnt lgkmcnt(1)
	v_mfma_f32_32x32x16_bf16 v[16:31], v[52:55], v[72:75], v[16:31]
	global_load_dwordx4 v[52:55], v[76:77], off offset:1024
	v_mfma_f32_32x32x16_bf16 v[0:15], v[48:51], v[72:75], v[0:15]
	v_add_co_u32_e32 v72, vcc, s18, v92
	global_load_dwordx4 v[48:51], v[78:79], off offset:1024
	s_nop 0
	v_addc_co_u32_e32 v73, vcc, 0, v93, vcc
	s_waitcnt lgkmcnt(0)
	v_mfma_f32_32x32x16_bf16 v[16:31], v[32:35], v[68:71], v[16:31]
	global_load_dwordx4 v[32:35], v[76:77], off offset:2048
	v_mfma_f32_32x32x16_bf16 v[0:15], v[36:39], v[68:71], v[0:15]
	ds_read_b128 v[68:71], v103 offset:4704
	global_load_dwordx4 v[36:39], v[78:79], off offset:2048
	s_waitcnt lgkmcnt(0)
	v_mfma_f32_32x32x16_bf16 v[16:31], v[40:43], v[68:71], v[16:31]
	global_load_dwordx4 v[40:43], v[76:77], off offset:3072
	v_mfma_f32_32x32x16_bf16 v[0:15], v[44:47], v[68:71], v[0:15]
	global_load_dwordx4 v[44:47], v[78:79], off offset:3072
	ds_write_b128 v88, v[64:67]
	global_load_dwordx4 v[64:67], v96, s[10:11] offset:1808
	global_load_dwordx4 v[68:71], v96, s[10:11] offset:1792
	s_nop 0
	global_load_dwordx4 v[72:75], v[72:73], off offset:2816
	s_waitcnt lgkmcnt(0)
	s_barrier
	s_waitcnt vmcnt(0)
	v_lshlrev_b32_e32 v76, 16, v72
	v_and_b32_e32 v77, 0xffff0000, v72
	v_lshlrev_b32_e32 v72, 16, v73
	v_and_b32_e32 v73, 0xffff0000, v73
	v_pk_add_f32 v[68:69], v[68:69], v[76:77]
	v_pk_add_f32 v[70:71], v[70:71], v[72:73]
	v_cvt_pk_bf16_f32 v68, v68, v69
	v_cvt_pk_bf16_f32 v69, v70, v71
	v_lshlrev_b32_e32 v70, 16, v74
	v_and_b32_e32 v71, 0xffff0000, v74
	v_pk_add_f32 v[64:65], v[64:65], v[70:71]
	v_add_co_u32_e32 v76, vcc, s15, v90
	v_cvt_pk_bf16_f32 v70, v64, v65
	v_lshlrev_b32_e32 v64, 16, v75
	v_and_b32_e32 v65, 0xffff0000, v75
	v_pk_add_f32 v[64:65], v[66:67], v[64:65]
	v_addc_co_u32_e32 v77, vcc, 0, v91, vcc
	v_cvt_pk_bf16_f32 v71, v64, v65
	ds_read_b128 v[64:67], v103
	ds_read_b128 v[72:75], v103 offset:32
	s_waitcnt lgkmcnt(1)
	v_mfma_f32_32x32x16_bf16 v[16:31], v[56:59], v[64:67], v[16:31]
	v_add_co_u32_e32 v78, vcc, s29, v90
	global_load_dwordx4 v[56:59], v[76:77], off
	s_nop 0
	v_addc_co_u32_e32 v79, vcc, 0, v91, vcc
	s_mov_b32 s15, 0x12000
	v_mfma_f32_32x32x16_bf16 v[0:15], v[60:63], v[64:67], v[0:15]
	ds_read_b128 v[64:67], v103 offset:64
	global_load_dwordx4 v[60:63], v[78:79], off
	s_waitcnt lgkmcnt(1)
	v_mfma_f32_32x32x16_bf16 v[16:31], v[52:55], v[72:75], v[16:31]
	global_load_dwordx4 v[52:55], v[76:77], off offset:1024
	v_mfma_f32_32x32x16_bf16 v[0:15], v[48:51], v[72:75], v[0:15]
	global_load_dwordx4 v[48:51], v[78:79], off offset:1024
	s_waitcnt lgkmcnt(0)
	v_mfma_f32_32x32x16_bf16 v[16:31], v[32:35], v[64:67], v[16:31]
	global_load_dwordx4 v[32:35], v[76:77], off offset:2048
	v_mfma_f32_32x32x16_bf16 v[0:15], v[36:39], v[64:67], v[0:15]
	ds_read_b128 v[64:67], v103 offset:96
	global_load_dwordx4 v[36:39], v[78:79], off offset:2048
	s_waitcnt lgkmcnt(0)
	v_mfma_f32_32x32x16_bf16 v[16:31], v[40:43], v[64:67], v[16:31]
	global_load_dwordx4 v[40:43], v[76:77], off offset:3072
	v_mfma_f32_32x32x16_bf16 v[0:15], v[44:47], v[64:67], v[0:15]
	v_add_co_u32_e32 v64, vcc, s25, v92
	global_load_dwordx4 v[44:47], v[78:79], off offset:3072
	ds_write_b128 v88, v[68:71] offset:4608
	v_addc_co_u32_e32 v65, vcc, 0, v93, vcc
	global_load_dwordx4 v[64:67], v[64:65], off offset:2048
	s_nop 0
	global_load_dwordx4 v[68:71], v96, s[10:11] offset:2064
	global_load_dwordx4 v[72:75], v96, s[10:11] offset:2048
	s_waitcnt lgkmcnt(0)
	s_barrier
	s_waitcnt vmcnt(2)
	v_lshlrev_b32_e32 v76, 16, v64
	v_and_b32_e32 v77, 0xffff0000, v64
	s_waitcnt vmcnt(0)
	v_pk_add_f32 v[72:73], v[72:73], v[76:77]
	v_add_co_u32_e32 v76, vcc, s13, v90
	v_cvt_pk_bf16_f32 v64, v72, v73
	v_lshlrev_b32_e32 v72, 16, v65
	v_and_b32_e32 v73, 0xffff0000, v65
	v_pk_add_f32 v[72:73], v[74:75], v[72:73]
	v_addc_co_u32_e32 v77, vcc, 0, v91, vcc
	v_cvt_pk_bf16_f32 v65, v72, v73
	v_lshlrev_b32_e32 v72, 16, v66
	v_and_b32_e32 v73, 0xffff0000, v66
	v_pk_add_f32 v[68:69], v[68:69], v[72:73]
	s_mov_b32 s13, 0x28000
	v_cvt_pk_bf16_f32 v66, v68, v69
	v_lshlrev_b32_e32 v68, 16, v67
	v_and_b32_e32 v69, 0xffff0000, v67
	v_pk_add_f32 v[68:69], v[70:71], v[68:69]
	v_add_co_u32_e32 v78, vcc, s13, v90
	v_cvt_pk_bf16_f32 v67, v68, v69
	ds_read_b128 v[68:71], v103 offset:4608
	ds_read_b128 v[72:75], v103 offset:4640
	s_waitcnt lgkmcnt(1)
	v_mfma_f32_32x32x16_bf16 v[16:31], v[56:59], v[68:71], v[16:31]
	v_addc_co_u32_e32 v79, vcc, 0, v91, vcc
	global_load_dwordx4 v[56:59], v[76:77], off
	s_mov_b32 s13, 0x2a000
	v_mfma_f32_32x32x16_bf16 v[0:15], v[60:63], v[68:71], v[0:15]
	ds_read_b128 v[68:71], v103 offset:4672
	global_load_dwordx4 v[60:63], v[78:79], off
	s_waitcnt lgkmcnt(1)
	v_mfma_f32_32x32x16_bf16 v[16:31], v[52:55], v[72:75], v[16:31]
	global_load_dwordx4 v[52:55], v[76:77], off offset:1024
	v_mfma_f32_32x32x16_bf16 v[0:15], v[48:51], v[72:75], v[0:15]
	v_add_co_u32_e32 v72, vcc, s19, v92
	global_load_dwordx4 v[48:51], v[78:79], off offset:1024
	s_nop 0
	v_addc_co_u32_e32 v73, vcc, 0, v93, vcc
	s_waitcnt lgkmcnt(0)
	v_mfma_f32_32x32x16_bf16 v[16:31], v[32:35], v[68:71], v[16:31]
	global_load_dwordx4 v[32:35], v[76:77], off offset:2048
	v_mfma_f32_32x32x16_bf16 v[0:15], v[36:39], v[68:71], v[0:15]
	ds_read_b128 v[68:71], v103 offset:4704
	global_load_dwordx4 v[36:39], v[78:79], off offset:2048
	s_waitcnt lgkmcnt(0)
	v_mfma_f32_32x32x16_bf16 v[16:31], v[40:43], v[68:71], v[16:31]
	global_load_dwordx4 v[40:43], v[76:77], off offset:3072
	v_mfma_f32_32x32x16_bf16 v[0:15], v[44:47], v[68:71], v[0:15]
	global_load_dwordx4 v[44:47], v[78:79], off offset:3072
	ds_write_b128 v88, v[64:67]
	global_load_dwordx4 v[64:67], v96, s[10:11] offset:2320
	global_load_dwordx4 v[68:71], v96, s[10:11] offset:2304
	s_nop 0
	global_load_dwordx4 v[72:75], v[72:73], off offset:1280
	s_waitcnt lgkmcnt(0)
	s_barrier
	s_waitcnt vmcnt(0)
	v_lshlrev_b32_e32 v76, 16, v72
	v_and_b32_e32 v77, 0xffff0000, v72
	v_lshlrev_b32_e32 v72, 16, v73
	v_and_b32_e32 v73, 0xffff0000, v73
	v_pk_add_f32 v[68:69], v[68:69], v[76:77]
	v_pk_add_f32 v[70:71], v[70:71], v[72:73]
	v_cvt_pk_bf16_f32 v68, v68, v69
	v_cvt_pk_bf16_f32 v69, v70, v71
	v_lshlrev_b32_e32 v70, 16, v74
	v_and_b32_e32 v71, 0xffff0000, v74
	v_pk_add_f32 v[64:65], v[64:65], v[70:71]
	v_add_co_u32_e32 v76, vcc, s17, v90
	v_cvt_pk_bf16_f32 v70, v64, v65
	v_lshlrev_b32_e32 v64, 16, v75
	v_and_b32_e32 v65, 0xffff0000, v75
	v_pk_add_f32 v[64:65], v[66:67], v[64:65]
	v_addc_co_u32_e32 v77, vcc, 0, v91, vcc
	v_cvt_pk_bf16_f32 v71, v64, v65
	ds_read_b128 v[64:67], v103
	ds_read_b128 v[72:75], v103 offset:32
	s_waitcnt lgkmcnt(1)
	v_mfma_f32_32x32x16_bf16 v[16:31], v[56:59], v[64:67], v[16:31]
	v_add_co_u32_e32 v78, vcc, s30, v90
	global_load_dwordx4 v[56:59], v[76:77], off
	s_nop 0
	v_addc_co_u32_e32 v79, vcc, 0, v91, vcc
	s_mov_b32 s17, 0x15000
	v_mfma_f32_32x32x16_bf16 v[0:15], v[60:63], v[64:67], v[0:15]
	ds_read_b128 v[64:67], v103 offset:64
	global_load_dwordx4 v[60:63], v[78:79], off
	s_waitcnt lgkmcnt(1)
	v_mfma_f32_32x32x16_bf16 v[16:31], v[52:55], v[72:75], v[16:31]
	global_load_dwordx4 v[52:55], v[76:77], off offset:1024
	v_mfma_f32_32x32x16_bf16 v[0:15], v[48:51], v[72:75], v[0:15]
	global_load_dwordx4 v[48:51], v[78:79], off offset:1024
	s_waitcnt lgkmcnt(0)
	v_mfma_f32_32x32x16_bf16 v[16:31], v[32:35], v[64:67], v[16:31]
	global_load_dwordx4 v[32:35], v[76:77], off offset:2048
	v_mfma_f32_32x32x16_bf16 v[0:15], v[36:39], v[64:67], v[0:15]
	ds_read_b128 v[64:67], v103 offset:96
	global_load_dwordx4 v[36:39], v[78:79], off offset:2048
	s_waitcnt lgkmcnt(0)
	v_mfma_f32_32x32x16_bf16 v[16:31], v[40:43], v[64:67], v[16:31]
	global_load_dwordx4 v[40:43], v[76:77], off offset:3072
	v_mfma_f32_32x32x16_bf16 v[0:15], v[44:47], v[64:67], v[0:15]
	v_add_co_u32_e32 v64, vcc, s15, v92
	global_load_dwordx4 v[44:47], v[78:79], off offset:3072
	ds_write_b128 v88, v[68:71] offset:4608
	v_addc_co_u32_e32 v65, vcc, 0, v93, vcc
	global_load_dwordx4 v[64:67], v[64:65], off offset:512
	s_nop 0
	global_load_dwordx4 v[68:71], v96, s[10:11] offset:2576
	global_load_dwordx4 v[72:75], v96, s[10:11] offset:2560
	s_waitcnt lgkmcnt(0)
	s_barrier
	s_waitcnt vmcnt(2)
	v_lshlrev_b32_e32 v76, 16, v64
	v_and_b32_e32 v77, 0xffff0000, v64
	s_waitcnt vmcnt(0)
	v_pk_add_f32 v[72:73], v[72:73], v[76:77]
	v_add_co_u32_e32 v76, vcc, s16, v90
	v_cvt_pk_bf16_f32 v64, v72, v73
	v_lshlrev_b32_e32 v72, 16, v65
	v_and_b32_e32 v73, 0xffff0000, v65
	v_pk_add_f32 v[72:73], v[74:75], v[72:73]
	v_addc_co_u32_e32 v77, vcc, 0, v91, vcc
	v_cvt_pk_bf16_f32 v65, v72, v73
	v_lshlrev_b32_e32 v72, 16, v66
	v_and_b32_e32 v73, 0xffff0000, v66
	v_pk_add_f32 v[68:69], v[68:69], v[72:73]
	v_add_co_u32_e32 v78, vcc, s13, v90
	v_cvt_pk_bf16_f32 v66, v68, v69
	v_lshlrev_b32_e32 v68, 16, v67
	v_and_b32_e32 v69, 0xffff0000, v67
	v_pk_add_f32 v[68:69], v[70:71], v[68:69]
	v_addc_co_u32_e32 v79, vcc, 0, v91, vcc
	v_cvt_pk_bf16_f32 v67, v68, v69
	ds_read_b128 v[68:71], v103 offset:4608
	ds_read_b128 v[72:75], v103 offset:4640
	s_waitcnt lgkmcnt(1)
	v_mfma_f32_32x32x16_bf16 v[16:31], v[56:59], v[68:71], v[16:31]
	s_mov_b32 s16, 0x13000
	global_load_dwordx4 v[56:59], v[76:77], off
	s_mov_b32 s13, 0xb000
	v_mfma_f32_32x32x16_bf16 v[0:15], v[60:63], v[68:71], v[0:15]
	ds_read_b128 v[68:71], v103 offset:4672
	global_load_dwordx4 v[60:63], v[78:79], off
	s_waitcnt lgkmcnt(1)
	v_mfma_f32_32x32x16_bf16 v[16:31], v[52:55], v[72:75], v[16:31]
	global_load_dwordx4 v[52:55], v[76:77], off offset:1024
	v_mfma_f32_32x32x16_bf16 v[0:15], v[48:51], v[72:75], v[0:15]
	global_load_dwordx4 v[48:51], v[78:79], off offset:1024
	s_waitcnt lgkmcnt(0)
	v_mfma_f32_32x32x16_bf16 v[16:31], v[32:35], v[68:71], v[16:31]
	global_load_dwordx4 v[32:35], v[76:77], off offset:2048
	v_mfma_f32_32x32x16_bf16 v[0:15], v[36:39], v[68:71], v[0:15]
	ds_read_b128 v[68:71], v103 offset:4704
	global_load_dwordx4 v[36:39], v[78:79], off offset:2048
	s_waitcnt lgkmcnt(0)
	v_mfma_f32_32x32x16_bf16 v[16:31], v[40:43], v[68:71], v[16:31]
	global_load_dwordx4 v[40:43], v[76:77], off offset:3072
	v_mfma_f32_32x32x16_bf16 v[0:15], v[44:47], v[68:71], v[0:15]
	global_load_dwordx4 v[44:47], v[78:79], off offset:3072
	ds_write_b128 v88, v[64:67]
	v_add_co_u32_e32 v64, vcc, s16, v92
	global_load_dwordx4 v[66:69], v96, s[10:11] offset:2832
	global_load_dwordx4 v[70:73], v96, s[10:11] offset:2816
	v_addc_co_u32_e32 v65, vcc, 0, v93, vcc
	global_load_dwordx4 v[74:77], v[64:65], off offset:3840
	s_waitcnt lgkmcnt(0)
	s_barrier
	s_waitcnt vmcnt(0)
	v_lshlrev_b32_e32 v64, 16, v74
	v_and_b32_e32 v65, 0xffff0000, v74
	v_pk_add_f32 v[64:65], v[70:71], v[64:65]
	v_lshlrev_b32_e32 v70, 16, v75
	v_and_b32_e32 v71, 0xffff0000, v75
	v_pk_add_f32 v[70:71], v[72:73], v[70:71]
	v_cvt_pk_bf16_f32 v64, v64, v65
	v_cvt_pk_bf16_f32 v65, v70, v71
	v_lshlrev_b32_e32 v70, 16, v76
	v_and_b32_e32 v71, 0xffff0000, v76
	v_pk_add_f32 v[66:67], v[66:67], v[70:71]
	v_lshlrev_b32_e32 v70, 16, v77
	v_and_b32_e32 v71, 0xffff0000, v77
	v_pk_add_f32 v[68:69], v[68:69], v[70:71]
	v_cvt_pk_bf16_f32 v66, v66, v67
	v_cvt_pk_bf16_f32 v67, v68, v69
	ds_read_b128 v[74:77], v103
	ds_read_b128 v[68:71], v103 offset:32
	s_waitcnt lgkmcnt(1)
	v_mfma_f32_32x32x16_bf16 v[16:31], v[56:59], v[74:77], v[16:31]
	v_add_co_u32_e32 v72, vcc, s13, v90
	s_mov_b32 s13, 0x2c000
	s_nop 0
	v_addc_co_u32_e32 v73, vcc, 0, v91, vcc
	global_load_dwordx4 v[56:59], v[72:73], off
	v_mfma_f32_32x32x16_bf16 v[0:15], v[60:63], v[74:77], v[0:15]
	v_add_co_u32_e32 v74, vcc, s31, v90
	s_nop 1
	v_addc_co_u32_e32 v75, vcc, 0, v91, vcc
	global_load_dwordx4 v[60:63], v[74:75], off
	s_waitcnt lgkmcnt(0)
	v_mfma_f32_32x32x16_bf16 v[16:31], v[52:55], v[68:71], v[16:31]
	global_load_dwordx4 v[52:55], v[72:73], off offset:1024
	v_mfma_f32_32x32x16_bf16 v[0:15], v[48:51], v[68:71], v[0:15]
	ds_read_b128 v[68:71], v103 offset:64
	global_load_dwordx4 v[48:51], v[74:75], off offset:1024
	s_waitcnt lgkmcnt(0)
	v_mfma_f32_32x32x16_bf16 v[16:31], v[32:35], v[68:71], v[16:31]
	global_load_dwordx4 v[32:35], v[72:73], off offset:2048
	v_mfma_f32_32x32x16_bf16 v[0:15], v[36:39], v[68:71], v[0:15]
	ds_read_b128 v[68:71], v103 offset:96
	global_load_dwordx4 v[36:39], v[74:75], off offset:2048
	s_waitcnt lgkmcnt(0)
	v_mfma_f32_32x32x16_bf16 v[16:31], v[40:43], v[68:71], v[16:31]
	global_load_dwordx4 v[40:43], v[72:73], off offset:3072
	v_mfma_f32_32x32x16_bf16 v[0:15], v[44:47], v[68:71], v[0:15]
	global_load_dwordx4 v[44:47], v[74:75], off offset:3072
	ds_write_b128 v88, v[64:67] offset:4608
	v_add_co_u32_e32 v64, vcc, s17, v92
	s_nop 1
	v_addc_co_u32_e32 v65, vcc, 0, v93, vcc
	global_load_dwordx4 v[64:67], v[64:65], off offset:3072
	s_nop 0
	global_load_dwordx4 v[68:71], v96, s[10:11] offset:3088
	global_load_dwordx4 v[72:75], v96, s[10:11] offset:3072
	s_waitcnt lgkmcnt(0)
	s_barrier
	s_waitcnt vmcnt(2)
	v_lshlrev_b32_e32 v76, 16, v64
	v_and_b32_e32 v77, 0xffff0000, v64
	s_waitcnt vmcnt(0)
	v_pk_add_f32 v[72:73], v[72:73], v[76:77]
	v_add_co_u32_e32 v76, vcc, s18, v90
	v_cvt_pk_bf16_f32 v64, v72, v73
	v_lshlrev_b32_e32 v72, 16, v65
	v_and_b32_e32 v73, 0xffff0000, v65
	v_pk_add_f32 v[72:73], v[74:75], v[72:73]
	v_addc_co_u32_e32 v77, vcc, 0, v91, vcc
	v_cvt_pk_bf16_f32 v65, v72, v73
	v_lshlrev_b32_e32 v72, 16, v66
	v_and_b32_e32 v73, 0xffff0000, v66
	v_pk_add_f32 v[68:69], v[68:69], v[72:73]
	s_mov_b32 s18, 0x17000
	v_cvt_pk_bf16_f32 v66, v68, v69
	v_lshlrev_b32_e32 v68, 16, v67
	v_and_b32_e32 v69, 0xffff0000, v67
	v_pk_add_f32 v[68:69], v[70:71], v[68:69]
	s_nop 0
	v_cvt_pk_bf16_f32 v67, v68, v69
	ds_read_b128 v[72:75], v103 offset:4608
	ds_read_b128 v[68:71], v103 offset:4640
	s_waitcnt lgkmcnt(1)
	v_mfma_f32_32x32x16_bf16 v[0:15], v[60:63], v[72:75], v[0:15]
	v_mfma_f32_32x32x16_bf16 v[16:31], v[56:59], v[72:75], v[16:31]
	v_add_co_u32_e32 v72, vcc, s13, v90
	global_load_dwordx4 v[56:59], v[76:77], off
	s_nop 0
	v_addc_co_u32_e32 v73, vcc, 0, v91, vcc
	global_load_dwordx4 v[60:63], v[72:73], off
	s_mov_b32 s13, 0xd000
	s_waitcnt lgkmcnt(0)
	v_mfma_f32_32x32x16_bf16 v[0:15], v[48:51], v[68:71], v[0:15]
	global_load_dwordx4 v[48:51], v[72:73], off offset:1024
	v_mfma_f32_32x32x16_bf16 v[16:31], v[52:55], v[68:71], v[16:31]
	ds_read_b128 v[68:71], v103 offset:4672
	global_load_dwordx4 v[52:55], v[76:77], off offset:1024
	s_waitcnt lgkmcnt(0)
	v_mfma_f32_32x32x16_bf16 v[0:15], v[36:39], v[68:71], v[0:15]
	global_load_dwordx4 v[36:39], v[72:73], off offset:2048
	v_mfma_f32_32x32x16_bf16 v[16:31], v[32:35], v[68:71], v[16:31]
	ds_read_b128 v[68:71], v103 offset:4704
	global_load_dwordx4 v[32:35], v[76:77], off offset:2048
	s_waitcnt lgkmcnt(0)
	v_mfma_f32_32x32x16_bf16 v[0:15], v[44:47], v[68:71], v[0:15]
	global_load_dwordx4 v[44:47], v[72:73], off offset:3072
	v_add_co_u32_e32 v72, vcc, s18, v92
	s_nop 1
	v_addc_co_u32_e32 v73, vcc, 0, v93, vcc
	v_add_co_u32_e32 v80, vcc, s13, v90
	v_mfma_f32_32x32x16_bf16 v[16:31], v[40:43], v[68:71], v[16:31]
	global_load_dwordx4 v[40:43], v[76:77], off offset:3072
	ds_write_b128 v88, v[64:67]
	global_load_dwordx4 v[64:67], v96, s[10:11] offset:3344
	global_load_dwordx4 v[68:71], v96, s[10:11] offset:3328
	v_addc_co_u32_e32 v81, vcc, 0, v91, vcc
	global_load_dwordx4 v[72:75], v[72:73], off offset:2304
	s_waitcnt lgkmcnt(0)
	s_barrier
	v_add_co_u32_e32 v82, vcc, s34, v90
	s_mov_b32 s13, 0x2e000
	s_nop 0
	v_addc_co_u32_e32 v83, vcc, 0, v91, vcc
	s_waitcnt vmcnt(0)
	v_lshlrev_b32_e32 v76, 16, v72
	v_and_b32_e32 v77, 0xffff0000, v72
	v_lshlrev_b32_e32 v72, 16, v73
	v_and_b32_e32 v73, 0xffff0000, v73
	v_pk_add_f32 v[68:69], v[68:69], v[76:77]
	v_pk_add_f32 v[70:71], v[70:71], v[72:73]
	v_cvt_pk_bf16_f32 v68, v68, v69
	v_cvt_pk_bf16_f32 v69, v70, v71
	v_lshlrev_b32_e32 v70, 16, v74
	v_and_b32_e32 v71, 0xffff0000, v74
	v_pk_add_f32 v[64:65], v[64:65], v[70:71]
	s_nop 0
	v_cvt_pk_bf16_f32 v70, v64, v65
	v_lshlrev_b32_e32 v64, 16, v75
	v_and_b32_e32 v65, 0xffff0000, v75
	v_pk_add_f32 v[64:65], v[66:67], v[64:65]
	s_nop 0
	v_cvt_pk_bf16_f32 v71, v64, v65
	ds_read_b128 v[72:75], v103
	ds_read_b128 v[64:67], v103 offset:32
	s_waitcnt lgkmcnt(1)
	v_mfma_f32_32x32x16_bf16 v[16:31], v[56:59], v[72:75], v[16:31]
	global_load_dwordx4 v[56:59], v[80:81], off
	global_load_dwordx4 v[84:87], v[82:83], off
	global_load_dwordx4 v[76:79], v[82:83], off offset:1024
	v_mfma_f32_32x32x16_bf16 v[0:15], v[60:63], v[72:75], v[0:15]
	global_load_dwordx4 v[60:63], v[80:81], off offset:1024
	global_load_dwordx4 v[72:75], v[82:83], off offset:2048
	s_waitcnt lgkmcnt(0)
	v_mfma_f32_32x32x16_bf16 v[16:31], v[52:55], v[64:67], v[16:31]
	global_load_dwordx4 v[52:55], v[82:83], off offset:3072
	v_mfma_f32_32x32x16_bf16 v[0:15], v[48:51], v[64:67], v[0:15]
	ds_read_b128 v[48:51], v103 offset:64
	global_load_dwordx4 v[64:67], v[80:81], off offset:2048
	s_waitcnt lgkmcnt(0)
	v_mfma_f32_32x32x16_bf16 v[16:31], v[32:35], v[48:51], v[16:31]
	ds_read_b128 v[32:35], v103 offset:96
	v_mfma_f32_32x32x16_bf16 v[0:15], v[36:39], v[48:51], v[0:15]
	global_load_dwordx4 v[48:51], v[80:81], off offset:3072
	ds_write_b128 v88, v[68:71] offset:4608
	s_waitcnt lgkmcnt(1)
	v_mfma_f32_32x32x16_bf16 v[16:31], v[40:43], v[32:35], v[16:31]
	v_mfma_f32_32x32x16_bf16 v[0:15], v[44:47], v[32:35], v[0:15]
	v_add_co_u32_e32 v32, vcc, s24, v92
	s_nop 1
	v_addc_co_u32_e32 v33, vcc, 0, v93, vcc
	global_load_dwordx4 v[32:35], v[32:33], off offset:1536
	s_nop 0
	global_load_dwordx4 v[36:39], v96, s[10:11] offset:3600
	global_load_dwordx4 v[40:43], v96, s[10:11] offset:3584
	s_waitcnt lgkmcnt(0)
	s_barrier
	v_add_co_u32_e32 v98, vcc, s25, v90
	s_mov_b32 s25, 0x1d000
	s_nop 0
	v_addc_co_u32_e32 v99, vcc, 0, v91, vcc
	s_waitcnt vmcnt(2)
	v_lshlrev_b32_e32 v44, 16, v32
	v_and_b32_e32 v45, 0xffff0000, v32
	v_lshlrev_b32_e32 v32, 16, v33
	v_and_b32_e32 v33, 0xffff0000, v33
	s_waitcnt vmcnt(0)
	v_pk_add_f32 v[32:33], v[42:43], v[32:33]
	v_pk_add_f32 v[40:41], v[40:41], v[44:45]
	v_cvt_pk_bf16_f32 v81, v32, v33
	v_lshlrev_b32_e32 v32, 16, v34
	v_and_b32_e32 v33, 0xffff0000, v34
	v_pk_add_f32 v[32:33], v[36:37], v[32:33]
	v_cvt_pk_bf16_f32 v80, v40, v41
	v_cvt_pk_bf16_f32 v82, v32, v33
	v_lshlrev_b32_e32 v32, 16, v35
	v_and_b32_e32 v33, 0xffff0000, v35
	v_pk_add_f32 v[32:33], v[38:39], v[32:33]
	s_nop 0
	v_cvt_pk_bf16_f32 v83, v32, v33
	ds_read_b128 v[32:35], v103 offset:4608
	ds_read_b128 v[36:39], v103 offset:4640
	s_waitcnt lgkmcnt(1)
	v_mfma_f32_32x32x16_bf16 v[16:31], v[56:59], v[32:35], v[16:31]
	ds_read_b128 v[44:47], v103 offset:4672
	global_load_dwordx4 v[68:71], v[98:99], off
	global_load_dwordx4 v[40:43], v[98:99], off offset:2048
	v_mfma_f32_32x32x16_bf16 v[0:15], v[84:87], v[32:35], v[0:15]
	v_add_co_u32_e32 v84, vcc, s13, v90
	s_mov_b32 s13, 0x1b000
	s_nop 0
	v_addc_co_u32_e32 v85, vcc, 0, v91, vcc
	global_load_dwordx4 v[56:59], v[84:85], off
	global_load_dwordx4 v[32:35], v[98:99], off offset:1024
	s_waitcnt lgkmcnt(1)
	v_mfma_f32_32x32x16_bf16 v[16:31], v[60:63], v[36:39], v[16:31]
	ds_read_b128 v[60:63], v103 offset:4704
	v_mfma_f32_32x32x16_bf16 v[0:15], v[76:79], v[36:39], v[0:15]
	global_load_dwordx4 v[36:39], v[84:85], off offset:1024
	s_waitcnt lgkmcnt(1)
	v_mfma_f32_32x32x16_bf16 v[16:31], v[64:67], v[44:47], v[16:31]
	v_mfma_f32_32x32x16_bf16 v[0:15], v[72:75], v[44:47], v[0:15]
	global_load_dwordx4 v[44:47], v[84:85], off offset:2048
	s_waitcnt lgkmcnt(0)
	v_mfma_f32_32x32x16_bf16 v[16:31], v[48:51], v[60:63], v[16:31]
	global_load_dwordx4 v[48:51], v[98:99], off offset:3072
	v_mfma_f32_32x32x16_bf16 v[0:15], v[52:55], v[60:63], v[0:15]
	v_add_co_u32_e32 v60, vcc, s13, v92
	global_load_dwordx4 v[52:55], v[84:85], off offset:3072
	ds_write_b128 v88, v[80:83]
	v_addc_co_u32_e32 v61, vcc, 0, v93, vcc
	global_load_dwordx4 v[62:65], v96, s[10:11] offset:3856
	global_load_dwordx4 v[72:75], v96, s[10:11] offset:3840
	global_load_dwordx4 v[76:79], v[60:61], off offset:768
	s_waitcnt lgkmcnt(0)
	s_barrier
	s_mov_b32 s10, 0xf000
	s_waitcnt vmcnt(0)
	v_lshlrev_b32_e32 v60, 16, v76
	v_and_b32_e32 v61, 0xffff0000, v76
	v_lshlrev_b32_e32 v66, 16, v77
	v_and_b32_e32 v67, 0xffff0000, v77
	v_pk_add_f32 v[60:61], v[72:73], v[60:61]
	v_pk_add_f32 v[66:67], v[74:75], v[66:67]
	v_cvt_pk_bf16_f32 v60, v60, v61
	v_cvt_pk_bf16_f32 v61, v66, v67
	v_lshlrev_b32_e32 v66, 16, v78
	v_and_b32_e32 v67, 0xffff0000, v78
	v_pk_add_f32 v[62:63], v[62:63], v[66:67]
	v_lshlrev_b32_e32 v66, 16, v79
	v_and_b32_e32 v67, 0xffff0000, v79
	v_pk_add_f32 v[64:65], v[64:65], v[66:67]
	v_cvt_pk_bf16_f32 v62, v62, v63
	v_cvt_pk_bf16_f32 v63, v64, v65
	ds_read_b128 v[72:75], v103
	ds_read_b128 v[64:67], v103 offset:32
	s_waitcnt lgkmcnt(1)
	v_mfma_f32_32x32x16_bf16 v[16:31], v[68:71], v[72:75], v[16:31]
	v_add_co_u32_e32 v76, vcc, s10, v90
	s_mov_b64 s[10:11], 0x1000
	s_nop 0
	v_addc_co_u32_e32 v77, vcc, 0, v91, vcc
	global_load_dwordx4 v[68:71], v[76:77], off
	v_mfma_f32_32x32x16_bf16 v[0:15], v[56:59], v[72:75], v[0:15]
	v_add_co_u32_e32 v72, vcc, s35, v90
	s_nop 1
	v_addc_co_u32_e32 v73, vcc, 0, v91, vcc
	global_load_dwordx4 v[56:59], v[72:73], off
	s_waitcnt lgkmcnt(0)
	v_mfma_f32_32x32x16_bf16 v[16:31], v[32:35], v[64:67], v[16:31]
	global_load_dwordx4 v[32:35], v[76:77], off offset:1024
	v_mfma_f32_32x32x16_bf16 v[0:15], v[36:39], v[64:67], v[0:15]
	ds_read_b128 v[64:67], v103 offset:64
	global_load_dwordx4 v[36:39], v[72:73], off offset:1024
	s_waitcnt lgkmcnt(0)
	v_mfma_f32_32x32x16_bf16 v[16:31], v[40:43], v[64:67], v[16:31]
	global_load_dwordx4 v[40:43], v[76:77], off offset:2048
	v_mfma_f32_32x32x16_bf16 v[0:15], v[44:47], v[64:67], v[0:15]
	ds_read_b128 v[64:67], v103 offset:96
	global_load_dwordx4 v[44:47], v[72:73], off offset:2048
	s_waitcnt lgkmcnt(0)
	v_mfma_f32_32x32x16_bf16 v[16:31], v[48:51], v[64:67], v[16:31]
	global_load_dwordx4 v[48:51], v[76:77], off offset:3072
	v_mfma_f32_32x32x16_bf16 v[0:15], v[52:55], v[64:67], v[0:15]
	global_load_dwordx4 v[52:55], v[72:73], off offset:3072
	ds_write_b128 v88, v[60:63] offset:4608
	v_add_co_u32_e32 v60, vcc, s25, v92
	v_lshl_add_u64 v[72:73], v[94:95], 0, s[10:11]
	s_nop 0
	v_addc_co_u32_e32 v61, vcc, 0, v93, vcc
	global_load_dwordx4 v[60:63], v[60:61], off
	v_add_co_u32_e32 v96, vcc, s14, v94
	s_mov_b32 s14, 0x1e000
	s_nop 0
	v_addc_co_u32_e32 v97, vcc, 0, v95, vcc
	global_load_dwordx4 v[64:67], v[96:97], off
	s_nop 0
	global_load_dwordx4 v[72:75], v[72:73], off offset:16
	s_waitcnt lgkmcnt(0)
	s_barrier
	s_mov_b64 s[10:11], 0x1100
	s_waitcnt vmcnt(2)
	v_lshlrev_b32_e32 v76, 16, v60
	v_and_b32_e32 v77, 0xffff0000, v60
	s_waitcnt vmcnt(1)
	v_pk_add_f32 v[64:65], v[64:65], v[76:77]
	s_nop 0
	v_cvt_pk_bf16_f32 v60, v64, v65
	v_lshlrev_b32_e32 v64, 16, v61
	v_and_b32_e32 v65, 0xffff0000, v61
	v_pk_add_f32 v[64:65], v[66:67], v[64:65]
	s_nop 0
	v_cvt_pk_bf16_f32 v61, v64, v65
	v_lshlrev_b32_e32 v64, 16, v62
	v_and_b32_e32 v65, 0xffff0000, v62
	s_waitcnt vmcnt(0)
	v_pk_add_f32 v[64:65], v[72:73], v[64:65]
	v_add_co_u32_e32 v72, vcc, s19, v90
	v_cvt_pk_bf16_f32 v62, v64, v65
	v_lshlrev_b32_e32 v64, 16, v63
	v_and_b32_e32 v65, 0xffff0000, v63
	v_pk_add_f32 v[64:65], v[74:75], v[64:65]
	v_addc_co_u32_e32 v73, vcc, 0, v91, vcc
	v_cvt_pk_bf16_f32 v63, v64, v65
	ds_read_b128 v[74:77], v103 offset:4608
	ds_read_b128 v[64:67], v103 offset:4640
	s_waitcnt lgkmcnt(1)
	v_mfma_f32_32x32x16_bf16 v[16:31], v[68:71], v[74:77], v[16:31]
	global_load_dwordx4 v[68:71], v[72:73], off
	v_mfma_f32_32x32x16_bf16 v[0:15], v[56:59], v[74:77], v[0:15]
	v_add_co_u32_e32 v74, vcc, s23, v90
	s_nop 1
	v_addc_co_u32_e32 v75, vcc, 0, v91, vcc
	global_load_dwordx4 v[56:59], v[74:75], off
	s_waitcnt lgkmcnt(0)
	v_mfma_f32_32x32x16_bf16 v[16:31], v[32:35], v[64:67], v[16:31]
	global_load_dwordx4 v[32:35], v[72:73], off offset:1024
	v_mfma_f32_32x32x16_bf16 v[0:15], v[36:39], v[64:67], v[0:15]
	ds_read_b128 v[64:67], v103 offset:4672
	global_load_dwordx4 v[36:39], v[74:75], off offset:1024
	s_waitcnt lgkmcnt(0)
	v_mfma_f32_32x32x16_bf16 v[16:31], v[40:43], v[64:67], v[16:31]
	global_load_dwordx4 v[40:43], v[72:73], off offset:2048
	v_mfma_f32_32x32x16_bf16 v[0:15], v[44:47], v[64:67], v[0:15]
	ds_read_b128 v[64:67], v103 offset:4704
	global_load_dwordx4 v[44:47], v[74:75], off offset:2048
	s_waitcnt lgkmcnt(0)
	v_mfma_f32_32x32x16_bf16 v[16:31], v[48:51], v[64:67], v[16:31]
	global_load_dwordx4 v[48:51], v[72:73], off offset:3072
	v_add_co_u32_e32 v72, vcc, s14, v92
	s_nop 1
	v_addc_co_u32_e32 v73, vcc, 0, v93, vcc
	v_mfma_f32_32x32x16_bf16 v[0:15], v[52:55], v[64:67], v[0:15]
	global_load_dwordx4 v[52:55], v[74:75], off offset:3072
	ds_write_b128 v88, v[60:63]
	v_lshl_add_u64 v[64:65], v[94:95], 0, s[10:11]
	global_load_dwordx4 v[60:63], v[96:97], off offset:256
	s_nop 0
	global_load_dwordx4 v[64:67], v[64:65], off offset:16
	s_mov_b32 s10, 0x11000
	global_load_dwordx4 v[72:75], v[72:73], off offset:3328
	s_waitcnt lgkmcnt(0)
	s_barrier
	v_add_co_u32_e32 v80, vcc, s10, v90
	s_mov_b32 s10, 0x31000
	s_nop 0
	v_addc_co_u32_e32 v81, vcc, 0, v91, vcc
	s_waitcnt vmcnt(0)
	v_lshlrev_b32_e32 v76, 16, v72
	v_and_b32_e32 v77, 0xffff0000, v72
	v_lshlrev_b32_e32 v72, 16, v73
	v_and_b32_e32 v73, 0xffff0000, v73
	v_pk_add_f32 v[60:61], v[60:61], v[76:77]
	v_pk_add_f32 v[62:63], v[62:63], v[72:73]
	v_cvt_pk_bf16_f32 v60, v60, v61
	v_cvt_pk_bf16_f32 v61, v62, v63
	v_lshlrev_b32_e32 v62, 16, v74
	v_and_b32_e32 v63, 0xffff0000, v74
	v_pk_add_f32 v[62:63], v[64:65], v[62:63]
	v_lshlrev_b32_e32 v64, 16, v75
	v_and_b32_e32 v65, 0xffff0000, v75
	v_pk_add_f32 v[64:65], v[66:67], v[64:65]
	v_cvt_pk_bf16_f32 v62, v62, v63
	v_cvt_pk_bf16_f32 v63, v64, v65
	ds_read_b128 v[72:75], v103
	ds_read_b128 v[64:67], v103 offset:32
	s_waitcnt lgkmcnt(1)
	v_mfma_f32_32x32x16_bf16 v[16:31], v[68:71], v[72:75], v[16:31]
	global_load_dwordx4 v[76:79], v[80:81], off
	v_mfma_f32_32x32x16_bf16 v[0:15], v[56:59], v[72:75], v[0:15]
	ds_read_b128 v[56:59], v103 offset:64
	v_add_co_u32_e32 v72, vcc, s10, v90
	s_mov_b64 s[10:11], 0x1200
	s_nop 0
	v_addc_co_u32_e32 v73, vcc, 0, v91, vcc
	global_load_dwordx4 v[68:71], v[72:73], off
	s_waitcnt lgkmcnt(1)
	v_mfma_f32_32x32x16_bf16 v[16:31], v[32:35], v[64:67], v[16:31]
	global_load_dwordx4 v[32:35], v[80:81], off offset:1024
	v_mfma_f32_32x32x16_bf16 v[0:15], v[36:39], v[64:67], v[0:15]
	global_load_dwordx4 v[36:39], v[72:73], off offset:1024
	v_lshl_add_u64 v[64:65], v[94:95], 0, s[10:11]
	s_mov_b64 s[10:11], 0x1300
	s_waitcnt lgkmcnt(0)
	v_mfma_f32_32x32x16_bf16 v[16:31], v[40:43], v[56:59], v[16:31]
	global_load_dwordx4 v[40:43], v[80:81], off offset:2048
	v_mfma_f32_32x32x16_bf16 v[0:15], v[44:47], v[56:59], v[0:15]
	ds_read_b128 v[56:59], v103 offset:96
	global_load_dwordx4 v[44:47], v[72:73], off offset:2048
	s_waitcnt lgkmcnt(0)
	v_mfma_f32_32x32x16_bf16 v[16:31], v[48:51], v[56:59], v[16:31]
	global_load_dwordx4 v[48:51], v[80:81], off offset:3072
	v_mfma_f32_32x32x16_bf16 v[0:15], v[52:55], v[56:59], v[0:15]
	v_add_co_u32_e32 v56, vcc, s22, v92
	global_load_dwordx4 v[52:55], v[72:73], off offset:3072
	ds_write_b128 v88, v[60:63] offset:4608
	v_addc_co_u32_e32 v57, vcc, 0, v93, vcc
	global_load_dwordx4 v[56:59], v[56:57], off offset:2560
	s_nop 0
	global_load_dwordx4 v[60:63], v[96:97], off offset:512
	global_load_dwordx4 v[72:75], v[64:65], off offset:16
	s_waitcnt lgkmcnt(0)
	s_barrier
	s_waitcnt vmcnt(2)
	v_lshlrev_b32_e32 v64, 16, v56
	v_and_b32_e32 v65, 0xffff0000, v56
	v_lshlrev_b32_e32 v56, 16, v57
	v_and_b32_e32 v57, 0xffff0000, v57
	s_waitcnt vmcnt(1)
	v_pk_add_f32 v[56:57], v[62:63], v[56:57]
	v_pk_add_f32 v[60:61], v[60:61], v[64:65]
	v_cvt_pk_bf16_f32 v65, v56, v57
	v_lshlrev_b32_e32 v56, 16, v58
	v_and_b32_e32 v57, 0xffff0000, v58
	s_waitcnt vmcnt(0)
	v_pk_add_f32 v[56:57], v[72:73], v[56:57]
	v_cvt_pk_bf16_f32 v64, v60, v61
	v_cvt_pk_bf16_f32 v66, v56, v57
	v_lshlrev_b32_e32 v56, 16, v59
	v_and_b32_e32 v57, 0xffff0000, v59
	v_pk_add_f32 v[56:57], v[74:75], v[56:57]
	ds_read_b128 v[60:63], v103 offset:4608
	ds_read_b128 v[72:75], v103 offset:4640
	s_waitcnt lgkmcnt(1)
	v_mfma_f32_32x32x16_bf16 v[16:31], v[76:79], v[60:63], v[16:31]
	v_add_co_u32_e32 v76, vcc, s15, v90
	s_mov_b32 s15, 0x32000
	s_nop 0
	v_addc_co_u32_e32 v77, vcc, 0, v91, vcc
	v_add_co_u32_e32 v78, vcc, s15, v90
	v_mfma_f32_32x32x16_bf16 v[0:15], v[68:71], v[60:63], v[0:15]
	ds_read_b128 v[68:71], v103 offset:4672
	v_addc_co_u32_e32 v79, vcc, 0, v91, vcc
	v_cvt_pk_bf16_f32 v67, v56, v57
	global_load_dwordx4 v[56:59], v[76:77], off
	global_load_dwordx4 v[60:63], v[78:79], off
	s_waitcnt lgkmcnt(1)
	v_mfma_f32_32x32x16_bf16 v[16:31], v[32:35], v[72:75], v[16:31]
	global_load_dwordx4 v[32:35], v[76:77], off offset:1024
	v_mfma_f32_32x32x16_bf16 v[0:15], v[36:39], v[72:75], v[0:15]
	v_add_co_u32_e32 v72, vcc, s26, v92
	global_load_dwordx4 v[36:39], v[78:79], off offset:1024
	s_nop 0
	v_addc_co_u32_e32 v73, vcc, 0, v93, vcc
	v_add_co_u32_e32 v84, vcc, s16, v90
	s_waitcnt lgkmcnt(0)
	v_mfma_f32_32x32x16_bf16 v[16:31], v[40:43], v[68:71], v[16:31]
	global_load_dwordx4 v[40:43], v[76:77], off offset:2048
	v_addc_co_u32_e32 v85, vcc, 0, v91, vcc
	s_mov_b32 s16, 0x34000
	v_mfma_f32_32x32x16_bf16 v[0:15], v[44:47], v[68:71], v[0:15]
	ds_read_b128 v[68:71], v103 offset:4704
	global_load_dwordx4 v[44:47], v[78:79], off offset:2048
	s_waitcnt lgkmcnt(0)
	v_mfma_f32_32x32x16_bf16 v[16:31], v[48:51], v[68:71], v[16:31]
	global_load_dwordx4 v[48:51], v[76:77], off offset:3072
	v_mfma_f32_32x32x16_bf16 v[0:15], v[52:55], v[68:71], v[0:15]
	global_load_dwordx4 v[52:55], v[78:79], off offset:3072
	ds_write_b128 v88, v[64:67]
	v_lshl_add_u64 v[68:69], v[94:95], 0, s[10:11]
	global_load_dwordx4 v[64:67], v[96:97], off offset:768
	s_nop 0
	global_load_dwordx4 v[68:71], v[68:69], off offset:16
	s_mov_b32 s10, 0x33000
	global_load_dwordx4 v[72:75], v[72:73], off offset:1792
	s_waitcnt lgkmcnt(0)
	s_barrier
	s_waitcnt vmcnt(0)
	v_lshlrev_b32_e32 v76, 16, v72
	v_and_b32_e32 v77, 0xffff0000, v72
	v_lshlrev_b32_e32 v72, 16, v73
	v_and_b32_e32 v73, 0xffff0000, v73
	v_pk_add_f32 v[64:65], v[64:65], v[76:77]
	v_pk_add_f32 v[66:67], v[66:67], v[72:73]
	v_cvt_pk_bf16_f32 v64, v64, v65
	v_cvt_pk_bf16_f32 v65, v66, v67
	v_lshlrev_b32_e32 v66, 16, v74
	v_and_b32_e32 v67, 0xffff0000, v74
	v_pk_add_f32 v[66:67], v[68:69], v[66:67]
	v_lshlrev_b32_e32 v68, 16, v75
	v_and_b32_e32 v69, 0xffff0000, v75
	v_pk_add_f32 v[68:69], v[70:71], v[68:69]
	v_cvt_pk_bf16_f32 v66, v66, v67
	v_cvt_pk_bf16_f32 v67, v68, v69
	ds_read_b128 v[72:75], v103
	ds_read_b128 v[68:71], v103 offset:32
	s_waitcnt lgkmcnt(1)
	v_mfma_f32_32x32x16_bf16 v[16:31], v[56:59], v[72:75], v[16:31]
	global_load_dwordx4 v[80:83], v[84:85], off
	v_mfma_f32_32x32x16_bf16 v[0:15], v[60:63], v[72:75], v[0:15]
	v_add_co_u32_e32 v72, vcc, s10, v90
	global_load_dwordx4 v[60:63], v[84:85], off offset:1024
	s_nop 0
	v_addc_co_u32_e32 v73, vcc, 0, v91, vcc
	global_load_dwordx4 v[76:79], v[72:73], off
	global_load_dwordx4 v[56:59], v[72:73], off offset:1024
	s_waitcnt lgkmcnt(0)
	v_mfma_f32_32x32x16_bf16 v[16:31], v[32:35], v[68:71], v[16:31]
	ds_read_b128 v[32:35], v103 offset:64
	s_mov_b64 s[10:11], 0x1400
	v_mfma_f32_32x32x16_bf16 v[0:15], v[36:39], v[68:71], v[0:15]
	s_waitcnt lgkmcnt(0)
	v_mfma_f32_32x32x16_bf16 v[16:31], v[40:43], v[32:35], v[16:31]
	global_load_dwordx4 v[40:43], v[84:85], off offset:2048
	v_mfma_f32_32x32x16_bf16 v[0:15], v[44:47], v[32:35], v[0:15]
	ds_read_b128 v[32:35], v103 offset:96
	global_load_dwordx4 v[44:47], v[72:73], off offset:2048
	s_waitcnt lgkmcnt(0)
	v_mfma_f32_32x32x16_bf16 v[16:31], v[48:51], v[32:35], v[16:31]
	global_load_dwordx4 v[48:51], v[84:85], off offset:3072
	v_mfma_f32_32x32x16_bf16 v[0:15], v[52:55], v[32:35], v[0:15]
	v_add_co_u32_e32 v32, vcc, s27, v92
	global_load_dwordx4 v[52:55], v[72:73], off offset:3072
	ds_write_b128 v88, v[64:67] offset:4608
	v_addc_co_u32_e32 v33, vcc, 0, v93, vcc
	global_load_dwordx4 v[32:35], v[32:33], off offset:1024
	v_lshl_add_u64 v[64:65], v[94:95], 0, s[10:11]
	global_load_dwordx4 v[36:39], v[96:97], off offset:1024
	global_load_dwordx4 v[66:69], v[64:65], off offset:16
	s_waitcnt lgkmcnt(0)
	s_barrier
	s_mov_b32 s10, 0x14000
	s_waitcnt vmcnt(2)
	v_lshlrev_b32_e32 v64, 16, v32
	v_and_b32_e32 v65, 0xffff0000, v32
	v_lshlrev_b32_e32 v32, 16, v33
	v_and_b32_e32 v33, 0xffff0000, v33
	s_waitcnt vmcnt(1)
	v_pk_add_f32 v[32:33], v[38:39], v[32:33]
	v_pk_add_f32 v[36:37], v[36:37], v[64:65]
	v_cvt_pk_bf16_f32 v65, v32, v33
	v_lshlrev_b32_e32 v32, 16, v34
	v_and_b32_e32 v33, 0xffff0000, v34
	s_waitcnt vmcnt(0)
	v_pk_add_f32 v[32:33], v[66:67], v[32:33]
	v_cvt_pk_bf16_f32 v64, v36, v37
	v_cvt_pk_bf16_f32 v66, v32, v33
	v_lshlrev_b32_e32 v32, 16, v35
	v_and_b32_e32 v33, 0xffff0000, v35
	v_pk_add_f32 v[32:33], v[68:69], v[32:33]
	s_nop 0
	v_cvt_pk_bf16_f32 v67, v32, v33
	ds_read_b128 v[32:35], v103 offset:4608
	ds_read_b128 v[72:75], v103 offset:4640
	s_waitcnt lgkmcnt(1)
	v_mfma_f32_32x32x16_bf16 v[16:31], v[80:83], v[32:35], v[16:31]
	v_add_co_u32_e32 v80, vcc, s10, v90
	s_mov_b64 s[10:11], 0x1500
	s_nop 0
	v_addc_co_u32_e32 v81, vcc, 0, v91, vcc
	global_load_dwordx4 v[36:39], v[80:81], off
	global_load_dwordx4 v[68:71], v[80:81], off offset:1024
	v_mfma_f32_32x32x16_bf16 v[0:15], v[76:79], v[32:35], v[0:15]
	v_add_co_u32_e32 v76, vcc, s16, v90
	s_nop 1
	v_addc_co_u32_e32 v77, vcc, 0, v91, vcc
	global_load_dwordx4 v[32:35], v[76:77], off
	s_waitcnt lgkmcnt(0)
	v_mfma_f32_32x32x16_bf16 v[16:31], v[60:63], v[72:75], v[16:31]
	v_add_co_u32_e32 v60, vcc, s28, v92
	s_nop 1
	v_addc_co_u32_e32 v61, vcc, 0, v93, vcc
	v_add_co_u32_e32 v84, vcc, s17, v90
	v_mfma_f32_32x32x16_bf16 v[0:15], v[56:59], v[72:75], v[0:15]
	ds_read_b128 v[56:59], v103 offset:4672
	global_load_dwordx4 v[72:75], v[76:77], off offset:1024
	v_addc_co_u32_e32 v85, vcc, 0, v91, vcc
	s_mov_b32 s17, 0x36000
	s_waitcnt lgkmcnt(0)
	v_mfma_f32_32x32x16_bf16 v[16:31], v[40:43], v[56:59], v[16:31]
	global_load_dwordx4 v[40:43], v[80:81], off offset:2048
	v_mfma_f32_32x32x16_bf16 v[0:15], v[44:47], v[56:59], v[0:15]
	ds_read_b128 v[56:59], v103 offset:4704
	global_load_dwordx4 v[44:47], v[76:77], off offset:2048
	s_nop 0
	global_load_dwordx4 v[76:79], v[76:77], off offset:3072
	s_waitcnt lgkmcnt(0)
	v_mfma_f32_32x32x16_bf16 v[16:31], v[48:51], v[56:59], v[16:31]
	global_load_dwordx4 v[48:51], v[80:81], off offset:3072
	ds_write_b128 v88, v[64:67]
	v_mfma_f32_32x32x16_bf16 v[0:15], v[52:55], v[56:59], v[0:15]
	v_lshl_add_u64 v[56:57], v[94:95], 0, s[10:11]
	global_load_dwordx4 v[52:55], v[96:97], off offset:1280
	s_nop 0
	global_load_dwordx4 v[56:59], v[56:57], off offset:16
	s_mov_b32 s10, 0x35000
	global_load_dwordx4 v[60:63], v[60:61], off offset:256
	s_waitcnt lgkmcnt(0)
	s_barrier
	v_add_co_u32_e32 v86, vcc, s10, v90
	s_mov_b64 s[10:11], 0x1600
	s_nop 0
	v_addc_co_u32_e32 v87, vcc, 0, v91, vcc
	s_waitcnt vmcnt(0)
	v_lshlrev_b32_e32 v64, 16, v60
	v_and_b32_e32 v65, 0xffff0000, v60
	v_pk_add_f32 v[52:53], v[52:53], v[64:65]
	s_nop 0
	v_cvt_pk_bf16_f32 v64, v52, v53
	v_lshlrev_b32_e32 v52, 16, v61
	v_and_b32_e32 v53, 0xffff0000, v61
	v_pk_add_f32 v[52:53], v[54:55], v[52:53]
	s_nop 0
	v_cvt_pk_bf16_f32 v65, v52, v53
	v_lshlrev_b32_e32 v52, 16, v62
	v_and_b32_e32 v53, 0xffff0000, v62
	v_pk_add_f32 v[52:53], v[56:57], v[52:53]
	s_nop 0
	v_cvt_pk_bf16_f32 v66, v52, v53
	v_lshlrev_b32_e32 v52, 16, v63
	v_and_b32_e32 v53, 0xffff0000, v63
	v_pk_add_f32 v[52:53], v[58:59], v[52:53]
	s_nop 0
	v_cvt_pk_bf16_f32 v67, v52, v53
	ds_read_b128 v[56:59], v103
	ds_read_b128 v[52:55], v103 offset:32
	s_waitcnt lgkmcnt(1)
	v_mfma_f32_32x32x16_bf16 v[16:31], v[36:39], v[56:59], v[16:31]
	global_load_dwordx4 v[80:83], v[84:85], off
	global_load_dwordx4 v[60:63], v[86:87], off
	global_load_dwordx4 v[36:39], v[84:85], off offset:2048
	v_mfma_f32_32x32x16_bf16 v[0:15], v[32:35], v[56:59], v[0:15]
	ds_read_b128 v[32:35], v103 offset:64
	global_load_dwordx4 v[56:59], v[84:85], off offset:1024
	s_waitcnt lgkmcnt(1)
	v_mfma_f32_32x32x16_bf16 v[16:31], v[68:71], v[52:55], v[16:31]
	v_lshl_add_u64 v[68:69], v[94:95], 0, s[10:11]
	s_mov_b32 s10, 0x16000
	v_mfma_f32_32x32x16_bf16 v[0:15], v[72:75], v[52:55], v[0:15]
	global_load_dwordx4 v[52:55], v[86:87], off offset:1024
	s_waitcnt lgkmcnt(0)
	v_mfma_f32_32x32x16_bf16 v[16:31], v[40:43], v[32:35], v[16:31]
	global_load_dwordx4 v[40:43], v[86:87], off offset:2048
	v_mfma_f32_32x32x16_bf16 v[0:15], v[44:47], v[32:35], v[0:15]
	ds_read_b128 v[32:35], v103 offset:96
	global_load_dwordx4 v[44:47], v[84:85], off offset:3072
	s_waitcnt lgkmcnt(0)
	v_mfma_f32_32x32x16_bf16 v[16:31], v[48:51], v[32:35], v[16:31]
	global_load_dwordx4 v[48:51], v[86:87], off offset:3072
	ds_write_b128 v88, v[64:67] offset:4608
	v_mfma_f32_32x32x16_bf16 v[0:15], v[76:79], v[32:35], v[0:15]
	v_add_co_u32_e32 v32, vcc, s29, v92
	s_nop 1
	v_addc_co_u32_e32 v33, vcc, 0, v93, vcc
	global_load_dwordx4 v[32:35], v[32:33], off offset:3584
	s_nop 0
	global_load_dwordx4 v[64:67], v[96:97], off offset:1536
	s_nop 0
	global_load_dwordx4 v[68:71], v[68:69], off offset:16
	s_waitcnt lgkmcnt(0)
	s_barrier
	v_add_co_u32_e32 v76, vcc, s10, v90
	s_mov_b64 s[10:11], 0x1700
	s_nop 0
	v_addc_co_u32_e32 v77, vcc, 0, v91, vcc
	v_add_co_u32_e32 v78, vcc, s17, v90
	s_waitcnt vmcnt(2)
	v_lshlrev_b32_e32 v72, 16, v32
	v_and_b32_e32 v73, 0xffff0000, v32
	v_lshlrev_b32_e32 v32, 16, v33
	v_and_b32_e32 v33, 0xffff0000, v33
	s_waitcnt vmcnt(1)
	v_pk_add_f32 v[64:65], v[64:65], v[72:73]
	v_pk_add_f32 v[32:33], v[66:67], v[32:33]
	v_cvt_pk_bf16_f32 v64, v64, v65
	v_cvt_pk_bf16_f32 v65, v32, v33
	v_lshlrev_b32_e32 v32, 16, v34
	v_and_b32_e32 v33, 0xffff0000, v34
	s_waitcnt vmcnt(0)
	v_pk_add_f32 v[32:33], v[68:69], v[32:33]
	v_addc_co_u32_e32 v79, vcc, 0, v91, vcc
	v_cvt_pk_bf16_f32 v66, v32, v33
	v_lshlrev_b32_e32 v32, 16, v35
	v_and_b32_e32 v33, 0xffff0000, v35
	v_pk_add_f32 v[32:33], v[70:71], v[32:33]
	ds_read_b128 v[72:75], v103 offset:4608
	ds_read_b128 v[68:71], v103 offset:4640
	s_waitcnt lgkmcnt(1)
	v_mfma_f32_32x32x16_bf16 v[16:31], v[80:83], v[72:75], v[16:31]
	v_cvt_pk_bf16_f32 v67, v32, v33
	global_load_dwordx4 v[32:35], v[76:77], off
	v_mfma_f32_32x32x16_bf16 v[0:15], v[60:63], v[72:75], v[0:15]
	ds_read_b128 v[60:63], v103 offset:4672
	global_load_dwordx4 v[72:75], v[78:79], off
	s_waitcnt lgkmcnt(1)
	v_mfma_f32_32x32x16_bf16 v[16:31], v[56:59], v[68:71], v[16:31]
	global_load_dwordx4 v[56:59], v[76:77], off offset:1024
	v_mfma_f32_32x32x16_bf16 v[0:15], v[52:55], v[68:71], v[0:15]
	v_add_co_u32_e32 v68, vcc, s30, v92
	global_load_dwordx4 v[52:55], v[78:79], off offset:1024
	s_nop 0
	v_addc_co_u32_e32 v69, vcc, 0, v93, vcc
	s_waitcnt lgkmcnt(0)
	v_mfma_f32_32x32x16_bf16 v[16:31], v[36:39], v[60:63], v[16:31]
	global_load_dwordx4 v[36:39], v[76:77], off offset:2048
	v_mfma_f32_32x32x16_bf16 v[0:15], v[40:43], v[60:63], v[0:15]
	ds_read_b128 v[60:63], v103 offset:4704
	global_load_dwordx4 v[40:43], v[78:79], off offset:2048
	s_waitcnt lgkmcnt(0)
	v_mfma_f32_32x32x16_bf16 v[16:31], v[44:47], v[60:63], v[16:31]
	global_load_dwordx4 v[44:47], v[76:77], off offset:3072
	v_mfma_f32_32x32x16_bf16 v[0:15], v[48:51], v[60:63], v[0:15]
	global_load_dwordx4 v[48:51], v[78:79], off offset:3072
	ds_write_b128 v88, v[64:67]
	v_lshl_add_u64 v[64:65], v[94:95], 0, s[10:11]
	global_load_dwordx4 v[60:63], v[96:97], off offset:1792
	s_nop 0
	global_load_dwordx4 v[64:67], v[64:65], off offset:16
	s_mov_b32 s10, 0x37000
	global_load_dwordx4 v[68:71], v[68:69], off offset:2816
	s_waitcnt lgkmcnt(0)
	s_barrier
	s_waitcnt vmcnt(0)
	v_lshlrev_b32_e32 v76, 16, v68
	v_and_b32_e32 v77, 0xffff0000, v68
	v_lshlrev_b32_e32 v68, 16, v69
	v_and_b32_e32 v69, 0xffff0000, v69
	v_pk_add_f32 v[60:61], v[60:61], v[76:77]
	v_pk_add_f32 v[62:63], v[62:63], v[68:69]
	v_cvt_pk_bf16_f32 v60, v60, v61
	v_cvt_pk_bf16_f32 v61, v62, v63
	v_lshlrev_b32_e32 v62, 16, v70
	v_and_b32_e32 v63, 0xffff0000, v70
	v_pk_add_f32 v[62:63], v[64:65], v[62:63]
	v_lshlrev_b32_e32 v64, 16, v71
	v_and_b32_e32 v65, 0xffff0000, v71
	v_pk_add_f32 v[64:65], v[66:67], v[64:65]
	v_cvt_pk_bf16_f32 v62, v62, v63
	v_cvt_pk_bf16_f32 v63, v64, v65
	ds_read_b128 v[64:67], v103
	ds_read_b128 v[68:71], v103 offset:32
	s_waitcnt lgkmcnt(1)
	v_mfma_f32_32x32x16_bf16 v[16:31], v[32:35], v[64:67], v[16:31]
	v_add_co_u32_e32 v76, vcc, s18, v90
	s_mov_b32 s18, 0x38000
	s_nop 0
	v_addc_co_u32_e32 v77, vcc, 0, v91, vcc
	global_load_dwordx4 v[32:35], v[76:77], off
	v_mfma_f32_32x32x16_bf16 v[0:15], v[72:75], v[64:67], v[0:15]
	v_add_co_u32_e32 v72, vcc, s10, v90
	s_mov_b64 s[10:11], 0x1800
	s_nop 0
	v_addc_co_u32_e32 v73, vcc, 0, v91, vcc
	global_load_dwordx4 v[64:67], v[72:73], off
	s_waitcnt lgkmcnt(0)
	v_mfma_f32_32x32x16_bf16 v[16:31], v[56:59], v[68:71], v[16:31]
	global_load_dwordx4 v[56:59], v[76:77], off offset:1024
	v_mfma_f32_32x32x16_bf16 v[0:15], v[52:55], v[68:71], v[0:15]
	ds_read_b128 v[68:71], v103 offset:64
	global_load_dwordx4 v[52:55], v[72:73], off offset:1024
	s_waitcnt lgkmcnt(0)
	v_mfma_f32_32x32x16_bf16 v[16:31], v[36:39], v[68:71], v[16:31]
	global_load_dwordx4 v[36:39], v[76:77], off offset:2048
	v_mfma_f32_32x32x16_bf16 v[0:15], v[40:43], v[68:71], v[0:15]
	ds_read_b128 v[68:71], v103 offset:96
	global_load_dwordx4 v[40:43], v[72:73], off offset:2048
	s_waitcnt lgkmcnt(0)
	v_mfma_f32_32x32x16_bf16 v[16:31], v[44:47], v[68:71], v[16:31]
	global_load_dwordx4 v[44:47], v[76:77], off offset:3072
	v_mfma_f32_32x32x16_bf16 v[0:15], v[48:51], v[68:71], v[0:15]
	global_load_dwordx4 v[48:51], v[72:73], off offset:3072
	ds_write_b128 v88, v[60:63] offset:4608
	v_add_co_u32_e32 v60, vcc, s31, v92
	v_lshl_add_u64 v[72:73], v[94:95], 0, s[10:11]
	s_nop 0
	v_addc_co_u32_e32 v61, vcc, 0, v93, vcc
	global_load_dwordx4 v[60:63], v[60:61], off offset:2048
	s_nop 0
	global_load_dwordx4 v[68:71], v[96:97], off offset:2048
	s_nop 0
	global_load_dwordx4 v[72:75], v[72:73], off offset:16
	s_waitcnt lgkmcnt(0)
	s_barrier
	s_mov_b32 s10, 0x18000
	s_waitcnt vmcnt(2)
	v_lshlrev_b32_e32 v76, 16, v60
	v_and_b32_e32 v77, 0xffff0000, v60
	s_waitcnt vmcnt(1)
	v_pk_add_f32 v[68:69], v[68:69], v[76:77]
	v_add_co_u32_e32 v76, vcc, s10, v90
	v_cvt_pk_bf16_f32 v60, v68, v69
	v_lshlrev_b32_e32 v68, 16, v61
	v_and_b32_e32 v69, 0xffff0000, v61
	v_pk_add_f32 v[68:69], v[70:71], v[68:69]
	v_addc_co_u32_e32 v77, vcc, 0, v91, vcc
	v_cvt_pk_bf16_f32 v61, v68, v69
	v_lshlrev_b32_e32 v68, 16, v62
	v_and_b32_e32 v69, 0xffff0000, v62
	s_waitcnt vmcnt(0)
	v_pk_add_f32 v[68:69], v[72:73], v[68:69]
	v_add_co_u32_e32 v80, vcc, s18, v90
	v_cvt_pk_bf16_f32 v62, v68, v69
	v_lshlrev_b32_e32 v68, 16, v63
	v_and_b32_e32 v69, 0xffff0000, v63
	v_pk_add_f32 v[68:69], v[74:75], v[68:69]
	v_addc_co_u32_e32 v81, vcc, 0, v91, vcc
	v_cvt_pk_bf16_f32 v63, v68, v69
	ds_read_b128 v[72:75], v103 offset:4608
	ds_read_b128 v[68:71], v103 offset:4640
	s_waitcnt lgkmcnt(1)
	v_mfma_f32_32x32x16_bf16 v[16:31], v[32:35], v[72:75], v[16:31]
	s_mov_b64 s[10:11], 0x1900
	global_load_dwordx4 v[32:35], v[76:77], off
	v_mfma_f32_32x32x16_bf16 v[0:15], v[64:67], v[72:75], v[0:15]
	ds_read_b128 v[72:75], v103 offset:4672
	global_load_dwordx4 v[64:67], v[80:81], off
	s_waitcnt lgkmcnt(1)
	v_mfma_f32_32x32x16_bf16 v[16:31], v[56:59], v[68:71], v[16:31]
	global_load_dwordx4 v[56:59], v[76:77], off offset:1024
	v_mfma_f32_32x32x16_bf16 v[0:15], v[52:55], v[68:71], v[0:15]
	global_load_dwordx4 v[52:55], v[80:81], off offset:1024
	global_load_dwordx4 v[68:71], v[76:77], off offset:2048
	s_nop 0
	global_load_dwordx4 v[76:79], v[76:77], off offset:3072
	s_waitcnt lgkmcnt(0)
	v_mfma_f32_32x32x16_bf16 v[16:31], v[36:39], v[72:75], v[16:31]
	ds_read_b128 v[36:39], v103 offset:4704
	v_mfma_f32_32x32x16_bf16 v[0:15], v[40:43], v[72:75], v[0:15]
	global_load_dwordx4 v[72:75], v[80:81], off offset:2048
	v_lshl_add_u64 v[40:41], v[94:95], 0, s[10:11]
	global_load_dwordx4 v[80:83], v[80:81], off offset:3072
	ds_write_b128 v88, v[60:63]
	s_mov_b32 s10, 0x39000
	s_waitcnt lgkmcnt(1)
	v_mfma_f32_32x32x16_bf16 v[16:31], v[44:47], v[36:39], v[16:31]
	v_add_co_u32_e32 v44, vcc, s34, v92
	s_nop 1
	v_addc_co_u32_e32 v45, vcc, 0, v93, vcc
	v_mfma_f32_32x32x16_bf16 v[0:15], v[48:51], v[36:39], v[0:15]
	global_load_dwordx4 v[36:39], v[96:97], off offset:2304
	s_nop 0
	global_load_dwordx4 v[40:43], v[40:41], off offset:16
	s_nop 0
	global_load_dwordx4 v[44:47], v[44:45], off offset:1280
	s_waitcnt lgkmcnt(0)
	s_barrier
	s_waitcnt vmcnt(0)
	v_lshlrev_b32_e32 v48, 16, v44
	v_and_b32_e32 v49, 0xffff0000, v44
	v_pk_add_f32 v[36:37], v[36:37], v[48:49]
	v_add_co_u32_e32 v48, vcc, s24, v90
	v_cvt_pk_bf16_f32 v84, v36, v37
	v_lshlrev_b32_e32 v36, 16, v45
	v_and_b32_e32 v37, 0xffff0000, v45
	v_pk_add_f32 v[36:37], v[38:39], v[36:37]
	v_addc_co_u32_e32 v49, vcc, 0, v91, vcc
	v_cvt_pk_bf16_f32 v85, v36, v37
	v_lshlrev_b32_e32 v36, 16, v46
	v_and_b32_e32 v37, 0xffff0000, v46
	v_pk_add_f32 v[36:37], v[40:41], v[36:37]
	s_nop 0
	v_cvt_pk_bf16_f32 v86, v36, v37
	v_lshlrev_b32_e32 v36, 16, v47
	v_and_b32_e32 v37, 0xffff0000, v47
	v_pk_add_f32 v[36:37], v[42:43], v[36:37]
	s_nop 0
	v_cvt_pk_bf16_f32 v87, v36, v37
	ds_read_b128 v[36:39], v103
	ds_read_b128 v[40:43], v103 offset:32
	s_waitcnt lgkmcnt(1)
	v_mfma_f32_32x32x16_bf16 v[16:31], v[32:35], v[36:39], v[16:31]
	ds_read_b128 v[44:47], v103 offset:64
	global_load_dwordx4 v[32:35], v[48:49], off
	global_load_dwordx4 v[60:63], v[48:49], off offset:1024
	v_mfma_f32_32x32x16_bf16 v[0:15], v[64:67], v[36:39], v[0:15]
	v_add_co_u32_e32 v64, vcc, s10, v90
	s_mov_b64 s[10:11], 0x1a00
	s_nop 0
	v_addc_co_u32_e32 v65, vcc, 0, v91, vcc
	global_load_dwordx4 v[36:39], v[64:65], off
	s_waitcnt lgkmcnt(1)
	v_mfma_f32_32x32x16_bf16 v[16:31], v[56:59], v[40:43], v[16:31]
	global_load_dwordx4 v[56:59], v[64:65], off offset:1024
	v_mfma_f32_32x32x16_bf16 v[0:15], v[52:55], v[40:43], v[0:15]
	ds_read_b128 v[52:55], v103 offset:96
	global_load_dwordx4 v[40:43], v[48:49], off offset:2048
	s_nop 0
	global_load_dwordx4 v[48:51], v[48:49], off offset:3072
	s_waitcnt lgkmcnt(1)
	v_mfma_f32_32x32x16_bf16 v[16:31], v[68:71], v[44:47], v[16:31]
	v_mfma_f32_32x32x16_bf16 v[0:15], v[72:75], v[44:47], v[0:15]
	global_load_dwordx4 v[44:47], v[64:65], off offset:2048
	v_lshl_add_u64 v[72:73], v[94:95], 0, s[10:11]
	s_mov_b32 s10, 0x1a000
	s_waitcnt lgkmcnt(0)
	v_mfma_f32_32x32x16_bf16 v[16:31], v[76:79], v[52:55], v[16:31]
	v_mfma_f32_32x32x16_bf16 v[0:15], v[80:83], v[52:55], v[0:15]
	global_load_dwordx4 v[52:55], v[64:65], off offset:3072
	v_add_co_u32_e32 v64, vcc, s35, v92
	ds_write_b128 v88, v[84:87] offset:4608
	s_nop 0
	v_addc_co_u32_e32 v65, vcc, 0, v93, vcc
	global_load_dwordx4 v[64:67], v[64:65], off offset:512
	s_nop 0
	global_load_dwordx4 v[68:71], v[96:97], off offset:2560
	s_nop 0
	global_load_dwordx4 v[72:75], v[72:73], off offset:16
	s_waitcnt lgkmcnt(0)
	s_barrier
	s_waitcnt vmcnt(2)
	v_lshlrev_b32_e32 v76, 16, v64
	v_and_b32_e32 v77, 0xffff0000, v64
	s_waitcnt vmcnt(1)
	v_pk_add_f32 v[68:69], v[68:69], v[76:77]
	v_add_co_u32_e32 v76, vcc, s10, v90
	v_cvt_pk_bf16_f32 v64, v68, v69
	v_lshlrev_b32_e32 v68, 16, v65
	v_and_b32_e32 v69, 0xffff0000, v65
	v_pk_add_f32 v[68:69], v[70:71], v[68:69]
	v_addc_co_u32_e32 v77, vcc, 0, v91, vcc
	v_cvt_pk_bf16_f32 v65, v68, v69
	v_lshlrev_b32_e32 v68, 16, v66
	v_and_b32_e32 v69, 0xffff0000, v66
	s_waitcnt vmcnt(0)
	v_pk_add_f32 v[68:69], v[72:73], v[68:69]
	s_mov_b32 s10, 0x3a000
	v_cvt_pk_bf16_f32 v66, v68, v69
	v_lshlrev_b32_e32 v68, 16, v67
	v_and_b32_e32 v69, 0xffff0000, v67
	v_pk_add_f32 v[68:69], v[74:75], v[68:69]
	s_nop 0
	v_cvt_pk_bf16_f32 v67, v68, v69
	ds_read_b128 v[72:75], v103 offset:4608
	ds_read_b128 v[68:71], v103 offset:4640
	s_waitcnt lgkmcnt(1)
	v_mfma_f32_32x32x16_bf16 v[0:15], v[36:39], v[72:75], v[0:15]
	v_mfma_f32_32x32x16_bf16 v[16:31], v[32:35], v[72:75], v[16:31]
	v_add_co_u32_e32 v72, vcc, s10, v90
	s_mov_b64 s[10:11], 0x1b00
	s_nop 0
	v_addc_co_u32_e32 v73, vcc, 0, v91, vcc
	global_load_dwordx4 v[36:39], v[72:73], off
	global_load_dwordx4 v[32:35], v[76:77], off
	s_waitcnt lgkmcnt(0)
	v_mfma_f32_32x32x16_bf16 v[0:15], v[56:59], v[68:71], v[0:15]
	global_load_dwordx4 v[56:59], v[72:73], off offset:1024
	v_mfma_f32_32x32x16_bf16 v[16:31], v[60:63], v[68:71], v[16:31]
	ds_read_b128 v[68:71], v103 offset:4672
	global_load_dwordx4 v[60:63], v[76:77], off offset:1024
	s_waitcnt lgkmcnt(0)
	v_mfma_f32_32x32x16_bf16 v[0:15], v[44:47], v[68:71], v[0:15]
	global_load_dwordx4 v[44:47], v[72:73], off offset:2048
	v_mfma_f32_32x32x16_bf16 v[16:31], v[40:43], v[68:71], v[16:31]
	ds_read_b128 v[68:71], v103 offset:4704
	global_load_dwordx4 v[40:43], v[76:77], off offset:2048
	s_waitcnt lgkmcnt(0)
	v_mfma_f32_32x32x16_bf16 v[0:15], v[52:55], v[68:71], v[0:15]
	global_load_dwordx4 v[52:55], v[72:73], off offset:3072
	v_add_co_u32_e32 v72, vcc, s23, v92
	s_nop 1
	v_addc_co_u32_e32 v73, vcc, 0, v93, vcc
	v_add_co_u32_e32 v80, vcc, s13, v90
	v_mfma_f32_32x32x16_bf16 v[16:31], v[48:51], v[68:71], v[16:31]
	global_load_dwordx4 v[48:51], v[76:77], off offset:3072
	ds_write_b128 v88, v[64:67]
	v_lshl_add_u64 v[68:69], v[94:95], 0, s[10:11]
	global_load_dwordx4 v[64:67], v[96:97], off offset:2816
	s_nop 0
	global_load_dwordx4 v[68:71], v[68:69], off offset:16
	v_addc_co_u32_e32 v81, vcc, 0, v91, vcc
	global_load_dwordx4 v[72:75], v[72:73], off offset:3840
	s_waitcnt lgkmcnt(0)
	s_barrier
	s_mov_b32 s10, 0x3b000
	v_add_co_u32_e32 v82, vcc, s10, v90
	s_mov_b64 s[10:11], 0x1c00
	s_nop 0
	v_addc_co_u32_e32 v83, vcc, 0, v91, vcc
	s_waitcnt vmcnt(0)
	v_lshlrev_b32_e32 v76, 16, v72
	v_and_b32_e32 v77, 0xffff0000, v72
	v_lshlrev_b32_e32 v72, 16, v73
	v_and_b32_e32 v73, 0xffff0000, v73
	v_pk_add_f32 v[64:65], v[64:65], v[76:77]
	v_pk_add_f32 v[66:67], v[66:67], v[72:73]
	v_cvt_pk_bf16_f32 v64, v64, v65
	v_cvt_pk_bf16_f32 v65, v66, v67
	v_lshlrev_b32_e32 v66, 16, v74
	v_and_b32_e32 v67, 0xffff0000, v74
	v_pk_add_f32 v[66:67], v[68:69], v[66:67]
	v_lshlrev_b32_e32 v68, 16, v75
	v_and_b32_e32 v69, 0xffff0000, v75
	v_pk_add_f32 v[68:69], v[70:71], v[68:69]
	v_cvt_pk_bf16_f32 v66, v66, v67
	v_cvt_pk_bf16_f32 v67, v68, v69
	ds_read_b128 v[72:75], v103
	ds_read_b128 v[68:71], v103 offset:32
	s_waitcnt lgkmcnt(1)
	v_mfma_f32_32x32x16_bf16 v[16:31], v[32:35], v[72:75], v[16:31]
	global_load_dwordx4 v[76:79], v[80:81], off
	global_load_dwordx4 v[32:35], v[80:81], off offset:1024
	v_mfma_f32_32x32x16_bf16 v[0:15], v[36:39], v[72:75], v[0:15]
	global_load_dwordx4 v[72:75], v[82:83], off
	global_load_dwordx4 v[36:39], v[82:83], off offset:1024
	s_waitcnt lgkmcnt(0)
	v_mfma_f32_32x32x16_bf16 v[16:31], v[60:63], v[68:71], v[16:31]
	global_load_dwordx4 v[60:63], v[82:83], off offset:2048
	v_mfma_f32_32x32x16_bf16 v[0:15], v[56:59], v[68:71], v[0:15]
	ds_read_b128 v[56:59], v103 offset:64
	s_waitcnt lgkmcnt(0)
	v_mfma_f32_32x32x16_bf16 v[16:31], v[40:43], v[56:59], v[16:31]
	global_load_dwordx4 v[40:43], v[80:81], off offset:2048
	v_mfma_f32_32x32x16_bf16 v[0:15], v[44:47], v[56:59], v[0:15]
	ds_read_b128 v[44:47], v103 offset:96
	s_waitcnt lgkmcnt(0)
	v_mfma_f32_32x32x16_bf16 v[16:31], v[48:51], v[44:47], v[16:31]
	global_load_dwordx4 v[48:51], v[80:81], off offset:3072
	v_mfma_f32_32x32x16_bf16 v[0:15], v[52:55], v[44:47], v[0:15]
	v_add_co_u32_e32 v44, vcc, s15, v92
	global_load_dwordx4 v[52:55], v[82:83], off offset:3072
	ds_write_b128 v88, v[64:67] offset:4608
	v_addc_co_u32_e32 v45, vcc, 0, v93, vcc
	global_load_dwordx4 v[44:47], v[44:45], off offset:3072
	v_lshl_add_u64 v[64:65], v[94:95], 0, s[10:11]
	global_load_dwordx4 v[56:59], v[96:97], off offset:3072
	global_load_dwordx4 v[66:69], v[64:65], off offset:16
	s_waitcnt lgkmcnt(0)
	s_barrier
	s_mov_b32 s10, 0x1c000
	s_waitcnt vmcnt(2)
	v_lshlrev_b32_e32 v64, 16, v44
	v_and_b32_e32 v65, 0xffff0000, v44
	v_lshlrev_b32_e32 v44, 16, v45
	v_and_b32_e32 v45, 0xffff0000, v45
	s_waitcnt vmcnt(1)
	v_pk_add_f32 v[44:45], v[58:59], v[44:45]
	v_pk_add_f32 v[56:57], v[56:57], v[64:65]
	v_cvt_pk_bf16_f32 v65, v44, v45
	v_lshlrev_b32_e32 v44, 16, v46
	v_and_b32_e32 v45, 0xffff0000, v46
	s_waitcnt vmcnt(0)
	v_pk_add_f32 v[44:45], v[66:67], v[44:45]
	v_cvt_pk_bf16_f32 v64, v56, v57
	v_cvt_pk_bf16_f32 v66, v44, v45
	v_lshlrev_b32_e32 v44, 16, v47
	v_and_b32_e32 v45, 0xffff0000, v47
	v_pk_add_f32 v[44:45], v[68:69], v[44:45]
	s_nop 0
	v_cvt_pk_bf16_f32 v67, v44, v45
	ds_read_b128 v[56:59], v103 offset:4608
	ds_read_b128 v[44:47], v103 offset:4640
	s_waitcnt lgkmcnt(1)
	v_mfma_f32_32x32x16_bf16 v[16:31], v[76:79], v[56:59], v[16:31]
	v_add_co_u32_e32 v76, vcc, s10, v90
	s_mov_b32 s10, 0x3c000
	s_nop 0
	v_addc_co_u32_e32 v77, vcc, 0, v91, vcc
	v_add_co_u32_e32 v78, vcc, s10, v90
	v_mfma_f32_32x32x16_bf16 v[0:15], v[72:75], v[56:59], v[0:15]
	ds_read_b128 v[72:75], v103 offset:4672
	v_addc_co_u32_e32 v79, vcc, 0, v91, vcc
	s_mov_b64 s[10:11], 0x1d00
	global_load_dwordx4 v[68:71], v[76:77], off
	global_load_dwordx4 v[56:59], v[78:79], off
	s_waitcnt lgkmcnt(1)
	v_mfma_f32_32x32x16_bf16 v[16:31], v[32:35], v[44:47], v[16:31]
	global_load_dwordx4 v[32:35], v[76:77], off offset:1024
	v_mfma_f32_32x32x16_bf16 v[0:15], v[36:39], v[44:47], v[0:15]
	global_load_dwordx4 v[36:39], v[78:79], off offset:1024
	global_load_dwordx4 v[44:47], v[76:77], off offset:2048
	s_waitcnt lgkmcnt(0)
	v_mfma_f32_32x32x16_bf16 v[16:31], v[40:43], v[72:75], v[16:31]
	global_load_dwordx4 v[40:43], v[78:79], off offset:2048
	v_mfma_f32_32x32x16_bf16 v[0:15], v[60:63], v[72:75], v[0:15]
	ds_read_b128 v[60:63], v103 offset:4704
	v_add_co_u32_e32 v72, vcc, s16, v92
	s_nop 1
	v_addc_co_u32_e32 v73, vcc, 0, v93, vcc
	v_add_co_u32_e32 v80, vcc, s25, v90
	s_waitcnt lgkmcnt(0)
	v_mfma_f32_32x32x16_bf16 v[16:31], v[48:51], v[60:63], v[16:31]
	global_load_dwordx4 v[48:51], v[76:77], off offset:3072
	v_addc_co_u32_e32 v81, vcc, 0, v91, vcc
	v_mfma_f32_32x32x16_bf16 v[0:15], v[52:55], v[60:63], v[0:15]
	global_load_dwordx4 v[52:55], v[78:79], off offset:3072
	ds_write_b128 v88, v[64:67]
	v_lshl_add_u64 v[64:65], v[94:95], 0, s[10:11]
	global_load_dwordx4 v[60:63], v[96:97], off offset:3328
	s_nop 0
	global_load_dwordx4 v[64:67], v[64:65], off offset:16
	s_mov_b32 s10, 0x3d000
	global_load_dwordx4 v[72:75], v[72:73], off offset:2304
	s_waitcnt lgkmcnt(0)
	s_barrier
	v_add_co_u32_e32 v82, vcc, s10, v90
	s_mov_b64 s[10:11], 0x1e00
	s_nop 0
	v_addc_co_u32_e32 v83, vcc, 0, v91, vcc
	s_waitcnt vmcnt(0)
	v_lshlrev_b32_e32 v76, 16, v72
	v_and_b32_e32 v77, 0xffff0000, v72
	v_lshlrev_b32_e32 v72, 16, v73
	v_and_b32_e32 v73, 0xffff0000, v73
	v_pk_add_f32 v[60:61], v[60:61], v[76:77]
	v_pk_add_f32 v[62:63], v[62:63], v[72:73]
	v_cvt_pk_bf16_f32 v60, v60, v61
	v_cvt_pk_bf16_f32 v61, v62, v63
	v_lshlrev_b32_e32 v62, 16, v74
	v_and_b32_e32 v63, 0xffff0000, v74
	v_pk_add_f32 v[62:63], v[64:65], v[62:63]
	v_lshlrev_b32_e32 v64, 16, v75
	v_and_b32_e32 v65, 0xffff0000, v75
	v_pk_add_f32 v[64:65], v[66:67], v[64:65]
	v_cvt_pk_bf16_f32 v62, v62, v63
	v_cvt_pk_bf16_f32 v63, v64, v65
	ds_read_b128 v[72:75], v103
	ds_read_b128 v[64:67], v103 offset:32
	s_waitcnt lgkmcnt(1)
	v_mfma_f32_32x32x16_bf16 v[16:31], v[68:71], v[72:75], v[16:31]
	global_load_dwordx4 v[76:79], v[80:81], off
	global_load_dwordx4 v[68:71], v[80:81], off offset:1024
	v_mfma_f32_32x32x16_bf16 v[0:15], v[56:59], v[72:75], v[0:15]
	global_load_dwordx4 v[72:75], v[82:83], off
	global_load_dwordx4 v[56:59], v[80:81], off offset:2048
	s_waitcnt lgkmcnt(0)
	v_mfma_f32_32x32x16_bf16 v[16:31], v[32:35], v[64:67], v[16:31]
	ds_read_b128 v[32:35], v103 offset:64
	v_mfma_f32_32x32x16_bf16 v[0:15], v[36:39], v[64:67], v[0:15]
	ds_read_b128 v[36:39], v103 offset:96
	global_load_dwordx4 v[64:67], v[82:83], off offset:1024
	s_waitcnt lgkmcnt(1)
	v_mfma_f32_32x32x16_bf16 v[16:31], v[44:47], v[32:35], v[16:31]
	v_add_co_u32_e32 v44, vcc, s17, v92
	s_nop 1
	v_addc_co_u32_e32 v45, vcc, 0, v93, vcc
	v_mfma_f32_32x32x16_bf16 v[0:15], v[40:43], v[32:35], v[0:15]
	global_load_dwordx4 v[40:43], v[82:83], off offset:2048
	global_load_dwordx4 v[32:35], v[80:81], off offset:3072
	v_add_co_u32_e32 v80, vcc, s14, v90
	s_nop 1
	v_addc_co_u32_e32 v81, vcc, 0, v91, vcc
	s_waitcnt lgkmcnt(0)
	v_mfma_f32_32x32x16_bf16 v[16:31], v[48:51], v[36:39], v[16:31]
	v_mfma_f32_32x32x16_bf16 v[0:15], v[52:55], v[36:39], v[0:15]
	global_load_dwordx4 v[36:39], v[82:83], off offset:3072
	ds_write_b128 v88, v[60:63] offset:4608
	global_load_dwordx4 v[44:47], v[44:45], off offset:1536
	v_lshl_add_u64 v[52:53], v[94:95], 0, s[10:11]
	global_load_dwordx4 v[48:51], v[96:97], off offset:3584
	s_nop 0
	global_load_dwordx4 v[52:55], v[52:53], off offset:16
	s_waitcnt lgkmcnt(0)
	s_barrier
	s_mov_b32 s10, 0x3e000
	v_add_co_u32_e32 v82, vcc, s10, v90
	s_mov_b64 s[10:11], 0x1f00
	s_nop 0
	v_addc_co_u32_e32 v83, vcc, 0, v91, vcc
	s_waitcnt vmcnt(2)
	v_lshlrev_b32_e32 v60, 16, v44
	v_and_b32_e32 v61, 0xffff0000, v44
	v_lshlrev_b32_e32 v44, 16, v45
	v_and_b32_e32 v45, 0xffff0000, v45
	s_waitcnt vmcnt(1)
	v_pk_add_f32 v[44:45], v[50:51], v[44:45]
	v_pk_add_f32 v[48:49], v[48:49], v[60:61]
	v_cvt_pk_bf16_f32 v61, v44, v45
	v_lshlrev_b32_e32 v44, 16, v46
	v_and_b32_e32 v45, 0xffff0000, v46
	s_waitcnt vmcnt(0)
	v_pk_add_f32 v[44:45], v[52:53], v[44:45]
	v_cvt_pk_bf16_f32 v60, v48, v49
	v_cvt_pk_bf16_f32 v62, v44, v45
	v_lshlrev_b32_e32 v44, 16, v47
	v_and_b32_e32 v45, 0xffff0000, v47
	v_pk_add_f32 v[44:45], v[54:55], v[44:45]
	s_nop 0
	v_cvt_pk_bf16_f32 v63, v44, v45
	ds_read_b128 v[48:51], v103 offset:4608
	ds_read_b128 v[44:47], v103 offset:4640
	s_waitcnt lgkmcnt(1)
	v_mfma_f32_32x32x16_bf16 v[0:15], v[72:75], v[48:51], v[0:15]
	ds_read_b128 v[52:55], v103 offset:4672
	global_load_dwordx4 v[72:75], v[82:83], off
	v_mfma_f32_32x32x16_bf16 v[16:31], v[76:79], v[48:51], v[16:31]
	global_load_dwordx4 v[76:79], v[80:81], off
	global_load_dwordx4 v[48:51], v[80:81], off offset:2048
	s_waitcnt lgkmcnt(1)
	v_mfma_f32_32x32x16_bf16 v[0:15], v[64:67], v[44:47], v[0:15]
	v_mfma_f32_32x32x16_bf16 v[16:31], v[68:71], v[44:47], v[16:31]
	global_load_dwordx4 v[68:71], v[80:81], off offset:1024
	global_load_dwordx4 v[44:47], v[82:83], off offset:1024
	s_waitcnt lgkmcnt(0)
	v_mfma_f32_32x32x16_bf16 v[0:15], v[40:43], v[52:55], v[0:15]
	global_load_dwordx4 v[40:43], v[80:81], off offset:3072
	v_mfma_f32_32x32x16_bf16 v[16:31], v[56:59], v[52:55], v[16:31]
	ds_read_b128 v[56:59], v103 offset:4704
	global_load_dwordx4 v[52:55], v[82:83], off offset:2048
	s_waitcnt lgkmcnt(0)
	v_mfma_f32_32x32x16_bf16 v[0:15], v[36:39], v[56:59], v[0:15]
	global_load_dwordx4 v[36:39], v[82:83], off offset:3072
	ds_write_b128 v88, v[60:63]
	v_add_co_u32_e32 v60, vcc, s18, v92
	s_nop 1
	v_addc_co_u32_e32 v61, vcc, 0, v93, vcc
	v_mfma_f32_32x32x16_bf16 v[16:31], v[32:35], v[56:59], v[16:31]
	v_lshl_add_u64 v[56:57], v[94:95], 0, s[10:11]
	global_load_dwordx4 v[32:35], v[96:97], off offset:3840
	s_nop 0
	global_load_dwordx4 v[56:59], v[56:57], off offset:16
	s_mov_b32 s10, 0x1f000
	global_load_dwordx4 v[60:63], v[60:61], off offset:768
	s_waitcnt lgkmcnt(0)
	s_barrier
	s_waitcnt vmcnt(0)
	v_lshlrev_b32_e32 v64, 16, v60
	v_and_b32_e32 v65, 0xffff0000, v60
	v_lshlrev_b32_e32 v60, 16, v61
	v_and_b32_e32 v61, 0xffff0000, v61
	v_pk_add_f32 v[32:33], v[32:33], v[64:65]
	v_pk_add_f32 v[34:35], v[34:35], v[60:61]
	v_cvt_pk_bf16_f32 v32, v32, v33
	v_cvt_pk_bf16_f32 v33, v34, v35
	v_lshlrev_b32_e32 v34, 16, v62
	v_and_b32_e32 v35, 0xffff0000, v62
	v_pk_add_f32 v[34:35], v[56:57], v[34:35]
	v_lshlrev_b32_e32 v56, 16, v63
	v_and_b32_e32 v57, 0xffff0000, v63
	v_pk_add_f32 v[56:57], v[58:59], v[56:57]
	v_cvt_pk_bf16_f32 v34, v34, v35
	v_cvt_pk_bf16_f32 v35, v56, v57
	ds_read_b128 v[64:67], v103
	ds_read_b128 v[56:59], v103 offset:32
	s_waitcnt lgkmcnt(1)
	v_mfma_f32_32x32x16_bf16 v[16:31], v[76:79], v[64:67], v[16:31]
	v_add_co_u32_e32 v76, vcc, s10, v90
	s_mov_b32 s10, 0x3f000
	s_nop 0
	v_addc_co_u32_e32 v77, vcc, 0, v91, vcc
	global_load_dwordx4 v[60:63], v[76:77], off
	v_mfma_f32_32x32x16_bf16 v[0:15], v[72:75], v[64:67], v[0:15]
	v_add_co_u32_e32 v72, vcc, s10, v90
	s_movk_i32 s10, 0x210
	s_nop 0
	v_addc_co_u32_e32 v73, vcc, 0, v91, vcc
	global_load_dwordx4 v[64:67], v[72:73], off
	s_waitcnt lgkmcnt(0)
	v_mfma_f32_32x32x16_bf16 v[16:31], v[68:71], v[56:59], v[16:31]
	global_load_dwordx4 v[68:71], v[76:77], off offset:1024
	v_mfma_f32_32x32x16_bf16 v[0:15], v[44:47], v[56:59], v[0:15]
	global_load_dwordx4 v[44:47], v[72:73], off offset:1024
	ds_read_b128 v[56:59], v103 offset:64
	s_waitcnt lgkmcnt(0)
	v_mfma_f32_32x32x16_bf16 v[16:31], v[48:51], v[56:59], v[16:31]
	global_load_dwordx4 v[48:51], v[76:77], off offset:2048
	v_mfma_f32_32x32x16_bf16 v[0:15], v[52:55], v[56:59], v[0:15]
	global_load_dwordx4 v[52:55], v[72:73], off offset:2048
	ds_read_b128 v[56:59], v103 offset:96
	s_waitcnt lgkmcnt(0)
	v_mfma_f32_32x32x16_bf16 v[16:31], v[40:43], v[56:59], v[16:31]
	global_load_dwordx4 v[40:43], v[76:77], off offset:3072
	v_mfma_f32_32x32x16_bf16 v[0:15], v[36:39], v[56:59], v[0:15]
	global_load_dwordx4 v[36:39], v[72:73], off offset:3072
	ds_write_b128 v88, v[32:35] offset:4608
	s_waitcnt lgkmcnt(0)
	s_barrier
	ds_read_b128 v[32:35], v103 offset:4608
	ds_read_b128 v[56:59], v103 offset:4640
	s_waitcnt vmcnt(7) lgkmcnt(1)
	v_mfma_f32_32x32x16_bf16 v[16:31], v[60:63], v[32:35], v[16:31]
	s_waitcnt vmcnt(6)
	v_mfma_f32_32x32x16_bf16 v[0:15], v[64:67], v[32:35], v[0:15]
	ds_read_b128 v[32:35], v103 offset:4672
	s_waitcnt vmcnt(5) lgkmcnt(1)
	v_mfma_f32_32x32x16_bf16 v[16:31], v[68:71], v[56:59], v[16:31]
	s_waitcnt vmcnt(4)
	v_mfma_f32_32x32x16_bf16 v[0:15], v[44:47], v[56:59], v[0:15]
	s_waitcnt vmcnt(3) lgkmcnt(0)
	v_mfma_f32_32x32x16_bf16 v[16:31], v[48:51], v[32:35], v[16:31]
	s_waitcnt vmcnt(2)
	v_mfma_f32_32x32x16_bf16 v[0:15], v[52:55], v[32:35], v[0:15]
	ds_read_b128 v[32:35], v103 offset:4704
	s_waitcnt lgkmcnt(0)
	s_barrier
	s_waitcnt vmcnt(1)
	v_mfma_f32_32x32x16_bf16 v[16:31], v[40:43], v[32:35], v[16:31]
	s_waitcnt vmcnt(0)
	v_mfma_f32_32x32x16_bf16 v[0:15], v[36:39], v[32:35], v[0:15]
	v_and_b32_e32 v32, 0x7fffffc0, v198
	v_lshlrev_b32_e32 v32, 1, v32
	v_mad_u32_u24 v32, v100, s10, v32
	v_lshl_or_b32 v34, v102, 3, v32
	s_nop 6
	v_mul_f32_e32 v32, 0xbfb8aa3b, v16
	v_mul_f32_e32 v33, 0xbfb8aa3b, v17
	v_exp_f32_e32 v32, v32
	v_exp_f32_e32 v33, v33
	s_nop 0
	v_pk_add_f32 v[32:33], v[32:33], 1.0 op_sel_hi:[1,0]
	s_nop 0
	v_div_scale_f32 v35, s[10:11], v33, v33, v17
	v_rcp_f32_e32 v36, v35
	s_nop 0
	v_fma_f32 v37, -v35, v36, 1.0
	v_fmac_f32_e32 v36, v37, v36
	v_div_scale_f32 v37, vcc, v17, v33, v17
	v_mul_f32_e32 v38, v37, v36
	v_fma_f32 v39, -v35, v38, v37
	v_fmac_f32_e32 v38, v39, v36
	v_fma_f32 v35, -v35, v38, v37
	v_div_fmas_f32 v35, v35, v36, v38
	v_div_fixup_f32 v33, v35, v33, v17
	v_div_scale_f32 v17, s[10:11], v32, v32, v16
	v_rcp_f32_e32 v35, v17
	s_nop 0
	v_fma_f32 v36, -v17, v35, 1.0
	v_fmac_f32_e32 v35, v36, v35
	v_div_scale_f32 v36, vcc, v16, v32, v16
	v_mul_f32_e32 v37, v36, v35
	v_fma_f32 v38, -v17, v37, v36
	v_fmac_f32_e32 v37, v38, v35
	v_fma_f32 v17, -v17, v37, v36
	v_div_fmas_f32 v17, v17, v35, v37
	v_div_fixup_f32 v32, v17, v32, v16
	v_mul_f32_e32 v16, 0xbfb8aa3b, v18
	v_mul_f32_e32 v17, 0xbfb8aa3b, v19
	v_exp_f32_e32 v16, v16
	v_exp_f32_e32 v17, v17
	s_nop 0
	v_pk_add_f32 v[16:17], v[16:17], 1.0 op_sel_hi:[1,0]
	s_nop 0
	v_div_scale_f32 v35, s[10:11], v17, v17, v19
	v_rcp_f32_e32 v36, v35
	s_nop 0
	v_fma_f32 v37, -v35, v36, 1.0
	v_fmac_f32_e32 v36, v37, v36
	v_div_scale_f32 v37, vcc, v19, v17, v19
	v_mul_f32_e32 v38, v37, v36
	v_fma_f32 v39, -v35, v38, v37
	v_fmac_f32_e32 v38, v39, v36
	v_fma_f32 v35, -v35, v38, v37
	v_div_fmas_f32 v35, v35, v36, v38
	v_div_fixup_f32 v17, v35, v17, v19
	v_div_scale_f32 v19, s[10:11], v16, v16, v18
	v_rcp_f32_e32 v35, v19
	s_nop 0
	v_fma_f32 v36, -v19, v35, 1.0
	v_fmac_f32_e32 v35, v36, v35
	v_div_scale_f32 v36, vcc, v18, v16, v18
	v_mul_f32_e32 v37, v36, v35
	v_fma_f32 v38, -v19, v37, v36
	v_fmac_f32_e32 v37, v38, v35
	v_fma_f32 v19, -v19, v37, v36
	v_div_fmas_f32 v19, v19, v35, v37
	v_div_fixup_f32 v18, v19, v16, v18
	v_cvt_pk_bf16_f32 v17, v18, v17
	v_mul_f32_e32 v18, 0xbfb8aa3b, v20
	v_mul_f32_e32 v19, 0xbfb8aa3b, v21
	v_exp_f32_e32 v18, v18
	v_exp_f32_e32 v19, v19
	v_cvt_pk_bf16_f32 v16, v32, v33
	v_pk_add_f32 v[18:19], v[18:19], 1.0 op_sel_hi:[1,0]
	s_nop 0
	v_div_scale_f32 v32, s[10:11], v19, v19, v21
	v_rcp_f32_e32 v33, v32
	s_nop 0
	v_fma_f32 v35, -v32, v33, 1.0
	v_fmac_f32_e32 v33, v35, v33
	v_div_scale_f32 v35, vcc, v21, v19, v21
	v_mul_f32_e32 v36, v35, v33
	v_fma_f32 v37, -v32, v36, v35
	v_fmac_f32_e32 v36, v37, v33
	v_fma_f32 v32, -v32, v36, v35
	v_div_fmas_f32 v32, v32, v33, v36
	v_div_fixup_f32 v21, v32, v19, v21
	v_div_scale_f32 v19, s[10:11], v18, v18, v20
	v_rcp_f32_e32 v32, v19
	s_nop 0
	v_fma_f32 v33, -v19, v32, 1.0
	v_fmac_f32_e32 v32, v33, v32
	v_div_scale_f32 v33, vcc, v20, v18, v20
	v_mul_f32_e32 v35, v33, v32
	v_fma_f32 v36, -v19, v35, v33
	v_fmac_f32_e32 v35, v36, v32
	v_fma_f32 v19, -v19, v35, v33
	v_div_fmas_f32 v19, v19, v32, v35
	v_div_fixup_f32 v20, v19, v18, v20
	v_mul_f32_e32 v18, 0xbfb8aa3b, v22
	v_mul_f32_e32 v19, 0xbfb8aa3b, v23
	v_exp_f32_e32 v18, v18
	v_exp_f32_e32 v19, v19
	s_nop 0
	v_pk_add_f32 v[18:19], v[18:19], 1.0 op_sel_hi:[1,0]
	s_nop 0
	v_div_scale_f32 v32, s[10:11], v19, v19, v23
	v_rcp_f32_e32 v33, v32
	s_nop 0
	v_fma_f32 v35, -v32, v33, 1.0
	v_fmac_f32_e32 v33, v35, v33
	v_div_scale_f32 v35, vcc, v23, v19, v23
	v_mul_f32_e32 v36, v35, v33
	v_fma_f32 v37, -v32, v36, v35
	v_fmac_f32_e32 v36, v37, v33
	v_fma_f32 v32, -v32, v36, v35
	v_div_fmas_f32 v32, v32, v33, v36
	v_div_fixup_f32 v19, v32, v19, v23
	v_div_scale_f32 v23, s[10:11], v18, v18, v22
	v_rcp_f32_e32 v32, v23
	s_nop 0
	v_fma_f32 v33, -v23, v32, 1.0
	v_fmac_f32_e32 v32, v33, v32
	v_div_scale_f32 v33, vcc, v22, v18, v22
	v_mul_f32_e32 v35, v33, v32
	v_fma_f32 v36, -v23, v35, v33
	v_fmac_f32_e32 v35, v36, v32
	v_fma_f32 v23, -v23, v35, v33
	v_div_fmas_f32 v23, v23, v32, v35
	v_div_fixup_f32 v22, v23, v18, v22
	v_cvt_pk_bf16_f32 v18, v20, v21
	v_cvt_pk_bf16_f32 v19, v22, v19
	v_add_u32_e32 v20, 0xa000, v34
	ds_write2_b64 v20, v[16:17], v[18:19] offset0:64 offset1:66
	v_mul_f32_e32 v16, 0xbfb8aa3b, v24
	v_mul_f32_e32 v17, 0xbfb8aa3b, v25
	v_exp_f32_e32 v16, v16
	v_exp_f32_e32 v17, v17
	s_nop 0
	v_pk_add_f32 v[16:17], v[16:17], 1.0 op_sel_hi:[1,0]
	s_nop 0
	v_div_scale_f32 v18, s[10:11], v17, v17, v25
	v_rcp_f32_e32 v19, v18
	s_nop 0
	v_fma_f32 v21, -v18, v19, 1.0
	v_fmac_f32_e32 v19, v21, v19
	v_div_scale_f32 v21, vcc, v25, v17, v25
	v_mul_f32_e32 v22, v21, v19
	v_fma_f32 v23, -v18, v22, v21
	v_fmac_f32_e32 v22, v23, v19
	v_fma_f32 v18, -v18, v22, v21
	v_div_fmas_f32 v18, v18, v19, v22
	v_div_fixup_f32 v18, v18, v17, v25
	v_div_scale_f32 v17, s[10:11], v16, v16, v24
	v_rcp_f32_e32 v19, v17
	s_nop 0
	v_fma_f32 v21, -v17, v19, 1.0
	v_fmac_f32_e32 v19, v21, v19
	v_div_scale_f32 v21, vcc, v24, v16, v24
	v_mul_f32_e32 v22, v21, v19
	v_fma_f32 v23, -v17, v22, v21
	v_fmac_f32_e32 v22, v23, v19
	v_fma_f32 v17, -v17, v22, v21
	v_div_fmas_f32 v17, v17, v19, v22
	v_div_fixup_f32 v19, v17, v16, v24
	v_mul_f32_e32 v16, 0xbfb8aa3b, v26
	v_mul_f32_e32 v17, 0xbfb8aa3b, v27
	v_exp_f32_e32 v16, v16
	v_exp_f32_e32 v17, v17
	s_nop 0
	v_pk_add_f32 v[16:17], v[16:17], 1.0 op_sel_hi:[1,0]
	s_nop 0
	v_div_scale_f32 v21, s[10:11], v17, v17, v27
	v_rcp_f32_e32 v22, v21
	s_nop 0
	v_fma_f32 v23, -v21, v22, 1.0
	v_fmac_f32_e32 v22, v23, v22
	v_div_scale_f32 v23, vcc, v27, v17, v27
	v_mul_f32_e32 v24, v23, v22
	v_fma_f32 v25, -v21, v24, v23
	v_fmac_f32_e32 v24, v25, v22
	v_fma_f32 v21, -v21, v24, v23
	v_div_fmas_f32 v21, v21, v22, v24
	v_div_fixup_f32 v17, v21, v17, v27
	v_div_scale_f32 v21, s[10:11], v16, v16, v26
	v_rcp_f32_e32 v22, v21
	s_nop 0
	v_fma_f32 v23, -v21, v22, 1.0
	v_fmac_f32_e32 v22, v23, v22
	v_div_scale_f32 v23, vcc, v26, v16, v26
	v_mul_f32_e32 v24, v23, v22
	v_fma_f32 v25, -v21, v24, v23
	v_fmac_f32_e32 v24, v25, v22
	v_fma_f32 v21, -v21, v24, v23
	v_div_fmas_f32 v21, v21, v22, v24
	v_div_fixup_f32 v21, v21, v16, v26
	v_cvt_pk_bf16_f32 v16, v19, v18
	v_mul_f32_e32 v18, 0xbfb8aa3b, v28
	v_mul_f32_e32 v19, 0xbfb8aa3b, v29
	v_exp_f32_e32 v18, v18
	v_exp_f32_e32 v19, v19
	v_cvt_pk_bf16_f32 v17, v21, v17
	v_pk_add_f32 v[18:19], v[18:19], 1.0 op_sel_hi:[1,0]
	s_nop 0
	v_div_scale_f32 v21, s[10:11], v19, v19, v29
	v_rcp_f32_e32 v22, v21
	s_nop 0
	v_fma_f32 v23, -v21, v22, 1.0
	v_fmac_f32_e32 v22, v23, v22
	v_div_scale_f32 v23, vcc, v29, v19, v29
	v_mul_f32_e32 v24, v23, v22
	v_fma_f32 v25, -v21, v24, v23
	v_fmac_f32_e32 v24, v25, v22
	v_fma_f32 v21, -v21, v24, v23
	v_div_fmas_f32 v21, v21, v22, v24
	v_div_fixup_f32 v21, v21, v19, v29
	v_div_scale_f32 v19, s[10:11], v18, v18, v28
	v_rcp_f32_e32 v22, v19
	s_nop 0
	v_fma_f32 v23, -v19, v22, 1.0
	v_fmac_f32_e32 v22, v23, v22
	v_div_scale_f32 v23, vcc, v28, v18, v28
	v_mul_f32_e32 v24, v23, v22
	v_fma_f32 v25, -v19, v24, v23
	v_fmac_f32_e32 v24, v25, v22
	v_fma_f32 v19, -v19, v24, v23
	v_div_fmas_f32 v19, v19, v22, v24
	v_div_fixup_f32 v22, v19, v18, v28
	v_mul_f32_e32 v18, 0xbfb8aa3b, v30
	v_mul_f32_e32 v19, 0xbfb8aa3b, v31
	v_exp_f32_e32 v18, v18
	v_exp_f32_e32 v19, v19
	s_nop 0
	v_pk_add_f32 v[18:19], v[18:19], 1.0 op_sel_hi:[1,0]
	s_nop 0
	v_div_scale_f32 v23, s[10:11], v19, v19, v31
	v_rcp_f32_e32 v24, v23
	s_nop 0
	v_fma_f32 v25, -v23, v24, 1.0
	v_fmac_f32_e32 v24, v25, v24
	v_div_scale_f32 v25, vcc, v31, v19, v31
	v_mul_f32_e32 v26, v25, v24
	v_fma_f32 v27, -v23, v26, v25
	v_fmac_f32_e32 v26, v27, v24
	v_fma_f32 v23, -v23, v26, v25
	v_div_fmas_f32 v23, v23, v24, v26
	v_div_fixup_f32 v19, v23, v19, v31
	v_div_scale_f32 v23, s[10:11], v18, v18, v30
	v_rcp_f32_e32 v24, v23
	s_nop 0
	v_fma_f32 v25, -v23, v24, 1.0
	v_fmac_f32_e32 v24, v25, v24
	v_div_scale_f32 v25, vcc, v30, v18, v30
	v_mul_f32_e32 v26, v25, v24
	v_fma_f32 v27, -v23, v26, v25
	v_fmac_f32_e32 v26, v27, v24
	v_fma_f32 v23, -v23, v26, v25
	v_div_fmas_f32 v23, v23, v24, v26
	v_div_fixup_f32 v23, v23, v18, v30
	v_cvt_pk_bf16_f32 v18, v22, v21
	v_cvt_pk_bf16_f32 v19, v23, v19
	ds_write2_b64 v20, v[16:17], v[18:19] offset0:68 offset1:70
	v_mul_f32_e32 v16, 0xbfb8aa3b, v0
	v_mul_f32_e32 v17, 0xbfb8aa3b, v1
	v_exp_f32_e32 v16, v16
	v_exp_f32_e32 v17, v17
	s_nop 0
	v_pk_add_f32 v[16:17], v[16:17], 1.0 op_sel_hi:[1,0]
	s_nop 0
	v_div_scale_f32 v18, s[10:11], v17, v17, v1
	v_rcp_f32_e32 v19, v18
	s_nop 0
	v_fma_f32 v21, -v18, v19, 1.0
	v_fmac_f32_e32 v19, v21, v19
	v_div_scale_f32 v21, vcc, v1, v17, v1
	v_mul_f32_e32 v22, v21, v19
	v_fma_f32 v23, -v18, v22, v21
	v_fmac_f32_e32 v22, v23, v19
	v_fma_f32 v18, -v18, v22, v21
	v_div_fmas_f32 v18, v18, v19, v22
	v_div_fixup_f32 v17, v18, v17, v1
	v_div_scale_f32 v1, s[10:11], v16, v16, v0
	v_rcp_f32_e32 v18, v1
	s_nop 0
	v_fma_f32 v19, -v1, v18, 1.0
	v_fmac_f32_e32 v18, v19, v18
	v_div_scale_f32 v19, vcc, v0, v16, v0
	v_mul_f32_e32 v21, v19, v18
	v_fma_f32 v22, -v1, v21, v19
	v_fmac_f32_e32 v21, v22, v18
	v_fma_f32 v1, -v1, v21, v19
	v_div_fmas_f32 v1, v1, v18, v21
	v_div_fixup_f32 v16, v1, v16, v0
	v_mul_f32_e32 v0, 0xbfb8aa3b, v2
	v_mul_f32_e32 v1, 0xbfb8aa3b, v3
	v_exp_f32_e32 v0, v0
	v_exp_f32_e32 v1, v1
	s_nop 0
	v_pk_add_f32 v[0:1], v[0:1], 1.0 op_sel_hi:[1,0]
	s_nop 0
	v_div_scale_f32 v18, s[10:11], v1, v1, v3
	v_rcp_f32_e32 v19, v18
	s_nop 0
	v_fma_f32 v21, -v18, v19, 1.0
	v_fmac_f32_e32 v19, v21, v19
	v_div_scale_f32 v21, vcc, v3, v1, v3
	v_mul_f32_e32 v22, v21, v19
	v_fma_f32 v23, -v18, v22, v21
	v_fmac_f32_e32 v22, v23, v19
	v_fma_f32 v18, -v18, v22, v21
	v_div_fmas_f32 v18, v18, v19, v22
	v_div_fixup_f32 v1, v18, v1, v3
	v_div_scale_f32 v3, s[10:11], v0, v0, v2
	v_rcp_f32_e32 v18, v3
	s_nop 0
	v_fma_f32 v19, -v3, v18, 1.0
	v_fmac_f32_e32 v18, v19, v18
	v_div_scale_f32 v19, vcc, v2, v0, v2
	v_mul_f32_e32 v21, v19, v18
	v_fma_f32 v22, -v3, v21, v19
	v_fmac_f32_e32 v21, v22, v18
	v_fma_f32 v3, -v3, v21, v19
	v_div_fmas_f32 v3, v3, v18, v21
	v_div_fixup_f32 v2, v3, v0, v2
	v_cvt_pk_bf16_f32 v1, v2, v1
	v_mul_f32_e32 v2, 0xbfb8aa3b, v4
	v_mul_f32_e32 v3, 0xbfb8aa3b, v5
	v_exp_f32_e32 v2, v2
	v_exp_f32_e32 v3, v3
	v_cvt_pk_bf16_f32 v0, v16, v17
	v_pk_add_f32 v[2:3], v[2:3], 1.0 op_sel_hi:[1,0]
	s_nop 0
	v_div_scale_f32 v16, s[10:11], v3, v3, v5
	v_rcp_f32_e32 v17, v16
	s_nop 0
	v_fma_f32 v18, -v16, v17, 1.0
	v_fmac_f32_e32 v17, v18, v17
	v_div_scale_f32 v18, vcc, v5, v3, v5
	v_mul_f32_e32 v19, v18, v17
	v_fma_f32 v21, -v16, v19, v18
	v_fmac_f32_e32 v19, v21, v17
	v_fma_f32 v16, -v16, v19, v18
	v_div_fmas_f32 v16, v16, v17, v19
	v_div_fixup_f32 v5, v16, v3, v5
	v_div_scale_f32 v3, s[10:11], v2, v2, v4
	v_rcp_f32_e32 v16, v3
	s_nop 0
	v_fma_f32 v17, -v3, v16, 1.0
	v_fmac_f32_e32 v16, v17, v16
	v_div_scale_f32 v17, vcc, v4, v2, v4
	v_mul_f32_e32 v18, v17, v16
	v_fma_f32 v19, -v3, v18, v17
	v_fmac_f32_e32 v18, v19, v16
	v_fma_f32 v3, -v3, v18, v17
	v_div_fmas_f32 v3, v3, v16, v18
	v_div_fixup_f32 v4, v3, v2, v4
	v_mul_f32_e32 v2, 0xbfb8aa3b, v6
	v_mul_f32_e32 v3, 0xbfb8aa3b, v7
	v_exp_f32_e32 v2, v2
	v_exp_f32_e32 v3, v3
	s_nop 0
	v_pk_add_f32 v[2:3], v[2:3], 1.0 op_sel_hi:[1,0]
	s_nop 0
	v_div_scale_f32 v16, s[10:11], v3, v3, v7
	v_rcp_f32_e32 v17, v16
	s_nop 0
	v_fma_f32 v18, -v16, v17, 1.0
	v_fmac_f32_e32 v17, v18, v17
	v_div_scale_f32 v18, vcc, v7, v3, v7
	v_mul_f32_e32 v19, v18, v17
	v_fma_f32 v21, -v16, v19, v18
	v_fmac_f32_e32 v19, v21, v17
	v_fma_f32 v16, -v16, v19, v18
	v_div_fmas_f32 v16, v16, v17, v19
	v_div_fixup_f32 v3, v16, v3, v7
	v_div_scale_f32 v7, s[10:11], v2, v2, v6
	v_rcp_f32_e32 v16, v7
	s_nop 0
	v_fma_f32 v17, -v7, v16, 1.0
	v_fmac_f32_e32 v16, v17, v16
	v_div_scale_f32 v17, vcc, v6, v2, v6
	v_mul_f32_e32 v18, v17, v16
	v_fma_f32 v19, -v7, v18, v17
	v_fmac_f32_e32 v18, v19, v16
	v_fma_f32 v7, -v7, v18, v17
	v_div_fmas_f32 v7, v7, v16, v18
	v_div_fixup_f32 v6, v7, v2, v6
	v_cvt_pk_bf16_f32 v2, v4, v5
	v_cvt_pk_bf16_f32 v3, v6, v3
	ds_write2_b64 v20, v[0:1], v[2:3] offset0:72 offset1:74
	v_mul_f32_e32 v0, 0xbfb8aa3b, v8
	v_mul_f32_e32 v1, 0xbfb8aa3b, v9
	v_exp_f32_e32 v0, v0
	v_exp_f32_e32 v1, v1
	s_nop 0
	v_pk_add_f32 v[0:1], v[0:1], 1.0 op_sel_hi:[1,0]
	s_nop 0
	v_div_scale_f32 v2, s[10:11], v1, v1, v9
	v_rcp_f32_e32 v3, v2
	s_nop 0
	v_fma_f32 v4, -v2, v3, 1.0
	v_fmac_f32_e32 v3, v4, v3
	v_div_scale_f32 v4, vcc, v9, v1, v9
	v_mul_f32_e32 v5, v4, v3
	v_fma_f32 v6, -v2, v5, v4
	v_fmac_f32_e32 v5, v6, v3
	v_fma_f32 v2, -v2, v5, v4
	v_div_fmas_f32 v2, v2, v3, v5
	v_div_fixup_f32 v2, v2, v1, v9
	v_div_scale_f32 v1, s[10:11], v0, v0, v8
	v_rcp_f32_e32 v3, v1
	s_nop 0
	v_fma_f32 v4, -v1, v3, 1.0
	v_fmac_f32_e32 v3, v4, v3
	v_div_scale_f32 v4, vcc, v8, v0, v8
	v_mul_f32_e32 v5, v4, v3
	v_fma_f32 v6, -v1, v5, v4
	v_fmac_f32_e32 v5, v6, v3
	v_fma_f32 v1, -v1, v5, v4
	v_div_fmas_f32 v1, v1, v3, v5
	v_div_fixup_f32 v3, v1, v0, v8
	v_mul_f32_e32 v0, 0xbfb8aa3b, v10
	v_mul_f32_e32 v1, 0xbfb8aa3b, v11
	v_exp_f32_e32 v0, v0
	v_exp_f32_e32 v1, v1
	s_nop 0
	v_pk_add_f32 v[0:1], v[0:1], 1.0 op_sel_hi:[1,0]
	s_nop 0
	v_div_scale_f32 v4, s[10:11], v1, v1, v11
	v_rcp_f32_e32 v5, v4
	s_nop 0
	v_fma_f32 v6, -v4, v5, 1.0
	v_fmac_f32_e32 v5, v6, v5
	v_div_scale_f32 v6, vcc, v11, v1, v11
	v_mul_f32_e32 v7, v6, v5
	v_fma_f32 v8, -v4, v7, v6
	v_fmac_f32_e32 v7, v8, v5
	v_fma_f32 v4, -v4, v7, v6
	v_div_fmas_f32 v4, v4, v5, v7
	v_div_fixup_f32 v1, v4, v1, v11
	v_div_scale_f32 v4, s[10:11], v0, v0, v10
	v_rcp_f32_e32 v5, v4
	s_nop 0
	v_fma_f32 v6, -v4, v5, 1.0
	v_fmac_f32_e32 v5, v6, v5
	v_div_scale_f32 v6, vcc, v10, v0, v10
	v_mul_f32_e32 v7, v6, v5
	v_fma_f32 v8, -v4, v7, v6
	v_fmac_f32_e32 v7, v8, v5
	v_fma_f32 v4, -v4, v7, v6
	v_div_fmas_f32 v4, v4, v5, v7
	v_div_fixup_f32 v4, v4, v0, v10
	v_cvt_pk_bf16_f32 v0, v3, v2
	v_mul_f32_e32 v2, 0xbfb8aa3b, v12
	v_mul_f32_e32 v3, 0xbfb8aa3b, v13
	v_exp_f32_e32 v2, v2
	v_exp_f32_e32 v3, v3
	v_cvt_pk_bf16_f32 v1, v4, v1
	v_pk_add_f32 v[2:3], v[2:3], 1.0 op_sel_hi:[1,0]
	s_nop 0
	v_div_scale_f32 v4, s[10:11], v3, v3, v13
	v_rcp_f32_e32 v5, v4
	s_nop 0
	v_fma_f32 v6, -v4, v5, 1.0
	v_fmac_f32_e32 v5, v6, v5
	v_div_scale_f32 v6, vcc, v13, v3, v13
	v_mul_f32_e32 v7, v6, v5
	v_fma_f32 v8, -v4, v7, v6
	v_fmac_f32_e32 v7, v8, v5
	v_fma_f32 v4, -v4, v7, v6
	v_div_fmas_f32 v4, v4, v5, v7
	v_div_fixup_f32 v4, v4, v3, v13
	v_div_scale_f32 v3, s[10:11], v2, v2, v12
	v_rcp_f32_e32 v5, v3
	s_nop 0
	v_fma_f32 v6, -v3, v5, 1.0
	v_fmac_f32_e32 v5, v6, v5
	v_div_scale_f32 v6, vcc, v12, v2, v12
	v_mul_f32_e32 v7, v6, v5
	v_fma_f32 v8, -v3, v7, v6
	v_fmac_f32_e32 v7, v8, v5
	v_fma_f32 v3, -v3, v7, v6
	v_div_fmas_f32 v3, v3, v5, v7
	v_div_fixup_f32 v5, v3, v2, v12
	v_mul_f32_e32 v2, 0xbfb8aa3b, v14
	v_mul_f32_e32 v3, 0xbfb8aa3b, v15
	v_exp_f32_e32 v2, v2
	v_exp_f32_e32 v3, v3
	s_nop 0
	v_pk_add_f32 v[2:3], v[2:3], 1.0 op_sel_hi:[1,0]
	s_nop 0
	v_div_scale_f32 v6, s[10:11], v3, v3, v15
	v_rcp_f32_e32 v7, v6
	s_nop 0
	v_fma_f32 v8, -v6, v7, 1.0
	v_fmac_f32_e32 v7, v8, v7
	v_div_scale_f32 v8, vcc, v15, v3, v15
	v_mul_f32_e32 v9, v8, v7
	v_fma_f32 v10, -v6, v9, v8
	v_fmac_f32_e32 v9, v10, v7
	v_fma_f32 v6, -v6, v9, v8
	v_div_fmas_f32 v6, v6, v7, v9
	v_div_fixup_f32 v3, v6, v3, v15
	v_div_scale_f32 v6, s[10:11], v2, v2, v14
	v_rcp_f32_e32 v7, v6
	s_nop 0
	v_fma_f32 v8, -v6, v7, 1.0
	v_fmac_f32_e32 v7, v8, v7
	v_div_scale_f32 v8, vcc, v14, v2, v14
	v_mul_f32_e32 v9, v8, v7
	v_fma_f32 v10, -v6, v9, v8
	v_fmac_f32_e32 v9, v10, v7
	v_fma_f32 v6, -v6, v9, v8
	v_div_fmas_f32 v6, v6, v7, v9
	v_div_fixup_f32 v6, v6, v2, v14
	v_cvt_pk_bf16_f32 v2, v5, v4
	v_cvt_pk_bf16_f32 v3, v6, v3
	v_cmp_gt_i32_e32 vcc, 2, v101
	ds_write2_b64 v20, v[0:1], v[2:3] offset0:76 offset1:78
	s_waitcnt lgkmcnt(0)
	s_barrier
	s_and_saveexec_b64 s[10:11], vcc
	s_cbranch_execz .LBB0_370
	v_lshlrev_b32_e32 v16, 5, v101
	v_or_b32_e32 v0, v16, v100
	v_mul_u32_u24_e32 v2, 0x210, v100
	v_ashrrev_i32_e32 v1, 31, v0
	s_mov_b32 s13, 0xa200
	s_lshl_b64 s[8:9], s[8:9], 15
	v_lshlrev_b64 v[0:1], 9, v[0:1]
	v_add3_u32 v17, v2, v89, s13
	v_and_b32_e32 v2, 32, v198
	v_lshl_add_u64 v[0:1], s[8:9], 0, v[0:1]
	v_lshrrev_b32_e32 v2, 1, v2
	v_or_b32_e32 v0, v0, v2
	v_lshl_add_u64 v[18:19], s[52:53], 0, v[0:1]
	v_mov_b32_e32 v0, 0
	s_mov_b64 s[8:9], 0
	v_mov_b32_e32 v1, v0
	v_mov_b32_e32 v2, v0
	v_mov_b32_e32 v3, v0
	v_mov_b32_e32 v4, v0
	v_mov_b32_e32 v5, v0
	v_mov_b32_e32 v6, v0
	v_mov_b32_e32 v7, v0
	v_mov_b32_e32 v8, v0
	v_mov_b32_e32 v9, v0
	v_mov_b32_e32 v10, v0
	v_mov_b32_e32 v11, v0
	v_mov_b32_e32 v12, v0
	v_mov_b32_e32 v13, v0
	v_mov_b32_e32 v14, v0
	v_mov_b32_e32 v15, v0
.LBB0_756:
	v_lshl_add_u64 v[20:21], v[18:19], 0, s[8:9]
	s_mov_b32 s13, 0x17a0000
	v_add_co_u32_e32 v32, vcc, s13, v20
	s_add_u32 s8, s8, 0x80
	s_nop 0
	v_addc_co_u32_e32 v33, vcc, 0, v21, vcc
	global_load_dwordx4 v[20:23], v[32:33], off
	ds_read_b128 v[24:27], v17
	ds_read_b128 v[28:31], v17 offset:32
	s_addc_u32 s9, s9, 0
	s_cmpk_eq_i32 s8, 0x200
	s_waitcnt vmcnt(0) lgkmcnt(1)
	v_mfma_f32_32x32x16_bf16 v[0:15], v[20:23], v[24:27], v[0:15]
	global_load_dwordx4 v[20:23], v[32:33], off offset:32
	ds_read_b128 v[24:27], v17 offset:64
	s_waitcnt vmcnt(0) lgkmcnt(1)
	v_mfma_f32_32x32x16_bf16 v[0:15], v[20:23], v[28:31], v[0:15]
	global_load_dwordx4 v[20:23], v[32:33], off offset:64
	s_waitcnt vmcnt(0) lgkmcnt(0)
	v_mfma_f32_32x32x16_bf16 v[0:15], v[20:23], v[24:27], v[0:15]
	global_load_dwordx4 v[20:23], v[32:33], off offset:96
	ds_read_b128 v[24:27], v17 offset:96
	v_add_u32_e32 v17, 0x80, v17
	s_waitcnt vmcnt(0) lgkmcnt(0)
	v_mfma_f32_32x32x16_bf16 v[0:15], v[20:23], v[24:27], v[0:15]
	s_cbranch_scc0 .LBB0_756
	v_or_b32_e32 v17, s12, v100
	s_movk_i32 s8, 0x3f8
	v_cmp_gt_u32_e32 vcc, s8, v17
	s_and_saveexec_b64 s[8:9], vcc
	s_xor_b64 s[8:9], exec, s[8:9]
	s_cbranch_execz .LBB0_370
	s_and_b64 s[0:1], s[0:1], exec
	s_mov_b32 s0, 0xd1d0000
	v_mul_u32_u24_e32 v18, 0x409, v17
	s_cselect_b32 s0, s0, 0xd1f0000
	v_lshrrev_b32_e32 v18, 17, v18
	s_add_u32 s0, s52, s0
	s_addc_u32 s1, s53, 0
	v_add_lshl_u32 v192, v17, v18, 7
	v_lshl_add_u64 v[18:19], s[0:1], 0, v[192:193]
	v_ashrrev_i32_e32 v17, 31, v16
	v_lshl_add_u64 v[16:17], v[16:17], 1, v[18:19]
	v_lshlrev_b32_e32 v192, 3, v102
	v_lshl_add_u64 v[16:17], v[16:17], 0, v[192:193]
	v_cvt_pk_bf16_f32 v0, v0, v1
	v_cvt_pk_bf16_f32 v1, v2, v3
	global_store_dwordx2 v[16:17], v[0:1], off
	v_cvt_pk_bf16_f32 v0, v4, v5
	v_cvt_pk_bf16_f32 v1, v6, v7
	global_store_dwordx2 v[16:17], v[0:1], off offset:16
	v_cvt_pk_bf16_f32 v0, v8, v9
	v_cvt_pk_bf16_f32 v1, v10, v11
	global_store_dwordx2 v[16:17], v[0:1], off offset:32
	v_cvt_pk_bf16_f32 v0, v12, v13
	v_cvt_pk_bf16_f32 v1, v14, v15
	global_store_dwordx2 v[16:17], v[0:1], off offset:48
	s_branch .LBB0_370

.LBB0_815:
	s_ashr_i32 s8, s60, 31
	s_lshr_b32 s8, s8, 25
	s_add_i32 s8, s60, s8
	s_ashr_i32 s61, s8, 7
	s_and_b32 s8, s8, 0xffffff80
	v_mov_b32_e32 v152, v166
	s_sub_i32 s34, s60, s8
	s_lshl_b32 s8, s61, 3
	v_ashrrev_i32_e32 v168, 6, v152
	v_lshl_add_u32 v0, v168, 1, s8
	s_lshl_b32 s30, s34, 7
	v_ashrrev_i32_e32 v1, 31, v0
	v_lshlrev_b64 v[0:1], 16, v[0:1]
	s_ashr_i32 s31, s30, 31
	v_lshl_add_u64 v[16:17], s[20:21], 0, v[0:1]
	s_lshl_b64 s[8:9], s[30:31], 11
	v_lshlrev_b32_e32 v0, 4, v152
	v_ashrrev_i32_e32 v21, 3, v152
	s_add_u32 s8, s54, s8
	v_and_b32_e32 v20, 0x70, v0
	s_addc_u32 s9, s55, s9
	v_lshl_or_b32 v192, v21, 11, v20
	v_lshl_add_u64 v[158:159], s[8:9], 0, v[192:193]
	s_mov_b32 s8, 0x10000
	v_add_co_u32_e32 v160, vcc, s8, v158
	s_mov_b32 s9, 0x20000
	s_nop 0
	v_addc_co_u32_e32 v161, vcc, 0, v159, vcc
	v_add_co_u32_e32 v162, vcc, s9, v158
	s_barrier
	global_load_dwordx4 v[0:3], v[158:159], off
	global_load_dwordx4 v[4:7], v[160:161], off
	v_addc_co_u32_e32 v163, vcc, 0, v159, vcc
	s_mov_b32 s9, 0x30000
	v_add_co_u32_e32 v164, vcc, s9, v158
	global_load_dwordx4 v[8:11], v[162:163], off
	s_nop 0
	v_addc_co_u32_e32 v165, vcc, 0, v159, vcc
	global_load_dwordx4 v[12:15], v[164:165], off
	v_and_b32_e32 v153, 63, v152
	v_lshlrev_b32_e32 v192, 4, v153
	v_lshl_add_u64 v[156:157], v[16:17], 0, v[192:193]
	v_add_co_u32_e32 v22, vcc, s8, v156
	s_movk_i32 s10, 0x90
	s_nop 0
	v_addc_co_u32_e32 v23, vcc, 0, v157, vcc
	v_mad_u64_u32 v[154:155], s[8:9], v21, s10, v[20:21]
	global_load_dwordx4 v[16:19], v[156:157], off
	global_load_dwordx4 v[148:151], v[156:157], off offset:1024
	global_load_dwordx4 v[140:143], v[156:157], off offset:2048
	global_load_dwordx4 v[132:135], v[156:157], off offset:3072
	global_load_dwordx4 v[170:173], v[22:23], off
	global_load_dwordx4 v[144:147], v[22:23], off offset:1024
	global_load_dwordx4 v[136:139], v[22:23], off offset:2048
	global_load_dwordx4 v[128:131], v[22:23], off offset:3072
	v_bfe_u32 v169, v152, 5, 1
	v_and_b32_e32 v167, 31, v152
	s_waitcnt vmcnt(0) lgkmcnt(0)
	ds_write_b128 v154, v[0:3]
	ds_write_b128 v154, v[4:7] offset:4608
	ds_write_b128 v154, v[8:11] offset:9216
	ds_write_b128 v154, v[12:15] offset:13824
	global_load_dwordx4 v[174:177], v[158:159], off offset:128
	global_load_dwordx4 v[178:181], v[160:161], off offset:128
	global_load_dwordx4 v[182:185], v[162:163], off offset:128
	global_load_dwordx4 v[186:189], v[164:165], off offset:128
	v_lshlrev_b32_e32 v0, 4, v169
	v_mad_u32_u24 v155, v167, s10, v0
	s_waitcnt lgkmcnt(0)
	s_barrier
	ds_read_b128 v[0:3], v155 offset:4608
	ds_read_b128 v[4:7], v155 offset:9216
	ds_read_b128 v[8:11], v155 offset:13824
	ds_read_b128 v[12:15], v155
	ds_read_b128 v[198:201], v155 offset:32
	ds_read_b128 v[202:205], v155 offset:4640
	ds_read_b128 v[206:209], v155 offset:9248
	ds_read_b128 v[210:213], v155 offset:13856
	s_setprio 2
	s_movk_i32 s8, 0x1000
	v_add_co_u32_e32 v190, vcc, s8, v156
	s_mov_b32 s8, 0x11000
	s_nop 0
	v_addc_co_u32_e32 v191, vcc, 0, v157, vcc
	v_add_co_u32_e32 v242, vcc, s8, v156
	s_waitcnt lgkmcnt(0)
	v_mfma_f32_32x32x16_bf16 v[112:127], v[16:19], v[12:15], 0
	v_addc_co_u32_e32 v243, vcc, 0, v157, vcc
	global_load_dwordx4 v[214:217], v[190:191], off
	v_mfma_f32_32x32x16_bf16 v[80:95], v[16:19], v[0:3], 0
	v_mfma_f32_32x32x16_bf16 v[48:63], v[16:19], v[4:7], 0
	v_mfma_f32_32x32x16_bf16 v[16:31], v[16:19], v[8:11], 0
	v_mfma_f32_32x32x16_bf16 v[96:111], v[170:173], v[12:15], 0
	v_mfma_f32_32x32x16_bf16 v[64:79], v[170:173], v[0:3], 0
	v_mfma_f32_32x32x16_bf16 v[32:47], v[170:173], v[4:7], 0
	v_mfma_f32_32x32x16_bf16 v[0:15], v[170:173], v[8:11], 0
	global_load_dwordx4 v[170:173], v[242:243], off
	s_setprio 0
	ds_read_b128 v[218:221], v155 offset:64
	ds_read_b128 v[228:231], v155 offset:4672
	ds_read_b128 v[234:237], v155 offset:9280
	ds_read_b128 v[238:241], v155 offset:13888
	s_setprio 2
	v_mfma_f32_32x32x16_bf16 v[112:127], v[148:151], v[198:201], v[112:127]
	v_mfma_f32_32x32x16_bf16 v[80:95], v[148:151], v[202:205], v[80:95]
	v_mfma_f32_32x32x16_bf16 v[48:63], v[148:151], v[206:209], v[48:63]
	v_mfma_f32_32x32x16_bf16 v[16:31], v[148:151], v[210:213], v[16:31]
	v_mfma_f32_32x32x16_bf16 v[96:111], v[144:147], v[198:201], v[96:111]
	global_load_dwordx4 v[148:151], v[190:191], off offset:1024
	global_load_dwordx4 v[198:201], v[242:243], off offset:1024
	v_mfma_f32_32x32x16_bf16 v[64:79], v[144:147], v[202:205], v[64:79]
	v_mfma_f32_32x32x16_bf16 v[32:47], v[144:147], v[206:209], v[32:47]
	v_mfma_f32_32x32x16_bf16 v[0:15], v[144:147], v[210:213], v[0:15]
	s_setprio 0
	ds_read_b128 v[144:147], v155 offset:96
	ds_read_b128 v[202:205], v155 offset:4704
	ds_read_b128 v[206:209], v155 offset:9312
	ds_read_b128 v[210:213], v155 offset:13920
	s_setprio 2
	s_waitcnt lgkmcnt(0)
	v_mfma_f32_32x32x16_bf16 v[112:127], v[140:143], v[218:221], v[112:127]
	v_mfma_f32_32x32x16_bf16 v[80:95], v[140:143], v[228:231], v[80:95]
	v_mfma_f32_32x32x16_bf16 v[48:63], v[140:143], v[234:237], v[48:63]
	v_mfma_f32_32x32x16_bf16 v[16:31], v[140:143], v[238:241], v[16:31]
	v_mfma_f32_32x32x16_bf16 v[96:111], v[136:139], v[218:221], v[96:111]
	global_load_dwordx4 v[140:143], v[190:191], off offset:2048
	global_load_dwordx4 v[218:221], v[242:243], off offset:2048
	v_mfma_f32_32x32x16_bf16 v[64:79], v[136:139], v[228:231], v[64:79]
	v_mfma_f32_32x32x16_bf16 v[32:47], v[136:139], v[234:237], v[32:47]
	v_mfma_f32_32x32x16_bf16 v[0:15], v[136:139], v[238:241], v[0:15]
	s_setprio 0
	s_setprio 2
	v_mfma_f32_32x32x16_bf16 v[112:127], v[132:135], v[144:147], v[112:127]
	v_mfma_f32_32x32x16_bf16 v[80:95], v[132:135], v[202:205], v[80:95]
	v_mfma_f32_32x32x16_bf16 v[48:63], v[132:135], v[206:209], v[48:63]
	v_mfma_f32_32x32x16_bf16 v[16:31], v[132:135], v[210:213], v[16:31]
	global_load_dwordx4 v[132:135], v[190:191], off offset:3072
	global_load_dwordx4 v[136:139], v[242:243], off offset:3072
	v_mfma_f32_32x32x16_bf16 v[96:111], v[128:131], v[144:147], v[96:111]
	v_mfma_f32_32x32x16_bf16 v[64:79], v[128:131], v[202:205], v[64:79]
	v_mfma_f32_32x32x16_bf16 v[32:47], v[128:131], v[206:209], v[32:47]
	v_mfma_f32_32x32x16_bf16 v[0:15], v[128:131], v[210:213], v[0:15]
	s_setprio 0
	s_waitcnt vmcnt(0)
	ds_write_b128 v154, v[174:177] offset:18432
	ds_write_b128 v154, v[178:181] offset:23040
	ds_write_b128 v154, v[182:185] offset:27648
	ds_write_b128 v154, v[186:189] offset:32256
	global_load_dwordx4 v[128:131], v[158:159], off offset:256
	global_load_dwordx4 v[144:147], v[160:161], off offset:256
	global_load_dwordx4 v[174:177], v[162:163], off offset:256
	global_load_dwordx4 v[178:181], v[164:165], off offset:256
	s_waitcnt lgkmcnt(0)
	s_barrier
	ds_read_b128 v[182:185], v155 offset:18432
	ds_read_b128 v[186:189], v155 offset:18464
	ds_read_b128 v[202:205], v155 offset:23040
	ds_read_b128 v[206:209], v155 offset:23072
	ds_read_b128 v[210:213], v155 offset:27648
	ds_read_b128 v[228:231], v155 offset:27680
	ds_read_b128 v[234:237], v155 offset:32256
	ds_read_b128 v[238:241], v155 offset:32288
	s_setprio 2
	s_movk_i32 s8, 0x2000
	v_add_co_u32_e32 v190, vcc, s8, v156
	s_mov_b32 s8, 0x12000
	s_nop 0
	v_addc_co_u32_e32 v191, vcc, 0, v157, vcc
	v_add_co_u32_e32 v242, vcc, s8, v156
	s_waitcnt lgkmcnt(0)
	v_mfma_f32_32x32x16_bf16 v[112:127], v[214:217], v[182:185], v[112:127]
	v_addc_co_u32_e32 v243, vcc, 0, v157, vcc
	v_mfma_f32_32x32x16_bf16 v[80:95], v[214:217], v[202:205], v[80:95]
	v_mfma_f32_32x32x16_bf16 v[96:111], v[170:173], v[182:185], v[96:111]
	v_mfma_f32_32x32x16_bf16 v[64:79], v[170:173], v[202:205], v[64:79]
	global_load_dwordx4 v[182:185], v[190:191], off
	global_load_dwordx4 v[202:205], v[242:243], off
	v_mfma_f32_32x32x16_bf16 v[48:63], v[214:217], v[210:213], v[48:63]
	v_mfma_f32_32x32x16_bf16 v[16:31], v[214:217], v[234:237], v[16:31]
	v_mfma_f32_32x32x16_bf16 v[32:47], v[170:173], v[210:213], v[32:47]
	v_mfma_f32_32x32x16_bf16 v[0:15], v[170:173], v[234:237], v[0:15]
	s_setprio 0
	ds_read_b128 v[170:173], v155 offset:18496
	ds_read_b128 v[210:213], v155 offset:23104
	ds_read_b128 v[214:217], v155 offset:27712
	ds_read_b128 v[234:237], v155 offset:32320
	s_setprio 2
	v_mfma_f32_32x32x16_bf16 v[112:127], v[148:151], v[186:189], v[112:127]
	v_mfma_f32_32x32x16_bf16 v[80:95], v[148:151], v[206:209], v[80:95]
	v_mfma_f32_32x32x16_bf16 v[48:63], v[148:151], v[228:231], v[48:63]
	v_mfma_f32_32x32x16_bf16 v[16:31], v[148:151], v[238:241], v[16:31]
	v_mfma_f32_32x32x16_bf16 v[96:111], v[198:201], v[186:189], v[96:111]
	global_load_dwordx4 v[148:151], v[190:191], off offset:1024
	global_load_dwordx4 v[186:189], v[242:243], off offset:1024
	v_mfma_f32_32x32x16_bf16 v[64:79], v[198:201], v[206:209], v[64:79]
	v_mfma_f32_32x32x16_bf16 v[32:47], v[198:201], v[228:231], v[32:47]
	v_mfma_f32_32x32x16_bf16 v[0:15], v[198:201], v[238:241], v[0:15]
	s_setprio 0
	ds_read_b128 v[198:201], v155 offset:18528
	ds_read_b128 v[206:209], v155 offset:23136
	ds_read_b128 v[228:231], v155 offset:27744
	ds_read_b128 v[238:241], v155 offset:32352
	s_setprio 2
	s_waitcnt lgkmcnt(0)
	v_mfma_f32_32x32x16_bf16 v[112:127], v[140:143], v[170:173], v[112:127]
	v_mfma_f32_32x32x16_bf16 v[80:95], v[140:143], v[210:213], v[80:95]
	v_mfma_f32_32x32x16_bf16 v[48:63], v[140:143], v[214:217], v[48:63]
	v_mfma_f32_32x32x16_bf16 v[16:31], v[140:143], v[234:237], v[16:31]
	v_mfma_f32_32x32x16_bf16 v[96:111], v[218:221], v[170:173], v[96:111]
	global_load_dwordx4 v[140:143], v[190:191], off offset:2048
	global_load_dwordx4 v[170:173], v[242:243], off offset:2048
	v_mfma_f32_32x32x16_bf16 v[64:79], v[218:221], v[210:213], v[64:79]
	v_mfma_f32_32x32x16_bf16 v[32:47], v[218:221], v[214:217], v[32:47]
	v_mfma_f32_32x32x16_bf16 v[0:15], v[218:221], v[234:237], v[0:15]
	s_setprio 0
	s_setprio 2
	v_mfma_f32_32x32x16_bf16 v[112:127], v[132:135], v[198:201], v[112:127]
	v_mfma_f32_32x32x16_bf16 v[80:95], v[132:135], v[206:209], v[80:95]
	v_mfma_f32_32x32x16_bf16 v[48:63], v[132:135], v[228:231], v[48:63]
	v_mfma_f32_32x32x16_bf16 v[16:31], v[132:135], v[238:241], v[16:31]
	v_mfma_f32_32x32x16_bf16 v[96:111], v[136:139], v[198:201], v[96:111]
	global_load_dwordx4 v[132:135], v[190:191], off offset:3072
	global_load_dwordx4 v[198:201], v[242:243], off offset:3072
	v_mfma_f32_32x32x16_bf16 v[64:79], v[136:139], v[206:209], v[64:79]
	v_mfma_f32_32x32x16_bf16 v[32:47], v[136:139], v[228:231], v[32:47]
	v_mfma_f32_32x32x16_bf16 v[0:15], v[136:139], v[238:241], v[0:15]
	s_setprio 0
	s_waitcnt vmcnt(0)
	ds_write_b128 v154, v[128:131]
	ds_write_b128 v154, v[144:147] offset:4608
	ds_write_b128 v154, v[174:177] offset:9216
	ds_write_b128 v154, v[178:181] offset:13824
	global_load_dwordx4 v[128:131], v[164:165], off offset:384
	global_load_dwordx4 v[136:139], v[162:163], off offset:384
	global_load_dwordx4 v[144:147], v[160:161], off offset:384
	global_load_dwordx4 v[174:177], v[158:159], off offset:384
	s_waitcnt lgkmcnt(0)
	s_barrier
	ds_read_b128 v[178:181], v155
	ds_read_b128 v[206:209], v155 offset:32
	ds_read_b128 v[210:213], v155 offset:4608
	ds_read_b128 v[214:217], v155 offset:4640
	ds_read_b128 v[218:221], v155 offset:9216
	ds_read_b128 v[228:231], v155 offset:9248
	ds_read_b128 v[234:237], v155 offset:13824
	ds_read_b128 v[238:241], v155 offset:13856
	s_setprio 2
	s_movk_i32 s8, 0x3000
	v_add_co_u32_e32 v190, vcc, s8, v156
	s_mov_b32 s8, 0x13000
	s_nop 0
	v_addc_co_u32_e32 v191, vcc, 0, v157, vcc
	v_add_co_u32_e32 v242, vcc, s8, v156
	s_waitcnt lgkmcnt(0)
	v_mfma_f32_32x32x16_bf16 v[112:127], v[182:185], v[178:181], v[112:127]
	v_addc_co_u32_e32 v243, vcc, 0, v157, vcc
	v_mfma_f32_32x32x16_bf16 v[80:95], v[182:185], v[210:213], v[80:95]
	v_mfma_f32_32x32x16_bf16 v[48:63], v[182:185], v[218:221], v[48:63]
	v_mfma_f32_32x32x16_bf16 v[16:31], v[182:185], v[234:237], v[16:31]
	v_mfma_f32_32x32x16_bf16 v[96:111], v[202:205], v[178:181], v[96:111]
	global_load_dwordx4 v[178:181], v[190:191], off
	global_load_dwordx4 v[182:185], v[242:243], off
	v_mfma_f32_32x32x16_bf16 v[64:79], v[202:205], v[210:213], v[64:79]
	v_mfma_f32_32x32x16_bf16 v[32:47], v[202:205], v[218:221], v[32:47]
	v_mfma_f32_32x32x16_bf16 v[0:15], v[202:205], v[234:237], v[0:15]
	s_setprio 0
	ds_read_b128 v[202:205], v155 offset:64
	ds_read_b128 v[210:213], v155 offset:4672
	ds_read_b128 v[218:221], v155 offset:9280
	ds_read_b128 v[234:237], v155 offset:13888
	s_setprio 2
	v_mfma_f32_32x32x16_bf16 v[112:127], v[148:151], v[206:209], v[112:127]
	v_mfma_f32_32x32x16_bf16 v[80:95], v[148:151], v[214:217], v[80:95]
	v_mfma_f32_32x32x16_bf16 v[48:63], v[148:151], v[228:231], v[48:63]
	v_mfma_f32_32x32x16_bf16 v[16:31], v[148:151], v[238:241], v[16:31]
	v_mfma_f32_32x32x16_bf16 v[96:111], v[186:189], v[206:209], v[96:111]
	global_load_dwordx4 v[148:151], v[190:191], off offset:1024
	global_load_dwordx4 v[206:209], v[242:243], off offset:1024
	v_mfma_f32_32x32x16_bf16 v[64:79], v[186:189], v[214:217], v[64:79]
	v_mfma_f32_32x32x16_bf16 v[32:47], v[186:189], v[228:231], v[32:47]
	v_mfma_f32_32x32x16_bf16 v[0:15], v[186:189], v[238:241], v[0:15]
	s_setprio 0
	ds_read_b128 v[186:189], v155 offset:96
	ds_read_b128 v[214:217], v155 offset:4704
	ds_read_b128 v[228:231], v155 offset:9312
	ds_read_b128 v[238:241], v155 offset:13920
	s_setprio 2
	s_waitcnt lgkmcnt(0)
	v_mfma_f32_32x32x16_bf16 v[112:127], v[140:143], v[202:205], v[112:127]
	v_mfma_f32_32x32x16_bf16 v[80:95], v[140:143], v[210:213], v[80:95]
	v_mfma_f32_32x32x16_bf16 v[48:63], v[140:143], v[218:221], v[48:63]
	v_mfma_f32_32x32x16_bf16 v[16:31], v[140:143], v[234:237], v[16:31]
	v_mfma_f32_32x32x16_bf16 v[96:111], v[170:173], v[202:205], v[96:111]
	global_load_dwordx4 v[140:143], v[190:191], off offset:2048
	global_load_dwordx4 v[202:205], v[242:243], off offset:2048
	v_mfma_f32_32x32x16_bf16 v[64:79], v[170:173], v[210:213], v[64:79]
	v_mfma_f32_32x32x16_bf16 v[32:47], v[170:173], v[218:221], v[32:47]
	v_mfma_f32_32x32x16_bf16 v[0:15], v[170:173], v[234:237], v[0:15]
	s_setprio 0
	s_setprio 2
	v_mfma_f32_32x32x16_bf16 v[112:127], v[132:135], v[186:189], v[112:127]
	v_mfma_f32_32x32x16_bf16 v[80:95], v[132:135], v[214:217], v[80:95]
	v_mfma_f32_32x32x16_bf16 v[48:63], v[132:135], v[228:231], v[48:63]
	v_mfma_f32_32x32x16_bf16 v[16:31], v[132:135], v[238:241], v[16:31]
	global_load_dwordx4 v[132:135], v[190:191], off offset:3072
	global_load_dwordx4 v[170:173], v[242:243], off offset:3072
	v_mfma_f32_32x32x16_bf16 v[96:111], v[198:201], v[186:189], v[96:111]
	v_mfma_f32_32x32x16_bf16 v[64:79], v[198:201], v[214:217], v[64:79]
	v_mfma_f32_32x32x16_bf16 v[32:47], v[198:201], v[228:231], v[32:47]
	v_mfma_f32_32x32x16_bf16 v[0:15], v[198:201], v[238:241], v[0:15]
	s_setprio 0
	s_waitcnt vmcnt(0)
	ds_write_b128 v154, v[174:177] offset:18432
	ds_write_b128 v154, v[144:147] offset:23040
	ds_write_b128 v154, v[136:139] offset:27648
	ds_write_b128 v154, v[128:131] offset:32256
	global_load_dwordx4 v[128:131], v[158:159], off offset:512
	global_load_dwordx4 v[136:139], v[160:161], off offset:512
	global_load_dwordx4 v[144:147], v[162:163], off offset:512
	global_load_dwordx4 v[174:177], v[164:165], off offset:512
	s_waitcnt lgkmcnt(0)
	s_barrier
	ds_read_b128 v[186:189], v155 offset:18432
	ds_read_b128 v[198:201], v155 offset:18464
	ds_read_b128 v[210:213], v155 offset:23040
	ds_read_b128 v[214:217], v155 offset:23072
	ds_read_b128 v[218:221], v155 offset:27648
	ds_read_b128 v[228:231], v155 offset:27680
	ds_read_b128 v[234:237], v155 offset:32256
	ds_read_b128 v[238:241], v155 offset:32288
	s_setprio 2
	s_movk_i32 s8, 0x4000
	v_add_co_u32_e32 v190, vcc, s8, v156
	s_mov_b32 s8, 0x14000
	s_nop 0
	v_addc_co_u32_e32 v191, vcc, 0, v157, vcc
	v_add_co_u32_e32 v242, vcc, s8, v156
	s_waitcnt lgkmcnt(0)
	v_mfma_f32_32x32x16_bf16 v[112:127], v[178:181], v[186:189], v[112:127]
	v_addc_co_u32_e32 v243, vcc, 0, v157, vcc
	v_mfma_f32_32x32x16_bf16 v[80:95], v[178:181], v[210:213], v[80:95]
	v_mfma_f32_32x32x16_bf16 v[48:63], v[178:181], v[218:221], v[48:63]
	v_mfma_f32_32x32x16_bf16 v[16:31], v[178:181], v[234:237], v[16:31]
	v_mfma_f32_32x32x16_bf16 v[96:111], v[182:185], v[186:189], v[96:111]
	global_load_dwordx4 v[178:181], v[190:191], off
	global_load_dwordx4 v[186:189], v[242:243], off
	v_mfma_f32_32x32x16_bf16 v[64:79], v[182:185], v[210:213], v[64:79]
	v_mfma_f32_32x32x16_bf16 v[32:47], v[182:185], v[218:221], v[32:47]
	v_mfma_f32_32x32x16_bf16 v[0:15], v[182:185], v[234:237], v[0:15]
	s_setprio 0
	ds_read_b128 v[182:185], v155 offset:18496
	ds_read_b128 v[210:213], v155 offset:23104
	ds_read_b128 v[218:221], v155 offset:27712
	ds_read_b128 v[234:237], v155 offset:32320
	s_setprio 2
	v_mfma_f32_32x32x16_bf16 v[112:127], v[148:151], v[198:201], v[112:127]
	v_mfma_f32_32x32x16_bf16 v[80:95], v[148:151], v[214:217], v[80:95]
	v_mfma_f32_32x32x16_bf16 v[48:63], v[148:151], v[228:231], v[48:63]
	v_mfma_f32_32x32x16_bf16 v[16:31], v[148:151], v[238:241], v[16:31]
	v_mfma_f32_32x32x16_bf16 v[96:111], v[206:209], v[198:201], v[96:111]
	global_load_dwordx4 v[148:151], v[190:191], off offset:1024
	global_load_dwordx4 v[198:201], v[242:243], off offset:1024
	v_mfma_f32_32x32x16_bf16 v[64:79], v[206:209], v[214:217], v[64:79]
	v_mfma_f32_32x32x16_bf16 v[32:47], v[206:209], v[228:231], v[32:47]
	v_mfma_f32_32x32x16_bf16 v[0:15], v[206:209], v[238:241], v[0:15]
	s_setprio 0
	ds_read_b128 v[206:209], v155 offset:18528
	ds_read_b128 v[214:217], v155 offset:23136
	ds_read_b128 v[228:231], v155 offset:27744
	ds_read_b128 v[238:241], v155 offset:32352
	s_setprio 2
	s_waitcnt lgkmcnt(0)
	v_mfma_f32_32x32x16_bf16 v[112:127], v[140:143], v[182:185], v[112:127]
	v_mfma_f32_32x32x16_bf16 v[80:95], v[140:143], v[210:213], v[80:95]
	v_mfma_f32_32x32x16_bf16 v[48:63], v[140:143], v[218:221], v[48:63]
	v_mfma_f32_32x32x16_bf16 v[16:31], v[140:143], v[234:237], v[16:31]
	v_mfma_f32_32x32x16_bf16 v[96:111], v[202:205], v[182:185], v[96:111]
	global_load_dwordx4 v[140:143], v[190:191], off offset:2048
	global_load_dwordx4 v[182:185], v[242:243], off offset:2048
	v_mfma_f32_32x32x16_bf16 v[64:79], v[202:205], v[210:213], v[64:79]
	v_mfma_f32_32x32x16_bf16 v[32:47], v[202:205], v[218:221], v[32:47]
	v_mfma_f32_32x32x16_bf16 v[0:15], v[202:205], v[234:237], v[0:15]
	s_setprio 0
	s_setprio 2
	v_mfma_f32_32x32x16_bf16 v[112:127], v[132:135], v[206:209], v[112:127]
	v_mfma_f32_32x32x16_bf16 v[80:95], v[132:135], v[214:217], v[80:95]
	v_mfma_f32_32x32x16_bf16 v[48:63], v[132:135], v[228:231], v[48:63]
	v_mfma_f32_32x32x16_bf16 v[16:31], v[132:135], v[238:241], v[16:31]
	global_load_dwordx4 v[132:135], v[190:191], off offset:3072
	global_load_dwordx4 v[202:205], v[242:243], off offset:3072
	v_mfma_f32_32x32x16_bf16 v[96:111], v[170:173], v[206:209], v[96:111]
	v_mfma_f32_32x32x16_bf16 v[64:79], v[170:173], v[214:217], v[64:79]
	v_mfma_f32_32x32x16_bf16 v[32:47], v[170:173], v[228:231], v[32:47]
	v_mfma_f32_32x32x16_bf16 v[0:15], v[170:173], v[238:241], v[0:15]
	s_setprio 0
	s_waitcnt vmcnt(0)
	ds_write_b128 v154, v[128:131]
	ds_write_b128 v154, v[136:139] offset:4608
	ds_write_b128 v154, v[144:147] offset:9216
	ds_write_b128 v154, v[174:177] offset:13824
	global_load_dwordx4 v[128:131], v[164:165], off offset:640
	global_load_dwordx4 v[136:139], v[162:163], off offset:640
	global_load_dwordx4 v[144:147], v[160:161], off offset:640
	global_load_dwordx4 v[170:173], v[158:159], off offset:640
	s_waitcnt lgkmcnt(0)
	s_barrier
	ds_read_b128 v[174:177], v155
	ds_read_b128 v[206:209], v155 offset:32
	ds_read_b128 v[210:213], v155 offset:4608
	ds_read_b128 v[214:217], v155 offset:4640
	ds_read_b128 v[218:221], v155 offset:9216
	ds_read_b128 v[228:231], v155 offset:9248
	ds_read_b128 v[234:237], v155 offset:13824
	ds_read_b128 v[238:241], v155 offset:13856
	s_setprio 2
	s_movk_i32 s8, 0x5000
	v_add_co_u32_e32 v190, vcc, s8, v156
	s_mov_b32 s8, 0x15000
	s_nop 0
	v_addc_co_u32_e32 v191, vcc, 0, v157, vcc
	v_add_co_u32_e32 v242, vcc, s8, v156
	s_waitcnt lgkmcnt(0)
	v_mfma_f32_32x32x16_bf16 v[112:127], v[178:181], v[174:177], v[112:127]
	v_addc_co_u32_e32 v243, vcc, 0, v157, vcc
	v_mfma_f32_32x32x16_bf16 v[80:95], v[178:181], v[210:213], v[80:95]
	v_mfma_f32_32x32x16_bf16 v[48:63], v[178:181], v[218:221], v[48:63]
	v_mfma_f32_32x32x16_bf16 v[16:31], v[178:181], v[234:237], v[16:31]
	v_mfma_f32_32x32x16_bf16 v[96:111], v[186:189], v[174:177], v[96:111]
	global_load_dwordx4 v[174:177], v[190:191], off
	global_load_dwordx4 v[178:181], v[242:243], off
	v_mfma_f32_32x32x16_bf16 v[64:79], v[186:189], v[210:213], v[64:79]
	v_mfma_f32_32x32x16_bf16 v[32:47], v[186:189], v[218:221], v[32:47]
	v_mfma_f32_32x32x16_bf16 v[0:15], v[186:189], v[234:237], v[0:15]
	s_setprio 0
	ds_read_b128 v[186:189], v155 offset:64
	ds_read_b128 v[210:213], v155 offset:4672
	ds_read_b128 v[218:221], v155 offset:9280
	ds_read_b128 v[234:237], v155 offset:13888
	s_setprio 2
	v_mfma_f32_32x32x16_bf16 v[112:127], v[148:151], v[206:209], v[112:127]
	v_mfma_f32_32x32x16_bf16 v[80:95], v[148:151], v[214:217], v[80:95]
	v_mfma_f32_32x32x16_bf16 v[48:63], v[148:151], v[228:231], v[48:63]
	v_mfma_f32_32x32x16_bf16 v[16:31], v[148:151], v[238:241], v[16:31]
	v_mfma_f32_32x32x16_bf16 v[96:111], v[198:201], v[206:209], v[96:111]
	global_load_dwordx4 v[148:151], v[190:191], off offset:1024
	global_load_dwordx4 v[206:209], v[242:243], off offset:1024
	v_mfma_f32_32x32x16_bf16 v[64:79], v[198:201], v[214:217], v[64:79]
	v_mfma_f32_32x32x16_bf16 v[32:47], v[198:201], v[228:231], v[32:47]
	v_mfma_f32_32x32x16_bf16 v[0:15], v[198:201], v[238:241], v[0:15]
	s_setprio 0
	ds_read_b128 v[198:201], v155 offset:96
	ds_read_b128 v[214:217], v155 offset:4704
	ds_read_b128 v[228:231], v155 offset:9312
	ds_read_b128 v[238:241], v155 offset:13920
	s_setprio 2
	s_waitcnt lgkmcnt(0)
	v_mfma_f32_32x32x16_bf16 v[112:127], v[140:143], v[186:189], v[112:127]
	v_mfma_f32_32x32x16_bf16 v[80:95], v[140:143], v[210:213], v[80:95]
	v_mfma_f32_32x32x16_bf16 v[48:63], v[140:143], v[218:221], v[48:63]
	v_mfma_f32_32x32x16_bf16 v[16:31], v[140:143], v[234:237], v[16:31]
	v_mfma_f32_32x32x16_bf16 v[96:111], v[182:185], v[186:189], v[96:111]
	global_load_dwordx4 v[140:143], v[190:191], off offset:2048
	global_load_dwordx4 v[186:189], v[242:243], off offset:2048
	v_mfma_f32_32x32x16_bf16 v[64:79], v[182:185], v[210:213], v[64:79]
	v_mfma_f32_32x32x16_bf16 v[32:47], v[182:185], v[218:221], v[32:47]
	v_mfma_f32_32x32x16_bf16 v[0:15], v[182:185], v[234:237], v[0:15]
	s_setprio 0
	s_setprio 2
	v_mfma_f32_32x32x16_bf16 v[112:127], v[132:135], v[198:201], v[112:127]
	v_mfma_f32_32x32x16_bf16 v[80:95], v[132:135], v[214:217], v[80:95]
	v_mfma_f32_32x32x16_bf16 v[48:63], v[132:135], v[228:231], v[48:63]
	v_mfma_f32_32x32x16_bf16 v[16:31], v[132:135], v[238:241], v[16:31]
	global_load_dwordx4 v[132:135], v[190:191], off offset:3072
	global_load_dwordx4 v[182:185], v[242:243], off offset:3072
	v_mfma_f32_32x32x16_bf16 v[96:111], v[202:205], v[198:201], v[96:111]
	v_mfma_f32_32x32x16_bf16 v[64:79], v[202:205], v[214:217], v[64:79]
	v_mfma_f32_32x32x16_bf16 v[32:47], v[202:205], v[228:231], v[32:47]
	v_mfma_f32_32x32x16_bf16 v[0:15], v[202:205], v[238:241], v[0:15]
	s_setprio 0
	s_waitcnt vmcnt(0)
	ds_write_b128 v154, v[170:173] offset:18432
	ds_write_b128 v154, v[144:147] offset:23040
	ds_write_b128 v154, v[136:139] offset:27648
	ds_write_b128 v154, v[128:131] offset:32256
	global_load_dwordx4 v[128:131], v[158:159], off offset:768
	global_load_dwordx4 v[136:139], v[160:161], off offset:768
	global_load_dwordx4 v[144:147], v[162:163], off offset:768
	global_load_dwordx4 v[170:173], v[164:165], off offset:768
	s_waitcnt lgkmcnt(0)
	s_barrier
	ds_read_b128 v[198:201], v155 offset:18432
	ds_read_b128 v[202:205], v155 offset:18464
	ds_read_b128 v[210:213], v155 offset:23040
	ds_read_b128 v[214:217], v155 offset:23072
	ds_read_b128 v[218:221], v155 offset:27648
	ds_read_b128 v[228:231], v155 offset:27680
	ds_read_b128 v[234:237], v155 offset:32256
	ds_read_b128 v[238:241], v155 offset:32288
	s_setprio 2
	s_movk_i32 s8, 0x6000
	v_add_co_u32_e32 v190, vcc, s8, v156
	s_mov_b32 s8, 0x16000
	s_nop 0
	v_addc_co_u32_e32 v191, vcc, 0, v157, vcc
	v_add_co_u32_e32 v242, vcc, s8, v156
	s_waitcnt lgkmcnt(0)
	v_mfma_f32_32x32x16_bf16 v[112:127], v[174:177], v[198:201], v[112:127]
	v_addc_co_u32_e32 v243, vcc, 0, v157, vcc
	v_mfma_f32_32x32x16_bf16 v[80:95], v[174:177], v[210:213], v[80:95]
	v_mfma_f32_32x32x16_bf16 v[48:63], v[174:177], v[218:221], v[48:63]
	v_mfma_f32_32x32x16_bf16 v[16:31], v[174:177], v[234:237], v[16:31]
	v_mfma_f32_32x32x16_bf16 v[96:111], v[178:181], v[198:201], v[96:111]
	global_load_dwordx4 v[174:177], v[190:191], off
	global_load_dwordx4 v[198:201], v[242:243], off
	v_mfma_f32_32x32x16_bf16 v[64:79], v[178:181], v[210:213], v[64:79]
	v_mfma_f32_32x32x16_bf16 v[32:47], v[178:181], v[218:221], v[32:47]
	v_mfma_f32_32x32x16_bf16 v[0:15], v[178:181], v[234:237], v[0:15]
	s_setprio 0
	ds_read_b128 v[178:181], v155 offset:18496
	ds_read_b128 v[210:213], v155 offset:23104
	ds_read_b128 v[218:221], v155 offset:27712
	ds_read_b128 v[234:237], v155 offset:32320
	s_setprio 2
	v_mfma_f32_32x32x16_bf16 v[112:127], v[148:151], v[202:205], v[112:127]
	v_mfma_f32_32x32x16_bf16 v[80:95], v[148:151], v[214:217], v[80:95]
	v_mfma_f32_32x32x16_bf16 v[48:63], v[148:151], v[228:231], v[48:63]
	v_mfma_f32_32x32x16_bf16 v[16:31], v[148:151], v[238:241], v[16:31]
	v_mfma_f32_32x32x16_bf16 v[96:111], v[206:209], v[202:205], v[96:111]
	global_load_dwordx4 v[148:151], v[190:191], off offset:1024
	global_load_dwordx4 v[202:205], v[242:243], off offset:1024
	v_mfma_f32_32x32x16_bf16 v[64:79], v[206:209], v[214:217], v[64:79]
	v_mfma_f32_32x32x16_bf16 v[32:47], v[206:209], v[228:231], v[32:47]
	v_mfma_f32_32x32x16_bf16 v[0:15], v[206:209], v[238:241], v[0:15]
	s_setprio 0
	ds_read_b128 v[206:209], v155 offset:18528
	ds_read_b128 v[214:217], v155 offset:23136
	ds_read_b128 v[228:231], v155 offset:27744
	ds_read_b128 v[238:241], v155 offset:32352
	s_setprio 2
	s_waitcnt lgkmcnt(0)
	v_mfma_f32_32x32x16_bf16 v[112:127], v[140:143], v[178:181], v[112:127]
	v_mfma_f32_32x32x16_bf16 v[80:95], v[140:143], v[210:213], v[80:95]
	v_mfma_f32_32x32x16_bf16 v[48:63], v[140:143], v[218:221], v[48:63]
	v_mfma_f32_32x32x16_bf16 v[16:31], v[140:143], v[234:237], v[16:31]
	v_mfma_f32_32x32x16_bf16 v[96:111], v[186:189], v[178:181], v[96:111]
	global_load_dwordx4 v[140:143], v[190:191], off offset:2048
	global_load_dwordx4 v[178:181], v[242:243], off offset:2048
	v_mfma_f32_32x32x16_bf16 v[64:79], v[186:189], v[210:213], v[64:79]
	v_mfma_f32_32x32x16_bf16 v[32:47], v[186:189], v[218:221], v[32:47]
	v_mfma_f32_32x32x16_bf16 v[0:15], v[186:189], v[234:237], v[0:15]
	s_setprio 0
	s_setprio 2
	v_mfma_f32_32x32x16_bf16 v[112:127], v[132:135], v[206:209], v[112:127]
	v_mfma_f32_32x32x16_bf16 v[80:95], v[132:135], v[214:217], v[80:95]
	v_mfma_f32_32x32x16_bf16 v[48:63], v[132:135], v[228:231], v[48:63]
	v_mfma_f32_32x32x16_bf16 v[16:31], v[132:135], v[238:241], v[16:31]
	global_load_dwordx4 v[132:135], v[190:191], off offset:3072
	global_load_dwordx4 v[186:189], v[242:243], off offset:3072
	v_mfma_f32_32x32x16_bf16 v[96:111], v[182:185], v[206:209], v[96:111]
	v_mfma_f32_32x32x16_bf16 v[64:79], v[182:185], v[214:217], v[64:79]
	v_mfma_f32_32x32x16_bf16 v[32:47], v[182:185], v[228:231], v[32:47]
	v_mfma_f32_32x32x16_bf16 v[0:15], v[182:185], v[238:241], v[0:15]
	s_setprio 0
	s_waitcnt vmcnt(0)
	ds_write_b128 v154, v[128:131]
	ds_write_b128 v154, v[136:139] offset:4608
	ds_write_b128 v154, v[144:147] offset:9216
	ds_write_b128 v154, v[170:173] offset:13824
	global_load_dwordx4 v[128:131], v[164:165], off offset:896
	global_load_dwordx4 v[136:139], v[162:163], off offset:896
	global_load_dwordx4 v[144:147], v[160:161], off offset:896
	global_load_dwordx4 v[170:173], v[158:159], off offset:896
	s_waitcnt lgkmcnt(0)
	s_barrier
	ds_read_b128 v[182:185], v155
	ds_read_b128 v[206:209], v155 offset:32
	ds_read_b128 v[210:213], v155 offset:4608
	ds_read_b128 v[214:217], v155 offset:4640
	ds_read_b128 v[218:221], v155 offset:9216
	ds_read_b128 v[228:231], v155 offset:9248
	ds_read_b128 v[234:237], v155 offset:13824
	ds_read_b128 v[238:241], v155 offset:13856
	s_setprio 2
	s_movk_i32 s8, 0x7000
	v_add_co_u32_e32 v190, vcc, s8, v156
	s_mov_b32 s8, 0x17000
	s_nop 0
	v_addc_co_u32_e32 v191, vcc, 0, v157, vcc
	v_add_co_u32_e32 v242, vcc, s8, v156
	s_waitcnt lgkmcnt(0)
	v_mfma_f32_32x32x16_bf16 v[112:127], v[174:177], v[182:185], v[112:127]
	v_addc_co_u32_e32 v243, vcc, 0, v157, vcc
	v_mfma_f32_32x32x16_bf16 v[80:95], v[174:177], v[210:213], v[80:95]
	v_mfma_f32_32x32x16_bf16 v[48:63], v[174:177], v[218:221], v[48:63]
	v_mfma_f32_32x32x16_bf16 v[16:31], v[174:177], v[234:237], v[16:31]
	v_mfma_f32_32x32x16_bf16 v[96:111], v[198:201], v[182:185], v[96:111]
	global_load_dwordx4 v[174:177], v[190:191], off
	global_load_dwordx4 v[182:185], v[242:243], off
	v_mfma_f32_32x32x16_bf16 v[64:79], v[198:201], v[210:213], v[64:79]
	v_mfma_f32_32x32x16_bf16 v[32:47], v[198:201], v[218:221], v[32:47]
	v_mfma_f32_32x32x16_bf16 v[0:15], v[198:201], v[234:237], v[0:15]
	s_setprio 0
	ds_read_b128 v[198:201], v155 offset:64
	ds_read_b128 v[210:213], v155 offset:4672
	ds_read_b128 v[218:221], v155 offset:9280
	ds_read_b128 v[234:237], v155 offset:13888
	s_setprio 2
	v_mfma_f32_32x32x16_bf16 v[112:127], v[148:151], v[206:209], v[112:127]
	v_mfma_f32_32x32x16_bf16 v[80:95], v[148:151], v[214:217], v[80:95]
	v_mfma_f32_32x32x16_bf16 v[48:63], v[148:151], v[228:231], v[48:63]
	v_mfma_f32_32x32x16_bf16 v[16:31], v[148:151], v[238:241], v[16:31]
	v_mfma_f32_32x32x16_bf16 v[96:111], v[202:205], v[206:209], v[96:111]
	global_load_dwordx4 v[148:151], v[190:191], off offset:1024
	global_load_dwordx4 v[206:209], v[242:243], off offset:1024
	v_mfma_f32_32x32x16_bf16 v[64:79], v[202:205], v[214:217], v[64:79]
	v_mfma_f32_32x32x16_bf16 v[32:47], v[202:205], v[228:231], v[32:47]
	v_mfma_f32_32x32x16_bf16 v[0:15], v[202:205], v[238:241], v[0:15]
	s_setprio 0
	ds_read_b128 v[202:205], v155 offset:96
	ds_read_b128 v[214:217], v155 offset:4704
	ds_read_b128 v[228:231], v155 offset:9312
	ds_read_b128 v[238:241], v155 offset:13920
	s_setprio 2
	s_waitcnt lgkmcnt(0)
	v_mfma_f32_32x32x16_bf16 v[112:127], v[140:143], v[198:201], v[112:127]
	v_mfma_f32_32x32x16_bf16 v[80:95], v[140:143], v[210:213], v[80:95]
	v_mfma_f32_32x32x16_bf16 v[48:63], v[140:143], v[218:221], v[48:63]
	v_mfma_f32_32x32x16_bf16 v[16:31], v[140:143], v[234:237], v[16:31]
	v_mfma_f32_32x32x16_bf16 v[96:111], v[178:181], v[198:201], v[96:111]
	global_load_dwordx4 v[140:143], v[190:191], off offset:2048
	global_load_dwordx4 v[198:201], v[242:243], off offset:2048
	v_mfma_f32_32x32x16_bf16 v[64:79], v[178:181], v[210:213], v[64:79]
	v_mfma_f32_32x32x16_bf16 v[32:47], v[178:181], v[218:221], v[32:47]
	v_mfma_f32_32x32x16_bf16 v[0:15], v[178:181], v[234:237], v[0:15]
	s_setprio 0
	s_setprio 2
	v_mfma_f32_32x32x16_bf16 v[112:127], v[132:135], v[202:205], v[112:127]
	v_mfma_f32_32x32x16_bf16 v[80:95], v[132:135], v[214:217], v[80:95]
	v_mfma_f32_32x32x16_bf16 v[48:63], v[132:135], v[228:231], v[48:63]
	v_mfma_f32_32x32x16_bf16 v[16:31], v[132:135], v[238:241], v[16:31]
	global_load_dwordx4 v[132:135], v[190:191], off offset:3072
	global_load_dwordx4 v[178:181], v[242:243], off offset:3072
	v_mfma_f32_32x32x16_bf16 v[96:111], v[186:189], v[202:205], v[96:111]
	v_mfma_f32_32x32x16_bf16 v[64:79], v[186:189], v[214:217], v[64:79]
	v_mfma_f32_32x32x16_bf16 v[32:47], v[186:189], v[228:231], v[32:47]
	v_mfma_f32_32x32x16_bf16 v[0:15], v[186:189], v[238:241], v[0:15]
	s_setprio 0
	s_waitcnt vmcnt(0)
	ds_write_b128 v154, v[170:173] offset:18432
	ds_write_b128 v154, v[144:147] offset:23040
	ds_write_b128 v154, v[136:139] offset:27648
	ds_write_b128 v154, v[128:131] offset:32256
	global_load_dwordx4 v[128:131], v[158:159], off offset:1024
	global_load_dwordx4 v[136:139], v[160:161], off offset:1024
	global_load_dwordx4 v[144:147], v[162:163], off offset:1024
	global_load_dwordx4 v[170:173], v[164:165], off offset:1024
	s_waitcnt lgkmcnt(0)
	s_barrier
	ds_read_b128 v[186:189], v155 offset:18432
	ds_read_b128 v[202:205], v155 offset:18464
	ds_read_b128 v[210:213], v155 offset:23040
	ds_read_b128 v[214:217], v155 offset:23072
	ds_read_b128 v[218:221], v155 offset:27648
	ds_read_b128 v[228:231], v155 offset:27680
	ds_read_b128 v[234:237], v155 offset:32256
	ds_read_b128 v[238:241], v155 offset:32288
	s_setprio 2
	s_mov_b32 s8, 0x8000
	v_add_co_u32_e32 v190, vcc, s8, v156
	s_mov_b32 s8, 0x18000
	s_nop 0
	v_addc_co_u32_e32 v191, vcc, 0, v157, vcc
	v_add_co_u32_e32 v242, vcc, s8, v156
	s_waitcnt lgkmcnt(0)
	v_mfma_f32_32x32x16_bf16 v[112:127], v[174:177], v[186:189], v[112:127]
	v_addc_co_u32_e32 v243, vcc, 0, v157, vcc
	v_mfma_f32_32x32x16_bf16 v[80:95], v[174:177], v[210:213], v[80:95]
	v_mfma_f32_32x32x16_bf16 v[48:63], v[174:177], v[218:221], v[48:63]
	v_mfma_f32_32x32x16_bf16 v[16:31], v[174:177], v[234:237], v[16:31]
	v_mfma_f32_32x32x16_bf16 v[96:111], v[182:185], v[186:189], v[96:111]
	global_load_dwordx4 v[174:177], v[190:191], off
	global_load_dwordx4 v[186:189], v[242:243], off
	v_mfma_f32_32x32x16_bf16 v[64:79], v[182:185], v[210:213], v[64:79]
	v_mfma_f32_32x32x16_bf16 v[32:47], v[182:185], v[218:221], v[32:47]
	v_mfma_f32_32x32x16_bf16 v[0:15], v[182:185], v[234:237], v[0:15]
	s_setprio 0
	ds_read_b128 v[182:185], v155 offset:18496
	ds_read_b128 v[210:213], v155 offset:23104
	ds_read_b128 v[218:221], v155 offset:27712
	ds_read_b128 v[234:237], v155 offset:32320
	s_setprio 2
	v_mfma_f32_32x32x16_bf16 v[112:127], v[148:151], v[202:205], v[112:127]
	v_mfma_f32_32x32x16_bf16 v[80:95], v[148:151], v[214:217], v[80:95]
	v_mfma_f32_32x32x16_bf16 v[48:63], v[148:151], v[228:231], v[48:63]
	v_mfma_f32_32x32x16_bf16 v[16:31], v[148:151], v[238:241], v[16:31]
	v_mfma_f32_32x32x16_bf16 v[96:111], v[206:209], v[202:205], v[96:111]
	global_load_dwordx4 v[148:151], v[190:191], off offset:1024
	global_load_dwordx4 v[202:205], v[242:243], off offset:1024
	v_mfma_f32_32x32x16_bf16 v[64:79], v[206:209], v[214:217], v[64:79]
	v_mfma_f32_32x32x16_bf16 v[32:47], v[206:209], v[228:231], v[32:47]
	v_mfma_f32_32x32x16_bf16 v[0:15], v[206:209], v[238:241], v[0:15]
	s_setprio 0
	ds_read_b128 v[206:209], v155 offset:18528
	ds_read_b128 v[214:217], v155 offset:23136
	ds_read_b128 v[228:231], v155 offset:27744
	ds_read_b128 v[238:241], v155 offset:32352
	s_setprio 2
	s_waitcnt lgkmcnt(0)
	v_mfma_f32_32x32x16_bf16 v[112:127], v[140:143], v[182:185], v[112:127]
	v_mfma_f32_32x32x16_bf16 v[80:95], v[140:143], v[210:213], v[80:95]
	v_mfma_f32_32x32x16_bf16 v[48:63], v[140:143], v[218:221], v[48:63]
	v_mfma_f32_32x32x16_bf16 v[16:31], v[140:143], v[234:237], v[16:31]
	v_mfma_f32_32x32x16_bf16 v[96:111], v[198:201], v[182:185], v[96:111]
	global_load_dwordx4 v[140:143], v[190:191], off offset:2048
	global_load_dwordx4 v[182:185], v[242:243], off offset:2048
	v_mfma_f32_32x32x16_bf16 v[64:79], v[198:201], v[210:213], v[64:79]
	v_mfma_f32_32x32x16_bf16 v[32:47], v[198:201], v[218:221], v[32:47]
	v_mfma_f32_32x32x16_bf16 v[0:15], v[198:201], v[234:237], v[0:15]
	s_setprio 0
	s_setprio 2
	v_mfma_f32_32x32x16_bf16 v[112:127], v[132:135], v[206:209], v[112:127]
	v_mfma_f32_32x32x16_bf16 v[80:95], v[132:135], v[214:217], v[80:95]
	v_mfma_f32_32x32x16_bf16 v[48:63], v[132:135], v[228:231], v[48:63]
	v_mfma_f32_32x32x16_bf16 v[16:31], v[132:135], v[238:241], v[16:31]
	global_load_dwordx4 v[132:135], v[190:191], off offset:3072
	global_load_dwordx4 v[198:201], v[242:243], off offset:3072
	v_mfma_f32_32x32x16_bf16 v[96:111], v[178:181], v[206:209], v[96:111]
	v_mfma_f32_32x32x16_bf16 v[64:79], v[178:181], v[214:217], v[64:79]
	v_mfma_f32_32x32x16_bf16 v[32:47], v[178:181], v[228:231], v[32:47]
	v_mfma_f32_32x32x16_bf16 v[0:15], v[178:181], v[238:241], v[0:15]
	s_setprio 0
	s_waitcnt vmcnt(0)
	ds_write_b128 v154, v[128:131]
	ds_write_b128 v154, v[136:139] offset:4608
	ds_write_b128 v154, v[144:147] offset:9216
	ds_write_b128 v154, v[170:173] offset:13824
	global_load_dwordx4 v[128:131], v[164:165], off offset:1152
	global_load_dwordx4 v[136:139], v[162:163], off offset:1152
	global_load_dwordx4 v[144:147], v[160:161], off offset:1152
	global_load_dwordx4 v[170:173], v[158:159], off offset:1152
	s_waitcnt lgkmcnt(0)
	s_barrier
	ds_read_b128 v[178:181], v155
	ds_read_b128 v[206:209], v155 offset:32
	ds_read_b128 v[210:213], v155 offset:4608
	ds_read_b128 v[214:217], v155 offset:4640
	ds_read_b128 v[218:221], v155 offset:9216
	ds_read_b128 v[228:231], v155 offset:9248
	ds_read_b128 v[234:237], v155 offset:13824
	ds_read_b128 v[238:241], v155 offset:13856
	s_setprio 2
	s_mov_b32 s8, 0x9000
	v_add_co_u32_e32 v190, vcc, s8, v156
	s_mov_b32 s8, 0x19000
	s_nop 0
	v_addc_co_u32_e32 v191, vcc, 0, v157, vcc
	v_add_co_u32_e32 v242, vcc, s8, v156
	s_waitcnt lgkmcnt(0)
	v_mfma_f32_32x32x16_bf16 v[112:127], v[174:177], v[178:181], v[112:127]
	v_addc_co_u32_e32 v243, vcc, 0, v157, vcc
	v_mfma_f32_32x32x16_bf16 v[80:95], v[174:177], v[210:213], v[80:95]
	v_mfma_f32_32x32x16_bf16 v[48:63], v[174:177], v[218:221], v[48:63]
	v_mfma_f32_32x32x16_bf16 v[16:31], v[174:177], v[234:237], v[16:31]
	v_mfma_f32_32x32x16_bf16 v[96:111], v[186:189], v[178:181], v[96:111]
	global_load_dwordx4 v[174:177], v[190:191], off
	global_load_dwordx4 v[178:181], v[242:243], off
	v_mfma_f32_32x32x16_bf16 v[64:79], v[186:189], v[210:213], v[64:79]
	v_mfma_f32_32x32x16_bf16 v[32:47], v[186:189], v[218:221], v[32:47]
	v_mfma_f32_32x32x16_bf16 v[0:15], v[186:189], v[234:237], v[0:15]
	s_setprio 0
	ds_read_b128 v[186:189], v155 offset:64
	ds_read_b128 v[210:213], v155 offset:4672
	ds_read_b128 v[218:221], v155 offset:9280
	ds_read_b128 v[234:237], v155 offset:13888
	s_setprio 2
	v_mfma_f32_32x32x16_bf16 v[112:127], v[148:151], v[206:209], v[112:127]
	v_mfma_f32_32x32x16_bf16 v[80:95], v[148:151], v[214:217], v[80:95]
	v_mfma_f32_32x32x16_bf16 v[48:63], v[148:151], v[228:231], v[48:63]
	v_mfma_f32_32x32x16_bf16 v[16:31], v[148:151], v[238:241], v[16:31]
	v_mfma_f32_32x32x16_bf16 v[96:111], v[202:205], v[206:209], v[96:111]
	global_load_dwordx4 v[148:151], v[190:191], off offset:1024
	global_load_dwordx4 v[206:209], v[242:243], off offset:1024
	v_mfma_f32_32x32x16_bf16 v[64:79], v[202:205], v[214:217], v[64:79]
	v_mfma_f32_32x32x16_bf16 v[32:47], v[202:205], v[228:231], v[32:47]
	v_mfma_f32_32x32x16_bf16 v[0:15], v[202:205], v[238:241], v[0:15]
	s_setprio 0
	ds_read_b128 v[202:205], v155 offset:96
	ds_read_b128 v[214:217], v155 offset:4704
	ds_read_b128 v[228:231], v155 offset:9312
	ds_read_b128 v[238:241], v155 offset:13920
	s_setprio 2
	s_waitcnt lgkmcnt(0)
	v_mfma_f32_32x32x16_bf16 v[112:127], v[140:143], v[186:189], v[112:127]
	v_mfma_f32_32x32x16_bf16 v[80:95], v[140:143], v[210:213], v[80:95]
	v_mfma_f32_32x32x16_bf16 v[48:63], v[140:143], v[218:221], v[48:63]
	v_mfma_f32_32x32x16_bf16 v[16:31], v[140:143], v[234:237], v[16:31]
	v_mfma_f32_32x32x16_bf16 v[96:111], v[182:185], v[186:189], v[96:111]
	global_load_dwordx4 v[140:143], v[190:191], off offset:2048
	global_load_dwordx4 v[186:189], v[242:243], off offset:2048
	v_mfma_f32_32x32x16_bf16 v[64:79], v[182:185], v[210:213], v[64:79]
	v_mfma_f32_32x32x16_bf16 v[32:47], v[182:185], v[218:221], v[32:47]
	v_mfma_f32_32x32x16_bf16 v[0:15], v[182:185], v[234:237], v[0:15]
	s_setprio 0
	s_setprio 2
	v_mfma_f32_32x32x16_bf16 v[112:127], v[132:135], v[202:205], v[112:127]
	v_mfma_f32_32x32x16_bf16 v[80:95], v[132:135], v[214:217], v[80:95]
	v_mfma_f32_32x32x16_bf16 v[48:63], v[132:135], v[228:231], v[48:63]
	v_mfma_f32_32x32x16_bf16 v[16:31], v[132:135], v[238:241], v[16:31]
	global_load_dwordx4 v[132:135], v[190:191], off offset:3072
	global_load_dwordx4 v[182:185], v[242:243], off offset:3072
	v_mfma_f32_32x32x16_bf16 v[96:111], v[198:201], v[202:205], v[96:111]
	v_mfma_f32_32x32x16_bf16 v[64:79], v[198:201], v[214:217], v[64:79]
	v_mfma_f32_32x32x16_bf16 v[32:47], v[198:201], v[228:231], v[32:47]
	v_mfma_f32_32x32x16_bf16 v[0:15], v[198:201], v[238:241], v[0:15]
	s_setprio 0
	s_waitcnt vmcnt(0)
	ds_write_b128 v154, v[170:173] offset:18432
	ds_write_b128 v154, v[144:147] offset:23040
	ds_write_b128 v154, v[136:139] offset:27648
	ds_write_b128 v154, v[128:131] offset:32256
	global_load_dwordx4 v[128:131], v[158:159], off offset:1280
	global_load_dwordx4 v[136:139], v[160:161], off offset:1280
	global_load_dwordx4 v[144:147], v[162:163], off offset:1280
	global_load_dwordx4 v[170:173], v[164:165], off offset:1280
	s_waitcnt lgkmcnt(0)
	s_barrier
	ds_read_b128 v[198:201], v155 offset:18432
	ds_read_b128 v[202:205], v155 offset:18464
	ds_read_b128 v[210:213], v155 offset:23040
	ds_read_b128 v[214:217], v155 offset:23072
	ds_read_b128 v[218:221], v155 offset:27648
	ds_read_b128 v[228:231], v155 offset:27680
	ds_read_b128 v[234:237], v155 offset:32256
	ds_read_b128 v[238:241], v155 offset:32288
	s_setprio 2
	s_mov_b32 s8, 0xa000
	v_add_co_u32_e32 v190, vcc, s8, v156
	s_mov_b32 s8, 0x1a000
	s_nop 0
	v_addc_co_u32_e32 v191, vcc, 0, v157, vcc
	v_add_co_u32_e32 v242, vcc, s8, v156
	s_waitcnt lgkmcnt(0)
	v_mfma_f32_32x32x16_bf16 v[112:127], v[174:177], v[198:201], v[112:127]
	v_addc_co_u32_e32 v243, vcc, 0, v157, vcc
	v_mfma_f32_32x32x16_bf16 v[80:95], v[174:177], v[210:213], v[80:95]
	v_mfma_f32_32x32x16_bf16 v[48:63], v[174:177], v[218:221], v[48:63]
	v_mfma_f32_32x32x16_bf16 v[16:31], v[174:177], v[234:237], v[16:31]
	v_mfma_f32_32x32x16_bf16 v[96:111], v[178:181], v[198:201], v[96:111]
	global_load_dwordx4 v[174:177], v[190:191], off
	global_load_dwordx4 v[198:201], v[242:243], off
	v_mfma_f32_32x32x16_bf16 v[64:79], v[178:181], v[210:213], v[64:79]
	v_mfma_f32_32x32x16_bf16 v[32:47], v[178:181], v[218:221], v[32:47]
	v_mfma_f32_32x32x16_bf16 v[0:15], v[178:181], v[234:237], v[0:15]
	s_setprio 0
	ds_read_b128 v[178:181], v155 offset:18496
	ds_read_b128 v[210:213], v155 offset:23104
	ds_read_b128 v[218:221], v155 offset:27712
	ds_read_b128 v[234:237], v155 offset:32320
	s_setprio 2
	v_mfma_f32_32x32x16_bf16 v[112:127], v[148:151], v[202:205], v[112:127]
	v_mfma_f32_32x32x16_bf16 v[80:95], v[148:151], v[214:217], v[80:95]
	v_mfma_f32_32x32x16_bf16 v[48:63], v[148:151], v[228:231], v[48:63]
	v_mfma_f32_32x32x16_bf16 v[16:31], v[148:151], v[238:241], v[16:31]
	v_mfma_f32_32x32x16_bf16 v[96:111], v[206:209], v[202:205], v[96:111]
	global_load_dwordx4 v[148:151], v[190:191], off offset:1024
	global_load_dwordx4 v[202:205], v[242:243], off offset:1024
	v_mfma_f32_32x32x16_bf16 v[64:79], v[206:209], v[214:217], v[64:79]
	v_mfma_f32_32x32x16_bf16 v[32:47], v[206:209], v[228:231], v[32:47]
	v_mfma_f32_32x32x16_bf16 v[0:15], v[206:209], v[238:241], v[0:15]
	s_setprio 0
	ds_read_b128 v[206:209], v155 offset:18528
	ds_read_b128 v[214:217], v155 offset:23136
	ds_read_b128 v[228:231], v155 offset:27744
	ds_read_b128 v[238:241], v155 offset:32352
	s_setprio 2
	s_waitcnt lgkmcnt(0)
	v_mfma_f32_32x32x16_bf16 v[112:127], v[140:143], v[178:181], v[112:127]
	v_mfma_f32_32x32x16_bf16 v[80:95], v[140:143], v[210:213], v[80:95]
	v_mfma_f32_32x32x16_bf16 v[48:63], v[140:143], v[218:221], v[48:63]
	v_mfma_f32_32x32x16_bf16 v[16:31], v[140:143], v[234:237], v[16:31]
	v_mfma_f32_32x32x16_bf16 v[96:111], v[186:189], v[178:181], v[96:111]
	global_load_dwordx4 v[140:143], v[190:191], off offset:2048
	global_load_dwordx4 v[178:181], v[242:243], off offset:2048
	v_mfma_f32_32x32x16_bf16 v[64:79], v[186:189], v[210:213], v[64:79]
	v_mfma_f32_32x32x16_bf16 v[32:47], v[186:189], v[218:221], v[32:47]
	v_mfma_f32_32x32x16_bf16 v[0:15], v[186:189], v[234:237], v[0:15]
	s_setprio 0
	s_setprio 2
	v_mfma_f32_32x32x16_bf16 v[112:127], v[132:135], v[206:209], v[112:127]
	v_mfma_f32_32x32x16_bf16 v[80:95], v[132:135], v[214:217], v[80:95]
	v_mfma_f32_32x32x16_bf16 v[48:63], v[132:135], v[228:231], v[48:63]
	v_mfma_f32_32x32x16_bf16 v[16:31], v[132:135], v[238:241], v[16:31]
	global_load_dwordx4 v[132:135], v[190:191], off offset:3072
	global_load_dwordx4 v[186:189], v[242:243], off offset:3072
	v_mfma_f32_32x32x16_bf16 v[96:111], v[182:185], v[206:209], v[96:111]
	v_mfma_f32_32x32x16_bf16 v[64:79], v[182:185], v[214:217], v[64:79]
	v_mfma_f32_32x32x16_bf16 v[32:47], v[182:185], v[228:231], v[32:47]
	v_mfma_f32_32x32x16_bf16 v[0:15], v[182:185], v[238:241], v[0:15]
	s_setprio 0
	s_waitcnt vmcnt(0)
	ds_write_b128 v154, v[128:131]
	ds_write_b128 v154, v[136:139] offset:4608
	ds_write_b128 v154, v[144:147] offset:9216
	ds_write_b128 v154, v[170:173] offset:13824
	global_load_dwordx4 v[128:131], v[164:165], off offset:1408
	global_load_dwordx4 v[136:139], v[162:163], off offset:1408
	global_load_dwordx4 v[144:147], v[160:161], off offset:1408
	global_load_dwordx4 v[170:173], v[158:159], off offset:1408
	s_waitcnt lgkmcnt(0)
	s_barrier
	ds_read_b128 v[182:185], v155
	ds_read_b128 v[206:209], v155 offset:32
	ds_read_b128 v[210:213], v155 offset:4608
	ds_read_b128 v[214:217], v155 offset:4640
	ds_read_b128 v[218:221], v155 offset:9216
	ds_read_b128 v[228:231], v155 offset:9248
	ds_read_b128 v[234:237], v155 offset:13824
	ds_read_b128 v[238:241], v155 offset:13856
	s_setprio 2
	s_mov_b32 s8, 0xb000
	v_add_co_u32_e32 v190, vcc, s8, v156
	s_mov_b32 s8, 0x1b000
	s_nop 0
	v_addc_co_u32_e32 v191, vcc, 0, v157, vcc
	v_add_co_u32_e32 v242, vcc, s8, v156
	s_waitcnt lgkmcnt(0)
	v_mfma_f32_32x32x16_bf16 v[112:127], v[174:177], v[182:185], v[112:127]
	v_addc_co_u32_e32 v243, vcc, 0, v157, vcc
	v_mfma_f32_32x32x16_bf16 v[80:95], v[174:177], v[210:213], v[80:95]
	v_mfma_f32_32x32x16_bf16 v[48:63], v[174:177], v[218:221], v[48:63]
	v_mfma_f32_32x32x16_bf16 v[16:31], v[174:177], v[234:237], v[16:31]
	v_mfma_f32_32x32x16_bf16 v[96:111], v[198:201], v[182:185], v[96:111]
	global_load_dwordx4 v[174:177], v[190:191], off
	global_load_dwordx4 v[182:185], v[242:243], off
	v_mfma_f32_32x32x16_bf16 v[64:79], v[198:201], v[210:213], v[64:79]
	v_mfma_f32_32x32x16_bf16 v[32:47], v[198:201], v[218:221], v[32:47]
	v_mfma_f32_32x32x16_bf16 v[0:15], v[198:201], v[234:237], v[0:15]
	s_setprio 0
	ds_read_b128 v[198:201], v155 offset:64
	ds_read_b128 v[210:213], v155 offset:4672
	ds_read_b128 v[218:221], v155 offset:9280
	ds_read_b128 v[234:237], v155 offset:13888
	s_setprio 2
	v_mfma_f32_32x32x16_bf16 v[112:127], v[148:151], v[206:209], v[112:127]
	v_mfma_f32_32x32x16_bf16 v[80:95], v[148:151], v[214:217], v[80:95]
	v_mfma_f32_32x32x16_bf16 v[48:63], v[148:151], v[228:231], v[48:63]
	v_mfma_f32_32x32x16_bf16 v[16:31], v[148:151], v[238:241], v[16:31]
	v_mfma_f32_32x32x16_bf16 v[96:111], v[202:205], v[206:209], v[96:111]
	global_load_dwordx4 v[148:151], v[190:191], off offset:1024
	global_load_dwordx4 v[206:209], v[242:243], off offset:1024
	v_mfma_f32_32x32x16_bf16 v[64:79], v[202:205], v[214:217], v[64:79]
	v_mfma_f32_32x32x16_bf16 v[32:47], v[202:205], v[228:231], v[32:47]
	v_mfma_f32_32x32x16_bf16 v[0:15], v[202:205], v[238:241], v[0:15]
	s_setprio 0
	ds_read_b128 v[202:205], v155 offset:96
	ds_read_b128 v[214:217], v155 offset:4704
	ds_read_b128 v[228:231], v155 offset:9312
	ds_read_b128 v[238:241], v155 offset:13920
	s_setprio 2
	s_waitcnt lgkmcnt(0)
	v_mfma_f32_32x32x16_bf16 v[112:127], v[140:143], v[198:201], v[112:127]
	v_mfma_f32_32x32x16_bf16 v[80:95], v[140:143], v[210:213], v[80:95]
	v_mfma_f32_32x32x16_bf16 v[48:63], v[140:143], v[218:221], v[48:63]
	v_mfma_f32_32x32x16_bf16 v[16:31], v[140:143], v[234:237], v[16:31]
	v_mfma_f32_32x32x16_bf16 v[96:111], v[178:181], v[198:201], v[96:111]
	global_load_dwordx4 v[140:143], v[190:191], off offset:2048
	global_load_dwordx4 v[198:201], v[242:243], off offset:2048
	v_mfma_f32_32x32x16_bf16 v[64:79], v[178:181], v[210:213], v[64:79]
	v_mfma_f32_32x32x16_bf16 v[32:47], v[178:181], v[218:221], v[32:47]
	v_mfma_f32_32x32x16_bf16 v[0:15], v[178:181], v[234:237], v[0:15]
	s_setprio 0
	s_setprio 2
	v_mfma_f32_32x32x16_bf16 v[112:127], v[132:135], v[202:205], v[112:127]
	v_mfma_f32_32x32x16_bf16 v[80:95], v[132:135], v[214:217], v[80:95]
	v_mfma_f32_32x32x16_bf16 v[48:63], v[132:135], v[228:231], v[48:63]
	v_mfma_f32_32x32x16_bf16 v[16:31], v[132:135], v[238:241], v[16:31]
	global_load_dwordx4 v[132:135], v[190:191], off offset:3072
	global_load_dwordx4 v[178:181], v[242:243], off offset:3072
	v_mfma_f32_32x32x16_bf16 v[96:111], v[186:189], v[202:205], v[96:111]
	v_mfma_f32_32x32x16_bf16 v[64:79], v[186:189], v[214:217], v[64:79]
	v_mfma_f32_32x32x16_bf16 v[32:47], v[186:189], v[228:231], v[32:47]
	v_mfma_f32_32x32x16_bf16 v[0:15], v[186:189], v[238:241], v[0:15]
	s_setprio 0
	s_waitcnt vmcnt(0)
	ds_write_b128 v154, v[170:173] offset:18432
	ds_write_b128 v154, v[144:147] offset:23040
	ds_write_b128 v154, v[136:139] offset:27648
	ds_write_b128 v154, v[128:131] offset:32256
	global_load_dwordx4 v[128:131], v[158:159], off offset:1536
	global_load_dwordx4 v[136:139], v[160:161], off offset:1536
	global_load_dwordx4 v[144:147], v[162:163], off offset:1536
	global_load_dwordx4 v[170:173], v[164:165], off offset:1536
	s_waitcnt lgkmcnt(0)
	s_barrier
	ds_read_b128 v[186:189], v155 offset:18432
	ds_read_b128 v[202:205], v155 offset:18464
	ds_read_b128 v[210:213], v155 offset:23040
	ds_read_b128 v[214:217], v155 offset:23072
	ds_read_b128 v[218:221], v155 offset:27648
	ds_read_b128 v[228:231], v155 offset:27680
	ds_read_b128 v[234:237], v155 offset:32256
	ds_read_b128 v[238:241], v155 offset:32288
	s_setprio 2
	s_mov_b32 s8, 0xc000
	v_add_co_u32_e32 v190, vcc, s8, v156
	s_mov_b32 s8, 0x1c000
	s_nop 0
	v_addc_co_u32_e32 v191, vcc, 0, v157, vcc
	v_add_co_u32_e32 v242, vcc, s8, v156
	s_waitcnt lgkmcnt(0)
	v_mfma_f32_32x32x16_bf16 v[112:127], v[174:177], v[186:189], v[112:127]
	v_addc_co_u32_e32 v243, vcc, 0, v157, vcc
	v_mfma_f32_32x32x16_bf16 v[80:95], v[174:177], v[210:213], v[80:95]
	v_mfma_f32_32x32x16_bf16 v[48:63], v[174:177], v[218:221], v[48:63]
	v_mfma_f32_32x32x16_bf16 v[16:31], v[174:177], v[234:237], v[16:31]
	v_mfma_f32_32x32x16_bf16 v[96:111], v[182:185], v[186:189], v[96:111]
	global_load_dwordx4 v[174:177], v[190:191], off
	global_load_dwordx4 v[186:189], v[242:243], off
	v_mfma_f32_32x32x16_bf16 v[64:79], v[182:185], v[210:213], v[64:79]
	v_mfma_f32_32x32x16_bf16 v[32:47], v[182:185], v[218:221], v[32:47]
	v_mfma_f32_32x32x16_bf16 v[0:15], v[182:185], v[234:237], v[0:15]
	s_setprio 0
	ds_read_b128 v[182:185], v155 offset:18496
	ds_read_b128 v[210:213], v155 offset:23104
	ds_read_b128 v[218:221], v155 offset:27712
	ds_read_b128 v[234:237], v155 offset:32320
	s_setprio 2
	v_mfma_f32_32x32x16_bf16 v[112:127], v[148:151], v[202:205], v[112:127]
	v_mfma_f32_32x32x16_bf16 v[80:95], v[148:151], v[214:217], v[80:95]
	v_mfma_f32_32x32x16_bf16 v[48:63], v[148:151], v[228:231], v[48:63]
	v_mfma_f32_32x32x16_bf16 v[16:31], v[148:151], v[238:241], v[16:31]
	v_mfma_f32_32x32x16_bf16 v[96:111], v[206:209], v[202:205], v[96:111]
	global_load_dwordx4 v[148:151], v[190:191], off offset:1024
	global_load_dwordx4 v[202:205], v[242:243], off offset:1024
	v_mfma_f32_32x32x16_bf16 v[64:79], v[206:209], v[214:217], v[64:79]
	v_mfma_f32_32x32x16_bf16 v[32:47], v[206:209], v[228:231], v[32:47]
	v_mfma_f32_32x32x16_bf16 v[0:15], v[206:209], v[238:241], v[0:15]
	s_setprio 0
	ds_read_b128 v[206:209], v155 offset:18528
	ds_read_b128 v[214:217], v155 offset:23136
	ds_read_b128 v[228:231], v155 offset:27744
	ds_read_b128 v[238:241], v155 offset:32352
	s_setprio 2
	s_waitcnt lgkmcnt(0)
	v_mfma_f32_32x32x16_bf16 v[112:127], v[140:143], v[182:185], v[112:127]
	v_mfma_f32_32x32x16_bf16 v[80:95], v[140:143], v[210:213], v[80:95]
	v_mfma_f32_32x32x16_bf16 v[48:63], v[140:143], v[218:221], v[48:63]
	v_mfma_f32_32x32x16_bf16 v[16:31], v[140:143], v[234:237], v[16:31]
	v_mfma_f32_32x32x16_bf16 v[96:111], v[198:201], v[182:185], v[96:111]
	global_load_dwordx4 v[140:143], v[190:191], off offset:2048
	global_load_dwordx4 v[182:185], v[242:243], off offset:2048
	v_mfma_f32_32x32x16_bf16 v[64:79], v[198:201], v[210:213], v[64:79]
	v_mfma_f32_32x32x16_bf16 v[32:47], v[198:201], v[218:221], v[32:47]
	v_mfma_f32_32x32x16_bf16 v[0:15], v[198:201], v[234:237], v[0:15]
	s_setprio 0
	s_setprio 2
	v_mfma_f32_32x32x16_bf16 v[112:127], v[132:135], v[206:209], v[112:127]
	v_mfma_f32_32x32x16_bf16 v[80:95], v[132:135], v[214:217], v[80:95]
	v_mfma_f32_32x32x16_bf16 v[48:63], v[132:135], v[228:231], v[48:63]
	v_mfma_f32_32x32x16_bf16 v[16:31], v[132:135], v[238:241], v[16:31]
	global_load_dwordx4 v[132:135], v[190:191], off offset:3072
	global_load_dwordx4 v[198:201], v[242:243], off offset:3072
	v_mfma_f32_32x32x16_bf16 v[96:111], v[178:181], v[206:209], v[96:111]
	v_mfma_f32_32x32x16_bf16 v[64:79], v[178:181], v[214:217], v[64:79]
	v_mfma_f32_32x32x16_bf16 v[32:47], v[178:181], v[228:231], v[32:47]
	v_mfma_f32_32x32x16_bf16 v[0:15], v[178:181], v[238:241], v[0:15]
	s_setprio 0
	s_waitcnt vmcnt(0)
	ds_write_b128 v154, v[128:131]
	ds_write_b128 v154, v[136:139] offset:4608
	ds_write_b128 v154, v[144:147] offset:9216
	ds_write_b128 v154, v[170:173] offset:13824
	global_load_dwordx4 v[128:131], v[164:165], off offset:1664
	global_load_dwordx4 v[136:139], v[162:163], off offset:1664
	global_load_dwordx4 v[144:147], v[160:161], off offset:1664
	global_load_dwordx4 v[170:173], v[158:159], off offset:1664
	s_waitcnt lgkmcnt(0)
	s_barrier
	ds_read_b128 v[178:181], v155
	ds_read_b128 v[206:209], v155 offset:32
	ds_read_b128 v[210:213], v155 offset:4608
	ds_read_b128 v[214:217], v155 offset:4640
	ds_read_b128 v[218:221], v155 offset:9216
	ds_read_b128 v[228:231], v155 offset:9248
	ds_read_b128 v[234:237], v155 offset:13824
	ds_read_b128 v[238:241], v155 offset:13856
	s_setprio 2
	s_mov_b32 s8, 0xd000
	v_add_co_u32_e32 v190, vcc, s8, v156
	s_mov_b32 s8, 0x1d000
	s_nop 0
	v_addc_co_u32_e32 v191, vcc, 0, v157, vcc
	v_add_co_u32_e32 v242, vcc, s8, v156
	s_waitcnt lgkmcnt(0)
	v_mfma_f32_32x32x16_bf16 v[112:127], v[174:177], v[178:181], v[112:127]
	v_addc_co_u32_e32 v243, vcc, 0, v157, vcc
	v_mfma_f32_32x32x16_bf16 v[80:95], v[174:177], v[210:213], v[80:95]
	v_mfma_f32_32x32x16_bf16 v[48:63], v[174:177], v[218:221], v[48:63]
	v_mfma_f32_32x32x16_bf16 v[16:31], v[174:177], v[234:237], v[16:31]
	v_mfma_f32_32x32x16_bf16 v[96:111], v[186:189], v[178:181], v[96:111]
	global_load_dwordx4 v[174:177], v[190:191], off
	global_load_dwordx4 v[178:181], v[242:243], off
	v_mfma_f32_32x32x16_bf16 v[64:79], v[186:189], v[210:213], v[64:79]
	v_mfma_f32_32x32x16_bf16 v[32:47], v[186:189], v[218:221], v[32:47]
	v_mfma_f32_32x32x16_bf16 v[0:15], v[186:189], v[234:237], v[0:15]
	s_setprio 0
	ds_read_b128 v[186:189], v155 offset:64
	ds_read_b128 v[210:213], v155 offset:4672
	ds_read_b128 v[218:221], v155 offset:9280
	ds_read_b128 v[234:237], v155 offset:13888
	s_setprio 2
	v_mfma_f32_32x32x16_bf16 v[112:127], v[148:151], v[206:209], v[112:127]
	v_mfma_f32_32x32x16_bf16 v[80:95], v[148:151], v[214:217], v[80:95]
	v_mfma_f32_32x32x16_bf16 v[48:63], v[148:151], v[228:231], v[48:63]
	v_mfma_f32_32x32x16_bf16 v[16:31], v[148:151], v[238:241], v[16:31]
	v_mfma_f32_32x32x16_bf16 v[96:111], v[202:205], v[206:209], v[96:111]
	global_load_dwordx4 v[148:151], v[190:191], off offset:1024
	global_load_dwordx4 v[206:209], v[242:243], off offset:1024
	v_mfma_f32_32x32x16_bf16 v[64:79], v[202:205], v[214:217], v[64:79]
	v_mfma_f32_32x32x16_bf16 v[32:47], v[202:205], v[228:231], v[32:47]
	v_mfma_f32_32x32x16_bf16 v[0:15], v[202:205], v[238:241], v[0:15]
	s_setprio 0
	ds_read_b128 v[202:205], v155 offset:96
	ds_read_b128 v[214:217], v155 offset:4704
	ds_read_b128 v[228:231], v155 offset:9312
	ds_read_b128 v[238:241], v155 offset:13920
	s_setprio 2
	s_waitcnt lgkmcnt(0)
	v_mfma_f32_32x32x16_bf16 v[112:127], v[140:143], v[186:189], v[112:127]
	v_mfma_f32_32x32x16_bf16 v[80:95], v[140:143], v[210:213], v[80:95]
	v_mfma_f32_32x32x16_bf16 v[48:63], v[140:143], v[218:221], v[48:63]
	v_mfma_f32_32x32x16_bf16 v[16:31], v[140:143], v[234:237], v[16:31]
	v_mfma_f32_32x32x16_bf16 v[96:111], v[182:185], v[186:189], v[96:111]
	global_load_dwordx4 v[140:143], v[190:191], off offset:2048
	global_load_dwordx4 v[186:189], v[242:243], off offset:2048
	v_mfma_f32_32x32x16_bf16 v[64:79], v[182:185], v[210:213], v[64:79]
	v_mfma_f32_32x32x16_bf16 v[32:47], v[182:185], v[218:221], v[32:47]
	v_mfma_f32_32x32x16_bf16 v[0:15], v[182:185], v[234:237], v[0:15]
	s_setprio 0
	s_setprio 2
	v_mfma_f32_32x32x16_bf16 v[112:127], v[132:135], v[202:205], v[112:127]
	v_mfma_f32_32x32x16_bf16 v[80:95], v[132:135], v[214:217], v[80:95]
	v_mfma_f32_32x32x16_bf16 v[48:63], v[132:135], v[228:231], v[48:63]
	v_mfma_f32_32x32x16_bf16 v[16:31], v[132:135], v[238:241], v[16:31]
	global_load_dwordx4 v[132:135], v[190:191], off offset:3072
	global_load_dwordx4 v[182:185], v[242:243], off offset:3072
	v_mfma_f32_32x32x16_bf16 v[96:111], v[198:201], v[202:205], v[96:111]
	v_mfma_f32_32x32x16_bf16 v[64:79], v[198:201], v[214:217], v[64:79]
	v_mfma_f32_32x32x16_bf16 v[32:47], v[198:201], v[228:231], v[32:47]
	v_mfma_f32_32x32x16_bf16 v[0:15], v[198:201], v[238:241], v[0:15]
	s_setprio 0
	s_waitcnt vmcnt(0)
	ds_write_b128 v154, v[170:173] offset:18432
	ds_write_b128 v154, v[144:147] offset:23040
	ds_write_b128 v154, v[136:139] offset:27648
	ds_write_b128 v154, v[128:131] offset:32256
	global_load_dwordx4 v[128:131], v[158:159], off offset:1792
	global_load_dwordx4 v[136:139], v[160:161], off offset:1792
	global_load_dwordx4 v[144:147], v[162:163], off offset:1792
	global_load_dwordx4 v[170:173], v[164:165], off offset:1792
	s_waitcnt lgkmcnt(0)
	s_barrier
	ds_read_b128 v[198:201], v155 offset:18432
	ds_read_b128 v[202:205], v155 offset:18464
	ds_read_b128 v[210:213], v155 offset:23040
	ds_read_b128 v[214:217], v155 offset:23072
	ds_read_b128 v[218:221], v155 offset:27648
	ds_read_b128 v[228:231], v155 offset:27680
	ds_read_b128 v[234:237], v155 offset:32256
	ds_read_b128 v[238:241], v155 offset:32288
	s_setprio 2
	s_mov_b32 s8, 0xe000
	v_add_co_u32_e32 v190, vcc, s8, v156
	s_mov_b32 s8, 0x1e000
	s_nop 0
	v_addc_co_u32_e32 v191, vcc, 0, v157, vcc
	v_add_co_u32_e32 v242, vcc, s8, v156
	s_waitcnt lgkmcnt(0)
	v_mfma_f32_32x32x16_bf16 v[112:127], v[174:177], v[198:201], v[112:127]
	v_addc_co_u32_e32 v243, vcc, 0, v157, vcc
	v_mfma_f32_32x32x16_bf16 v[80:95], v[174:177], v[210:213], v[80:95]
	v_mfma_f32_32x32x16_bf16 v[48:63], v[174:177], v[218:221], v[48:63]
	v_mfma_f32_32x32x16_bf16 v[16:31], v[174:177], v[234:237], v[16:31]
	v_mfma_f32_32x32x16_bf16 v[96:111], v[178:181], v[198:201], v[96:111]
	global_load_dwordx4 v[174:177], v[190:191], off
	global_load_dwordx4 v[198:201], v[242:243], off
	v_mfma_f32_32x32x16_bf16 v[64:79], v[178:181], v[210:213], v[64:79]
	v_mfma_f32_32x32x16_bf16 v[32:47], v[178:181], v[218:221], v[32:47]
	v_mfma_f32_32x32x16_bf16 v[0:15], v[178:181], v[234:237], v[0:15]
	s_setprio 0
	ds_read_b128 v[178:181], v155 offset:18496
	ds_read_b128 v[210:213], v155 offset:23104
	ds_read_b128 v[218:221], v155 offset:27712
	ds_read_b128 v[234:237], v155 offset:32320
	s_setprio 2
	v_mfma_f32_32x32x16_bf16 v[112:127], v[148:151], v[202:205], v[112:127]
	v_mfma_f32_32x32x16_bf16 v[80:95], v[148:151], v[214:217], v[80:95]
	v_mfma_f32_32x32x16_bf16 v[48:63], v[148:151], v[228:231], v[48:63]
	v_mfma_f32_32x32x16_bf16 v[16:31], v[148:151], v[238:241], v[16:31]
	v_mfma_f32_32x32x16_bf16 v[96:111], v[206:209], v[202:205], v[96:111]
	global_load_dwordx4 v[148:151], v[190:191], off offset:1024
	global_load_dwordx4 v[202:205], v[242:243], off offset:1024
	v_mfma_f32_32x32x16_bf16 v[64:79], v[206:209], v[214:217], v[64:79]
	v_mfma_f32_32x32x16_bf16 v[32:47], v[206:209], v[228:231], v[32:47]
	v_mfma_f32_32x32x16_bf16 v[0:15], v[206:209], v[238:241], v[0:15]
	s_setprio 0
	ds_read_b128 v[206:209], v155 offset:18528
	ds_read_b128 v[214:217], v155 offset:23136
	ds_read_b128 v[228:231], v155 offset:27744
	ds_read_b128 v[238:241], v155 offset:32352
	s_setprio 2
	s_waitcnt lgkmcnt(0)
	v_mfma_f32_32x32x16_bf16 v[112:127], v[140:143], v[178:181], v[112:127]
	v_mfma_f32_32x32x16_bf16 v[80:95], v[140:143], v[210:213], v[80:95]
	v_mfma_f32_32x32x16_bf16 v[48:63], v[140:143], v[218:221], v[48:63]
	v_mfma_f32_32x32x16_bf16 v[16:31], v[140:143], v[234:237], v[16:31]
	v_mfma_f32_32x32x16_bf16 v[96:111], v[186:189], v[178:181], v[96:111]
	global_load_dwordx4 v[140:143], v[190:191], off offset:2048
	global_load_dwordx4 v[178:181], v[242:243], off offset:2048
	v_mfma_f32_32x32x16_bf16 v[64:79], v[186:189], v[210:213], v[64:79]
	v_mfma_f32_32x32x16_bf16 v[32:47], v[186:189], v[218:221], v[32:47]
	v_mfma_f32_32x32x16_bf16 v[0:15], v[186:189], v[234:237], v[0:15]
	s_setprio 0
	s_setprio 2
	v_mfma_f32_32x32x16_bf16 v[112:127], v[132:135], v[206:209], v[112:127]
	v_mfma_f32_32x32x16_bf16 v[80:95], v[132:135], v[214:217], v[80:95]
	v_mfma_f32_32x32x16_bf16 v[48:63], v[132:135], v[228:231], v[48:63]
	v_mfma_f32_32x32x16_bf16 v[16:31], v[132:135], v[238:241], v[16:31]
	global_load_dwordx4 v[132:135], v[190:191], off offset:3072
	global_load_dwordx4 v[186:189], v[242:243], off offset:3072
	v_mfma_f32_32x32x16_bf16 v[96:111], v[182:185], v[206:209], v[96:111]
	v_mfma_f32_32x32x16_bf16 v[64:79], v[182:185], v[214:217], v[64:79]
	v_mfma_f32_32x32x16_bf16 v[32:47], v[182:185], v[228:231], v[32:47]
	v_mfma_f32_32x32x16_bf16 v[0:15], v[182:185], v[238:241], v[0:15]
	s_setprio 0
	s_waitcnt vmcnt(0)
	ds_write_b128 v154, v[128:131]
	ds_write_b128 v154, v[136:139] offset:4608
	ds_write_b128 v154, v[144:147] offset:9216
	ds_write_b128 v154, v[170:173] offset:13824
	global_load_dwordx4 v[128:131], v[164:165], off offset:1920
	global_load_dwordx4 v[136:139], v[162:163], off offset:1920
	global_load_dwordx4 v[144:147], v[160:161], off offset:1920
	s_nop 0
	global_load_dwordx4 v[158:161], v[158:159], off offset:1920
	s_waitcnt lgkmcnt(0)
	s_barrier
	ds_read_b128 v[162:165], v155
	ds_read_b128 v[170:173], v155 offset:32
	ds_read_b128 v[182:185], v155 offset:4608
	ds_read_b128 v[206:209], v155 offset:4640
	ds_read_b128 v[210:213], v155 offset:9216
	ds_read_b128 v[214:217], v155 offset:9248
	ds_read_b128 v[218:221], v155 offset:13824
	ds_read_b128 v[228:231], v155 offset:13856
	s_setprio 2
	s_mov_b32 s8, 0xf000
	v_add_co_u32_e32 v190, vcc, s8, v156
	s_mov_b32 s8, 0x1f000
	s_nop 0
	v_addc_co_u32_e32 v191, vcc, 0, v157, vcc
	v_add_co_u32_e32 v156, vcc, s8, v156
	s_waitcnt lgkmcnt(0)
	v_mfma_f32_32x32x16_bf16 v[112:127], v[174:177], v[162:165], v[112:127]
	v_addc_co_u32_e32 v157, vcc, 0, v157, vcc
	v_mfma_f32_32x32x16_bf16 v[80:95], v[174:177], v[182:185], v[80:95]
	v_mfma_f32_32x32x16_bf16 v[48:63], v[174:177], v[210:213], v[48:63]
	v_mfma_f32_32x32x16_bf16 v[16:31], v[174:177], v[218:221], v[16:31]
	v_mfma_f32_32x32x16_bf16 v[96:111], v[198:201], v[162:165], v[96:111]
	global_load_dwordx4 v[162:165], v[190:191], off
	global_load_dwordx4 v[174:177], v[156:157], off
	v_mfma_f32_32x32x16_bf16 v[64:79], v[198:201], v[182:185], v[64:79]
	v_mfma_f32_32x32x16_bf16 v[32:47], v[198:201], v[210:213], v[32:47]
	v_mfma_f32_32x32x16_bf16 v[0:15], v[198:201], v[218:221], v[0:15]
	s_setprio 0
	ds_read_b128 v[182:185], v155 offset:64
	ds_read_b128 v[198:201], v155 offset:4672
	ds_read_b128 v[210:213], v155 offset:9280
	ds_read_b128 v[218:221], v155 offset:13888
	s_setprio 2
	v_mfma_f32_32x32x16_bf16 v[112:127], v[148:151], v[170:173], v[112:127]
	v_mfma_f32_32x32x16_bf16 v[80:95], v[148:151], v[206:209], v[80:95]
	v_mfma_f32_32x32x16_bf16 v[48:63], v[148:151], v[214:217], v[48:63]
	v_mfma_f32_32x32x16_bf16 v[16:31], v[148:151], v[228:231], v[16:31]
	v_mfma_f32_32x32x16_bf16 v[96:111], v[202:205], v[170:173], v[96:111]
	global_load_dwordx4 v[148:151], v[190:191], off offset:1024
	global_load_dwordx4 v[170:173], v[156:157], off offset:1024
	v_mfma_f32_32x32x16_bf16 v[64:79], v[202:205], v[206:209], v[64:79]
	v_mfma_f32_32x32x16_bf16 v[32:47], v[202:205], v[214:217], v[32:47]
	v_mfma_f32_32x32x16_bf16 v[0:15], v[202:205], v[228:231], v[0:15]
	s_setprio 0
	ds_read_b128 v[202:205], v155 offset:96
	ds_read_b128 v[206:209], v155 offset:4704
	ds_read_b128 v[214:217], v155 offset:9312
	ds_read_b128 v[228:231], v155 offset:13920
	s_setprio 2
	s_waitcnt lgkmcnt(0)
	v_mfma_f32_32x32x16_bf16 v[112:127], v[140:143], v[182:185], v[112:127]
	v_mfma_f32_32x32x16_bf16 v[80:95], v[140:143], v[198:201], v[80:95]
	v_mfma_f32_32x32x16_bf16 v[48:63], v[140:143], v[210:213], v[48:63]
	v_mfma_f32_32x32x16_bf16 v[16:31], v[140:143], v[218:221], v[16:31]
	v_mfma_f32_32x32x16_bf16 v[96:111], v[178:181], v[182:185], v[96:111]
	global_load_dwordx4 v[140:143], v[190:191], off offset:2048
	global_load_dwordx4 v[182:185], v[156:157], off offset:2048
	v_mfma_f32_32x32x16_bf16 v[64:79], v[178:181], v[198:201], v[64:79]
	v_mfma_f32_32x32x16_bf16 v[32:47], v[178:181], v[210:213], v[32:47]
	v_mfma_f32_32x32x16_bf16 v[0:15], v[178:181], v[218:221], v[0:15]
	s_setprio 0
	s_setprio 2
	v_mfma_f32_32x32x16_bf16 v[112:127], v[132:135], v[202:205], v[112:127]
	v_mfma_f32_32x32x16_bf16 v[80:95], v[132:135], v[206:209], v[80:95]
	v_mfma_f32_32x32x16_bf16 v[48:63], v[132:135], v[214:217], v[48:63]
	v_mfma_f32_32x32x16_bf16 v[16:31], v[132:135], v[228:231], v[16:31]
	global_load_dwordx4 v[132:135], v[190:191], off offset:3072
	global_load_dwordx4 v[178:181], v[156:157], off offset:3072
	v_mfma_f32_32x32x16_bf16 v[96:111], v[186:189], v[202:205], v[96:111]
	v_mfma_f32_32x32x16_bf16 v[64:79], v[186:189], v[206:209], v[64:79]
	v_mfma_f32_32x32x16_bf16 v[32:47], v[186:189], v[214:217], v[32:47]
	v_mfma_f32_32x32x16_bf16 v[0:15], v[186:189], v[228:231], v[0:15]
	s_setprio 0
	s_waitcnt vmcnt(0)
	ds_write_b128 v154, v[158:161] offset:18432
	ds_write_b128 v154, v[144:147] offset:23040
	ds_write_b128 v154, v[136:139] offset:27648
	ds_write_b128 v154, v[128:131] offset:32256
	s_waitcnt lgkmcnt(0)
	s_barrier
	ds_read_b128 v[128:131], v155 offset:18432
	ds_read_b128 v[136:139], v155 offset:18464
	ds_read_b128 v[144:147], v155 offset:23040
	ds_read_b128 v[156:159], v155 offset:23072
	ds_read_b128 v[186:189], v155 offset:27648
	ds_read_b128 v[198:201], v155 offset:27680
	ds_read_b128 v[202:205], v155 offset:32256
	ds_read_b128 v[206:209], v155 offset:32288
	s_setprio 2
	s_waitcnt lgkmcnt(7)
	v_mfma_f32_32x32x16_bf16 v[112:127], v[162:165], v[128:131], v[112:127]
	s_waitcnt lgkmcnt(5)
	v_mfma_f32_32x32x16_bf16 v[80:95], v[162:165], v[144:147], v[80:95]
	s_waitcnt lgkmcnt(3)
	v_mfma_f32_32x32x16_bf16 v[48:63], v[162:165], v[186:189], v[48:63]
	s_waitcnt lgkmcnt(1)
	v_mfma_f32_32x32x16_bf16 v[16:31], v[162:165], v[202:205], v[16:31]
	v_mfma_f32_32x32x16_bf16 v[96:111], v[174:177], v[128:131], v[96:111]
	v_mfma_f32_32x32x16_bf16 v[64:79], v[174:177], v[144:147], v[64:79]
	v_mfma_f32_32x32x16_bf16 v[32:47], v[174:177], v[186:189], v[32:47]
	v_mfma_f32_32x32x16_bf16 v[0:15], v[174:177], v[202:205], v[0:15]
	s_setprio 0
	ds_read_b128 v[128:131], v155 offset:18496
	ds_read_b128 v[144:147], v155 offset:23104
	ds_read_b128 v[160:163], v155 offset:27712
	ds_read_b128 v[174:177], v155 offset:32320
	s_setprio 2
	v_mfma_f32_32x32x16_bf16 v[112:127], v[148:151], v[136:139], v[112:127]
	v_mfma_f32_32x32x16_bf16 v[80:95], v[148:151], v[156:159], v[80:95]
	v_mfma_f32_32x32x16_bf16 v[48:63], v[148:151], v[198:201], v[48:63]
	s_waitcnt lgkmcnt(4)
	v_mfma_f32_32x32x16_bf16 v[16:31], v[148:151], v[206:209], v[16:31]
	v_mfma_f32_32x32x16_bf16 v[96:111], v[170:173], v[136:139], v[96:111]
	v_mfma_f32_32x32x16_bf16 v[64:79], v[170:173], v[156:159], v[64:79]
	v_mfma_f32_32x32x16_bf16 v[32:47], v[170:173], v[198:201], v[32:47]
	v_mfma_f32_32x32x16_bf16 v[0:15], v[170:173], v[206:209], v[0:15]
	s_setprio 0
	ds_read_b128 v[136:139], v155 offset:18528
	ds_read_b128 v[148:151], v155 offset:23136
	ds_read_b128 v[156:159], v155 offset:27744
	ds_read_b128 v[170:173], v155 offset:32352
	s_setprio 2
	s_waitcnt lgkmcnt(7)
	v_mfma_f32_32x32x16_bf16 v[112:127], v[140:143], v[128:131], v[112:127]
	s_waitcnt lgkmcnt(6)
	v_mfma_f32_32x32x16_bf16 v[80:95], v[140:143], v[144:147], v[80:95]
	s_waitcnt lgkmcnt(5)
	v_mfma_f32_32x32x16_bf16 v[48:63], v[140:143], v[160:163], v[48:63]
	s_waitcnt lgkmcnt(4)
	v_mfma_f32_32x32x16_bf16 v[16:31], v[140:143], v[174:177], v[16:31]
	v_mfma_f32_32x32x16_bf16 v[96:111], v[182:185], v[128:131], v[96:111]
	v_mfma_f32_32x32x16_bf16 v[64:79], v[182:185], v[144:147], v[64:79]
	v_mfma_f32_32x32x16_bf16 v[32:47], v[182:185], v[160:163], v[32:47]
	v_mfma_f32_32x32x16_bf16 v[0:15], v[182:185], v[174:177], v[0:15]
	s_setprio 0
	s_setprio 2
	s_waitcnt lgkmcnt(3)
	v_mfma_f32_32x32x16_bf16 v[112:127], v[132:135], v[136:139], v[112:127]
	s_waitcnt lgkmcnt(2)
	v_mfma_f32_32x32x16_bf16 v[80:95], v[132:135], v[148:151], v[80:95]
	s_waitcnt lgkmcnt(1)
	v_mfma_f32_32x32x16_bf16 v[48:63], v[132:135], v[156:159], v[48:63]
	s_waitcnt lgkmcnt(0)
	v_mfma_f32_32x32x16_bf16 v[16:31], v[132:135], v[170:173], v[16:31]
	v_mfma_f32_32x32x16_bf16 v[96:111], v[178:181], v[136:139], v[96:111]
	v_mfma_f32_32x32x16_bf16 v[64:79], v[178:181], v[148:151], v[64:79]
	v_mfma_f32_32x32x16_bf16 v[32:47], v[178:181], v[156:159], v[32:47]
	v_mfma_f32_32x32x16_bf16 v[0:15], v[178:181], v[170:173], v[0:15]
	s_setprio 0
	v_and_b32_e32 v128, 0xffffffc0, v152
	v_or_b32_e32 v130, s30, v167
	v_readlane_b32 s10, v253, 12
	v_lshl_add_u32 v128, s61, 8, v128
	v_readlane_b32 s11, v253, 13
	v_or_b32_e32 v138, 32, v130
	v_or_b32_e32 v136, 64, v130
	v_or_b32_e32 v134, 0x60, v130
	v_ashrrev_i32_e32 v129, 31, v128
	v_lshlrev_b32_e32 v141, 2, v169
	s_mov_b64 s[8:9], -1
	s_andn2_b64 vcc, exec, s[10:11]
	v_ashrrev_i32_e32 v131, 31, v130
	v_ashrrev_i32_e32 v139, 31, v138
	v_ashrrev_i32_e32 v137, 31, v136
	v_ashrrev_i32_e32 v135, 31, v134
	s_barrier
	s_cbranch_vccnz .LBB0_817
	v_lshlrev_b64 v[132:133], 11, v[130:131]
	v_lshl_add_u64 v[132:133], s[22:23], 0, v[132:133]
	v_lshlrev_b64 v[142:143], 1, v[128:129]
	v_lshl_add_u64 v[132:133], v[132:133], 0, v[142:143]
	v_lshlrev_b32_e32 v192, 1, v141
	v_lshl_add_u64 v[132:133], v[132:133], 0, v[192:193]
	v_cvt_pk_bf16_f32 v144, v112, v113
	v_cvt_pk_bf16_f32 v145, v114, v115
	global_store_dwordx2 v[132:133], v[144:145], off
	v_cvt_pk_bf16_f32 v144, v116, v117
	v_cvt_pk_bf16_f32 v145, v118, v119
	global_store_dwordx2 v[132:133], v[144:145], off offset:16
	v_cvt_pk_bf16_f32 v144, v120, v121
	v_cvt_pk_bf16_f32 v145, v122, v123
	global_store_dwordx2 v[132:133], v[144:145], off offset:32
	v_cvt_pk_bf16_f32 v144, v124, v125
	v_cvt_pk_bf16_f32 v145, v126, v127
	global_store_dwordx2 v[132:133], v[144:145], off offset:48
	v_cvt_pk_bf16_f32 v144, v96, v97
	v_cvt_pk_bf16_f32 v145, v98, v99
	global_store_dwordx2 v[132:133], v[144:145], off offset:64
	v_cvt_pk_bf16_f32 v144, v100, v101
	v_cvt_pk_bf16_f32 v145, v102, v103
	global_store_dwordx2 v[132:133], v[144:145], off offset:80
	v_cvt_pk_bf16_f32 v144, v104, v105
	v_cvt_pk_bf16_f32 v145, v106, v107
	global_store_dwordx2 v[132:133], v[144:145], off offset:96
	v_cvt_pk_bf16_f32 v144, v108, v109
	v_cvt_pk_bf16_f32 v145, v110, v111
	global_store_dwordx2 v[132:133], v[144:145], off offset:112
	v_lshlrev_b64 v[132:133], 11, v[138:139]
	v_lshl_add_u64 v[132:133], s[22:23], 0, v[132:133]
	v_lshl_add_u64 v[132:133], v[132:133], 0, v[142:143]
	v_lshl_add_u64 v[132:133], v[132:133], 0, v[192:193]
	v_cvt_pk_bf16_f32 v144, v80, v81
	v_cvt_pk_bf16_f32 v145, v82, v83
	global_store_dwordx2 v[132:133], v[144:145], off
	v_cvt_pk_bf16_f32 v144, v84, v85
	v_cvt_pk_bf16_f32 v145, v86, v87
	global_store_dwordx2 v[132:133], v[144:145], off offset:16
	v_cvt_pk_bf16_f32 v144, v88, v89
	v_cvt_pk_bf16_f32 v145, v90, v91
	global_store_dwordx2 v[132:133], v[144:145], off offset:32
	v_cvt_pk_bf16_f32 v144, v92, v93
	v_cvt_pk_bf16_f32 v145, v94, v95
	global_store_dwordx2 v[132:133], v[144:145], off offset:48
	v_cvt_pk_bf16_f32 v144, v64, v65
	v_cvt_pk_bf16_f32 v145, v66, v67
	global_store_dwordx2 v[132:133], v[144:145], off offset:64
	v_cvt_pk_bf16_f32 v144, v68, v69
	v_cvt_pk_bf16_f32 v145, v70, v71
	global_store_dwordx2 v[132:133], v[144:145], off offset:80
	v_cvt_pk_bf16_f32 v144, v72, v73
	v_cvt_pk_bf16_f32 v145, v74, v75
	global_store_dwordx2 v[132:133], v[144:145], off offset:96
	v_cvt_pk_bf16_f32 v144, v76, v77
	v_cvt_pk_bf16_f32 v145, v78, v79
	global_store_dwordx2 v[132:133], v[144:145], off offset:112
	v_lshlrev_b64 v[132:133], 11, v[136:137]
	v_lshl_add_u64 v[132:133], s[22:23], 0, v[132:133]
	v_lshl_add_u64 v[132:133], v[132:133], 0, v[142:143]
	v_lshl_add_u64 v[132:133], v[132:133], 0, v[192:193]
	v_cvt_pk_bf16_f32 v144, v48, v49
	v_cvt_pk_bf16_f32 v145, v50, v51
	global_store_dwordx2 v[132:133], v[144:145], off
	v_cvt_pk_bf16_f32 v144, v52, v53
	v_cvt_pk_bf16_f32 v145, v54, v55
	global_store_dwordx2 v[132:133], v[144:145], off offset:16
	v_cvt_pk_bf16_f32 v144, v56, v57
	v_cvt_pk_bf16_f32 v145, v58, v59
	global_store_dwordx2 v[132:133], v[144:145], off offset:32
	v_cvt_pk_bf16_f32 v144, v60, v61
	v_cvt_pk_bf16_f32 v145, v62, v63
	global_store_dwordx2 v[132:133], v[144:145], off offset:48
	v_cvt_pk_bf16_f32 v144, v32, v33
	v_cvt_pk_bf16_f32 v145, v34, v35
	global_store_dwordx2 v[132:133], v[144:145], off offset:64
	v_cvt_pk_bf16_f32 v144, v36, v37
	v_cvt_pk_bf16_f32 v145, v38, v39
	global_store_dwordx2 v[132:133], v[144:145], off offset:80
	v_cvt_pk_bf16_f32 v144, v40, v41
	v_cvt_pk_bf16_f32 v145, v42, v43
	global_store_dwordx2 v[132:133], v[144:145], off offset:96
	v_cvt_pk_bf16_f32 v144, v44, v45
	v_cvt_pk_bf16_f32 v145, v46, v47
	global_store_dwordx2 v[132:133], v[144:145], off offset:112
	v_lshlrev_b64 v[132:133], 11, v[134:135]
	v_lshl_add_u64 v[132:133], s[22:23], 0, v[132:133]
	v_lshl_add_u64 v[132:133], v[132:133], 0, v[142:143]
	v_lshl_add_u64 v[132:133], v[132:133], 0, v[192:193]
	v_cvt_pk_bf16_f32 v142, v16, v17
	v_cvt_pk_bf16_f32 v143, v18, v19
	global_store_dwordx2 v[132:133], v[142:143], off
	v_cvt_pk_bf16_f32 v142, v20, v21
	v_cvt_pk_bf16_f32 v143, v22, v23
	global_store_dwordx2 v[132:133], v[142:143], off offset:16
	v_cvt_pk_bf16_f32 v142, v24, v25
	v_cvt_pk_bf16_f32 v143, v26, v27
	global_store_dwordx2 v[132:133], v[142:143], off offset:32
	v_cvt_pk_bf16_f32 v142, v28, v29
	v_cvt_pk_bf16_f32 v143, v30, v31
	global_store_dwordx2 v[132:133], v[142:143], off offset:48
	v_cvt_pk_bf16_f32 v142, v0, v1
	v_cvt_pk_bf16_f32 v143, v2, v3
	global_store_dwordx2 v[132:133], v[142:143], off offset:64
	v_cvt_pk_bf16_f32 v142, v4, v5
	v_cvt_pk_bf16_f32 v143, v6, v7
	global_store_dwordx2 v[132:133], v[142:143], off offset:80
	v_cvt_pk_bf16_f32 v142, v8, v9
	v_cvt_pk_bf16_f32 v143, v10, v11
	global_store_dwordx2 v[132:133], v[142:143], off offset:96
	v_cvt_pk_bf16_f32 v142, v12, v13
	v_cvt_pk_bf16_f32 v143, v14, v15
	s_mov_b64 s[8:9], 0
	global_store_dwordx2 v[132:133], v[142:143], off offset:112

.LBB0_826:
	s_or_b64 exec, exec, s[10:11]
	s_add_i32 s10, s34, s2
	s_ashr_i32 s11, s10, 31
	s_lshl_b64 s[10:11], s[10:11], 11
	s_add_u32 s14, s56, s10
	s_movk_i32 s10, 0x80
	s_addc_u32 s15, s57, s11
	v_cmp_gt_i32_e64 s[10:11], s10, v152
	v_ashrrev_i32_e32 v153, 31, v152
	v_lshlrev_b32_e32 v150, 2, v152
	s_waitcnt lgkmcnt(0)
	s_barrier
	s_and_saveexec_b64 s[12:13], s[10:11]
	s_xor_b64 s[12:13], exec, s[12:13]
	s_cbranch_execz .LBB0_828
	ds_read2st64_b32 v[132:133], v150 offset1:2
	ds_read2st64_b32 v[142:143], v150 offset0:4 offset1:6
	s_lshl_b32 s16, s61, 7
	s_ashr_i32 s17, s16, 31
	s_lshl_b64 s[16:17], s[16:17], 2
	s_waitcnt lgkmcnt(1)
	v_mov_b32_e32 v144, v132
	s_waitcnt lgkmcnt(0)
	v_mov_b32_e32 v145, v142
	v_mov_b32_e32 v142, v133
	s_add_u32 s16, s14, s16
	v_pk_add_f32 v[132:133], v[144:145], v[142:143]
	s_addc_u32 s17, s15, s17
	v_pk_add_f32 v[132:133], v[132:133], v[132:133] op_sel:[0,1] op_sel_hi:[1,0]
	v_lshl_add_u64 v[142:143], v[152:153], 2, s[16:17]
	global_store_dword v[142:143], v132, off sc1
.LBB0_828:
	s_or_b64 exec, exec, s[12:13]
	s_waitcnt vmcnt(0)
	s_ashr_i32 s35, s34, 31
	v_cmp_eq_u32_e64 s[12:13], 0, v152
	s_waitcnt lgkmcnt(0)
	s_barrier
	s_and_saveexec_b64 s[16:17], s[12:13]
	s_cbranch_execz .LBB0_842
	s_lshl_b64 s[36:37], s[34:35], 2
	s_add_u32 s36, s3, s36
	s_addc_u32 s37, s58, s37
	v_mov_b64_e32 v[132:133], s[36:37]
	global_atomic_add v[132:133], v251, off
	s_mov_b32 s31, 0x400001
	s_mov_b64 s[38:39], 0
	s_branch .LBB0_835

.LBB0_835:
	v_mov_b64_e32 v[132:133], s[36:37]
	global_load_dword v132, v[132:133], off sc1
	s_or_b64 s[40:41], s[40:41], exec
	s_waitcnt vmcnt(0) lgkmcnt(0)
	v_cmp_gt_u32_e32 vcc, 4, v132
	s_and_saveexec_b64 s[42:43], vcc
	s_cbranch_execz .LBB0_834
	v_mov_b64_e32 v[132:133], s[36:37]
	s_sleep 1
	global_load_dword v132, v[132:133], off sc1
	s_mov_b64 s[46:47], -1
	s_waitcnt vmcnt(0) lgkmcnt(0)
	v_cmp_gt_u32_e32 vcc, 4, v132
	s_and_saveexec_b64 s[44:45], vcc
	s_cbranch_execz .LBB0_833
	v_mov_b64_e32 v[132:133], s[36:37]
	s_sleep 1
	global_load_dword v132, v[132:133], off sc1
	s_mov_b64 s[48:49], -1
	s_waitcnt vmcnt(0) lgkmcnt(0)
	v_cmp_gt_u32_e32 vcc, 4, v132
	s_and_saveexec_b64 s[46:47], vcc
	s_cbranch_execz .LBB0_832
	v_mov_b64_e32 v[132:133], s[36:37]
	s_sleep 1
	global_load_dword v132, v[132:133], off sc1
	s_mov_b64 s[50:51], -1
	s_waitcnt vmcnt(0) lgkmcnt(0)
	v_cmp_gt_u32_e32 vcc, 4, v132
	s_and_saveexec_b64 s[48:49], vcc
	s_cbranch_execz .LBB0_831
	v_mov_b64_e32 v[132:133], s[36:37]
	s_sleep 1
	global_load_dword v132, v[132:133], off sc1
	s_waitcnt vmcnt(0) lgkmcnt(0)
	v_cmp_gt_u32_e32 vcc, 4, v132
	s_and_saveexec_b64 s[52:53], vcc
	s_cbranch_execz .LBB0_830
	s_add_i32 s31, s31, -5
	s_cmp_eq_u32 s31, 0
	s_cselect_b64 s[50:51], -1, 0
	s_orn2_b64 s[50:51], s[50:51], exec
	s_sleep 1
	s_branch .LBB0_830

.LBB0_842:
	s_or_b64 exec, exec, s[16:17]
	s_barrier
	s_and_saveexec_b64 s[16:17], s[10:11]
	s_cbranch_execz .LBB0_844
	v_lshl_add_u64 v[132:133], v[152:153], 2, s[14:15]
	global_load_dword v142, v[132:133], off sc1
	global_load_dword v144, v[132:133], off offset:512 sc1
	global_load_dword v143, v[132:133], off offset:1024 sc1
	global_load_dword v145, v[132:133], off offset:1536 sc1
	s_waitcnt vmcnt(0) lgkmcnt(0)
	v_pk_add_f32 v[132:133], v[142:143], v[144:145]
	s_nop 0
	v_add_f32_e32 v132, v132, v133
	ds_write_b32 v150, v132 offset:2048
.LBB0_844:
	s_or_b64 exec, exec, s[16:17]
	s_waitcnt lgkmcnt(0)
	s_barrier
	ds_read_b32 v133, v154 offset:2048
	s_mov_b32 s14, 0x800000
	v_lshlrev_b64 v[144:145], 10, v[130:131]
	v_lshlrev_b64 v[130:131], 11, v[130:131]
	v_cndmask_b32_e64 v132, 8, 0, s[8:9]
	s_waitcnt lgkmcnt(0)
	v_fmamk_f32 v133, v133, 0x3a800000, v224
	v_cmp_gt_f32_e32 vcc, s14, v133
	v_mul_f32_e32 v140, 0x4b800000, v133
	v_lshl_add_u64 v[130:131], s[26:27], 0, v[130:131]
	v_cndmask_b32_e32 v133, v133, v140, vcc
	v_rsq_f32_e32 v133, v133
	v_lshl_add_u64 v[130:131], v[128:129], 1, v[130:131]
	v_lshlrev_b32_e32 v132, 1, v132
	v_lshl_add_u64 v[142:143], v[128:129], 2, s[24:25]
	v_mul_f32_e32 v140, 0x45800000, v133
	v_cndmask_b32_e32 v140, v133, v140, vcc
	v_mov_b32_e32 v133, v193
	v_lshl_add_u64 v[146:147], v[130:131], 0, v[132:133]
	global_load_dwordx4 v[156:159], v[146:147], off
	v_lshlrev_b32_e32 v192, 2, v141
	v_lshl_add_u64 v[130:131], v[142:143], 0, v[192:193]
	v_readlane_b32 s16, v253, 47
	v_readlane_b32 s36, v252, 2
	v_pk_mul_f32 v[112:113], v[112:113], v[140:141] op_sel_hi:[1,0]
	v_pk_mul_f32 v[114:115], v[114:115], v[140:141] op_sel_hi:[1,0]
	v_readlane_b32 s17, v253, 48
	v_readlane_b32 s37, v252, 3
	s_mov_b64 s[14:15], -1
	s_and_b64 vcc, exec, s[16:17]
	v_readlane_b32 s38, v252, 4
	v_readlane_b32 s39, v252, 5
	v_readlane_b32 s40, v252, 6
	v_readlane_b32 s41, v252, 7
	v_readlane_b32 s42, v252, 8
	v_readlane_b32 s43, v252, 9
	s_waitcnt vmcnt(0)
	v_mov_b32_e32 v133, v158
	v_mov_b32_e32 v155, v159
	global_load_dwordx4 v[158:161], v[130:131], off
	v_permlane32_swap_b32_e32 v156, v133
	v_permlane32_swap_b32_e32 v157, v155
	v_lshlrev_b32_e32 v142, 16, v156
	v_and_b32_e32 v143, 0xffff0000, v156
	v_lshlrev_b32_e32 v156, 16, v157
	v_and_b32_e32 v157, 0xffff0000, v157
	s_waitcnt vmcnt(0)
	v_pk_fma_f32 v[112:113], v[158:159], v[112:113], v[142:143]
	v_pk_fma_f32 v[114:115], v[160:161], v[114:115], v[156:157]
	v_lshl_add_u64 v[142:143], v[144:145], 2, s[36:37]
	s_cbranch_vccz .LBB0_846
	v_lshl_add_u64 v[156:157], v[128:129], 2, v[142:143]
	v_lshl_add_u64 v[156:157], v[156:157], 0, v[192:193]
	s_mov_b64 s[14:15], 0
	global_store_dwordx4 v[156:157], v[112:115], off

.LBB0_852:
	v_readlane_b32 s36, v253, 25
	v_readlane_b32 s37, v253, 26
	s_andn2_b64 vcc, exec, s[36:37]
	s_nop 0
	v_cndmask_b32_e64 v133, 0, 1, s[36:37]
	v_cmp_ne_u32_e64 s[14:15], 1, v133
	s_cbranch_vccnz .LBB0_854
	v_cvt_pk_bf16_f32 v112, v112, v113
	v_cvt_pk_bf16_f32 v113, v114, v115
	v_cvt_pk_bf16_f32 v114, v116, v117
	v_cvt_pk_bf16_f32 v115, v118, v119
	s_nop 0
	v_permlane32_swap_b32_e32 v112, v114
	v_permlane32_swap_b32_e32 v113, v115
	global_store_dwordx4 v[146:147], v[112:115], off
.LBB0_854:
	s_nop 1
	v_lshl_add_u64 v[112:113], v[144:145], 1, s[0:1]
	v_lshl_add_u64 v[144:145], v[128:129], 1, v[112:113]
	v_mov_b32_e32 v133, v193
	v_lshl_add_u64 v[146:147], v[144:145], 0, v[132:133]
	v_add_co_u32_e32 v112, vcc, 0x1dc0000, v146
	global_load_dwordx4 v[156:159], v[130:131], off offset:64
	s_nop 0
	v_addc_co_u32_e32 v113, vcc, 0, v147, vcc
	global_load_dwordx4 v[112:115], v[112:113], off offset:32
	s_mov_b64 s[36:37], -1
	s_and_b64 vcc, exec, s[16:17]
	s_waitcnt vmcnt(0) lgkmcnt(0)
	v_mov_b32_e32 v116, v114
	v_mov_b32_e32 v117, v115
	s_nop 0
	v_permlane32_swap_b32_e32 v112, v116
	v_permlane32_swap_b32_e32 v113, v117
	v_lshlrev_b32_e32 v114, 16, v112
	v_and_b32_e32 v115, 0xffff0000, v112
	v_lshlrev_b32_e32 v118, 16, v113
	v_and_b32_e32 v119, 0xffff0000, v113
	v_pk_mul_f32 v[112:113], v[120:121], v[140:141]
	s_nop 0
	v_pk_fma_f32 v[112:113], v[112:113], v[156:157], v[114:115]
	v_pk_mul_f32 v[114:115], v[122:123], v[140:141]
	s_nop 0
	v_pk_fma_f32 v[114:115], v[114:115], v[158:159], v[118:119]
	s_cbranch_vccnz .LBB0_856
	v_lshl_add_u64 v[118:119], v[128:129], 2, v[142:143]
	v_lshl_add_u64 v[118:119], v[118:119], 0, v[192:193]
	s_mov_b64 s[36:37], 0
	global_store_dwordx4 v[118:119], v[112:115], off offset:64

.LBB0_861:
	s_mov_b64 s[36:37], 0x1dc0020
	v_cvt_pk_bf16_f32 v112, v112, v113
	v_cvt_pk_bf16_f32 v113, v114, v115
	v_cvt_pk_bf16_f32 v114, v116, v117
	v_cvt_pk_bf16_f32 v115, v118, v119
	v_lshl_add_u64 v[120:121], v[146:147], 0, s[36:37]
	v_permlane32_swap_b32_e32 v112, v114
	v_permlane32_swap_b32_e32 v113, v115
	global_store_dwordx4 v[120:121], v[112:115], off
.LBB0_862:
	v_mov_b32_e32 v133, v193
	s_nop 0
	v_lshl_add_u64 v[112:113], v[144:145], 0, v[132:133]
	v_add_co_u32_e32 v114, vcc, 0x1dc0000, v112
	v_pk_mul_f32 v[96:97], v[96:97], v[140:141]
	s_nop 0
	v_addc_co_u32_e32 v115, vcc, 0, v113, vcc
	global_load_dwordx4 v[116:119], v[114:115], off offset:64
	v_pk_mul_f32 v[98:99], v[98:99], v[140:141]
	s_mov_b64 s[36:37], -1
	s_and_b64 vcc, exec, s[16:17]
	s_waitcnt vmcnt(0) lgkmcnt(0)
	v_mov_b32_e32 v114, v118
	v_mov_b32_e32 v115, v119
	global_load_dwordx4 v[118:121], v[130:131], off offset:128
	v_permlane32_swap_b32_e32 v116, v114
	v_permlane32_swap_b32_e32 v117, v115
	v_lshlrev_b32_e32 v122, 16, v116
	v_and_b32_e32 v123, 0xffff0000, v116
	v_lshlrev_b32_e32 v116, 16, v117
	v_and_b32_e32 v117, 0xffff0000, v117
	s_waitcnt vmcnt(0)
	v_pk_fma_f32 v[96:97], v[96:97], v[118:119], v[122:123]
	v_pk_fma_f32 v[98:99], v[98:99], v[120:121], v[116:117]
	s_cbranch_vccnz .LBB0_864
	v_lshl_add_u64 v[116:117], v[128:129], 2, v[142:143]
	v_lshl_add_u64 v[116:117], v[116:117], 0, v[192:193]
	s_mov_b64 s[36:37], 0
	global_store_dwordx4 v[116:117], v[96:99], off offset:128

.LBB0_869:
	s_mov_b64 s[36:37], 0x1dc0040
	v_cvt_pk_bf16_f32 v96, v96, v97
	v_cvt_pk_bf16_f32 v97, v98, v99
	v_cvt_pk_bf16_f32 v98, v100, v101
	v_cvt_pk_bf16_f32 v99, v102, v103
	v_lshl_add_u64 v[112:113], v[112:113], 0, s[36:37]
	v_permlane32_swap_b32_e32 v96, v98
	v_permlane32_swap_b32_e32 v97, v99
	global_store_dwordx4 v[112:113], v[96:99], off
.LBB0_870:
	v_mov_b32_e32 v133, v193
	v_lshl_add_u64 v[112:113], v[144:145], 0, v[132:133]
	v_add_co_u32_e32 v96, vcc, 0x1dc0000, v112
	global_load_dwordx4 v[114:117], v[130:131], off offset:192
	s_nop 0
	v_addc_co_u32_e32 v97, vcc, 0, v113, vcc
	global_load_dwordx4 v[96:99], v[96:97], off offset:96
	s_mov_b64 s[36:37], -1
	s_and_b64 vcc, exec, s[16:17]
	s_waitcnt vmcnt(0) lgkmcnt(0)
	v_mov_b32_e32 v100, v98
	v_mov_b32_e32 v101, v99
	s_nop 0
	v_permlane32_swap_b32_e32 v96, v100
	v_permlane32_swap_b32_e32 v97, v101
	v_lshlrev_b32_e32 v98, 16, v96
	v_and_b32_e32 v99, 0xffff0000, v96
	v_lshlrev_b32_e32 v102, 16, v97
	v_and_b32_e32 v103, 0xffff0000, v97
	v_pk_mul_f32 v[96:97], v[104:105], v[140:141]
	s_nop 0
	v_pk_fma_f32 v[96:97], v[96:97], v[114:115], v[98:99]
	v_pk_mul_f32 v[98:99], v[106:107], v[140:141]
	s_nop 0
	v_pk_fma_f32 v[98:99], v[98:99], v[116:117], v[102:103]
	s_cbranch_vccnz .LBB0_872
	v_lshl_add_u64 v[102:103], v[128:129], 2, v[142:143]
	v_lshl_add_u64 v[102:103], v[102:103], 0, v[192:193]
	s_mov_b64 s[36:37], 0
	global_store_dwordx4 v[102:103], v[96:99], off offset:192

.LBB0_877:
	s_mov_b64 s[36:37], 0x1dc0060
	v_cvt_pk_bf16_f32 v96, v96, v97
	v_cvt_pk_bf16_f32 v97, v98, v99
	v_cvt_pk_bf16_f32 v98, v100, v101
	v_cvt_pk_bf16_f32 v99, v102, v103
	v_lshl_add_u64 v[104:105], v[112:113], 0, s[36:37]
	v_permlane32_swap_b32_e32 v96, v98
	v_permlane32_swap_b32_e32 v97, v99
	global_store_dwordx4 v[104:105], v[96:99], off
.LBB0_878:
	s_nop 1
	v_lshlrev_b64 v[98:99], 11, v[138:139]
	v_lshl_add_u64 v[98:99], s[26:27], 0, v[98:99]
	v_lshl_add_u64 v[98:99], v[128:129], 1, v[98:99]
	v_mov_b32_e32 v133, v193
	v_lshl_add_u64 v[102:103], v[98:99], 0, v[132:133]
	global_load_dwordx4 v[108:111], v[102:103], off
	ds_read_b32 v96, v154 offset:2176
	s_mov_b32 s31, 0x800000
	v_readlane_b32 s40, v252, 2
	v_lshlrev_b64 v[100:101], 10, v[138:139]
	v_readlane_b32 s41, v252, 3
	s_waitcnt lgkmcnt(0)
	v_fmamk_f32 v96, v96, 0x3a800000, v224
	v_cmp_gt_f32_e32 vcc, s31, v96
	v_mul_f32_e32 v97, 0x4b800000, v96
	s_mov_b64 s[36:37], -1
	v_cndmask_b32_e32 v96, v96, v97, vcc
	v_rsq_f32_e32 v96, v96
	v_readlane_b32 s42, v252, 4
	v_readlane_b32 s43, v252, 5
	v_readlane_b32 s44, v252, 6
	v_mul_f32_e32 v97, 0x45800000, v96
	v_cndmask_b32_e32 v96, v96, v97, vcc
	v_pk_mul_f32 v[80:81], v[80:81], v[96:97] op_sel_hi:[1,0]
	v_pk_mul_f32 v[82:83], v[82:83], v[96:97] op_sel_hi:[1,0]
	s_and_b64 vcc, exec, s[16:17]
	v_readlane_b32 s45, v252, 7
	v_readlane_b32 s46, v252, 8
	v_readlane_b32 s47, v252, 9
	s_waitcnt vmcnt(0)
	v_mov_b32_e32 v105, v110
	v_mov_b32_e32 v106, v111
	global_load_dwordx4 v[110:113], v[130:131], off
	v_permlane32_swap_b32_e32 v108, v105
	v_permlane32_swap_b32_e32 v109, v106
	v_lshlrev_b32_e32 v98, 16, v108
	v_and_b32_e32 v99, 0xffff0000, v108
	v_lshlrev_b32_e32 v108, 16, v109
	v_and_b32_e32 v109, 0xffff0000, v109
	s_waitcnt vmcnt(0)
	v_pk_fma_f32 v[80:81], v[110:111], v[80:81], v[98:99]
	v_pk_fma_f32 v[82:83], v[112:113], v[82:83], v[108:109]
	v_lshl_add_u64 v[98:99], v[100:101], 2, s[40:41]
	s_cbranch_vccnz .LBB0_880
	v_lshl_add_u64 v[108:109], v[128:129], 2, v[98:99]
	v_lshl_add_u64 v[108:109], v[108:109], 0, v[192:193]
	s_mov_b64 s[36:37], 0
	global_store_dwordx4 v[108:109], v[80:83], off

.LBB0_885:
	v_cvt_pk_bf16_f32 v80, v80, v81
	v_cvt_pk_bf16_f32 v81, v82, v83
	v_cvt_pk_bf16_f32 v82, v84, v85
	v_cvt_pk_bf16_f32 v83, v86, v87
	s_nop 0
	v_permlane32_swap_b32_e32 v80, v82
	v_permlane32_swap_b32_e32 v81, v83
	global_store_dwordx4 v[102:103], v[80:83], off
.LBB0_886:
	s_nop 1
	v_lshl_add_u64 v[80:81], v[100:101], 1, s[0:1]
	v_lshl_add_u64 v[100:101], v[128:129], 1, v[80:81]
	v_mov_b32_e32 v133, v193
	v_lshl_add_u64 v[102:103], v[100:101], 0, v[132:133]
	v_add_co_u32_e32 v80, vcc, 0x1dc0000, v102
	global_load_dwordx4 v[106:109], v[130:131], off offset:64
	s_nop 0
	v_addc_co_u32_e32 v81, vcc, 0, v103, vcc
	global_load_dwordx4 v[80:83], v[80:81], off offset:32
	s_mov_b64 s[36:37], -1
	s_and_b64 vcc, exec, s[16:17]
	s_waitcnt vmcnt(0) lgkmcnt(0)
	v_mov_b32_e32 v84, v82
	v_mov_b32_e32 v85, v83
	s_nop 0
	v_permlane32_swap_b32_e32 v80, v84
	v_permlane32_swap_b32_e32 v81, v85
	v_lshlrev_b32_e32 v82, 16, v80
	v_and_b32_e32 v83, 0xffff0000, v80
	v_lshlrev_b32_e32 v86, 16, v81
	v_and_b32_e32 v87, 0xffff0000, v81
	v_pk_mul_f32 v[80:81], v[88:89], v[96:97]
	s_nop 0
	v_pk_fma_f32 v[80:81], v[80:81], v[106:107], v[82:83]
	v_pk_mul_f32 v[82:83], v[90:91], v[96:97]
	s_nop 0
	v_pk_fma_f32 v[82:83], v[82:83], v[108:109], v[86:87]
	s_cbranch_vccnz .LBB0_888
	v_lshl_add_u64 v[86:87], v[128:129], 2, v[98:99]
	v_lshl_add_u64 v[86:87], v[86:87], 0, v[192:193]
	s_mov_b64 s[36:37], 0
	global_store_dwordx4 v[86:87], v[80:83], off offset:64

.LBB0_893:
	s_mov_b64 s[36:37], 0x1dc0020
	v_cvt_pk_bf16_f32 v80, v80, v81
	v_cvt_pk_bf16_f32 v81, v82, v83
	v_cvt_pk_bf16_f32 v82, v84, v85
	v_cvt_pk_bf16_f32 v83, v86, v87
	v_lshl_add_u64 v[88:89], v[102:103], 0, s[36:37]
	v_permlane32_swap_b32_e32 v80, v82
	v_permlane32_swap_b32_e32 v81, v83
	global_store_dwordx4 v[88:89], v[80:83], off
.LBB0_894:
	v_mov_b32_e32 v133, v193
	s_nop 0
	v_lshl_add_u64 v[80:81], v[100:101], 0, v[132:133]
	v_add_co_u32_e32 v82, vcc, 0x1dc0000, v80
	v_pk_mul_f32 v[64:65], v[64:65], v[96:97]
	s_nop 0
	v_addc_co_u32_e32 v83, vcc, 0, v81, vcc
	global_load_dwordx4 v[84:87], v[82:83], off offset:64
	v_pk_mul_f32 v[66:67], v[66:67], v[96:97]
	s_mov_b64 s[36:37], -1
	s_and_b64 vcc, exec, s[16:17]
	s_waitcnt vmcnt(0) lgkmcnt(0)
	v_mov_b32_e32 v82, v86
	v_mov_b32_e32 v83, v87
	global_load_dwordx4 v[86:89], v[130:131], off offset:128
	v_permlane32_swap_b32_e32 v84, v82
	v_permlane32_swap_b32_e32 v85, v83
	v_lshlrev_b32_e32 v90, 16, v84
	v_and_b32_e32 v91, 0xffff0000, v84
	v_lshlrev_b32_e32 v84, 16, v85
	v_and_b32_e32 v85, 0xffff0000, v85
	s_waitcnt vmcnt(0)
	v_pk_fma_f32 v[64:65], v[64:65], v[86:87], v[90:91]
	v_pk_fma_f32 v[66:67], v[66:67], v[88:89], v[84:85]
	s_cbranch_vccnz .LBB0_896
	v_lshl_add_u64 v[84:85], v[128:129], 2, v[98:99]
	v_lshl_add_u64 v[84:85], v[84:85], 0, v[192:193]
	s_mov_b64 s[36:37], 0
	global_store_dwordx4 v[84:85], v[64:67], off offset:128

.LBB0_901:
	s_mov_b64 s[36:37], 0x1dc0040
	v_cvt_pk_bf16_f32 v64, v64, v65
	v_cvt_pk_bf16_f32 v65, v66, v67
	v_cvt_pk_bf16_f32 v66, v68, v69
	v_cvt_pk_bf16_f32 v67, v70, v71
	v_lshl_add_u64 v[80:81], v[80:81], 0, s[36:37]
	v_permlane32_swap_b32_e32 v64, v66
	v_permlane32_swap_b32_e32 v65, v67
	global_store_dwordx4 v[80:81], v[64:67], off
.LBB0_902:
	v_mov_b32_e32 v133, v193
	v_lshl_add_u64 v[80:81], v[100:101], 0, v[132:133]
	v_add_co_u32_e32 v64, vcc, 0x1dc0000, v80
	global_load_dwordx4 v[82:85], v[130:131], off offset:192
	s_nop 0
	v_addc_co_u32_e32 v65, vcc, 0, v81, vcc
	global_load_dwordx4 v[64:67], v[64:65], off offset:96
	s_mov_b64 s[36:37], -1
	s_and_b64 vcc, exec, s[16:17]
	s_waitcnt vmcnt(0) lgkmcnt(0)
	v_mov_b32_e32 v68, v66
	v_mov_b32_e32 v69, v67
	s_nop 0
	v_permlane32_swap_b32_e32 v64, v68
	v_permlane32_swap_b32_e32 v65, v69
	v_lshlrev_b32_e32 v66, 16, v64
	v_and_b32_e32 v67, 0xffff0000, v64
	v_lshlrev_b32_e32 v70, 16, v65
	v_and_b32_e32 v71, 0xffff0000, v65
	v_pk_mul_f32 v[64:65], v[72:73], v[96:97]
	s_nop 0
	v_pk_fma_f32 v[64:65], v[64:65], v[82:83], v[66:67]
	v_pk_mul_f32 v[66:67], v[74:75], v[96:97]
	s_nop 0
	v_pk_fma_f32 v[66:67], v[66:67], v[84:85], v[70:71]
	s_cbranch_vccnz .LBB0_904
	v_lshl_add_u64 v[70:71], v[128:129], 2, v[98:99]
	v_lshl_add_u64 v[70:71], v[70:71], 0, v[192:193]
	s_mov_b64 s[36:37], 0
	global_store_dwordx4 v[70:71], v[64:67], off offset:192

.LBB0_909:
	s_mov_b64 s[36:37], 0x1dc0060
	v_cvt_pk_bf16_f32 v64, v64, v65
	v_cvt_pk_bf16_f32 v65, v66, v67
	v_cvt_pk_bf16_f32 v66, v68, v69
	v_cvt_pk_bf16_f32 v67, v70, v71
	v_lshl_add_u64 v[72:73], v[80:81], 0, s[36:37]
	v_permlane32_swap_b32_e32 v64, v66
	v_permlane32_swap_b32_e32 v65, v67
	global_store_dwordx4 v[72:73], v[64:67], off
.LBB0_910:
	s_nop 1
	v_lshlrev_b64 v[66:67], 11, v[136:137]
	v_lshl_add_u64 v[66:67], s[26:27], 0, v[66:67]
	v_lshl_add_u64 v[66:67], v[128:129], 1, v[66:67]
	v_mov_b32_e32 v133, v193
	v_lshl_add_u64 v[70:71], v[66:67], 0, v[132:133]
	global_load_dwordx4 v[76:79], v[70:71], off
	ds_read_b32 v64, v154 offset:2304
	v_readlane_b32 s40, v252, 2
	v_lshlrev_b64 v[68:69], 10, v[136:137]
	v_readlane_b32 s41, v252, 3
	s_mov_b64 s[36:37], -1
	s_waitcnt lgkmcnt(0)
	v_fmamk_f32 v64, v64, 0x3a800000, v224
	v_cmp_gt_f32_e32 vcc, s31, v64
	v_mul_f32_e32 v65, 0x4b800000, v64
	v_readlane_b32 s42, v252, 4
	v_cndmask_b32_e32 v64, v64, v65, vcc
	v_rsq_f32_e32 v64, v64
	v_readlane_b32 s43, v252, 5
	v_readlane_b32 s44, v252, 6
	v_readlane_b32 s45, v252, 7
	v_mul_f32_e32 v65, 0x45800000, v64
	v_cndmask_b32_e32 v64, v64, v65, vcc
	v_pk_mul_f32 v[48:49], v[48:49], v[64:65] op_sel_hi:[1,0]
	v_pk_mul_f32 v[50:51], v[50:51], v[64:65] op_sel_hi:[1,0]
	s_and_b64 vcc, exec, s[16:17]
	v_readlane_b32 s46, v252, 8
	v_readlane_b32 s47, v252, 9
	s_waitcnt vmcnt(0)
	v_mov_b32_e32 v73, v78
	v_mov_b32_e32 v74, v79
	global_load_dwordx4 v[78:81], v[130:131], off
	v_permlane32_swap_b32_e32 v76, v73
	v_permlane32_swap_b32_e32 v77, v74
	v_lshlrev_b32_e32 v66, 16, v76
	v_and_b32_e32 v67, 0xffff0000, v76
	v_lshlrev_b32_e32 v76, 16, v77
	v_and_b32_e32 v77, 0xffff0000, v77
	s_waitcnt vmcnt(0)
	v_pk_fma_f32 v[48:49], v[78:79], v[48:49], v[66:67]
	v_pk_fma_f32 v[50:51], v[80:81], v[50:51], v[76:77]
	v_lshl_add_u64 v[66:67], v[68:69], 2, s[40:41]
	s_cbranch_vccnz .LBB0_912
	v_lshl_add_u64 v[76:77], v[128:129], 2, v[66:67]
	v_lshl_add_u64 v[76:77], v[76:77], 0, v[192:193]
	s_mov_b64 s[36:37], 0
	global_store_dwordx4 v[76:77], v[48:51], off

.LBB0_917:
	v_cvt_pk_bf16_f32 v48, v48, v49
	v_cvt_pk_bf16_f32 v49, v50, v51
	v_cvt_pk_bf16_f32 v50, v52, v53
	v_cvt_pk_bf16_f32 v51, v54, v55
	s_nop 0
	v_permlane32_swap_b32_e32 v48, v50
	v_permlane32_swap_b32_e32 v49, v51
	global_store_dwordx4 v[70:71], v[48:51], off
.LBB0_918:
	s_nop 1
	v_lshl_add_u64 v[48:49], v[68:69], 1, s[0:1]
	v_lshl_add_u64 v[68:69], v[128:129], 1, v[48:49]
	v_mov_b32_e32 v133, v193
	v_lshl_add_u64 v[70:71], v[68:69], 0, v[132:133]
	v_add_co_u32_e32 v48, vcc, 0x1dc0000, v70
	global_load_dwordx4 v[74:77], v[130:131], off offset:64
	s_nop 0
	v_addc_co_u32_e32 v49, vcc, 0, v71, vcc
	global_load_dwordx4 v[48:51], v[48:49], off offset:32
	s_mov_b64 s[36:37], -1
	s_and_b64 vcc, exec, s[16:17]
	s_waitcnt vmcnt(0) lgkmcnt(0)
	v_mov_b32_e32 v52, v50
	v_mov_b32_e32 v53, v51
	s_nop 0
	v_permlane32_swap_b32_e32 v48, v52
	v_permlane32_swap_b32_e32 v49, v53
	v_lshlrev_b32_e32 v50, 16, v48
	v_and_b32_e32 v51, 0xffff0000, v48
	v_lshlrev_b32_e32 v54, 16, v49
	v_and_b32_e32 v55, 0xffff0000, v49
	v_pk_mul_f32 v[48:49], v[56:57], v[64:65]
	s_nop 0
	v_pk_fma_f32 v[48:49], v[48:49], v[74:75], v[50:51]
	v_pk_mul_f32 v[50:51], v[58:59], v[64:65]
	s_nop 0
	v_pk_fma_f32 v[50:51], v[50:51], v[76:77], v[54:55]
	s_cbranch_vccnz .LBB0_920
	v_lshl_add_u64 v[54:55], v[128:129], 2, v[66:67]
	v_lshl_add_u64 v[54:55], v[54:55], 0, v[192:193]
	s_mov_b64 s[36:37], 0
	global_store_dwordx4 v[54:55], v[48:51], off offset:64

.LBB0_925:
	s_mov_b64 s[36:37], 0x1dc0020
	v_cvt_pk_bf16_f32 v48, v48, v49
	v_cvt_pk_bf16_f32 v49, v50, v51
	v_cvt_pk_bf16_f32 v50, v52, v53
	v_cvt_pk_bf16_f32 v51, v54, v55
	v_lshl_add_u64 v[56:57], v[70:71], 0, s[36:37]
	v_permlane32_swap_b32_e32 v48, v50
	v_permlane32_swap_b32_e32 v49, v51
	global_store_dwordx4 v[56:57], v[48:51], off
.LBB0_926:
	v_mov_b32_e32 v133, v193
	s_nop 0
	v_lshl_add_u64 v[48:49], v[68:69], 0, v[132:133]
	v_add_co_u32_e32 v50, vcc, 0x1dc0000, v48
	v_pk_mul_f32 v[32:33], v[32:33], v[64:65]
	s_nop 0
	v_addc_co_u32_e32 v51, vcc, 0, v49, vcc
	global_load_dwordx4 v[52:55], v[50:51], off offset:64
	v_pk_mul_f32 v[34:35], v[34:35], v[64:65]
	s_mov_b64 s[36:37], -1
	s_and_b64 vcc, exec, s[16:17]
	s_waitcnt vmcnt(0) lgkmcnt(0)
	v_mov_b32_e32 v50, v54
	v_mov_b32_e32 v51, v55
	global_load_dwordx4 v[54:57], v[130:131], off offset:128
	v_permlane32_swap_b32_e32 v52, v50
	v_permlane32_swap_b32_e32 v53, v51
	v_lshlrev_b32_e32 v58, 16, v52
	v_and_b32_e32 v59, 0xffff0000, v52
	v_lshlrev_b32_e32 v52, 16, v53
	v_and_b32_e32 v53, 0xffff0000, v53
	s_waitcnt vmcnt(0)
	v_pk_fma_f32 v[32:33], v[32:33], v[54:55], v[58:59]
	v_pk_fma_f32 v[34:35], v[34:35], v[56:57], v[52:53]
	s_cbranch_vccnz .LBB0_928
	v_lshl_add_u64 v[52:53], v[128:129], 2, v[66:67]
	v_lshl_add_u64 v[52:53], v[52:53], 0, v[192:193]
	s_mov_b64 s[36:37], 0
	global_store_dwordx4 v[52:53], v[32:35], off offset:128

.LBB0_933:
	s_mov_b64 s[36:37], 0x1dc0040
	v_cvt_pk_bf16_f32 v32, v32, v33
	v_cvt_pk_bf16_f32 v33, v34, v35
	v_cvt_pk_bf16_f32 v34, v36, v37
	v_cvt_pk_bf16_f32 v35, v38, v39
	v_lshl_add_u64 v[48:49], v[48:49], 0, s[36:37]
	v_permlane32_swap_b32_e32 v32, v34
	v_permlane32_swap_b32_e32 v33, v35
	global_store_dwordx4 v[48:49], v[32:35], off
.LBB0_934:
	v_mov_b32_e32 v133, v193
	v_lshl_add_u64 v[48:49], v[68:69], 0, v[132:133]
	v_add_co_u32_e32 v32, vcc, 0x1dc0000, v48
	global_load_dwordx4 v[50:53], v[130:131], off offset:192
	s_nop 0
	v_addc_co_u32_e32 v33, vcc, 0, v49, vcc
	global_load_dwordx4 v[32:35], v[32:33], off offset:96
	s_mov_b64 s[36:37], -1
	s_and_b64 vcc, exec, s[16:17]
	s_waitcnt vmcnt(0) lgkmcnt(0)
	v_mov_b32_e32 v36, v34
	v_mov_b32_e32 v37, v35
	s_nop 0
	v_permlane32_swap_b32_e32 v32, v36
	v_permlane32_swap_b32_e32 v33, v37
	v_lshlrev_b32_e32 v34, 16, v32
	v_and_b32_e32 v35, 0xffff0000, v32
	v_lshlrev_b32_e32 v38, 16, v33
	v_and_b32_e32 v39, 0xffff0000, v33
	v_pk_mul_f32 v[32:33], v[40:41], v[64:65]
	s_nop 0
	v_pk_fma_f32 v[32:33], v[32:33], v[50:51], v[34:35]
	v_pk_mul_f32 v[34:35], v[42:43], v[64:65]
	s_nop 0
	v_pk_fma_f32 v[34:35], v[34:35], v[52:53], v[38:39]
	s_cbranch_vccnz .LBB0_936
	v_lshl_add_u64 v[38:39], v[128:129], 2, v[66:67]
	v_lshl_add_u64 v[38:39], v[38:39], 0, v[192:193]
	s_mov_b64 s[36:37], 0
	global_store_dwordx4 v[38:39], v[32:35], off offset:192

.LBB0_941:
	s_mov_b64 s[36:37], 0x1dc0060
	v_cvt_pk_bf16_f32 v32, v32, v33
	v_cvt_pk_bf16_f32 v33, v34, v35
	v_cvt_pk_bf16_f32 v34, v36, v37
	v_cvt_pk_bf16_f32 v35, v38, v39
	v_lshl_add_u64 v[40:41], v[48:49], 0, s[36:37]
	v_permlane32_swap_b32_e32 v32, v34
	v_permlane32_swap_b32_e32 v33, v35
	global_store_dwordx4 v[40:41], v[32:35], off
.LBB0_942:
	s_nop 1
	v_lshlrev_b64 v[34:35], 11, v[134:135]
	v_lshl_add_u64 v[34:35], s[26:27], 0, v[34:35]
	v_lshl_add_u64 v[34:35], v[128:129], 1, v[34:35]
	v_mov_b32_e32 v133, v193
	v_lshl_add_u64 v[38:39], v[34:35], 0, v[132:133]
	global_load_dwordx4 v[44:47], v[38:39], off
	ds_read_b32 v32, v154 offset:2432
	v_readlane_b32 s40, v252, 2
	v_lshlrev_b64 v[36:37], 10, v[134:135]
	v_readlane_b32 s41, v252, 3
	s_mov_b64 s[36:37], -1
	s_waitcnt lgkmcnt(0)
	v_fmamk_f32 v32, v32, 0x3a800000, v224
	v_cmp_gt_f32_e32 vcc, s31, v32
	v_mul_f32_e32 v33, 0x4b800000, v32
	v_readlane_b32 s42, v252, 4
	v_cndmask_b32_e32 v32, v32, v33, vcc
	v_rsq_f32_e32 v32, v32
	v_readlane_b32 s43, v252, 5
	v_readlane_b32 s44, v252, 6
	v_readlane_b32 s45, v252, 7
	v_mul_f32_e32 v33, 0x45800000, v32
	v_cndmask_b32_e32 v32, v32, v33, vcc
	v_pk_mul_f32 v[16:17], v[16:17], v[32:33] op_sel_hi:[1,0]
	v_pk_mul_f32 v[18:19], v[18:19], v[32:33] op_sel_hi:[1,0]
	s_and_b64 vcc, exec, s[16:17]
	v_readlane_b32 s46, v252, 8
	v_readlane_b32 s47, v252, 9
	s_waitcnt vmcnt(0)
	v_mov_b32_e32 v41, v46
	v_mov_b32_e32 v42, v47
	global_load_dwordx4 v[46:49], v[130:131], off
	v_permlane32_swap_b32_e32 v44, v41
	v_permlane32_swap_b32_e32 v45, v42
	v_lshlrev_b32_e32 v34, 16, v44
	v_and_b32_e32 v35, 0xffff0000, v44
	v_lshlrev_b32_e32 v44, 16, v45
	v_and_b32_e32 v45, 0xffff0000, v45
	s_waitcnt vmcnt(0)
	v_pk_fma_f32 v[16:17], v[46:47], v[16:17], v[34:35]
	v_pk_fma_f32 v[18:19], v[48:49], v[18:19], v[44:45]
	v_lshl_add_u64 v[34:35], v[36:37], 2, s[40:41]
	s_cbranch_vccnz .LBB0_944
	v_lshl_add_u64 v[44:45], v[128:129], 2, v[34:35]
	v_lshl_add_u64 v[44:45], v[44:45], 0, v[192:193]
	s_mov_b64 s[36:37], 0
	global_store_dwordx4 v[44:45], v[16:19], off

.LBB0_949:
	v_cvt_pk_bf16_f32 v16, v16, v17
	v_cvt_pk_bf16_f32 v17, v18, v19
	v_cvt_pk_bf16_f32 v18, v20, v21
	v_cvt_pk_bf16_f32 v19, v22, v23
	s_nop 0
	v_permlane32_swap_b32_e32 v16, v18
	v_permlane32_swap_b32_e32 v17, v19
	global_store_dwordx4 v[38:39], v[16:19], off
.LBB0_950:
	s_nop 1
	v_lshl_add_u64 v[16:17], v[36:37], 1, s[0:1]
	v_lshl_add_u64 v[36:37], v[128:129], 1, v[16:17]
	v_mov_b32_e32 v133, v193
	v_lshl_add_u64 v[38:39], v[36:37], 0, v[132:133]
	v_add_co_u32_e32 v16, vcc, 0x1dc0000, v38
	global_load_dwordx4 v[42:45], v[130:131], off offset:64
	s_nop 0
	v_addc_co_u32_e32 v17, vcc, 0, v39, vcc
	global_load_dwordx4 v[16:19], v[16:17], off offset:32
	s_mov_b64 s[36:37], -1
	s_and_b64 vcc, exec, s[16:17]
	s_waitcnt vmcnt(0) lgkmcnt(0)
	v_mov_b32_e32 v20, v18
	v_mov_b32_e32 v21, v19
	s_nop 0
	v_permlane32_swap_b32_e32 v16, v20
	v_permlane32_swap_b32_e32 v17, v21
	v_lshlrev_b32_e32 v18, 16, v16
	v_and_b32_e32 v19, 0xffff0000, v16
	v_lshlrev_b32_e32 v22, 16, v17
	v_and_b32_e32 v23, 0xffff0000, v17
	v_pk_mul_f32 v[16:17], v[24:25], v[32:33]
	s_nop 0
	v_pk_fma_f32 v[16:17], v[16:17], v[42:43], v[18:19]
	v_pk_mul_f32 v[18:19], v[26:27], v[32:33]
	s_nop 0
	v_pk_fma_f32 v[18:19], v[18:19], v[44:45], v[22:23]
	s_cbranch_vccnz .LBB0_952
	v_lshl_add_u64 v[22:23], v[128:129], 2, v[34:35]
	v_lshl_add_u64 v[22:23], v[22:23], 0, v[192:193]
	s_mov_b64 s[36:37], 0
	global_store_dwordx4 v[22:23], v[16:19], off offset:64

.LBB0_957:
	s_mov_b64 s[36:37], 0x1dc0020
	v_cvt_pk_bf16_f32 v16, v16, v17
	v_cvt_pk_bf16_f32 v17, v18, v19
	v_cvt_pk_bf16_f32 v18, v20, v21
	v_cvt_pk_bf16_f32 v19, v22, v23
	v_lshl_add_u64 v[24:25], v[38:39], 0, s[36:37]
	v_permlane32_swap_b32_e32 v16, v18
	v_permlane32_swap_b32_e32 v17, v19
	global_store_dwordx4 v[24:25], v[16:19], off
.LBB0_958:
	v_mov_b32_e32 v133, v193
	s_nop 0
	v_lshl_add_u64 v[16:17], v[36:37], 0, v[132:133]
	v_add_co_u32_e32 v18, vcc, 0x1dc0000, v16
	v_pk_mul_f32 v[0:1], v[0:1], v[32:33]
	s_nop 0
	v_addc_co_u32_e32 v19, vcc, 0, v17, vcc
	global_load_dwordx4 v[20:23], v[18:19], off offset:64
	v_pk_mul_f32 v[2:3], v[2:3], v[32:33]
	s_mov_b64 s[36:37], -1
	s_and_b64 vcc, exec, s[16:17]
	s_waitcnt vmcnt(0) lgkmcnt(0)
	v_mov_b32_e32 v18, v22
	v_mov_b32_e32 v19, v23
	global_load_dwordx4 v[22:25], v[130:131], off offset:128
	v_permlane32_swap_b32_e32 v20, v18
	v_permlane32_swap_b32_e32 v21, v19
	v_lshlrev_b32_e32 v26, 16, v20
	v_and_b32_e32 v27, 0xffff0000, v20
	v_lshlrev_b32_e32 v20, 16, v21
	v_and_b32_e32 v21, 0xffff0000, v21
	s_waitcnt vmcnt(0)
	v_pk_fma_f32 v[0:1], v[0:1], v[22:23], v[26:27]
	v_pk_fma_f32 v[2:3], v[2:3], v[24:25], v[20:21]
	s_cbranch_vccnz .LBB0_960
	v_lshl_add_u64 v[20:21], v[128:129], 2, v[34:35]
	v_lshl_add_u64 v[20:21], v[20:21], 0, v[192:193]
	s_mov_b64 s[36:37], 0
	global_store_dwordx4 v[20:21], v[0:3], off offset:128

.LBB0_965:
	s_mov_b64 s[36:37], 0x1dc0040
	v_cvt_pk_bf16_f32 v0, v0, v1
	v_cvt_pk_bf16_f32 v1, v2, v3
	v_cvt_pk_bf16_f32 v2, v4, v5
	v_cvt_pk_bf16_f32 v3, v6, v7
	v_lshl_add_u64 v[16:17], v[16:17], 0, s[36:37]
	v_permlane32_swap_b32_e32 v0, v2
	v_permlane32_swap_b32_e32 v1, v3
	global_store_dwordx4 v[16:17], v[0:3], off
.LBB0_966:
	v_mov_b32_e32 v133, v193
	v_lshl_add_u64 v[16:17], v[36:37], 0, v[132:133]
	v_add_co_u32_e32 v0, vcc, 0x1dc0000, v16
	global_load_dwordx4 v[18:21], v[130:131], off offset:192
	s_nop 0
	v_addc_co_u32_e32 v1, vcc, 0, v17, vcc
	global_load_dwordx4 v[0:3], v[0:1], off offset:96
	s_mov_b64 s[36:37], -1
	s_and_b64 vcc, exec, s[16:17]
	s_waitcnt vmcnt(0) lgkmcnt(0)
	v_mov_b32_e32 v4, v2
	v_mov_b32_e32 v5, v3
	s_nop 0
	v_permlane32_swap_b32_e32 v0, v4
	v_permlane32_swap_b32_e32 v1, v5
	v_lshlrev_b32_e32 v2, 16, v0
	v_and_b32_e32 v3, 0xffff0000, v0
	v_lshlrev_b32_e32 v6, 16, v1
	v_and_b32_e32 v7, 0xffff0000, v1
	v_pk_mul_f32 v[0:1], v[8:9], v[32:33]
	s_nop 0
	v_pk_fma_f32 v[0:1], v[0:1], v[18:19], v[2:3]
	v_pk_mul_f32 v[2:3], v[10:11], v[32:33]
	s_nop 0
	v_pk_fma_f32 v[2:3], v[2:3], v[20:21], v[6:7]
	s_cbranch_vccnz .LBB0_968
	v_lshl_add_u64 v[6:7], v[128:129], 2, v[34:35]
	v_lshl_add_u64 v[6:7], v[6:7], 0, v[192:193]
	s_mov_b64 s[36:37], 0
	global_store_dwordx4 v[6:7], v[0:3], off offset:192

.LBB0_973:
	s_mov_b64 s[16:17], 0x1dc0060
	v_cvt_pk_bf16_f32 v0, v0, v1
	v_cvt_pk_bf16_f32 v1, v2, v3
	v_cvt_pk_bf16_f32 v2, v4, v5
	v_cvt_pk_bf16_f32 v3, v6, v7
	v_lshl_add_u64 v[8:9], v[16:17], 0, s[16:17]
	v_permlane32_swap_b32_e32 v0, v2
	v_permlane32_swap_b32_e32 v1, v3
	global_store_dwordx4 v[8:9], v[0:3], off

.LBB0_983:
	s_or_b64 exec, exec, s[14:15]
	s_mov_b64 s[14:15], 0x3e38aa3b
	s_add_i32 s8, s34, s18
	s_mov_b32 s9, s15
	s_lshl_b64 s[8:9], s[8:9], 11
	s_add_u32 s8, s56, s8
	s_addc_u32 s9, s57, s9
	s_waitcnt lgkmcnt(0)
	s_barrier
	s_and_saveexec_b64 s[14:15], s[10:11]
	s_xor_b64 s[14:15], exec, s[14:15]
	s_cbranch_execz .LBB0_985
	ds_read2st64_b32 v[0:1], v150 offset1:2
	ds_read2st64_b32 v[2:3], v150 offset0:4 offset1:6
	s_lshl_b32 s16, s61, 7
	s_ashr_i32 s17, s16, 31
	s_lshl_b64 s[16:17], s[16:17], 2
	s_waitcnt lgkmcnt(1)
	v_mov_b32_e32 v4, v0
	s_waitcnt lgkmcnt(0)
	v_mov_b32_e32 v5, v2
	v_mov_b32_e32 v2, v1
	s_add_u32 s16, s8, s16
	v_pk_add_f32 v[0:1], v[4:5], v[2:3]
	s_addc_u32 s17, s9, s17
	v_pk_add_f32 v[0:1], v[0:1], v[0:1] op_sel:[0,1] op_sel_hi:[1,0]
	v_lshl_add_u64 v[2:3], v[152:153], 2, s[16:17]
	global_store_dword v[2:3], v0, off sc1
.LBB0_985:
	s_or_b64 exec, exec, s[14:15]
	s_waitcnt vmcnt(0)
	s_waitcnt lgkmcnt(0)
	s_barrier
	s_and_saveexec_b64 s[14:15], s[12:13]
	s_cbranch_execz .LBB0_1029
	s_lshl_b64 s[12:13], s[34:35], 2
	s_add_u32 s12, s19, s12
	s_addc_u32 s13, s59, s13
	v_mov_b64_e32 v[0:1], s[12:13]
	global_atomic_add v[0:1], v251, off
	s_mov_b32 s31, 0x400001
	s_mov_b64 s[16:17], 0
	s_branch .LBB0_1022

.LBB0_1022:
	v_mov_b64_e32 v[0:1], s[12:13]
	global_load_dword v0, v[0:1], off sc1
	s_or_b64 s[34:35], s[34:35], exec
	s_waitcnt vmcnt(0) lgkmcnt(0)
	v_cmp_gt_u32_e32 vcc, 4, v0
	s_and_saveexec_b64 s[36:37], vcc
	s_cbranch_execz .LBB0_1021
	v_mov_b64_e32 v[0:1], s[12:13]
	s_sleep 1
	global_load_dword v0, v[0:1], off sc1
	s_mov_b64 s[40:41], -1
	s_waitcnt vmcnt(0) lgkmcnt(0)
	v_cmp_gt_u32_e32 vcc, 4, v0
	s_and_saveexec_b64 s[38:39], vcc
	s_cbranch_execz .LBB0_1020
	v_mov_b64_e32 v[0:1], s[12:13]
	s_sleep 1
	global_load_dword v0, v[0:1], off sc1
	s_mov_b64 s[42:43], -1
	s_waitcnt vmcnt(0) lgkmcnt(0)
	v_cmp_gt_u32_e32 vcc, 4, v0
	s_and_saveexec_b64 s[40:41], vcc
	s_cbranch_execz .LBB0_1019
	v_mov_b64_e32 v[0:1], s[12:13]
	s_sleep 1
	global_load_dword v0, v[0:1], off sc1
	s_mov_b64 s[44:45], -1
	s_waitcnt vmcnt(0) lgkmcnt(0)
	v_cmp_gt_u32_e32 vcc, 4, v0
	s_and_saveexec_b64 s[42:43], vcc
	s_cbranch_execz .LBB0_1018
	v_mov_b64_e32 v[0:1], s[12:13]
	s_sleep 1
	global_load_dword v0, v[0:1], off sc1
	s_waitcnt vmcnt(0) lgkmcnt(0)
	v_cmp_gt_u32_e32 vcc, 4, v0
	s_and_saveexec_b64 s[46:47], vcc
	s_cbranch_execz .LBB0_1017
	s_add_i32 s31, s31, -5
	s_cmp_eq_u32 s31, 0
	s_cselect_b64 s[44:45], -1, 0
	s_orn2_b64 s[44:45], s[44:45], exec
	s_sleep 1
	s_branch .LBB0_1017

.LBB0_1029:
	s_or_b64 exec, exec, s[14:15]
	s_barrier
	s_and_saveexec_b64 s[12:13], s[10:11]
	s_cbranch_execz .LBB0_1031
	v_lshl_add_u64 v[0:1], v[152:153], 2, s[8:9]
	global_load_dword v2, v[0:1], off sc1
	global_load_dword v4, v[0:1], off offset:512 sc1
	global_load_dword v3, v[0:1], off offset:1024 sc1
	global_load_dword v5, v[0:1], off offset:1536 sc1
	s_waitcnt vmcnt(0) lgkmcnt(0)
	v_pk_add_f32 v[0:1], v[2:3], v[4:5]
	s_nop 0
	v_add_f32_e32 v0, v0, v1
	ds_write_b32 v150, v0 offset:2048
.LBB0_1031:
	s_or_b64 exec, exec, s[12:13]
	s_add_i32 s8, s60, 0x7f
	s_cmpk_lt_u32 s8, 0xff
	s_cselect_b64 s[8:9], -1, 0
	s_and_b64 s[10:11], s[8:9], s[10:11]
	s_waitcnt lgkmcnt(0)
	s_barrier
	s_and_saveexec_b64 s[8:9], s[10:11]
	s_cbranch_execz .LBB0_813
	ds_read_b32 v0, v150 offset:2048
	s_mov_b32 s10, 0x800000
	s_waitcnt lgkmcnt(0)
	v_fmamk_f32 v0, v0, 0x3a800000, v224
	v_mul_f32_e32 v1, 0x4b800000, v0
	v_cmp_gt_f32_e32 vcc, s10, v0
	s_nop 1
	v_cndmask_b32_e32 v0, v0, v1, vcc
	v_rsq_f32_e32 v2, v0
	v_add_u32_e32 v0, s30, v152
	v_ashrrev_i32_e32 v1, 31, v0
	v_lshl_add_u64 v[0:1], v[0:1], 2, s[28:29]
	v_mul_f32_e32 v3, 0x45800000, v2
	v_cndmask_b32_e32 v2, v2, v3, vcc
	global_store_dword v[0:1], v2, off
	s_branch .LBB0_813

.LBB0_1090:
	v_lshl_add_u64 v[12:13], s[2:3], 0, v[8:9]
	v_add_co_u32_e32 v0, vcc, 0x3dd0000, v12
	v_readlane_b32 s14, v253, 47
	s_waitcnt lgkmcnt(0)
	v_addc_co_u32_e32 v1, vcc, 0, v13, vcc
	global_load_dwordx2 v[2:3], v[0:1], off
	global_load_dwordx2 v[18:19], v[0:1], off offset:1024
	v_readlane_b32 s15, v253, 48
	s_mov_b64 s[0:1], -1
	s_and_b64 vcc, exec, s[14:15]
	s_waitcnt vmcnt(0) lgkmcnt(0)
	v_lshlrev_b32_e32 v38, 16, v2
	v_and_b32_e32 v27, 0xffff0000, v2
	v_and_b32_e32 v29, 0xffff0000, v3
	v_lshlrev_b32_e32 v40, 16, v3
	global_load_dwordx2 v[2:3], v[0:1], off offset:512
	v_mov_b32_e32 v32, v27
	global_load_dwordx2 v[0:1], v[0:1], off offset:1536
	v_and_b32_e32 v15, 0xffff0000, v18
	v_lshlrev_b32_e32 v22, 16, v18
	v_and_b32_e32 v17, 0xffff0000, v19
	v_lshlrev_b32_e32 v24, 16, v19
	v_mov_b32_e32 v18, v15
	v_mov_b32_e32 v30, v29
	v_mov_b32_e32 v20, v17
	s_waitcnt vmcnt(0) lgkmcnt(0)
	v_lshlrev_b32_e32 v26, 16, v2
	v_and_b32_e32 v33, 0xffff0000, v2
	v_and_b32_e32 v31, 0xffff0000, v3
	v_lshlrev_b32_e32 v28, 16, v3
	v_mov_b32_e32 v39, v26
	v_pk_mul_f32 v[2:3], v[32:33], v[32:33]
	v_lshlrev_b32_e32 v14, 16, v0
	v_and_b32_e32 v19, 0xffff0000, v0
	v_pk_fma_f32 v[2:3], v[38:39], v[38:39], v[2:3]
	v_mov_b32_e32 v41, v28
	v_and_b32_e32 v21, 0xffff0000, v1
	v_lshlrev_b32_e32 v16, 16, v1
	v_mov_b32_e32 v23, v14
	v_pk_mul_f32 v[0:1], v[18:19], v[18:19]
	v_pk_fma_f32 v[2:3], v[40:41], v[40:41], v[2:3]
	v_pk_fma_f32 v[0:1], v[22:23], v[22:23], v[0:1]
	v_mov_b32_e32 v25, v16
	v_pk_fma_f32 v[2:3], v[30:31], v[30:31], v[2:3]
	v_pk_fma_f32 v[0:1], v[24:25], v[24:25], v[0:1]
	v_add_f32_e32 v2, v2, v3
	v_pk_fma_f32 v[0:1], v[20:21], v[20:21], v[0:1]
	s_nop 0
	v_add_f32_e32 v0, v2, v0
	v_add_f32_e32 v0, v0, v1
	ds_bpermute_b32 v1, v43, v0
	s_waitcnt lgkmcnt(0)
	v_add_f32_e32 v0, v0, v1
	ds_bpermute_b32 v1, v44, v0
	s_waitcnt lgkmcnt(0)
	v_add_f32_e32 v0, v0, v1
	ds_bpermute_b32 v1, v45, v0
	s_waitcnt lgkmcnt(0)
	v_add_f32_e32 v0, v0, v1
	ds_bpermute_b32 v1, v46, v0
	s_waitcnt lgkmcnt(0)
	v_add_f32_e32 v0, v0, v1
	ds_bpermute_b32 v1, v47, v0
	s_waitcnt lgkmcnt(0)
	v_add_f32_e32 v18, v0, v1
	ds_bpermute_b32 v20, v48, v18
	s_cbranch_vccz .LBB0_1092
	v_add_co_u32_e32 v0, vcc, 0x1dc0000, v12
	s_mov_b64 s[0:1], 0
	s_nop 0
	v_addc_co_u32_e32 v1, vcc, 0, v13, vcc
	global_load_dwordx2 v[2:3], v[0:1], off
	s_waitcnt vmcnt(0) lgkmcnt(0)
	v_lshlrev_b32_e32 v0, 16, v2
	v_and_b32_e32 v1, 0xffff0000, v2
	v_lshlrev_b32_e32 v2, 16, v3
	v_and_b32_e32 v3, 0xffff0000, v3

.LBB0_1097:
	v_add_co_u32_e32 v0, vcc, 0x1dc0000, v12
	s_nop 1
	v_addc_co_u32_e32 v1, vcc, 0, v13, vcc
	global_load_dwordx2 v[2:3], v[0:1], off offset:512
	s_waitcnt vmcnt(0) lgkmcnt(0)
	v_lshlrev_b32_e32 v0, 16, v2
	v_and_b32_e32 v1, 0xffff0000, v2
	v_lshlrev_b32_e32 v2, 16, v3
	v_and_b32_e32 v3, 0xffff0000, v3
	s_cbranch_execz .LBB0_1101
	s_branch .LBB0_1102

.LBB0_1099:
	v_pk_mul_f32 v[40:41], v[0:1], v[0:1]
	v_pk_mul_f32 v[50:51], v[2:3], v[2:3]
	v_add_f32_e32 v18, v40, v41
	v_add_f32_e32 v18, v50, v18
	v_cvt_pk_bf16_f32 v0, v0, v1
	v_cvt_pk_bf16_f32 v1, v2, v3
	v_add_co_u32_e32 v2, vcc, 0x1dc0000, v12
	v_add_f32_e32 v18, v51, v18
	s_nop 0
	v_addc_co_u32_e32 v3, vcc, 0, v13, vcc
	global_store_dwordx2 v[2:3], v[0:1], off
	s_and_b64 vcc, exec, s[0:1]
	s_mov_b64 s[14:15], -1
	s_cbranch_vccz .LBB0_1097

.LBB0_1105:
	v_add_co_u32_e32 v0, vcc, 0x1dc0000, v12
	s_nop 1
	v_addc_co_u32_e32 v1, vcc, 0, v13, vcc
	global_load_dwordx2 v[2:3], v[0:1], off offset:1024
	s_waitcnt vmcnt(0) lgkmcnt(0)
	v_lshlrev_b32_e32 v0, 16, v2
	v_and_b32_e32 v1, 0xffff0000, v2
	v_lshlrev_b32_e32 v2, 16, v3
	v_and_b32_e32 v3, 0xffff0000, v3
	s_cbranch_execz .LBB0_1109
	s_branch .LBB0_1110

.LBB0_1107:
	v_pk_mul_f32 v[26:27], v[0:1], v[0:1]
	v_pk_mul_f32 v[28:29], v[2:3], v[2:3]
	v_add_f32_e32 v20, v26, v27
	v_add_f32_e32 v20, v28, v20
	v_add_f32_e32 v20, v29, v20
	v_cvt_pk_bf16_f32 v0, v0, v1
	v_cvt_pk_bf16_f32 v1, v2, v3
	v_add_co_u32_e32 v2, vcc, 0x1dc0000, v12
	v_add_f32_e32 v18, v18, v20
	s_nop 0
	v_addc_co_u32_e32 v3, vcc, 0, v13, vcc
	global_store_dwordx2 v[2:3], v[0:1], off offset:512
	s_and_b64 vcc, exec, s[0:1]
	s_mov_b64 s[14:15], -1
	s_cbranch_vccz .LBB0_1105

.LBB0_1113:
	v_add_co_u32_e32 v0, vcc, 0x1dc0000, v12
	s_nop 1
	v_addc_co_u32_e32 v1, vcc, 0, v13, vcc
	global_load_dwordx2 v[2:3], v[0:1], off offset:1536
	s_waitcnt vmcnt(0) lgkmcnt(0)
	v_lshlrev_b32_e32 v0, 16, v2
	v_and_b32_e32 v1, 0xffff0000, v2
	v_lshlrev_b32_e32 v2, 16, v3
	v_and_b32_e32 v3, 0xffff0000, v3
	s_cbranch_execz .LBB0_1117
	s_branch .LBB0_1118

.LBB0_1115:
	v_pk_mul_f32 v[22:23], v[0:1], v[0:1]
	v_pk_mul_f32 v[24:25], v[2:3], v[2:3]
	v_add_f32_e32 v15, v22, v23
	v_add_f32_e32 v15, v24, v15
	v_add_f32_e32 v15, v25, v15
	v_cvt_pk_bf16_f32 v0, v0, v1
	v_cvt_pk_bf16_f32 v1, v2, v3
	v_add_co_u32_e32 v2, vcc, 0x1dc0000, v12
	v_add_f32_e32 v18, v18, v15
	s_nop 0
	v_addc_co_u32_e32 v3, vcc, 0, v13, vcc
	global_store_dwordx2 v[2:3], v[0:1], off offset:1024
	s_and_b64 vcc, exec, s[0:1]
	s_mov_b64 s[14:15], -1
	s_cbranch_vccz .LBB0_1113

.LBB0_1120:
	s_andn2_b64 vcc, exec, s[0:1]
	s_cbranch_vccnz .LBB0_1122
	v_pk_mul_f32 v[14:15], v[0:1], v[0:1]
	v_pk_mul_f32 v[16:17], v[2:3], v[2:3]
	v_add_f32_e32 v14, v14, v15
	v_add_f32_e32 v14, v16, v14
	v_add_f32_e32 v14, v17, v14
	v_cvt_pk_bf16_f32 v0, v0, v1
	v_cvt_pk_bf16_f32 v1, v2, v3
	v_add_co_u32_e32 v2, vcc, 0x1dc0000, v12
	v_add_f32_e32 v18, v18, v14
	s_nop 0
	v_addc_co_u32_e32 v3, vcc, 0, v13, vcc
	global_store_dwordx2 v[2:3], v[0:1], off offset:1536
.LBB0_1122:
	v_readlane_b32 s0, v253, 25
	v_readlane_b32 s1, v253, 26
	s_and_b64 vcc, exec, s[0:1]
	s_cbranch_vccz .LBB0_1089
	ds_bpermute_b32 v0, v43, v18
	s_waitcnt lgkmcnt(0)
	v_add_f32_e32 v0, v18, v0
	ds_bpermute_b32 v1, v44, v0
	s_waitcnt lgkmcnt(0)
	v_add_f32_e32 v0, v0, v1
	ds_bpermute_b32 v1, v45, v0
	s_waitcnt lgkmcnt(0)
	v_add_f32_e32 v0, v0, v1
	ds_bpermute_b32 v1, v46, v0
	s_waitcnt lgkmcnt(0)
	v_add_f32_e32 v0, v0, v1
	ds_bpermute_b32 v1, v47, v0
	s_waitcnt lgkmcnt(0)
	v_add_f32_e32 v0, v0, v1
	ds_bpermute_b32 v1, v48, v0
	s_and_saveexec_b64 s[0:1], s[8:9]
	s_cbranch_execz .LBB0_1088
	s_waitcnt lgkmcnt(0)
	v_add_f32_e32 v0, v0, v1
	v_fmamk_f32 v0, v0, 0x3a800000, v224
	s_mov_b32 s14, 0x800000
	v_mul_f32_e32 v1, 0x4b800000, v0
	v_cmp_gt_f32_e32 vcc, s14, v0
	s_nop 1
	v_cndmask_b32_e32 v0, v0, v1, vcc
	v_rsq_f32_e32 v0, v0
	s_nop 0
	v_mul_f32_e32 v1, 0x45800000, v0
	v_cndmask_b32_e32 v2, v0, v1, vcc
	v_lshl_add_u64 v[0:1], s[2:3], 0, v[6:7]
	global_store_dword v[0:1], v2, off
	s_branch .LBB0_1088
